# v35: + rope table loads (P3 k_rope, P4 up_q) issued ~20 deep into private register pairs; + norm-weight reload removed in P2/P7 epilogues
# speedup vs baseline: 1.1296x; 1.0314x over previous
.LBB0_658:
	s_and_b64 vcc, exec, s[2:3]
	s_cbranch_vccz .LBB0_596
	v_mov_b32_e32 v172, v208
	s_nop 0
	v_ashrrev_i32_e32 v0, 1, v172
	v_and_b32_e32 v0, 0xffffff80, v0
	s_waitcnt vmcnt(7)
	v_lshrrev_b32_e32 v130, 3, v172
	v_and_b32_e32 v173, 4, v130
	v_add_u32_e32 v174, s9, v0
	s_waitcnt vmcnt(6)
	v_or_b32_e32 v136, v174, v173
	v_min_i32_e32 v0, 0x403f, v136
	v_mul_hi_i32 v130, v0, s30
	v_lshrrev_b32_e32 v131, 31, v130
	v_ashrrev_i32_e32 v130, 11, v130
	v_add_u32_e32 v130, v130, v131
	v_mad_i32_i24 v0, v130, s31, v0
	v_cmp_lt_i32_e32 vcc, 15, v0
	s_and_saveexec_b64 s[0:1], vcc
	s_xor_b64 s[0:1], exec, s[0:1]
	v_lshlrev_b32_e32 v130, 12, v130
	v_add3_u32 v130, v130, v0, -16
	v_ashrrev_i32_e32 v131, 31, v130
	v_lshlrev_b64 v[130:131], 12, v[130:131]
	v_lshl_add_u64 v[132:133], s[56:57], 0, v[130:131]
	s_andn2_saveexec_b64 s[0:1], s[0:1]
	v_lshlrev_b32_e32 v130, 10, v0
	v_ashrrev_i32_e32 v131, 31, v130
	v_lshl_add_u64 v[132:133], v[130:131], 2, s[58:59]
	s_or_b64 exec, exec, s[0:1]
	v_bfe_u32 v0, v172, 6, 2
	v_and_b32_e32 v175, 31, v172
	v_lshlrev_b32_e32 v130, 6, v0
	v_or3_b32 v130, v130, s8, v175
	v_ashrrev_i32_e32 v131, 31, v130
	v_lshl_add_u64 v[132:133], v[130:131], 2, v[132:133]
	global_load_dword v176, v[132:133], off
	global_load_dword v177, v[132:133], off offset:128
	v_or_b32_e32 v166, 1, v136
	v_min_i32_e32 v132, 0x403f, v166
	v_mul_hi_i32 v133, v132, s30
	v_lshrrev_b32_e32 v134, 31, v133
	v_ashrrev_i32_e32 v133, 11, v133
	v_add_u32_e32 v135, v133, v134
	v_mad_i32_i24 v134, v135, s31, v132
	v_cmp_lt_i32_e32 vcc, 15, v134
	s_and_saveexec_b64 s[0:1], vcc
	s_xor_b64 s[0:1], exec, s[0:1]
	v_lshlrev_b32_e32 v132, 12, v135
	v_add3_u32 v132, v132, v134, -16
	v_ashrrev_i32_e32 v133, 31, v132
	v_lshlrev_b64 v[132:133], 12, v[132:133]
	v_lshl_add_u64 v[132:133], s[56:57], 0, v[132:133]
	s_andn2_saveexec_b64 s[0:1], s[0:1]
	v_lshlrev_b32_e32 v132, 10, v134
	v_ashrrev_i32_e32 v133, 31, v132
	v_lshl_add_u64 v[132:133], v[132:133], 2, s[58:59]
	s_or_b64 exec, exec, s[0:1]
	v_lshl_add_u64 v[132:133], v[130:131], 2, v[132:133]
	global_load_dword v181, v[132:133], off
	global_load_dword v182, v[132:133], off offset:128
	v_or_b32_e32 v164, 2, v136
	v_min_i32_e32 v132, 0x403f, v164
	v_mul_hi_i32 v133, v132, s30
	v_lshrrev_b32_e32 v134, 31, v133
	v_ashrrev_i32_e32 v133, 11, v133
	v_add_u32_e32 v135, v133, v134
	v_mad_i32_i24 v134, v135, s31, v132
	v_cmp_lt_i32_e32 vcc, 15, v134
	s_and_saveexec_b64 s[0:1], vcc
	s_xor_b64 s[0:1], exec, s[0:1]
	v_lshlrev_b32_e32 v132, 12, v135
	v_add3_u32 v132, v132, v134, -16
	v_ashrrev_i32_e32 v133, 31, v132
	v_lshlrev_b64 v[132:133], 12, v[132:133]
	v_lshl_add_u64 v[132:133], s[56:57], 0, v[132:133]
	s_andn2_saveexec_b64 s[0:1], s[0:1]
	v_lshlrev_b32_e32 v132, 10, v134
	v_ashrrev_i32_e32 v133, 31, v132
	v_lshl_add_u64 v[132:133], v[132:133], 2, s[58:59]
	s_or_b64 exec, exec, s[0:1]
	v_lshl_add_u64 v[132:133], v[130:131], 2, v[132:133]
	global_load_dword v183, v[132:133], off
	global_load_dword v184, v[132:133], off offset:128
	v_or_b32_e32 v162, 3, v136
	v_min_i32_e32 v132, 0x403f, v162
	v_mul_hi_i32 v133, v132, s30
	v_lshrrev_b32_e32 v134, 31, v133
	v_ashrrev_i32_e32 v133, 11, v133
	v_add_u32_e32 v135, v133, v134
	v_mad_i32_i24 v134, v135, s31, v132
	v_cmp_lt_i32_e32 vcc, 15, v134
	s_and_saveexec_b64 s[0:1], vcc
	s_xor_b64 s[0:1], exec, s[0:1]
	v_lshlrev_b32_e32 v132, 12, v135
	v_add3_u32 v132, v132, v134, -16
	v_ashrrev_i32_e32 v133, 31, v132
	v_lshlrev_b64 v[132:133], 12, v[132:133]
	v_lshl_add_u64 v[132:133], s[56:57], 0, v[132:133]
	s_andn2_saveexec_b64 s[0:1], s[0:1]
	v_lshlrev_b32_e32 v132, 10, v134
	v_ashrrev_i32_e32 v133, 31, v132
	v_lshl_add_u64 v[132:133], v[132:133], 2, s[58:59]
	s_or_b64 exec, exec, s[0:1]
	v_lshl_add_u64 v[132:133], v[130:131], 2, v[132:133]
	global_load_dword v185, v[132:133], off
	global_load_dword v186, v[132:133], off offset:128
	s_waitcnt vmcnt(13)
	v_or_b32_e32 v160, 8, v136
	v_min_i32_e32 v132, 0x403f, v160
	v_mul_hi_i32 v133, v132, s30
	v_lshrrev_b32_e32 v134, 31, v133
	v_ashrrev_i32_e32 v133, 11, v133
	v_add_u32_e32 v135, v133, v134
	v_mad_i32_i24 v134, v135, s31, v132
	v_cmp_lt_i32_e32 vcc, 15, v134
	s_and_saveexec_b64 s[0:1], vcc
	s_xor_b64 s[0:1], exec, s[0:1]
	v_lshlrev_b32_e32 v132, 12, v135
	v_add3_u32 v132, v132, v134, -16
	v_ashrrev_i32_e32 v133, 31, v132
	v_lshlrev_b64 v[132:133], 12, v[132:133]
	v_lshl_add_u64 v[132:133], s[56:57], 0, v[132:133]
	s_andn2_saveexec_b64 s[0:1], s[0:1]
	v_lshlrev_b32_e32 v132, 10, v134
	v_ashrrev_i32_e32 v133, 31, v132
	v_lshl_add_u64 v[132:133], v[132:133], 2, s[58:59]
	s_or_b64 exec, exec, s[0:1]
	v_lshl_add_u64 v[132:133], v[130:131], 2, v[132:133]
	global_load_dword v187, v[132:133], off
	global_load_dword v188, v[132:133], off offset:128
	v_or_b32_e32 v158, 9, v136
	v_min_i32_e32 v132, 0x403f, v158
	v_mul_hi_i32 v133, v132, s30
	v_lshrrev_b32_e32 v134, 31, v133
	v_ashrrev_i32_e32 v133, 11, v133
	v_add_u32_e32 v135, v133, v134
	v_mad_i32_i24 v134, v135, s31, v132
	v_cmp_lt_i32_e32 vcc, 15, v134
	s_and_saveexec_b64 s[0:1], vcc
	s_xor_b64 s[0:1], exec, s[0:1]
	v_lshlrev_b32_e32 v132, 12, v135
	v_add3_u32 v132, v132, v134, -16
	v_ashrrev_i32_e32 v133, 31, v132
	v_lshlrev_b64 v[132:133], 12, v[132:133]
	v_lshl_add_u64 v[132:133], s[56:57], 0, v[132:133]
	s_andn2_saveexec_b64 s[0:1], s[0:1]
	v_lshlrev_b32_e32 v132, 10, v134
	v_ashrrev_i32_e32 v133, 31, v132
	v_lshl_add_u64 v[132:133], v[132:133], 2, s[58:59]
	s_or_b64 exec, exec, s[0:1]
	v_lshl_add_u64 v[132:133], v[130:131], 2, v[132:133]
	global_load_dword v189, v[132:133], off
	global_load_dword v190, v[132:133], off offset:128
	s_waitcnt vmcnt(12)
	v_or_b32_e32 v156, 10, v136
	v_min_i32_e32 v132, 0x403f, v156
	v_mul_hi_i32 v133, v132, s30
	v_lshrrev_b32_e32 v134, 31, v133
	v_ashrrev_i32_e32 v133, 11, v133
	v_add_u32_e32 v135, v133, v134
	v_mad_i32_i24 v134, v135, s31, v132
	v_cmp_lt_i32_e32 vcc, 15, v134
	s_and_saveexec_b64 s[0:1], vcc
	s_xor_b64 s[0:1], exec, s[0:1]
	v_lshlrev_b32_e32 v132, 12, v135
	v_add3_u32 v132, v132, v134, -16
	v_ashrrev_i32_e32 v133, 31, v132
	v_lshlrev_b64 v[132:133], 12, v[132:133]
	v_lshl_add_u64 v[132:133], s[56:57], 0, v[132:133]
	s_andn2_saveexec_b64 s[0:1], s[0:1]
	v_lshlrev_b32_e32 v132, 10, v134
	v_ashrrev_i32_e32 v133, 31, v132
	v_lshl_add_u64 v[132:133], v[132:133], 2, s[58:59]
	s_or_b64 exec, exec, s[0:1]
	v_lshl_add_u64 v[132:133], v[130:131], 2, v[132:133]
	global_load_dword v191, v[132:133], off
	global_load_dword v192, v[132:133], off offset:128
	v_or_b32_e32 v154, 11, v136
	v_min_i32_e32 v132, 0x403f, v154
	v_mul_hi_i32 v133, v132, s30
	v_lshrrev_b32_e32 v134, 31, v133
	v_ashrrev_i32_e32 v133, 11, v133
	v_add_u32_e32 v135, v133, v134
	v_mad_i32_i24 v134, v135, s31, v132
	v_cmp_lt_i32_e32 vcc, 15, v134
	s_and_saveexec_b64 s[0:1], vcc
	s_xor_b64 s[0:1], exec, s[0:1]
	v_lshlrev_b32_e32 v132, 12, v135
	v_add3_u32 v132, v132, v134, -16
	v_ashrrev_i32_e32 v133, 31, v132
	v_lshlrev_b64 v[132:133], 12, v[132:133]
	v_lshl_add_u64 v[132:133], s[56:57], 0, v[132:133]
	s_andn2_saveexec_b64 s[0:1], s[0:1]
	v_lshlrev_b32_e32 v132, 10, v134
	v_ashrrev_i32_e32 v133, 31, v132
	v_lshl_add_u64 v[132:133], v[132:133], 2, s[58:59]
	s_or_b64 exec, exec, s[0:1]
	v_lshl_add_u64 v[132:133], v[130:131], 2, v[132:133]
	global_load_dword v193, v[132:133], off
	global_load_dword v194, v[132:133], off offset:128
	v_or_b32_e32 v152, 16, v136
	v_min_i32_e32 v132, 0x403f, v152
	v_mul_hi_i32 v133, v132, s30
	v_lshrrev_b32_e32 v134, 31, v133
	v_ashrrev_i32_e32 v133, 11, v133
	v_add_u32_e32 v135, v133, v134
	v_mad_i32_i24 v134, v135, s31, v132
	v_cmp_lt_i32_e32 vcc, 15, v134
	s_and_saveexec_b64 s[0:1], vcc
	s_xor_b64 s[0:1], exec, s[0:1]
	v_lshlrev_b32_e32 v132, 12, v135
	v_add3_u32 v132, v132, v134, -16
	v_ashrrev_i32_e32 v133, 31, v132
	v_lshlrev_b64 v[132:133], 12, v[132:133]
	v_lshl_add_u64 v[132:133], s[56:57], 0, v[132:133]
	s_andn2_saveexec_b64 s[0:1], s[0:1]
	v_lshlrev_b32_e32 v132, 10, v134
	v_ashrrev_i32_e32 v133, 31, v132
	v_lshl_add_u64 v[132:133], v[132:133], 2, s[58:59]
	s_or_b64 exec, exec, s[0:1]
	v_lshl_add_u64 v[132:133], v[130:131], 2, v[132:133]
	global_load_dword v195, v[132:133], off
	global_load_dword v196, v[132:133], off offset:128
	v_or_b32_e32 v150, 17, v136
	v_min_i32_e32 v132, 0x403f, v150
	v_mul_hi_i32 v133, v132, s30
	v_lshrrev_b32_e32 v134, 31, v133
	v_ashrrev_i32_e32 v133, 11, v133
	v_add_u32_e32 v135, v133, v134
	v_mad_i32_i24 v134, v135, s31, v132
	v_cmp_lt_i32_e32 vcc, 15, v134
	s_and_saveexec_b64 s[0:1], vcc
	s_xor_b64 s[0:1], exec, s[0:1]
	v_lshlrev_b32_e32 v132, 12, v135
	v_add3_u32 v132, v132, v134, -16
	v_ashrrev_i32_e32 v133, 31, v132
	v_lshlrev_b64 v[132:133], 12, v[132:133]
	v_lshl_add_u64 v[132:133], s[56:57], 0, v[132:133]
	s_andn2_saveexec_b64 s[0:1], s[0:1]
	v_lshlrev_b32_e32 v132, 10, v134
	v_ashrrev_i32_e32 v133, 31, v132
	v_lshl_add_u64 v[132:133], v[132:133], 2, s[58:59]
	s_or_b64 exec, exec, s[0:1]
	v_lshl_add_u64 v[132:133], v[130:131], 2, v[132:133]
	global_load_dword v197, v[132:133], off
	global_load_dword v198, v[132:133], off offset:128
	v_or_b32_e32 v148, 18, v136
	v_min_i32_e32 v132, 0x403f, v148
	v_mul_hi_i32 v133, v132, s30
	v_lshrrev_b32_e32 v134, 31, v133
	v_ashrrev_i32_e32 v133, 11, v133
	v_add_u32_e32 v135, v133, v134
	v_mad_i32_i24 v134, v135, s31, v132
	v_cmp_lt_i32_e32 vcc, 15, v134
	s_and_saveexec_b64 s[0:1], vcc
	s_xor_b64 s[0:1], exec, s[0:1]
	v_lshlrev_b32_e32 v132, 12, v135
	v_add3_u32 v132, v132, v134, -16
	v_ashrrev_i32_e32 v133, 31, v132
	v_lshlrev_b64 v[132:133], 12, v[132:133]
	v_lshl_add_u64 v[132:133], s[56:57], 0, v[132:133]
	s_andn2_saveexec_b64 s[0:1], s[0:1]
	v_lshlrev_b32_e32 v132, 10, v134
	v_ashrrev_i32_e32 v133, 31, v132
	v_lshl_add_u64 v[132:133], v[132:133], 2, s[58:59]
	s_or_b64 exec, exec, s[0:1]
	v_lshl_add_u64 v[132:133], v[130:131], 2, v[132:133]
	global_load_dword v199, v[132:133], off
	global_load_dword v200, v[132:133], off offset:128
	v_or_b32_e32 v146, 19, v136
	v_min_i32_e32 v132, 0x403f, v146
	v_mul_hi_i32 v133, v132, s30
	v_lshrrev_b32_e32 v134, 31, v133
	v_ashrrev_i32_e32 v133, 11, v133
	v_add_u32_e32 v135, v133, v134
	v_mad_i32_i24 v134, v135, s31, v132
	v_cmp_lt_i32_e32 vcc, 15, v134
	s_and_saveexec_b64 s[0:1], vcc
	s_xor_b64 s[0:1], exec, s[0:1]
	v_lshlrev_b32_e32 v132, 12, v135
	v_add3_u32 v132, v132, v134, -16
	v_ashrrev_i32_e32 v133, 31, v132
	v_lshlrev_b64 v[132:133], 12, v[132:133]
	v_lshl_add_u64 v[132:133], s[56:57], 0, v[132:133]
	s_andn2_saveexec_b64 s[0:1], s[0:1]
	v_lshlrev_b32_e32 v132, 10, v134
	v_ashrrev_i32_e32 v133, 31, v132
	v_lshl_add_u64 v[132:133], v[132:133], 2, s[58:59]
	s_or_b64 exec, exec, s[0:1]
	v_lshl_add_u64 v[132:133], v[130:131], 2, v[132:133]
	global_load_dword v201, v[132:133], off
	global_load_dword v202, v[132:133], off offset:128
	v_or_b32_e32 v144, 24, v136
	v_min_i32_e32 v132, 0x403f, v144
	v_mul_hi_i32 v133, v132, s30
	v_lshrrev_b32_e32 v134, 31, v133
	v_ashrrev_i32_e32 v133, 11, v133
	v_add_u32_e32 v135, v133, v134
	v_mad_i32_i24 v134, v135, s31, v132
	v_cmp_lt_i32_e32 vcc, 15, v134
	s_and_saveexec_b64 s[0:1], vcc
	s_xor_b64 s[0:1], exec, s[0:1]
	v_lshlrev_b32_e32 v132, 12, v135
	v_add3_u32 v132, v132, v134, -16
	v_ashrrev_i32_e32 v133, 31, v132
	v_lshlrev_b64 v[132:133], 12, v[132:133]
	v_lshl_add_u64 v[132:133], s[56:57], 0, v[132:133]
	s_andn2_saveexec_b64 s[0:1], s[0:1]
	v_lshlrev_b32_e32 v132, 10, v134
	v_ashrrev_i32_e32 v133, 31, v132
	v_lshl_add_u64 v[132:133], v[132:133], 2, s[58:59]
	s_or_b64 exec, exec, s[0:1]
	v_lshl_add_u64 v[132:133], v[130:131], 2, v[132:133]
	global_load_dword v203, v[132:133], off
	global_load_dword v204, v[132:133], off offset:128
	v_or_b32_e32 v142, 25, v136
	v_min_i32_e32 v132, 0x403f, v142
	v_mul_hi_i32 v133, v132, s30
	v_lshrrev_b32_e32 v134, 31, v133
	v_ashrrev_i32_e32 v133, 11, v133
	v_add_u32_e32 v135, v133, v134
	v_mad_i32_i24 v134, v135, s31, v132
	v_cmp_lt_i32_e32 vcc, 15, v134
	s_and_saveexec_b64 s[0:1], vcc
	s_xor_b64 s[0:1], exec, s[0:1]
	v_lshlrev_b32_e32 v132, 12, v135
	v_add3_u32 v132, v132, v134, -16
	v_ashrrev_i32_e32 v133, 31, v132
	v_lshlrev_b64 v[132:133], 12, v[132:133]
	v_lshl_add_u64 v[132:133], s[56:57], 0, v[132:133]
	s_andn2_saveexec_b64 s[0:1], s[0:1]
	v_lshlrev_b32_e32 v132, 10, v134
	v_ashrrev_i32_e32 v133, 31, v132
	v_lshl_add_u64 v[132:133], v[132:133], 2, s[58:59]
	s_or_b64 exec, exec, s[0:1]
	v_lshl_add_u64 v[132:133], v[130:131], 2, v[132:133]
	global_load_dword v205, v[132:133], off
	global_load_dword v206, v[132:133], off offset:128
	v_or_b32_e32 v140, 26, v136
	v_min_i32_e32 v132, 0x403f, v140
	v_mul_hi_i32 v133, v132, s30
	v_lshrrev_b32_e32 v134, 31, v133
	v_ashrrev_i32_e32 v133, 11, v133
	v_add_u32_e32 v135, v133, v134
	v_mad_i32_i24 v134, v135, s31, v132
	v_cmp_lt_i32_e32 vcc, 15, v134
	s_and_saveexec_b64 s[0:1], vcc
	s_xor_b64 s[0:1], exec, s[0:1]
	v_lshlrev_b32_e32 v132, 12, v135
	v_add3_u32 v132, v132, v134, -16
	v_ashrrev_i32_e32 v133, 31, v132
	v_lshlrev_b64 v[132:133], 12, v[132:133]
	v_lshl_add_u64 v[132:133], s[56:57], 0, v[132:133]
	s_andn2_saveexec_b64 s[0:1], s[0:1]
	v_lshlrev_b32_e32 v132, 10, v134
	v_ashrrev_i32_e32 v133, 31, v132
	v_lshl_add_u64 v[132:133], v[132:133], 2, s[58:59]
	s_or_b64 exec, exec, s[0:1]
	v_lshl_add_u64 v[132:133], v[130:131], 2, v[132:133]
	global_load_dword v207, v[132:133], off
	global_load_dword v210, v[132:133], off offset:128
	v_or_b32_e32 v138, 27, v136
	v_min_i32_e32 v132, 0x403f, v138
	v_mul_hi_i32 v133, v132, s30
	v_lshrrev_b32_e32 v134, 31, v133
	v_ashrrev_i32_e32 v133, 11, v133
	v_add_u32_e32 v135, v133, v134
	v_mad_i32_i24 v134, v135, s31, v132
	v_cmp_lt_i32_e32 vcc, 15, v134
	s_and_saveexec_b64 s[0:1], vcc
	s_xor_b64 s[0:1], exec, s[0:1]
	v_lshlrev_b32_e32 v132, 12, v135
	v_add3_u32 v132, v132, v134, -16
	v_ashrrev_i32_e32 v133, 31, v132
	v_lshlrev_b64 v[132:133], 12, v[132:133]
	v_lshl_add_u64 v[132:133], s[56:57], 0, v[132:133]
	s_andn2_saveexec_b64 s[0:1], s[0:1]
	v_lshlrev_b32_e32 v132, 10, v134
	v_ashrrev_i32_e32 v133, 31, v132
	v_lshl_add_u64 v[132:133], v[132:133], 2, s[58:59]
	s_or_b64 exec, exec, s[0:1]
	v_lshl_add_u64 v[132:133], v[130:131], 2, v[132:133]
	global_load_dword v211, v[132:133], off
	global_load_dword v212, v[132:133], off offset:128
	v_cmp_gt_i32_e32 vcc, s34, v136
	s_nop 1
	v_cndmask_b32_e32 v132, v179, v136, vcc
	v_mul_hi_i32 v133, v132, s30
	v_lshrrev_b32_e32 v134, 31, v133
	v_ashrrev_i32_e32 v133, 11, v133
	v_add_u32_e32 v134, v133, v134
	v_mad_i32_i24 v135, v134, s31, v132
	v_cmp_lt_i32_e64 s[0:1], 15, v135
	s_and_saveexec_b64 s[2:3], s[0:1]
	s_xor_b64 s[0:1], exec, s[2:3]
	v_lshlrev_b32_e32 v132, 12, v134
	v_add3_u32 v132, v132, v135, -16
	v_ashrrev_i32_e32 v133, 31, v132
	v_lshlrev_b64 v[132:133], 12, v[132:133]
	v_lshl_add_u64 v[132:133], s[88:89], 0, v[132:133]
	s_andn2_saveexec_b64 s[0:1], s[0:1]
	v_lshlrev_b32_e32 v132, 14, v134
	v_lshl_add_u32 v132, v135, 10, v132
	v_ashrrev_i32_e32 v133, 31, v132
	v_lshl_add_u64 v[132:133], v[132:133], 2, s[12:13]
	s_or_b64 exec, exec, s[0:1]
	v_ashrrev_i32_e32 v137, 31, v136
	v_lshlrev_b64 v[134:135], 11, v[136:137]
	v_lshl_add_u64 v[168:169], s[62:63], 0, v[134:135]
	v_lshlrev_b64 v[134:135], 2, v[130:131]
	s_waitcnt vmcnt(31)
	v_fmac_f32_e32 v176, 0.5, v114
	v_lshl_add_u64 v[168:169], v[130:131], 1, v[168:169]
	v_lshl_add_u64 v[170:171], v[132:133], 0, v[134:135]
	v_lshl_add_u64 v[132:133], s[68:69], 0, v[134:135]
	global_load_dword v242, v[132:133], off
	global_load_dword v243, v[132:133], off offset:128
	s_waitcnt vmcnt(0)
	s_and_saveexec_b64 s[0:1], vcc
	s_cbranch_execz .LBB0_729
	global_store_dword v[170:171], v176, off
	v_mul_f32_e32 v114, v176, v242
	v_cvt_pk_bf16_f32 v114, v114, s0
	global_store_short v[168:169], v114, off
.LBB0_729:
	s_or_b64 exec, exec, s[0:1]
	s_waitcnt vmcnt(30)
	v_fmac_f32_e32 v177, 0.5, v98
	s_and_saveexec_b64 s[0:1], vcc
	s_cbranch_execz .LBB0_731
	global_store_dword v[170:171], v177, off offset:128
	v_mul_f32_e32 v98, v177, v243
	v_cvt_pk_bf16_f32 v98, v98, s0
	global_store_short v[168:169], v98, off offset:64
.LBB0_731:
	s_or_b64 exec, exec, s[0:1]
	v_cmp_gt_i32_e32 vcc, s34, v166
	s_nop 1
	v_cndmask_b32_e32 v114, v179, v166, vcc
	v_mul_hi_i32 v98, v114, s30
	v_lshrrev_b32_e32 v137, 31, v98
	v_ashrrev_i32_e32 v98, 11, v98
	v_add_u32_e32 v98, v98, v137
	v_mad_i32_i24 v114, v98, s31, v114
	v_cmp_lt_i32_e64 s[0:1], 15, v114
	s_and_saveexec_b64 s[2:3], s[0:1]
	s_xor_b64 s[0:1], exec, s[2:3]
	v_lshlrev_b32_e32 v98, 12, v98
	v_add3_u32 v168, v98, v114, -16
	v_ashrrev_i32_e32 v169, 31, v168
	v_lshlrev_b64 v[168:169], 12, v[168:169]
	v_lshl_add_u64 v[168:169], s[88:89], 0, v[168:169]
	s_andn2_saveexec_b64 s[0:1], s[0:1]
	v_lshlrev_b32_e32 v98, 14, v98
	v_lshl_add_u32 v168, v114, 10, v98
	v_ashrrev_i32_e32 v169, 31, v168
	v_lshl_add_u64 v[168:169], v[168:169], 2, s[12:13]
	s_or_b64 exec, exec, s[0:1]
	v_ashrrev_i32_e32 v167, 31, v166
	v_lshlrev_b64 v[166:167], 11, v[166:167]
	v_lshl_add_u64 v[166:167], s[62:63], 0, v[166:167]
	s_waitcnt vmcnt(29)
	v_fmac_f32_e32 v181, 0.5, v115
	v_lshl_add_u64 v[114:115], v[130:131], 1, v[166:167]
	v_lshl_add_u64 v[166:167], v[168:169], 0, v[134:135]
	s_and_saveexec_b64 s[0:1], vcc
	s_cbranch_execz .LBB0_737
	global_store_dword v[166:167], v181, off
	v_mul_f32_e32 v98, v181, v242
	v_cvt_pk_bf16_f32 v98, v98, s0
	global_store_short v[114:115], v98, off
.LBB0_737:
	s_or_b64 exec, exec, s[0:1]
	s_waitcnt vmcnt(28)
	v_fmac_f32_e32 v182, 0.5, v99
	s_and_saveexec_b64 s[0:1], vcc
	s_cbranch_execz .LBB0_739
	global_store_dword v[166:167], v182, off offset:128
	v_mul_f32_e32 v98, v182, v243
	v_cvt_pk_bf16_f32 v98, v98, s0
	global_store_short v[114:115], v98, off offset:64
.LBB0_739:
	s_or_b64 exec, exec, s[0:1]
	v_cmp_gt_i32_e32 vcc, s34, v164
	s_nop 1
	v_cndmask_b32_e32 v98, v179, v164, vcc
	v_mul_hi_i32 v99, v98, s30
	v_lshrrev_b32_e32 v114, 31, v99
	v_ashrrev_i32_e32 v99, 11, v99
	v_add_u32_e32 v114, v99, v114
	v_mad_i32_i24 v115, v114, s31, v98
	v_cmp_lt_i32_e64 s[0:1], 15, v115
	s_and_saveexec_b64 s[2:3], s[0:1]
	s_xor_b64 s[0:1], exec, s[2:3]
	v_lshlrev_b32_e32 v98, 12, v114
	v_add3_u32 v98, v98, v115, -16
	v_ashrrev_i32_e32 v99, 31, v98
	v_lshlrev_b64 v[98:99], 12, v[98:99]
	v_lshl_add_u64 v[98:99], s[88:89], 0, v[98:99]
	s_andn2_saveexec_b64 s[0:1], s[0:1]
	v_lshlrev_b32_e32 v98, 14, v114
	v_lshl_add_u32 v98, v115, 10, v98
	v_ashrrev_i32_e32 v99, 31, v98
	v_lshl_add_u64 v[98:99], v[98:99], 2, s[12:13]
	s_or_b64 exec, exec, s[0:1]
	v_ashrrev_i32_e32 v165, 31, v164
	v_lshlrev_b64 v[114:115], 11, v[164:165]
	v_lshl_add_u64 v[114:115], s[62:63], 0, v[114:115]
	s_waitcnt vmcnt(27)
	v_fmac_f32_e32 v183, 0.5, v116
	v_lshl_add_u64 v[114:115], v[130:131], 1, v[114:115]
	v_lshl_add_u64 v[98:99], v[98:99], 0, v[134:135]
	s_and_saveexec_b64 s[0:1], vcc
	s_cbranch_execz .LBB0_745
	global_store_dword v[98:99], v183, off
	v_mul_f32_e32 v116, v183, v242
	v_cvt_pk_bf16_f32 v116, v116, s0
	global_store_short v[114:115], v116, off
.LBB0_745:
	s_or_b64 exec, exec, s[0:1]
	s_waitcnt vmcnt(26)
	v_fmac_f32_e32 v184, 0.5, v100
	s_and_saveexec_b64 s[0:1], vcc
	s_cbranch_execz .LBB0_747
	global_store_dword v[98:99], v184, off offset:128
	v_mul_f32_e32 v98, v184, v243
	v_cvt_pk_bf16_f32 v98, v98, s0
	global_store_short v[114:115], v98, off offset:64
.LBB0_747:
	s_or_b64 exec, exec, s[0:1]
	v_cmp_gt_i32_e32 vcc, s34, v162
	s_nop 1
	v_cndmask_b32_e32 v98, v179, v162, vcc
	v_mul_hi_i32 v99, v98, s30
	v_lshrrev_b32_e32 v100, 31, v99
	v_ashrrev_i32_e32 v99, 11, v99
	v_add_u32_e32 v100, v99, v100
	v_mad_i32_i24 v114, v100, s31, v98
	v_cmp_lt_i32_e64 s[0:1], 15, v114
	s_and_saveexec_b64 s[2:3], s[0:1]
	s_xor_b64 s[0:1], exec, s[2:3]
	v_lshlrev_b32_e32 v98, 12, v100
	v_add3_u32 v98, v98, v114, -16
	v_ashrrev_i32_e32 v99, 31, v98
	v_lshlrev_b64 v[98:99], 12, v[98:99]
	v_lshl_add_u64 v[98:99], s[88:89], 0, v[98:99]
	s_andn2_saveexec_b64 s[0:1], s[0:1]
	v_lshlrev_b32_e32 v98, 14, v100
	v_lshl_add_u32 v98, v114, 10, v98
	v_ashrrev_i32_e32 v99, 31, v98
	v_lshl_add_u64 v[98:99], v[98:99], 2, s[12:13]
	s_or_b64 exec, exec, s[0:1]
	v_ashrrev_i32_e32 v163, 31, v162
	v_lshlrev_b64 v[114:115], 11, v[162:163]
	v_lshl_add_u64 v[114:115], s[62:63], 0, v[114:115]
	s_waitcnt vmcnt(25)
	v_fmac_f32_e32 v185, 0.5, v117
	v_lshl_add_u64 v[114:115], v[130:131], 1, v[114:115]
	v_lshl_add_u64 v[98:99], v[98:99], 0, v[134:135]
	s_and_saveexec_b64 s[0:1], vcc
	s_cbranch_execz .LBB0_753
	global_store_dword v[98:99], v185, off
	v_mul_f32_e32 v100, v185, v242
	v_cvt_pk_bf16_f32 v100, v100, s0
	global_store_short v[114:115], v100, off
.LBB0_753:
	s_or_b64 exec, exec, s[0:1]
	s_waitcnt vmcnt(24)
	v_fmac_f32_e32 v186, 0.5, v101
	s_and_saveexec_b64 s[0:1], vcc
	s_cbranch_execz .LBB0_755
	global_store_dword v[98:99], v186, off offset:128
	v_mul_f32_e32 v98, v186, v243
	v_cvt_pk_bf16_f32 v98, v98, s0
	global_store_short v[114:115], v98, off offset:64
.LBB0_755:
	s_or_b64 exec, exec, s[0:1]
	v_cmp_gt_i32_e32 vcc, s34, v160
	s_nop 1
	v_cndmask_b32_e32 v98, v179, v160, vcc
	v_mul_hi_i32 v99, v98, s30
	v_lshrrev_b32_e32 v100, 31, v99
	v_ashrrev_i32_e32 v99, 11, v99
	v_add_u32_e32 v100, v99, v100
	v_mad_i32_i24 v101, v100, s31, v98
	v_cmp_lt_i32_e64 s[0:1], 15, v101
	s_and_saveexec_b64 s[2:3], s[0:1]
	s_xor_b64 s[0:1], exec, s[2:3]
	v_lshlrev_b32_e32 v98, 12, v100
	v_add3_u32 v98, v98, v101, -16
	v_ashrrev_i32_e32 v99, 31, v98
	v_lshlrev_b64 v[98:99], 12, v[98:99]
	v_lshl_add_u64 v[98:99], s[88:89], 0, v[98:99]
	s_andn2_saveexec_b64 s[0:1], s[0:1]
	v_lshlrev_b32_e32 v98, 14, v100
	v_lshl_add_u32 v98, v101, 10, v98
	v_ashrrev_i32_e32 v99, 31, v98
	v_lshl_add_u64 v[98:99], v[98:99], 2, s[12:13]
	s_or_b64 exec, exec, s[0:1]
	v_ashrrev_i32_e32 v161, 31, v160
	v_lshlrev_b64 v[100:101], 11, v[160:161]
	v_lshl_add_u64 v[100:101], s[62:63], 0, v[100:101]
	s_waitcnt vmcnt(23)
	v_fmac_f32_e32 v187, 0.5, v118
	v_lshl_add_u64 v[100:101], v[130:131], 1, v[100:101]
	v_lshl_add_u64 v[98:99], v[98:99], 0, v[134:135]
	s_and_saveexec_b64 s[0:1], vcc
	s_cbranch_execz .LBB0_761
	global_store_dword v[98:99], v187, off
	v_mul_f32_e32 v114, v187, v242
	v_cvt_pk_bf16_f32 v114, v114, s0
	global_store_short v[100:101], v114, off
.LBB0_761:
	s_or_b64 exec, exec, s[0:1]
	s_waitcnt vmcnt(22)
	v_fmac_f32_e32 v188, 0.5, v102
	s_and_saveexec_b64 s[0:1], vcc
	s_cbranch_execz .LBB0_763
	global_store_dword v[98:99], v188, off offset:128
	v_mul_f32_e32 v98, v188, v243
	v_cvt_pk_bf16_f32 v98, v98, s0
	global_store_short v[100:101], v98, off offset:64
.LBB0_763:
	s_or_b64 exec, exec, s[0:1]
	v_cmp_gt_i32_e32 vcc, s34, v158
	s_nop 1
	v_cndmask_b32_e32 v98, v179, v158, vcc
	v_mul_hi_i32 v99, v98, s30
	v_lshrrev_b32_e32 v100, 31, v99
	v_ashrrev_i32_e32 v99, 11, v99
	v_add_u32_e32 v100, v99, v100
	v_mad_i32_i24 v101, v100, s31, v98
	v_cmp_lt_i32_e64 s[0:1], 15, v101
	s_and_saveexec_b64 s[2:3], s[0:1]
	s_xor_b64 s[0:1], exec, s[2:3]
	v_lshlrev_b32_e32 v98, 12, v100
	v_add3_u32 v98, v98, v101, -16
	v_ashrrev_i32_e32 v99, 31, v98
	v_lshlrev_b64 v[98:99], 12, v[98:99]
	v_lshl_add_u64 v[98:99], s[88:89], 0, v[98:99]
	s_andn2_saveexec_b64 s[0:1], s[0:1]
	v_lshlrev_b32_e32 v98, 14, v100
	v_lshl_add_u32 v98, v101, 10, v98
	v_ashrrev_i32_e32 v99, 31, v98
	v_lshl_add_u64 v[98:99], v[98:99], 2, s[12:13]
	s_or_b64 exec, exec, s[0:1]
	v_ashrrev_i32_e32 v159, 31, v158
	v_lshlrev_b64 v[100:101], 11, v[158:159]
	v_lshl_add_u64 v[100:101], s[62:63], 0, v[100:101]
	s_waitcnt vmcnt(21)
	v_fmac_f32_e32 v189, 0.5, v119
	v_lshl_add_u64 v[100:101], v[130:131], 1, v[100:101]
	v_lshl_add_u64 v[98:99], v[98:99], 0, v[134:135]
	s_and_saveexec_b64 s[0:1], vcc
	s_cbranch_execz .LBB0_769
	global_store_dword v[98:99], v189, off
	v_mul_f32_e32 v102, v189, v242
	v_cvt_pk_bf16_f32 v102, v102, s0
	global_store_short v[100:101], v102, off
.LBB0_769:
	s_or_b64 exec, exec, s[0:1]
	s_waitcnt vmcnt(20)
	v_fmac_f32_e32 v190, 0.5, v103
	s_and_saveexec_b64 s[0:1], vcc
	s_cbranch_execz .LBB0_771
	global_store_dword v[98:99], v190, off offset:128
	v_mul_f32_e32 v98, v190, v243
	v_cvt_pk_bf16_f32 v98, v98, s0
	global_store_short v[100:101], v98, off offset:64
.LBB0_771:
	s_or_b64 exec, exec, s[0:1]
	v_cmp_gt_i32_e32 vcc, s34, v156
	s_nop 1
	v_cndmask_b32_e32 v98, v179, v156, vcc
	v_mul_hi_i32 v99, v98, s30
	v_lshrrev_b32_e32 v100, 31, v99
	v_ashrrev_i32_e32 v99, 11, v99
	v_add_u32_e32 v100, v99, v100
	v_mad_i32_i24 v101, v100, s31, v98
	v_cmp_lt_i32_e64 s[0:1], 15, v101
	s_and_saveexec_b64 s[2:3], s[0:1]
	s_xor_b64 s[0:1], exec, s[2:3]
	v_lshlrev_b32_e32 v98, 12, v100
	v_add3_u32 v98, v98, v101, -16
	v_ashrrev_i32_e32 v99, 31, v98
	v_lshlrev_b64 v[98:99], 12, v[98:99]
	v_lshl_add_u64 v[98:99], s[88:89], 0, v[98:99]
	s_andn2_saveexec_b64 s[0:1], s[0:1]
	v_lshlrev_b32_e32 v98, 14, v100
	v_lshl_add_u32 v98, v101, 10, v98
	v_ashrrev_i32_e32 v99, 31, v98
	v_lshl_add_u64 v[98:99], v[98:99], 2, s[12:13]
	s_or_b64 exec, exec, s[0:1]
	v_ashrrev_i32_e32 v157, 31, v156
	v_lshlrev_b64 v[100:101], 11, v[156:157]
	v_lshl_add_u64 v[100:101], s[62:63], 0, v[100:101]
	s_waitcnt vmcnt(19)
	v_fmac_f32_e32 v191, 0.5, v120
	v_lshl_add_u64 v[100:101], v[130:131], 1, v[100:101]
	v_lshl_add_u64 v[98:99], v[98:99], 0, v[134:135]
	s_and_saveexec_b64 s[0:1], vcc
	s_cbranch_execz .LBB0_777
	global_store_dword v[98:99], v191, off
	v_mul_f32_e32 v102, v191, v242
	v_cvt_pk_bf16_f32 v102, v102, s0
	global_store_short v[100:101], v102, off
.LBB0_777:
	s_or_b64 exec, exec, s[0:1]
	s_waitcnt vmcnt(18)
	v_fmac_f32_e32 v192, 0.5, v104
	s_and_saveexec_b64 s[0:1], vcc
	s_cbranch_execz .LBB0_779
	global_store_dword v[98:99], v192, off offset:128
	v_mul_f32_e32 v98, v192, v243
	v_cvt_pk_bf16_f32 v98, v98, s0
	global_store_short v[100:101], v98, off offset:64
.LBB0_779:
	s_or_b64 exec, exec, s[0:1]
	v_cmp_gt_i32_e32 vcc, s34, v154
	s_nop 1
	v_cndmask_b32_e32 v98, v179, v154, vcc
	v_mul_hi_i32 v99, v98, s30
	v_lshrrev_b32_e32 v100, 31, v99
	v_ashrrev_i32_e32 v99, 11, v99
	v_add_u32_e32 v100, v99, v100
	v_mad_i32_i24 v101, v100, s31, v98
	v_cmp_lt_i32_e64 s[0:1], 15, v101
	s_and_saveexec_b64 s[2:3], s[0:1]
	s_xor_b64 s[0:1], exec, s[2:3]
	v_lshlrev_b32_e32 v98, 12, v100
	v_add3_u32 v98, v98, v101, -16
	v_ashrrev_i32_e32 v99, 31, v98
	v_lshlrev_b64 v[98:99], 12, v[98:99]
	v_lshl_add_u64 v[98:99], s[88:89], 0, v[98:99]
	s_andn2_saveexec_b64 s[0:1], s[0:1]
	v_lshlrev_b32_e32 v98, 14, v100
	v_lshl_add_u32 v98, v101, 10, v98
	v_ashrrev_i32_e32 v99, 31, v98
	v_lshl_add_u64 v[98:99], v[98:99], 2, s[12:13]
	s_or_b64 exec, exec, s[0:1]
	v_ashrrev_i32_e32 v155, 31, v154
	v_lshlrev_b64 v[100:101], 11, v[154:155]
	v_lshl_add_u64 v[100:101], s[62:63], 0, v[100:101]
	s_waitcnt vmcnt(17)
	v_fmac_f32_e32 v193, 0.5, v121
	v_lshl_add_u64 v[100:101], v[130:131], 1, v[100:101]
	v_lshl_add_u64 v[98:99], v[98:99], 0, v[134:135]
	s_and_saveexec_b64 s[0:1], vcc
	s_cbranch_execz .LBB0_785
	global_store_dword v[98:99], v193, off
	v_mul_f32_e32 v102, v193, v242
	v_cvt_pk_bf16_f32 v102, v102, s0
	global_store_short v[100:101], v102, off
.LBB0_785:
	s_or_b64 exec, exec, s[0:1]
	s_waitcnt vmcnt(16)
	v_fmac_f32_e32 v194, 0.5, v105
	s_and_saveexec_b64 s[0:1], vcc
	s_cbranch_execz .LBB0_787
	global_store_dword v[98:99], v194, off offset:128
	v_mul_f32_e32 v98, v194, v243
	v_cvt_pk_bf16_f32 v98, v98, s0
	global_store_short v[100:101], v98, off offset:64
.LBB0_787:
	s_or_b64 exec, exec, s[0:1]
	v_cmp_gt_i32_e32 vcc, s34, v152
	s_nop 1
	v_cndmask_b32_e32 v98, v179, v152, vcc
	v_mul_hi_i32 v99, v98, s30
	v_lshrrev_b32_e32 v100, 31, v99
	v_ashrrev_i32_e32 v99, 11, v99
	v_add_u32_e32 v100, v99, v100
	v_mad_i32_i24 v101, v100, s31, v98
	v_cmp_lt_i32_e64 s[0:1], 15, v101
	s_and_saveexec_b64 s[2:3], s[0:1]
	s_xor_b64 s[0:1], exec, s[2:3]
	v_lshlrev_b32_e32 v98, 12, v100
	v_add3_u32 v98, v98, v101, -16
	v_ashrrev_i32_e32 v99, 31, v98
	v_lshlrev_b64 v[98:99], 12, v[98:99]
	v_lshl_add_u64 v[98:99], s[88:89], 0, v[98:99]
	s_andn2_saveexec_b64 s[0:1], s[0:1]
	v_lshlrev_b32_e32 v98, 14, v100
	v_lshl_add_u32 v98, v101, 10, v98
	v_ashrrev_i32_e32 v99, 31, v98
	v_lshl_add_u64 v[98:99], v[98:99], 2, s[12:13]
	s_or_b64 exec, exec, s[0:1]
	v_ashrrev_i32_e32 v153, 31, v152
	v_lshlrev_b64 v[100:101], 11, v[152:153]
	v_lshl_add_u64 v[100:101], s[62:63], 0, v[100:101]
	s_waitcnt vmcnt(15)
	v_fmac_f32_e32 v195, 0.5, v122
	v_lshl_add_u64 v[100:101], v[130:131], 1, v[100:101]
	v_lshl_add_u64 v[98:99], v[98:99], 0, v[134:135]
	s_and_saveexec_b64 s[0:1], vcc
	s_cbranch_execz .LBB0_793
	global_store_dword v[98:99], v195, off
	v_mul_f32_e32 v102, v195, v242
	v_cvt_pk_bf16_f32 v102, v102, s0
	global_store_short v[100:101], v102, off
.LBB0_793:
	s_or_b64 exec, exec, s[0:1]
	s_waitcnt vmcnt(14)
	v_fmac_f32_e32 v196, 0.5, v106
	s_and_saveexec_b64 s[0:1], vcc
	s_cbranch_execz .LBB0_795
	global_store_dword v[98:99], v196, off offset:128
	v_mul_f32_e32 v98, v196, v243
	v_cvt_pk_bf16_f32 v98, v98, s0
	global_store_short v[100:101], v98, off offset:64
.LBB0_795:
	s_or_b64 exec, exec, s[0:1]
	v_cmp_gt_i32_e32 vcc, s34, v150
	s_nop 1
	v_cndmask_b32_e32 v98, v179, v150, vcc
	v_mul_hi_i32 v99, v98, s30
	v_lshrrev_b32_e32 v100, 31, v99
	v_ashrrev_i32_e32 v99, 11, v99
	v_add_u32_e32 v100, v99, v100
	v_mad_i32_i24 v101, v100, s31, v98
	v_cmp_lt_i32_e64 s[0:1], 15, v101
	s_and_saveexec_b64 s[2:3], s[0:1]
	s_xor_b64 s[0:1], exec, s[2:3]
	v_lshlrev_b32_e32 v98, 12, v100
	v_add3_u32 v98, v98, v101, -16
	v_ashrrev_i32_e32 v99, 31, v98
	v_lshlrev_b64 v[98:99], 12, v[98:99]
	v_lshl_add_u64 v[98:99], s[88:89], 0, v[98:99]
	s_andn2_saveexec_b64 s[0:1], s[0:1]
	v_lshlrev_b32_e32 v98, 14, v100
	v_lshl_add_u32 v98, v101, 10, v98
	v_ashrrev_i32_e32 v99, 31, v98
	v_lshl_add_u64 v[98:99], v[98:99], 2, s[12:13]
	s_or_b64 exec, exec, s[0:1]
	v_ashrrev_i32_e32 v151, 31, v150
	v_lshlrev_b64 v[100:101], 11, v[150:151]
	v_lshl_add_u64 v[100:101], s[62:63], 0, v[100:101]
	s_waitcnt vmcnt(13)
	v_fmac_f32_e32 v197, 0.5, v123
	v_lshl_add_u64 v[100:101], v[130:131], 1, v[100:101]
	v_lshl_add_u64 v[98:99], v[98:99], 0, v[134:135]
	s_and_saveexec_b64 s[0:1], vcc
	s_cbranch_execz .LBB0_801
	global_store_dword v[98:99], v197, off
	v_mul_f32_e32 v102, v197, v242
	v_cvt_pk_bf16_f32 v102, v102, s0
	global_store_short v[100:101], v102, off
.LBB0_801:
	s_or_b64 exec, exec, s[0:1]
	s_waitcnt vmcnt(12)
	v_fmac_f32_e32 v198, 0.5, v107
	s_and_saveexec_b64 s[0:1], vcc
	s_cbranch_execz .LBB0_803
	global_store_dword v[98:99], v198, off offset:128
	v_mul_f32_e32 v98, v198, v243
	v_cvt_pk_bf16_f32 v98, v98, s0
	global_store_short v[100:101], v98, off offset:64
.LBB0_803:
	s_or_b64 exec, exec, s[0:1]
	v_cmp_gt_i32_e32 vcc, s34, v148
	s_nop 1
	v_cndmask_b32_e32 v98, v179, v148, vcc
	v_mul_hi_i32 v99, v98, s30
	v_lshrrev_b32_e32 v100, 31, v99
	v_ashrrev_i32_e32 v99, 11, v99
	v_add_u32_e32 v100, v99, v100
	v_mad_i32_i24 v101, v100, s31, v98
	v_cmp_lt_i32_e64 s[0:1], 15, v101
	s_and_saveexec_b64 s[2:3], s[0:1]
	s_xor_b64 s[0:1], exec, s[2:3]
	v_lshlrev_b32_e32 v98, 12, v100
	v_add3_u32 v98, v98, v101, -16
	v_ashrrev_i32_e32 v99, 31, v98
	v_lshlrev_b64 v[98:99], 12, v[98:99]
	v_lshl_add_u64 v[98:99], s[88:89], 0, v[98:99]
	s_andn2_saveexec_b64 s[0:1], s[0:1]
	v_lshlrev_b32_e32 v98, 14, v100
	v_lshl_add_u32 v98, v101, 10, v98
	v_ashrrev_i32_e32 v99, 31, v98
	v_lshl_add_u64 v[98:99], v[98:99], 2, s[12:13]
	s_or_b64 exec, exec, s[0:1]
	v_ashrrev_i32_e32 v149, 31, v148
	v_lshlrev_b64 v[100:101], 11, v[148:149]
	v_lshl_add_u64 v[100:101], s[62:63], 0, v[100:101]
	s_waitcnt vmcnt(11)
	v_fmac_f32_e32 v199, 0.5, v124
	v_lshl_add_u64 v[100:101], v[130:131], 1, v[100:101]
	v_lshl_add_u64 v[98:99], v[98:99], 0, v[134:135]
	s_and_saveexec_b64 s[0:1], vcc
	s_cbranch_execz .LBB0_809
	global_store_dword v[98:99], v199, off
	v_mul_f32_e32 v102, v199, v242
	v_cvt_pk_bf16_f32 v102, v102, s0
	global_store_short v[100:101], v102, off
.LBB0_809:
	s_or_b64 exec, exec, s[0:1]
	s_waitcnt vmcnt(10)
	v_fmac_f32_e32 v200, 0.5, v108
	s_and_saveexec_b64 s[0:1], vcc
	s_cbranch_execz .LBB0_811
	global_store_dword v[98:99], v200, off offset:128
	v_mul_f32_e32 v98, v200, v243
	v_cvt_pk_bf16_f32 v98, v98, s0
	global_store_short v[100:101], v98, off offset:64
.LBB0_811:
	s_or_b64 exec, exec, s[0:1]
	v_cmp_gt_i32_e32 vcc, s34, v146
	s_nop 1
	v_cndmask_b32_e32 v98, v179, v146, vcc
	v_mul_hi_i32 v99, v98, s30
	v_lshrrev_b32_e32 v100, 31, v99
	v_ashrrev_i32_e32 v99, 11, v99
	v_add_u32_e32 v100, v99, v100
	v_mad_i32_i24 v101, v100, s31, v98
	v_cmp_lt_i32_e64 s[0:1], 15, v101
	s_and_saveexec_b64 s[2:3], s[0:1]
	s_xor_b64 s[0:1], exec, s[2:3]
	v_lshlrev_b32_e32 v98, 12, v100
	v_add3_u32 v98, v98, v101, -16
	v_ashrrev_i32_e32 v99, 31, v98
	v_lshlrev_b64 v[98:99], 12, v[98:99]
	v_lshl_add_u64 v[98:99], s[88:89], 0, v[98:99]
	s_andn2_saveexec_b64 s[0:1], s[0:1]
	v_lshlrev_b32_e32 v98, 14, v100
	v_lshl_add_u32 v98, v101, 10, v98
	v_ashrrev_i32_e32 v99, 31, v98
	v_lshl_add_u64 v[98:99], v[98:99], 2, s[12:13]
	s_or_b64 exec, exec, s[0:1]
	v_ashrrev_i32_e32 v147, 31, v146
	v_lshlrev_b64 v[100:101], 11, v[146:147]
	v_lshl_add_u64 v[100:101], s[62:63], 0, v[100:101]
	s_waitcnt vmcnt(9)
	v_fmac_f32_e32 v201, 0.5, v125
	v_lshl_add_u64 v[100:101], v[130:131], 1, v[100:101]
	v_lshl_add_u64 v[98:99], v[98:99], 0, v[134:135]
	s_and_saveexec_b64 s[0:1], vcc
	s_cbranch_execz .LBB0_817
	global_store_dword v[98:99], v201, off
	v_mul_f32_e32 v102, v201, v242
	v_cvt_pk_bf16_f32 v102, v102, s0
	global_store_short v[100:101], v102, off
.LBB0_817:
	s_or_b64 exec, exec, s[0:1]
	s_waitcnt vmcnt(8)
	v_fmac_f32_e32 v202, 0.5, v109
	s_and_saveexec_b64 s[0:1], vcc
	s_cbranch_execz .LBB0_819
	global_store_dword v[98:99], v202, off offset:128
	v_mul_f32_e32 v98, v202, v243
	v_cvt_pk_bf16_f32 v98, v98, s0
	global_store_short v[100:101], v98, off offset:64
.LBB0_819:
	s_or_b64 exec, exec, s[0:1]
	v_cmp_gt_i32_e32 vcc, s34, v144
	s_nop 1
	v_cndmask_b32_e32 v98, v179, v144, vcc
	v_mul_hi_i32 v99, v98, s30
	v_lshrrev_b32_e32 v100, 31, v99
	v_ashrrev_i32_e32 v99, 11, v99
	v_add_u32_e32 v100, v99, v100
	v_mad_i32_i24 v101, v100, s31, v98
	v_cmp_lt_i32_e64 s[0:1], 15, v101
	s_and_saveexec_b64 s[2:3], s[0:1]
	s_xor_b64 s[0:1], exec, s[2:3]
	v_lshlrev_b32_e32 v98, 12, v100
	v_add3_u32 v98, v98, v101, -16
	v_ashrrev_i32_e32 v99, 31, v98
	v_lshlrev_b64 v[98:99], 12, v[98:99]
	v_lshl_add_u64 v[98:99], s[88:89], 0, v[98:99]
	s_andn2_saveexec_b64 s[0:1], s[0:1]
	v_lshlrev_b32_e32 v98, 14, v100
	v_lshl_add_u32 v98, v101, 10, v98
	v_ashrrev_i32_e32 v99, 31, v98
	v_lshl_add_u64 v[98:99], v[98:99], 2, s[12:13]
	s_or_b64 exec, exec, s[0:1]
	v_ashrrev_i32_e32 v145, 31, v144
	v_lshlrev_b64 v[100:101], 11, v[144:145]
	v_lshl_add_u64 v[100:101], s[62:63], 0, v[100:101]
	s_waitcnt vmcnt(7)
	v_fmac_f32_e32 v203, 0.5, v126
	v_lshl_add_u64 v[100:101], v[130:131], 1, v[100:101]
	v_lshl_add_u64 v[98:99], v[98:99], 0, v[134:135]
	s_and_saveexec_b64 s[0:1], vcc
	s_cbranch_execz .LBB0_825
	global_store_dword v[98:99], v203, off
	v_mul_f32_e32 v102, v203, v242
	v_cvt_pk_bf16_f32 v102, v102, s0
	global_store_short v[100:101], v102, off
.LBB0_825:
	s_or_b64 exec, exec, s[0:1]
	s_waitcnt vmcnt(6)
	v_fmac_f32_e32 v204, 0.5, v110
	s_and_saveexec_b64 s[0:1], vcc
	s_cbranch_execz .LBB0_827
	global_store_dword v[98:99], v204, off offset:128
	v_mul_f32_e32 v98, v204, v243
	v_cvt_pk_bf16_f32 v98, v98, s0
	global_store_short v[100:101], v98, off offset:64
.LBB0_827:
	s_or_b64 exec, exec, s[0:1]
	v_cmp_gt_i32_e32 vcc, s34, v142
	s_nop 1
	v_cndmask_b32_e32 v98, v179, v142, vcc
	v_mul_hi_i32 v99, v98, s30
	v_lshrrev_b32_e32 v100, 31, v99
	v_ashrrev_i32_e32 v99, 11, v99
	v_add_u32_e32 v100, v99, v100
	v_mad_i32_i24 v101, v100, s31, v98
	v_cmp_lt_i32_e64 s[0:1], 15, v101
	s_and_saveexec_b64 s[2:3], s[0:1]
	s_xor_b64 s[0:1], exec, s[2:3]
	v_lshlrev_b32_e32 v98, 12, v100
	v_add3_u32 v98, v98, v101, -16
	v_ashrrev_i32_e32 v99, 31, v98
	v_lshlrev_b64 v[98:99], 12, v[98:99]
	v_lshl_add_u64 v[98:99], s[88:89], 0, v[98:99]
	s_andn2_saveexec_b64 s[0:1], s[0:1]
	v_lshlrev_b32_e32 v98, 14, v100
	v_lshl_add_u32 v98, v101, 10, v98
	v_ashrrev_i32_e32 v99, 31, v98
	v_lshl_add_u64 v[98:99], v[98:99], 2, s[12:13]
	s_or_b64 exec, exec, s[0:1]
	v_ashrrev_i32_e32 v143, 31, v142
	v_lshlrev_b64 v[100:101], 11, v[142:143]
	v_lshl_add_u64 v[100:101], s[62:63], 0, v[100:101]
	s_waitcnt vmcnt(5)
	v_fmac_f32_e32 v205, 0.5, v127
	v_lshl_add_u64 v[100:101], v[130:131], 1, v[100:101]
	v_lshl_add_u64 v[98:99], v[98:99], 0, v[134:135]
	s_and_saveexec_b64 s[0:1], vcc
	s_cbranch_execz .LBB0_833
	global_store_dword v[98:99], v205, off
	v_mul_f32_e32 v102, v205, v242
	v_cvt_pk_bf16_f32 v102, v102, s0
	global_store_short v[100:101], v102, off
.LBB0_833:
	s_or_b64 exec, exec, s[0:1]
	s_waitcnt vmcnt(4)
	v_fmac_f32_e32 v206, 0.5, v111
	s_and_saveexec_b64 s[0:1], vcc
	s_cbranch_execz .LBB0_835
	global_store_dword v[98:99], v206, off offset:128
	v_mul_f32_e32 v98, v206, v243
	v_cvt_pk_bf16_f32 v98, v98, s0
	global_store_short v[100:101], v98, off offset:64
.LBB0_835:
	s_or_b64 exec, exec, s[0:1]
	v_cmp_gt_i32_e32 vcc, s34, v140
	s_nop 1
	v_cndmask_b32_e32 v98, v179, v140, vcc
	v_mul_hi_i32 v99, v98, s30
	v_lshrrev_b32_e32 v100, 31, v99
	v_ashrrev_i32_e32 v99, 11, v99
	v_add_u32_e32 v100, v99, v100
	v_mad_i32_i24 v101, v100, s31, v98
	v_cmp_lt_i32_e64 s[0:1], 15, v101
	s_and_saveexec_b64 s[2:3], s[0:1]
	s_xor_b64 s[0:1], exec, s[2:3]
	v_lshlrev_b32_e32 v98, 12, v100
	v_add3_u32 v98, v98, v101, -16
	v_ashrrev_i32_e32 v99, 31, v98
	v_lshlrev_b64 v[98:99], 12, v[98:99]
	v_lshl_add_u64 v[98:99], s[88:89], 0, v[98:99]
	s_andn2_saveexec_b64 s[0:1], s[0:1]
	v_lshlrev_b32_e32 v98, 14, v100
	v_lshl_add_u32 v98, v101, 10, v98
	v_ashrrev_i32_e32 v99, 31, v98
	v_lshl_add_u64 v[98:99], v[98:99], 2, s[12:13]
	s_or_b64 exec, exec, s[0:1]
	v_ashrrev_i32_e32 v141, 31, v140
	v_lshlrev_b64 v[100:101], 11, v[140:141]
	v_lshl_add_u64 v[100:101], s[62:63], 0, v[100:101]
	s_waitcnt vmcnt(3)
	v_fmac_f32_e32 v207, 0.5, v128
	v_lshl_add_u64 v[100:101], v[130:131], 1, v[100:101]
	v_lshl_add_u64 v[98:99], v[98:99], 0, v[134:135]
	s_and_saveexec_b64 s[0:1], vcc
	s_cbranch_execz .LBB0_841
	global_store_dword v[98:99], v207, off
	v_mul_f32_e32 v102, v207, v242
	v_cvt_pk_bf16_f32 v102, v102, s0
	global_store_short v[100:101], v102, off
.LBB0_841:
	s_or_b64 exec, exec, s[0:1]
	s_waitcnt vmcnt(2)
	v_fmac_f32_e32 v210, 0.5, v112
	s_and_saveexec_b64 s[0:1], vcc
	s_cbranch_execz .LBB0_843
	global_store_dword v[98:99], v210, off offset:128
	v_mul_f32_e32 v98, v210, v243
	v_cvt_pk_bf16_f32 v98, v98, s0
	global_store_short v[100:101], v98, off offset:64
.LBB0_843:
	s_or_b64 exec, exec, s[0:1]
	v_cmp_gt_i32_e32 vcc, s34, v138
	s_nop 1
	v_cndmask_b32_e32 v98, v179, v138, vcc
	v_mul_hi_i32 v99, v98, s30
	v_lshrrev_b32_e32 v100, 31, v99
	v_ashrrev_i32_e32 v99, 11, v99
	v_add_u32_e32 v100, v99, v100
	v_mad_i32_i24 v101, v100, s31, v98
	v_cmp_lt_i32_e64 s[0:1], 15, v101
	s_and_saveexec_b64 s[2:3], s[0:1]
	s_xor_b64 s[0:1], exec, s[2:3]
	v_lshlrev_b32_e32 v98, 12, v100
	v_add3_u32 v98, v98, v101, -16
	v_ashrrev_i32_e32 v99, 31, v98
	v_lshlrev_b64 v[98:99], 12, v[98:99]
	v_lshl_add_u64 v[98:99], s[88:89], 0, v[98:99]
	s_andn2_saveexec_b64 s[0:1], s[0:1]
	v_lshlrev_b32_e32 v98, 14, v100
	v_lshl_add_u32 v98, v101, 10, v98
	v_ashrrev_i32_e32 v99, 31, v98
	v_lshl_add_u64 v[98:99], v[98:99], 2, s[12:13]
	s_or_b64 exec, exec, s[0:1]
	v_ashrrev_i32_e32 v139, 31, v138
	v_lshlrev_b64 v[100:101], 11, v[138:139]
	v_lshl_add_u64 v[100:101], s[62:63], 0, v[100:101]
	s_waitcnt vmcnt(1)
	v_fmac_f32_e32 v211, 0.5, v129
	v_lshl_add_u64 v[100:101], v[130:131], 1, v[100:101]
	v_lshl_add_u64 v[98:99], v[98:99], 0, v[134:135]
	s_and_saveexec_b64 s[0:1], vcc
	s_cbranch_execz .LBB0_849
	global_store_dword v[98:99], v211, off
	v_mul_f32_e32 v102, v211, v242
	v_cvt_pk_bf16_f32 v102, v102, s0
	global_store_short v[100:101], v102, off
.LBB0_849:
	s_or_b64 exec, exec, s[0:1]
	s_waitcnt vmcnt(0)
	v_fmac_f32_e32 v212, 0.5, v113
	s_and_saveexec_b64 s[0:1], vcc
	s_cbranch_execz .LBB0_851
	global_store_dword v[98:99], v212, off offset:128
	v_mul_f32_e32 v98, v212, v243
	v_cvt_pk_bf16_f32 v98, v98, s0
	global_store_short v[100:101], v98, off offset:64
.LBB0_851:
	s_or_b64 exec, exec, s[0:1]
	v_or_b32_e32 v128, 32, v136
	v_min_i32_e32 v98, 0x403f, v128
	v_mul_hi_i32 v99, v98, s30
	v_lshrrev_b32_e32 v100, 31, v99
	v_ashrrev_i32_e32 v99, 11, v99
	v_add_u32_e32 v101, v99, v100
	v_mad_i32_i24 v100, v101, s31, v98
	v_cmp_lt_i32_e32 vcc, 15, v100
	s_and_saveexec_b64 s[0:1], vcc
	s_xor_b64 s[0:1], exec, s[0:1]
	v_lshlrev_b32_e32 v98, 12, v101
	v_add3_u32 v98, v98, v100, -16
	v_ashrrev_i32_e32 v99, 31, v98
	v_lshlrev_b64 v[98:99], 12, v[98:99]
	v_lshl_add_u64 v[98:99], s[56:57], 0, v[98:99]
	s_andn2_saveexec_b64 s[0:1], s[0:1]
	v_lshlrev_b32_e32 v98, 10, v100
	v_ashrrev_i32_e32 v99, 31, v98
	v_lshl_add_u64 v[98:99], v[98:99], 2, s[58:59]
	s_or_b64 exec, exec, s[0:1]
	v_lshl_add_u64 v[98:99], v[130:131], 2, v[98:99]
	global_load_dword v137, v[98:99], off
	global_load_dword v140, v[98:99], off offset:128
	v_or_b32_e32 v126, 33, v136
	v_min_i32_e32 v98, 0x403f, v126
	v_mul_hi_i32 v99, v98, s30
	v_lshrrev_b32_e32 v100, 31, v99
	v_ashrrev_i32_e32 v99, 11, v99
	v_add_u32_e32 v101, v99, v100
	v_mad_i32_i24 v100, v101, s31, v98
	v_cmp_lt_i32_e32 vcc, 15, v100
	s_and_saveexec_b64 s[0:1], vcc
	s_xor_b64 s[0:1], exec, s[0:1]
	v_lshlrev_b32_e32 v98, 12, v101
	v_add3_u32 v98, v98, v100, -16
	v_ashrrev_i32_e32 v99, 31, v98
	v_lshlrev_b64 v[98:99], 12, v[98:99]
	v_lshl_add_u64 v[98:99], s[56:57], 0, v[98:99]
	s_andn2_saveexec_b64 s[0:1], s[0:1]
	v_lshlrev_b32_e32 v98, 10, v100
	v_ashrrev_i32_e32 v99, 31, v98
	v_lshl_add_u64 v[98:99], v[98:99], 2, s[58:59]
	s_or_b64 exec, exec, s[0:1]
	v_lshl_add_u64 v[98:99], v[130:131], 2, v[98:99]
	global_load_dword v141, v[98:99], off
	global_load_dword v142, v[98:99], off offset:128
	v_or_b32_e32 v124, 34, v136
	v_min_i32_e32 v98, 0x403f, v124
	v_mul_hi_i32 v99, v98, s30
	v_lshrrev_b32_e32 v100, 31, v99
	v_ashrrev_i32_e32 v99, 11, v99
	v_add_u32_e32 v101, v99, v100
	v_mad_i32_i24 v100, v101, s31, v98
	v_cmp_lt_i32_e32 vcc, 15, v100
	s_and_saveexec_b64 s[0:1], vcc
	s_xor_b64 s[0:1], exec, s[0:1]
	v_lshlrev_b32_e32 v98, 12, v101
	v_add3_u32 v98, v98, v100, -16
	v_ashrrev_i32_e32 v99, 31, v98
	v_lshlrev_b64 v[98:99], 12, v[98:99]
	v_lshl_add_u64 v[98:99], s[56:57], 0, v[98:99]
	s_andn2_saveexec_b64 s[0:1], s[0:1]
	v_lshlrev_b32_e32 v98, 10, v100
	v_ashrrev_i32_e32 v99, 31, v98
	v_lshl_add_u64 v[98:99], v[98:99], 2, s[58:59]
	s_or_b64 exec, exec, s[0:1]
	v_lshl_add_u64 v[98:99], v[130:131], 2, v[98:99]
	global_load_dword v143, v[98:99], off
	global_load_dword v144, v[98:99], off offset:128
	v_or_b32_e32 v122, 35, v136
	v_min_i32_e32 v98, 0x403f, v122
	v_mul_hi_i32 v99, v98, s30
	v_lshrrev_b32_e32 v100, 31, v99
	v_ashrrev_i32_e32 v99, 11, v99
	v_add_u32_e32 v101, v99, v100
	v_mad_i32_i24 v100, v101, s31, v98
	v_cmp_lt_i32_e32 vcc, 15, v100
	s_and_saveexec_b64 s[0:1], vcc
	s_xor_b64 s[0:1], exec, s[0:1]
	v_lshlrev_b32_e32 v98, 12, v101
	v_add3_u32 v98, v98, v100, -16
	v_ashrrev_i32_e32 v99, 31, v98
	v_lshlrev_b64 v[98:99], 12, v[98:99]
	v_lshl_add_u64 v[98:99], s[56:57], 0, v[98:99]
	s_andn2_saveexec_b64 s[0:1], s[0:1]
	v_lshlrev_b32_e32 v98, 10, v100
	v_ashrrev_i32_e32 v99, 31, v98
	v_lshl_add_u64 v[98:99], v[98:99], 2, s[58:59]
	s_or_b64 exec, exec, s[0:1]
	v_lshl_add_u64 v[98:99], v[130:131], 2, v[98:99]
	global_load_dword v145, v[98:99], off
	global_load_dword v146, v[98:99], off offset:128
	v_or_b32_e32 v120, 40, v136
	v_min_i32_e32 v98, 0x403f, v120
	v_mul_hi_i32 v99, v98, s30
	v_lshrrev_b32_e32 v100, 31, v99
	v_ashrrev_i32_e32 v99, 11, v99
	v_add_u32_e32 v101, v99, v100
	v_mad_i32_i24 v100, v101, s31, v98
	v_cmp_lt_i32_e32 vcc, 15, v100
	s_and_saveexec_b64 s[0:1], vcc
	s_xor_b64 s[0:1], exec, s[0:1]
	v_lshlrev_b32_e32 v98, 12, v101
	v_add3_u32 v98, v98, v100, -16
	v_ashrrev_i32_e32 v99, 31, v98
	v_lshlrev_b64 v[98:99], 12, v[98:99]
	v_lshl_add_u64 v[98:99], s[56:57], 0, v[98:99]
	s_andn2_saveexec_b64 s[0:1], s[0:1]
	v_lshlrev_b32_e32 v98, 10, v100
	v_ashrrev_i32_e32 v99, 31, v98
	v_lshl_add_u64 v[98:99], v[98:99], 2, s[58:59]
	s_or_b64 exec, exec, s[0:1]
	v_lshl_add_u64 v[98:99], v[130:131], 2, v[98:99]
	global_load_dword v147, v[98:99], off
	global_load_dword v148, v[98:99], off offset:128
	v_or_b32_e32 v118, 41, v136
	v_min_i32_e32 v98, 0x403f, v118
	v_mul_hi_i32 v99, v98, s30
	v_lshrrev_b32_e32 v100, 31, v99
	v_ashrrev_i32_e32 v99, 11, v99
	v_add_u32_e32 v101, v99, v100
	v_mad_i32_i24 v100, v101, s31, v98
	v_cmp_lt_i32_e32 vcc, 15, v100
	s_and_saveexec_b64 s[0:1], vcc
	s_xor_b64 s[0:1], exec, s[0:1]
	v_lshlrev_b32_e32 v98, 12, v101
	v_add3_u32 v98, v98, v100, -16
	v_ashrrev_i32_e32 v99, 31, v98
	v_lshlrev_b64 v[98:99], 12, v[98:99]
	v_lshl_add_u64 v[98:99], s[56:57], 0, v[98:99]
	s_andn2_saveexec_b64 s[0:1], s[0:1]
	v_lshlrev_b32_e32 v98, 10, v100
	v_ashrrev_i32_e32 v99, 31, v98
	v_lshl_add_u64 v[98:99], v[98:99], 2, s[58:59]
	s_or_b64 exec, exec, s[0:1]
	v_lshl_add_u64 v[98:99], v[130:131], 2, v[98:99]
	global_load_dword v149, v[98:99], off
	global_load_dword v150, v[98:99], off offset:128
	v_or_b32_e32 v116, 42, v136
	v_min_i32_e32 v98, 0x403f, v116
	v_mul_hi_i32 v99, v98, s30
	v_lshrrev_b32_e32 v100, 31, v99
	v_ashrrev_i32_e32 v99, 11, v99
	v_add_u32_e32 v101, v99, v100
	v_mad_i32_i24 v100, v101, s31, v98
	v_cmp_lt_i32_e32 vcc, 15, v100
	s_and_saveexec_b64 s[0:1], vcc
	s_xor_b64 s[0:1], exec, s[0:1]
	v_lshlrev_b32_e32 v98, 12, v101
	v_add3_u32 v98, v98, v100, -16
	v_ashrrev_i32_e32 v99, 31, v98
	v_lshlrev_b64 v[98:99], 12, v[98:99]
	v_lshl_add_u64 v[98:99], s[56:57], 0, v[98:99]
	s_andn2_saveexec_b64 s[0:1], s[0:1]
	v_lshlrev_b32_e32 v98, 10, v100
	v_ashrrev_i32_e32 v99, 31, v98
	v_lshl_add_u64 v[98:99], v[98:99], 2, s[58:59]
	s_or_b64 exec, exec, s[0:1]
	v_lshl_add_u64 v[98:99], v[130:131], 2, v[98:99]
	global_load_dword v151, v[98:99], off
	global_load_dword v152, v[98:99], off offset:128
	v_or_b32_e32 v114, 43, v136
	v_min_i32_e32 v98, 0x403f, v114
	v_mul_hi_i32 v99, v98, s30
	v_lshrrev_b32_e32 v100, 31, v99
	v_ashrrev_i32_e32 v99, 11, v99
	v_add_u32_e32 v101, v99, v100
	v_mad_i32_i24 v100, v101, s31, v98
	v_cmp_lt_i32_e32 vcc, 15, v100
	s_and_saveexec_b64 s[0:1], vcc
	s_xor_b64 s[0:1], exec, s[0:1]
	v_lshlrev_b32_e32 v98, 12, v101
	v_add3_u32 v98, v98, v100, -16
	v_ashrrev_i32_e32 v99, 31, v98
	v_lshlrev_b64 v[98:99], 12, v[98:99]
	v_lshl_add_u64 v[98:99], s[56:57], 0, v[98:99]
	s_andn2_saveexec_b64 s[0:1], s[0:1]
	v_lshlrev_b32_e32 v98, 10, v100
	v_ashrrev_i32_e32 v99, 31, v98
	v_lshl_add_u64 v[98:99], v[98:99], 2, s[58:59]
	s_or_b64 exec, exec, s[0:1]
	v_lshl_add_u64 v[98:99], v[130:131], 2, v[98:99]
	global_load_dword v153, v[98:99], off
	global_load_dword v154, v[98:99], off offset:128
	v_or_b32_e32 v112, 48, v136
	v_min_i32_e32 v98, 0x403f, v112
	v_mul_hi_i32 v99, v98, s30
	v_lshrrev_b32_e32 v100, 31, v99
	v_ashrrev_i32_e32 v99, 11, v99
	v_add_u32_e32 v101, v99, v100
	v_mad_i32_i24 v100, v101, s31, v98
	v_cmp_lt_i32_e32 vcc, 15, v100
	s_and_saveexec_b64 s[0:1], vcc
	s_xor_b64 s[0:1], exec, s[0:1]
	v_lshlrev_b32_e32 v98, 12, v101
	v_add3_u32 v98, v98, v100, -16
	v_ashrrev_i32_e32 v99, 31, v98
	v_lshlrev_b64 v[98:99], 12, v[98:99]
	v_lshl_add_u64 v[98:99], s[56:57], 0, v[98:99]
	s_andn2_saveexec_b64 s[0:1], s[0:1]
	v_lshlrev_b32_e32 v98, 10, v100
	v_ashrrev_i32_e32 v99, 31, v98
	v_lshl_add_u64 v[98:99], v[98:99], 2, s[58:59]
	s_or_b64 exec, exec, s[0:1]
	v_lshl_add_u64 v[98:99], v[130:131], 2, v[98:99]
	global_load_dword v155, v[98:99], off
	global_load_dword v156, v[98:99], off offset:128
	v_or_b32_e32 v110, 49, v136
	v_min_i32_e32 v98, 0x403f, v110
	v_mul_hi_i32 v99, v98, s30
	v_lshrrev_b32_e32 v100, 31, v99
	v_ashrrev_i32_e32 v99, 11, v99
	v_add_u32_e32 v101, v99, v100
	v_mad_i32_i24 v100, v101, s31, v98
	v_cmp_lt_i32_e32 vcc, 15, v100
	s_and_saveexec_b64 s[0:1], vcc
	s_xor_b64 s[0:1], exec, s[0:1]
	v_lshlrev_b32_e32 v98, 12, v101
	v_add3_u32 v98, v98, v100, -16
	v_ashrrev_i32_e32 v99, 31, v98
	v_lshlrev_b64 v[98:99], 12, v[98:99]
	v_lshl_add_u64 v[98:99], s[56:57], 0, v[98:99]
	s_andn2_saveexec_b64 s[0:1], s[0:1]
	v_lshlrev_b32_e32 v98, 10, v100
	v_ashrrev_i32_e32 v99, 31, v98
	v_lshl_add_u64 v[98:99], v[98:99], 2, s[58:59]
	s_or_b64 exec, exec, s[0:1]
	v_lshl_add_u64 v[98:99], v[130:131], 2, v[98:99]
	global_load_dword v157, v[98:99], off
	global_load_dword v158, v[98:99], off offset:128
	v_or_b32_e32 v108, 50, v136
	v_min_i32_e32 v98, 0x403f, v108
	v_mul_hi_i32 v99, v98, s30
	v_lshrrev_b32_e32 v100, 31, v99
	v_ashrrev_i32_e32 v99, 11, v99
	v_add_u32_e32 v101, v99, v100
	v_mad_i32_i24 v100, v101, s31, v98
	v_cmp_lt_i32_e32 vcc, 15, v100
	s_and_saveexec_b64 s[0:1], vcc
	s_xor_b64 s[0:1], exec, s[0:1]
	v_lshlrev_b32_e32 v98, 12, v101
	v_add3_u32 v98, v98, v100, -16
	v_ashrrev_i32_e32 v99, 31, v98
	v_lshlrev_b64 v[98:99], 12, v[98:99]
	v_lshl_add_u64 v[98:99], s[56:57], 0, v[98:99]
	s_andn2_saveexec_b64 s[0:1], s[0:1]
	v_lshlrev_b32_e32 v98, 10, v100
	v_ashrrev_i32_e32 v99, 31, v98
	v_lshl_add_u64 v[98:99], v[98:99], 2, s[58:59]
	s_or_b64 exec, exec, s[0:1]
	v_lshl_add_u64 v[98:99], v[130:131], 2, v[98:99]
	global_load_dword v159, v[98:99], off
	global_load_dword v160, v[98:99], off offset:128
	v_or_b32_e32 v106, 51, v136
	v_min_i32_e32 v98, 0x403f, v106
	v_mul_hi_i32 v99, v98, s30
	v_lshrrev_b32_e32 v100, 31, v99
	v_ashrrev_i32_e32 v99, 11, v99
	v_add_u32_e32 v101, v99, v100
	v_mad_i32_i24 v100, v101, s31, v98
	v_cmp_lt_i32_e32 vcc, 15, v100
	s_and_saveexec_b64 s[0:1], vcc
	s_xor_b64 s[0:1], exec, s[0:1]
	v_lshlrev_b32_e32 v98, 12, v101
	v_add3_u32 v98, v98, v100, -16
	v_ashrrev_i32_e32 v99, 31, v98
	v_lshlrev_b64 v[98:99], 12, v[98:99]
	v_lshl_add_u64 v[98:99], s[56:57], 0, v[98:99]
	s_andn2_saveexec_b64 s[0:1], s[0:1]
	v_lshlrev_b32_e32 v98, 10, v100
	v_ashrrev_i32_e32 v99, 31, v98
	v_lshl_add_u64 v[98:99], v[98:99], 2, s[58:59]
	s_or_b64 exec, exec, s[0:1]
	v_lshl_add_u64 v[98:99], v[130:131], 2, v[98:99]
	global_load_dword v161, v[98:99], off
	global_load_dword v162, v[98:99], off offset:128
	v_or_b32_e32 v104, 56, v136
	v_min_i32_e32 v98, 0x403f, v104
	v_mul_hi_i32 v99, v98, s30
	v_lshrrev_b32_e32 v100, 31, v99
	v_ashrrev_i32_e32 v99, 11, v99
	v_add_u32_e32 v101, v99, v100
	v_mad_i32_i24 v100, v101, s31, v98
	v_cmp_lt_i32_e32 vcc, 15, v100
	s_and_saveexec_b64 s[0:1], vcc
	s_xor_b64 s[0:1], exec, s[0:1]
	v_lshlrev_b32_e32 v98, 12, v101
	v_add3_u32 v98, v98, v100, -16
	v_ashrrev_i32_e32 v99, 31, v98
	v_lshlrev_b64 v[98:99], 12, v[98:99]
	v_lshl_add_u64 v[98:99], s[56:57], 0, v[98:99]
	s_andn2_saveexec_b64 s[0:1], s[0:1]
	v_lshlrev_b32_e32 v98, 10, v100
	v_ashrrev_i32_e32 v99, 31, v98
	v_lshl_add_u64 v[98:99], v[98:99], 2, s[58:59]
	s_or_b64 exec, exec, s[0:1]
	v_lshl_add_u64 v[98:99], v[130:131], 2, v[98:99]
	global_load_dword v163, v[98:99], off
	global_load_dword v164, v[98:99], off offset:128
	v_or_b32_e32 v102, 57, v136
	v_min_i32_e32 v98, 0x403f, v102
	v_mul_hi_i32 v99, v98, s30
	v_lshrrev_b32_e32 v100, 31, v99
	v_ashrrev_i32_e32 v99, 11, v99
	v_add_u32_e32 v101, v99, v100
	v_mad_i32_i24 v100, v101, s31, v98
	v_cmp_lt_i32_e32 vcc, 15, v100
	s_and_saveexec_b64 s[0:1], vcc
	s_xor_b64 s[0:1], exec, s[0:1]
	v_lshlrev_b32_e32 v98, 12, v101
	v_add3_u32 v98, v98, v100, -16
	v_ashrrev_i32_e32 v99, 31, v98
	v_lshlrev_b64 v[98:99], 12, v[98:99]
	v_lshl_add_u64 v[98:99], s[56:57], 0, v[98:99]
	s_andn2_saveexec_b64 s[0:1], s[0:1]
	v_lshlrev_b32_e32 v98, 10, v100
	v_ashrrev_i32_e32 v99, 31, v98
	v_lshl_add_u64 v[98:99], v[98:99], 2, s[58:59]
	s_or_b64 exec, exec, s[0:1]
	v_lshl_add_u64 v[98:99], v[130:131], 2, v[98:99]
	global_load_dword v167, v[98:99], off
	global_load_dword v168, v[98:99], off offset:128
	v_or_b32_e32 v100, 58, v136
	v_min_i32_e32 v98, 0x403f, v100
	v_mul_hi_i32 v99, v98, s30
	v_lshrrev_b32_e32 v101, 31, v99
	v_ashrrev_i32_e32 v99, 11, v99
	v_add_u32_e32 v103, v99, v101
	v_mad_i32_i24 v101, v103, s31, v98
	v_cmp_lt_i32_e32 vcc, 15, v101
	s_and_saveexec_b64 s[0:1], vcc
	s_xor_b64 s[0:1], exec, s[0:1]
	v_lshlrev_b32_e32 v98, 12, v103
	v_add3_u32 v98, v98, v101, -16
	v_ashrrev_i32_e32 v99, 31, v98
	v_lshlrev_b64 v[98:99], 12, v[98:99]
	v_lshl_add_u64 v[98:99], s[56:57], 0, v[98:99]
	s_andn2_saveexec_b64 s[0:1], s[0:1]
	v_lshlrev_b32_e32 v98, 10, v101
	v_ashrrev_i32_e32 v99, 31, v98
	v_lshl_add_u64 v[98:99], v[98:99], 2, s[58:59]
	s_or_b64 exec, exec, s[0:1]
	v_lshl_add_u64 v[98:99], v[130:131], 2, v[98:99]
	global_load_dword v169, v[98:99], off
	global_load_dword v170, v[98:99], off offset:128
	v_or_b32_e32 v98, 59, v136
	v_min_i32_e32 v99, 0x403f, v98
	v_mul_hi_i32 v101, v99, s30
	v_lshrrev_b32_e32 v103, 31, v101
	v_ashrrev_i32_e32 v101, 11, v101
	v_add_u32_e32 v101, v101, v103
	v_mad_i32_i24 v99, v101, s31, v99
	v_cmp_lt_i32_e32 vcc, 15, v99
	s_and_saveexec_b64 s[0:1], vcc
	s_xor_b64 s[0:1], exec, s[0:1]
	v_lshlrev_b32_e32 v101, 12, v101
	v_add3_u32 v138, v101, v99, -16
	v_ashrrev_i32_e32 v139, 31, v138
	v_lshlrev_b64 v[138:139], 12, v[138:139]
	v_lshl_add_u64 v[138:139], s[56:57], 0, v[138:139]
	s_andn2_saveexec_b64 s[0:1], s[0:1]
	v_lshlrev_b32_e32 v138, 10, v99
	v_ashrrev_i32_e32 v139, 31, v138
	v_lshl_add_u64 v[138:139], v[138:139], 2, s[58:59]
	s_or_b64 exec, exec, s[0:1]
	v_lshl_add_u64 v[138:139], v[130:131], 2, v[138:139]
	global_load_dword v165, v[138:139], off
	global_load_dword v166, v[138:139], off offset:128
	v_cmp_gt_i32_e32 vcc, s34, v128
	s_nop 1
	v_cndmask_b32_e32 v101, v179, v128, vcc
	v_mul_hi_i32 v99, v101, s30
	v_lshrrev_b32_e32 v103, 31, v99
	v_ashrrev_i32_e32 v99, 11, v99
	v_add_u32_e32 v99, v99, v103
	v_mad_i32_i24 v101, v99, s31, v101
	v_cmp_lt_i32_e64 s[0:1], 15, v101
	s_and_saveexec_b64 s[2:3], s[0:1]
	s_xor_b64 s[0:1], exec, s[2:3]
	v_lshlrev_b32_e32 v99, 12, v99
	v_add3_u32 v138, v99, v101, -16
	v_ashrrev_i32_e32 v139, 31, v138
	v_lshlrev_b64 v[138:139], 12, v[138:139]
	v_lshl_add_u64 v[138:139], s[88:89], 0, v[138:139]
	s_andn2_saveexec_b64 s[0:1], s[0:1]
	v_lshlrev_b32_e32 v99, 14, v99
	v_lshl_add_u32 v138, v101, 10, v99
	v_ashrrev_i32_e32 v139, 31, v138
	v_lshl_add_u64 v[138:139], v[138:139], 2, s[12:13]
	s_or_b64 exec, exec, s[0:1]
	v_ashrrev_i32_e32 v129, 31, v128
	v_lshlrev_b64 v[128:129], 11, v[128:129]
	v_lshl_add_u64 v[128:129], s[62:63], 0, v[128:129]
	s_waitcnt vmcnt(31)
	v_fmac_f32_e32 v137, 0.5, v82
	v_lshl_add_u64 v[128:129], v[130:131], 1, v[128:129]
	v_lshl_add_u64 v[138:139], v[138:139], 0, v[134:135]
	s_and_saveexec_b64 s[0:1], vcc
	s_cbranch_execz .LBB0_921
	global_store_dword v[138:139], v137, off
	v_mul_f32_e32 v82, v137, v242
	v_cvt_pk_bf16_f32 v82, v82, s0
	global_store_short v[128:129], v82, off
.LBB0_921:
	s_or_b64 exec, exec, s[0:1]
	s_waitcnt vmcnt(30)
	v_fmac_f32_e32 v140, 0.5, v66
	s_and_saveexec_b64 s[0:1], vcc
	s_cbranch_execz .LBB0_923
	global_store_dword v[138:139], v140, off offset:128
	v_mul_f32_e32 v66, v140, v243
	v_cvt_pk_bf16_f32 v66, v66, s0
	global_store_short v[128:129], v66, off offset:64
.LBB0_923:
	s_or_b64 exec, exec, s[0:1]
	v_cmp_gt_i32_e32 vcc, s34, v126
	s_nop 1
	v_cndmask_b32_e32 v82, v179, v126, vcc
	v_mul_hi_i32 v66, v82, s30
	v_lshrrev_b32_e32 v99, 31, v66
	v_ashrrev_i32_e32 v66, 11, v66
	v_add_u32_e32 v66, v66, v99
	v_mad_i32_i24 v82, v66, s31, v82
	v_cmp_lt_i32_e64 s[0:1], 15, v82
	s_and_saveexec_b64 s[2:3], s[0:1]
	s_xor_b64 s[0:1], exec, s[2:3]
	v_lshlrev_b32_e32 v66, 12, v66
	v_add3_u32 v128, v66, v82, -16
	v_ashrrev_i32_e32 v129, 31, v128
	v_lshlrev_b64 v[128:129], 12, v[128:129]
	v_lshl_add_u64 v[128:129], s[88:89], 0, v[128:129]
	s_andn2_saveexec_b64 s[0:1], s[0:1]
	v_lshlrev_b32_e32 v66, 14, v66
	v_lshl_add_u32 v128, v82, 10, v66
	v_ashrrev_i32_e32 v129, 31, v128
	v_lshl_add_u64 v[128:129], v[128:129], 2, s[12:13]
	s_or_b64 exec, exec, s[0:1]
	v_ashrrev_i32_e32 v127, 31, v126
	v_lshlrev_b64 v[126:127], 11, v[126:127]
	v_lshl_add_u64 v[126:127], s[62:63], 0, v[126:127]
	s_waitcnt vmcnt(29)
	v_fmac_f32_e32 v141, 0.5, v83
	v_lshl_add_u64 v[82:83], v[130:131], 1, v[126:127]
	v_lshl_add_u64 v[126:127], v[128:129], 0, v[134:135]
	s_and_saveexec_b64 s[0:1], vcc
	s_cbranch_execz .LBB0_929
	global_store_dword v[126:127], v141, off
	v_mul_f32_e32 v66, v141, v242
	v_cvt_pk_bf16_f32 v66, v66, s0
	global_store_short v[82:83], v66, off
.LBB0_929:
	s_or_b64 exec, exec, s[0:1]
	s_waitcnt vmcnt(28)
	v_fmac_f32_e32 v142, 0.5, v67
	s_and_saveexec_b64 s[0:1], vcc
	s_cbranch_execz .LBB0_931
	global_store_dword v[126:127], v142, off offset:128
	v_mul_f32_e32 v66, v142, v243
	v_cvt_pk_bf16_f32 v66, v66, s0
	global_store_short v[82:83], v66, off offset:64
.LBB0_931:
	s_or_b64 exec, exec, s[0:1]
	v_cmp_gt_i32_e32 vcc, s34, v124
	s_nop 1
	v_cndmask_b32_e32 v66, v179, v124, vcc
	v_mul_hi_i32 v67, v66, s30
	v_lshrrev_b32_e32 v82, 31, v67
	v_ashrrev_i32_e32 v67, 11, v67
	v_add_u32_e32 v82, v67, v82
	v_mad_i32_i24 v83, v82, s31, v66
	v_cmp_lt_i32_e64 s[0:1], 15, v83
	s_and_saveexec_b64 s[2:3], s[0:1]
	s_xor_b64 s[0:1], exec, s[2:3]
	v_lshlrev_b32_e32 v66, 12, v82
	v_add3_u32 v66, v66, v83, -16
	v_ashrrev_i32_e32 v67, 31, v66
	v_lshlrev_b64 v[66:67], 12, v[66:67]
	v_lshl_add_u64 v[66:67], s[88:89], 0, v[66:67]
	s_andn2_saveexec_b64 s[0:1], s[0:1]
	v_lshlrev_b32_e32 v66, 14, v82
	v_lshl_add_u32 v66, v83, 10, v66
	v_ashrrev_i32_e32 v67, 31, v66
	v_lshl_add_u64 v[66:67], v[66:67], 2, s[12:13]
	s_or_b64 exec, exec, s[0:1]
	v_ashrrev_i32_e32 v125, 31, v124
	v_lshlrev_b64 v[82:83], 11, v[124:125]
	v_lshl_add_u64 v[82:83], s[62:63], 0, v[82:83]
	s_waitcnt vmcnt(27)
	v_fmac_f32_e32 v143, 0.5, v84
	v_lshl_add_u64 v[82:83], v[130:131], 1, v[82:83]
	v_lshl_add_u64 v[66:67], v[66:67], 0, v[134:135]
	s_and_saveexec_b64 s[0:1], vcc
	s_cbranch_execz .LBB0_937
	global_store_dword v[66:67], v143, off
	v_mul_f32_e32 v84, v143, v242
	v_cvt_pk_bf16_f32 v84, v84, s0
	global_store_short v[82:83], v84, off
.LBB0_937:
	s_or_b64 exec, exec, s[0:1]
	s_waitcnt vmcnt(26)
	v_fmac_f32_e32 v144, 0.5, v68
	s_and_saveexec_b64 s[0:1], vcc
	s_cbranch_execz .LBB0_939
	global_store_dword v[66:67], v144, off offset:128
	v_mul_f32_e32 v66, v144, v243
	v_cvt_pk_bf16_f32 v66, v66, s0
	global_store_short v[82:83], v66, off offset:64
.LBB0_939:
	s_or_b64 exec, exec, s[0:1]
	v_cmp_gt_i32_e32 vcc, s34, v122
	s_nop 1
	v_cndmask_b32_e32 v66, v179, v122, vcc
	v_mul_hi_i32 v67, v66, s30
	v_lshrrev_b32_e32 v68, 31, v67
	v_ashrrev_i32_e32 v67, 11, v67
	v_add_u32_e32 v68, v67, v68
	v_mad_i32_i24 v82, v68, s31, v66
	v_cmp_lt_i32_e64 s[0:1], 15, v82
	s_and_saveexec_b64 s[2:3], s[0:1]
	s_xor_b64 s[0:1], exec, s[2:3]
	v_lshlrev_b32_e32 v66, 12, v68
	v_add3_u32 v66, v66, v82, -16
	v_ashrrev_i32_e32 v67, 31, v66
	v_lshlrev_b64 v[66:67], 12, v[66:67]
	v_lshl_add_u64 v[66:67], s[88:89], 0, v[66:67]
	s_andn2_saveexec_b64 s[0:1], s[0:1]
	v_lshlrev_b32_e32 v66, 14, v68
	v_lshl_add_u32 v66, v82, 10, v66
	v_ashrrev_i32_e32 v67, 31, v66
	v_lshl_add_u64 v[66:67], v[66:67], 2, s[12:13]
	s_or_b64 exec, exec, s[0:1]
	v_ashrrev_i32_e32 v123, 31, v122
	v_lshlrev_b64 v[82:83], 11, v[122:123]
	v_lshl_add_u64 v[82:83], s[62:63], 0, v[82:83]
	s_waitcnt vmcnt(25)
	v_fmac_f32_e32 v145, 0.5, v85
	v_lshl_add_u64 v[82:83], v[130:131], 1, v[82:83]
	v_lshl_add_u64 v[66:67], v[66:67], 0, v[134:135]
	s_and_saveexec_b64 s[0:1], vcc
	s_cbranch_execz .LBB0_945
	global_store_dword v[66:67], v145, off
	v_mul_f32_e32 v68, v145, v242
	v_cvt_pk_bf16_f32 v68, v68, s0
	global_store_short v[82:83], v68, off
.LBB0_945:
	s_or_b64 exec, exec, s[0:1]
	s_waitcnt vmcnt(24)
	v_fmac_f32_e32 v146, 0.5, v69
	s_and_saveexec_b64 s[0:1], vcc
	s_cbranch_execz .LBB0_947
	global_store_dword v[66:67], v146, off offset:128
	v_mul_f32_e32 v66, v146, v243
	v_cvt_pk_bf16_f32 v66, v66, s0
	global_store_short v[82:83], v66, off offset:64
.LBB0_947:
	s_or_b64 exec, exec, s[0:1]
	v_cmp_gt_i32_e32 vcc, s34, v120
	s_nop 1
	v_cndmask_b32_e32 v66, v179, v120, vcc
	v_mul_hi_i32 v67, v66, s30
	v_lshrrev_b32_e32 v68, 31, v67
	v_ashrrev_i32_e32 v67, 11, v67
	v_add_u32_e32 v68, v67, v68
	v_mad_i32_i24 v69, v68, s31, v66
	v_cmp_lt_i32_e64 s[0:1], 15, v69
	s_and_saveexec_b64 s[2:3], s[0:1]
	s_xor_b64 s[0:1], exec, s[2:3]
	v_lshlrev_b32_e32 v66, 12, v68
	v_add3_u32 v66, v66, v69, -16
	v_ashrrev_i32_e32 v67, 31, v66
	v_lshlrev_b64 v[66:67], 12, v[66:67]
	v_lshl_add_u64 v[66:67], s[88:89], 0, v[66:67]
	s_andn2_saveexec_b64 s[0:1], s[0:1]
	v_lshlrev_b32_e32 v66, 14, v68
	v_lshl_add_u32 v66, v69, 10, v66
	v_ashrrev_i32_e32 v67, 31, v66
	v_lshl_add_u64 v[66:67], v[66:67], 2, s[12:13]
	s_or_b64 exec, exec, s[0:1]
	v_ashrrev_i32_e32 v121, 31, v120
	v_lshlrev_b64 v[68:69], 11, v[120:121]
	v_lshl_add_u64 v[68:69], s[62:63], 0, v[68:69]
	s_waitcnt vmcnt(23)
	v_fmac_f32_e32 v147, 0.5, v86
	v_lshl_add_u64 v[68:69], v[130:131], 1, v[68:69]
	v_lshl_add_u64 v[66:67], v[66:67], 0, v[134:135]
	s_and_saveexec_b64 s[0:1], vcc
	s_cbranch_execz .LBB0_953
	global_store_dword v[66:67], v147, off
	v_mul_f32_e32 v82, v147, v242
	v_cvt_pk_bf16_f32 v82, v82, s0
	global_store_short v[68:69], v82, off
.LBB0_953:
	s_or_b64 exec, exec, s[0:1]
	s_waitcnt vmcnt(22)
	v_fmac_f32_e32 v148, 0.5, v70
	s_and_saveexec_b64 s[0:1], vcc
	s_cbranch_execz .LBB0_955
	global_store_dword v[66:67], v148, off offset:128
	v_mul_f32_e32 v66, v148, v243
	v_cvt_pk_bf16_f32 v66, v66, s0
	global_store_short v[68:69], v66, off offset:64
.LBB0_955:
	s_or_b64 exec, exec, s[0:1]
	v_cmp_gt_i32_e32 vcc, s34, v118
	s_nop 1
	v_cndmask_b32_e32 v66, v179, v118, vcc
	v_mul_hi_i32 v67, v66, s30
	v_lshrrev_b32_e32 v68, 31, v67
	v_ashrrev_i32_e32 v67, 11, v67
	v_add_u32_e32 v68, v67, v68
	v_mad_i32_i24 v69, v68, s31, v66
	v_cmp_lt_i32_e64 s[0:1], 15, v69
	s_and_saveexec_b64 s[2:3], s[0:1]
	s_xor_b64 s[0:1], exec, s[2:3]
	v_lshlrev_b32_e32 v66, 12, v68
	v_add3_u32 v66, v66, v69, -16
	v_ashrrev_i32_e32 v67, 31, v66
	v_lshlrev_b64 v[66:67], 12, v[66:67]
	v_lshl_add_u64 v[66:67], s[88:89], 0, v[66:67]
	s_andn2_saveexec_b64 s[0:1], s[0:1]
	v_lshlrev_b32_e32 v66, 14, v68
	v_lshl_add_u32 v66, v69, 10, v66
	v_ashrrev_i32_e32 v67, 31, v66
	v_lshl_add_u64 v[66:67], v[66:67], 2, s[12:13]
	s_or_b64 exec, exec, s[0:1]
	v_ashrrev_i32_e32 v119, 31, v118
	v_lshlrev_b64 v[68:69], 11, v[118:119]
	v_lshl_add_u64 v[68:69], s[62:63], 0, v[68:69]
	s_waitcnt vmcnt(21)
	v_fmac_f32_e32 v149, 0.5, v87
	v_lshl_add_u64 v[68:69], v[130:131], 1, v[68:69]
	v_lshl_add_u64 v[66:67], v[66:67], 0, v[134:135]
	s_and_saveexec_b64 s[0:1], vcc
	s_cbranch_execz .LBB0_961
	global_store_dword v[66:67], v149, off
	v_mul_f32_e32 v70, v149, v242
	v_cvt_pk_bf16_f32 v70, v70, s0
	global_store_short v[68:69], v70, off
.LBB0_961:
	s_or_b64 exec, exec, s[0:1]
	s_waitcnt vmcnt(20)
	v_fmac_f32_e32 v150, 0.5, v71
	s_and_saveexec_b64 s[0:1], vcc
	s_cbranch_execz .LBB0_963
	global_store_dword v[66:67], v150, off offset:128
	v_mul_f32_e32 v66, v150, v243
	v_cvt_pk_bf16_f32 v66, v66, s0
	global_store_short v[68:69], v66, off offset:64
.LBB0_963:
	s_or_b64 exec, exec, s[0:1]
	v_cmp_gt_i32_e32 vcc, s34, v116
	s_nop 1
	v_cndmask_b32_e32 v66, v179, v116, vcc
	v_mul_hi_i32 v67, v66, s30
	v_lshrrev_b32_e32 v68, 31, v67
	v_ashrrev_i32_e32 v67, 11, v67
	v_add_u32_e32 v68, v67, v68
	v_mad_i32_i24 v69, v68, s31, v66
	v_cmp_lt_i32_e64 s[0:1], 15, v69
	s_and_saveexec_b64 s[2:3], s[0:1]
	s_xor_b64 s[0:1], exec, s[2:3]
	v_lshlrev_b32_e32 v66, 12, v68
	v_add3_u32 v66, v66, v69, -16
	v_ashrrev_i32_e32 v67, 31, v66
	v_lshlrev_b64 v[66:67], 12, v[66:67]
	v_lshl_add_u64 v[66:67], s[88:89], 0, v[66:67]
	s_andn2_saveexec_b64 s[0:1], s[0:1]
	v_lshlrev_b32_e32 v66, 14, v68
	v_lshl_add_u32 v66, v69, 10, v66
	v_ashrrev_i32_e32 v67, 31, v66
	v_lshl_add_u64 v[66:67], v[66:67], 2, s[12:13]
	s_or_b64 exec, exec, s[0:1]
	v_ashrrev_i32_e32 v117, 31, v116
	v_lshlrev_b64 v[68:69], 11, v[116:117]
	v_lshl_add_u64 v[68:69], s[62:63], 0, v[68:69]
	s_waitcnt vmcnt(19)
	v_fmac_f32_e32 v151, 0.5, v88
	v_lshl_add_u64 v[68:69], v[130:131], 1, v[68:69]
	v_lshl_add_u64 v[66:67], v[66:67], 0, v[134:135]
	s_and_saveexec_b64 s[0:1], vcc
	s_cbranch_execz .LBB0_969
	global_store_dword v[66:67], v151, off
	v_mul_f32_e32 v70, v151, v242
	v_cvt_pk_bf16_f32 v70, v70, s0
	global_store_short v[68:69], v70, off
.LBB0_969:
	s_or_b64 exec, exec, s[0:1]
	s_waitcnt vmcnt(18)
	v_fmac_f32_e32 v152, 0.5, v72
	s_and_saveexec_b64 s[0:1], vcc
	s_cbranch_execz .LBB0_971
	global_store_dword v[66:67], v152, off offset:128
	v_mul_f32_e32 v66, v152, v243
	v_cvt_pk_bf16_f32 v66, v66, s0
	global_store_short v[68:69], v66, off offset:64
.LBB0_971:
	s_or_b64 exec, exec, s[0:1]
	v_cmp_gt_i32_e32 vcc, s34, v114
	s_nop 1
	v_cndmask_b32_e32 v66, v179, v114, vcc
	v_mul_hi_i32 v67, v66, s30
	v_lshrrev_b32_e32 v68, 31, v67
	v_ashrrev_i32_e32 v67, 11, v67
	v_add_u32_e32 v68, v67, v68
	v_mad_i32_i24 v69, v68, s31, v66
	v_cmp_lt_i32_e64 s[0:1], 15, v69
	s_and_saveexec_b64 s[2:3], s[0:1]
	s_xor_b64 s[0:1], exec, s[2:3]
	v_lshlrev_b32_e32 v66, 12, v68
	v_add3_u32 v66, v66, v69, -16
	v_ashrrev_i32_e32 v67, 31, v66
	v_lshlrev_b64 v[66:67], 12, v[66:67]
	v_lshl_add_u64 v[66:67], s[88:89], 0, v[66:67]
	s_andn2_saveexec_b64 s[0:1], s[0:1]
	v_lshlrev_b32_e32 v66, 14, v68
	v_lshl_add_u32 v66, v69, 10, v66
	v_ashrrev_i32_e32 v67, 31, v66
	v_lshl_add_u64 v[66:67], v[66:67], 2, s[12:13]
	s_or_b64 exec, exec, s[0:1]
	v_ashrrev_i32_e32 v115, 31, v114
	v_lshlrev_b64 v[68:69], 11, v[114:115]
	v_lshl_add_u64 v[68:69], s[62:63], 0, v[68:69]
	s_waitcnt vmcnt(17)
	v_fmac_f32_e32 v153, 0.5, v89
	v_lshl_add_u64 v[68:69], v[130:131], 1, v[68:69]
	v_lshl_add_u64 v[66:67], v[66:67], 0, v[134:135]
	s_and_saveexec_b64 s[0:1], vcc
	s_cbranch_execz .LBB0_977
	global_store_dword v[66:67], v153, off
	v_mul_f32_e32 v70, v153, v242
	v_cvt_pk_bf16_f32 v70, v70, s0
	global_store_short v[68:69], v70, off
.LBB0_977:
	s_or_b64 exec, exec, s[0:1]
	s_waitcnt vmcnt(16)
	v_fmac_f32_e32 v154, 0.5, v73
	s_and_saveexec_b64 s[0:1], vcc
	s_cbranch_execz .LBB0_979
	global_store_dword v[66:67], v154, off offset:128
	v_mul_f32_e32 v66, v154, v243
	v_cvt_pk_bf16_f32 v66, v66, s0
	global_store_short v[68:69], v66, off offset:64
.LBB0_979:
	s_or_b64 exec, exec, s[0:1]
	v_cmp_gt_i32_e32 vcc, s34, v112
	s_nop 1
	v_cndmask_b32_e32 v66, v179, v112, vcc
	v_mul_hi_i32 v67, v66, s30
	v_lshrrev_b32_e32 v68, 31, v67
	v_ashrrev_i32_e32 v67, 11, v67
	v_add_u32_e32 v68, v67, v68
	v_mad_i32_i24 v69, v68, s31, v66
	v_cmp_lt_i32_e64 s[0:1], 15, v69
	s_and_saveexec_b64 s[2:3], s[0:1]
	s_xor_b64 s[0:1], exec, s[2:3]
	v_lshlrev_b32_e32 v66, 12, v68
	v_add3_u32 v66, v66, v69, -16
	v_ashrrev_i32_e32 v67, 31, v66
	v_lshlrev_b64 v[66:67], 12, v[66:67]
	v_lshl_add_u64 v[66:67], s[88:89], 0, v[66:67]
	s_andn2_saveexec_b64 s[0:1], s[0:1]
	v_lshlrev_b32_e32 v66, 14, v68
	v_lshl_add_u32 v66, v69, 10, v66
	v_ashrrev_i32_e32 v67, 31, v66
	v_lshl_add_u64 v[66:67], v[66:67], 2, s[12:13]
	s_or_b64 exec, exec, s[0:1]
	v_ashrrev_i32_e32 v113, 31, v112
	v_lshlrev_b64 v[68:69], 11, v[112:113]
	v_lshl_add_u64 v[68:69], s[62:63], 0, v[68:69]
	s_waitcnt vmcnt(15)
	v_fmac_f32_e32 v155, 0.5, v90
	v_lshl_add_u64 v[68:69], v[130:131], 1, v[68:69]
	v_lshl_add_u64 v[66:67], v[66:67], 0, v[134:135]
	s_and_saveexec_b64 s[0:1], vcc
	s_cbranch_execz .LBB0_985
	global_store_dword v[66:67], v155, off
	v_mul_f32_e32 v70, v155, v242
	v_cvt_pk_bf16_f32 v70, v70, s0
	global_store_short v[68:69], v70, off
.LBB0_985:
	s_or_b64 exec, exec, s[0:1]
	s_waitcnt vmcnt(14)
	v_fmac_f32_e32 v156, 0.5, v74
	s_and_saveexec_b64 s[0:1], vcc
	s_cbranch_execz .LBB0_987
	global_store_dword v[66:67], v156, off offset:128
	v_mul_f32_e32 v66, v156, v243
	v_cvt_pk_bf16_f32 v66, v66, s0
	global_store_short v[68:69], v66, off offset:64
.LBB0_987:
	s_or_b64 exec, exec, s[0:1]
	v_cmp_gt_i32_e32 vcc, s34, v110
	s_nop 1
	v_cndmask_b32_e32 v66, v179, v110, vcc
	v_mul_hi_i32 v67, v66, s30
	v_lshrrev_b32_e32 v68, 31, v67
	v_ashrrev_i32_e32 v67, 11, v67
	v_add_u32_e32 v68, v67, v68
	v_mad_i32_i24 v69, v68, s31, v66
	v_cmp_lt_i32_e64 s[0:1], 15, v69
	s_and_saveexec_b64 s[2:3], s[0:1]
	s_xor_b64 s[0:1], exec, s[2:3]
	v_lshlrev_b32_e32 v66, 12, v68
	v_add3_u32 v66, v66, v69, -16
	v_ashrrev_i32_e32 v67, 31, v66
	v_lshlrev_b64 v[66:67], 12, v[66:67]
	v_lshl_add_u64 v[66:67], s[88:89], 0, v[66:67]
	s_andn2_saveexec_b64 s[0:1], s[0:1]
	v_lshlrev_b32_e32 v66, 14, v68
	v_lshl_add_u32 v66, v69, 10, v66
	v_ashrrev_i32_e32 v67, 31, v66
	v_lshl_add_u64 v[66:67], v[66:67], 2, s[12:13]
	s_or_b64 exec, exec, s[0:1]
	v_ashrrev_i32_e32 v111, 31, v110
	v_lshlrev_b64 v[68:69], 11, v[110:111]
	v_lshl_add_u64 v[68:69], s[62:63], 0, v[68:69]
	s_waitcnt vmcnt(13)
	v_fmac_f32_e32 v157, 0.5, v91
	v_lshl_add_u64 v[68:69], v[130:131], 1, v[68:69]
	v_lshl_add_u64 v[66:67], v[66:67], 0, v[134:135]
	s_and_saveexec_b64 s[0:1], vcc
	s_cbranch_execz .LBB0_993
	global_store_dword v[66:67], v157, off
	v_mul_f32_e32 v70, v157, v242
	v_cvt_pk_bf16_f32 v70, v70, s0
	global_store_short v[68:69], v70, off
.LBB0_993:
	s_or_b64 exec, exec, s[0:1]
	s_waitcnt vmcnt(12)
	v_fmac_f32_e32 v158, 0.5, v75
	s_and_saveexec_b64 s[0:1], vcc
	s_cbranch_execz .LBB0_995
	global_store_dword v[66:67], v158, off offset:128
	v_mul_f32_e32 v66, v158, v243
	v_cvt_pk_bf16_f32 v66, v66, s0
	global_store_short v[68:69], v66, off offset:64
.LBB0_995:
	s_or_b64 exec, exec, s[0:1]
	v_cmp_gt_i32_e32 vcc, s34, v108
	s_nop 1
	v_cndmask_b32_e32 v66, v179, v108, vcc
	v_mul_hi_i32 v67, v66, s30
	v_lshrrev_b32_e32 v68, 31, v67
	v_ashrrev_i32_e32 v67, 11, v67
	v_add_u32_e32 v68, v67, v68
	v_mad_i32_i24 v69, v68, s31, v66
	v_cmp_lt_i32_e64 s[0:1], 15, v69
	s_and_saveexec_b64 s[2:3], s[0:1]
	s_xor_b64 s[0:1], exec, s[2:3]
	v_lshlrev_b32_e32 v66, 12, v68
	v_add3_u32 v66, v66, v69, -16
	v_ashrrev_i32_e32 v67, 31, v66
	v_lshlrev_b64 v[66:67], 12, v[66:67]
	v_lshl_add_u64 v[66:67], s[88:89], 0, v[66:67]
	s_andn2_saveexec_b64 s[0:1], s[0:1]
	v_lshlrev_b32_e32 v66, 14, v68
	v_lshl_add_u32 v66, v69, 10, v66
	v_ashrrev_i32_e32 v67, 31, v66
	v_lshl_add_u64 v[66:67], v[66:67], 2, s[12:13]
	s_or_b64 exec, exec, s[0:1]
	v_ashrrev_i32_e32 v109, 31, v108
	v_lshlrev_b64 v[68:69], 11, v[108:109]
	v_lshl_add_u64 v[68:69], s[62:63], 0, v[68:69]
	s_waitcnt vmcnt(11)
	v_fmac_f32_e32 v159, 0.5, v92
	v_lshl_add_u64 v[68:69], v[130:131], 1, v[68:69]
	v_lshl_add_u64 v[66:67], v[66:67], 0, v[134:135]
	s_and_saveexec_b64 s[0:1], vcc
	s_cbranch_execz .LBB0_1001
	global_store_dword v[66:67], v159, off
	v_mul_f32_e32 v70, v159, v242
	v_cvt_pk_bf16_f32 v70, v70, s0
	global_store_short v[68:69], v70, off
.LBB0_1001:
	s_or_b64 exec, exec, s[0:1]
	s_waitcnt vmcnt(10)
	v_fmac_f32_e32 v160, 0.5, v76
	s_and_saveexec_b64 s[0:1], vcc
	s_cbranch_execz .LBB0_1003
	global_store_dword v[66:67], v160, off offset:128
	v_mul_f32_e32 v66, v160, v243
	v_cvt_pk_bf16_f32 v66, v66, s0
	global_store_short v[68:69], v66, off offset:64
.LBB0_1003:
	s_or_b64 exec, exec, s[0:1]
	v_cmp_gt_i32_e32 vcc, s34, v106
	s_nop 1
	v_cndmask_b32_e32 v66, v179, v106, vcc
	v_mul_hi_i32 v67, v66, s30
	v_lshrrev_b32_e32 v68, 31, v67
	v_ashrrev_i32_e32 v67, 11, v67
	v_add_u32_e32 v68, v67, v68
	v_mad_i32_i24 v69, v68, s31, v66
	v_cmp_lt_i32_e64 s[0:1], 15, v69
	s_and_saveexec_b64 s[2:3], s[0:1]
	s_xor_b64 s[0:1], exec, s[2:3]
	v_lshlrev_b32_e32 v66, 12, v68
	v_add3_u32 v66, v66, v69, -16
	v_ashrrev_i32_e32 v67, 31, v66
	v_lshlrev_b64 v[66:67], 12, v[66:67]
	v_lshl_add_u64 v[66:67], s[88:89], 0, v[66:67]
	s_andn2_saveexec_b64 s[0:1], s[0:1]
	v_lshlrev_b32_e32 v66, 14, v68
	v_lshl_add_u32 v66, v69, 10, v66
	v_ashrrev_i32_e32 v67, 31, v66
	v_lshl_add_u64 v[66:67], v[66:67], 2, s[12:13]
	s_or_b64 exec, exec, s[0:1]
	v_ashrrev_i32_e32 v107, 31, v106
	v_lshlrev_b64 v[68:69], 11, v[106:107]
	v_lshl_add_u64 v[68:69], s[62:63], 0, v[68:69]
	s_waitcnt vmcnt(9)
	v_fmac_f32_e32 v161, 0.5, v93
	v_lshl_add_u64 v[68:69], v[130:131], 1, v[68:69]
	v_lshl_add_u64 v[66:67], v[66:67], 0, v[134:135]
	s_and_saveexec_b64 s[0:1], vcc
	s_cbranch_execz .LBB0_1009
	global_store_dword v[66:67], v161, off
	v_mul_f32_e32 v70, v161, v242
	v_cvt_pk_bf16_f32 v70, v70, s0
	global_store_short v[68:69], v70, off
.LBB0_1009:
	s_or_b64 exec, exec, s[0:1]
	s_waitcnt vmcnt(8)
	v_fmac_f32_e32 v162, 0.5, v77
	s_and_saveexec_b64 s[0:1], vcc
	s_cbranch_execz .LBB0_1011
	global_store_dword v[66:67], v162, off offset:128
	v_mul_f32_e32 v66, v162, v243
	v_cvt_pk_bf16_f32 v66, v66, s0
	global_store_short v[68:69], v66, off offset:64
.LBB0_1011:
	s_or_b64 exec, exec, s[0:1]
	v_cmp_gt_i32_e32 vcc, s34, v104
	s_nop 1
	v_cndmask_b32_e32 v66, v179, v104, vcc
	v_mul_hi_i32 v67, v66, s30
	v_lshrrev_b32_e32 v68, 31, v67
	v_ashrrev_i32_e32 v67, 11, v67
	v_add_u32_e32 v68, v67, v68
	v_mad_i32_i24 v69, v68, s31, v66
	v_cmp_lt_i32_e64 s[0:1], 15, v69
	s_and_saveexec_b64 s[2:3], s[0:1]
	s_xor_b64 s[0:1], exec, s[2:3]
	v_lshlrev_b32_e32 v66, 12, v68
	v_add3_u32 v66, v66, v69, -16
	v_ashrrev_i32_e32 v67, 31, v66
	v_lshlrev_b64 v[66:67], 12, v[66:67]
	v_lshl_add_u64 v[66:67], s[88:89], 0, v[66:67]
	s_andn2_saveexec_b64 s[0:1], s[0:1]
	v_lshlrev_b32_e32 v66, 14, v68
	v_lshl_add_u32 v66, v69, 10, v66
	v_ashrrev_i32_e32 v67, 31, v66
	v_lshl_add_u64 v[66:67], v[66:67], 2, s[12:13]
	s_or_b64 exec, exec, s[0:1]
	v_ashrrev_i32_e32 v105, 31, v104
	v_lshlrev_b64 v[68:69], 11, v[104:105]
	v_lshl_add_u64 v[68:69], s[62:63], 0, v[68:69]
	s_waitcnt vmcnt(7)
	v_fmac_f32_e32 v163, 0.5, v94
	v_lshl_add_u64 v[68:69], v[130:131], 1, v[68:69]
	v_lshl_add_u64 v[66:67], v[66:67], 0, v[134:135]
	s_and_saveexec_b64 s[0:1], vcc
	s_cbranch_execz .LBB0_1017
	global_store_dword v[66:67], v163, off
	v_mul_f32_e32 v70, v163, v242
	v_cvt_pk_bf16_f32 v70, v70, s0
	global_store_short v[68:69], v70, off
.LBB0_1017:
	s_or_b64 exec, exec, s[0:1]
	s_waitcnt vmcnt(6)
	v_fmac_f32_e32 v164, 0.5, v78
	s_and_saveexec_b64 s[0:1], vcc
	s_cbranch_execz .LBB0_1019
	global_store_dword v[66:67], v164, off offset:128
	v_mul_f32_e32 v66, v164, v243
	v_cvt_pk_bf16_f32 v66, v66, s0
	global_store_short v[68:69], v66, off offset:64
.LBB0_1019:
	s_or_b64 exec, exec, s[0:1]
	v_cmp_gt_i32_e32 vcc, s34, v102
	s_nop 1
	v_cndmask_b32_e32 v66, v179, v102, vcc
	v_mul_hi_i32 v67, v66, s30
	v_lshrrev_b32_e32 v68, 31, v67
	v_ashrrev_i32_e32 v67, 11, v67
	v_add_u32_e32 v68, v67, v68
	v_mad_i32_i24 v69, v68, s31, v66
	v_cmp_lt_i32_e64 s[0:1], 15, v69
	s_and_saveexec_b64 s[2:3], s[0:1]
	s_xor_b64 s[0:1], exec, s[2:3]
	v_lshlrev_b32_e32 v66, 12, v68
	v_add3_u32 v66, v66, v69, -16
	v_ashrrev_i32_e32 v67, 31, v66
	v_lshlrev_b64 v[66:67], 12, v[66:67]
	v_lshl_add_u64 v[66:67], s[88:89], 0, v[66:67]
	s_andn2_saveexec_b64 s[0:1], s[0:1]
	v_lshlrev_b32_e32 v66, 14, v68
	v_lshl_add_u32 v66, v69, 10, v66
	v_ashrrev_i32_e32 v67, 31, v66
	v_lshl_add_u64 v[66:67], v[66:67], 2, s[12:13]
	s_or_b64 exec, exec, s[0:1]
	v_ashrrev_i32_e32 v103, 31, v102
	v_lshlrev_b64 v[68:69], 11, v[102:103]
	v_lshl_add_u64 v[68:69], s[62:63], 0, v[68:69]
	s_waitcnt vmcnt(5)
	v_fmac_f32_e32 v167, 0.5, v95
	v_lshl_add_u64 v[68:69], v[130:131], 1, v[68:69]
	v_lshl_add_u64 v[66:67], v[66:67], 0, v[134:135]
	s_and_saveexec_b64 s[0:1], vcc
	s_cbranch_execz .LBB0_1025
	global_store_dword v[66:67], v167, off
	v_mul_f32_e32 v70, v167, v242
	v_cvt_pk_bf16_f32 v70, v70, s0
	global_store_short v[68:69], v70, off
.LBB0_1025:
	s_or_b64 exec, exec, s[0:1]
	s_waitcnt vmcnt(4)
	v_fmac_f32_e32 v168, 0.5, v79
	s_and_saveexec_b64 s[0:1], vcc
	s_cbranch_execz .LBB0_1027
	global_store_dword v[66:67], v168, off offset:128
	v_mul_f32_e32 v66, v168, v243
	v_cvt_pk_bf16_f32 v66, v66, s0
	global_store_short v[68:69], v66, off offset:64
.LBB0_1027:
	s_or_b64 exec, exec, s[0:1]
	v_cmp_gt_i32_e32 vcc, s34, v100
	s_nop 1
	v_cndmask_b32_e32 v66, v179, v100, vcc
	v_mul_hi_i32 v67, v66, s30
	v_lshrrev_b32_e32 v68, 31, v67
	v_ashrrev_i32_e32 v67, 11, v67
	v_add_u32_e32 v68, v67, v68
	v_mad_i32_i24 v69, v68, s31, v66
	v_cmp_lt_i32_e64 s[0:1], 15, v69
	s_and_saveexec_b64 s[2:3], s[0:1]
	s_xor_b64 s[0:1], exec, s[2:3]
	v_lshlrev_b32_e32 v66, 12, v68
	v_add3_u32 v66, v66, v69, -16
	v_ashrrev_i32_e32 v67, 31, v66
	v_lshlrev_b64 v[66:67], 12, v[66:67]
	v_lshl_add_u64 v[66:67], s[88:89], 0, v[66:67]
	s_andn2_saveexec_b64 s[0:1], s[0:1]
	v_lshlrev_b32_e32 v66, 14, v68
	v_lshl_add_u32 v66, v69, 10, v66
	v_ashrrev_i32_e32 v67, 31, v66
	v_lshl_add_u64 v[66:67], v[66:67], 2, s[12:13]
	s_or_b64 exec, exec, s[0:1]
	v_ashrrev_i32_e32 v101, 31, v100
	v_lshlrev_b64 v[68:69], 11, v[100:101]
	v_lshl_add_u64 v[68:69], s[62:63], 0, v[68:69]
	s_waitcnt vmcnt(3)
	v_fmac_f32_e32 v169, 0.5, v96
	v_lshl_add_u64 v[68:69], v[130:131], 1, v[68:69]
	v_lshl_add_u64 v[66:67], v[66:67], 0, v[134:135]
	s_and_saveexec_b64 s[0:1], vcc
	s_cbranch_execz .LBB0_1033
	global_store_dword v[66:67], v169, off
	v_mul_f32_e32 v70, v169, v242
	v_cvt_pk_bf16_f32 v70, v70, s0
	global_store_short v[68:69], v70, off
.LBB0_1033:
	s_or_b64 exec, exec, s[0:1]
	s_waitcnt vmcnt(2)
	v_fmac_f32_e32 v170, 0.5, v80
	s_and_saveexec_b64 s[0:1], vcc
	s_cbranch_execz .LBB0_1035
	global_store_dword v[66:67], v170, off offset:128
	v_mul_f32_e32 v66, v170, v243
	v_cvt_pk_bf16_f32 v66, v66, s0
	global_store_short v[68:69], v66, off offset:64
.LBB0_1035:
	s_or_b64 exec, exec, s[0:1]
	v_cmp_gt_i32_e32 vcc, s34, v98
	s_nop 1
	v_cndmask_b32_e32 v66, v179, v98, vcc
	v_mul_hi_i32 v67, v66, s30
	v_lshrrev_b32_e32 v68, 31, v67
	v_ashrrev_i32_e32 v67, 11, v67
	v_add_u32_e32 v68, v67, v68
	v_mad_i32_i24 v69, v68, s31, v66
	v_cmp_lt_i32_e64 s[0:1], 15, v69
	s_and_saveexec_b64 s[2:3], s[0:1]
	s_xor_b64 s[0:1], exec, s[2:3]
	v_lshlrev_b32_e32 v66, 12, v68
	v_add3_u32 v66, v66, v69, -16
	v_ashrrev_i32_e32 v67, 31, v66
	v_lshlrev_b64 v[66:67], 12, v[66:67]
	v_lshl_add_u64 v[66:67], s[88:89], 0, v[66:67]
	s_andn2_saveexec_b64 s[0:1], s[0:1]
	v_lshlrev_b32_e32 v66, 14, v68
	v_lshl_add_u32 v66, v69, 10, v66
	v_ashrrev_i32_e32 v67, 31, v66
	v_lshl_add_u64 v[66:67], v[66:67], 2, s[12:13]
	s_or_b64 exec, exec, s[0:1]
	v_ashrrev_i32_e32 v99, 31, v98
	v_lshlrev_b64 v[68:69], 11, v[98:99]
	v_lshl_add_u64 v[68:69], s[62:63], 0, v[68:69]
	s_waitcnt vmcnt(1)
	v_fmac_f32_e32 v165, 0.5, v97
	v_lshl_add_u64 v[68:69], v[130:131], 1, v[68:69]
	v_lshl_add_u64 v[66:67], v[66:67], 0, v[134:135]
	s_and_saveexec_b64 s[0:1], vcc
	s_cbranch_execz .LBB0_1041
	global_store_dword v[66:67], v165, off
	v_mul_f32_e32 v70, v165, v242
	v_cvt_pk_bf16_f32 v70, v70, s0
	global_store_short v[68:69], v70, off
.LBB0_1041:
	s_or_b64 exec, exec, s[0:1]
	s_waitcnt vmcnt(0)
	v_fmac_f32_e32 v166, 0.5, v81
	s_and_saveexec_b64 s[0:1], vcc
	s_cbranch_execz .LBB0_1043
	global_store_dword v[66:67], v166, off offset:128
	v_mul_f32_e32 v66, v166, v243
	v_cvt_pk_bf16_f32 v66, v66, s0
	global_store_short v[68:69], v66, off offset:64
.LBB0_1043:
	s_or_b64 exec, exec, s[0:1]
	v_lshlrev_b32_e32 v66, 1, v175
	v_lshlrev_b32_e32 v103, 1, v172
	v_and_b32_e32 v66, 32, v66
	v_and_b32_e32 v103, 24, v103
	v_and_b32_e32 v104, 3, v172
	v_or3_b32 v66, v104, v103, v66
	v_and_b32_e32 v104, 64, v180
	v_xor_b32_e32 v103, 16, v180
	v_add_u32_e32 v108, 64, v104
	v_mul_f32_e32 v81, v140, v140
	v_mul_f32_e32 v97, v177, v177
	v_and_b32_e32 v98, 16, v172
	v_cmp_lt_i32_e32 vcc, v103, v108
	v_fmac_f32_e32 v81, v137, v137
	v_fmac_f32_e32 v97, v176, v176
	v_cndmask_b32_e32 v103, v180, v103, vcc
	v_cmp_eq_u32_e32 vcc, 0, v98
	v_lshlrev_b32_e32 v104, 2, v103
	v_mul_f32_e32 v77, v148, v148
	v_cndmask_b32_e32 v98, v97, v81, vcc
	ds_bpermute_b32 v98, v104, v98
	v_mul_f32_e32 v78, v146, v146
	v_mul_f32_e32 v80, v142, v142
	v_mul_f32_e32 v93, v188, v188
	v_mul_f32_e32 v94, v186, v186
	v_mul_f32_e32 v96, v182, v182
	v_mul_f32_e32 v71, v160, v160
	v_mul_f32_e32 v72, v158, v158
	v_mul_f32_e32 v74, v154, v154
	v_mul_f32_e32 v75, v152, v152
	v_mul_f32_e32 v76, v150, v150
	v_fmac_f32_e32 v77, v147, v147
	v_fmac_f32_e32 v78, v145, v145
	v_mul_f32_e32 v79, v144, v144
	v_fmac_f32_e32 v80, v141, v141
	v_mul_f32_e32 v87, v200, v200
	v_mul_f32_e32 v88, v198, v198
	v_mul_f32_e32 v90, v194, v194
	v_mul_f32_e32 v91, v192, v192
	v_mul_f32_e32 v92, v190, v190
	v_fmac_f32_e32 v93, v187, v187
	v_fmac_f32_e32 v94, v185, v185
	v_mul_f32_e32 v95, v184, v184
	v_fmac_f32_e32 v96, v181, v181
	v_cndmask_b32_e32 v81, v81, v97, vcc
	v_mul_f32_e32 v68, v168, v168
	v_mul_f32_e32 v69, v164, v164
	v_mul_f32_e32 v70, v162, v162
	v_fmac_f32_e32 v71, v159, v159
	v_fmac_f32_e32 v72, v157, v157
	v_mul_f32_e32 v73, v156, v156
	v_fmac_f32_e32 v74, v153, v153
	v_fmac_f32_e32 v75, v151, v151
	v_fmac_f32_e32 v76, v149, v149
	v_fmac_f32_e32 v79, v143, v143
	v_mul_f32_e32 v84, v206, v206
	v_mul_f32_e32 v85, v204, v204
	v_mul_f32_e32 v86, v202, v202
	v_fmac_f32_e32 v87, v199, v199
	v_fmac_f32_e32 v88, v197, v197
	v_mul_f32_e32 v89, v196, v196
	v_fmac_f32_e32 v90, v193, v193
	v_fmac_f32_e32 v91, v191, v191
	v_fmac_f32_e32 v92, v189, v189
	v_fmac_f32_e32 v95, v183, v183
	s_waitcnt lgkmcnt(0)
	v_add_f32_e32 v81, v81, v98
	v_cndmask_b32_e32 v97, v96, v80, vcc
	v_cndmask_b32_e32 v98, v94, v78, vcc
	v_cndmask_b32_e32 v78, v78, v94, vcc
	v_cndmask_b32_e32 v94, v93, v77, vcc
	v_mul_f32_e32 v67, v170, v170
	v_fmac_f32_e32 v68, v167, v167
	v_fmac_f32_e32 v69, v163, v163
	v_fmac_f32_e32 v70, v161, v161
	v_fmac_f32_e32 v73, v155, v155
	v_mul_f32_e32 v83, v210, v210
	v_fmac_f32_e32 v84, v205, v205
	v_fmac_f32_e32 v85, v203, v203
	v_fmac_f32_e32 v86, v201, v201
	v_fmac_f32_e32 v89, v195, v195
	v_cndmask_b32_e32 v80, v80, v96, vcc
	ds_bpermute_b32 v96, v104, v97
	v_cndmask_b32_e32 v97, v95, v79, vcc
	v_cndmask_b32_e32 v79, v79, v95, vcc
	v_cndmask_b32_e32 v77, v77, v93, vcc
	ds_bpermute_b32 v93, v104, v94
	v_cndmask_b32_e32 v94, v92, v76, vcc
	v_cndmask_b32_e32 v95, v91, v75, vcc
	v_cndmask_b32_e32 v76, v76, v92, vcc
	v_cndmask_b32_e32 v75, v75, v91, vcc
	v_cndmask_b32_e32 v91, v90, v74, vcc
	v_cndmask_b32_e32 v92, v88, v72, vcc
	v_cndmask_b32_e32 v72, v72, v88, vcc
	v_cndmask_b32_e32 v88, v87, v71, vcc
	v_fmac_f32_e32 v67, v169, v169
	v_mul_f32_e32 v82, v212, v212
	v_fmac_f32_e32 v83, v207, v207
	v_mul_f32_e32 v103, v166, v166
	v_cndmask_b32_e32 v74, v74, v90, vcc
	ds_bpermute_b32 v90, v104, v91
	v_cndmask_b32_e32 v91, v89, v73, vcc
	v_cndmask_b32_e32 v73, v73, v89, vcc
	v_cndmask_b32_e32 v71, v71, v87, vcc
	ds_bpermute_b32 v87, v104, v88
	v_cndmask_b32_e32 v88, v86, v70, vcc
	v_cndmask_b32_e32 v89, v85, v69, vcc
	v_cndmask_b32_e32 v69, v69, v85, vcc
	v_cndmask_b32_e32 v85, v84, v68, vcc
	v_fmac_f32_e32 v82, v211, v211
	v_fmac_f32_e32 v103, v165, v165
	ds_bpermute_b32 v97, v104, v97
	ds_bpermute_b32 v98, v104, v98
	ds_bpermute_b32 v91, v104, v91
	ds_bpermute_b32 v88, v104, v88
	v_cndmask_b32_e32 v68, v68, v84, vcc
	ds_bpermute_b32 v84, v104, v85
	v_cndmask_b32_e32 v85, v83, v67, vcc
	ds_bpermute_b32 v94, v104, v94
	ds_bpermute_b32 v95, v104, v95
	ds_bpermute_b32 v92, v104, v92
	ds_bpermute_b32 v89, v104, v89
	v_cndmask_b32_e32 v70, v70, v86, vcc
	ds_bpermute_b32 v85, v104, v85
	v_cndmask_b32_e32 v86, v82, v103, vcc
	s_lshl_b32 s0, s4, 2
	ds_bpermute_b32 v86, v104, v86
	s_ashr_i32 s1, s0, 31
	v_cndmask_b32_e32 v67, v67, v83, vcc
	v_xor_b32_e32 v83, 8, v180
	v_and_b32_e32 v99, 8, v172
	s_lshl_b64 s[8:9], s[0:1], 2
	v_cmp_lt_i32_e64 s[0:1], v83, v108
	s_waitcnt lgkmcnt(10)
	v_add_f32_e32 v79, v79, v97
	s_waitcnt lgkmcnt(9)
	v_add_f32_e32 v78, v78, v98
	s_waitcnt lgkmcnt(8)
	v_add_f32_e32 v73, v73, v91
	v_add_f32_e32 v71, v71, v87
	s_waitcnt lgkmcnt(7)
	v_add_f32_e32 v70, v70, v88
	v_cndmask_b32_e64 v83, v180, v83, s[0:1]
	v_cmp_eq_u32_e64 s[2:3], 0, v99
	v_add_f32_e32 v80, v80, v96
	v_add_f32_e32 v77, v77, v93
	s_waitcnt lgkmcnt(5)
	v_add_f32_e32 v76, v76, v94
	s_waitcnt lgkmcnt(4)
	v_add_f32_e32 v75, v75, v95
	s_waitcnt lgkmcnt(3)
	v_add_f32_e32 v72, v72, v92
	s_waitcnt lgkmcnt(2)
	v_add_f32_e32 v69, v69, v89
	v_add_f32_e32 v68, v68, v84
	s_waitcnt lgkmcnt(1)
	v_add_f32_e32 v67, v67, v85
	v_cndmask_b32_e32 v82, v103, v82, vcc
	v_lshlrev_b32_e32 v105, 2, v83
	v_cndmask_b32_e64 v83, v81, v73, s[2:3]
	v_cndmask_b32_e64 v84, v79, v71, s[2:3]
	v_cndmask_b32_e64 v71, v71, v79, s[2:3]
	v_cndmask_b32_e64 v79, v78, v70, s[2:3]
	v_add_f32_e32 v74, v74, v90
	s_waitcnt lgkmcnt(0)
	v_add_f32_e32 v82, v82, v86
	v_cndmask_b32_e64 v73, v73, v81, s[2:3]
	ds_bpermute_b32 v81, v105, v83
	v_cndmask_b32_e64 v83, v80, v72, s[2:3]
	v_cndmask_b32_e64 v72, v72, v80, s[2:3]
	v_cndmask_b32_e64 v70, v70, v78, s[2:3]
	ds_bpermute_b32 v78, v105, v79
	v_cndmask_b32_e64 v79, v77, v69, s[2:3]
	v_cndmask_b32_e64 v80, v76, v68, s[2:3]
	v_cndmask_b32_e64 v68, v68, v76, s[2:3]
	v_cndmask_b32_e64 v76, v75, v67, s[2:3]
	ds_bpermute_b32 v83, v105, v83
	ds_bpermute_b32 v79, v105, v79
	ds_bpermute_b32 v80, v105, v80
	v_cndmask_b32_e64 v67, v67, v75, s[2:3]
	ds_bpermute_b32 v75, v105, v76
	v_cndmask_b32_e64 v76, v74, v82, s[2:3]
	ds_bpermute_b32 v84, v105, v84
	ds_bpermute_b32 v76, v105, v76
	v_cndmask_b32_e64 v69, v69, v77, s[2:3]
	v_xor_b32_e32 v77, 4, v180
	v_and_b32_e32 v100, 4, v172
	v_cmp_lt_i32_e64 s[0:1], v77, v108
	s_waitcnt lgkmcnt(7)
	v_add_f32_e32 v73, v73, v81
	s_waitcnt lgkmcnt(5)
	v_add_f32_e32 v72, v72, v83
	s_waitcnt lgkmcnt(4)
	v_add_f32_e32 v69, v69, v79
	s_waitcnt lgkmcnt(3)
	v_add_f32_e32 v68, v68, v80
	v_cndmask_b32_e64 v77, v180, v77, s[0:1]
	v_cmp_eq_u32_e64 s[4:5], 0, v100
	v_cndmask_b32_e64 v74, v82, v74, s[2:3]
	s_waitcnt lgkmcnt(1)
	v_add_f32_e32 v71, v71, v84
	v_add_f32_e32 v70, v70, v78
	v_lshlrev_b32_e32 v106, 2, v77
	v_cndmask_b32_e64 v77, v73, v69, s[4:5]
	v_add_f32_e32 v67, v67, v75
	s_waitcnt lgkmcnt(0)
	v_add_f32_e32 v74, v74, v76
	v_cndmask_b32_e64 v69, v69, v73, s[4:5]
	v_cndmask_b32_e64 v73, v72, v68, s[4:5]
	v_cndmask_b32_e64 v68, v68, v72, s[4:5]
	ds_bpermute_b32 v72, v106, v73
	v_cndmask_b32_e64 v73, v71, v67, s[4:5]
	v_cndmask_b32_e64 v75, v70, v74, s[4:5]
	ds_bpermute_b32 v77, v106, v77
	ds_bpermute_b32 v73, v106, v73
	ds_bpermute_b32 v75, v106, v75
	v_cndmask_b32_e64 v67, v67, v71, s[4:5]
	v_xor_b32_e32 v71, 2, v180
	v_and_b32_e32 v101, 2, v172
	v_cndmask_b32_e64 v70, v74, v70, s[4:5]
	v_cmp_lt_i32_e64 s[0:1], v71, v108
	s_waitcnt lgkmcnt(2)
	v_add_f32_e32 v69, v69, v77
	v_add_f32_e32 v68, v68, v72
	s_waitcnt lgkmcnt(1)
	v_add_f32_e32 v67, v67, v73
	s_waitcnt lgkmcnt(0)
	v_add_f32_e32 v70, v70, v75
	v_cndmask_b32_e64 v71, v180, v71, s[0:1]
	v_cmp_eq_u32_e64 s[6:7], 0, v101
	v_lshlrev_b32_e32 v107, 2, v71
	v_and_b32_e32 v102, 1, v172
	v_cndmask_b32_e64 v71, v69, v67, s[6:7]
	v_cndmask_b32_e64 v72, v68, v70, s[6:7]
	ds_bpermute_b32 v71, v107, v71
	ds_bpermute_b32 v72, v107, v72
	v_cndmask_b32_e64 v67, v67, v69, s[6:7]
	v_xor_b32_e32 v69, 1, v180
	s_add_u32 s10, s70, s8
	v_cndmask_b32_e64 v68, v70, v68, s[6:7]
	v_cmp_lt_i32_e64 s[0:1], v69, v108
	s_addc_u32 s11, s71, s9
	s_waitcnt lgkmcnt(1)
	v_add_f32_e32 v67, v67, v71
	s_waitcnt lgkmcnt(0)
	v_add_f32_e32 v70, v68, v72
	v_cmp_eq_u32_e64 s[8:9], 0, v102
	v_cndmask_b32_e64 v69, v180, v69, s[0:1]
	v_lshlrev_b32_e32 v108, 2, v69
	v_cndmask_b32_e64 v68, v67, v70, s[8:9]
	ds_bpermute_b32 v71, v108, v68
	v_or3_b32 v66, v66, v173, v174
	v_lshlrev_b32_e32 v0, 2, v0
	v_lshl_add_u64 v[68:69], s[10:11], 0, v[0:1]
	v_cndmask_b32_e64 v0, v70, v67, s[8:9]
	v_ashrrev_i32_e32 v67, 31, v66
	s_waitcnt lgkmcnt(0)
	v_add_f32_e32 v0, v0, v71
	v_lshlrev_b64 v[70:71], 6, v[66:67]
	v_lshl_add_u64 v[70:71], v[68:69], 0, v[70:71]
	v_or_b32_e32 v100, 64, v136
	global_store_dword v[70:71], v0, off
	v_min_i32_e32 v0, 0x403f, v100
	v_mul_hi_i32 v67, v0, s30
	v_lshrrev_b32_e32 v70, 31, v67
	v_ashrrev_i32_e32 v67, 11, v67
	v_add_u32_e32 v67, v67, v70
	v_mad_i32_i24 v0, v67, s31, v0
	v_cmp_lt_i32_e64 s[0:1], 15, v0
	s_and_saveexec_b64 s[10:11], s[0:1]
	s_xor_b64 s[0:1], exec, s[10:11]
	v_lshlrev_b32_e32 v67, 12, v67
	v_add3_u32 v70, v67, v0, -16
	v_ashrrev_i32_e32 v71, 31, v70
	v_lshlrev_b64 v[70:71], 12, v[70:71]
	v_lshl_add_u64 v[70:71], s[56:57], 0, v[70:71]
	s_andn2_saveexec_b64 s[0:1], s[0:1]
	v_lshlrev_b32_e32 v70, 10, v0
	v_ashrrev_i32_e32 v71, 31, v70
	v_lshl_add_u64 v[70:71], v[70:71], 2, s[58:59]
	s_or_b64 exec, exec, s[0:1]
	v_lshl_add_u64 v[70:71], v[130:131], 2, v[70:71]
	global_load_dword v0, v[70:71], off
	global_load_dword v67, v[70:71], off offset:128
	v_or_b32_e32 v98, 0x41, v136
	v_min_i32_e32 v70, 0x403f, v98
	v_mul_hi_i32 v71, v70, s30
	v_lshrrev_b32_e32 v72, 31, v71
	v_ashrrev_i32_e32 v71, 11, v71
	v_add_u32_e32 v73, v71, v72
	v_mad_i32_i24 v72, v73, s31, v70
	v_cmp_lt_i32_e64 s[0:1], 15, v72
	s_and_saveexec_b64 s[10:11], s[0:1]
	s_xor_b64 s[0:1], exec, s[10:11]
	v_lshlrev_b32_e32 v70, 12, v73
	v_add3_u32 v70, v70, v72, -16
	v_ashrrev_i32_e32 v71, 31, v70
	v_lshlrev_b64 v[70:71], 12, v[70:71]
	v_lshl_add_u64 v[70:71], s[56:57], 0, v[70:71]
	s_andn2_saveexec_b64 s[0:1], s[0:1]
	v_lshlrev_b32_e32 v70, 10, v72
	v_ashrrev_i32_e32 v71, 31, v70
	v_lshl_add_u64 v[70:71], v[70:71], 2, s[58:59]
	s_or_b64 exec, exec, s[0:1]
	v_lshl_add_u64 v[70:71], v[130:131], 2, v[70:71]
	global_load_dword v109, v[70:71], off
	global_load_dword v110, v[70:71], off offset:128
	v_or_b32_e32 v96, 0x42, v136
	v_min_i32_e32 v70, 0x403f, v96
	v_mul_hi_i32 v71, v70, s30
	v_lshrrev_b32_e32 v72, 31, v71
	v_ashrrev_i32_e32 v71, 11, v71
	v_add_u32_e32 v73, v71, v72
	v_mad_i32_i24 v72, v73, s31, v70
	v_cmp_lt_i32_e64 s[0:1], 15, v72
	s_and_saveexec_b64 s[10:11], s[0:1]
	s_xor_b64 s[0:1], exec, s[10:11]
	v_lshlrev_b32_e32 v70, 12, v73
	v_add3_u32 v70, v70, v72, -16
	v_ashrrev_i32_e32 v71, 31, v70
	v_lshlrev_b64 v[70:71], 12, v[70:71]
	v_lshl_add_u64 v[70:71], s[56:57], 0, v[70:71]
	s_andn2_saveexec_b64 s[0:1], s[0:1]
	v_lshlrev_b32_e32 v70, 10, v72
	v_ashrrev_i32_e32 v71, 31, v70
	v_lshl_add_u64 v[70:71], v[70:71], 2, s[58:59]
	s_or_b64 exec, exec, s[0:1]
	v_lshl_add_u64 v[70:71], v[130:131], 2, v[70:71]
	global_load_dword v111, v[70:71], off
	global_load_dword v112, v[70:71], off offset:128
	v_or_b32_e32 v94, 0x43, v136
	v_min_i32_e32 v70, 0x403f, v94
	v_mul_hi_i32 v71, v70, s30
	v_lshrrev_b32_e32 v72, 31, v71
	v_ashrrev_i32_e32 v71, 11, v71
	v_add_u32_e32 v73, v71, v72
	v_mad_i32_i24 v72, v73, s31, v70
	v_cmp_lt_i32_e64 s[0:1], 15, v72
	s_and_saveexec_b64 s[10:11], s[0:1]
	s_xor_b64 s[0:1], exec, s[10:11]
	v_lshlrev_b32_e32 v70, 12, v73
	v_add3_u32 v70, v70, v72, -16
	v_ashrrev_i32_e32 v71, 31, v70
	v_lshlrev_b64 v[70:71], 12, v[70:71]
	v_lshl_add_u64 v[70:71], s[56:57], 0, v[70:71]
	s_andn2_saveexec_b64 s[0:1], s[0:1]
	v_lshlrev_b32_e32 v70, 10, v72
	v_ashrrev_i32_e32 v71, 31, v70
	v_lshl_add_u64 v[70:71], v[70:71], 2, s[58:59]
	s_or_b64 exec, exec, s[0:1]
	v_lshl_add_u64 v[70:71], v[130:131], 2, v[70:71]
	global_load_dword v113, v[70:71], off
	global_load_dword v114, v[70:71], off offset:128
	v_or_b32_e32 v92, 0x48, v136
	v_min_i32_e32 v70, 0x403f, v92
	v_mul_hi_i32 v71, v70, s30
	v_lshrrev_b32_e32 v72, 31, v71
	v_ashrrev_i32_e32 v71, 11, v71
	v_add_u32_e32 v73, v71, v72
	v_mad_i32_i24 v72, v73, s31, v70
	v_cmp_lt_i32_e64 s[0:1], 15, v72
	s_and_saveexec_b64 s[10:11], s[0:1]
	s_xor_b64 s[0:1], exec, s[10:11]
	v_lshlrev_b32_e32 v70, 12, v73
	v_add3_u32 v70, v70, v72, -16
	v_ashrrev_i32_e32 v71, 31, v70
	v_lshlrev_b64 v[70:71], 12, v[70:71]
	v_lshl_add_u64 v[70:71], s[56:57], 0, v[70:71]
	s_andn2_saveexec_b64 s[0:1], s[0:1]
	v_lshlrev_b32_e32 v70, 10, v72
	v_ashrrev_i32_e32 v71, 31, v70
	v_lshl_add_u64 v[70:71], v[70:71], 2, s[58:59]
	s_or_b64 exec, exec, s[0:1]
	v_lshl_add_u64 v[70:71], v[130:131], 2, v[70:71]
	global_load_dword v115, v[70:71], off
	global_load_dword v116, v[70:71], off offset:128
	v_or_b32_e32 v90, 0x49, v136
	v_min_i32_e32 v70, 0x403f, v90
	v_mul_hi_i32 v71, v70, s30
	v_lshrrev_b32_e32 v72, 31, v71
	v_ashrrev_i32_e32 v71, 11, v71
	v_add_u32_e32 v73, v71, v72
	v_mad_i32_i24 v72, v73, s31, v70
	v_cmp_lt_i32_e64 s[0:1], 15, v72
	s_and_saveexec_b64 s[10:11], s[0:1]
	s_xor_b64 s[0:1], exec, s[10:11]
	v_lshlrev_b32_e32 v70, 12, v73
	v_add3_u32 v70, v70, v72, -16
	v_ashrrev_i32_e32 v71, 31, v70
	v_lshlrev_b64 v[70:71], 12, v[70:71]
	v_lshl_add_u64 v[70:71], s[56:57], 0, v[70:71]
	s_andn2_saveexec_b64 s[0:1], s[0:1]
	v_lshlrev_b32_e32 v70, 10, v72
	v_ashrrev_i32_e32 v71, 31, v70
	v_lshl_add_u64 v[70:71], v[70:71], 2, s[58:59]
	s_or_b64 exec, exec, s[0:1]
	v_lshl_add_u64 v[70:71], v[130:131], 2, v[70:71]
	global_load_dword v117, v[70:71], off
	global_load_dword v118, v[70:71], off offset:128
	v_or_b32_e32 v88, 0x4a, v136
	v_min_i32_e32 v70, 0x403f, v88
	v_mul_hi_i32 v71, v70, s30
	v_lshrrev_b32_e32 v72, 31, v71
	v_ashrrev_i32_e32 v71, 11, v71
	v_add_u32_e32 v73, v71, v72
	v_mad_i32_i24 v72, v73, s31, v70
	v_cmp_lt_i32_e64 s[0:1], 15, v72
	s_and_saveexec_b64 s[10:11], s[0:1]
	s_xor_b64 s[0:1], exec, s[10:11]
	v_lshlrev_b32_e32 v70, 12, v73
	v_add3_u32 v70, v70, v72, -16
	v_ashrrev_i32_e32 v71, 31, v70
	v_lshlrev_b64 v[70:71], 12, v[70:71]
	v_lshl_add_u64 v[70:71], s[56:57], 0, v[70:71]
	s_andn2_saveexec_b64 s[0:1], s[0:1]
	v_lshlrev_b32_e32 v70, 10, v72
	v_ashrrev_i32_e32 v71, 31, v70
	v_lshl_add_u64 v[70:71], v[70:71], 2, s[58:59]
	s_or_b64 exec, exec, s[0:1]
	v_lshl_add_u64 v[70:71], v[130:131], 2, v[70:71]
	global_load_dword v119, v[70:71], off
	global_load_dword v120, v[70:71], off offset:128
	v_or_b32_e32 v86, 0x4b, v136
	v_min_i32_e32 v70, 0x403f, v86
	v_mul_hi_i32 v71, v70, s30
	v_lshrrev_b32_e32 v72, 31, v71
	v_ashrrev_i32_e32 v71, 11, v71
	v_add_u32_e32 v73, v71, v72
	v_mad_i32_i24 v72, v73, s31, v70
	v_cmp_lt_i32_e64 s[0:1], 15, v72
	s_and_saveexec_b64 s[10:11], s[0:1]
	s_xor_b64 s[0:1], exec, s[10:11]
	v_lshlrev_b32_e32 v70, 12, v73
	v_add3_u32 v70, v70, v72, -16
	v_ashrrev_i32_e32 v71, 31, v70
	v_lshlrev_b64 v[70:71], 12, v[70:71]
	v_lshl_add_u64 v[70:71], s[56:57], 0, v[70:71]
	s_andn2_saveexec_b64 s[0:1], s[0:1]
	v_lshlrev_b32_e32 v70, 10, v72
	v_ashrrev_i32_e32 v71, 31, v70
	v_lshl_add_u64 v[70:71], v[70:71], 2, s[58:59]
	s_or_b64 exec, exec, s[0:1]
	v_lshl_add_u64 v[70:71], v[130:131], 2, v[70:71]
	global_load_dword v121, v[70:71], off
	global_load_dword v122, v[70:71], off offset:128
	v_or_b32_e32 v84, 0x50, v136
	v_min_i32_e32 v70, 0x403f, v84
	v_mul_hi_i32 v71, v70, s30
	v_lshrrev_b32_e32 v72, 31, v71
	v_ashrrev_i32_e32 v71, 11, v71
	v_add_u32_e32 v73, v71, v72
	v_mad_i32_i24 v72, v73, s31, v70
	v_cmp_lt_i32_e64 s[0:1], 15, v72
	s_and_saveexec_b64 s[10:11], s[0:1]
	s_xor_b64 s[0:1], exec, s[10:11]
	v_lshlrev_b32_e32 v70, 12, v73
	v_add3_u32 v70, v70, v72, -16
	v_ashrrev_i32_e32 v71, 31, v70
	v_lshlrev_b64 v[70:71], 12, v[70:71]
	v_lshl_add_u64 v[70:71], s[56:57], 0, v[70:71]
	s_andn2_saveexec_b64 s[0:1], s[0:1]
	v_lshlrev_b32_e32 v70, 10, v72
	v_ashrrev_i32_e32 v71, 31, v70
	v_lshl_add_u64 v[70:71], v[70:71], 2, s[58:59]
	s_or_b64 exec, exec, s[0:1]
	v_lshl_add_u64 v[70:71], v[130:131], 2, v[70:71]
	global_load_dword v123, v[70:71], off
	global_load_dword v124, v[70:71], off offset:128
	v_or_b32_e32 v82, 0x51, v136
	v_min_i32_e32 v70, 0x403f, v82
	v_mul_hi_i32 v71, v70, s30
	v_lshrrev_b32_e32 v72, 31, v71
	v_ashrrev_i32_e32 v71, 11, v71
	v_add_u32_e32 v73, v71, v72
	v_mad_i32_i24 v72, v73, s31, v70
	v_cmp_lt_i32_e64 s[0:1], 15, v72
	s_and_saveexec_b64 s[10:11], s[0:1]
	s_xor_b64 s[0:1], exec, s[10:11]
	v_lshlrev_b32_e32 v70, 12, v73
	v_add3_u32 v70, v70, v72, -16
	v_ashrrev_i32_e32 v71, 31, v70
	v_lshlrev_b64 v[70:71], 12, v[70:71]
	v_lshl_add_u64 v[70:71], s[56:57], 0, v[70:71]
	s_andn2_saveexec_b64 s[0:1], s[0:1]
	v_lshlrev_b32_e32 v70, 10, v72
	v_ashrrev_i32_e32 v71, 31, v70
	v_lshl_add_u64 v[70:71], v[70:71], 2, s[58:59]
	s_or_b64 exec, exec, s[0:1]
	v_lshl_add_u64 v[70:71], v[130:131], 2, v[70:71]
	global_load_dword v125, v[70:71], off
	global_load_dword v126, v[70:71], off offset:128
	v_or_b32_e32 v80, 0x52, v136
	v_min_i32_e32 v70, 0x403f, v80
	v_mul_hi_i32 v71, v70, s30
	v_lshrrev_b32_e32 v72, 31, v71
	v_ashrrev_i32_e32 v71, 11, v71
	v_add_u32_e32 v73, v71, v72
	v_mad_i32_i24 v72, v73, s31, v70
	v_cmp_lt_i32_e64 s[0:1], 15, v72
	s_and_saveexec_b64 s[10:11], s[0:1]
	s_xor_b64 s[0:1], exec, s[10:11]
	v_lshlrev_b32_e32 v70, 12, v73
	v_add3_u32 v70, v70, v72, -16
	v_ashrrev_i32_e32 v71, 31, v70
	v_lshlrev_b64 v[70:71], 12, v[70:71]
	v_lshl_add_u64 v[70:71], s[56:57], 0, v[70:71]
	s_andn2_saveexec_b64 s[0:1], s[0:1]
	v_lshlrev_b32_e32 v70, 10, v72
	v_ashrrev_i32_e32 v71, 31, v70
	v_lshl_add_u64 v[70:71], v[70:71], 2, s[58:59]
	s_or_b64 exec, exec, s[0:1]
	v_lshl_add_u64 v[70:71], v[130:131], 2, v[70:71]
	global_load_dword v127, v[70:71], off
	global_load_dword v128, v[70:71], off offset:128
	v_or_b32_e32 v78, 0x53, v136
	v_min_i32_e32 v70, 0x403f, v78
	v_mul_hi_i32 v71, v70, s30
	v_lshrrev_b32_e32 v72, 31, v71
	v_ashrrev_i32_e32 v71, 11, v71
	v_add_u32_e32 v73, v71, v72
	v_mad_i32_i24 v72, v73, s31, v70
	v_cmp_lt_i32_e64 s[0:1], 15, v72
	s_and_saveexec_b64 s[10:11], s[0:1]
	s_xor_b64 s[0:1], exec, s[10:11]
	v_lshlrev_b32_e32 v70, 12, v73
	v_add3_u32 v70, v70, v72, -16
	v_ashrrev_i32_e32 v71, 31, v70
	v_lshlrev_b64 v[70:71], 12, v[70:71]
	v_lshl_add_u64 v[70:71], s[56:57], 0, v[70:71]
	s_andn2_saveexec_b64 s[0:1], s[0:1]
	v_lshlrev_b32_e32 v70, 10, v72
	v_ashrrev_i32_e32 v71, 31, v70
	v_lshl_add_u64 v[70:71], v[70:71], 2, s[58:59]
	s_or_b64 exec, exec, s[0:1]
	v_lshl_add_u64 v[70:71], v[130:131], 2, v[70:71]
	global_load_dword v129, v[70:71], off
	global_load_dword v137, v[70:71], off offset:128
	v_or_b32_e32 v76, 0x58, v136
	v_min_i32_e32 v70, 0x403f, v76
	v_mul_hi_i32 v71, v70, s30
	v_lshrrev_b32_e32 v72, 31, v71
	v_ashrrev_i32_e32 v71, 11, v71
	v_add_u32_e32 v73, v71, v72
	v_mad_i32_i24 v72, v73, s31, v70
	v_cmp_lt_i32_e64 s[0:1], 15, v72
	s_and_saveexec_b64 s[10:11], s[0:1]
	s_xor_b64 s[0:1], exec, s[10:11]
	v_lshlrev_b32_e32 v70, 12, v73
	v_add3_u32 v70, v70, v72, -16
	v_ashrrev_i32_e32 v71, 31, v70
	v_lshlrev_b64 v[70:71], 12, v[70:71]
	v_lshl_add_u64 v[70:71], s[56:57], 0, v[70:71]
	s_andn2_saveexec_b64 s[0:1], s[0:1]
	v_lshlrev_b32_e32 v70, 10, v72
	v_ashrrev_i32_e32 v71, 31, v70
	v_lshl_add_u64 v[70:71], v[70:71], 2, s[58:59]
	s_or_b64 exec, exec, s[0:1]
	v_lshl_add_u64 v[70:71], v[130:131], 2, v[70:71]
	global_load_dword v138, v[70:71], off
	global_load_dword v139, v[70:71], off offset:128
	v_or_b32_e32 v74, 0x59, v136
	v_min_i32_e32 v70, 0x403f, v74
	v_mul_hi_i32 v71, v70, s30
	v_lshrrev_b32_e32 v72, 31, v71
	v_ashrrev_i32_e32 v71, 11, v71
	v_add_u32_e32 v73, v71, v72
	v_mad_i32_i24 v72, v73, s31, v70
	v_cmp_lt_i32_e64 s[0:1], 15, v72
	s_and_saveexec_b64 s[10:11], s[0:1]
	s_xor_b64 s[0:1], exec, s[10:11]
	v_lshlrev_b32_e32 v70, 12, v73
	v_add3_u32 v70, v70, v72, -16
	v_ashrrev_i32_e32 v71, 31, v70
	v_lshlrev_b64 v[70:71], 12, v[70:71]
	v_lshl_add_u64 v[70:71], s[56:57], 0, v[70:71]
	s_andn2_saveexec_b64 s[0:1], s[0:1]
	v_lshlrev_b32_e32 v70, 10, v72
	v_ashrrev_i32_e32 v71, 31, v70
	v_lshl_add_u64 v[70:71], v[70:71], 2, s[58:59]
	s_or_b64 exec, exec, s[0:1]
	v_lshl_add_u64 v[70:71], v[130:131], 2, v[70:71]
	global_load_dword v140, v[70:71], off
	global_load_dword v141, v[70:71], off offset:128
	v_or_b32_e32 v72, 0x5a, v136
	v_min_i32_e32 v70, 0x403f, v72
	v_mul_hi_i32 v71, v70, s30
	v_lshrrev_b32_e32 v73, 31, v71
	v_ashrrev_i32_e32 v71, 11, v71
	v_add_u32_e32 v75, v71, v73
	v_mad_i32_i24 v73, v75, s31, v70
	v_cmp_lt_i32_e64 s[0:1], 15, v73
	s_and_saveexec_b64 s[10:11], s[0:1]
	s_xor_b64 s[0:1], exec, s[10:11]
	v_lshlrev_b32_e32 v70, 12, v75
	v_add3_u32 v70, v70, v73, -16
	v_ashrrev_i32_e32 v71, 31, v70
	v_lshlrev_b64 v[70:71], 12, v[70:71]
	v_lshl_add_u64 v[70:71], s[56:57], 0, v[70:71]
	s_andn2_saveexec_b64 s[0:1], s[0:1]
	v_lshlrev_b32_e32 v70, 10, v73
	v_ashrrev_i32_e32 v71, 31, v70
	v_lshl_add_u64 v[70:71], v[70:71], 2, s[58:59]
	s_or_b64 exec, exec, s[0:1]
	v_lshl_add_u64 v[70:71], v[130:131], 2, v[70:71]
	global_load_dword v142, v[70:71], off
	global_load_dword v143, v[70:71], off offset:128
	v_or_b32_e32 v70, 0x5b, v136
	v_min_i32_e32 v71, 0x403f, v70
	v_mul_hi_i32 v73, v71, s30
	v_lshrrev_b32_e32 v75, 31, v73
	v_ashrrev_i32_e32 v73, 11, v73
	v_add_u32_e32 v73, v73, v75
	v_mad_i32_i24 v71, v73, s31, v71
	v_cmp_lt_i32_e64 s[0:1], 15, v71
	s_and_saveexec_b64 s[10:11], s[0:1]
	s_xor_b64 s[0:1], exec, s[10:11]
	v_lshlrev_b32_e32 v73, 12, v73
	v_add3_u32 v102, v73, v71, -16
	v_ashrrev_i32_e32 v103, 31, v102
	v_lshlrev_b64 v[102:103], 12, v[102:103]
	v_lshl_add_u64 v[102:103], s[56:57], 0, v[102:103]
	s_andn2_saveexec_b64 s[0:1], s[0:1]
	v_lshlrev_b32_e32 v102, 10, v71
	v_ashrrev_i32_e32 v103, 31, v102
	v_lshl_add_u64 v[102:103], v[102:103], 2, s[58:59]
	s_or_b64 exec, exec, s[0:1]
	v_lshl_add_u64 v[102:103], v[130:131], 2, v[102:103]
	global_load_dword v144, v[102:103], off
	global_load_dword v145, v[102:103], off offset:128
	v_cmp_gt_i32_e64 s[10:11], s34, v100
	s_nop 1
	v_cndmask_b32_e64 v73, v179, v100, s[10:11]
	v_mul_hi_i32 v71, v73, s30
	v_lshrrev_b32_e32 v75, 31, v71
	v_ashrrev_i32_e32 v71, 11, v71
	v_add_u32_e32 v71, v71, v75
	v_mad_i32_i24 v73, v71, s31, v73
	v_cmp_lt_i32_e64 s[0:1], 15, v73
	s_and_saveexec_b64 s[36:37], s[0:1]
	s_xor_b64 s[0:1], exec, s[36:37]
	v_lshlrev_b32_e32 v71, 12, v71
	v_add3_u32 v102, v71, v73, -16
	v_ashrrev_i32_e32 v103, 31, v102
	v_lshlrev_b64 v[102:103], 12, v[102:103]
	v_lshl_add_u64 v[102:103], s[88:89], 0, v[102:103]
	s_andn2_saveexec_b64 s[0:1], s[0:1]
	v_lshlrev_b32_e32 v71, 14, v71
	v_lshl_add_u32 v102, v73, 10, v71
	v_ashrrev_i32_e32 v103, 31, v102
	v_lshl_add_u64 v[102:103], v[102:103], 2, s[12:13]
	s_or_b64 exec, exec, s[0:1]
	v_ashrrev_i32_e32 v101, 31, v100
	v_lshlrev_b64 v[100:101], 11, v[100:101]
	v_lshl_add_u64 v[100:101], s[62:63], 0, v[100:101]
	s_waitcnt vmcnt(31)
	v_fmac_f32_e32 v0, 0.5, v50
	v_lshl_add_u64 v[100:101], v[130:131], 1, v[100:101]
	v_lshl_add_u64 v[102:103], v[102:103], 0, v[134:135]
	s_and_saveexec_b64 s[0:1], s[10:11]
	s_cbranch_execz .LBB0_1113
	global_store_dword v[102:103], v0, off
	v_mul_f32_e32 v50, v0, v242
	v_cvt_pk_bf16_f32 v50, v50, s0
	global_store_short v[100:101], v50, off
.LBB0_1113:
	s_or_b64 exec, exec, s[0:1]
	s_waitcnt vmcnt(30)
	v_fmac_f32_e32 v67, 0.5, v34
	s_and_saveexec_b64 s[0:1], s[10:11]
	s_cbranch_execz .LBB0_1115
	global_store_dword v[102:103], v67, off offset:128
	v_mul_f32_e32 v34, v67, v243
	v_cvt_pk_bf16_f32 v34, v34, s0
	global_store_short v[100:101], v34, off offset:64
.LBB0_1115:
	s_or_b64 exec, exec, s[0:1]
	v_cmp_gt_i32_e64 s[10:11], s34, v98
	s_nop 1
	v_cndmask_b32_e64 v50, v179, v98, s[10:11]
	v_mul_hi_i32 v34, v50, s30
	v_lshrrev_b32_e32 v71, 31, v34
	v_ashrrev_i32_e32 v34, 11, v34
	v_add_u32_e32 v34, v34, v71
	v_mad_i32_i24 v50, v34, s31, v50
	v_cmp_lt_i32_e64 s[0:1], 15, v50
	s_and_saveexec_b64 s[36:37], s[0:1]
	s_xor_b64 s[0:1], exec, s[36:37]
	v_lshlrev_b32_e32 v34, 12, v34
	v_add3_u32 v100, v34, v50, -16
	v_ashrrev_i32_e32 v101, 31, v100
	v_lshlrev_b64 v[100:101], 12, v[100:101]
	v_lshl_add_u64 v[100:101], s[88:89], 0, v[100:101]
	s_andn2_saveexec_b64 s[0:1], s[0:1]
	v_lshlrev_b32_e32 v34, 14, v34
	v_lshl_add_u32 v100, v50, 10, v34
	v_ashrrev_i32_e32 v101, 31, v100
	v_lshl_add_u64 v[100:101], v[100:101], 2, s[12:13]
	s_or_b64 exec, exec, s[0:1]
	v_ashrrev_i32_e32 v99, 31, v98
	v_lshlrev_b64 v[98:99], 11, v[98:99]
	v_lshl_add_u64 v[98:99], s[62:63], 0, v[98:99]
	s_waitcnt vmcnt(29)
	v_fmac_f32_e32 v109, 0.5, v51
	v_lshl_add_u64 v[50:51], v[130:131], 1, v[98:99]
	v_lshl_add_u64 v[98:99], v[100:101], 0, v[134:135]
	s_and_saveexec_b64 s[0:1], s[10:11]
	s_cbranch_execz .LBB0_1121
	global_store_dword v[98:99], v109, off
	v_mul_f32_e32 v34, v109, v242
	v_cvt_pk_bf16_f32 v34, v34, s0
	global_store_short v[50:51], v34, off
.LBB0_1121:
	s_or_b64 exec, exec, s[0:1]
	s_waitcnt vmcnt(28)
	v_fmac_f32_e32 v110, 0.5, v35
	s_and_saveexec_b64 s[0:1], s[10:11]
	s_cbranch_execz .LBB0_1123
	global_store_dword v[98:99], v110, off offset:128
	v_mul_f32_e32 v34, v110, v243
	v_cvt_pk_bf16_f32 v34, v34, s0
	global_store_short v[50:51], v34, off offset:64
.LBB0_1123:
	s_or_b64 exec, exec, s[0:1]
	v_cmp_gt_i32_e64 s[10:11], s34, v96
	s_nop 1
	v_cndmask_b32_e64 v34, v179, v96, s[10:11]
	v_mul_hi_i32 v35, v34, s30
	v_lshrrev_b32_e32 v50, 31, v35
	v_ashrrev_i32_e32 v35, 11, v35
	v_add_u32_e32 v50, v35, v50
	v_mad_i32_i24 v51, v50, s31, v34
	v_cmp_lt_i32_e64 s[0:1], 15, v51
	s_and_saveexec_b64 s[36:37], s[0:1]
	s_xor_b64 s[0:1], exec, s[36:37]
	v_lshlrev_b32_e32 v34, 12, v50
	v_add3_u32 v34, v34, v51, -16
	v_ashrrev_i32_e32 v35, 31, v34
	v_lshlrev_b64 v[34:35], 12, v[34:35]
	v_lshl_add_u64 v[34:35], s[88:89], 0, v[34:35]
	s_andn2_saveexec_b64 s[0:1], s[0:1]
	v_lshlrev_b32_e32 v34, 14, v50
	v_lshl_add_u32 v34, v51, 10, v34
	v_ashrrev_i32_e32 v35, 31, v34
	v_lshl_add_u64 v[34:35], v[34:35], 2, s[12:13]
	s_or_b64 exec, exec, s[0:1]
	v_ashrrev_i32_e32 v97, 31, v96
	v_lshlrev_b64 v[50:51], 11, v[96:97]
	v_lshl_add_u64 v[50:51], s[62:63], 0, v[50:51]
	s_waitcnt vmcnt(27)
	v_fmac_f32_e32 v111, 0.5, v52
	v_lshl_add_u64 v[50:51], v[130:131], 1, v[50:51]
	v_lshl_add_u64 v[34:35], v[34:35], 0, v[134:135]
	s_and_saveexec_b64 s[0:1], s[10:11]
	s_cbranch_execz .LBB0_1129
	global_store_dword v[34:35], v111, off
	v_mul_f32_e32 v52, v111, v242
	v_cvt_pk_bf16_f32 v52, v52, s0
	global_store_short v[50:51], v52, off
.LBB0_1129:
	s_or_b64 exec, exec, s[0:1]
	s_waitcnt vmcnt(26)
	v_fmac_f32_e32 v112, 0.5, v36
	s_and_saveexec_b64 s[0:1], s[10:11]
	s_cbranch_execz .LBB0_1131
	global_store_dword v[34:35], v112, off offset:128
	v_mul_f32_e32 v34, v112, v243
	v_cvt_pk_bf16_f32 v34, v34, s0
	global_store_short v[50:51], v34, off offset:64
.LBB0_1131:
	s_or_b64 exec, exec, s[0:1]
	v_cmp_gt_i32_e64 s[10:11], s34, v94
	s_nop 1
	v_cndmask_b32_e64 v34, v179, v94, s[10:11]
	v_mul_hi_i32 v35, v34, s30
	v_lshrrev_b32_e32 v36, 31, v35
	v_ashrrev_i32_e32 v35, 11, v35
	v_add_u32_e32 v36, v35, v36
	v_mad_i32_i24 v50, v36, s31, v34
	v_cmp_lt_i32_e64 s[0:1], 15, v50
	s_and_saveexec_b64 s[36:37], s[0:1]
	s_xor_b64 s[0:1], exec, s[36:37]
	v_lshlrev_b32_e32 v34, 12, v36
	v_add3_u32 v34, v34, v50, -16
	v_ashrrev_i32_e32 v35, 31, v34
	v_lshlrev_b64 v[34:35], 12, v[34:35]
	v_lshl_add_u64 v[34:35], s[88:89], 0, v[34:35]
	s_andn2_saveexec_b64 s[0:1], s[0:1]
	v_lshlrev_b32_e32 v34, 14, v36
	v_lshl_add_u32 v34, v50, 10, v34
	v_ashrrev_i32_e32 v35, 31, v34
	v_lshl_add_u64 v[34:35], v[34:35], 2, s[12:13]
	s_or_b64 exec, exec, s[0:1]
	v_ashrrev_i32_e32 v95, 31, v94
	v_lshlrev_b64 v[50:51], 11, v[94:95]
	v_lshl_add_u64 v[50:51], s[62:63], 0, v[50:51]
	s_waitcnt vmcnt(25)
	v_fmac_f32_e32 v113, 0.5, v53
	v_lshl_add_u64 v[50:51], v[130:131], 1, v[50:51]
	v_lshl_add_u64 v[34:35], v[34:35], 0, v[134:135]
	s_and_saveexec_b64 s[0:1], s[10:11]
	s_cbranch_execz .LBB0_1137
	global_store_dword v[34:35], v113, off
	v_mul_f32_e32 v36, v113, v242
	v_cvt_pk_bf16_f32 v36, v36, s0
	global_store_short v[50:51], v36, off
.LBB0_1137:
	s_or_b64 exec, exec, s[0:1]
	s_waitcnt vmcnt(24)
	v_fmac_f32_e32 v114, 0.5, v37
	s_and_saveexec_b64 s[0:1], s[10:11]
	s_cbranch_execz .LBB0_1139
	global_store_dword v[34:35], v114, off offset:128
	v_mul_f32_e32 v34, v114, v243
	v_cvt_pk_bf16_f32 v34, v34, s0
	global_store_short v[50:51], v34, off offset:64
.LBB0_1139:
	s_or_b64 exec, exec, s[0:1]
	v_cmp_gt_i32_e64 s[10:11], s34, v92
	s_nop 1
	v_cndmask_b32_e64 v34, v179, v92, s[10:11]
	v_mul_hi_i32 v35, v34, s30
	v_lshrrev_b32_e32 v36, 31, v35
	v_ashrrev_i32_e32 v35, 11, v35
	v_add_u32_e32 v36, v35, v36
	v_mad_i32_i24 v37, v36, s31, v34
	v_cmp_lt_i32_e64 s[0:1], 15, v37
	s_and_saveexec_b64 s[36:37], s[0:1]
	s_xor_b64 s[0:1], exec, s[36:37]
	v_lshlrev_b32_e32 v34, 12, v36
	v_add3_u32 v34, v34, v37, -16
	v_ashrrev_i32_e32 v35, 31, v34
	v_lshlrev_b64 v[34:35], 12, v[34:35]
	v_lshl_add_u64 v[34:35], s[88:89], 0, v[34:35]
	s_andn2_saveexec_b64 s[0:1], s[0:1]
	v_lshlrev_b32_e32 v34, 14, v36
	v_lshl_add_u32 v34, v37, 10, v34
	v_ashrrev_i32_e32 v35, 31, v34
	v_lshl_add_u64 v[34:35], v[34:35], 2, s[12:13]
	s_or_b64 exec, exec, s[0:1]
	v_ashrrev_i32_e32 v93, 31, v92
	v_lshlrev_b64 v[36:37], 11, v[92:93]
	v_lshl_add_u64 v[36:37], s[62:63], 0, v[36:37]
	s_waitcnt vmcnt(23)
	v_fmac_f32_e32 v115, 0.5, v54
	v_lshl_add_u64 v[36:37], v[130:131], 1, v[36:37]
	v_lshl_add_u64 v[34:35], v[34:35], 0, v[134:135]
	s_and_saveexec_b64 s[0:1], s[10:11]
	s_cbranch_execz .LBB0_1145
	global_store_dword v[34:35], v115, off
	v_mul_f32_e32 v50, v115, v242
	v_cvt_pk_bf16_f32 v50, v50, s0
	global_store_short v[36:37], v50, off
.LBB0_1145:
	s_or_b64 exec, exec, s[0:1]
	s_waitcnt vmcnt(22)
	v_fmac_f32_e32 v116, 0.5, v38
	s_and_saveexec_b64 s[0:1], s[10:11]
	s_cbranch_execz .LBB0_1147
	global_store_dword v[34:35], v116, off offset:128
	v_mul_f32_e32 v34, v116, v243
	v_cvt_pk_bf16_f32 v34, v34, s0
	global_store_short v[36:37], v34, off offset:64
.LBB0_1147:
	s_or_b64 exec, exec, s[0:1]
	v_cmp_gt_i32_e64 s[10:11], s34, v90
	s_nop 1
	v_cndmask_b32_e64 v34, v179, v90, s[10:11]
	v_mul_hi_i32 v35, v34, s30
	v_lshrrev_b32_e32 v36, 31, v35
	v_ashrrev_i32_e32 v35, 11, v35
	v_add_u32_e32 v36, v35, v36
	v_mad_i32_i24 v37, v36, s31, v34
	v_cmp_lt_i32_e64 s[0:1], 15, v37
	s_and_saveexec_b64 s[36:37], s[0:1]
	s_xor_b64 s[0:1], exec, s[36:37]
	v_lshlrev_b32_e32 v34, 12, v36
	v_add3_u32 v34, v34, v37, -16
	v_ashrrev_i32_e32 v35, 31, v34
	v_lshlrev_b64 v[34:35], 12, v[34:35]
	v_lshl_add_u64 v[34:35], s[88:89], 0, v[34:35]
	s_andn2_saveexec_b64 s[0:1], s[0:1]
	v_lshlrev_b32_e32 v34, 14, v36
	v_lshl_add_u32 v34, v37, 10, v34
	v_ashrrev_i32_e32 v35, 31, v34
	v_lshl_add_u64 v[34:35], v[34:35], 2, s[12:13]
	s_or_b64 exec, exec, s[0:1]
	v_ashrrev_i32_e32 v91, 31, v90
	v_lshlrev_b64 v[36:37], 11, v[90:91]
	v_lshl_add_u64 v[36:37], s[62:63], 0, v[36:37]
	s_waitcnt vmcnt(21)
	v_fmac_f32_e32 v117, 0.5, v55
	v_lshl_add_u64 v[36:37], v[130:131], 1, v[36:37]
	v_lshl_add_u64 v[34:35], v[34:35], 0, v[134:135]
	s_and_saveexec_b64 s[0:1], s[10:11]
	s_cbranch_execz .LBB0_1153
	global_store_dword v[34:35], v117, off
	v_mul_f32_e32 v38, v117, v242
	v_cvt_pk_bf16_f32 v38, v38, s0
	global_store_short v[36:37], v38, off
.LBB0_1153:
	s_or_b64 exec, exec, s[0:1]
	s_waitcnt vmcnt(20)
	v_fmac_f32_e32 v118, 0.5, v39
	s_and_saveexec_b64 s[0:1], s[10:11]
	s_cbranch_execz .LBB0_1155
	global_store_dword v[34:35], v118, off offset:128
	v_mul_f32_e32 v34, v118, v243
	v_cvt_pk_bf16_f32 v34, v34, s0
	global_store_short v[36:37], v34, off offset:64
.LBB0_1155:
	s_or_b64 exec, exec, s[0:1]
	v_cmp_gt_i32_e64 s[10:11], s34, v88
	s_nop 1
	v_cndmask_b32_e64 v34, v179, v88, s[10:11]
	v_mul_hi_i32 v35, v34, s30
	v_lshrrev_b32_e32 v36, 31, v35
	v_ashrrev_i32_e32 v35, 11, v35
	v_add_u32_e32 v36, v35, v36
	v_mad_i32_i24 v37, v36, s31, v34
	v_cmp_lt_i32_e64 s[0:1], 15, v37
	s_and_saveexec_b64 s[36:37], s[0:1]
	s_xor_b64 s[0:1], exec, s[36:37]
	v_lshlrev_b32_e32 v34, 12, v36
	v_add3_u32 v34, v34, v37, -16
	v_ashrrev_i32_e32 v35, 31, v34
	v_lshlrev_b64 v[34:35], 12, v[34:35]
	v_lshl_add_u64 v[34:35], s[88:89], 0, v[34:35]
	s_andn2_saveexec_b64 s[0:1], s[0:1]
	v_lshlrev_b32_e32 v34, 14, v36
	v_lshl_add_u32 v34, v37, 10, v34
	v_ashrrev_i32_e32 v35, 31, v34
	v_lshl_add_u64 v[34:35], v[34:35], 2, s[12:13]
	s_or_b64 exec, exec, s[0:1]
	v_ashrrev_i32_e32 v89, 31, v88
	v_lshlrev_b64 v[36:37], 11, v[88:89]
	v_lshl_add_u64 v[36:37], s[62:63], 0, v[36:37]
	s_waitcnt vmcnt(19)
	v_fmac_f32_e32 v119, 0.5, v56
	v_lshl_add_u64 v[36:37], v[130:131], 1, v[36:37]
	v_lshl_add_u64 v[34:35], v[34:35], 0, v[134:135]
	s_and_saveexec_b64 s[0:1], s[10:11]
	s_cbranch_execz .LBB0_1161
	global_store_dword v[34:35], v119, off
	v_mul_f32_e32 v38, v119, v242
	v_cvt_pk_bf16_f32 v38, v38, s0
	global_store_short v[36:37], v38, off
.LBB0_1161:
	s_or_b64 exec, exec, s[0:1]
	s_waitcnt vmcnt(18)
	v_fmac_f32_e32 v120, 0.5, v40
	s_and_saveexec_b64 s[0:1], s[10:11]
	s_cbranch_execz .LBB0_1163
	global_store_dword v[34:35], v120, off offset:128
	v_mul_f32_e32 v34, v120, v243
	v_cvt_pk_bf16_f32 v34, v34, s0
	global_store_short v[36:37], v34, off offset:64
.LBB0_1163:
	s_or_b64 exec, exec, s[0:1]
	v_cmp_gt_i32_e64 s[10:11], s34, v86
	s_nop 1
	v_cndmask_b32_e64 v34, v179, v86, s[10:11]
	v_mul_hi_i32 v35, v34, s30
	v_lshrrev_b32_e32 v36, 31, v35
	v_ashrrev_i32_e32 v35, 11, v35
	v_add_u32_e32 v36, v35, v36
	v_mad_i32_i24 v37, v36, s31, v34
	v_cmp_lt_i32_e64 s[0:1], 15, v37
	s_and_saveexec_b64 s[36:37], s[0:1]
	s_xor_b64 s[0:1], exec, s[36:37]
	v_lshlrev_b32_e32 v34, 12, v36
	v_add3_u32 v34, v34, v37, -16
	v_ashrrev_i32_e32 v35, 31, v34
	v_lshlrev_b64 v[34:35], 12, v[34:35]
	v_lshl_add_u64 v[34:35], s[88:89], 0, v[34:35]
	s_andn2_saveexec_b64 s[0:1], s[0:1]
	v_lshlrev_b32_e32 v34, 14, v36
	v_lshl_add_u32 v34, v37, 10, v34
	v_ashrrev_i32_e32 v35, 31, v34
	v_lshl_add_u64 v[34:35], v[34:35], 2, s[12:13]
	s_or_b64 exec, exec, s[0:1]
	v_ashrrev_i32_e32 v87, 31, v86
	v_lshlrev_b64 v[36:37], 11, v[86:87]
	v_lshl_add_u64 v[36:37], s[62:63], 0, v[36:37]
	s_waitcnt vmcnt(17)
	v_fmac_f32_e32 v121, 0.5, v57
	v_lshl_add_u64 v[36:37], v[130:131], 1, v[36:37]
	v_lshl_add_u64 v[34:35], v[34:35], 0, v[134:135]
	s_and_saveexec_b64 s[0:1], s[10:11]
	s_cbranch_execz .LBB0_1169
	global_store_dword v[34:35], v121, off
	v_mul_f32_e32 v38, v121, v242
	v_cvt_pk_bf16_f32 v38, v38, s0
	global_store_short v[36:37], v38, off
.LBB0_1169:
	s_or_b64 exec, exec, s[0:1]
	s_waitcnt vmcnt(16)
	v_fmac_f32_e32 v122, 0.5, v41
	s_and_saveexec_b64 s[0:1], s[10:11]
	s_cbranch_execz .LBB0_1171
	global_store_dword v[34:35], v122, off offset:128
	v_mul_f32_e32 v34, v122, v243
	v_cvt_pk_bf16_f32 v34, v34, s0
	global_store_short v[36:37], v34, off offset:64
.LBB0_1171:
	s_or_b64 exec, exec, s[0:1]
	v_cmp_gt_i32_e64 s[10:11], s34, v84
	s_nop 1
	v_cndmask_b32_e64 v34, v179, v84, s[10:11]
	v_mul_hi_i32 v35, v34, s30
	v_lshrrev_b32_e32 v36, 31, v35
	v_ashrrev_i32_e32 v35, 11, v35
	v_add_u32_e32 v36, v35, v36
	v_mad_i32_i24 v37, v36, s31, v34
	v_cmp_lt_i32_e64 s[0:1], 15, v37
	s_and_saveexec_b64 s[36:37], s[0:1]
	s_xor_b64 s[0:1], exec, s[36:37]
	v_lshlrev_b32_e32 v34, 12, v36
	v_add3_u32 v34, v34, v37, -16
	v_ashrrev_i32_e32 v35, 31, v34
	v_lshlrev_b64 v[34:35], 12, v[34:35]
	v_lshl_add_u64 v[34:35], s[88:89], 0, v[34:35]
	s_andn2_saveexec_b64 s[0:1], s[0:1]
	v_lshlrev_b32_e32 v34, 14, v36
	v_lshl_add_u32 v34, v37, 10, v34
	v_ashrrev_i32_e32 v35, 31, v34
	v_lshl_add_u64 v[34:35], v[34:35], 2, s[12:13]
	s_or_b64 exec, exec, s[0:1]
	v_ashrrev_i32_e32 v85, 31, v84
	v_lshlrev_b64 v[36:37], 11, v[84:85]
	v_lshl_add_u64 v[36:37], s[62:63], 0, v[36:37]
	s_waitcnt vmcnt(15)
	v_fmac_f32_e32 v123, 0.5, v58
	v_lshl_add_u64 v[36:37], v[130:131], 1, v[36:37]
	v_lshl_add_u64 v[34:35], v[34:35], 0, v[134:135]
	s_and_saveexec_b64 s[0:1], s[10:11]
	s_cbranch_execz .LBB0_1177
	global_store_dword v[34:35], v123, off
	v_mul_f32_e32 v38, v123, v242
	v_cvt_pk_bf16_f32 v38, v38, s0
	global_store_short v[36:37], v38, off
.LBB0_1177:
	s_or_b64 exec, exec, s[0:1]
	s_waitcnt vmcnt(14)
	v_fmac_f32_e32 v124, 0.5, v42
	s_and_saveexec_b64 s[0:1], s[10:11]
	s_cbranch_execz .LBB0_1179
	global_store_dword v[34:35], v124, off offset:128
	v_mul_f32_e32 v34, v124, v243
	v_cvt_pk_bf16_f32 v34, v34, s0
	global_store_short v[36:37], v34, off offset:64
.LBB0_1179:
	s_or_b64 exec, exec, s[0:1]
	v_cmp_gt_i32_e64 s[10:11], s34, v82
	s_nop 1
	v_cndmask_b32_e64 v34, v179, v82, s[10:11]
	v_mul_hi_i32 v35, v34, s30
	v_lshrrev_b32_e32 v36, 31, v35
	v_ashrrev_i32_e32 v35, 11, v35
	v_add_u32_e32 v36, v35, v36
	v_mad_i32_i24 v37, v36, s31, v34
	v_cmp_lt_i32_e64 s[0:1], 15, v37
	s_and_saveexec_b64 s[36:37], s[0:1]
	s_xor_b64 s[0:1], exec, s[36:37]
	v_lshlrev_b32_e32 v34, 12, v36
	v_add3_u32 v34, v34, v37, -16
	v_ashrrev_i32_e32 v35, 31, v34
	v_lshlrev_b64 v[34:35], 12, v[34:35]
	v_lshl_add_u64 v[34:35], s[88:89], 0, v[34:35]
	s_andn2_saveexec_b64 s[0:1], s[0:1]
	v_lshlrev_b32_e32 v34, 14, v36
	v_lshl_add_u32 v34, v37, 10, v34
	v_ashrrev_i32_e32 v35, 31, v34
	v_lshl_add_u64 v[34:35], v[34:35], 2, s[12:13]
	s_or_b64 exec, exec, s[0:1]
	v_ashrrev_i32_e32 v83, 31, v82
	v_lshlrev_b64 v[36:37], 11, v[82:83]
	v_lshl_add_u64 v[36:37], s[62:63], 0, v[36:37]
	s_waitcnt vmcnt(13)
	v_fmac_f32_e32 v125, 0.5, v59
	v_lshl_add_u64 v[36:37], v[130:131], 1, v[36:37]
	v_lshl_add_u64 v[34:35], v[34:35], 0, v[134:135]
	s_and_saveexec_b64 s[0:1], s[10:11]
	s_cbranch_execz .LBB0_1185
	global_store_dword v[34:35], v125, off
	v_mul_f32_e32 v38, v125, v242
	v_cvt_pk_bf16_f32 v38, v38, s0
	global_store_short v[36:37], v38, off
.LBB0_1185:
	s_or_b64 exec, exec, s[0:1]
	s_waitcnt vmcnt(12)
	v_fmac_f32_e32 v126, 0.5, v43
	s_and_saveexec_b64 s[0:1], s[10:11]
	s_cbranch_execz .LBB0_1187
	global_store_dword v[34:35], v126, off offset:128
	v_mul_f32_e32 v34, v126, v243
	v_cvt_pk_bf16_f32 v34, v34, s0
	global_store_short v[36:37], v34, off offset:64
.LBB0_1187:
	s_or_b64 exec, exec, s[0:1]
	v_cmp_gt_i32_e64 s[10:11], s34, v80
	s_nop 1
	v_cndmask_b32_e64 v34, v179, v80, s[10:11]
	v_mul_hi_i32 v35, v34, s30
	v_lshrrev_b32_e32 v36, 31, v35
	v_ashrrev_i32_e32 v35, 11, v35
	v_add_u32_e32 v36, v35, v36
	v_mad_i32_i24 v37, v36, s31, v34
	v_cmp_lt_i32_e64 s[0:1], 15, v37
	s_and_saveexec_b64 s[36:37], s[0:1]
	s_xor_b64 s[0:1], exec, s[36:37]
	v_lshlrev_b32_e32 v34, 12, v36
	v_add3_u32 v34, v34, v37, -16
	v_ashrrev_i32_e32 v35, 31, v34
	v_lshlrev_b64 v[34:35], 12, v[34:35]
	v_lshl_add_u64 v[34:35], s[88:89], 0, v[34:35]
	s_andn2_saveexec_b64 s[0:1], s[0:1]
	v_lshlrev_b32_e32 v34, 14, v36
	v_lshl_add_u32 v34, v37, 10, v34
	v_ashrrev_i32_e32 v35, 31, v34
	v_lshl_add_u64 v[34:35], v[34:35], 2, s[12:13]
	s_or_b64 exec, exec, s[0:1]
	v_ashrrev_i32_e32 v81, 31, v80
	v_lshlrev_b64 v[36:37], 11, v[80:81]
	v_lshl_add_u64 v[36:37], s[62:63], 0, v[36:37]
	s_waitcnt vmcnt(11)
	v_fmac_f32_e32 v127, 0.5, v60
	v_lshl_add_u64 v[36:37], v[130:131], 1, v[36:37]
	v_lshl_add_u64 v[34:35], v[34:35], 0, v[134:135]
	s_and_saveexec_b64 s[0:1], s[10:11]
	s_cbranch_execz .LBB0_1193
	global_store_dword v[34:35], v127, off
	v_mul_f32_e32 v38, v127, v242
	v_cvt_pk_bf16_f32 v38, v38, s0
	global_store_short v[36:37], v38, off
.LBB0_1193:
	s_or_b64 exec, exec, s[0:1]
	s_waitcnt vmcnt(10)
	v_fmac_f32_e32 v128, 0.5, v44
	s_and_saveexec_b64 s[0:1], s[10:11]
	s_cbranch_execz .LBB0_1195
	global_store_dword v[34:35], v128, off offset:128
	v_mul_f32_e32 v34, v128, v243
	v_cvt_pk_bf16_f32 v34, v34, s0
	global_store_short v[36:37], v34, off offset:64
.LBB0_1195:
	s_or_b64 exec, exec, s[0:1]
	v_cmp_gt_i32_e64 s[10:11], s34, v78
	s_nop 1
	v_cndmask_b32_e64 v34, v179, v78, s[10:11]
	v_mul_hi_i32 v35, v34, s30
	v_lshrrev_b32_e32 v36, 31, v35
	v_ashrrev_i32_e32 v35, 11, v35
	v_add_u32_e32 v36, v35, v36
	v_mad_i32_i24 v37, v36, s31, v34
	v_cmp_lt_i32_e64 s[0:1], 15, v37
	s_and_saveexec_b64 s[36:37], s[0:1]
	s_xor_b64 s[0:1], exec, s[36:37]
	v_lshlrev_b32_e32 v34, 12, v36
	v_add3_u32 v34, v34, v37, -16
	v_ashrrev_i32_e32 v35, 31, v34
	v_lshlrev_b64 v[34:35], 12, v[34:35]
	v_lshl_add_u64 v[34:35], s[88:89], 0, v[34:35]
	s_andn2_saveexec_b64 s[0:1], s[0:1]
	v_lshlrev_b32_e32 v34, 14, v36
	v_lshl_add_u32 v34, v37, 10, v34
	v_ashrrev_i32_e32 v35, 31, v34
	v_lshl_add_u64 v[34:35], v[34:35], 2, s[12:13]
	s_or_b64 exec, exec, s[0:1]
	v_ashrrev_i32_e32 v79, 31, v78
	v_lshlrev_b64 v[36:37], 11, v[78:79]
	v_lshl_add_u64 v[36:37], s[62:63], 0, v[36:37]
	s_waitcnt vmcnt(9)
	v_fmac_f32_e32 v129, 0.5, v61
	v_lshl_add_u64 v[36:37], v[130:131], 1, v[36:37]
	v_lshl_add_u64 v[34:35], v[34:35], 0, v[134:135]
	s_and_saveexec_b64 s[0:1], s[10:11]
	s_cbranch_execz .LBB0_1201
	global_store_dword v[34:35], v129, off
	v_mul_f32_e32 v38, v129, v242
	v_cvt_pk_bf16_f32 v38, v38, s0
	global_store_short v[36:37], v38, off
.LBB0_1201:
	s_or_b64 exec, exec, s[0:1]
	s_waitcnt vmcnt(8)
	v_fmac_f32_e32 v137, 0.5, v45
	s_and_saveexec_b64 s[0:1], s[10:11]
	s_cbranch_execz .LBB0_1203
	global_store_dword v[34:35], v137, off offset:128
	v_mul_f32_e32 v34, v137, v243
	v_cvt_pk_bf16_f32 v34, v34, s0
	global_store_short v[36:37], v34, off offset:64
.LBB0_1203:
	s_or_b64 exec, exec, s[0:1]
	v_cmp_gt_i32_e64 s[10:11], s34, v76
	s_nop 1
	v_cndmask_b32_e64 v34, v179, v76, s[10:11]
	v_mul_hi_i32 v35, v34, s30
	v_lshrrev_b32_e32 v36, 31, v35
	v_ashrrev_i32_e32 v35, 11, v35
	v_add_u32_e32 v36, v35, v36
	v_mad_i32_i24 v37, v36, s31, v34
	v_cmp_lt_i32_e64 s[0:1], 15, v37
	s_and_saveexec_b64 s[36:37], s[0:1]
	s_xor_b64 s[0:1], exec, s[36:37]
	v_lshlrev_b32_e32 v34, 12, v36
	v_add3_u32 v34, v34, v37, -16
	v_ashrrev_i32_e32 v35, 31, v34
	v_lshlrev_b64 v[34:35], 12, v[34:35]
	v_lshl_add_u64 v[34:35], s[88:89], 0, v[34:35]
	s_andn2_saveexec_b64 s[0:1], s[0:1]
	v_lshlrev_b32_e32 v34, 14, v36
	v_lshl_add_u32 v34, v37, 10, v34
	v_ashrrev_i32_e32 v35, 31, v34
	v_lshl_add_u64 v[34:35], v[34:35], 2, s[12:13]
	s_or_b64 exec, exec, s[0:1]
	v_ashrrev_i32_e32 v77, 31, v76
	v_lshlrev_b64 v[36:37], 11, v[76:77]
	v_lshl_add_u64 v[36:37], s[62:63], 0, v[36:37]
	s_waitcnt vmcnt(7)
	v_fmac_f32_e32 v138, 0.5, v62
	v_lshl_add_u64 v[36:37], v[130:131], 1, v[36:37]
	v_lshl_add_u64 v[34:35], v[34:35], 0, v[134:135]
	s_and_saveexec_b64 s[0:1], s[10:11]
	s_cbranch_execz .LBB0_1209
	global_store_dword v[34:35], v138, off
	v_mul_f32_e32 v38, v138, v242
	v_cvt_pk_bf16_f32 v38, v38, s0
	global_store_short v[36:37], v38, off
.LBB0_1209:
	s_or_b64 exec, exec, s[0:1]
	s_waitcnt vmcnt(6)
	v_fmac_f32_e32 v139, 0.5, v46
	s_and_saveexec_b64 s[0:1], s[10:11]
	s_cbranch_execz .LBB0_1211
	global_store_dword v[34:35], v139, off offset:128
	v_mul_f32_e32 v34, v139, v243
	v_cvt_pk_bf16_f32 v34, v34, s0
	global_store_short v[36:37], v34, off offset:64
.LBB0_1211:
	s_or_b64 exec, exec, s[0:1]
	v_cmp_gt_i32_e64 s[10:11], s34, v74
	s_nop 1
	v_cndmask_b32_e64 v34, v179, v74, s[10:11]
	v_mul_hi_i32 v35, v34, s30
	v_lshrrev_b32_e32 v36, 31, v35
	v_ashrrev_i32_e32 v35, 11, v35
	v_add_u32_e32 v36, v35, v36
	v_mad_i32_i24 v37, v36, s31, v34
	v_cmp_lt_i32_e64 s[0:1], 15, v37
	s_and_saveexec_b64 s[36:37], s[0:1]
	s_xor_b64 s[0:1], exec, s[36:37]
	v_lshlrev_b32_e32 v34, 12, v36
	v_add3_u32 v34, v34, v37, -16
	v_ashrrev_i32_e32 v35, 31, v34
	v_lshlrev_b64 v[34:35], 12, v[34:35]
	v_lshl_add_u64 v[34:35], s[88:89], 0, v[34:35]
	s_andn2_saveexec_b64 s[0:1], s[0:1]
	v_lshlrev_b32_e32 v34, 14, v36
	v_lshl_add_u32 v34, v37, 10, v34
	v_ashrrev_i32_e32 v35, 31, v34
	v_lshl_add_u64 v[34:35], v[34:35], 2, s[12:13]
	s_or_b64 exec, exec, s[0:1]
	v_ashrrev_i32_e32 v75, 31, v74
	v_lshlrev_b64 v[36:37], 11, v[74:75]
	v_lshl_add_u64 v[36:37], s[62:63], 0, v[36:37]
	s_waitcnt vmcnt(5)
	v_fmac_f32_e32 v140, 0.5, v63
	v_lshl_add_u64 v[36:37], v[130:131], 1, v[36:37]
	v_lshl_add_u64 v[34:35], v[34:35], 0, v[134:135]
	s_and_saveexec_b64 s[0:1], s[10:11]
	s_cbranch_execz .LBB0_1217
	global_store_dword v[34:35], v140, off
	v_mul_f32_e32 v38, v140, v242
	v_cvt_pk_bf16_f32 v38, v38, s0
	global_store_short v[36:37], v38, off
.LBB0_1217:
	s_or_b64 exec, exec, s[0:1]
	s_waitcnt vmcnt(4)
	v_fmac_f32_e32 v141, 0.5, v47
	s_and_saveexec_b64 s[0:1], s[10:11]
	s_cbranch_execz .LBB0_1219
	global_store_dword v[34:35], v141, off offset:128
	v_mul_f32_e32 v34, v141, v243
	v_cvt_pk_bf16_f32 v34, v34, s0
	global_store_short v[36:37], v34, off offset:64
.LBB0_1219:
	s_or_b64 exec, exec, s[0:1]
	v_cmp_gt_i32_e64 s[10:11], s34, v72
	s_nop 1
	v_cndmask_b32_e64 v34, v179, v72, s[10:11]
	v_mul_hi_i32 v35, v34, s30
	v_lshrrev_b32_e32 v36, 31, v35
	v_ashrrev_i32_e32 v35, 11, v35
	v_add_u32_e32 v36, v35, v36
	v_mad_i32_i24 v37, v36, s31, v34
	v_cmp_lt_i32_e64 s[0:1], 15, v37
	s_and_saveexec_b64 s[36:37], s[0:1]
	s_xor_b64 s[0:1], exec, s[36:37]
	v_lshlrev_b32_e32 v34, 12, v36
	v_add3_u32 v34, v34, v37, -16
	v_ashrrev_i32_e32 v35, 31, v34
	v_lshlrev_b64 v[34:35], 12, v[34:35]
	v_lshl_add_u64 v[34:35], s[88:89], 0, v[34:35]
	s_andn2_saveexec_b64 s[0:1], s[0:1]
	v_lshlrev_b32_e32 v34, 14, v36
	v_lshl_add_u32 v34, v37, 10, v34
	v_ashrrev_i32_e32 v35, 31, v34
	v_lshl_add_u64 v[34:35], v[34:35], 2, s[12:13]
	s_or_b64 exec, exec, s[0:1]
	v_ashrrev_i32_e32 v73, 31, v72
	v_lshlrev_b64 v[36:37], 11, v[72:73]
	v_lshl_add_u64 v[36:37], s[62:63], 0, v[36:37]
	s_waitcnt vmcnt(3)
	v_fmac_f32_e32 v142, 0.5, v64
	v_lshl_add_u64 v[36:37], v[130:131], 1, v[36:37]
	v_lshl_add_u64 v[34:35], v[34:35], 0, v[134:135]
	s_and_saveexec_b64 s[0:1], s[10:11]
	s_cbranch_execz .LBB0_1225
	global_store_dword v[34:35], v142, off
	v_mul_f32_e32 v38, v142, v242
	v_cvt_pk_bf16_f32 v38, v38, s0
	global_store_short v[36:37], v38, off
.LBB0_1225:
	s_or_b64 exec, exec, s[0:1]
	s_waitcnt vmcnt(2)
	v_fmac_f32_e32 v143, 0.5, v48
	s_and_saveexec_b64 s[0:1], s[10:11]
	s_cbranch_execz .LBB0_1227
	global_store_dword v[34:35], v143, off offset:128
	v_mul_f32_e32 v34, v143, v243
	v_cvt_pk_bf16_f32 v34, v34, s0
	global_store_short v[36:37], v34, off offset:64
.LBB0_1227:
	s_or_b64 exec, exec, s[0:1]
	v_cmp_gt_i32_e64 s[10:11], s34, v70
	s_nop 1
	v_cndmask_b32_e64 v34, v179, v70, s[10:11]
	v_mul_hi_i32 v35, v34, s30
	v_lshrrev_b32_e32 v36, 31, v35
	v_ashrrev_i32_e32 v35, 11, v35
	v_add_u32_e32 v36, v35, v36
	v_mad_i32_i24 v37, v36, s31, v34
	v_cmp_lt_i32_e64 s[0:1], 15, v37
	s_and_saveexec_b64 s[36:37], s[0:1]
	s_xor_b64 s[0:1], exec, s[36:37]
	v_lshlrev_b32_e32 v34, 12, v36
	v_add3_u32 v34, v34, v37, -16
	v_ashrrev_i32_e32 v35, 31, v34
	v_lshlrev_b64 v[34:35], 12, v[34:35]
	v_lshl_add_u64 v[34:35], s[88:89], 0, v[34:35]
	s_andn2_saveexec_b64 s[0:1], s[0:1]
	v_lshlrev_b32_e32 v34, 14, v36
	v_lshl_add_u32 v34, v37, 10, v34
	v_ashrrev_i32_e32 v35, 31, v34
	v_lshl_add_u64 v[34:35], v[34:35], 2, s[12:13]
	s_or_b64 exec, exec, s[0:1]
	v_ashrrev_i32_e32 v71, 31, v70
	v_lshlrev_b64 v[36:37], 11, v[70:71]
	v_lshl_add_u64 v[36:37], s[62:63], 0, v[36:37]
	s_waitcnt vmcnt(1)
	v_fmac_f32_e32 v144, 0.5, v65
	v_lshl_add_u64 v[36:37], v[130:131], 1, v[36:37]
	v_lshl_add_u64 v[34:35], v[34:35], 0, v[134:135]
	s_and_saveexec_b64 s[0:1], s[10:11]
	s_cbranch_execz .LBB0_1233
	global_store_dword v[34:35], v144, off
	v_mul_f32_e32 v38, v144, v242
	v_cvt_pk_bf16_f32 v38, v38, s0
	global_store_short v[36:37], v38, off
.LBB0_1233:
	s_or_b64 exec, exec, s[0:1]
	s_waitcnt vmcnt(0)
	v_fmac_f32_e32 v145, 0.5, v49
	s_and_saveexec_b64 s[0:1], s[10:11]
	s_cbranch_execz .LBB0_1235
	global_store_dword v[34:35], v145, off offset:128
	v_mul_f32_e32 v34, v145, v243
	v_cvt_pk_bf16_f32 v34, v34, s0
	global_store_short v[36:37], v34, off offset:64
.LBB0_1235:
	s_or_b64 exec, exec, s[0:1]
	v_or_b32_e32 v64, 0x60, v136
	v_min_i32_e32 v34, 0x403f, v64
	v_mul_hi_i32 v35, v34, s30
	v_lshrrev_b32_e32 v36, 31, v35
	v_ashrrev_i32_e32 v35, 11, v35
	v_add_u32_e32 v37, v35, v36
	v_mad_i32_i24 v36, v37, s31, v34
	v_cmp_lt_i32_e64 s[0:1], 15, v36
	s_and_saveexec_b64 s[10:11], s[0:1]
	s_xor_b64 s[0:1], exec, s[10:11]
	v_lshlrev_b32_e32 v34, 12, v37
	v_add3_u32 v34, v34, v36, -16
	v_ashrrev_i32_e32 v35, 31, v34
	v_lshlrev_b64 v[34:35], 12, v[34:35]
	v_lshl_add_u64 v[34:35], s[56:57], 0, v[34:35]
	s_andn2_saveexec_b64 s[0:1], s[0:1]
	v_lshlrev_b32_e32 v34, 10, v36
	v_ashrrev_i32_e32 v35, 31, v34
	v_lshl_add_u64 v[34:35], v[34:35], 2, s[58:59]
	s_or_b64 exec, exec, s[0:1]
	v_lshl_add_u64 v[34:35], v[130:131], 2, v[34:35]
	global_load_dword v72, v[34:35], off
	global_load_dword v73, v[34:35], off offset:128
	v_or_b32_e32 v62, 0x61, v136
	v_min_i32_e32 v34, 0x403f, v62
	v_mul_hi_i32 v35, v34, s30
	v_lshrrev_b32_e32 v36, 31, v35
	v_ashrrev_i32_e32 v35, 11, v35
	v_add_u32_e32 v37, v35, v36
	v_mad_i32_i24 v36, v37, s31, v34
	v_cmp_lt_i32_e64 s[0:1], 15, v36
	s_and_saveexec_b64 s[10:11], s[0:1]
	s_xor_b64 s[0:1], exec, s[10:11]
	v_lshlrev_b32_e32 v34, 12, v37
	v_add3_u32 v34, v34, v36, -16
	v_ashrrev_i32_e32 v35, 31, v34
	v_lshlrev_b64 v[34:35], 12, v[34:35]
	v_lshl_add_u64 v[34:35], s[56:57], 0, v[34:35]
	s_andn2_saveexec_b64 s[0:1], s[0:1]
	v_lshlrev_b32_e32 v34, 10, v36
	v_ashrrev_i32_e32 v35, 31, v34
	v_lshl_add_u64 v[34:35], v[34:35], 2, s[58:59]
	s_or_b64 exec, exec, s[0:1]
	v_lshl_add_u64 v[34:35], v[130:131], 2, v[34:35]
	global_load_dword v74, v[34:35], off
	global_load_dword v75, v[34:35], off offset:128
	v_or_b32_e32 v60, 0x62, v136
	v_min_i32_e32 v34, 0x403f, v60
	v_mul_hi_i32 v35, v34, s30
	v_lshrrev_b32_e32 v36, 31, v35
	v_ashrrev_i32_e32 v35, 11, v35
	v_add_u32_e32 v37, v35, v36
	v_mad_i32_i24 v36, v37, s31, v34
	v_cmp_lt_i32_e64 s[0:1], 15, v36
	s_and_saveexec_b64 s[10:11], s[0:1]
	s_xor_b64 s[0:1], exec, s[10:11]
	v_lshlrev_b32_e32 v34, 12, v37
	v_add3_u32 v34, v34, v36, -16
	v_ashrrev_i32_e32 v35, 31, v34
	v_lshlrev_b64 v[34:35], 12, v[34:35]
	v_lshl_add_u64 v[34:35], s[56:57], 0, v[34:35]
	s_andn2_saveexec_b64 s[0:1], s[0:1]
	v_lshlrev_b32_e32 v34, 10, v36
	v_ashrrev_i32_e32 v35, 31, v34
	v_lshl_add_u64 v[34:35], v[34:35], 2, s[58:59]
	s_or_b64 exec, exec, s[0:1]
	v_lshl_add_u64 v[34:35], v[130:131], 2, v[34:35]
	global_load_dword v76, v[34:35], off
	global_load_dword v77, v[34:35], off offset:128
	v_or_b32_e32 v58, 0x63, v136
	v_min_i32_e32 v34, 0x403f, v58
	v_mul_hi_i32 v35, v34, s30
	v_lshrrev_b32_e32 v36, 31, v35
	v_ashrrev_i32_e32 v35, 11, v35
	v_add_u32_e32 v37, v35, v36
	v_mad_i32_i24 v36, v37, s31, v34
	v_cmp_lt_i32_e64 s[0:1], 15, v36
	s_and_saveexec_b64 s[10:11], s[0:1]
	s_xor_b64 s[0:1], exec, s[10:11]
	v_lshlrev_b32_e32 v34, 12, v37
	v_add3_u32 v34, v34, v36, -16
	v_ashrrev_i32_e32 v35, 31, v34
	v_lshlrev_b64 v[34:35], 12, v[34:35]
	v_lshl_add_u64 v[34:35], s[56:57], 0, v[34:35]
	s_andn2_saveexec_b64 s[0:1], s[0:1]
	v_lshlrev_b32_e32 v34, 10, v36
	v_ashrrev_i32_e32 v35, 31, v34
	v_lshl_add_u64 v[34:35], v[34:35], 2, s[58:59]
	s_or_b64 exec, exec, s[0:1]
	v_lshl_add_u64 v[34:35], v[130:131], 2, v[34:35]
	global_load_dword v78, v[34:35], off
	global_load_dword v79, v[34:35], off offset:128
	v_or_b32_e32 v56, 0x68, v136
	v_min_i32_e32 v34, 0x403f, v56
	v_mul_hi_i32 v35, v34, s30
	v_lshrrev_b32_e32 v36, 31, v35
	v_ashrrev_i32_e32 v35, 11, v35
	v_add_u32_e32 v37, v35, v36
	v_mad_i32_i24 v36, v37, s31, v34
	v_cmp_lt_i32_e64 s[0:1], 15, v36
	s_and_saveexec_b64 s[10:11], s[0:1]
	s_xor_b64 s[0:1], exec, s[10:11]
	v_lshlrev_b32_e32 v34, 12, v37
	v_add3_u32 v34, v34, v36, -16
	v_ashrrev_i32_e32 v35, 31, v34
	v_lshlrev_b64 v[34:35], 12, v[34:35]
	v_lshl_add_u64 v[34:35], s[56:57], 0, v[34:35]
	s_andn2_saveexec_b64 s[0:1], s[0:1]
	v_lshlrev_b32_e32 v34, 10, v36
	v_ashrrev_i32_e32 v35, 31, v34
	v_lshl_add_u64 v[34:35], v[34:35], 2, s[58:59]
	s_or_b64 exec, exec, s[0:1]
	v_lshl_add_u64 v[34:35], v[130:131], 2, v[34:35]
	global_load_dword v80, v[34:35], off
	global_load_dword v81, v[34:35], off offset:128
	v_or_b32_e32 v54, 0x69, v136
	v_min_i32_e32 v34, 0x403f, v54
	v_mul_hi_i32 v35, v34, s30
	v_lshrrev_b32_e32 v36, 31, v35
	v_ashrrev_i32_e32 v35, 11, v35
	v_add_u32_e32 v37, v35, v36
	v_mad_i32_i24 v36, v37, s31, v34
	v_cmp_lt_i32_e64 s[0:1], 15, v36
	s_and_saveexec_b64 s[10:11], s[0:1]
	s_xor_b64 s[0:1], exec, s[10:11]
	v_lshlrev_b32_e32 v34, 12, v37
	v_add3_u32 v34, v34, v36, -16
	v_ashrrev_i32_e32 v35, 31, v34
	v_lshlrev_b64 v[34:35], 12, v[34:35]
	v_lshl_add_u64 v[34:35], s[56:57], 0, v[34:35]
	s_andn2_saveexec_b64 s[0:1], s[0:1]
	v_lshlrev_b32_e32 v34, 10, v36
	v_ashrrev_i32_e32 v35, 31, v34
	v_lshl_add_u64 v[34:35], v[34:35], 2, s[58:59]
	s_or_b64 exec, exec, s[0:1]
	v_lshl_add_u64 v[34:35], v[130:131], 2, v[34:35]
	global_load_dword v82, v[34:35], off
	global_load_dword v83, v[34:35], off offset:128
	v_or_b32_e32 v52, 0x6a, v136
	v_min_i32_e32 v34, 0x403f, v52
	v_mul_hi_i32 v35, v34, s30
	v_lshrrev_b32_e32 v36, 31, v35
	v_ashrrev_i32_e32 v35, 11, v35
	v_add_u32_e32 v37, v35, v36
	v_mad_i32_i24 v36, v37, s31, v34
	v_cmp_lt_i32_e64 s[0:1], 15, v36
	s_and_saveexec_b64 s[10:11], s[0:1]
	s_xor_b64 s[0:1], exec, s[10:11]
	v_lshlrev_b32_e32 v34, 12, v37
	v_add3_u32 v34, v34, v36, -16
	v_ashrrev_i32_e32 v35, 31, v34
	v_lshlrev_b64 v[34:35], 12, v[34:35]
	v_lshl_add_u64 v[34:35], s[56:57], 0, v[34:35]
	s_andn2_saveexec_b64 s[0:1], s[0:1]
	v_lshlrev_b32_e32 v34, 10, v36
	v_ashrrev_i32_e32 v35, 31, v34
	v_lshl_add_u64 v[34:35], v[34:35], 2, s[58:59]
	s_or_b64 exec, exec, s[0:1]
	v_lshl_add_u64 v[34:35], v[130:131], 2, v[34:35]
	global_load_dword v84, v[34:35], off
	global_load_dword v85, v[34:35], off offset:128
	v_or_b32_e32 v50, 0x6b, v136
	v_min_i32_e32 v34, 0x403f, v50
	v_mul_hi_i32 v35, v34, s30
	v_lshrrev_b32_e32 v36, 31, v35
	v_ashrrev_i32_e32 v35, 11, v35
	v_add_u32_e32 v37, v35, v36
	v_mad_i32_i24 v36, v37, s31, v34
	v_cmp_lt_i32_e64 s[0:1], 15, v36
	s_and_saveexec_b64 s[10:11], s[0:1]
	s_xor_b64 s[0:1], exec, s[10:11]
	v_lshlrev_b32_e32 v34, 12, v37
	v_add3_u32 v34, v34, v36, -16
	v_ashrrev_i32_e32 v35, 31, v34
	v_lshlrev_b64 v[34:35], 12, v[34:35]
	v_lshl_add_u64 v[34:35], s[56:57], 0, v[34:35]
	s_andn2_saveexec_b64 s[0:1], s[0:1]
	v_lshlrev_b32_e32 v34, 10, v36
	v_ashrrev_i32_e32 v35, 31, v34
	v_lshl_add_u64 v[34:35], v[34:35], 2, s[58:59]
	s_or_b64 exec, exec, s[0:1]
	v_lshl_add_u64 v[34:35], v[130:131], 2, v[34:35]
	global_load_dword v86, v[34:35], off
	global_load_dword v87, v[34:35], off offset:128
	v_or_b32_e32 v48, 0x70, v136
	v_min_i32_e32 v34, 0x403f, v48
	v_mul_hi_i32 v35, v34, s30
	v_lshrrev_b32_e32 v36, 31, v35
	v_ashrrev_i32_e32 v35, 11, v35
	v_add_u32_e32 v37, v35, v36
	v_mad_i32_i24 v36, v37, s31, v34
	v_cmp_lt_i32_e64 s[0:1], 15, v36
	s_and_saveexec_b64 s[10:11], s[0:1]
	s_xor_b64 s[0:1], exec, s[10:11]
	v_lshlrev_b32_e32 v34, 12, v37
	v_add3_u32 v34, v34, v36, -16
	v_ashrrev_i32_e32 v35, 31, v34
	v_lshlrev_b64 v[34:35], 12, v[34:35]
	v_lshl_add_u64 v[34:35], s[56:57], 0, v[34:35]
	s_andn2_saveexec_b64 s[0:1], s[0:1]
	v_lshlrev_b32_e32 v34, 10, v36
	v_ashrrev_i32_e32 v35, 31, v34
	v_lshl_add_u64 v[34:35], v[34:35], 2, s[58:59]
	s_or_b64 exec, exec, s[0:1]
	v_lshl_add_u64 v[34:35], v[130:131], 2, v[34:35]
	global_load_dword v88, v[34:35], off
	global_load_dword v89, v[34:35], off offset:128
	v_or_b32_e32 v46, 0x71, v136
	v_min_i32_e32 v34, 0x403f, v46
	v_mul_hi_i32 v35, v34, s30
	v_lshrrev_b32_e32 v36, 31, v35
	v_ashrrev_i32_e32 v35, 11, v35
	v_add_u32_e32 v37, v35, v36
	v_mad_i32_i24 v36, v37, s31, v34
	v_cmp_lt_i32_e64 s[0:1], 15, v36
	s_and_saveexec_b64 s[10:11], s[0:1]
	s_xor_b64 s[0:1], exec, s[10:11]
	v_lshlrev_b32_e32 v34, 12, v37
	v_add3_u32 v34, v34, v36, -16
	v_ashrrev_i32_e32 v35, 31, v34
	v_lshlrev_b64 v[34:35], 12, v[34:35]
	v_lshl_add_u64 v[34:35], s[56:57], 0, v[34:35]
	s_andn2_saveexec_b64 s[0:1], s[0:1]
	v_lshlrev_b32_e32 v34, 10, v36
	v_ashrrev_i32_e32 v35, 31, v34
	v_lshl_add_u64 v[34:35], v[34:35], 2, s[58:59]
	s_or_b64 exec, exec, s[0:1]
	v_lshl_add_u64 v[34:35], v[130:131], 2, v[34:35]
	global_load_dword v90, v[34:35], off
	global_load_dword v91, v[34:35], off offset:128
	v_or_b32_e32 v44, 0x72, v136
	v_min_i32_e32 v34, 0x403f, v44
	v_mul_hi_i32 v35, v34, s30
	v_lshrrev_b32_e32 v36, 31, v35
	v_ashrrev_i32_e32 v35, 11, v35
	v_add_u32_e32 v37, v35, v36
	v_mad_i32_i24 v36, v37, s31, v34
	v_cmp_lt_i32_e64 s[0:1], 15, v36
	s_and_saveexec_b64 s[10:11], s[0:1]
	s_xor_b64 s[0:1], exec, s[10:11]
	v_lshlrev_b32_e32 v34, 12, v37
	v_add3_u32 v34, v34, v36, -16
	v_ashrrev_i32_e32 v35, 31, v34
	v_lshlrev_b64 v[34:35], 12, v[34:35]
	v_lshl_add_u64 v[34:35], s[56:57], 0, v[34:35]
	s_andn2_saveexec_b64 s[0:1], s[0:1]
	v_lshlrev_b32_e32 v34, 10, v36
	v_ashrrev_i32_e32 v35, 31, v34
	v_lshl_add_u64 v[34:35], v[34:35], 2, s[58:59]
	s_or_b64 exec, exec, s[0:1]
	v_lshl_add_u64 v[34:35], v[130:131], 2, v[34:35]
	global_load_dword v92, v[34:35], off
	global_load_dword v93, v[34:35], off offset:128
	v_or_b32_e32 v42, 0x73, v136
	v_min_i32_e32 v34, 0x403f, v42
	v_mul_hi_i32 v35, v34, s30
	v_lshrrev_b32_e32 v36, 31, v35
	v_ashrrev_i32_e32 v35, 11, v35
	v_add_u32_e32 v37, v35, v36
	v_mad_i32_i24 v36, v37, s31, v34
	v_cmp_lt_i32_e64 s[0:1], 15, v36
	s_and_saveexec_b64 s[10:11], s[0:1]
	s_xor_b64 s[0:1], exec, s[10:11]
	v_lshlrev_b32_e32 v34, 12, v37
	v_add3_u32 v34, v34, v36, -16
	v_ashrrev_i32_e32 v35, 31, v34
	v_lshlrev_b64 v[34:35], 12, v[34:35]
	v_lshl_add_u64 v[34:35], s[56:57], 0, v[34:35]
	s_andn2_saveexec_b64 s[0:1], s[0:1]
	v_lshlrev_b32_e32 v34, 10, v36
	v_ashrrev_i32_e32 v35, 31, v34
	v_lshl_add_u64 v[34:35], v[34:35], 2, s[58:59]
	s_or_b64 exec, exec, s[0:1]
	v_lshl_add_u64 v[34:35], v[130:131], 2, v[34:35]
	global_load_dword v94, v[34:35], off
	global_load_dword v95, v[34:35], off offset:128
	v_or_b32_e32 v40, 0x78, v136
	v_min_i32_e32 v34, 0x403f, v40
	v_mul_hi_i32 v35, v34, s30
	v_lshrrev_b32_e32 v36, 31, v35
	v_ashrrev_i32_e32 v35, 11, v35
	v_add_u32_e32 v37, v35, v36
	v_mad_i32_i24 v36, v37, s31, v34
	v_cmp_lt_i32_e64 s[0:1], 15, v36
	s_and_saveexec_b64 s[10:11], s[0:1]
	s_xor_b64 s[0:1], exec, s[10:11]
	v_lshlrev_b32_e32 v34, 12, v37
	v_add3_u32 v34, v34, v36, -16
	v_ashrrev_i32_e32 v35, 31, v34
	v_lshlrev_b64 v[34:35], 12, v[34:35]
	v_lshl_add_u64 v[34:35], s[56:57], 0, v[34:35]
	s_andn2_saveexec_b64 s[0:1], s[0:1]
	v_lshlrev_b32_e32 v34, 10, v36
	v_ashrrev_i32_e32 v35, 31, v34
	v_lshl_add_u64 v[34:35], v[34:35], 2, s[58:59]
	s_or_b64 exec, exec, s[0:1]
	v_lshl_add_u64 v[34:35], v[130:131], 2, v[34:35]
	global_load_dword v96, v[34:35], off
	global_load_dword v97, v[34:35], off offset:128
	v_or_b32_e32 v38, 0x79, v136
	v_min_i32_e32 v34, 0x403f, v38
	v_mul_hi_i32 v35, v34, s30
	v_lshrrev_b32_e32 v36, 31, v35
	v_ashrrev_i32_e32 v35, 11, v35
	v_add_u32_e32 v37, v35, v36
	v_mad_i32_i24 v36, v37, s31, v34
	v_cmp_lt_i32_e64 s[0:1], 15, v36
	s_and_saveexec_b64 s[10:11], s[0:1]
	s_xor_b64 s[0:1], exec, s[10:11]
	v_lshlrev_b32_e32 v34, 12, v37
	v_add3_u32 v34, v34, v36, -16
	v_ashrrev_i32_e32 v35, 31, v34
	v_lshlrev_b64 v[34:35], 12, v[34:35]
	v_lshl_add_u64 v[34:35], s[56:57], 0, v[34:35]
	s_andn2_saveexec_b64 s[0:1], s[0:1]
	v_lshlrev_b32_e32 v34, 10, v36
	v_ashrrev_i32_e32 v35, 31, v34
	v_lshl_add_u64 v[34:35], v[34:35], 2, s[58:59]
	s_or_b64 exec, exec, s[0:1]
	v_lshl_add_u64 v[34:35], v[130:131], 2, v[34:35]
	global_load_dword v99, v[34:35], off
	global_load_dword v101, v[34:35], off offset:128
	v_or_b32_e32 v36, 0x7a, v136
	v_min_i32_e32 v34, 0x403f, v36
	v_mul_hi_i32 v35, v34, s30
	v_lshrrev_b32_e32 v37, 31, v35
	v_ashrrev_i32_e32 v35, 11, v35
	v_add_u32_e32 v39, v35, v37
	v_mad_i32_i24 v37, v39, s31, v34
	v_cmp_lt_i32_e64 s[0:1], 15, v37
	s_and_saveexec_b64 s[10:11], s[0:1]
	s_xor_b64 s[0:1], exec, s[10:11]
	v_lshlrev_b32_e32 v34, 12, v39
	v_add3_u32 v34, v34, v37, -16
	v_ashrrev_i32_e32 v35, 31, v34
	v_lshlrev_b64 v[34:35], 12, v[34:35]
	v_lshl_add_u64 v[34:35], s[56:57], 0, v[34:35]
	s_andn2_saveexec_b64 s[0:1], s[0:1]
	v_lshlrev_b32_e32 v34, 10, v37
	v_ashrrev_i32_e32 v35, 31, v34
	v_lshl_add_u64 v[34:35], v[34:35], 2, s[58:59]
	s_or_b64 exec, exec, s[0:1]
	v_lshl_add_u64 v[34:35], v[130:131], 2, v[34:35]
	global_load_dword v102, v[34:35], off
	global_load_dword v103, v[34:35], off offset:128
	v_or_b32_e32 v34, 0x7b, v136
	v_min_i32_e32 v35, 0x403f, v34
	v_mul_hi_i32 v37, v35, s30
	v_lshrrev_b32_e32 v39, 31, v37
	v_ashrrev_i32_e32 v37, 11, v37
	v_add_u32_e32 v37, v37, v39
	v_mad_i32_i24 v35, v37, s31, v35
	v_cmp_lt_i32_e64 s[0:1], 15, v35
	s_and_saveexec_b64 s[10:11], s[0:1]
	s_xor_b64 s[0:1], exec, s[10:11]
	v_lshlrev_b32_e32 v37, 12, v37
	v_add3_u32 v70, v37, v35, -16
	v_ashrrev_i32_e32 v71, 31, v70
	v_lshlrev_b64 v[70:71], 12, v[70:71]
	v_lshl_add_u64 v[70:71], s[56:57], 0, v[70:71]
	s_andn2_saveexec_b64 s[0:1], s[0:1]
	v_lshlrev_b32_e32 v70, 10, v35
	v_ashrrev_i32_e32 v71, 31, v70
	v_lshl_add_u64 v[70:71], v[70:71], 2, s[58:59]
	s_or_b64 exec, exec, s[0:1]
	v_lshl_add_u64 v[70:71], v[130:131], 2, v[70:71]
	global_load_dword v98, v[70:71], off
	global_load_dword v100, v[70:71], off offset:128
	v_cmp_gt_i32_e64 s[10:11], s34, v64
	s_nop 1
	v_cndmask_b32_e64 v37, v179, v64, s[10:11]
	v_mul_hi_i32 v35, v37, s30
	v_lshrrev_b32_e32 v39, 31, v35
	v_ashrrev_i32_e32 v35, 11, v35
	v_add_u32_e32 v35, v35, v39
	v_mad_i32_i24 v37, v35, s31, v37
	v_cmp_lt_i32_e64 s[0:1], 15, v37
	s_and_saveexec_b64 s[36:37], s[0:1]
	s_xor_b64 s[0:1], exec, s[36:37]
	v_lshlrev_b32_e32 v35, 12, v35
	v_add3_u32 v70, v35, v37, -16
	v_ashrrev_i32_e32 v71, 31, v70
	v_lshlrev_b64 v[70:71], 12, v[70:71]
	v_lshl_add_u64 v[70:71], s[88:89], 0, v[70:71]
	s_andn2_saveexec_b64 s[0:1], s[0:1]
	v_lshlrev_b32_e32 v35, 14, v35
	v_lshl_add_u32 v70, v37, 10, v35
	v_ashrrev_i32_e32 v71, 31, v70
	v_lshl_add_u64 v[70:71], v[70:71], 2, s[12:13]
	s_or_b64 exec, exec, s[0:1]
	v_ashrrev_i32_e32 v65, 31, v64
	v_lshlrev_b64 v[64:65], 11, v[64:65]
	v_lshl_add_u64 v[64:65], s[62:63], 0, v[64:65]
	s_waitcnt vmcnt(31)
	v_fmac_f32_e32 v72, 0.5, v18
	v_lshl_add_u64 v[64:65], v[130:131], 1, v[64:65]
	v_lshl_add_u64 v[70:71], v[70:71], 0, v[134:135]
	s_and_saveexec_b64 s[0:1], s[10:11]
	s_cbranch_execz .LBB0_1305
	global_store_dword v[70:71], v72, off
	v_mul_f32_e32 v18, v72, v242
	v_cvt_pk_bf16_f32 v18, v18, s0
	global_store_short v[64:65], v18, off
.LBB0_1305:
	s_or_b64 exec, exec, s[0:1]
	s_waitcnt vmcnt(30)
	v_fmac_f32_e32 v73, 0.5, v2
	s_and_saveexec_b64 s[0:1], s[10:11]
	s_cbranch_execz .LBB0_1307
	global_store_dword v[70:71], v73, off offset:128
	v_mul_f32_e32 v2, v73, v243
	v_cvt_pk_bf16_f32 v2, v2, s0
	global_store_short v[64:65], v2, off offset:64
.LBB0_1307:
	s_or_b64 exec, exec, s[0:1]
	v_cmp_gt_i32_e64 s[10:11], s34, v62
	s_nop 1
	v_cndmask_b32_e64 v18, v179, v62, s[10:11]
	v_mul_hi_i32 v2, v18, s30
	v_lshrrev_b32_e32 v35, 31, v2
	v_ashrrev_i32_e32 v2, 11, v2
	v_add_u32_e32 v2, v2, v35
	v_mad_i32_i24 v18, v2, s31, v18
	v_cmp_lt_i32_e64 s[0:1], 15, v18
	s_and_saveexec_b64 s[36:37], s[0:1]
	s_xor_b64 s[0:1], exec, s[36:37]
	v_lshlrev_b32_e32 v2, 12, v2
	v_add3_u32 v64, v2, v18, -16
	v_ashrrev_i32_e32 v65, 31, v64
	v_lshlrev_b64 v[64:65], 12, v[64:65]
	v_lshl_add_u64 v[64:65], s[88:89], 0, v[64:65]
	s_andn2_saveexec_b64 s[0:1], s[0:1]
	v_lshlrev_b32_e32 v2, 14, v2
	v_lshl_add_u32 v64, v18, 10, v2
	v_ashrrev_i32_e32 v65, 31, v64
	v_lshl_add_u64 v[64:65], v[64:65], 2, s[12:13]
	s_or_b64 exec, exec, s[0:1]
	v_ashrrev_i32_e32 v63, 31, v62
	v_lshlrev_b64 v[62:63], 11, v[62:63]
	v_lshl_add_u64 v[62:63], s[62:63], 0, v[62:63]
	s_waitcnt vmcnt(29)
	v_fmac_f32_e32 v74, 0.5, v19
	v_lshl_add_u64 v[18:19], v[130:131], 1, v[62:63]
	v_lshl_add_u64 v[62:63], v[64:65], 0, v[134:135]
	s_and_saveexec_b64 s[0:1], s[10:11]
	s_cbranch_execz .LBB0_1313
	global_store_dword v[62:63], v74, off
	v_mul_f32_e32 v2, v74, v242
	v_cvt_pk_bf16_f32 v2, v2, s0
	global_store_short v[18:19], v2, off
.LBB0_1313:
	s_or_b64 exec, exec, s[0:1]
	s_waitcnt vmcnt(28)
	v_fmac_f32_e32 v75, 0.5, v3
	s_and_saveexec_b64 s[0:1], s[10:11]
	s_cbranch_execz .LBB0_1315
	global_store_dword v[62:63], v75, off offset:128
	v_mul_f32_e32 v2, v75, v243
	v_cvt_pk_bf16_f32 v2, v2, s0
	global_store_short v[18:19], v2, off offset:64
.LBB0_1315:
	s_or_b64 exec, exec, s[0:1]
	v_cmp_gt_i32_e64 s[10:11], s34, v60
	s_nop 1
	v_cndmask_b32_e64 v2, v179, v60, s[10:11]
	v_mul_hi_i32 v3, v2, s30
	v_lshrrev_b32_e32 v18, 31, v3
	v_ashrrev_i32_e32 v3, 11, v3
	v_add_u32_e32 v18, v3, v18
	v_mad_i32_i24 v19, v18, s31, v2
	v_cmp_lt_i32_e64 s[0:1], 15, v19
	s_and_saveexec_b64 s[36:37], s[0:1]
	s_xor_b64 s[0:1], exec, s[36:37]
	v_lshlrev_b32_e32 v2, 12, v18
	v_add3_u32 v2, v2, v19, -16
	v_ashrrev_i32_e32 v3, 31, v2
	v_lshlrev_b64 v[2:3], 12, v[2:3]
	v_lshl_add_u64 v[2:3], s[88:89], 0, v[2:3]
	s_andn2_saveexec_b64 s[0:1], s[0:1]
	v_lshlrev_b32_e32 v2, 14, v18
	v_lshl_add_u32 v2, v19, 10, v2
	v_ashrrev_i32_e32 v3, 31, v2
	v_lshl_add_u64 v[2:3], v[2:3], 2, s[12:13]
	s_or_b64 exec, exec, s[0:1]
	v_ashrrev_i32_e32 v61, 31, v60
	v_lshlrev_b64 v[18:19], 11, v[60:61]
	v_lshl_add_u64 v[18:19], s[62:63], 0, v[18:19]
	s_waitcnt vmcnt(27)
	v_fmac_f32_e32 v76, 0.5, v20
	v_lshl_add_u64 v[18:19], v[130:131], 1, v[18:19]
	v_lshl_add_u64 v[2:3], v[2:3], 0, v[134:135]
	s_and_saveexec_b64 s[0:1], s[10:11]
	s_cbranch_execz .LBB0_1321
	global_store_dword v[2:3], v76, off
	v_mul_f32_e32 v20, v76, v242
	v_cvt_pk_bf16_f32 v20, v20, s0
	global_store_short v[18:19], v20, off
.LBB0_1321:
	s_or_b64 exec, exec, s[0:1]
	s_waitcnt vmcnt(26)
	v_fmac_f32_e32 v77, 0.5, v4
	s_and_saveexec_b64 s[0:1], s[10:11]
	s_cbranch_execz .LBB0_1323
	global_store_dword v[2:3], v77, off offset:128
	v_mul_f32_e32 v2, v77, v243
	v_cvt_pk_bf16_f32 v2, v2, s0
	global_store_short v[18:19], v2, off offset:64
.LBB0_1323:
	s_or_b64 exec, exec, s[0:1]
	v_cmp_gt_i32_e64 s[10:11], s34, v58
	s_nop 1
	v_cndmask_b32_e64 v2, v179, v58, s[10:11]
	v_mul_hi_i32 v3, v2, s30
	v_lshrrev_b32_e32 v4, 31, v3
	v_ashrrev_i32_e32 v3, 11, v3
	v_add_u32_e32 v4, v3, v4
	v_mad_i32_i24 v18, v4, s31, v2
	v_cmp_lt_i32_e64 s[0:1], 15, v18
	s_and_saveexec_b64 s[36:37], s[0:1]
	s_xor_b64 s[0:1], exec, s[36:37]
	v_lshlrev_b32_e32 v2, 12, v4
	v_add3_u32 v2, v2, v18, -16
	v_ashrrev_i32_e32 v3, 31, v2
	v_lshlrev_b64 v[2:3], 12, v[2:3]
	v_lshl_add_u64 v[2:3], s[88:89], 0, v[2:3]
	s_andn2_saveexec_b64 s[0:1], s[0:1]
	v_lshlrev_b32_e32 v2, 14, v4
	v_lshl_add_u32 v2, v18, 10, v2
	v_ashrrev_i32_e32 v3, 31, v2
	v_lshl_add_u64 v[2:3], v[2:3], 2, s[12:13]
	s_or_b64 exec, exec, s[0:1]
	v_ashrrev_i32_e32 v59, 31, v58
	v_lshlrev_b64 v[18:19], 11, v[58:59]
	v_lshl_add_u64 v[18:19], s[62:63], 0, v[18:19]
	s_waitcnt vmcnt(25)
	v_fmac_f32_e32 v78, 0.5, v21
	v_lshl_add_u64 v[18:19], v[130:131], 1, v[18:19]
	v_lshl_add_u64 v[2:3], v[2:3], 0, v[134:135]
	s_and_saveexec_b64 s[0:1], s[10:11]
	s_cbranch_execz .LBB0_1329
	global_store_dword v[2:3], v78, off
	v_mul_f32_e32 v4, v78, v242
	v_cvt_pk_bf16_f32 v4, v4, s0
	global_store_short v[18:19], v4, off
.LBB0_1329:
	s_or_b64 exec, exec, s[0:1]
	s_waitcnt vmcnt(24)
	v_fmac_f32_e32 v79, 0.5, v5
	s_and_saveexec_b64 s[0:1], s[10:11]
	s_cbranch_execz .LBB0_1331
	global_store_dword v[2:3], v79, off offset:128
	v_mul_f32_e32 v2, v79, v243
	v_cvt_pk_bf16_f32 v2, v2, s0
	global_store_short v[18:19], v2, off offset:64
.LBB0_1331:
	s_or_b64 exec, exec, s[0:1]
	v_cmp_gt_i32_e64 s[10:11], s34, v56
	s_nop 1
	v_cndmask_b32_e64 v2, v179, v56, s[10:11]
	v_mul_hi_i32 v3, v2, s30
	v_lshrrev_b32_e32 v4, 31, v3
	v_ashrrev_i32_e32 v3, 11, v3
	v_add_u32_e32 v4, v3, v4
	v_mad_i32_i24 v5, v4, s31, v2
	v_cmp_lt_i32_e64 s[0:1], 15, v5
	s_and_saveexec_b64 s[36:37], s[0:1]
	s_xor_b64 s[0:1], exec, s[36:37]
	v_lshlrev_b32_e32 v2, 12, v4
	v_add3_u32 v2, v2, v5, -16
	v_ashrrev_i32_e32 v3, 31, v2
	v_lshlrev_b64 v[2:3], 12, v[2:3]
	v_lshl_add_u64 v[2:3], s[88:89], 0, v[2:3]
	s_andn2_saveexec_b64 s[0:1], s[0:1]
	v_lshlrev_b32_e32 v2, 14, v4
	v_lshl_add_u32 v2, v5, 10, v2
	v_ashrrev_i32_e32 v3, 31, v2
	v_lshl_add_u64 v[2:3], v[2:3], 2, s[12:13]
	s_or_b64 exec, exec, s[0:1]
	v_ashrrev_i32_e32 v57, 31, v56
	v_lshlrev_b64 v[4:5], 11, v[56:57]
	v_lshl_add_u64 v[4:5], s[62:63], 0, v[4:5]
	s_waitcnt vmcnt(23)
	v_fmac_f32_e32 v80, 0.5, v22
	v_lshl_add_u64 v[4:5], v[130:131], 1, v[4:5]
	v_lshl_add_u64 v[2:3], v[2:3], 0, v[134:135]
	s_and_saveexec_b64 s[0:1], s[10:11]
	s_cbranch_execz .LBB0_1337
	global_store_dword v[2:3], v80, off
	v_mul_f32_e32 v18, v80, v242
	v_cvt_pk_bf16_f32 v18, v18, s0
	global_store_short v[4:5], v18, off
.LBB0_1337:
	s_or_b64 exec, exec, s[0:1]
	s_waitcnt vmcnt(22)
	v_fmac_f32_e32 v81, 0.5, v6
	s_and_saveexec_b64 s[0:1], s[10:11]
	s_cbranch_execz .LBB0_1339
	global_store_dword v[2:3], v81, off offset:128
	v_mul_f32_e32 v2, v81, v243
	v_cvt_pk_bf16_f32 v2, v2, s0
	global_store_short v[4:5], v2, off offset:64
.LBB0_1339:
	s_or_b64 exec, exec, s[0:1]
	v_cmp_gt_i32_e64 s[10:11], s34, v54
	s_nop 1
	v_cndmask_b32_e64 v2, v179, v54, s[10:11]
	v_mul_hi_i32 v3, v2, s30
	v_lshrrev_b32_e32 v4, 31, v3
	v_ashrrev_i32_e32 v3, 11, v3
	v_add_u32_e32 v4, v3, v4
	v_mad_i32_i24 v5, v4, s31, v2
	v_cmp_lt_i32_e64 s[0:1], 15, v5
	s_and_saveexec_b64 s[36:37], s[0:1]
	s_xor_b64 s[0:1], exec, s[36:37]
	v_lshlrev_b32_e32 v2, 12, v4
	v_add3_u32 v2, v2, v5, -16
	v_ashrrev_i32_e32 v3, 31, v2
	v_lshlrev_b64 v[2:3], 12, v[2:3]
	v_lshl_add_u64 v[2:3], s[88:89], 0, v[2:3]
	s_andn2_saveexec_b64 s[0:1], s[0:1]
	v_lshlrev_b32_e32 v2, 14, v4
	v_lshl_add_u32 v2, v5, 10, v2
	v_ashrrev_i32_e32 v3, 31, v2
	v_lshl_add_u64 v[2:3], v[2:3], 2, s[12:13]
	s_or_b64 exec, exec, s[0:1]
	v_ashrrev_i32_e32 v55, 31, v54
	v_lshlrev_b64 v[4:5], 11, v[54:55]
	v_lshl_add_u64 v[4:5], s[62:63], 0, v[4:5]
	s_waitcnt vmcnt(21)
	v_fmac_f32_e32 v82, 0.5, v23
	v_lshl_add_u64 v[4:5], v[130:131], 1, v[4:5]
	v_lshl_add_u64 v[2:3], v[2:3], 0, v[134:135]
	s_and_saveexec_b64 s[0:1], s[10:11]
	s_cbranch_execz .LBB0_1345
	global_store_dword v[2:3], v82, off
	v_mul_f32_e32 v6, v82, v242
	v_cvt_pk_bf16_f32 v6, v6, s0
	global_store_short v[4:5], v6, off
.LBB0_1345:
	s_or_b64 exec, exec, s[0:1]
	s_waitcnt vmcnt(20)
	v_fmac_f32_e32 v83, 0.5, v7
	s_and_saveexec_b64 s[0:1], s[10:11]
	s_cbranch_execz .LBB0_1347
	global_store_dword v[2:3], v83, off offset:128
	v_mul_f32_e32 v2, v83, v243
	v_cvt_pk_bf16_f32 v2, v2, s0
	global_store_short v[4:5], v2, off offset:64
.LBB0_1347:
	s_or_b64 exec, exec, s[0:1]
	v_cmp_gt_i32_e64 s[10:11], s34, v52
	s_nop 1
	v_cndmask_b32_e64 v2, v179, v52, s[10:11]
	v_mul_hi_i32 v3, v2, s30
	v_lshrrev_b32_e32 v4, 31, v3
	v_ashrrev_i32_e32 v3, 11, v3
	v_add_u32_e32 v4, v3, v4
	v_mad_i32_i24 v5, v4, s31, v2
	v_cmp_lt_i32_e64 s[0:1], 15, v5
	s_and_saveexec_b64 s[36:37], s[0:1]
	s_xor_b64 s[0:1], exec, s[36:37]
	v_lshlrev_b32_e32 v2, 12, v4
	v_add3_u32 v2, v2, v5, -16
	v_ashrrev_i32_e32 v3, 31, v2
	v_lshlrev_b64 v[2:3], 12, v[2:3]
	v_lshl_add_u64 v[2:3], s[88:89], 0, v[2:3]
	s_andn2_saveexec_b64 s[0:1], s[0:1]
	v_lshlrev_b32_e32 v2, 14, v4
	v_lshl_add_u32 v2, v5, 10, v2
	v_ashrrev_i32_e32 v3, 31, v2
	v_lshl_add_u64 v[2:3], v[2:3], 2, s[12:13]
	s_or_b64 exec, exec, s[0:1]
	v_ashrrev_i32_e32 v53, 31, v52
	v_lshlrev_b64 v[4:5], 11, v[52:53]
	v_lshl_add_u64 v[4:5], s[62:63], 0, v[4:5]
	s_waitcnt vmcnt(19)
	v_fmac_f32_e32 v84, 0.5, v24
	v_lshl_add_u64 v[4:5], v[130:131], 1, v[4:5]
	v_lshl_add_u64 v[2:3], v[2:3], 0, v[134:135]
	s_and_saveexec_b64 s[0:1], s[10:11]
	s_cbranch_execz .LBB0_1353
	global_store_dword v[2:3], v84, off
	v_mul_f32_e32 v6, v84, v242
	v_cvt_pk_bf16_f32 v6, v6, s0
	global_store_short v[4:5], v6, off
.LBB0_1353:
	s_or_b64 exec, exec, s[0:1]
	s_waitcnt vmcnt(18)
	v_fmac_f32_e32 v85, 0.5, v8
	s_and_saveexec_b64 s[0:1], s[10:11]
	s_cbranch_execz .LBB0_1355
	global_store_dword v[2:3], v85, off offset:128
	v_mul_f32_e32 v2, v85, v243
	v_cvt_pk_bf16_f32 v2, v2, s0
	global_store_short v[4:5], v2, off offset:64
.LBB0_1355:
	s_or_b64 exec, exec, s[0:1]
	v_cmp_gt_i32_e64 s[10:11], s34, v50
	s_nop 1
	v_cndmask_b32_e64 v2, v179, v50, s[10:11]
	v_mul_hi_i32 v3, v2, s30
	v_lshrrev_b32_e32 v4, 31, v3
	v_ashrrev_i32_e32 v3, 11, v3
	v_add_u32_e32 v4, v3, v4
	v_mad_i32_i24 v5, v4, s31, v2
	v_cmp_lt_i32_e64 s[0:1], 15, v5
	s_and_saveexec_b64 s[36:37], s[0:1]
	s_xor_b64 s[0:1], exec, s[36:37]
	v_lshlrev_b32_e32 v2, 12, v4
	v_add3_u32 v2, v2, v5, -16
	v_ashrrev_i32_e32 v3, 31, v2
	v_lshlrev_b64 v[2:3], 12, v[2:3]
	v_lshl_add_u64 v[2:3], s[88:89], 0, v[2:3]
	s_andn2_saveexec_b64 s[0:1], s[0:1]
	v_lshlrev_b32_e32 v2, 14, v4
	v_lshl_add_u32 v2, v5, 10, v2
	v_ashrrev_i32_e32 v3, 31, v2
	v_lshl_add_u64 v[2:3], v[2:3], 2, s[12:13]
	s_or_b64 exec, exec, s[0:1]
	v_ashrrev_i32_e32 v51, 31, v50
	v_lshlrev_b64 v[4:5], 11, v[50:51]
	v_lshl_add_u64 v[4:5], s[62:63], 0, v[4:5]
	s_waitcnt vmcnt(17)
	v_fmac_f32_e32 v86, 0.5, v25
	v_lshl_add_u64 v[4:5], v[130:131], 1, v[4:5]
	v_lshl_add_u64 v[2:3], v[2:3], 0, v[134:135]
	s_and_saveexec_b64 s[0:1], s[10:11]
	s_cbranch_execz .LBB0_1361
	global_store_dword v[2:3], v86, off
	v_mul_f32_e32 v6, v86, v242
	v_cvt_pk_bf16_f32 v6, v6, s0
	global_store_short v[4:5], v6, off
.LBB0_1361:
	s_or_b64 exec, exec, s[0:1]
	s_waitcnt vmcnt(16)
	v_fmac_f32_e32 v87, 0.5, v9
	s_and_saveexec_b64 s[0:1], s[10:11]
	s_cbranch_execz .LBB0_1363
	global_store_dword v[2:3], v87, off offset:128
	v_mul_f32_e32 v2, v87, v243
	v_cvt_pk_bf16_f32 v2, v2, s0
	global_store_short v[4:5], v2, off offset:64
.LBB0_1363:
	s_or_b64 exec, exec, s[0:1]
	v_cmp_gt_i32_e64 s[10:11], s34, v48
	s_nop 1
	v_cndmask_b32_e64 v2, v179, v48, s[10:11]
	v_mul_hi_i32 v3, v2, s30
	v_lshrrev_b32_e32 v4, 31, v3
	v_ashrrev_i32_e32 v3, 11, v3
	v_add_u32_e32 v4, v3, v4
	v_mad_i32_i24 v5, v4, s31, v2
	v_cmp_lt_i32_e64 s[0:1], 15, v5
	s_and_saveexec_b64 s[36:37], s[0:1]
	s_xor_b64 s[0:1], exec, s[36:37]
	v_lshlrev_b32_e32 v2, 12, v4
	v_add3_u32 v2, v2, v5, -16
	v_ashrrev_i32_e32 v3, 31, v2
	v_lshlrev_b64 v[2:3], 12, v[2:3]
	v_lshl_add_u64 v[2:3], s[88:89], 0, v[2:3]
	s_andn2_saveexec_b64 s[0:1], s[0:1]
	v_lshlrev_b32_e32 v2, 14, v4
	v_lshl_add_u32 v2, v5, 10, v2
	v_ashrrev_i32_e32 v3, 31, v2
	v_lshl_add_u64 v[2:3], v[2:3], 2, s[12:13]
	s_or_b64 exec, exec, s[0:1]
	v_ashrrev_i32_e32 v49, 31, v48
	v_lshlrev_b64 v[4:5], 11, v[48:49]
	v_lshl_add_u64 v[4:5], s[62:63], 0, v[4:5]
	s_waitcnt vmcnt(15)
	v_fmac_f32_e32 v88, 0.5, v26
	v_lshl_add_u64 v[4:5], v[130:131], 1, v[4:5]
	v_lshl_add_u64 v[2:3], v[2:3], 0, v[134:135]
	s_and_saveexec_b64 s[0:1], s[10:11]
	s_cbranch_execz .LBB0_1369
	global_store_dword v[2:3], v88, off
	v_mul_f32_e32 v6, v88, v242
	v_cvt_pk_bf16_f32 v6, v6, s0
	global_store_short v[4:5], v6, off
.LBB0_1369:
	s_or_b64 exec, exec, s[0:1]
	s_waitcnt vmcnt(14)
	v_fmac_f32_e32 v89, 0.5, v10
	s_and_saveexec_b64 s[0:1], s[10:11]
	s_cbranch_execz .LBB0_1371
	global_store_dword v[2:3], v89, off offset:128
	v_mul_f32_e32 v2, v89, v243
	v_cvt_pk_bf16_f32 v2, v2, s0
	global_store_short v[4:5], v2, off offset:64
.LBB0_1371:
	s_or_b64 exec, exec, s[0:1]
	v_cmp_gt_i32_e64 s[10:11], s34, v46
	s_nop 1
	v_cndmask_b32_e64 v2, v179, v46, s[10:11]
	v_mul_hi_i32 v3, v2, s30
	v_lshrrev_b32_e32 v4, 31, v3
	v_ashrrev_i32_e32 v3, 11, v3
	v_add_u32_e32 v4, v3, v4
	v_mad_i32_i24 v5, v4, s31, v2
	v_cmp_lt_i32_e64 s[0:1], 15, v5
	s_and_saveexec_b64 s[36:37], s[0:1]
	s_xor_b64 s[0:1], exec, s[36:37]
	v_lshlrev_b32_e32 v2, 12, v4
	v_add3_u32 v2, v2, v5, -16
	v_ashrrev_i32_e32 v3, 31, v2
	v_lshlrev_b64 v[2:3], 12, v[2:3]
	v_lshl_add_u64 v[2:3], s[88:89], 0, v[2:3]
	s_andn2_saveexec_b64 s[0:1], s[0:1]
	v_lshlrev_b32_e32 v2, 14, v4
	v_lshl_add_u32 v2, v5, 10, v2
	v_ashrrev_i32_e32 v3, 31, v2
	v_lshl_add_u64 v[2:3], v[2:3], 2, s[12:13]
	s_or_b64 exec, exec, s[0:1]
	v_ashrrev_i32_e32 v47, 31, v46
	v_lshlrev_b64 v[4:5], 11, v[46:47]
	v_lshl_add_u64 v[4:5], s[62:63], 0, v[4:5]
	s_waitcnt vmcnt(13)
	v_fmac_f32_e32 v90, 0.5, v27
	v_lshl_add_u64 v[4:5], v[130:131], 1, v[4:5]
	v_lshl_add_u64 v[2:3], v[2:3], 0, v[134:135]
	s_and_saveexec_b64 s[0:1], s[10:11]
	s_cbranch_execz .LBB0_1377
	global_store_dword v[2:3], v90, off
	v_mul_f32_e32 v6, v90, v242
	v_cvt_pk_bf16_f32 v6, v6, s0
	global_store_short v[4:5], v6, off
.LBB0_1377:
	s_or_b64 exec, exec, s[0:1]
	s_waitcnt vmcnt(12)
	v_fmac_f32_e32 v91, 0.5, v11
	s_and_saveexec_b64 s[0:1], s[10:11]
	s_cbranch_execz .LBB0_1379
	global_store_dword v[2:3], v91, off offset:128
	v_mul_f32_e32 v2, v91, v243
	v_cvt_pk_bf16_f32 v2, v2, s0
	global_store_short v[4:5], v2, off offset:64
.LBB0_1379:
	s_or_b64 exec, exec, s[0:1]
	v_cmp_gt_i32_e64 s[10:11], s34, v44
	s_nop 1
	v_cndmask_b32_e64 v2, v179, v44, s[10:11]
	v_mul_hi_i32 v3, v2, s30
	v_lshrrev_b32_e32 v4, 31, v3
	v_ashrrev_i32_e32 v3, 11, v3
	v_add_u32_e32 v4, v3, v4
	v_mad_i32_i24 v5, v4, s31, v2
	v_cmp_lt_i32_e64 s[0:1], 15, v5
	s_and_saveexec_b64 s[36:37], s[0:1]
	s_xor_b64 s[0:1], exec, s[36:37]
	v_lshlrev_b32_e32 v2, 12, v4
	v_add3_u32 v2, v2, v5, -16
	v_ashrrev_i32_e32 v3, 31, v2
	v_lshlrev_b64 v[2:3], 12, v[2:3]
	v_lshl_add_u64 v[2:3], s[88:89], 0, v[2:3]
	s_andn2_saveexec_b64 s[0:1], s[0:1]
	v_lshlrev_b32_e32 v2, 14, v4
	v_lshl_add_u32 v2, v5, 10, v2
	v_ashrrev_i32_e32 v3, 31, v2
	v_lshl_add_u64 v[2:3], v[2:3], 2, s[12:13]
	s_or_b64 exec, exec, s[0:1]
	v_ashrrev_i32_e32 v45, 31, v44
	v_lshlrev_b64 v[4:5], 11, v[44:45]
	v_lshl_add_u64 v[4:5], s[62:63], 0, v[4:5]
	s_waitcnt vmcnt(11)
	v_fmac_f32_e32 v92, 0.5, v28
	v_lshl_add_u64 v[4:5], v[130:131], 1, v[4:5]
	v_lshl_add_u64 v[2:3], v[2:3], 0, v[134:135]
	s_and_saveexec_b64 s[0:1], s[10:11]
	s_cbranch_execz .LBB0_1385
	global_store_dword v[2:3], v92, off
	v_mul_f32_e32 v6, v92, v242
	v_cvt_pk_bf16_f32 v6, v6, s0
	global_store_short v[4:5], v6, off
.LBB0_1385:
	s_or_b64 exec, exec, s[0:1]
	s_waitcnt vmcnt(10)
	v_fmac_f32_e32 v93, 0.5, v12
	s_and_saveexec_b64 s[0:1], s[10:11]
	s_cbranch_execz .LBB0_1387
	global_store_dword v[2:3], v93, off offset:128
	v_mul_f32_e32 v2, v93, v243
	v_cvt_pk_bf16_f32 v2, v2, s0
	global_store_short v[4:5], v2, off offset:64
.LBB0_1387:
	s_or_b64 exec, exec, s[0:1]
	v_cmp_gt_i32_e64 s[10:11], s34, v42
	s_nop 1
	v_cndmask_b32_e64 v2, v179, v42, s[10:11]
	v_mul_hi_i32 v3, v2, s30
	v_lshrrev_b32_e32 v4, 31, v3
	v_ashrrev_i32_e32 v3, 11, v3
	v_add_u32_e32 v4, v3, v4
	v_mad_i32_i24 v5, v4, s31, v2
	v_cmp_lt_i32_e64 s[0:1], 15, v5
	s_and_saveexec_b64 s[36:37], s[0:1]
	s_xor_b64 s[0:1], exec, s[36:37]
	v_lshlrev_b32_e32 v2, 12, v4
	v_add3_u32 v2, v2, v5, -16
	v_ashrrev_i32_e32 v3, 31, v2
	v_lshlrev_b64 v[2:3], 12, v[2:3]
	v_lshl_add_u64 v[2:3], s[88:89], 0, v[2:3]
	s_andn2_saveexec_b64 s[0:1], s[0:1]
	v_lshlrev_b32_e32 v2, 14, v4
	v_lshl_add_u32 v2, v5, 10, v2
	v_ashrrev_i32_e32 v3, 31, v2
	v_lshl_add_u64 v[2:3], v[2:3], 2, s[12:13]
	s_or_b64 exec, exec, s[0:1]
	v_ashrrev_i32_e32 v43, 31, v42
	v_lshlrev_b64 v[4:5], 11, v[42:43]
	v_lshl_add_u64 v[4:5], s[62:63], 0, v[4:5]
	s_waitcnt vmcnt(9)
	v_fmac_f32_e32 v94, 0.5, v29
	v_lshl_add_u64 v[4:5], v[130:131], 1, v[4:5]
	v_lshl_add_u64 v[2:3], v[2:3], 0, v[134:135]
	s_and_saveexec_b64 s[0:1], s[10:11]
	s_cbranch_execz .LBB0_1393
	global_store_dword v[2:3], v94, off
	v_mul_f32_e32 v6, v94, v242
	v_cvt_pk_bf16_f32 v6, v6, s0
	global_store_short v[4:5], v6, off
.LBB0_1393:
	s_or_b64 exec, exec, s[0:1]
	s_waitcnt vmcnt(8)
	v_fmac_f32_e32 v95, 0.5, v13
	s_and_saveexec_b64 s[0:1], s[10:11]
	s_cbranch_execz .LBB0_1395
	global_store_dword v[2:3], v95, off offset:128
	v_mul_f32_e32 v2, v95, v243
	v_cvt_pk_bf16_f32 v2, v2, s0
	global_store_short v[4:5], v2, off offset:64
.LBB0_1395:
	s_or_b64 exec, exec, s[0:1]
	v_cmp_gt_i32_e64 s[10:11], s34, v40
	s_nop 1
	v_cndmask_b32_e64 v2, v179, v40, s[10:11]
	v_mul_hi_i32 v3, v2, s30
	v_lshrrev_b32_e32 v4, 31, v3
	v_ashrrev_i32_e32 v3, 11, v3
	v_add_u32_e32 v4, v3, v4
	v_mad_i32_i24 v5, v4, s31, v2
	v_cmp_lt_i32_e64 s[0:1], 15, v5
	s_and_saveexec_b64 s[36:37], s[0:1]
	s_xor_b64 s[0:1], exec, s[36:37]
	v_lshlrev_b32_e32 v2, 12, v4
	v_add3_u32 v2, v2, v5, -16
	v_ashrrev_i32_e32 v3, 31, v2
	v_lshlrev_b64 v[2:3], 12, v[2:3]
	v_lshl_add_u64 v[2:3], s[88:89], 0, v[2:3]
	s_andn2_saveexec_b64 s[0:1], s[0:1]
	v_lshlrev_b32_e32 v2, 14, v4
	v_lshl_add_u32 v2, v5, 10, v2
	v_ashrrev_i32_e32 v3, 31, v2
	v_lshl_add_u64 v[2:3], v[2:3], 2, s[12:13]
	s_or_b64 exec, exec, s[0:1]
	v_ashrrev_i32_e32 v41, 31, v40
	v_lshlrev_b64 v[4:5], 11, v[40:41]
	v_lshl_add_u64 v[4:5], s[62:63], 0, v[4:5]
	s_waitcnt vmcnt(7)
	v_fmac_f32_e32 v96, 0.5, v30
	v_lshl_add_u64 v[4:5], v[130:131], 1, v[4:5]
	v_lshl_add_u64 v[2:3], v[2:3], 0, v[134:135]
	s_and_saveexec_b64 s[0:1], s[10:11]
	s_cbranch_execz .LBB0_1401
	global_store_dword v[2:3], v96, off
	v_mul_f32_e32 v6, v96, v242
	v_cvt_pk_bf16_f32 v6, v6, s0
	global_store_short v[4:5], v6, off
.LBB0_1401:
	s_or_b64 exec, exec, s[0:1]
	s_waitcnt vmcnt(6)
	v_fmac_f32_e32 v97, 0.5, v14
	s_and_saveexec_b64 s[0:1], s[10:11]
	s_cbranch_execz .LBB0_1403
	global_store_dword v[2:3], v97, off offset:128
	v_mul_f32_e32 v2, v97, v243
	v_cvt_pk_bf16_f32 v2, v2, s0
	global_store_short v[4:5], v2, off offset:64
.LBB0_1403:
	s_or_b64 exec, exec, s[0:1]
	v_cmp_gt_i32_e64 s[10:11], s34, v38
	s_nop 1
	v_cndmask_b32_e64 v2, v179, v38, s[10:11]
	v_mul_hi_i32 v3, v2, s30
	v_lshrrev_b32_e32 v4, 31, v3
	v_ashrrev_i32_e32 v3, 11, v3
	v_add_u32_e32 v4, v3, v4
	v_mad_i32_i24 v5, v4, s31, v2
	v_cmp_lt_i32_e64 s[0:1], 15, v5
	s_and_saveexec_b64 s[36:37], s[0:1]
	s_xor_b64 s[0:1], exec, s[36:37]
	v_lshlrev_b32_e32 v2, 12, v4
	v_add3_u32 v2, v2, v5, -16
	v_ashrrev_i32_e32 v3, 31, v2
	v_lshlrev_b64 v[2:3], 12, v[2:3]
	v_lshl_add_u64 v[2:3], s[88:89], 0, v[2:3]
	s_andn2_saveexec_b64 s[0:1], s[0:1]
	v_lshlrev_b32_e32 v2, 14, v4
	v_lshl_add_u32 v2, v5, 10, v2
	v_ashrrev_i32_e32 v3, 31, v2
	v_lshl_add_u64 v[2:3], v[2:3], 2, s[12:13]
	s_or_b64 exec, exec, s[0:1]
	v_ashrrev_i32_e32 v39, 31, v38
	v_lshlrev_b64 v[4:5], 11, v[38:39]
	v_lshl_add_u64 v[4:5], s[62:63], 0, v[4:5]
	s_waitcnt vmcnt(5)
	v_fmac_f32_e32 v99, 0.5, v31
	v_lshl_add_u64 v[4:5], v[130:131], 1, v[4:5]
	v_lshl_add_u64 v[2:3], v[2:3], 0, v[134:135]
	s_and_saveexec_b64 s[0:1], s[10:11]
	s_cbranch_execz .LBB0_1409
	global_store_dword v[2:3], v99, off
	v_mul_f32_e32 v6, v99, v242
	v_cvt_pk_bf16_f32 v6, v6, s0
	global_store_short v[4:5], v6, off
.LBB0_1409:
	s_or_b64 exec, exec, s[0:1]
	s_waitcnt vmcnt(4)
	v_fmac_f32_e32 v101, 0.5, v15
	s_and_saveexec_b64 s[0:1], s[10:11]
	s_cbranch_execz .LBB0_1411
	global_store_dword v[2:3], v101, off offset:128
	v_mul_f32_e32 v2, v101, v243
	v_cvt_pk_bf16_f32 v2, v2, s0
	global_store_short v[4:5], v2, off offset:64
.LBB0_1411:
	s_or_b64 exec, exec, s[0:1]
	v_cmp_gt_i32_e64 s[10:11], s34, v36
	s_nop 1
	v_cndmask_b32_e64 v2, v179, v36, s[10:11]
	v_mul_hi_i32 v3, v2, s30
	v_lshrrev_b32_e32 v4, 31, v3
	v_ashrrev_i32_e32 v3, 11, v3
	v_add_u32_e32 v4, v3, v4
	v_mad_i32_i24 v5, v4, s31, v2
	v_cmp_lt_i32_e64 s[0:1], 15, v5
	s_and_saveexec_b64 s[36:37], s[0:1]
	s_xor_b64 s[0:1], exec, s[36:37]
	v_lshlrev_b32_e32 v2, 12, v4
	v_add3_u32 v2, v2, v5, -16
	v_ashrrev_i32_e32 v3, 31, v2
	v_lshlrev_b64 v[2:3], 12, v[2:3]
	v_lshl_add_u64 v[2:3], s[88:89], 0, v[2:3]
	s_andn2_saveexec_b64 s[0:1], s[0:1]
	v_lshlrev_b32_e32 v2, 14, v4
	v_lshl_add_u32 v2, v5, 10, v2
	v_ashrrev_i32_e32 v3, 31, v2
	v_lshl_add_u64 v[2:3], v[2:3], 2, s[12:13]
	s_or_b64 exec, exec, s[0:1]
	v_ashrrev_i32_e32 v37, 31, v36
	v_lshlrev_b64 v[4:5], 11, v[36:37]
	v_lshl_add_u64 v[4:5], s[62:63], 0, v[4:5]
	s_waitcnt vmcnt(3)
	v_fmac_f32_e32 v102, 0.5, v32
	v_lshl_add_u64 v[4:5], v[130:131], 1, v[4:5]
	v_lshl_add_u64 v[2:3], v[2:3], 0, v[134:135]
	s_and_saveexec_b64 s[0:1], s[10:11]
	s_cbranch_execz .LBB0_1417
	global_store_dword v[2:3], v102, off
	v_mul_f32_e32 v6, v102, v242
	v_cvt_pk_bf16_f32 v6, v6, s0
	global_store_short v[4:5], v6, off
.LBB0_1417:
	s_or_b64 exec, exec, s[0:1]
	s_waitcnt vmcnt(2)
	v_fmac_f32_e32 v103, 0.5, v16
	s_and_saveexec_b64 s[0:1], s[10:11]
	s_cbranch_execz .LBB0_1419
	global_store_dword v[2:3], v103, off offset:128
	v_mul_f32_e32 v2, v103, v243
	v_cvt_pk_bf16_f32 v2, v2, s0
	global_store_short v[4:5], v2, off offset:64
.LBB0_1419:
	s_or_b64 exec, exec, s[0:1]
	v_cmp_gt_i32_e64 s[10:11], s34, v34
	s_nop 1
	v_cndmask_b32_e64 v2, v179, v34, s[10:11]
	v_mul_hi_i32 v3, v2, s30
	v_lshrrev_b32_e32 v4, 31, v3
	v_ashrrev_i32_e32 v3, 11, v3
	v_add_u32_e32 v4, v3, v4
	v_mad_i32_i24 v5, v4, s31, v2
	v_cmp_lt_i32_e64 s[0:1], 15, v5
	s_and_saveexec_b64 s[36:37], s[0:1]
	s_xor_b64 s[0:1], exec, s[36:37]
	v_lshlrev_b32_e32 v2, 12, v4
	v_add3_u32 v2, v2, v5, -16
	v_ashrrev_i32_e32 v3, 31, v2
	v_lshlrev_b64 v[2:3], 12, v[2:3]
	v_lshl_add_u64 v[2:3], s[88:89], 0, v[2:3]
	s_andn2_saveexec_b64 s[0:1], s[0:1]
	v_lshlrev_b32_e32 v2, 14, v4
	v_lshl_add_u32 v2, v5, 10, v2
	v_ashrrev_i32_e32 v3, 31, v2
	v_lshl_add_u64 v[2:3], v[2:3], 2, s[12:13]
	s_or_b64 exec, exec, s[0:1]
	v_ashrrev_i32_e32 v35, 31, v34
	v_lshlrev_b64 v[4:5], 11, v[34:35]
	v_lshl_add_u64 v[4:5], s[62:63], 0, v[4:5]
	s_waitcnt vmcnt(1)
	v_fmac_f32_e32 v98, 0.5, v33
	v_lshl_add_u64 v[4:5], v[130:131], 1, v[4:5]
	v_lshl_add_u64 v[2:3], v[2:3], 0, v[134:135]
	s_and_saveexec_b64 s[0:1], s[10:11]
	s_cbranch_execz .LBB0_1425
	global_store_dword v[2:3], v98, off
	v_mul_f32_e32 v6, v98, v242
	v_cvt_pk_bf16_f32 v6, v6, s0
	global_store_short v[4:5], v6, off

.LBB0_2153:
	s_or_saveexec_b64 s[6:7], s[8:9]
	v_or_b32_e32 v128, 8, v138
	v_or_b32_e32 v129, 16, v138
	v_or_b32_e32 v130, 24, v138
	s_waitcnt vmcnt(3)
	v_add_u32_e32 v149, s18, v128
	v_lshl_add_u32 v150, v128, 2, v200
	s_waitcnt vmcnt(2)
	v_add_u32_e32 v147, s18, v129
	v_lshl_add_u32 v148, v129, 2, v200
	v_add_u32_e32 v145, s18, v130
	v_lshl_add_u32 v146, v130, 2, v200
	v_or_b32_e32 v144, 32, v138
	v_or_b32_e32 v143, 40, v138
	s_xor_b64 exec, exec, s[6:7]
	s_cbranch_execz .LBB0_2155
	s_waitcnt vmcnt(0)
	v_min_i32_e32 v128, 0x403f, v139
	v_mul_hi_i32 v129, v128, s36
	v_lshrrev_b32_e32 v130, 31, v129
	v_ashrrev_i32_e32 v129, 11, v129
	v_add_u32_e32 v129, v129, v130
	v_mul_i32_i24_e32 v129, 0x1010, v129
	v_and_b32_e32 v151, 15, v132
	v_sub_u32_e32 v128, v128, v129
	v_lshl_or_b32 v128, v128, 4, v151
	v_ashrrev_i32_e32 v129, 31, v128
	v_lshl_add_u64 v[128:129], v[128:129], 3, s[74:75]
	global_load_dwordx2 v[174:175], v[128:129], off
	v_add_u32_e32 v236,1,v139
	v_min_i32_e32 v240,0x403f,v236
	v_mul_hi_i32 v243,v240,s36
	v_lshrrev_b32_e32 v241,31,v243
	v_ashrrev_i32_e32 v243,11,v243
	v_add_u32_e32 v243,v243,v241
	v_mul_i32_i24_e32 v244,0x1010,v243
	v_sub_u32_e32 v244,v240,v244
	v_lshl_or_b32 v240,v244,4,v151
	v_ashrrev_i32_e32 v241,31,v240
	v_lshl_add_u64 v[240:241],v[240:241],3,s[74:75]
	global_load_dwordx2 v[176:177], v[240:241], off
	v_add_u32_e32 v236,2,v139
	v_min_i32_e32 v240,0x403f,v236
	v_mul_hi_i32 v243,v240,s36
	v_lshrrev_b32_e32 v244,31,v243
	v_ashrrev_i32_e32 v243,11,v243
	v_add_u32_e32 v243,v243,v244
	v_mul_i32_i24_e32 v241,0x1010,v243
	v_sub_u32_e32 v240,v240,v241
	v_lshl_or_b32 v240,v240,4,v151
	v_ashrrev_i32_e32 v241,31,v240
	v_lshl_add_u64 v[240:241],v[240:241],3,s[74:75]
	global_load_dwordx2 v[178:179], v[240:241], off
	v_add_u32_e32 v237,3,v139
	v_min_i32_e32 v240,0x403f,v237
	v_mul_hi_i32 v241,v240,s36
	v_lshrrev_b32_e32 v242,31,v241
	v_ashrrev_i32_e32 v241,11,v241
	v_add_u32_e32 v241,v241,v242
	v_mul_i32_i24_e32 v244,0x1010,v241
	v_sub_u32_e32 v244,v240,v244
	v_lshl_or_b32 v240,v244,4,v151
	v_ashrrev_i32_e32 v241,31,v240
	v_lshl_add_u64 v[240:241],v[240:241],3,s[74:75]
	global_load_dwordx2 v[180:181], v[240:241], off
	v_min_i32_e32 v236,0x403f,v149
	v_mul_hi_i32 v240,v236,s36
	v_lshrrev_b32_e32 v241,31,v240
	v_ashrrev_i32_e32 v240,11,v240
	v_add_u32_e32 v242,v240,v241
	v_mul_i32_i24_e32 v242,0x1010,v242
	v_sub_u32_e32 v236,v236,v242
	v_lshl_or_b32 v236,v236,4,v151
	v_ashrrev_i32_e32 v237,31,v236
	v_lshl_add_u64 v[236:237],v[236:237],3,s[74:75]
	global_load_dwordx2 v[182:183], v[236:237], off
	v_add_u32_e32 v237,9,v139
	v_min_i32_e32 v240,0x403f,v237
	v_mul_hi_i32 v242,v240,s36
	v_lshrrev_b32_e32 v243,31,v242
	v_ashrrev_i32_e32 v242,11,v242
	v_add_u32_e32 v241,v242,v243
	v_mul_i32_i24_e32 v244,0x1010,v241
	v_sub_u32_e32 v244,v240,v244
	v_lshl_or_b32 v240,v244,4,v151
	v_ashrrev_i32_e32 v241,31,v240
	v_lshl_add_u64 v[240:241],v[240:241],3,s[74:75]
	global_load_dwordx2 v[184:185], v[240:241], off
	v_mov_b32_e32 v243, v113
	v_add_u32_e32 v236,10,v139
	v_min_i32_e32 v240,0x403f,v236
	v_mul_hi_i32 v242,v240,s36
	v_lshrrev_b32_e32 v237,31,v242
	v_ashrrev_i32_e32 v242,11,v242
	v_add_u32_e32 v242,v242,v237
	v_mul_i32_i24_e32 v241,0x1010,v242
	v_sub_u32_e32 v240,v240,v241
	v_lshl_or_b32 v240,v240,4,v151
	v_ashrrev_i32_e32 v241,31,v240
	v_lshl_add_u64 v[240:241],v[240:241],3,s[74:75]
	global_load_dwordx2 v[186:187], v[240:241], off
	v_add_u32_e32 v237,11,v139
	v_min_i32_e32 v240,0x403f,v237
	v_mul_hi_i32 v241,v240,s36
	v_lshrrev_b32_e32 v242,31,v241
	v_ashrrev_i32_e32 v241,11,v241
	v_add_u32_e32 v241,v241,v242
	v_mul_i32_i24_e32 v241,0x1010,v241
	v_sub_u32_e32 v242,v240,v241
	v_lshl_or_b32 v242,v242,4,v151
	v_ashrrev_i32_e32 v243,31,v242
	v_lshl_add_u64 v[242:243],v[242:243],3,s[74:75]
	global_load_dwordx2 v[188:189], v[242:243], off
	v_min_i32_e32 v236,0x403f,v147
	v_mul_hi_i32 v240,v236,s36
	v_lshrrev_b32_e32 v241,31,v240
	v_ashrrev_i32_e32 v240,11,v240
	v_add_u32_e32 v240,v240,v241
	v_mul_i32_i24_e32 v240,0x1010,v240
	v_sub_u32_e32 v236,v236,v240
	v_lshl_or_b32 v236,v236,4,v151
	v_ashrrev_i32_e32 v237,31,v236
	v_lshl_add_u64 v[236:237],v[236:237],3,s[74:75]
	global_load_dwordx2 v[190:191], v[236:237], off
	v_add_u32_e32 v236,17,v139
	v_min_i32_e32 v240,0x403f,v236
	v_mul_hi_i32 v241,v240,s36
	v_lshrrev_b32_e32 v242,31,v241
	v_ashrrev_i32_e32 v241,11,v241
	v_add_u32_e32 v241,v241,v242
	v_mul_i32_i24_e32 v241,0x1010,v241
	v_sub_u32_e32 v240,v240,v241
	v_lshl_or_b32 v240,v240,4,v151
	v_ashrrev_i32_e32 v241,31,v240
	v_lshl_add_u64 v[240:241],v[240:241],3,s[74:75]
	global_load_dwordx2 v[194:195], v[240:241], off
	v_add_u32_e32 v237,18,v139
	v_min_i32_e32 v240,0x403f,v237
	v_mul_hi_i32 v241,v240,s36
	v_lshrrev_b32_e32 v242,31,v241
	v_ashrrev_i32_e32 v241,11,v241
	v_add_u32_e32 v241,v241,v242
	v_mul_i32_i24_e32 v241,0x1010,v241
	v_sub_u32_e32 v240,v240,v241
	v_lshl_or_b32 v240,v240,4,v151
	v_ashrrev_i32_e32 v241,31,v240
	v_lshl_add_u64 v[240:241],v[240:241],3,s[74:75]
	global_load_dwordx2 v[196:197], v[240:241], off
	v_add_u32_e32 v236,19,v139
	v_min_i32_e32 v240,0x403f,v236
	v_mul_hi_i32 v241,v240,s36
	v_lshrrev_b32_e32 v242,31,v241
	v_ashrrev_i32_e32 v241,11,v241
	v_add_u32_e32 v241,v241,v242
	v_mul_i32_i24_e32 v241,0x1010,v241
	v_sub_u32_e32 v240,v240,v241
	v_lshl_or_b32 v240,v240,4,v151
	v_ashrrev_i32_e32 v241,31,v240
	v_lshl_add_u64 v[240:241],v[240:241],3,s[74:75]
	global_load_dwordx2 v[198:199], v[240:241], off
	v_min_i32_e32 v236,0x403f,v145
	v_mul_hi_i32 v237,v236,s36
	v_lshrrev_b32_e32 v240,31,v237
	v_ashrrev_i32_e32 v237,11,v237
	v_add_u32_e32 v237,v237,v240
	v_mul_i32_i24_e32 v237,0x1010,v237
	v_sub_u32_e32 v236,v236,v237
	v_lshl_or_b32 v236,v236,4,v151
	v_ashrrev_i32_e32 v237,31,v236
	v_lshl_add_u64 v[236:237],v[236:237],3,s[74:75]
	global_load_dwordx2 v[204:205], v[236:237], off
	v_add_u32_e32 v236,25,v139
	v_min_i32_e32 v240,0x403f,v236
	v_mul_hi_i32 v241,v240,s36
	v_lshrrev_b32_e32 v242,31,v241
	v_ashrrev_i32_e32 v241,11,v241
	v_add_u32_e32 v241,v241,v242
	v_mul_i32_i24_e32 v241,0x1010,v241
	v_sub_u32_e32 v240,v240,v241
	v_lshl_or_b32 v240,v240,4,v151
	v_ashrrev_i32_e32 v241,31,v240
	v_lshl_add_u64 v[240:241],v[240:241],3,s[74:75]
	global_load_dwordx2 v[206:207], v[240:241], off
	v_add_u32_e32 v237,26,v139
	v_min_i32_e32 v240,0x403f,v237
	v_mul_hi_i32 v241,v240,s36
	v_lshrrev_b32_e32 v242,31,v241
	v_ashrrev_i32_e32 v241,11,v241
	v_add_u32_e32 v241,v241,v242
	v_mul_i32_i24_e32 v241,0x1010,v241
	v_sub_u32_e32 v240,v240,v241
	v_lshl_or_b32 v240,v240,4,v151
	v_ashrrev_i32_e32 v241,31,v240
	v_lshl_add_u64 v[240:241],v[240:241],3,s[74:75]
	global_load_dwordx2 v[224:225], v[240:241], off
	v_add_u32_e32 v236,27,v139
	v_min_i32_e32 v240,0x403f,v236
	v_mul_hi_i32 v241,v240,s36
	v_lshrrev_b32_e32 v242,31,v241
	v_ashrrev_i32_e32 v241,11,v241
	v_add_u32_e32 v241,v241,v242
	v_mul_i32_i24_e32 v241,0x1010,v241
	v_sub_u32_e32 v240,v240,v241
	v_lshl_or_b32 v240,v240,4,v151
	v_ashrrev_i32_e32 v241,31,v240
	v_lshl_add_u64 v[240:241],v[240:241],3,s[74:75]
	global_load_dwordx2 v[226:227], v[240:241], off
	v_mov_b32_e32 v243, v117
	v_add_u32_e32 v236,s18,v144
	v_min_i32_e32 v240,0x403f,v236
	v_mul_hi_i32 v241,v240,s36
	v_lshrrev_b32_e32 v242,31,v241
	v_ashrrev_i32_e32 v241,11,v241
	v_add_u32_e32 v241,v241,v242
	v_mul_i32_i24_e32 v241,0x1010,v241
	v_sub_u32_e32 v240,v240,v241
	v_lshl_or_b32 v240,v240,4,v151
	v_ashrrev_i32_e32 v241,31,v240
	v_lshl_add_u64 v[240:241],v[240:241],3,s[74:75]
	global_load_dwordx2 v[228:229], v[240:241], off
	v_add_u32_e32 v236,33,v139
	v_min_i32_e32 v240,0x403f,v236
	v_mul_hi_i32 v243,v240,s36
	v_lshrrev_b32_e32 v241,31,v243
	v_ashrrev_i32_e32 v245,11,v243
	v_add_u32_e32 v241,v245,v241
	v_mul_i32_i24_e32 v241,0x1010,v241
	v_sub_u32_e32 v240,v240,v241
	v_lshl_or_b32 v240,v240,4,v151
	v_ashrrev_i32_e32 v241,31,v240
	v_lshl_add_u64 v[240:241],v[240:241],3,s[74:75]
	global_load_dwordx2 v[230:231], v[240:241], off
	v_add_u32_e32 v236,34,v139
	v_min_i32_e32 v240,0x403f,v236
	v_mul_hi_i32 v242,v240,s36
	v_lshrrev_b32_e32 v237,31,v242
	v_ashrrev_i32_e32 v242,11,v242
	v_add_u32_e32 v242,v242,v237
	v_mul_i32_i24_e32 v242,0x1010,v242
	v_sub_u32_e32 v240,v240,v242
	v_lshl_or_b32 v240,v240,4,v151
	v_ashrrev_i32_e32 v241,31,v240
	v_lshl_add_u64 v[240:241],v[240:241],3,s[74:75]
	global_load_dwordx2 v[232:233], v[240:241], off
	v_add_u32_e32 v237,35,v139
	v_min_i32_e32 v240,0x403f,v237
	v_mul_hi_i32 v241,v240,s36
	v_lshrrev_b32_e32 v242,31,v241
	v_ashrrev_i32_e32 v241,11,v241
	v_add_u32_e32 v241,v241,v242
	v_mul_i32_i24_e32 v241,0x1010,v241
	v_sub_u32_e32 v240,v240,v241
	v_lshl_or_b32 v240,v240,4,v151
	v_ashrrev_i32_e32 v241,31,v240
	v_lshl_add_u64 v[240:241],v[240:241],3,s[74:75]
	global_load_dwordx2 v[234:235], v[240:241], off
	v_and_b32_e32 v153, 64, v203
	v_add_u32_e32 v158, 1, v139
	ds_read_b128 v[132:135], v141
	ds_read_b128 v[128:131], v146
	v_xor_b32_e32 v152, 16, v203
	v_add_u32_e32 v153, 64, v153
	v_min_i32_e32 v156, 0x403f, v158
	v_cmp_lt_i32_e32 vcc, v152, v153
	v_mul_hi_i32 v153, v156, s36
	v_lshrrev_b32_e32 v157, 31, v153
	v_cndmask_b32_e32 v152, v203, v152, vcc
	v_ashrrev_i32_e32 v153, 11, v153
	v_lshlrev_b32_e32 v152, 2, v152
	v_add_u32_e32 v153, v153, v157
	s_waitcnt lgkmcnt(1)
	v_mul_f32_e32 v112, v112, v132
	v_mul_i32_i24_e32 v132, 0x1010, v153
	ds_bpermute_b32 v153, v152, v112
	v_sub_u32_e32 v132, v156, v132
	v_lshl_or_b32 v156, v132, 4, v151
	v_cmp_gt_u32_e32 vcc, 16, v142
	v_lshl_or_b32 v192, v139, 5, v142
	v_lshl_add_u64 v[154:155], v[192:193], 1, s[56:57]
	v_ashrrev_i32_e32 v157, 31, v156
	v_lshl_add_u64 v[156:157], v[156:157], 3, s[74:75]
	v_mul_f32_e32 v133, v113, v133
	v_lshl_or_b32 v192, v158, 5, v142
	v_mul_f32_e32 v114, v114, v134
	v_mul_f32_e32 v135, v115, v135
	s_waitcnt lgkmcnt(0)
	s_waitcnt vmcnt(19)
	v_mul_f32_e32 v132, v175, v153
	v_cndmask_b32_e64 v132, v132, -v132, vcc
	v_fmac_f32_e32 v132, v112, v174
	v_add_u32_e32 v236,s18,v143
	v_min_i32_e32 v240,0x403f,v236
	v_mul_hi_i32 v242,v240,s36
	v_lshrrev_b32_e32 v243,31,v242
	v_ashrrev_i32_e32 v242,11,v242
	v_add_u32_e32 v242,v242,v243
	v_mul_i32_i24_e32 v242,0x1010,v242
	v_sub_u32_e32 v240,v240,v242
	v_lshl_or_b32 v240,v240,4,v151
	v_ashrrev_i32_e32 v241,31,v240
	v_lshl_add_u64 v[240:241],v[240:241],3,s[74:75]
	global_load_dwordx2 v[174:175], v[240:241], off
	v_cvt_pk_bf16_f32 v112, v132, s0
	global_store_short v[154:155], v112, off
	v_add_u32_e32 v132, 2, v139
	v_min_i32_e32 v112, 0x403f, v132
	v_mul_hi_i32 v153, v112, s36
	v_lshrrev_b32_e32 v156, 31, v153
	v_ashrrev_i32_e32 v153, 11, v153
	v_add_u32_e32 v153, v153, v156
	v_mul_i32_i24_e32 v113, 0x1010, v153
	ds_bpermute_b32 v153, v152, v133
	v_sub_u32_e32 v112, v112, v113
	v_lshl_or_b32 v112, v112, 4, v151
	v_lshl_add_u64 v[154:155], v[192:193], 1, s[56:57]
	v_ashrrev_i32_e32 v113, 31, v112
	v_lshl_add_u64 v[112:113], v[112:113], 3, s[74:75]
	v_lshl_or_b32 v192, v132, 5, v142
	s_waitcnt lgkmcnt(0)
	s_waitcnt vmcnt(20)
	v_mul_f32_e32 v137, v177, v153
	v_cndmask_b32_e64 v137, v137, -v137, vcc
	v_fmac_f32_e32 v137, v133, v176
	v_add_u32_e32 v236,41,v139
	v_min_i32_e32 v240,0x403f,v236
	v_mul_hi_i32 v243,v240,s36
	v_lshrrev_b32_e32 v241,31,v243
	v_ashrrev_i32_e32 v245,11,v243
	v_add_u32_e32 v241,v245,v241
	v_mul_i32_i24_e32 v241,0x1010,v241
	v_sub_u32_e32 v240,v240,v241
	v_lshl_or_b32 v240,v240,4,v151
	v_ashrrev_i32_e32 v241,31,v240
	v_lshl_add_u64 v[240:241],v[240:241],3,s[74:75]
	global_load_dwordx2 v[176:177], v[240:241], off
	v_cvt_pk_bf16_f32 v133, v137, s0
	global_store_short v[154:155], v133, off
	v_add_u32_e32 v153, 3, v139
	v_min_i32_e32 v136, 0x403f, v153
	v_mul_hi_i32 v137, v136, s36
	v_lshrrev_b32_e32 v154, 31, v137
	v_ashrrev_i32_e32 v137, 11, v137
	v_add_u32_e32 v137, v137, v154
	ds_bpermute_b32 v154, v152, v114
	v_mul_i32_i24_e32 v134, 0x1010, v137
	v_sub_u32_e32 v134, v136, v134
	v_lshl_or_b32 v136, v134, 4, v151
	v_lshl_add_u64 v[132:133], v[192:193], 1, s[56:57]
	v_ashrrev_i32_e32 v137, 31, v136
	v_lshl_add_u64 v[136:137], v[136:137], 3, s[74:75]
	v_lshl_or_b32 v192, v153, 5, v142
	v_add_u32_e32 v153, 9, v139
	v_min_i32_e32 v156, 0x403f, v153
	s_waitcnt lgkmcnt(0)
	s_waitcnt vmcnt(21)
	v_mul_f32_e32 v113, v179, v154
	v_cndmask_b32_e64 v113, v113, -v113, vcc
	v_fmac_f32_e32 v113, v114, v178
	v_add_u32_e32 v236,42,v139
	v_min_i32_e32 v240,0x403f,v236
	v_mul_hi_i32 v242,v240,s36
	v_lshrrev_b32_e32 v237,31,v242
	v_ashrrev_i32_e32 v242,11,v242
	v_add_u32_e32 v242,v242,v237
	v_mul_i32_i24_e32 v242,0x1010,v242
	v_sub_u32_e32 v240,v240,v242
	v_lshl_or_b32 v240,v240,4,v151
	v_ashrrev_i32_e32 v241,31,v240
	v_lshl_add_u64 v[240:241],v[240:241],3,s[74:75]
	global_load_dwordx2 v[178:179], v[240:241], off
	v_cvt_pk_bf16_f32 v112, v113, s0
	global_store_short v[132:133], v112, off
	ds_bpermute_b32 v136, v152, v135
	v_min_i32_e32 v114, 0x403f, v149
	v_mul_hi_i32 v132, v114, s36
	v_lshrrev_b32_e32 v133, 31, v132
	v_ashrrev_i32_e32 v132, 11, v132
	v_add_u32_e32 v134, v132, v133
	v_mul_i32_i24_e32 v134, 0x1010, v134
	v_sub_u32_e32 v114, v114, v134
	v_lshl_or_b32 v114, v114, 4, v151
	v_lshl_add_u64 v[132:133], v[192:193], 1, s[56:57]
	v_ashrrev_i32_e32 v115, 31, v114
	v_lshl_add_u64 v[114:115], v[114:115], 3, s[74:75]
	v_mul_hi_i32 v154, v156, s36
	v_lshrrev_b32_e32 v155, 31, v154
	v_ashrrev_i32_e32 v154, 11, v154
	v_add_u32_e32 v157, v154, v155
	v_lshl_or_b32 v192, v149, 5, v142
	v_lshl_add_u64 v[154:155], v[192:193], 1, s[56:57]
	v_lshl_or_b32 v192, v153, 5, v142
	s_waitcnt lgkmcnt(0)
	s_waitcnt vmcnt(22)
	v_mul_f32_e32 v113, v181, v136
	v_cndmask_b32_e64 v113, v113, -v113, vcc
	v_fmac_f32_e32 v113, v135, v180
	v_add_u32_e32 v237,43,v139
	v_min_i32_e32 v240,0x403f,v237
	v_mul_hi_i32 v241,v240,s36
	v_lshrrev_b32_e32 v242,31,v241
	v_ashrrev_i32_e32 v241,11,v241
	v_add_u32_e32 v241,v241,v242
	v_mul_i32_i24_e32 v241,0x1010,v241
	v_sub_u32_e32 v240,v240,v241
	v_lshl_or_b32 v240,v240,4,v151
	v_ashrrev_i32_e32 v241,31,v240
	v_lshl_add_u64 v[240:241],v[240:241],3,s[74:75]
	global_load_dwordx2 v[180:181], v[240:241], off
	v_cvt_pk_bf16_f32 v112, v113, s0
	global_store_short v[132:133], v112, off
	ds_read_b128 v[112:115], v150
	ds_read_b128 v[132:135], v148
	s_waitcnt lgkmcnt(1)
	v_mul_f32_e32 v112, v116, v112
	ds_bpermute_b32 v158, v152, v112
	v_mul_i32_i24_e32 v116, 0x1010, v157
	v_sub_u32_e32 v116, v156, v116
	v_lshl_or_b32 v156, v116, 4, v151
	v_ashrrev_i32_e32 v157, 31, v156
	v_lshl_add_u64 v[156:157], v[156:157], 3, s[74:75]
	v_mul_f32_e32 v114, v118, v114
	ds_bpermute_b32 v118, v152, v114
	s_waitcnt lgkmcnt(1)
	s_waitcnt vmcnt(23)
	v_mul_f32_e32 v116, v183, v158
	v_cndmask_b32_e64 v116, v116, -v116, vcc
	v_fmac_f32_e32 v116, v112, v182
	v_or_b32_e32 v236,48,v138
	v_add_u32_e32 v240,s18,v236
	v_min_i32_e32 v242,0x403f,v240
	v_mul_hi_i32 v244,v242,s36
	v_lshrrev_b32_e32 v245,31,v244
	v_ashrrev_i32_e32 v244,11,v244
	v_add_u32_e32 v244,v244,v245
	v_mul_i32_i24_e32 v244,0x1010,v244
	v_sub_u32_e32 v242,v242,v244
	v_lshl_or_b32 v242,v242,4,v151
	v_ashrrev_i32_e32 v243,31,v242
	v_lshl_add_u64 v[242:243],v[242:243],3,s[74:75]
	global_load_dwordx2 v[182:183], v[242:243], off
	v_cvt_pk_bf16_f32 v112, v116, s0
	global_store_short v[154:155], v112, off
	v_add_u32_e32 v154, 10, v139
	v_min_i32_e32 v116, 0x403f, v154
	v_mul_hi_i32 v112, v116, s36
	v_lshrrev_b32_e32 v155, 31, v112
	v_ashrrev_i32_e32 v112, 11, v112
	v_add_u32_e32 v112, v112, v155
	v_mul_f32_e32 v155, v117, v113
	ds_bpermute_b32 v153, v152, v155
	v_mul_i32_i24_e32 v117, 0x1010, v112
	v_sub_u32_e32 v116, v116, v117
	v_lshl_or_b32 v116, v116, 4, v151
	v_lshl_add_u64 v[112:113], v[192:193], 1, s[56:57]
	v_ashrrev_i32_e32 v117, 31, v116
	v_lshl_add_u64 v[116:117], v[116:117], 3, s[74:75]
	v_lshl_or_b32 v192, v154, 5, v142
	s_waitcnt lgkmcnt(0)
	s_waitcnt vmcnt(24)
	v_mul_f32_e32 v137, v185, v153
	v_cndmask_b32_e64 v137, v137, -v137, vcc
	v_fmac_f32_e32 v137, v155, v184
	v_add_u32_e32 v236,49,v139
	v_min_i32_e32 v240,0x403f,v236
	v_mul_hi_i32 v243,v240,s36
	v_lshrrev_b32_e32 v241,31,v243
	v_ashrrev_i32_e32 v245,11,v243
	v_add_u32_e32 v241,v245,v241
	v_mul_i32_i24_e32 v241,0x1010,v241
	v_sub_u32_e32 v240,v240,v241
	v_lshl_or_b32 v240,v240,4,v151
	v_ashrrev_i32_e32 v241,31,v240
	v_lshl_add_u64 v[240:241],v[240:241],3,s[74:75]
	global_load_dwordx2 v[184:185], v[240:241], off
	v_cvt_pk_bf16_f32 v136, v137, s0
	global_store_short v[112:113], v136, off
	v_add_u32_e32 v153, 11, v139
	v_min_i32_e32 v116, 0x403f, v153
	v_mul_hi_i32 v117, v116, s36
	v_lshrrev_b32_e32 v136, 31, v117
	v_ashrrev_i32_e32 v117, 11, v117
	v_add_u32_e32 v117, v117, v136
	v_mul_i32_i24_e32 v117, 0x1010, v117
	v_sub_u32_e32 v136, v116, v117
	v_lshl_or_b32 v136, v136, 4, v151
	v_lshl_add_u64 v[116:117], v[192:193], 1, s[56:57]
	v_ashrrev_i32_e32 v137, 31, v136
	v_lshl_add_u64 v[136:137], v[136:137], 3, s[74:75]
	v_lshl_or_b32 v192, v153, 5, v142
	s_waitcnt vmcnt(25)
	v_mul_f32_e32 v113, v187, v118
	v_cndmask_b32_e64 v113, v113, -v113, vcc
	v_fmac_f32_e32 v113, v114, v186
	v_add_u32_e32 v236,50,v139
	v_min_i32_e32 v240,0x403f,v236
	v_mul_hi_i32 v242,v240,s36
	v_lshrrev_b32_e32 v243,31,v242
	v_ashrrev_i32_e32 v242,11,v242
	v_add_u32_e32 v242,v242,v243
	v_mul_i32_i24_e32 v242,0x1010,v242
	v_sub_u32_e32 v240,v240,v242
	v_lshl_or_b32 v240,v240,4,v151
	v_ashrrev_i32_e32 v241,31,v240
	v_lshl_add_u64 v[240:241],v[240:241],3,s[74:75]
	global_load_dwordx2 v[186:187], v[240:241], off
	v_cvt_pk_bf16_f32 v112, v113, s0
	global_store_short v[116:117], v112, off
	v_mul_f32_e32 v118, v119, v115
	ds_bpermute_b32 v119, v152, v118
	v_min_i32_e32 v114, 0x403f, v147
	v_mul_hi_i32 v116, v114, s36
	v_lshrrev_b32_e32 v117, 31, v116
	v_ashrrev_i32_e32 v116, 11, v116
	v_add_u32_e32 v116, v116, v117
	v_mul_i32_i24_e32 v116, 0x1010, v116
	v_sub_u32_e32 v114, v114, v116
	v_lshl_or_b32 v114, v114, 4, v151
	v_ashrrev_i32_e32 v115, 31, v114
	v_lshl_add_u64 v[116:117], v[192:193], 1, s[56:57]
	v_lshl_add_u64 v[114:115], v[114:115], 3, s[74:75]
	v_lshl_or_b32 v192, v147, 5, v142
	s_waitcnt lgkmcnt(0)
	s_waitcnt vmcnt(26)
	v_mul_f32_e32 v113, v189, v119
	v_cndmask_b32_e64 v113, v113, -v113, vcc
	v_fmac_f32_e32 v113, v118, v188
	v_add_u32_e32 v237,51,v139
	v_min_i32_e32 v240,0x403f,v237
	v_mul_hi_i32 v241,v240,s36
	v_lshrrev_b32_e32 v242,31,v241
	v_ashrrev_i32_e32 v241,11,v241
	v_add_u32_e32 v241,v241,v242
	v_mul_i32_i24_e32 v241,0x1010,v241
	v_sub_u32_e32 v240,v240,v241
	v_lshl_or_b32 v240,v240,4,v151
	v_ashrrev_i32_e32 v241,31,v240
	v_lshl_add_u64 v[240:241],v[240:241],3,s[74:75]
	global_load_dwordx2 v[188:189], v[240:241], off
	v_cvt_pk_bf16_f32 v112, v113, s0
	global_store_short v[116:117], v112, off
	v_mul_f32_e32 v119, v120, v132
	v_add_u32_e32 v118, 17, v139
	ds_bpermute_b32 v120, v152, v119
	v_min_i32_e32 v114, 0x403f, v118
	v_mul_hi_i32 v115, v114, s36
	v_lshrrev_b32_e32 v116, 31, v115
	v_ashrrev_i32_e32 v115, 11, v115
	v_add_u32_e32 v115, v115, v116
	v_mul_i32_i24_e32 v115, 0x1010, v115
	v_sub_u32_e32 v114, v114, v115
	v_lshl_or_b32 v114, v114, 4, v151
	v_ashrrev_i32_e32 v115, 31, v114
	v_lshl_add_u64 v[116:117], v[192:193], 1, s[56:57]
	v_lshl_add_u64 v[114:115], v[114:115], 3, s[74:75]
	v_lshl_or_b32 v192, v118, 5, v142
	v_add_u32_e32 v118, 19, v139
	s_waitcnt lgkmcnt(0)
	s_waitcnt vmcnt(27)
	v_mul_f32_e32 v113, v191, v120
	v_cndmask_b32_e64 v113, v113, -v113, vcc
	v_fmac_f32_e32 v113, v119, v190
	v_or_b32_e32 v236,56,v138
	v_add_u32_e32 v240,s18,v236
	v_min_i32_e32 v242,0x403f,v240
	v_mul_hi_i32 v244,v242,s36
	v_lshrrev_b32_e32 v245,31,v244
	v_ashrrev_i32_e32 v244,11,v244
	v_add_u32_e32 v244,v244,v245
	v_mul_i32_i24_e32 v244,0x1010,v244
	v_sub_u32_e32 v242,v242,v244
	v_lshl_or_b32 v242,v242,4,v151
	v_ashrrev_i32_e32 v243,31,v242
	v_lshl_add_u64 v[242:243],v[242:243],3,s[74:75]
	global_load_dwordx2 v[190:191], v[242:243], off
	v_cvt_pk_bf16_f32 v112, v113, s0
	global_store_short v[116:117], v112, off
	v_mul_f32_e32 v120, v121, v133
	v_add_u32_e32 v119, 18, v139
	ds_bpermute_b32 v121, v152, v120
	v_min_i32_e32 v114, 0x403f, v119
	v_mul_hi_i32 v115, v114, s36
	v_lshrrev_b32_e32 v116, 31, v115
	v_ashrrev_i32_e32 v115, 11, v115
	v_add_u32_e32 v115, v115, v116
	v_mul_i32_i24_e32 v115, 0x1010, v115
	v_sub_u32_e32 v114, v114, v115
	v_lshl_or_b32 v114, v114, 4, v151
	v_ashrrev_i32_e32 v115, 31, v114
	v_lshl_add_u64 v[116:117], v[192:193], 1, s[56:57]
	v_lshl_add_u64 v[114:115], v[114:115], 3, s[74:75]
	v_lshl_or_b32 v192, v119, 5, v142
	v_mul_f32_e32 v119, v123, v135
	s_waitcnt lgkmcnt(0)
	s_waitcnt vmcnt(28)
	v_mul_f32_e32 v113, v195, v121
	v_cndmask_b32_e64 v113, v113, -v113, vcc
	v_fmac_f32_e32 v113, v120, v194
	v_add_u32_e32 v236,57,v139
	v_min_i32_e32 v240,0x403f,v236
	v_mul_hi_i32 v243,v240,s36
	v_lshrrev_b32_e32 v241,31,v243
	v_ashrrev_i32_e32 v245,11,v243
	v_add_u32_e32 v241,v245,v241
	v_mul_i32_i24_e32 v241,0x1010,v241
	v_sub_u32_e32 v240,v240,v241
	v_lshl_or_b32 v240,v240,4,v151
	v_ashrrev_i32_e32 v241,31,v240
	v_lshl_add_u64 v[240:241],v[240:241],3,s[74:75]
	global_load_dwordx2 v[194:195], v[240:241], off
	v_cvt_pk_bf16_f32 v112, v113, s0
	global_store_short v[116:117], v112, off
	v_mul_f32_e32 v120, v122, v134
	ds_bpermute_b32 v121, v152, v120
	v_min_i32_e32 v114, 0x403f, v118
	v_mul_hi_i32 v115, v114, s36
	v_lshrrev_b32_e32 v116, 31, v115
	v_ashrrev_i32_e32 v115, 11, v115
	v_add_u32_e32 v115, v115, v116
	v_mul_i32_i24_e32 v115, 0x1010, v115
	v_sub_u32_e32 v114, v114, v115
	v_lshl_or_b32 v114, v114, 4, v151
	v_ashrrev_i32_e32 v115, 31, v114
	v_lshl_add_u64 v[116:117], v[192:193], 1, s[56:57]
	v_lshl_add_u64 v[114:115], v[114:115], 3, s[74:75]
	v_lshl_or_b32 v192, v118, 5, v142
	v_add_u32_e32 v118, 25, v139
	v_add_u32_e32 v122, 33, v139
	s_waitcnt lgkmcnt(0)
	s_waitcnt vmcnt(29)
	v_mul_f32_e32 v113, v197, v121
	v_cndmask_b32_e64 v113, v113, -v113, vcc
	v_fmac_f32_e32 v113, v120, v196
	v_add_u32_e32 v236,58,v139
	v_min_i32_e32 v240,0x403f,v236
	v_mul_hi_i32 v242,v240,s36
	v_lshrrev_b32_e32 v243,31,v242
	v_ashrrev_i32_e32 v242,11,v242
	v_add_u32_e32 v242,v242,v243
	v_mul_i32_i24_e32 v242,0x1010,v242
	v_sub_u32_e32 v240,v240,v242
	v_lshl_or_b32 v240,v240,4,v151
	v_ashrrev_i32_e32 v241,31,v240
	v_lshl_add_u64 v[240:241],v[240:241],3,s[74:75]
	global_load_dwordx2 v[196:197], v[240:241], off
	v_cvt_pk_bf16_f32 v112, v113, s0
	global_store_short v[116:117], v112, off
	ds_bpermute_b32 v120, v152, v119
	v_min_i32_e32 v114, 0x403f, v145
	v_mul_hi_i32 v115, v114, s36
	v_lshrrev_b32_e32 v116, 31, v115
	v_ashrrev_i32_e32 v115, 11, v115
	v_add_u32_e32 v115, v115, v116
	v_mul_i32_i24_e32 v115, 0x1010, v115
	v_sub_u32_e32 v114, v114, v115
	v_lshl_or_b32 v114, v114, 4, v151
	v_ashrrev_i32_e32 v115, 31, v114
	v_lshl_add_u64 v[116:117], v[192:193], 1, s[56:57]
	v_lshl_add_u64 v[114:115], v[114:115], 3, s[74:75]
	v_lshl_or_b32 v192, v145, 5, v142
	s_waitcnt lgkmcnt(0)
	s_waitcnt vmcnt(30)
	v_mul_f32_e32 v113, v199, v120
	v_cndmask_b32_e64 v113, v113, -v113, vcc
	v_fmac_f32_e32 v113, v119, v198
	v_add_u32_e32 v237,59,v139
	v_min_i32_e32 v240,0x403f,v237
	v_mul_hi_i32 v241,v240,s36
	v_lshrrev_b32_e32 v242,31,v241
	v_ashrrev_i32_e32 v241,11,v241
	v_add_u32_e32 v241,v241,v242
	v_mul_i32_i24_e32 v241,0x1010,v241
	v_sub_u32_e32 v240,v240,v241
	v_lshl_or_b32 v240,v240,4,v151
	v_ashrrev_i32_e32 v241,31,v240
	v_lshl_add_u64 v[240:241],v[240:241],3,s[74:75]
	global_load_dwordx2 v[198:199], v[240:241], off
	v_cvt_pk_bf16_f32 v112, v113, s0
	global_store_short v[116:117], v112, off
	v_mul_f32_e32 v119, v124, v128
	ds_bpermute_b32 v120, v152, v119
	v_min_i32_e32 v114, 0x403f, v118
	v_mul_hi_i32 v115, v114, s36
	v_lshrrev_b32_e32 v116, 31, v115
	v_ashrrev_i32_e32 v115, 11, v115
	v_add_u32_e32 v115, v115, v116
	v_mul_i32_i24_e32 v115, 0x1010, v115
	v_sub_u32_e32 v114, v114, v115
	v_lshl_or_b32 v114, v114, 4, v151
	v_ashrrev_i32_e32 v115, 31, v114
	v_lshl_add_u64 v[116:117], v[192:193], 1, s[56:57]
	v_lshl_add_u64 v[114:115], v[114:115], 3, s[74:75]
	v_lshl_or_b32 v192, v118, 5, v142
	v_add_u32_e32 v118, 27, v139
	s_waitcnt lgkmcnt(0)
	s_waitcnt vmcnt(31)
	v_mul_f32_e32 v113, v205, v120
	v_cndmask_b32_e64 v113, v113, -v113, vcc
	v_fmac_f32_e32 v113, v119, v204
	v_or_b32_e32 v236,64,v138
	v_add_u32_e32 v240,s18,v236
	v_min_i32_e32 v242,0x403f,v240
	v_mul_hi_i32 v244,v242,s36
	v_lshrrev_b32_e32 v245,31,v244
	v_ashrrev_i32_e32 v244,11,v244
	v_add_u32_e32 v244,v244,v245
	v_mul_i32_i24_e32 v244,0x1010,v244
	v_sub_u32_e32 v242,v242,v244
	v_lshl_or_b32 v242,v242,4,v151
	v_ashrrev_i32_e32 v243,31,v242
	v_lshl_add_u64 v[242:243],v[242:243],3,s[74:75]
	global_load_dwordx2 v[204:205], v[242:243], off
	v_cvt_pk_bf16_f32 v112, v113, s0
	global_store_short v[116:117], v112, off
	v_mul_f32_e32 v120, v125, v129
	v_add_u32_e32 v119, 26, v139
	ds_bpermute_b32 v121, v152, v120
	v_min_i32_e32 v114, 0x403f, v119
	v_mul_hi_i32 v115, v114, s36
	v_lshrrev_b32_e32 v116, 31, v115
	v_ashrrev_i32_e32 v115, 11, v115
	v_add_u32_e32 v115, v115, v116
	v_mul_i32_i24_e32 v115, 0x1010, v115
	v_sub_u32_e32 v114, v114, v115
	v_lshl_or_b32 v114, v114, 4, v151
	v_ashrrev_i32_e32 v115, 31, v114
	v_lshl_add_u64 v[116:117], v[192:193], 1, s[56:57]
	v_lshl_add_u64 v[114:115], v[114:115], 3, s[74:75]
	v_lshl_or_b32 v192, v119, 5, v142
	v_mul_f32_e32 v119, v127, v131
	s_waitcnt lgkmcnt(0)
	s_waitcnt vmcnt(32)
	v_mul_f32_e32 v113, v207, v121
	v_cndmask_b32_e64 v113, v113, -v113, vcc
	v_fmac_f32_e32 v113, v120, v206
	v_add_u32_e32 v236,0x41,v139
	v_min_i32_e32 v240,0x403f,v236
	v_mul_hi_i32 v243,v240,s36
	v_lshrrev_b32_e32 v241,31,v243
	v_ashrrev_i32_e32 v245,11,v243
	v_add_u32_e32 v241,v245,v241
	v_mul_i32_i24_e32 v241,0x1010,v241
	v_sub_u32_e32 v240,v240,v241
	v_lshl_or_b32 v240,v240,4,v151
	v_ashrrev_i32_e32 v241,31,v240
	v_lshl_add_u64 v[240:241],v[240:241],3,s[74:75]
	global_load_dwordx2 v[206:207], v[240:241], off
	v_cvt_pk_bf16_f32 v112, v113, s0
	global_store_short v[116:117], v112, off
	v_mul_f32_e32 v120, v126, v130
	ds_bpermute_b32 v121, v152, v120
	v_min_i32_e32 v114, 0x403f, v118
	v_mul_hi_i32 v115, v114, s36
	v_lshrrev_b32_e32 v116, 31, v115
	v_ashrrev_i32_e32 v115, 11, v115
	v_add_u32_e32 v115, v115, v116
	v_mul_i32_i24_e32 v115, 0x1010, v115
	v_sub_u32_e32 v114, v114, v115
	v_lshl_or_b32 v114, v114, 4, v151
	v_ashrrev_i32_e32 v115, 31, v114
	v_lshl_add_u64 v[116:117], v[192:193], 1, s[56:57]
	v_lshl_add_u64 v[114:115], v[114:115], 3, s[74:75]
	v_lshl_or_b32 v192, v118, 5, v142
	v_min_i32_e32 v118, 0x403f, v122
	s_waitcnt lgkmcnt(0)
	s_waitcnt vmcnt(33)
	v_mul_f32_e32 v113, v225, v121
	v_cndmask_b32_e64 v113, v113, -v113, vcc
	v_fmac_f32_e32 v113, v120, v224
	v_add_u32_e32 v236,0x42,v139
	v_min_i32_e32 v240,0x403f,v236
	v_mul_hi_i32 v242,v240,s36
	v_lshrrev_b32_e32 v237,31,v242
	v_ashrrev_i32_e32 v242,11,v242
	v_add_u32_e32 v242,v242,v237
	v_mul_i32_i24_e32 v242,0x1010,v242
	v_sub_u32_e32 v240,v240,v242
	v_lshl_or_b32 v240,v240,4,v151
	v_ashrrev_i32_e32 v241,31,v240
	v_lshl_add_u64 v[240:241],v[240:241],3,s[74:75]
	global_load_dwordx2 v[224:225], v[240:241], off
	v_cvt_pk_bf16_f32 v112, v113, s0
	global_store_short v[116:117], v112, off
	ds_bpermute_b32 v121, v152, v119
	v_add_u32_e32 v120, s18, v144
	v_min_i32_e32 v114, 0x403f, v120
	v_mul_hi_i32 v115, v114, s36
	v_lshrrev_b32_e32 v116, 31, v115
	v_ashrrev_i32_e32 v115, 11, v115
	v_add_u32_e32 v115, v115, v116
	v_mul_i32_i24_e32 v115, 0x1010, v115
	v_sub_u32_e32 v114, v114, v115
	v_lshl_or_b32 v114, v114, 4, v151
	v_lshl_add_u64 v[116:117], v[192:193], 1, s[56:57]
	v_ashrrev_i32_e32 v115, 31, v114
	v_lshl_add_u64 v[114:115], v[114:115], 3, s[74:75]
	v_lshl_or_b32 v192, v120, 5, v142
	s_waitcnt lgkmcnt(0)
	s_waitcnt vmcnt(34)
	v_mul_f32_e32 v113, v227, v121
	v_cndmask_b32_e64 v113, v113, -v113, vcc
	v_fmac_f32_e32 v113, v119, v226
	v_add_u32_e32 v237,0x43,v139
	v_min_i32_e32 v240,0x403f,v237
	v_mul_hi_i32 v241,v240,s36
	v_lshrrev_b32_e32 v242,31,v241
	v_ashrrev_i32_e32 v241,11,v241
	v_add_u32_e32 v241,v241,v242
	v_mul_i32_i24_e32 v241,0x1010,v241
	v_sub_u32_e32 v240,v240,v241
	v_lshl_or_b32 v240,v240,4,v151
	v_ashrrev_i32_e32 v241,31,v240
	v_lshl_add_u64 v[240:241],v[240:241],3,s[74:75]
	global_load_dwordx2 v[226:227], v[240:241], off
	v_cvt_pk_bf16_f32 v112, v113, s0
	global_store_short v[116:117], v112, off
	v_lshl_add_u32 v112, v144, 2, v200
	v_mul_hi_i32 v113, v118, s36
	v_lshrrev_b32_e32 v119, 31, v113
	v_ashrrev_i32_e32 v121, 11, v113
	ds_read_b128 v[112:115], v112
	v_add_u32_e32 v119, v121, v119
	v_mul_i32_i24_e32 v119, 0x1010, v119
	v_sub_u32_e32 v118, v118, v119
	v_lshl_or_b32 v118, v118, 4, v151
	s_waitcnt lgkmcnt(0)
	v_mul_f32_e32 v96, v96, v112
	ds_bpermute_b32 v112, v152, v96
	v_ashrrev_i32_e32 v119, 31, v118
	v_lshl_add_u64 v[120:121], v[192:193], 1, s[56:57]
	v_lshl_add_u64 v[118:119], v[118:119], 3, s[74:75]
	v_lshl_or_b32 v192, v122, 5, v142
	v_mul_f32_e32 v98, v98, v114
	ds_bpermute_b32 v114, v152, v98
	s_waitcnt lgkmcnt(1)
	s_waitcnt vmcnt(35)
	v_mul_f32_e32 v112, v229, v112
	v_cndmask_b32_e64 v112, v112, -v112, vcc
	v_fmac_f32_e32 v112, v96, v228
	v_or_b32_e32 v236,0x48,v138
	v_add_u32_e32 v240,s18,v236
	v_min_i32_e32 v242,0x403f,v240
	v_mul_hi_i32 v244,v242,s36
	v_lshrrev_b32_e32 v245,31,v244
	v_ashrrev_i32_e32 v244,11,v244
	v_add_u32_e32 v244,v244,v245
	v_mul_i32_i24_e32 v244,0x1010,v244
	v_sub_u32_e32 v242,v242,v244
	v_lshl_or_b32 v242,v242,4,v151
	v_ashrrev_i32_e32 v243,31,v242
	v_lshl_add_u64 v[242:243],v[242:243],3,s[74:75]
	global_load_dwordx2 v[228:229], v[242:243], off
	v_cvt_pk_bf16_f32 v96, v112, s0
	global_store_short v[120:121], v96, off
	v_add_u32_e32 v118, 34, v139
	v_min_i32_e32 v96, 0x403f, v118
	v_mul_hi_i32 v112, v96, s36
	v_lshrrev_b32_e32 v119, 31, v112
	v_ashrrev_i32_e32 v112, 11, v112
	v_add_u32_e32 v112, v112, v119
	v_mul_f32_e32 v119, v97, v113
	ds_bpermute_b32 v120, v152, v119
	v_mul_i32_i24_e32 v112, 0x1010, v112
	v_sub_u32_e32 v96, v96, v112
	v_lshl_or_b32 v96, v96, 4, v151
	v_ashrrev_i32_e32 v97, 31, v96
	v_lshl_add_u64 v[112:113], v[192:193], 1, s[56:57]
	v_lshl_add_u64 v[96:97], v[96:97], 3, s[74:75]
	v_lshl_or_b32 v192, v118, 5, v142
	v_add_u32_e32 v118, 41, v139
	s_waitcnt lgkmcnt(0)
	s_waitcnt vmcnt(36)
	v_mul_f32_e32 v117, v231, v120
	v_cndmask_b32_e64 v117, v117, -v117, vcc
	v_fmac_f32_e32 v117, v119, v230
	v_add_u32_e32 v236,0x49,v139
	v_min_i32_e32 v240,0x403f,v236
	v_mul_hi_i32 v243,v240,s36
	v_lshrrev_b32_e32 v241,31,v243
	v_ashrrev_i32_e32 v245,11,v243
	v_add_u32_e32 v241,v245,v241
	v_mul_i32_i24_e32 v241,0x1010,v241
	v_sub_u32_e32 v240,v240,v241
	v_lshl_or_b32 v240,v240,4,v151
	v_ashrrev_i32_e32 v241,31,v240
	v_lshl_add_u64 v[240:241],v[240:241],3,s[74:75]
	global_load_dwordx2 v[230:231], v[240:241], off
	v_cvt_pk_bf16_f32 v116, v117, s0
	global_store_short v[112:113], v116, off
	v_add_u32_e32 v119, 35, v139
	v_min_i32_e32 v112, 0x403f, v119
	v_mul_hi_i32 v113, v112, s36
	v_lshrrev_b32_e32 v116, 31, v113
	v_ashrrev_i32_e32 v113, 11, v113
	v_add_u32_e32 v113, v113, v116
	v_mul_i32_i24_e32 v113, 0x1010, v113
	v_sub_u32_e32 v112, v112, v113
	v_lshl_or_b32 v112, v112, 4, v151
	v_ashrrev_i32_e32 v113, 31, v112
	v_lshl_add_u64 v[116:117], v[192:193], 1, s[56:57]
	v_lshl_add_u64 v[112:113], v[112:113], 3, s[74:75]
	v_lshl_or_b32 v192, v119, 5, v142
	s_waitcnt vmcnt(37)
	v_mul_f32_e32 v97, v233, v114
	v_cndmask_b32_e64 v97, v97, -v97, vcc
	v_fmac_f32_e32 v97, v98, v232
	v_add_u32_e32 v236,0x4a,v139
	v_min_i32_e32 v240,0x403f,v236
	v_mul_hi_i32 v242,v240,s36
	v_lshrrev_b32_e32 v237,31,v242
	v_ashrrev_i32_e32 v242,11,v242
	v_add_u32_e32 v242,v242,v237
	v_mul_i32_i24_e32 v242,0x1010,v242
	v_sub_u32_e32 v240,v240,v242
	v_lshl_or_b32 v240,v240,4,v151
	v_ashrrev_i32_e32 v241,31,v240
	v_lshl_add_u64 v[240:241],v[240:241],3,s[74:75]
	global_load_dwordx2 v[232:233], v[240:241], off
	v_cvt_pk_bf16_f32 v96, v97, s0
	global_store_short v[116:117], v96, off
	v_mul_f32_e32 v114, v99, v115
	v_add_u32_e32 v116, s18, v143
	ds_bpermute_b32 v115, v152, v114
	v_min_i32_e32 v98, 0x403f, v116
	v_mul_hi_i32 v112, v98, s36
	v_lshrrev_b32_e32 v113, 31, v112
	v_ashrrev_i32_e32 v112, 11, v112
	v_add_u32_e32 v112, v112, v113
	v_mul_i32_i24_e32 v112, 0x1010, v112
	v_sub_u32_e32 v98, v98, v112
	v_lshl_or_b32 v98, v98, 4, v151
	v_ashrrev_i32_e32 v99, 31, v98
	v_lshl_add_u64 v[112:113], v[192:193], 1, s[56:57]
	v_lshl_add_u64 v[98:99], v[98:99], 3, s[74:75]
	v_lshl_or_b32 v192, v116, 5, v142
	s_waitcnt lgkmcnt(0)
	s_waitcnt vmcnt(38)
	v_mul_f32_e32 v97, v235, v115
	v_cndmask_b32_e64 v97, v97, -v97, vcc
	v_fmac_f32_e32 v97, v114, v234
	v_add_u32_e32 v237,0x4b,v139
	v_min_i32_e32 v240,0x403f,v237
	v_mul_hi_i32 v241,v240,s36
	v_lshrrev_b32_e32 v242,31,v241
	v_ashrrev_i32_e32 v241,11,v241
	v_add_u32_e32 v241,v241,v242
	v_mul_i32_i24_e32 v241,0x1010,v241
	v_sub_u32_e32 v240,v240,v241
	v_lshl_or_b32 v240,v240,4,v151
	v_ashrrev_i32_e32 v241,31,v240
	v_lshl_add_u64 v[240:241],v[240:241],3,s[74:75]
	global_load_dwordx2 v[234:235], v[240:241], off
	v_cvt_pk_bf16_f32 v96, v97, s0
	global_store_short v[112:113], v96, off
	v_min_i32_e32 v114, 0x403f, v118
	v_lshl_add_u32 v96, v143, 2, v200
	v_mul_hi_i32 v97, v114, s36
	v_lshrrev_b32_e32 v115, 31, v97
	v_ashrrev_i32_e32 v117, 11, v97
	ds_read_b128 v[96:99], v96
	v_add_u32_e32 v115, v117, v115
	v_mul_i32_i24_e32 v115, 0x1010, v115
	v_sub_u32_e32 v114, v114, v115
	v_lshl_or_b32 v114, v114, 4, v151
	s_waitcnt lgkmcnt(0)
	v_mul_f32_e32 v96, v100, v96
	ds_bpermute_b32 v100, v152, v96
	v_ashrrev_i32_e32 v115, 31, v114
	v_lshl_add_u64 v[116:117], v[192:193], 1, s[56:57]
	v_lshl_add_u64 v[114:115], v[114:115], 3, s[74:75]
	v_lshl_or_b32 v192, v118, 5, v142
	v_mul_f32_e32 v98, v102, v98
	ds_bpermute_b32 v102, v152, v98
	v_mul_f32_e32 v103, v103, v99
	s_waitcnt lgkmcnt(1)
	s_waitcnt vmcnt(39)
	v_mul_f32_e32 v100, v175, v100
	v_cndmask_b32_e64 v100, v100, -v100, vcc
	v_fmac_f32_e32 v100, v96, v174
	v_or_b32_e32 v236,0x50,v138
	v_add_u32_e32 v240,s18,v236
	v_min_i32_e32 v242,0x403f,v240
	v_mul_hi_i32 v244,v242,s36
	v_lshrrev_b32_e32 v245,31,v244
	v_ashrrev_i32_e32 v244,11,v244
	v_add_u32_e32 v244,v244,v245
	v_mul_i32_i24_e32 v244,0x1010,v244
	v_sub_u32_e32 v242,v242,v244
	v_lshl_or_b32 v242,v242,4,v151
	v_ashrrev_i32_e32 v243,31,v242
	v_lshl_add_u64 v[242:243],v[242:243],3,s[74:75]
	global_load_dwordx2 v[174:175], v[242:243], off
	v_cvt_pk_bf16_f32 v96, v100, s0
	global_store_short v[116:117], v96, off
	v_add_u32_e32 v114, 42, v139
	v_min_i32_e32 v96, 0x403f, v114
	v_mul_hi_i32 v100, v96, s36
	v_lshrrev_b32_e32 v115, 31, v100
	v_ashrrev_i32_e32 v100, 11, v100
	v_add_u32_e32 v100, v100, v115
	v_mul_f32_e32 v115, v101, v97
	ds_bpermute_b32 v116, v152, v115
	v_mul_i32_i24_e32 v100, 0x1010, v100
	v_sub_u32_e32 v96, v96, v100
	v_lshl_or_b32 v96, v96, 4, v151
	v_ashrrev_i32_e32 v97, 31, v96
	v_lshl_add_u64 v[100:101], v[192:193], 1, s[56:57]
	v_lshl_add_u64 v[96:97], v[96:97], 3, s[74:75]
	v_lshl_or_b32 v192, v114, 5, v142
	v_add_u32_e32 v114, 49, v139
	s_waitcnt lgkmcnt(0)
	s_waitcnt vmcnt(39)
	v_mul_f32_e32 v113, v177, v116
	v_cndmask_b32_e64 v113, v113, -v113, vcc
	v_fmac_f32_e32 v113, v115, v176
	v_add_u32_e32 v236,0x51,v139
	v_min_i32_e32 v240,0x403f,v236
	v_mul_hi_i32 v243,v240,s36
	v_lshrrev_b32_e32 v241,31,v243
	v_ashrrev_i32_e32 v245,11,v243
	v_add_u32_e32 v241,v245,v241
	v_mul_i32_i24_e32 v241,0x1010,v241
	v_sub_u32_e32 v240,v240,v241
	v_lshl_or_b32 v240,v240,4,v151
	v_ashrrev_i32_e32 v241,31,v240
	v_lshl_add_u64 v[240:241],v[240:241],3,s[74:75]
	global_load_dwordx2 v[176:177], v[240:241], off
	v_cvt_pk_bf16_f32 v112, v113, s0
	global_store_short v[100:101], v112, off
	v_add_u32_e32 v115, 43, v139
	v_min_i32_e32 v100, 0x403f, v115
	v_mul_hi_i32 v101, v100, s36
	v_lshrrev_b32_e32 v112, 31, v101
	v_ashrrev_i32_e32 v101, 11, v101
	v_add_u32_e32 v101, v101, v112
	v_mul_i32_i24_e32 v101, 0x1010, v101
	v_sub_u32_e32 v100, v100, v101
	v_lshl_or_b32 v100, v100, 4, v151
	v_ashrrev_i32_e32 v101, 31, v100
	v_lshl_add_u64 v[112:113], v[192:193], 1, s[56:57]
	v_lshl_add_u64 v[100:101], v[100:101], 3, s[74:75]
	v_lshl_or_b32 v192, v115, 5, v142
	s_waitcnt vmcnt(39)
	v_mul_f32_e32 v97, v179, v102
	v_cndmask_b32_e64 v97, v97, -v97, vcc
	v_fmac_f32_e32 v97, v98, v178
	v_add_u32_e32 v236,0x52,v139
	v_min_i32_e32 v240,0x403f,v236
	v_mul_hi_i32 v242,v240,s36
	v_lshrrev_b32_e32 v243,31,v242
	v_ashrrev_i32_e32 v242,11,v242
	v_add_u32_e32 v242,v242,v243
	v_mul_i32_i24_e32 v242,0x1010,v242
	v_sub_u32_e32 v240,v240,v242
	v_lshl_or_b32 v240,v240,4,v151
	v_ashrrev_i32_e32 v241,31,v240
	v_lshl_add_u64 v[240:241],v[240:241],3,s[74:75]
	global_load_dwordx2 v[178:179], v[240:241], off
	v_cvt_pk_bf16_f32 v96, v97, s0
	global_store_short v[112:113], v96, off
	v_or_b32_e32 v102, 48, v138
	v_add_u32_e32 v112, s18, v102
	ds_bpermute_b32 v113, v152, v103
	v_min_i32_e32 v98, 0x403f, v112
	v_mul_hi_i32 v100, v98, s36
	v_lshrrev_b32_e32 v101, 31, v100
	v_ashrrev_i32_e32 v100, 11, v100
	v_add_u32_e32 v100, v100, v101
	v_mul_i32_i24_e32 v100, 0x1010, v100
	v_sub_u32_e32 v98, v98, v100
	v_lshl_or_b32 v98, v98, 4, v151
	v_ashrrev_i32_e32 v99, 31, v98
	v_lshl_add_u64 v[100:101], v[192:193], 1, s[56:57]
	v_lshl_add_u64 v[98:99], v[98:99], 3, s[74:75]
	v_lshl_or_b32 v192, v112, 5, v142
	s_waitcnt lgkmcnt(0)
	s_waitcnt vmcnt(39)
	v_mul_f32_e32 v97, v181, v113
	v_cndmask_b32_e64 v97, v97, -v97, vcc
	v_fmac_f32_e32 v97, v103, v180
	v_add_u32_e32 v237,0x53,v139
	v_min_i32_e32 v240,0x403f,v237
	v_mul_hi_i32 v241,v240,s36
	v_lshrrev_b32_e32 v242,31,v241
	v_ashrrev_i32_e32 v241,11,v241
	v_add_u32_e32 v241,v241,v242
	v_mul_i32_i24_e32 v241,0x1010,v241
	v_sub_u32_e32 v240,v240,v241
	v_lshl_or_b32 v240,v240,4,v151
	v_ashrrev_i32_e32 v241,31,v240
	v_lshl_add_u64 v[240:241],v[240:241],3,s[74:75]
	global_load_dwordx2 v[180:181], v[240:241], off
	v_cvt_pk_bf16_f32 v96, v97, s0
	global_store_short v[100:101], v96, off
	v_lshl_add_u32 v96, v102, 2, v200
	v_min_i32_e32 v102, 0x403f, v114
	v_mul_hi_i32 v97, v102, s36
	v_lshrrev_b32_e32 v103, 31, v97
	v_ashrrev_i32_e32 v113, 11, v97
	ds_read_b128 v[96:99], v96
	v_add_u32_e32 v103, v113, v103
	v_mul_i32_i24_e32 v103, 0x1010, v103
	v_sub_u32_e32 v102, v102, v103
	v_lshl_or_b32 v102, v102, 4, v151
	s_waitcnt lgkmcnt(0)
	v_mul_f32_e32 v96, v104, v96
	ds_bpermute_b32 v104, v152, v96
	v_ashrrev_i32_e32 v103, 31, v102
	v_lshl_add_u64 v[112:113], v[192:193], 1, s[56:57]
	v_lshl_add_u64 v[102:103], v[102:103], 3, s[74:75]
	v_mul_f32_e32 v105, v105, v97
	v_lshl_or_b32 v192, v114, 5, v142
	v_mul_f32_e32 v98, v106, v98
	ds_bpermute_b32 v106, v152, v98
	s_waitcnt lgkmcnt(1)
	s_waitcnt vmcnt(39)
	v_mul_f32_e32 v101, v183, v104
	v_cndmask_b32_e64 v101, v101, -v101, vcc
	v_fmac_f32_e32 v101, v96, v182
	v_or_b32_e32 v236,0x58,v138
	v_add_u32_e32 v240,s18,v236
	v_min_i32_e32 v242,0x403f,v240
	v_mul_hi_i32 v244,v242,s36
	v_lshrrev_b32_e32 v245,31,v244
	v_ashrrev_i32_e32 v244,11,v244
	v_add_u32_e32 v244,v244,v245
	v_mul_i32_i24_e32 v244,0x1010,v244
	v_sub_u32_e32 v242,v242,v244
	v_lshl_or_b32 v242,v242,4,v151
	v_ashrrev_i32_e32 v243,31,v242
	v_lshl_add_u64 v[242:243],v[242:243],3,s[74:75]
	global_load_dwordx2 v[182:183], v[242:243], off
	v_cvt_pk_bf16_f32 v96, v101, s0
	global_store_short v[112:113], v96, off
	v_add_u32_e32 v104, 50, v139
	ds_bpermute_b32 v112, v152, v105
	v_min_i32_e32 v96, 0x403f, v104
	v_mul_hi_i32 v102, v96, s36
	v_lshrrev_b32_e32 v103, 31, v102
	v_ashrrev_i32_e32 v102, 11, v102
	v_add_u32_e32 v102, v102, v103
	v_mul_i32_i24_e32 v102, 0x1010, v102
	v_sub_u32_e32 v96, v96, v102
	v_lshl_or_b32 v96, v96, 4, v151
	v_ashrrev_i32_e32 v97, 31, v96
	v_lshl_add_u64 v[102:103], v[192:193], 1, s[56:57]
	v_lshl_add_u64 v[96:97], v[96:97], 3, s[74:75]
	v_lshl_or_b32 v192, v104, 5, v142
	s_waitcnt lgkmcnt(0)
	s_waitcnt vmcnt(39)
	v_mul_f32_e32 v101, v185, v112
	v_cndmask_b32_e64 v101, v101, -v101, vcc
	v_fmac_f32_e32 v101, v105, v184
	v_add_u32_e32 v236,0x59,v139
	v_min_i32_e32 v240,0x403f,v236
	v_mul_hi_i32 v243,v240,s36
	v_lshrrev_b32_e32 v241,31,v243
	v_ashrrev_i32_e32 v245,11,v243
	v_add_u32_e32 v241,v245,v241
	v_mul_i32_i24_e32 v241,0x1010,v241
	v_sub_u32_e32 v240,v240,v241
	v_lshl_or_b32 v240,v240,4,v151
	v_ashrrev_i32_e32 v241,31,v240
	v_lshl_add_u64 v[240:241],v[240:241],3,s[74:75]
	global_load_dwordx2 v[184:185], v[240:241], off
	v_cvt_pk_bf16_f32 v100, v101, s0
	global_store_short v[102:103], v100, off
	v_add_u32_e32 v105, 51, v139
	v_min_i32_e32 v100, 0x403f, v105
	v_mul_hi_i32 v101, v100, s36
	v_lshrrev_b32_e32 v102, 31, v101
	v_ashrrev_i32_e32 v101, 11, v101
	v_add_u32_e32 v101, v101, v102
	v_mul_i32_i24_e32 v101, 0x1010, v101
	v_sub_u32_e32 v100, v100, v101
	v_lshl_or_b32 v100, v100, 4, v151
	v_ashrrev_i32_e32 v101, 31, v100
	v_lshl_add_u64 v[102:103], v[192:193], 1, s[56:57]
	v_lshl_add_u64 v[100:101], v[100:101], 3, s[74:75]
	v_lshl_or_b32 v192, v105, 5, v142
	s_waitcnt vmcnt(39)
	v_mul_f32_e32 v97, v187, v106
	v_cndmask_b32_e64 v97, v97, -v97, vcc
	v_fmac_f32_e32 v97, v98, v186
	v_add_u32_e32 v236,0x5a,v139
	v_min_i32_e32 v240,0x403f,v236
	v_mul_hi_i32 v242,v240,s36
	v_lshrrev_b32_e32 v243,31,v242
	v_ashrrev_i32_e32 v242,11,v242
	v_add_u32_e32 v242,v242,v243
	v_mul_i32_i24_e32 v242,0x1010,v242
	v_sub_u32_e32 v240,v240,v242
	v_lshl_or_b32 v240,v240,4,v151
	v_ashrrev_i32_e32 v241,31,v240
	v_lshl_add_u64 v[240:241],v[240:241],3,s[74:75]
	global_load_dwordx2 v[186:187], v[240:241], off
	v_cvt_pk_bf16_f32 v96, v97, s0
	global_store_short v[102:103], v96, off
	v_or_b32_e32 v102, 56, v138
	v_mul_f32_e32 v103, v107, v99
	v_add_u32_e32 v104, s18, v102
	ds_bpermute_b32 v106, v152, v103
	v_min_i32_e32 v98, 0x403f, v104
	v_mul_hi_i32 v100, v98, s36
	v_lshrrev_b32_e32 v101, 31, v100
	v_ashrrev_i32_e32 v100, 11, v100
	v_add_u32_e32 v100, v100, v101
	v_mul_i32_i24_e32 v100, 0x1010, v100
	v_sub_u32_e32 v98, v98, v100
	v_lshl_or_b32 v98, v98, 4, v151
	v_ashrrev_i32_e32 v99, 31, v98
	v_lshl_add_u64 v[100:101], v[192:193], 1, s[56:57]
	v_lshl_add_u64 v[98:99], v[98:99], 3, s[74:75]
	v_lshl_or_b32 v192, v104, 5, v142
	s_waitcnt lgkmcnt(0)
	s_waitcnt vmcnt(39)
	v_mul_f32_e32 v97, v189, v106
	v_cndmask_b32_e64 v97, v97, -v97, vcc
	v_fmac_f32_e32 v97, v103, v188
	v_add_u32_e32 v237,0x5b,v139
	v_min_i32_e32 v240,0x403f,v237
	v_mul_hi_i32 v241,v240,s36
	v_lshrrev_b32_e32 v242,31,v241
	v_ashrrev_i32_e32 v241,11,v241
	v_add_u32_e32 v241,v241,v242
	v_mul_i32_i24_e32 v241,0x1010,v241
	v_sub_u32_e32 v240,v240,v241
	v_lshl_or_b32 v240,v240,4,v151
	v_ashrrev_i32_e32 v241,31,v240
	v_lshl_add_u64 v[240:241],v[240:241],3,s[74:75]
	global_load_dwordx2 v[188:189], v[240:241], off
	v_cvt_pk_bf16_f32 v96, v97, s0
	global_store_short v[100:101], v96, off
	v_add_u32_e32 v106, 57, v139
	v_lshl_add_u32 v96, v102, 2, v200
	v_min_i32_e32 v102, 0x403f, v106
	v_mul_hi_i32 v97, v102, s36
	v_lshrrev_b32_e32 v103, 31, v97
	v_ashrrev_i32_e32 v105, 11, v97
	ds_read_b128 v[96:99], v96
	v_add_u32_e32 v103, v105, v103
	v_mul_i32_i24_e32 v103, 0x1010, v103
	v_sub_u32_e32 v102, v102, v103
	v_lshl_or_b32 v102, v102, 4, v151
	s_waitcnt lgkmcnt(0)
	v_mul_f32_e32 v96, v108, v96
	ds_bpermute_b32 v107, v152, v96
	v_ashrrev_i32_e32 v103, 31, v102
	v_lshl_add_u64 v[104:105], v[192:193], 1, s[56:57]
	v_lshl_add_u64 v[102:103], v[102:103], 3, s[74:75]
	v_lshl_or_b32 v192, v106, 5, v142
	v_mul_f32_e32 v98, v110, v98
	ds_bpermute_b32 v106, v152, v98
	s_waitcnt lgkmcnt(1)
	s_waitcnt vmcnt(39)
	v_mul_f32_e32 v101, v191, v107
	v_cndmask_b32_e64 v101, v101, -v101, vcc
	v_fmac_f32_e32 v101, v96, v190
	v_or_b32_e32 v236,0x60,v138
	v_add_u32_e32 v240,s18,v236
	v_min_i32_e32 v242,0x403f,v240
	v_mul_hi_i32 v244,v242,s36
	v_lshrrev_b32_e32 v245,31,v244
	v_ashrrev_i32_e32 v244,11,v244
	v_add_u32_e32 v244,v244,v245
	v_mul_i32_i24_e32 v244,0x1010,v244
	v_sub_u32_e32 v242,v242,v244
	v_lshl_or_b32 v242,v242,4,v151
	v_ashrrev_i32_e32 v243,31,v242
	v_lshl_add_u64 v[242:243],v[242:243],3,s[74:75]
	global_load_dwordx2 v[190:191], v[242:243], off
	v_cvt_pk_bf16_f32 v96, v101, s0
	global_store_short v[104:105], v96, off
	v_mul_f32_e32 v105, v109, v97
	v_add_u32_e32 v104, 58, v139
	ds_bpermute_b32 v107, v152, v105
	v_min_i32_e32 v96, 0x403f, v104
	v_mul_hi_i32 v102, v96, s36
	v_lshrrev_b32_e32 v103, 31, v102
	v_ashrrev_i32_e32 v102, 11, v102
	v_add_u32_e32 v102, v102, v103
	v_mul_i32_i24_e32 v102, 0x1010, v102
	v_sub_u32_e32 v96, v96, v102
	v_lshl_or_b32 v96, v96, 4, v151
	v_ashrrev_i32_e32 v97, 31, v96
	v_lshl_add_u64 v[102:103], v[192:193], 1, s[56:57]
	v_lshl_add_u64 v[96:97], v[96:97], 3, s[74:75]
	v_lshl_or_b32 v192, v104, 5, v142
	s_waitcnt lgkmcnt(0)
	s_waitcnt vmcnt(39)
	v_mul_f32_e32 v101, v195, v107
	v_cndmask_b32_e64 v101, v101, -v101, vcc
	v_fmac_f32_e32 v101, v105, v194
	v_add_u32_e32 v236,0x61,v139
	v_min_i32_e32 v240,0x403f,v236
	v_mul_hi_i32 v243,v240,s36
	v_lshrrev_b32_e32 v241,31,v243
	v_ashrrev_i32_e32 v245,11,v243
	v_add_u32_e32 v241,v245,v241
	v_mul_i32_i24_e32 v241,0x1010,v241
	v_sub_u32_e32 v240,v240,v241
	v_lshl_or_b32 v240,v240,4,v151
	v_ashrrev_i32_e32 v241,31,v240
	v_lshl_add_u64 v[240:241],v[240:241],3,s[74:75]
	global_load_dwordx2 v[194:195], v[240:241], off
	v_cvt_pk_bf16_f32 v100, v101, s0
	global_store_short v[102:103], v100, off
	v_add_u32_e32 v105, 59, v139
	v_min_i32_e32 v100, 0x403f, v105
	v_mul_hi_i32 v101, v100, s36
	v_lshrrev_b32_e32 v102, 31, v101
	v_ashrrev_i32_e32 v101, 11, v101
	v_add_u32_e32 v101, v101, v102
	v_mul_i32_i24_e32 v101, 0x1010, v101
	v_sub_u32_e32 v100, v100, v101
	v_lshl_or_b32 v100, v100, 4, v151
	v_ashrrev_i32_e32 v101, 31, v100
	v_lshl_add_u64 v[102:103], v[192:193], 1, s[56:57]
	v_lshl_add_u64 v[100:101], v[100:101], 3, s[74:75]
	v_lshl_or_b32 v192, v105, 5, v142
	s_waitcnt vmcnt(39)
	v_mul_f32_e32 v97, v197, v106
	v_cndmask_b32_e64 v97, v97, -v97, vcc
	v_fmac_f32_e32 v97, v98, v196
	v_add_u32_e32 v236,0x62,v139
	v_min_i32_e32 v240,0x403f,v236
	v_mul_hi_i32 v242,v240,s36
	v_lshrrev_b32_e32 v237,31,v242
	v_ashrrev_i32_e32 v242,11,v242
	v_add_u32_e32 v242,v242,v237
	v_mul_i32_i24_e32 v242,0x1010,v242
	v_sub_u32_e32 v240,v240,v242
	v_lshl_or_b32 v240,v240,4,v151
	v_ashrrev_i32_e32 v241,31,v240
	v_lshl_add_u64 v[240:241],v[240:241],3,s[74:75]
	global_load_dwordx2 v[196:197], v[240:241], off
	v_cvt_pk_bf16_f32 v96, v97, s0
	global_store_short v[102:103], v96, off
	v_mul_f32_e32 v103, v111, v99
	v_or_b32_e32 v102, 64, v138
	ds_bpermute_b32 v106, v152, v103
	v_add_u32_e32 v104, s18, v102
	v_min_i32_e32 v98, 0x403f, v104
	v_mul_hi_i32 v100, v98, s36
	v_lshrrev_b32_e32 v101, 31, v100
	v_ashrrev_i32_e32 v100, 11, v100
	v_add_u32_e32 v100, v100, v101
	v_mul_i32_i24_e32 v100, 0x1010, v100
	v_sub_u32_e32 v98, v98, v100
	v_lshl_or_b32 v98, v98, 4, v151
	v_lshl_add_u64 v[100:101], v[192:193], 1, s[56:57]
	v_ashrrev_i32_e32 v99, 31, v98
	v_lshl_add_u64 v[98:99], v[98:99], 3, s[74:75]
	v_lshl_or_b32 v192, v104, 5, v142
	s_waitcnt lgkmcnt(0)
	s_waitcnt vmcnt(39)
	v_mul_f32_e32 v97, v199, v106
	v_cndmask_b32_e64 v97, v97, -v97, vcc
	v_fmac_f32_e32 v97, v103, v198
	v_add_u32_e32 v237,0x63,v139
	v_min_i32_e32 v240,0x403f,v237
	v_mul_hi_i32 v241,v240,s36
	v_lshrrev_b32_e32 v242,31,v241
	v_ashrrev_i32_e32 v241,11,v241
	v_add_u32_e32 v241,v241,v242
	v_mul_i32_i24_e32 v241,0x1010,v241
	v_sub_u32_e32 v240,v240,v241
	v_lshl_or_b32 v240,v240,4,v151
	v_ashrrev_i32_e32 v241,31,v240
	v_lshl_add_u64 v[240:241],v[240:241],3,s[74:75]
	global_load_dwordx2 v[198:199], v[240:241], off
	v_cvt_pk_bf16_f32 v96, v97, s0
	global_store_short v[100:101], v96, off
	v_add_u32_e32 v106, 0x41, v139
	v_lshl_add_u32 v96, v102, 2, v200
	v_min_i32_e32 v102, 0x403f, v106
	v_mul_hi_i32 v97, v102, s36
	v_lshrrev_b32_e32 v103, 31, v97
	v_ashrrev_i32_e32 v105, 11, v97
	ds_read_b128 v[96:99], v96
	v_add_u32_e32 v103, v105, v103
	v_mul_i32_i24_e32 v103, 0x1010, v103
	v_sub_u32_e32 v102, v102, v103
	v_lshl_or_b32 v102, v102, 4, v151
	s_waitcnt lgkmcnt(0)
	v_mul_f32_e32 v80, v80, v96
	ds_bpermute_b32 v96, v152, v80
	v_ashrrev_i32_e32 v103, 31, v102
	v_lshl_add_u64 v[104:105], v[192:193], 1, s[56:57]
	v_lshl_add_u64 v[102:103], v[102:103], 3, s[74:75]
	v_lshl_or_b32 v192, v106, 5, v142
	v_mul_f32_e32 v82, v82, v98
	ds_bpermute_b32 v98, v152, v82
	v_mul_f32_e32 v99, v83, v99
	s_waitcnt lgkmcnt(1)
	s_waitcnt vmcnt(39)
	v_mul_f32_e32 v96, v205, v96
	v_cndmask_b32_e64 v96, v96, -v96, vcc
	v_fmac_f32_e32 v96, v80, v204
	v_or_b32_e32 v236,0x68,v138
	v_add_u32_e32 v240,s18,v236
	v_min_i32_e32 v242,0x403f,v240
	v_mul_hi_i32 v244,v242,s36
	v_lshrrev_b32_e32 v245,31,v244
	v_ashrrev_i32_e32 v244,11,v244
	v_add_u32_e32 v244,v244,v245
	v_mul_i32_i24_e32 v244,0x1010,v244
	v_sub_u32_e32 v242,v242,v244
	v_lshl_or_b32 v242,v242,4,v151
	v_ashrrev_i32_e32 v243,31,v242
	v_lshl_add_u64 v[242:243],v[242:243],3,s[74:75]
	global_load_dwordx2 v[204:205], v[242:243], off
	v_cvt_pk_bf16_f32 v80, v96, s0
	global_store_short v[104:105], v80, off
	v_add_u32_e32 v102, 0x42, v139
	v_min_i32_e32 v80, 0x403f, v102
	v_mul_hi_i32 v96, v80, s36
	v_lshrrev_b32_e32 v103, 31, v96
	v_ashrrev_i32_e32 v96, 11, v96
	v_add_u32_e32 v96, v96, v103
	v_mul_f32_e32 v103, v81, v97
	ds_bpermute_b32 v104, v152, v103
	v_mul_i32_i24_e32 v96, 0x1010, v96
	v_sub_u32_e32 v80, v80, v96
	v_lshl_or_b32 v80, v80, 4, v151
	v_ashrrev_i32_e32 v81, 31, v80
	v_lshl_add_u64 v[96:97], v[192:193], 1, s[56:57]
	v_lshl_add_u64 v[80:81], v[80:81], 3, s[74:75]
	v_lshl_or_b32 v192, v102, 5, v142
	v_add_u32_e32 v102, 0x49, v139
	s_waitcnt lgkmcnt(0)
	s_waitcnt vmcnt(39)
	v_mul_f32_e32 v101, v207, v104
	v_cndmask_b32_e64 v101, v101, -v101, vcc
	v_fmac_f32_e32 v101, v103, v206
	v_add_u32_e32 v236,0x69,v139
	v_min_i32_e32 v240,0x403f,v236
	v_mul_hi_i32 v243,v240,s36
	v_lshrrev_b32_e32 v241,31,v243
	v_ashrrev_i32_e32 v245,11,v243
	v_add_u32_e32 v241,v245,v241
	v_mul_i32_i24_e32 v241,0x1010,v241
	v_sub_u32_e32 v240,v240,v241
	v_lshl_or_b32 v240,v240,4,v151
	v_ashrrev_i32_e32 v241,31,v240
	v_lshl_add_u64 v[240:241],v[240:241],3,s[74:75]
	global_load_dwordx2 v[206:207], v[240:241], off
	v_cvt_pk_bf16_f32 v100, v101, s0
	global_store_short v[96:97], v100, off
	v_add_u32_e32 v103, 0x43, v139
	v_min_i32_e32 v96, 0x403f, v103
	v_mul_hi_i32 v97, v96, s36
	v_lshrrev_b32_e32 v100, 31, v97
	v_ashrrev_i32_e32 v97, 11, v97
	v_add_u32_e32 v97, v97, v100
	v_mul_i32_i24_e32 v97, 0x1010, v97
	v_sub_u32_e32 v96, v96, v97
	v_lshl_or_b32 v96, v96, 4, v151
	v_ashrrev_i32_e32 v97, 31, v96
	v_lshl_add_u64 v[100:101], v[192:193], 1, s[56:57]
	v_lshl_add_u64 v[96:97], v[96:97], 3, s[74:75]
	v_lshl_or_b32 v192, v103, 5, v142
	s_waitcnt vmcnt(39)
	v_mul_f32_e32 v81, v225, v98
	v_cndmask_b32_e64 v81, v81, -v81, vcc
	v_fmac_f32_e32 v81, v82, v224
	v_add_u32_e32 v236,0x6a,v139
	v_min_i32_e32 v240,0x403f,v236
	v_mul_hi_i32 v242,v240,s36
	v_lshrrev_b32_e32 v237,31,v242
	v_ashrrev_i32_e32 v242,11,v242
	v_add_u32_e32 v242,v242,v237
	v_mul_i32_i24_e32 v242,0x1010,v242
	v_sub_u32_e32 v240,v240,v242
	v_lshl_or_b32 v240,v240,4,v151
	v_ashrrev_i32_e32 v241,31,v240
	v_lshl_add_u64 v[240:241],v[240:241],3,s[74:75]
	global_load_dwordx2 v[224:225], v[240:241], off
	v_cvt_pk_bf16_f32 v80, v81, s0
	global_store_short v[100:101], v80, off
	v_or_b32_e32 v98, 0x48, v138
	v_add_u32_e32 v100, s18, v98
	ds_bpermute_b32 v101, v152, v99
	v_min_i32_e32 v82, 0x403f, v100
	v_mul_hi_i32 v96, v82, s36
	v_lshrrev_b32_e32 v97, 31, v96
	v_ashrrev_i32_e32 v96, 11, v96
	v_add_u32_e32 v96, v96, v97
	v_mul_i32_i24_e32 v96, 0x1010, v96
	v_sub_u32_e32 v82, v82, v96
	v_lshl_or_b32 v82, v82, 4, v151
	v_ashrrev_i32_e32 v83, 31, v82
	v_lshl_add_u64 v[96:97], v[192:193], 1, s[56:57]
	v_lshl_add_u64 v[82:83], v[82:83], 3, s[74:75]
	v_lshl_or_b32 v192, v100, 5, v142
	s_waitcnt lgkmcnt(0)
	s_waitcnt vmcnt(39)
	v_mul_f32_e32 v81, v227, v101
	v_cndmask_b32_e64 v81, v81, -v81, vcc
	v_fmac_f32_e32 v81, v99, v226
	v_add_u32_e32 v237,0x6b,v139
	v_min_i32_e32 v240,0x403f,v237
	v_mul_hi_i32 v241,v240,s36
	v_lshrrev_b32_e32 v242,31,v241
	v_ashrrev_i32_e32 v241,11,v241
	v_add_u32_e32 v241,v241,v242
	v_mul_i32_i24_e32 v241,0x1010,v241
	v_sub_u32_e32 v240,v240,v241
	v_lshl_or_b32 v240,v240,4,v151
	v_ashrrev_i32_e32 v241,31,v240
	v_lshl_add_u64 v[240:241],v[240:241],3,s[74:75]
	global_load_dwordx2 v[226:227], v[240:241], off
	v_cvt_pk_bf16_f32 v80, v81, s0
	global_store_short v[96:97], v80, off
	v_lshl_add_u32 v80, v98, 2, v200
	v_min_i32_e32 v98, 0x403f, v102
	v_mul_hi_i32 v81, v98, s36
	v_lshrrev_b32_e32 v99, 31, v81
	v_ashrrev_i32_e32 v101, 11, v81
	ds_read_b128 v[80:83], v80
	v_add_u32_e32 v99, v101, v99
	v_mul_i32_i24_e32 v99, 0x1010, v99
	v_sub_u32_e32 v98, v98, v99
	v_lshl_or_b32 v98, v98, 4, v151
	s_waitcnt lgkmcnt(0)
	v_mul_f32_e32 v80, v84, v80
	ds_bpermute_b32 v84, v152, v80
	v_ashrrev_i32_e32 v99, 31, v98
	v_lshl_add_u64 v[100:101], v[192:193], 1, s[56:57]
	v_lshl_add_u64 v[98:99], v[98:99], 3, s[74:75]
	v_lshl_or_b32 v192, v102, 5, v142
	v_mul_f32_e32 v82, v86, v82
	ds_bpermute_b32 v86, v152, v82
	v_mul_f32_e32 v87, v87, v83
	s_waitcnt lgkmcnt(1)
	s_waitcnt vmcnt(39)
	v_mul_f32_e32 v84, v229, v84
	v_cndmask_b32_e64 v84, v84, -v84, vcc
	v_fmac_f32_e32 v84, v80, v228
	v_or_b32_e32 v236,0x70,v138
	v_add_u32_e32 v240,s18,v236
	v_min_i32_e32 v242,0x403f,v240
	v_mul_hi_i32 v244,v242,s36
	v_lshrrev_b32_e32 v245,31,v244
	v_ashrrev_i32_e32 v244,11,v244
	v_add_u32_e32 v244,v244,v245
	v_mul_i32_i24_e32 v244,0x1010,v244
	v_sub_u32_e32 v242,v242,v244
	v_lshl_or_b32 v242,v242,4,v151
	v_ashrrev_i32_e32 v243,31,v242
	v_lshl_add_u64 v[242:243],v[242:243],3,s[74:75]
	global_load_dwordx2 v[228:229], v[242:243], off
	v_cvt_pk_bf16_f32 v80, v84, s0
	global_store_short v[100:101], v80, off
	v_add_u32_e32 v98, 0x4a, v139
	v_min_i32_e32 v80, 0x403f, v98
	v_mul_hi_i32 v84, v80, s36
	v_lshrrev_b32_e32 v99, 31, v84
	v_ashrrev_i32_e32 v84, 11, v84
	v_add_u32_e32 v84, v84, v99
	v_mul_f32_e32 v99, v85, v81
	ds_bpermute_b32 v100, v152, v99
	v_mul_i32_i24_e32 v84, 0x1010, v84
	v_sub_u32_e32 v80, v80, v84
	v_lshl_or_b32 v80, v80, 4, v151
	v_ashrrev_i32_e32 v81, 31, v80
	v_lshl_add_u64 v[84:85], v[192:193], 1, s[56:57]
	v_lshl_add_u64 v[80:81], v[80:81], 3, s[74:75]
	v_lshl_or_b32 v192, v98, 5, v142
	v_add_u32_e32 v98, 0x51, v139
	s_waitcnt lgkmcnt(0)
	s_waitcnt vmcnt(39)
	v_mul_f32_e32 v97, v231, v100
	v_cndmask_b32_e64 v97, v97, -v97, vcc
	v_fmac_f32_e32 v97, v99, v230
	v_add_u32_e32 v236,0x71,v139
	v_min_i32_e32 v240,0x403f,v236
	v_mul_hi_i32 v243,v240,s36
	v_lshrrev_b32_e32 v241,31,v243
	v_ashrrev_i32_e32 v245,11,v243
	v_add_u32_e32 v241,v245,v241
	v_mul_i32_i24_e32 v241,0x1010,v241
	v_sub_u32_e32 v240,v240,v241
	v_lshl_or_b32 v240,v240,4,v151
	v_ashrrev_i32_e32 v241,31,v240
	v_lshl_add_u64 v[240:241],v[240:241],3,s[74:75]
	global_load_dwordx2 v[230:231], v[240:241], off
	v_cvt_pk_bf16_f32 v96, v97, s0
	global_store_short v[84:85], v96, off
	v_add_u32_e32 v99, 0x4b, v139
	v_min_i32_e32 v84, 0x403f, v99
	v_mul_hi_i32 v85, v84, s36
	v_lshrrev_b32_e32 v96, 31, v85
	v_ashrrev_i32_e32 v85, 11, v85
	v_add_u32_e32 v85, v85, v96
	v_mul_i32_i24_e32 v85, 0x1010, v85
	v_sub_u32_e32 v84, v84, v85
	v_lshl_or_b32 v84, v84, 4, v151
	v_ashrrev_i32_e32 v85, 31, v84
	v_lshl_add_u64 v[96:97], v[192:193], 1, s[56:57]
	v_lshl_add_u64 v[84:85], v[84:85], 3, s[74:75]
	v_lshl_or_b32 v192, v99, 5, v142
	s_waitcnt vmcnt(39)
	v_mul_f32_e32 v81, v233, v86
	v_cndmask_b32_e64 v81, v81, -v81, vcc
	v_fmac_f32_e32 v81, v82, v232
	v_add_u32_e32 v236,0x72,v139
	v_min_i32_e32 v240,0x403f,v236
	v_mul_hi_i32 v242,v240,s36
	v_lshrrev_b32_e32 v243,31,v242
	v_ashrrev_i32_e32 v242,11,v242
	v_add_u32_e32 v242,v242,v243
	v_mul_i32_i24_e32 v242,0x1010,v242
	v_sub_u32_e32 v240,v240,v242
	v_lshl_or_b32 v240,v240,4,v151
	v_ashrrev_i32_e32 v241,31,v240
	v_lshl_add_u64 v[240:241],v[240:241],3,s[74:75]
	global_load_dwordx2 v[232:233], v[240:241], off
	v_cvt_pk_bf16_f32 v80, v81, s0
	global_store_short v[96:97], v80, off
	v_or_b32_e32 v86, 0x50, v138
	v_add_u32_e32 v96, s18, v86
	ds_bpermute_b32 v97, v152, v87
	v_min_i32_e32 v82, 0x403f, v96
	v_mul_hi_i32 v84, v82, s36
	v_lshrrev_b32_e32 v85, 31, v84
	v_ashrrev_i32_e32 v84, 11, v84
	v_add_u32_e32 v84, v84, v85
	v_mul_i32_i24_e32 v84, 0x1010, v84
	v_sub_u32_e32 v82, v82, v84
	v_lshl_or_b32 v82, v82, 4, v151
	v_ashrrev_i32_e32 v83, 31, v82
	v_lshl_add_u64 v[84:85], v[192:193], 1, s[56:57]
	v_lshl_add_u64 v[82:83], v[82:83], 3, s[74:75]
	v_lshl_or_b32 v192, v96, 5, v142
	s_waitcnt lgkmcnt(0)
	s_waitcnt vmcnt(39)
	v_mul_f32_e32 v81, v235, v97
	v_cndmask_b32_e64 v81, v81, -v81, vcc
	v_fmac_f32_e32 v81, v87, v234
	v_add_u32_e32 v237,0x73,v139
	v_min_i32_e32 v240,0x403f,v237
	v_mul_hi_i32 v241,v240,s36
	v_lshrrev_b32_e32 v242,31,v241
	v_ashrrev_i32_e32 v241,11,v241
	v_add_u32_e32 v241,v241,v242
	v_mul_i32_i24_e32 v241,0x1010,v241
	v_sub_u32_e32 v240,v240,v241
	v_lshl_or_b32 v240,v240,4,v151
	v_ashrrev_i32_e32 v241,31,v240
	v_lshl_add_u64 v[240:241],v[240:241],3,s[74:75]
	global_load_dwordx2 v[234:235], v[240:241], off
	v_cvt_pk_bf16_f32 v80, v81, s0
	global_store_short v[84:85], v80, off
	v_lshl_add_u32 v80, v86, 2, v200
	v_min_i32_e32 v86, 0x403f, v98
	v_mul_hi_i32 v81, v86, s36
	v_lshrrev_b32_e32 v87, 31, v81
	v_ashrrev_i32_e32 v97, 11, v81
	ds_read_b128 v[80:83], v80
	v_add_u32_e32 v87, v97, v87
	v_mul_i32_i24_e32 v87, 0x1010, v87
	v_sub_u32_e32 v86, v86, v87
	v_lshl_or_b32 v86, v86, 4, v151
	s_waitcnt lgkmcnt(0)
	v_mul_f32_e32 v80, v88, v80
	ds_bpermute_b32 v88, v152, v80
	v_ashrrev_i32_e32 v87, 31, v86
	v_lshl_add_u64 v[96:97], v[192:193], 1, s[56:57]
	v_lshl_add_u64 v[86:87], v[86:87], 3, s[74:75]
	v_mul_f32_e32 v89, v89, v81
	v_lshl_or_b32 v192, v98, 5, v142
	v_mul_f32_e32 v82, v90, v82
	ds_bpermute_b32 v90, v152, v82
	s_waitcnt lgkmcnt(1)
	s_waitcnt vmcnt(39)
	v_mul_f32_e32 v85, v175, v88
	v_cndmask_b32_e64 v85, v85, -v85, vcc
	v_fmac_f32_e32 v85, v80, v174
	v_or_b32_e32 v236,0x78,v138
	v_add_u32_e32 v240,s18,v236
	v_min_i32_e32 v242,0x403f,v240
	v_mul_hi_i32 v244,v242,s36
	v_lshrrev_b32_e32 v245,31,v244
	v_ashrrev_i32_e32 v244,11,v244
	v_add_u32_e32 v244,v244,v245
	v_mul_i32_i24_e32 v244,0x1010,v244
	v_sub_u32_e32 v242,v242,v244
	v_lshl_or_b32 v242,v242,4,v151
	v_ashrrev_i32_e32 v243,31,v242
	v_lshl_add_u64 v[242:243],v[242:243],3,s[74:75]
	global_load_dwordx2 v[174:175], v[242:243], off
	v_cvt_pk_bf16_f32 v80, v85, s0
	global_store_short v[96:97], v80, off
	v_add_u32_e32 v88, 0x52, v139
	ds_bpermute_b32 v96, v152, v89
	v_min_i32_e32 v80, 0x403f, v88
	v_mul_hi_i32 v86, v80, s36
	v_lshrrev_b32_e32 v87, 31, v86
	v_ashrrev_i32_e32 v86, 11, v86
	v_add_u32_e32 v86, v86, v87
	v_mul_i32_i24_e32 v86, 0x1010, v86
	v_sub_u32_e32 v80, v80, v86
	v_lshl_or_b32 v80, v80, 4, v151
	v_ashrrev_i32_e32 v81, 31, v80
	v_lshl_add_u64 v[86:87], v[192:193], 1, s[56:57]
	v_lshl_add_u64 v[80:81], v[80:81], 3, s[74:75]
	v_lshl_or_b32 v192, v88, 5, v142
	s_waitcnt lgkmcnt(0)
	s_waitcnt vmcnt(39)
	v_mul_f32_e32 v85, v177, v96
	v_cndmask_b32_e64 v85, v85, -v85, vcc
	v_fmac_f32_e32 v85, v89, v176
	v_add_u32_e32 v236,0x79,v139
	v_min_i32_e32 v240,0x403f,v236
	v_mul_hi_i32 v243,v240,s36
	v_lshrrev_b32_e32 v241,31,v243
	v_ashrrev_i32_e32 v245,11,v243
	v_add_u32_e32 v241,v245,v241
	v_mul_i32_i24_e32 v241,0x1010,v241
	v_sub_u32_e32 v240,v240,v241
	v_lshl_or_b32 v240,v240,4,v151
	v_ashrrev_i32_e32 v241,31,v240
	v_lshl_add_u64 v[240:241],v[240:241],3,s[74:75]
	global_load_dwordx2 v[176:177], v[240:241], off
	v_cvt_pk_bf16_f32 v84, v85, s0
	global_store_short v[86:87], v84, off
	v_add_u32_e32 v89, 0x53, v139
	v_min_i32_e32 v84, 0x403f, v89
	v_mul_hi_i32 v85, v84, s36
	v_lshrrev_b32_e32 v86, 31, v85
	v_ashrrev_i32_e32 v85, 11, v85
	v_add_u32_e32 v85, v85, v86
	v_mul_i32_i24_e32 v85, 0x1010, v85
	v_sub_u32_e32 v84, v84, v85
	v_lshl_or_b32 v84, v84, 4, v151
	v_ashrrev_i32_e32 v85, 31, v84
	v_lshl_add_u64 v[86:87], v[192:193], 1, s[56:57]
	v_lshl_add_u64 v[84:85], v[84:85], 3, s[74:75]
	v_lshl_or_b32 v192, v89, 5, v142
	s_waitcnt vmcnt(39)
	v_mul_f32_e32 v81, v179, v90
	v_cndmask_b32_e64 v81, v81, -v81, vcc
	v_fmac_f32_e32 v81, v82, v178
	v_add_u32_e32 v236,0x7a,v139
	v_min_i32_e32 v240,0x403f,v236
	v_mul_hi_i32 v242,v240,s36
	v_lshrrev_b32_e32 v243,31,v242
	v_ashrrev_i32_e32 v242,11,v242
	v_add_u32_e32 v242,v242,v243
	v_mul_i32_i24_e32 v242,0x1010,v242
	v_sub_u32_e32 v240,v240,v242
	v_lshl_or_b32 v240,v240,4,v151
	v_ashrrev_i32_e32 v241,31,v240
	v_lshl_add_u64 v[240:241],v[240:241],3,s[74:75]
	global_load_dwordx2 v[178:179], v[240:241], off
	v_cvt_pk_bf16_f32 v80, v81, s0
	global_store_short v[86:87], v80, off
	v_or_b32_e32 v86, 0x58, v138
	v_mul_f32_e32 v87, v91, v83
	v_add_u32_e32 v88, s18, v86
	ds_bpermute_b32 v90, v152, v87
	v_min_i32_e32 v82, 0x403f, v88
	v_mul_hi_i32 v84, v82, s36
	v_lshrrev_b32_e32 v85, 31, v84
	v_ashrrev_i32_e32 v84, 11, v84
	v_add_u32_e32 v84, v84, v85
	v_mul_i32_i24_e32 v84, 0x1010, v84
	v_sub_u32_e32 v82, v82, v84
	v_lshl_or_b32 v82, v82, 4, v151
	v_ashrrev_i32_e32 v83, 31, v82
	v_lshl_add_u64 v[84:85], v[192:193], 1, s[56:57]
	v_lshl_add_u64 v[82:83], v[82:83], 3, s[74:75]
	v_lshl_or_b32 v192, v88, 5, v142
	s_waitcnt lgkmcnt(0)
	s_waitcnt vmcnt(39)
	v_mul_f32_e32 v81, v181, v90
	v_cndmask_b32_e64 v81, v81, -v81, vcc
	v_fmac_f32_e32 v81, v87, v180
	v_add_u32_e32 v237,0x7b,v139
	v_min_i32_e32 v240,0x403f,v237
	v_mul_hi_i32 v241,v240,s36
	v_lshrrev_b32_e32 v242,31,v241
	v_ashrrev_i32_e32 v241,11,v241
	v_add_u32_e32 v241,v241,v242
	v_mul_i32_i24_e32 v241,0x1010,v241
	v_sub_u32_e32 v240,v240,v241
	v_lshl_or_b32 v240,v240,4,v151
	v_ashrrev_i32_e32 v241,31,v240
	v_lshl_add_u64 v[240:241],v[240:241],3,s[74:75]
	global_load_dwordx2 v[180:181], v[240:241], off
	v_cvt_pk_bf16_f32 v80, v81, s0
	global_store_short v[84:85], v80, off
	v_add_u32_e32 v90, 0x59, v139
	v_lshl_add_u32 v80, v86, 2, v200
	v_min_i32_e32 v86, 0x403f, v90
	v_mul_hi_i32 v81, v86, s36
	v_lshrrev_b32_e32 v87, 31, v81
	v_ashrrev_i32_e32 v89, 11, v81
	ds_read_b128 v[80:83], v80
	v_add_u32_e32 v87, v89, v87
	v_mul_i32_i24_e32 v87, 0x1010, v87
	v_sub_u32_e32 v86, v86, v87
	v_lshl_or_b32 v86, v86, 4, v151
	s_waitcnt lgkmcnt(0)
	v_mul_f32_e32 v80, v92, v80
	ds_bpermute_b32 v91, v152, v80
	v_ashrrev_i32_e32 v87, 31, v86
	v_lshl_add_u64 v[88:89], v[192:193], 1, s[56:57]
	v_lshl_add_u64 v[86:87], v[86:87], 3, s[74:75]
	v_lshl_or_b32 v192, v90, 5, v142
	v_mul_f32_e32 v82, v94, v82
	ds_bpermute_b32 v90, v152, v82
	s_waitcnt lgkmcnt(1)
	s_waitcnt vmcnt(39)
	v_mul_f32_e32 v85, v183, v91
	v_cndmask_b32_e64 v85, v85, -v85, vcc
	v_fmac_f32_e32 v85, v80, v182
	v_cvt_pk_bf16_f32 v80, v85, s0
	global_store_short v[88:89], v80, off
	v_mul_f32_e32 v89, v93, v81
	v_add_u32_e32 v88, 0x5a, v139
	ds_bpermute_b32 v91, v152, v89
	v_min_i32_e32 v80, 0x403f, v88
	v_mul_hi_i32 v86, v80, s36
	v_lshrrev_b32_e32 v87, 31, v86
	v_ashrrev_i32_e32 v86, 11, v86
	v_add_u32_e32 v86, v86, v87
	v_mul_i32_i24_e32 v86, 0x1010, v86
	v_sub_u32_e32 v80, v80, v86
	v_lshl_or_b32 v80, v80, 4, v151
	v_ashrrev_i32_e32 v81, 31, v80
	v_lshl_add_u64 v[86:87], v[192:193], 1, s[56:57]
	v_lshl_add_u64 v[80:81], v[80:81], 3, s[74:75]
	v_lshl_or_b32 v192, v88, 5, v142
	s_waitcnt lgkmcnt(0)
	s_waitcnt vmcnt(38)
	v_mul_f32_e32 v85, v185, v91
	v_cndmask_b32_e64 v85, v85, -v85, vcc
	v_fmac_f32_e32 v85, v89, v184
	v_cvt_pk_bf16_f32 v84, v85, s0
	global_store_short v[86:87], v84, off
	v_add_u32_e32 v89, 0x5b, v139
	v_min_i32_e32 v84, 0x403f, v89
	v_mul_hi_i32 v85, v84, s36
	v_lshrrev_b32_e32 v86, 31, v85
	v_ashrrev_i32_e32 v85, 11, v85
	v_add_u32_e32 v85, v85, v86
	v_mul_i32_i24_e32 v85, 0x1010, v85
	v_sub_u32_e32 v84, v84, v85
	v_lshl_or_b32 v84, v84, 4, v151
	v_ashrrev_i32_e32 v85, 31, v84
	v_lshl_add_u64 v[86:87], v[192:193], 1, s[56:57]
	v_lshl_add_u64 v[84:85], v[84:85], 3, s[74:75]
	v_lshl_or_b32 v192, v89, 5, v142
	s_waitcnt vmcnt(37)
	v_mul_f32_e32 v81, v187, v90
	v_cndmask_b32_e64 v81, v81, -v81, vcc
	v_fmac_f32_e32 v81, v82, v186
	v_cvt_pk_bf16_f32 v80, v81, s0
	global_store_short v[86:87], v80, off
	v_mul_f32_e32 v87, v95, v83
	v_or_b32_e32 v86, 0x60, v138
	ds_bpermute_b32 v90, v152, v87
	v_add_u32_e32 v88, s18, v86
	v_min_i32_e32 v82, 0x403f, v88
	v_mul_hi_i32 v84, v82, s36
	v_lshrrev_b32_e32 v85, 31, v84
	v_ashrrev_i32_e32 v84, 11, v84
	v_add_u32_e32 v84, v84, v85
	v_mul_i32_i24_e32 v84, 0x1010, v84
	v_sub_u32_e32 v82, v82, v84
	v_lshl_or_b32 v82, v82, 4, v151
	v_lshl_add_u64 v[84:85], v[192:193], 1, s[56:57]
	v_ashrrev_i32_e32 v83, 31, v82
	v_lshl_add_u64 v[82:83], v[82:83], 3, s[74:75]
	v_lshl_or_b32 v192, v88, 5, v142
	s_waitcnt lgkmcnt(0)
	s_waitcnt vmcnt(36)
	v_mul_f32_e32 v81, v189, v90
	v_cndmask_b32_e64 v81, v81, -v81, vcc
	v_fmac_f32_e32 v81, v87, v188
	v_cvt_pk_bf16_f32 v80, v81, s0
	global_store_short v[84:85], v80, off
	v_add_u32_e32 v90, 0x61, v139
	v_lshl_add_u32 v80, v86, 2, v200
	v_min_i32_e32 v86, 0x403f, v90
	v_mul_hi_i32 v81, v86, s36
	v_lshrrev_b32_e32 v87, 31, v81
	v_ashrrev_i32_e32 v89, 11, v81
	ds_read_b128 v[80:83], v80
	v_add_u32_e32 v87, v89, v87
	v_mul_i32_i24_e32 v87, 0x1010, v87
	v_sub_u32_e32 v86, v86, v87
	v_lshl_or_b32 v86, v86, 4, v151
	s_waitcnt lgkmcnt(0)
	v_mul_f32_e32 v64, v64, v80
	ds_bpermute_b32 v80, v152, v64
	v_ashrrev_i32_e32 v87, 31, v86
	v_lshl_add_u64 v[88:89], v[192:193], 1, s[56:57]
	v_lshl_add_u64 v[86:87], v[86:87], 3, s[74:75]
	v_lshl_or_b32 v192, v90, 5, v142
	v_mul_f32_e32 v66, v66, v82
	ds_bpermute_b32 v82, v152, v66
	v_mul_f32_e32 v83, v67, v83
	s_waitcnt lgkmcnt(1)
	s_waitcnt vmcnt(35)
	v_mul_f32_e32 v80, v191, v80
	v_cndmask_b32_e64 v80, v80, -v80, vcc
	v_fmac_f32_e32 v80, v64, v190
	v_cvt_pk_bf16_f32 v64, v80, s0
	global_store_short v[88:89], v64, off
	v_add_u32_e32 v86, 0x62, v139
	v_min_i32_e32 v64, 0x403f, v86
	v_mul_hi_i32 v80, v64, s36
	v_lshrrev_b32_e32 v87, 31, v80
	v_ashrrev_i32_e32 v80, 11, v80
	v_add_u32_e32 v80, v80, v87
	v_mul_f32_e32 v87, v65, v81
	ds_bpermute_b32 v88, v152, v87
	v_mul_i32_i24_e32 v80, 0x1010, v80
	v_sub_u32_e32 v64, v64, v80
	v_lshl_or_b32 v64, v64, 4, v151
	v_ashrrev_i32_e32 v65, 31, v64
	v_lshl_add_u64 v[80:81], v[192:193], 1, s[56:57]
	v_lshl_add_u64 v[64:65], v[64:65], 3, s[74:75]
	v_lshl_or_b32 v192, v86, 5, v142
	v_add_u32_e32 v86, 0x69, v139
	s_waitcnt lgkmcnt(0)
	s_waitcnt vmcnt(34)
	v_mul_f32_e32 v85, v195, v88
	v_cndmask_b32_e64 v85, v85, -v85, vcc
	v_fmac_f32_e32 v85, v87, v194
	v_cvt_pk_bf16_f32 v84, v85, s0
	global_store_short v[80:81], v84, off
	v_add_u32_e32 v87, 0x63, v139
	v_min_i32_e32 v80, 0x403f, v87
	v_mul_hi_i32 v81, v80, s36
	v_lshrrev_b32_e32 v84, 31, v81
	v_ashrrev_i32_e32 v81, 11, v81
	v_add_u32_e32 v81, v81, v84
	v_mul_i32_i24_e32 v81, 0x1010, v81
	v_sub_u32_e32 v80, v80, v81
	v_lshl_or_b32 v80, v80, 4, v151
	v_ashrrev_i32_e32 v81, 31, v80
	v_lshl_add_u64 v[84:85], v[192:193], 1, s[56:57]
	v_lshl_add_u64 v[80:81], v[80:81], 3, s[74:75]
	v_lshl_or_b32 v192, v87, 5, v142
	s_waitcnt vmcnt(33)
	v_mul_f32_e32 v65, v197, v82
	v_cndmask_b32_e64 v65, v65, -v65, vcc
	v_fmac_f32_e32 v65, v66, v196
	v_cvt_pk_bf16_f32 v64, v65, s0
	global_store_short v[84:85], v64, off
	v_or_b32_e32 v82, 0x68, v138
	v_add_u32_e32 v84, s18, v82
	ds_bpermute_b32 v85, v152, v83
	v_min_i32_e32 v66, 0x403f, v84
	v_mul_hi_i32 v80, v66, s36
	v_lshrrev_b32_e32 v81, 31, v80
	v_ashrrev_i32_e32 v80, 11, v80
	v_add_u32_e32 v80, v80, v81
	v_mul_i32_i24_e32 v80, 0x1010, v80
	v_sub_u32_e32 v66, v66, v80
	v_lshl_or_b32 v66, v66, 4, v151
	v_ashrrev_i32_e32 v67, 31, v66
	v_lshl_add_u64 v[80:81], v[192:193], 1, s[56:57]
	v_lshl_add_u64 v[66:67], v[66:67], 3, s[74:75]
	v_lshl_or_b32 v192, v84, 5, v142
	s_waitcnt lgkmcnt(0)
	s_waitcnt vmcnt(32)
	v_mul_f32_e32 v65, v199, v85
	v_cndmask_b32_e64 v65, v65, -v65, vcc
	v_fmac_f32_e32 v65, v83, v198
	v_cvt_pk_bf16_f32 v64, v65, s0
	global_store_short v[80:81], v64, off
	v_lshl_add_u32 v64, v82, 2, v200
	v_min_i32_e32 v82, 0x403f, v86
	v_mul_hi_i32 v65, v82, s36
	v_lshrrev_b32_e32 v83, 31, v65
	v_ashrrev_i32_e32 v85, 11, v65
	ds_read_b128 v[64:67], v64
	v_add_u32_e32 v83, v85, v83
	v_mul_i32_i24_e32 v83, 0x1010, v83
	v_sub_u32_e32 v82, v82, v83
	v_lshl_or_b32 v82, v82, 4, v151
	s_waitcnt lgkmcnt(0)
	v_mul_f32_e32 v64, v68, v64
	ds_bpermute_b32 v68, v152, v64
	v_ashrrev_i32_e32 v83, 31, v82
	v_lshl_add_u64 v[84:85], v[192:193], 1, s[56:57]
	v_lshl_add_u64 v[82:83], v[82:83], 3, s[74:75]
	v_lshl_or_b32 v192, v86, 5, v142
	v_mul_f32_e32 v66, v70, v66
	ds_bpermute_b32 v70, v152, v66
	v_mul_f32_e32 v71, v71, v67
	s_waitcnt lgkmcnt(1)
	s_waitcnt vmcnt(31)
	v_mul_f32_e32 v68, v205, v68
	v_cndmask_b32_e64 v68, v68, -v68, vcc
	v_fmac_f32_e32 v68, v64, v204
	v_cvt_pk_bf16_f32 v64, v68, s0
	global_store_short v[84:85], v64, off
	v_add_u32_e32 v82, 0x6a, v139
	v_min_i32_e32 v64, 0x403f, v82
	v_mul_hi_i32 v68, v64, s36
	v_lshrrev_b32_e32 v83, 31, v68
	v_ashrrev_i32_e32 v68, 11, v68
	v_add_u32_e32 v68, v68, v83
	v_mul_f32_e32 v83, v69, v65
	ds_bpermute_b32 v84, v152, v83
	v_mul_i32_i24_e32 v68, 0x1010, v68
	v_sub_u32_e32 v64, v64, v68
	v_lshl_or_b32 v64, v64, 4, v151
	v_ashrrev_i32_e32 v65, 31, v64
	v_lshl_add_u64 v[68:69], v[192:193], 1, s[56:57]
	v_lshl_add_u64 v[64:65], v[64:65], 3, s[74:75]
	v_lshl_or_b32 v192, v82, 5, v142
	v_add_u32_e32 v82, 0x71, v139
	s_waitcnt lgkmcnt(0)
	s_waitcnt vmcnt(30)
	v_mul_f32_e32 v81, v207, v84
	v_cndmask_b32_e64 v81, v81, -v81, vcc
	v_fmac_f32_e32 v81, v83, v206
	v_cvt_pk_bf16_f32 v80, v81, s0
	global_store_short v[68:69], v80, off
	v_add_u32_e32 v83, 0x6b, v139
	v_min_i32_e32 v68, 0x403f, v83
	v_mul_hi_i32 v69, v68, s36
	v_lshrrev_b32_e32 v80, 31, v69
	v_ashrrev_i32_e32 v69, 11, v69
	v_add_u32_e32 v69, v69, v80
	v_mul_i32_i24_e32 v69, 0x1010, v69
	v_sub_u32_e32 v68, v68, v69
	v_lshl_or_b32 v68, v68, 4, v151
	v_ashrrev_i32_e32 v69, 31, v68
	v_lshl_add_u64 v[80:81], v[192:193], 1, s[56:57]
	v_lshl_add_u64 v[68:69], v[68:69], 3, s[74:75]
	v_lshl_or_b32 v192, v83, 5, v142
	s_waitcnt vmcnt(29)
	v_mul_f32_e32 v65, v225, v70
	v_cndmask_b32_e64 v65, v65, -v65, vcc
	v_fmac_f32_e32 v65, v66, v224
	v_cvt_pk_bf16_f32 v64, v65, s0
	global_store_short v[80:81], v64, off
	v_or_b32_e32 v70, 0x70, v138
	v_add_u32_e32 v80, s18, v70
	ds_bpermute_b32 v81, v152, v71
	v_min_i32_e32 v66, 0x403f, v80
	v_mul_hi_i32 v68, v66, s36
	v_lshrrev_b32_e32 v69, 31, v68
	v_ashrrev_i32_e32 v68, 11, v68
	v_add_u32_e32 v68, v68, v69
	v_mul_i32_i24_e32 v68, 0x1010, v68
	v_sub_u32_e32 v66, v66, v68
	v_lshl_or_b32 v66, v66, 4, v151
	v_ashrrev_i32_e32 v67, 31, v66
	v_lshl_add_u64 v[68:69], v[192:193], 1, s[56:57]
	v_lshl_add_u64 v[66:67], v[66:67], 3, s[74:75]
	v_lshl_or_b32 v192, v80, 5, v142
	s_waitcnt lgkmcnt(0)
	s_waitcnt vmcnt(28)
	v_mul_f32_e32 v65, v227, v81
	v_cndmask_b32_e64 v65, v65, -v65, vcc
	v_fmac_f32_e32 v65, v71, v226
	v_cvt_pk_bf16_f32 v64, v65, s0
	global_store_short v[68:69], v64, off
	v_lshl_add_u32 v64, v70, 2, v200
	v_min_i32_e32 v70, 0x403f, v82
	v_mul_hi_i32 v65, v70, s36
	v_lshrrev_b32_e32 v71, 31, v65
	v_ashrrev_i32_e32 v81, 11, v65
	ds_read_b128 v[64:67], v64
	v_add_u32_e32 v71, v81, v71
	v_mul_i32_i24_e32 v71, 0x1010, v71
	v_sub_u32_e32 v70, v70, v71
	v_lshl_or_b32 v70, v70, 4, v151
	s_waitcnt lgkmcnt(0)
	v_mul_f32_e32 v64, v72, v64
	ds_bpermute_b32 v72, v152, v64
	v_ashrrev_i32_e32 v71, 31, v70
	v_lshl_add_u64 v[80:81], v[192:193], 1, s[56:57]
	v_lshl_add_u64 v[70:71], v[70:71], 3, s[74:75]
	v_mul_f32_e32 v73, v73, v65
	v_lshl_or_b32 v192, v82, 5, v142
	v_mul_f32_e32 v66, v74, v66
	ds_bpermute_b32 v74, v152, v66
	s_waitcnt lgkmcnt(1)
	s_waitcnt vmcnt(27)
	v_mul_f32_e32 v69, v229, v72
	v_cndmask_b32_e64 v69, v69, -v69, vcc
	v_fmac_f32_e32 v69, v64, v228
	v_cvt_pk_bf16_f32 v64, v69, s0
	global_store_short v[80:81], v64, off
	v_add_u32_e32 v72, 0x72, v139
	ds_bpermute_b32 v80, v152, v73
	v_min_i32_e32 v64, 0x403f, v72
	v_mul_hi_i32 v70, v64, s36
	v_lshrrev_b32_e32 v71, 31, v70
	v_ashrrev_i32_e32 v70, 11, v70
	v_add_u32_e32 v70, v70, v71
	v_mul_i32_i24_e32 v70, 0x1010, v70
	v_sub_u32_e32 v64, v64, v70
	v_lshl_or_b32 v64, v64, 4, v151
	v_ashrrev_i32_e32 v65, 31, v64
	v_lshl_add_u64 v[70:71], v[192:193], 1, s[56:57]
	v_lshl_add_u64 v[64:65], v[64:65], 3, s[74:75]
	v_lshl_or_b32 v192, v72, 5, v142
	s_waitcnt lgkmcnt(0)
	s_waitcnt vmcnt(26)
	v_mul_f32_e32 v69, v231, v80
	v_cndmask_b32_e64 v69, v69, -v69, vcc
	v_fmac_f32_e32 v69, v73, v230
	v_cvt_pk_bf16_f32 v68, v69, s0
	global_store_short v[70:71], v68, off
	v_add_u32_e32 v73, 0x73, v139
	v_min_i32_e32 v68, 0x403f, v73
	v_mul_hi_i32 v69, v68, s36
	v_lshrrev_b32_e32 v70, 31, v69
	v_ashrrev_i32_e32 v69, 11, v69
	v_add_u32_e32 v69, v69, v70
	v_mul_i32_i24_e32 v69, 0x1010, v69
	v_sub_u32_e32 v68, v68, v69
	v_lshl_or_b32 v68, v68, 4, v151
	v_ashrrev_i32_e32 v69, 31, v68
	v_lshl_add_u64 v[70:71], v[192:193], 1, s[56:57]
	v_lshl_add_u64 v[68:69], v[68:69], 3, s[74:75]
	v_lshl_or_b32 v192, v73, 5, v142
	s_waitcnt vmcnt(25)
	v_mul_f32_e32 v65, v233, v74
	v_cndmask_b32_e64 v65, v65, -v65, vcc
	v_fmac_f32_e32 v65, v66, v232
	v_cvt_pk_bf16_f32 v64, v65, s0
	global_store_short v[70:71], v64, off
	v_or_b32_e32 v70, 0x78, v138
	v_mul_f32_e32 v71, v75, v67
	v_add_u32_e32 v72, s18, v70
	ds_bpermute_b32 v74, v152, v71
	v_min_i32_e32 v66, 0x403f, v72
	v_mul_hi_i32 v68, v66, s36
	v_lshrrev_b32_e32 v69, 31, v68
	v_ashrrev_i32_e32 v68, 11, v68
	v_add_u32_e32 v68, v68, v69
	v_mul_i32_i24_e32 v68, 0x1010, v68
	v_sub_u32_e32 v66, v66, v68
	v_lshl_or_b32 v66, v66, 4, v151
	v_ashrrev_i32_e32 v67, 31, v66
	v_lshl_add_u64 v[68:69], v[192:193], 1, s[56:57]
	v_lshl_add_u64 v[66:67], v[66:67], 3, s[74:75]
	v_lshl_or_b32 v192, v72, 5, v142
	s_waitcnt lgkmcnt(0)
	s_waitcnt vmcnt(24)
	v_mul_f32_e32 v65, v235, v74
	v_cndmask_b32_e64 v65, v65, -v65, vcc
	v_fmac_f32_e32 v65, v71, v234
	v_cvt_pk_bf16_f32 v64, v65, s0
	global_store_short v[68:69], v64, off
	v_add_u32_e32 v74, 0x79, v139
	v_lshl_add_u32 v64, v70, 2, v200
	v_min_i32_e32 v70, 0x403f, v74
	v_mul_hi_i32 v65, v70, s36
	v_lshrrev_b32_e32 v71, 31, v65
	v_ashrrev_i32_e32 v73, 11, v65
	ds_read_b128 v[64:67], v64
	v_add_u32_e32 v71, v73, v71
	v_mul_i32_i24_e32 v71, 0x1010, v71
	v_sub_u32_e32 v70, v70, v71
	v_lshl_or_b32 v70, v70, 4, v151
	s_waitcnt lgkmcnt(0)
	v_mul_f32_e32 v64, v76, v64
	ds_bpermute_b32 v75, v152, v64
	v_ashrrev_i32_e32 v71, 31, v70
	v_lshl_add_u64 v[72:73], v[192:193], 1, s[56:57]
	v_lshl_add_u64 v[70:71], v[70:71], 3, s[74:75]
	v_lshl_or_b32 v192, v74, 5, v142
	v_mul_f32_e32 v66, v78, v66
	ds_bpermute_b32 v74, v152, v66
	s_waitcnt lgkmcnt(1)
	s_waitcnt vmcnt(23)
	v_mul_f32_e32 v69, v175, v75
	v_cndmask_b32_e64 v69, v69, -v69, vcc
	v_fmac_f32_e32 v69, v64, v174
	v_cvt_pk_bf16_f32 v64, v69, s0
	global_store_short v[72:73], v64, off
	v_mul_f32_e32 v73, v77, v65
	v_add_u32_e32 v72, 0x7a, v139
	ds_bpermute_b32 v75, v152, v73
	v_min_i32_e32 v64, 0x403f, v72
	v_mul_hi_i32 v70, v64, s36
	v_lshrrev_b32_e32 v71, 31, v70
	v_ashrrev_i32_e32 v70, 11, v70
	v_add_u32_e32 v70, v70, v71
	v_mul_i32_i24_e32 v70, 0x1010, v70
	v_sub_u32_e32 v64, v64, v70
	v_lshl_or_b32 v64, v64, 4, v151
	v_ashrrev_i32_e32 v65, 31, v64
	v_lshl_add_u64 v[70:71], v[192:193], 1, s[56:57]
	v_lshl_add_u64 v[64:65], v[64:65], 3, s[74:75]
	v_lshl_or_b32 v192, v72, 5, v142
	s_waitcnt lgkmcnt(0)
	s_waitcnt vmcnt(22)
	v_mul_f32_e32 v69, v177, v75
	v_cndmask_b32_e64 v69, v69, -v69, vcc
	v_fmac_f32_e32 v69, v73, v176
	v_cvt_pk_bf16_f32 v68, v69, s0
	global_store_short v[70:71], v68, off
	v_add_u32_e32 v73, 0x7b, v139
	v_min_i32_e32 v68, 0x403f, v73
	v_mul_hi_i32 v69, v68, s36
	v_lshrrev_b32_e32 v70, 31, v69
	v_ashrrev_i32_e32 v69, 11, v69
	v_add_u32_e32 v69, v69, v70
	v_mul_i32_i24_e32 v69, 0x1010, v69
	v_sub_u32_e32 v68, v68, v69
	v_lshl_or_b32 v68, v68, 4, v151
	v_ashrrev_i32_e32 v69, 31, v68
	v_lshl_add_u64 v[70:71], v[192:193], 1, s[56:57]
	v_lshl_add_u64 v[68:69], v[68:69], 3, s[74:75]
	v_lshl_or_b32 v192, v73, 5, v142
	s_waitcnt vmcnt(21)
	v_mul_f32_e32 v65, v179, v74
	v_cndmask_b32_e64 v65, v65, -v65, vcc
	v_fmac_f32_e32 v65, v66, v178
	v_cvt_pk_bf16_f32 v64, v65, s0
	global_store_short v[70:71], v64, off
	v_mul_f32_e32 v66, v79, v67
	ds_bpermute_b32 v67, v152, v66
	s_waitcnt lgkmcnt(0)
	s_waitcnt vmcnt(20)
	v_mul_f32_e32 v65, v181, v67
	v_cndmask_b32_e64 v65, v65, -v65, vcc
	v_fmac_f32_e32 v65, v66, v180
	v_cvt_pk_bf16_f32 v66, v65, s0
	v_lshl_add_u64 v[64:65], v[192:193], 1, s[56:57]
	global_store_short v[64:65], v66, off

.LBB0_3047:
	s_or_saveexec_b64 s[10:11], s[0:1]
	v_add_u32_e32 v130, s8, v133
	v_or_b32_e32 v130, v130, v143
	v_min_i32_e32 v130, 0x403f, v130
	v_mul_hi_i32 v131, v130, s25
	v_lshrrev_b32_e32 v133, 31, v131
	v_ashrrev_i32_e32 v131, 11, v131
	v_add_u32_e32 v131, v131, v133
	v_mul_i32_i24_e32 v131, 0x1010, v131
	v_sub_u32_e32 v162, v130, v131
	v_and_b32_e32 v143, 15, v132
	v_lshlrev_b32_e32 v163, 4, v162
	v_or_b32_e32 v130, v163, v143
	s_xor_b64 exec, exec, s[10:11]
	s_cbranch_execz .LBB0_3049
	s_waitcnt vmcnt(0)
	v_ashrrev_i32_e32 v131, 31, v130
	v_lshl_add_u64 v[132:133], v[130:131], 3, s[74:75]
	global_load_dwordx2 v[174:175], v[132:133], off
	v_cmp_lt_i32_e64 s[100:101],s27,v162
	s_nop 1
	v_cndmask_b32_e64 v237,16,v218,s[100:101]
	v_add_u32_e32 v240,v237,v163
	v_or_b32_e32 v240,v240,v143
	v_ashrrev_i32_e32 v241,31,v240
	v_lshl_add_u64 v[240:241],v[240:241],3,s[74:75]
	global_load_dwordx2 v[176:177], v[240:241], off
	v_mov_b32_e32 v237, v113
	v_cmp_lt_i32_e64 s[100:101],s28,v162
	s_nop 1
	v_cndmask_b32_e64 v236,32,v219,s[100:101]
	v_add_u32_e32 v241,v236,v163
	v_or_b32_e32 v242,v241,v143
	v_ashrrev_i32_e32 v243,31,v242
	v_lshl_add_u64 v[242:243],v[242:243],3,s[74:75]
	global_load_dwordx2 v[178:179], v[242:243], off
	v_cmp_lt_i32_e64 s[100:101],s29,v162
	s_nop 1
	v_cndmask_b32_e64 v237,48,v220,s[100:101]
	v_add_u32_e32 v237,v237,v163
	v_or_b32_e32 v240,v237,v143
	v_ashrrev_i32_e32 v241,31,v240
	v_lshl_add_u64 v[240:241],v[240:241],3,s[74:75]
	global_load_dwordx2 v[180:181], v[240:241], off
	v_cmp_lt_i32_e64 s[100:101],s30,v162
	s_nop 1
	v_cndmask_b32_e64 v236,8,v221,s[100:101]
	v_add_u32_e32 v241,v236,v162
	v_lshlrev_b32_e32 v242,4,v241
	v_add_u32_e32 v236,0xfffeff00,v242
	v_cmp_lt_i32_e64 s[100:101],s31,v241
	s_nop 1
	v_cndmask_b32_e64 v236,v242,v236,s[100:101]
	v_or_b32_e32 v236,v236,v143
	v_ashrrev_i32_e32 v237,31,v236
	v_lshl_add_u64 v[236:237],v[236:237],3,s[74:75]
	global_load_dwordx2 v[182:183], v[236:237], off
	v_cmp_lt_i32_e64 s[100:101],s30,v162
	s_nop 1
	v_cndmask_b32_e64 v236,8,v221,s[100:101]
	v_add_u32_e32 v241,v236,v162
	v_lshlrev_b32_e32 v242,4,v241
	v_cmp_lt_i32_e64 s[100:101],s27,v241
	s_nop 1
	v_cndmask_b32_e64 v244,16,v218,s[100:101]
	v_add_u32_e32 v244,v244,v242
	v_or_b32_e32 v244,v244,v143
	v_ashrrev_i32_e32 v245,31,v244
	v_lshl_add_u64 v[244:245],v[244:245],3,s[74:75]
	global_load_dwordx2 v[184:185], v[244:245], off
	v_cmp_lt_i32_e64 s[100:101],s30,v162
	s_nop 1
	v_cndmask_b32_e64 v236,8,v221,s[100:101]
	v_add_u32_e32 v241,v236,v162
	v_lshlrev_b32_e32 v242,4,v241
	v_cmp_lt_i32_e64 s[100:101],s28,v241
	s_nop 1
	v_cndmask_b32_e64 v236,32,v219,s[100:101]
	v_add_u32_e32 v236,v236,v242
	v_or_b32_e32 v236,v236,v143
	v_ashrrev_i32_e32 v237,31,v236
	v_lshl_add_u64 v[236:237],v[236:237],3,s[74:75]
	global_load_dwordx2 v[186:187], v[236:237], off
	v_mov_b32_e32 v237, v113
	v_cmp_lt_i32_e64 s[100:101],s30,v162
	s_nop 1
	v_cndmask_b32_e64 v236,8,v221,s[100:101]
	v_add_u32_e32 v241,v236,v162
	v_lshlrev_b32_e32 v242,4,v241
	v_cmp_lt_i32_e64 s[100:101],s29,v241
	s_nop 1
	v_cndmask_b32_e64 v244,48,v220,s[100:101]
	v_add_u32_e32 v244,v244,v242
	v_or_b32_e32 v244,v244,v143
	v_ashrrev_i32_e32 v245,31,v244
	v_lshl_add_u64 v[244:245],v[244:245],3,s[74:75]
	global_load_dwordx2 v[188:189], v[244:245], off
	v_cmp_lt_i32_e64 s[100:101],s30,v162
	s_nop 1
	v_cndmask_b32_e64 v236,8,v221,s[100:101]
	v_add_u32_e32 v241,v236,v162
	v_cmp_lt_i32_e64 s[100:101],s30,v241
	s_nop 1
	v_cndmask_b32_e64 v236,8,v221,s[100:101]
	v_add_u32_e32 v241,v236,v241
	v_lshlrev_b32_e32 v242,4,v241
	v_add_u32_e32 v236,0xfffeff00,v242
	v_cmp_lt_i32_e64 s[100:101],s31,v241
	s_nop 1
	v_cndmask_b32_e64 v236,v242,v236,s[100:101]
	v_or_b32_e32 v236,v236,v143
	v_ashrrev_i32_e32 v237,31,v236
	v_lshl_add_u64 v[236:237],v[236:237],3,s[74:75]
	global_load_dwordx2 v[190:191], v[236:237], off
	v_cmp_lt_i32_e64 s[100:101],s30,v162
	s_nop 1
	v_cndmask_b32_e64 v236,8,v221,s[100:101]
	v_add_u32_e32 v241,v236,v162
	v_cmp_lt_i32_e64 s[100:101],s30,v241
	s_nop 1
	v_cndmask_b32_e64 v236,8,v221,s[100:101]
	v_add_u32_e32 v241,v236,v241
	v_lshlrev_b32_e32 v242,4,v241
	v_cmp_lt_i32_e64 s[100:101],s27,v241
	s_nop 1
	v_cndmask_b32_e64 v244,16,v218,s[100:101]
	v_add_u32_e32 v244,v244,v242
	v_or_b32_e32 v244,v244,v143
	v_ashrrev_i32_e32 v245,31,v244
	v_lshl_add_u64 v[244:245],v[244:245],3,s[74:75]
	global_load_dwordx2 v[194:195], v[244:245], off
	v_cmp_lt_i32_e64 s[100:101],s30,v162
	s_nop 1
	v_cndmask_b32_e64 v236,8,v221,s[100:101]
	v_add_u32_e32 v241,v236,v162
	v_cmp_lt_i32_e64 s[100:101],s30,v241
	s_nop 1
	v_cndmask_b32_e64 v236,8,v221,s[100:101]
	v_add_u32_e32 v241,v236,v241
	v_lshlrev_b32_e32 v242,4,v241
	v_cmp_lt_i32_e64 s[100:101],s28,v241
	s_nop 1
	v_cndmask_b32_e64 v236,32,v219,s[100:101]
	v_add_u32_e32 v236,v236,v242
	v_or_b32_e32 v236,v236,v143
	v_ashrrev_i32_e32 v237,31,v236
	v_lshl_add_u64 v[236:237],v[236:237],3,s[74:75]
	global_load_dwordx2 v[196:197], v[236:237], off
	v_mov_b32_e32 v237, v113
	v_cmp_lt_i32_e64 s[100:101],s30,v162
	s_nop 1
	v_cndmask_b32_e64 v236,8,v221,s[100:101]
	v_add_u32_e32 v241,v236,v162
	v_cmp_lt_i32_e64 s[100:101],s30,v241
	s_nop 1
	v_cndmask_b32_e64 v236,8,v221,s[100:101]
	v_add_u32_e32 v241,v236,v241
	v_lshlrev_b32_e32 v242,4,v241
	v_cmp_lt_i32_e64 s[100:101],s29,v241
	s_nop 1
	v_cndmask_b32_e64 v244,48,v220,s[100:101]
	v_add_u32_e32 v244,v244,v242
	v_or_b32_e32 v244,v244,v143
	v_ashrrev_i32_e32 v245,31,v244
	v_lshl_add_u64 v[244:245],v[244:245],3,s[74:75]
	global_load_dwordx2 v[198:199], v[244:245], off
	v_cmp_lt_i32_e64 s[100:101],s30,v162
	s_nop 1
	v_cndmask_b32_e64 v236,8,v221,s[100:101]
	v_add_u32_e32 v241,v236,v162
	v_cmp_lt_i32_e64 s[100:101],s30,v241
	s_nop 1
	v_cndmask_b32_e64 v236,8,v221,s[100:101]
	v_add_u32_e32 v241,v236,v241
	v_cmp_lt_i32_e64 s[100:101],s30,v241
	s_nop 1
	v_cndmask_b32_e64 v236,8,v221,s[100:101]
	v_add_u32_e32 v242,v236,v241
	v_lshlrev_b32_e32 v243,4,v242
	v_add_u32_e32 v236,0xfffeff00,v243
	v_cmp_lt_i32_e64 s[100:101],s31,v242
	s_nop 1
	v_cndmask_b32_e64 v236,v243,v236,s[100:101]
	v_or_b32_e32 v236,v236,v143
	v_ashrrev_i32_e32 v237,31,v236
	v_lshl_add_u64 v[236:237],v[236:237],3,s[74:75]
	global_load_dwordx2 v[204:205], v[236:237], off
	v_cmp_lt_i32_e64 s[100:101],s30,v162
	s_nop 1
	v_cndmask_b32_e64 v236,8,v221,s[100:101]
	v_add_u32_e32 v241,v236,v162
	v_cmp_lt_i32_e64 s[100:101],s30,v241
	s_nop 1
	v_cndmask_b32_e64 v236,8,v221,s[100:101]
	v_add_u32_e32 v241,v236,v241
	v_cmp_lt_i32_e64 s[100:101],s30,v241
	s_nop 1
	v_cndmask_b32_e64 v236,8,v221,s[100:101]
	v_add_u32_e32 v242,v236,v241
	v_lshlrev_b32_e32 v243,4,v242
	v_cmp_lt_i32_e64 s[100:101],s27,v242
	s_nop 1
	v_cndmask_b32_e64 v244,16,v218,s[100:101]
	v_add_u32_e32 v244,v244,v243
	v_or_b32_e32 v244,v244,v143
	v_ashrrev_i32_e32 v245,31,v244
	v_lshl_add_u64 v[244:245],v[244:245],3,s[74:75]
	global_load_dwordx2 v[206:207], v[244:245], off
	v_cmp_lt_i32_e64 s[100:101],s30,v162
	s_nop 1
	v_cndmask_b32_e64 v236,8,v221,s[100:101]
	v_add_u32_e32 v241,v236,v162
	v_cmp_lt_i32_e64 s[100:101],s30,v241
	s_nop 1
	v_cndmask_b32_e64 v236,8,v221,s[100:101]
	v_add_u32_e32 v241,v236,v241
	v_cmp_lt_i32_e64 s[100:101],s30,v241
	s_nop 1
	v_cndmask_b32_e64 v236,8,v221,s[100:101]
	v_add_u32_e32 v242,v236,v241
	v_lshlrev_b32_e32 v243,4,v242
	v_cmp_lt_i32_e64 s[100:101],s28,v242
	s_nop 1
	v_cndmask_b32_e64 v236,32,v219,s[100:101]
	v_add_u32_e32 v236,v236,v243
	v_or_b32_e32 v236,v236,v143
	v_ashrrev_i32_e32 v237,31,v236
	v_lshl_add_u64 v[236:237],v[236:237],3,s[74:75]
	global_load_dwordx2 v[224:225], v[236:237], off
	v_mov_b32_e32 v237, v113
	v_cmp_lt_i32_e64 s[100:101],s30,v162
	s_nop 1
	v_cndmask_b32_e64 v236,8,v221,s[100:101]
	v_add_u32_e32 v241,v236,v162
	v_cmp_lt_i32_e64 s[100:101],s30,v241
	s_nop 1
	v_cndmask_b32_e64 v236,8,v221,s[100:101]
	v_add_u32_e32 v241,v236,v241
	v_cmp_lt_i32_e64 s[100:101],s30,v241
	s_nop 1
	v_cndmask_b32_e64 v236,8,v221,s[100:101]
	v_add_u32_e32 v242,v236,v241
	v_lshlrev_b32_e32 v243,4,v242
	v_cmp_lt_i32_e64 s[100:101],s29,v242
	s_nop 1
	v_cndmask_b32_e64 v244,48,v220,s[100:101]
	v_add_u32_e32 v244,v244,v243
	v_or_b32_e32 v244,v244,v143
	v_ashrrev_i32_e32 v245,31,v244
	v_lshl_add_u64 v[244:245],v[244:245],3,s[74:75]
	global_load_dwordx2 v[226:227], v[244:245], off
	v_cmp_lt_i32_e64 s[100:101],s33,v162
	s_nop 1
	v_cndmask_b32_e64 v236,32,v222,s[100:101]
	v_add_u32_e32 v236,v236,v162
	v_lshlrev_b32_e32 v237,4,v236
	v_add_u32_e32 v240,0xfffeff00,v237
	v_cmp_lt_i32_e64 s[100:101],s31,v236
	s_nop 1
	v_cndmask_b32_e64 v240,v237,v240,s[100:101]
	v_or_b32_e32 v240,v240,v143
	v_ashrrev_i32_e32 v241,31,v240
	v_lshl_add_u64 v[240:241],v[240:241],3,s[74:75]
	global_load_dwordx2 v[228:229], v[240:241], off
	v_cmp_lt_i32_e64 s[100:101],s33,v162
	s_nop 1
	v_cndmask_b32_e64 v236,32,v222,s[100:101]
	v_add_u32_e32 v236,v236,v162
	v_lshlrev_b32_e32 v237,4,v236
	v_cmp_lt_i32_e64 s[100:101],s27,v236
	s_nop 1
	v_cndmask_b32_e64 v240,16,v218,s[100:101]
	v_add_u32_e32 v240,v240,v237
	v_or_b32_e32 v240,v240,v143
	v_ashrrev_i32_e32 v241,31,v240
	v_lshl_add_u64 v[240:241],v[240:241],3,s[74:75]
	global_load_dwordx2 v[230:231], v[240:241], off
	v_cmp_lt_i32_e64 s[100:101],s33,v162
	s_nop 1
	v_cndmask_b32_e64 v236,32,v222,s[100:101]
	v_add_u32_e32 v236,v236,v162
	v_lshlrev_b32_e32 v237,4,v236
	v_cmp_lt_i32_e64 s[100:101],s28,v236
	s_nop 1
	v_cndmask_b32_e64 v240,32,v219,s[100:101]
	v_add_u32_e32 v240,v240,v237
	v_or_b32_e32 v240,v240,v143
	v_ashrrev_i32_e32 v241,31,v240
	v_lshl_add_u64 v[240:241],v[240:241],3,s[74:75]
	global_load_dwordx2 v[232:233], v[240:241], off
	v_cmp_lt_i32_e64 s[100:101],s33,v162
	s_nop 1
	v_cndmask_b32_e64 v236,32,v222,s[100:101]
	v_add_u32_e32 v236,v236,v162
	v_lshlrev_b32_e32 v237,4,v236
	v_cmp_lt_i32_e64 s[100:101],s29,v236
	s_nop 1
	v_cndmask_b32_e64 v240,48,v220,s[100:101]
	v_add_u32_e32 v237,v240,v237
	v_or_b32_e32 v240,v237,v143
	v_ashrrev_i32_e32 v241,31,v240
	v_lshl_add_u64 v[240:241],v[240:241],3,s[74:75]
	global_load_dwordx2 v[234:235], v[240:241], off
	ds_read_b128 v[164:167], v159
	v_and_b32_e32 v170, 64, v217
	v_mad_u64_u32 v[132:133], s[0:1], v158, s26, v[128:129]
	v_xor_b32_e32 v131, 16, v217
	v_cmp_lt_i32_e64 s[0:1], s27, v162
	v_add_u32_e32 v170, 64, v170
	s_waitcnt lgkmcnt(0)
	v_mul_f32_e32 v112, v112, v164
	v_cndmask_b32_e64 v171, 16, v218, s[0:1]
	v_cmp_lt_i32_e64 s[0:1], v131, v170
	v_mov_b32_e32 v133, v193
	v_add_u32_e32 v172, v171, v163
	v_cndmask_b32_e64 v131, v217, v131, s[0:1]
	v_lshlrev_b32_e32 v131, 2, v131
	ds_bpermute_b32 v164, v131, v112
	v_lshl_add_u64 v[170:171], v[132:133], 1, s[4:5]
	v_or_b32_e32 v172, v172, v143
	v_ashrrev_i32_e32 v173, 31, v172
	v_lshl_add_u64 v[172:173], v[172:173], 3, s[74:75]
	v_add_u32_e32 v192, 0x300, v132
	v_mul_f32_e32 v114, v114, v166
	ds_bpermute_b32 v166, v131, v114
	s_waitcnt lgkmcnt(1)
	s_waitcnt vmcnt(19)
	v_mul_f32_e32 v133, v175, v164
	v_cndmask_b32_e64 v133, v133, -v133, vcc
	v_fmac_f32_e32 v133, v112, v174
	v_cmp_lt_i32_e64 s[100:101],s33,v162
	s_nop 1
	v_cndmask_b32_e64 v236,32,v222,s[100:101]
	v_add_u32_e32 v236,v236,v162
	v_cmp_lt_i32_e64 s[100:101],s30,v236
	s_nop 1
	v_cndmask_b32_e64 v240,8,v221,s[100:101]
	v_add_u32_e32 v237,v240,v236
	v_lshlrev_b32_e32 v242,4,v237
	v_add_u32_e32 v240,0xfffeff00,v242
	v_cmp_lt_i32_e64 s[100:101],s31,v237
	s_nop 1
	v_cndmask_b32_e64 v240,v242,v240,s[100:101]
	v_or_b32_e32 v240,v240,v143
	v_ashrrev_i32_e32 v241,31,v240
	v_lshl_add_u64 v[240:241],v[240:241],3,s[74:75]
	global_load_dwordx2 v[174:175], v[240:241], off
	v_mul_f32_e32 v112, 0x3e16c740, v133
	v_cvt_pk_bf16_f32 v112, v112, s0
	global_store_short v[170:171], v112, off
	v_mul_f32_e32 v170, v113, v165
	ds_bpermute_b32 v171, v131, v170
	v_cmp_lt_i32_e64 s[0:1], s28, v162
	s_nop 1
	v_cndmask_b32_e64 v112, 32, v219, s[0:1]
	v_add_u32_e32 v133, v112, v163
	v_or_b32_e32 v164, v133, v143
	v_lshl_add_u64 v[112:113], v[192:193], 1, s[4:5]
	v_ashrrev_i32_e32 v165, 31, v164
	v_lshl_add_u64 v[164:165], v[164:165], 3, s[74:75]
	v_add_u32_e32 v192, 0x600, v132
	s_waitcnt lgkmcnt(0)
	s_waitcnt vmcnt(20)
	v_mul_f32_e32 v133, v177, v171
	v_cndmask_b32_e64 v133, v133, -v133, vcc
	v_fmac_f32_e32 v133, v170, v176
	v_cmp_lt_i32_e64 s[100:101],s33,v162
	s_nop 1
	v_cndmask_b32_e64 v236,32,v222,s[100:101]
	v_add_u32_e32 v236,v236,v162
	v_cmp_lt_i32_e64 s[100:101],s30,v236
	s_nop 1
	v_cndmask_b32_e64 v240,8,v221,s[100:101]
	v_add_u32_e32 v237,v240,v236
	v_lshlrev_b32_e32 v242,4,v237
	v_cmp_lt_i32_e64 s[100:101],s27,v237
	s_nop 1
	v_cndmask_b32_e64 v244,16,v218,s[100:101]
	v_add_u32_e32 v244,v244,v242
	v_or_b32_e32 v244,v244,v143
	v_ashrrev_i32_e32 v245,31,v244
	v_lshl_add_u64 v[244:245],v[244:245],3,s[74:75]
	global_load_dwordx2 v[176:177], v[244:245], off
	v_mul_f32_e32 v133, 0x3e16c740, v133
	v_cvt_pk_bf16_f32 v133, v133, s0
	global_store_short v[112:113], v133, off
	v_cmp_lt_i32_e64 s[0:1], s29, v162
	v_lshl_add_u64 v[168:169], v[192:193], 1, s[4:5]
	v_add_u32_e32 v192, 0x900, v132
	v_cndmask_b32_e64 v133, 48, v220, s[0:1]
	v_add_u32_e32 v133, v133, v163
	v_or_b32_e32 v164, v133, v143
	v_ashrrev_i32_e32 v165, 31, v164
	v_lshl_add_u64 v[164:165], v[164:165], 3, s[74:75]
	s_waitcnt vmcnt(21)
	v_mul_f32_e32 v113, v179, v166
	v_cndmask_b32_e64 v113, v113, -v113, vcc
	v_fmac_f32_e32 v113, v114, v178
	v_cmp_lt_i32_e64 s[100:101],s33,v162
	s_nop 1
	v_cndmask_b32_e64 v236,32,v222,s[100:101]
	v_add_u32_e32 v236,v236,v162
	v_cmp_lt_i32_e64 s[100:101],s30,v236
	s_nop 1
	v_cndmask_b32_e64 v240,8,v221,s[100:101]
	v_add_u32_e32 v237,v240,v236
	v_lshlrev_b32_e32 v242,4,v237
	v_cmp_lt_i32_e64 s[100:101],s28,v237
	s_nop 1
	v_cndmask_b32_e64 v240,32,v219,s[100:101]
	v_add_u32_e32 v240,v240,v242
	v_or_b32_e32 v240,v240,v143
	v_ashrrev_i32_e32 v241,31,v240
	v_lshl_add_u64 v[240:241],v[240:241],3,s[74:75]
	global_load_dwordx2 v[178:179], v[240:241], off
	v_mul_f32_e32 v112, 0x3e16c740, v113
	v_cvt_pk_bf16_f32 v112, v112, s0
	global_store_short v[168:169], v112, off
	v_mul_f32_e32 v114, v115, v167
	ds_bpermute_b32 v115, v131, v114
	s_waitcnt lgkmcnt(0)
	s_waitcnt vmcnt(22)
	v_mul_f32_e32 v113, v181, v115
	v_cndmask_b32_e64 v113, v113, -v113, vcc
	v_fmac_f32_e32 v113, v114, v180
	v_mov_b32_e32 v241, v97
	v_cmp_lt_i32_e64 s[100:101],s33,v162
	s_nop 1
	v_cndmask_b32_e64 v236,32,v222,s[100:101]
	v_add_u32_e32 v236,v236,v162
	v_cmp_lt_i32_e64 s[100:101],s30,v236
	s_nop 1
	v_cndmask_b32_e64 v240,8,v221,s[100:101]
	v_add_u32_e32 v237,v240,v236
	v_lshlrev_b32_e32 v242,4,v237
	v_cmp_lt_i32_e64 s[100:101],s29,v237
	s_nop 1
	v_cndmask_b32_e64 v244,48,v220,s[100:101]
	v_add_u32_e32 v244,v244,v242
	v_or_b32_e32 v244,v244,v143
	v_ashrrev_i32_e32 v245,31,v244
	v_lshl_add_u64 v[244:245],v[244:245],3,s[74:75]
	global_load_dwordx2 v[180:181], v[244:245], off
	v_mul_f32_e32 v112, 0x3e16c740, v113
	v_cvt_pk_bf16_f32 v114, v112, s0
	v_lshl_add_u64 v[112:113], v[192:193], 1, s[4:5]
	global_store_short v[112:113], v114, off
	v_cmp_lt_i32_e64 s[0:1], s30, v162
	v_add_u32_e32 v192, 0x1b00, v132
	s_nop 0
	v_cndmask_b32_e64 v112, 8, v221, s[0:1]
	v_add_u32_e32 v133, v112, v162
	v_lshlrev_b32_e32 v170, 4, v133
	v_add_u32_e32 v112, 0xfffeff00, v170
	v_cmp_lt_i32_e64 s[0:1], s31, v133
	s_nop 1
	v_cndmask_b32_e64 v112, v170, v112, s[0:1]
	v_or_b32_e32 v112, v112, v143
	v_ashrrev_i32_e32 v113, 31, v112
	v_lshl_add_u64 v[112:113], v[112:113], 3, s[74:75]
	ds_read_b128 v[112:115], v157
	v_mad_u64_u32 v[166:167], s[0:1], v156, s26, v[128:129]
	v_cmp_lt_i32_e64 s[0:1], s27, v133
	v_mov_b32_e32 v167, v193
	s_waitcnt lgkmcnt(0)
	v_mul_f32_e32 v112, v116, v112
	ds_bpermute_b32 v116, v131, v112
	v_cndmask_b32_e64 v168, 16, v218, s[0:1]
	v_add_u32_e32 v168, v168, v170
	v_or_b32_e32 v168, v168, v143
	v_lshl_add_u64 v[166:167], v[166:167], 1, s[4:5]
	v_ashrrev_i32_e32 v169, 31, v168
	v_lshl_add_u64 v[168:169], v[168:169], 3, s[74:75]
	v_mul_f32_e32 v114, v118, v114
	ds_bpermute_b32 v118, v131, v114
	s_waitcnt lgkmcnt(1)
	s_waitcnt vmcnt(23)
	v_mul_f32_e32 v116, v183, v116
	v_cndmask_b32_e64 v116, v116, -v116, vcc
	v_fmac_f32_e32 v116, v112, v182
	v_cmp_lt_i32_e64 s[100:101],s33,v162
	s_nop 1
	v_cndmask_b32_e64 v236,32,v222,s[100:101]
	v_add_u32_e32 v236,v236,v162
	v_cmp_lt_i32_e64 s[100:101],s30,v236
	s_nop 1
	v_cndmask_b32_e64 v240,8,v221,s[100:101]
	v_add_u32_e32 v237,v240,v236
	v_cmp_lt_i32_e64 s[100:101],s30,v237
	s_nop 1
	v_cndmask_b32_e64 v240,8,v221,s[100:101]
	v_add_u32_e32 v237,v240,v237
	v_lshlrev_b32_e32 v242,4,v237
	v_add_u32_e32 v240,0xfffeff00,v242
	v_cmp_lt_i32_e64 s[100:101],s31,v237
	s_nop 1
	v_cndmask_b32_e64 v240,v242,v240,s[100:101]
	v_or_b32_e32 v240,v240,v143
	v_ashrrev_i32_e32 v241,31,v240
	v_lshl_add_u64 v[240:241],v[240:241],3,s[74:75]
	global_load_dwordx2 v[182:183], v[240:241], off
	v_mul_f32_e32 v112, 0x3e16c740, v116
	v_cvt_pk_bf16_f32 v112, v112, s0
	global_store_short v[166:167], v112, off
	v_mul_f32_e32 v116, v117, v113
	ds_bpermute_b32 v117, v131, v116
	v_cmp_lt_i32_e64 s[0:1], s28, v133
	v_lshl_add_u64 v[166:167], v[192:193], 1, s[4:5]
	v_add_u32_e32 v192, 0x1e00, v132
	v_cndmask_b32_e64 v112, 32, v219, s[0:1]
	v_add_u32_e32 v112, v112, v170
	v_or_b32_e32 v112, v112, v143
	v_ashrrev_i32_e32 v113, 31, v112
	v_lshl_add_u64 v[112:113], v[112:113], 3, s[74:75]
	s_waitcnt lgkmcnt(0)
	s_waitcnt vmcnt(24)
	v_mul_f32_e32 v117, v185, v117
	v_cndmask_b32_e64 v117, v117, -v117, vcc
	v_fmac_f32_e32 v117, v116, v184
	v_cmp_lt_i32_e64 s[100:101],s33,v162
	s_nop 1
	v_cndmask_b32_e64 v236,32,v222,s[100:101]
	v_add_u32_e32 v236,v236,v162
	v_cmp_lt_i32_e64 s[100:101],s30,v236
	s_nop 1
	v_cndmask_b32_e64 v240,8,v221,s[100:101]
	v_add_u32_e32 v237,v240,v236
	v_cmp_lt_i32_e64 s[100:101],s30,v237
	s_nop 1
	v_cndmask_b32_e64 v240,8,v221,s[100:101]
	v_add_u32_e32 v237,v240,v237
	v_lshlrev_b32_e32 v242,4,v237
	v_cmp_lt_i32_e64 s[100:101],s27,v237
	s_nop 1
	v_cndmask_b32_e64 v244,16,v218,s[100:101]
	v_add_u32_e32 v244,v244,v242
	v_or_b32_e32 v244,v244,v143
	v_ashrrev_i32_e32 v245,31,v244
	v_lshl_add_u64 v[244:245],v[244:245],3,s[74:75]
	global_load_dwordx2 v[184:185], v[244:245], off
	v_mul_f32_e32 v116, 0x3e16c740, v117
	v_cvt_pk_bf16_f32 v116, v116, s0
	global_store_short v[166:167], v116, off
	v_cmp_lt_i32_e64 s[0:1], s29, v133
	v_lshl_add_u64 v[116:117], v[192:193], 1, s[4:5]
	v_add_u32_e32 v192, 0x2100, v132
	v_cndmask_b32_e64 v164, 48, v220, s[0:1]
	v_add_u32_e32 v164, v164, v170
	v_or_b32_e32 v164, v164, v143
	v_ashrrev_i32_e32 v165, 31, v164
	v_lshl_add_u64 v[164:165], v[164:165], 3, s[74:75]
	s_waitcnt vmcnt(25)
	v_mul_f32_e32 v113, v187, v118
	v_cndmask_b32_e64 v113, v113, -v113, vcc
	v_fmac_f32_e32 v113, v114, v186
	v_cmp_lt_i32_e64 s[100:101],s33,v162
	s_nop 1
	v_cndmask_b32_e64 v236,32,v222,s[100:101]
	v_add_u32_e32 v236,v236,v162
	v_cmp_lt_i32_e64 s[100:101],s30,v236
	s_nop 1
	v_cndmask_b32_e64 v240,8,v221,s[100:101]
	v_add_u32_e32 v237,v240,v236
	v_cmp_lt_i32_e64 s[100:101],s30,v237
	s_nop 1
	v_cndmask_b32_e64 v240,8,v221,s[100:101]
	v_add_u32_e32 v237,v240,v237
	v_lshlrev_b32_e32 v242,4,v237
	v_cmp_lt_i32_e64 s[100:101],s28,v237
	s_nop 1
	v_cndmask_b32_e64 v240,32,v219,s[100:101]
	v_add_u32_e32 v240,v240,v242
	v_or_b32_e32 v240,v240,v143
	v_ashrrev_i32_e32 v241,31,v240
	v_lshl_add_u64 v[240:241],v[240:241],3,s[74:75]
	global_load_dwordx2 v[186:187], v[240:241], off
	v_mul_f32_e32 v112, 0x3e16c740, v113
	v_cvt_pk_bf16_f32 v112, v112, s0
	global_store_short v[116:117], v112, off
	v_mul_f32_e32 v114, v119, v115
	ds_bpermute_b32 v115, v131, v114
	s_waitcnt lgkmcnt(0)
	s_waitcnt vmcnt(26)
	v_mul_f32_e32 v113, v189, v115
	v_cndmask_b32_e64 v113, v113, -v113, vcc
	v_fmac_f32_e32 v113, v114, v188
	v_mov_b32_e32 v241, v97
	v_cmp_lt_i32_e64 s[100:101],s33,v162
	s_nop 1
	v_cndmask_b32_e64 v236,32,v222,s[100:101]
	v_add_u32_e32 v236,v236,v162
	v_cmp_lt_i32_e64 s[100:101],s30,v236
	s_nop 1
	v_cndmask_b32_e64 v240,8,v221,s[100:101]
	v_add_u32_e32 v237,v240,v236
	v_cmp_lt_i32_e64 s[100:101],s30,v237
	s_nop 1
	v_cndmask_b32_e64 v240,8,v221,s[100:101]
	v_add_u32_e32 v237,v240,v237
	v_lshlrev_b32_e32 v242,4,v237
	v_cmp_lt_i32_e64 s[100:101],s29,v237
	s_nop 1
	v_cndmask_b32_e64 v244,48,v220,s[100:101]
	v_add_u32_e32 v244,v244,v242
	v_or_b32_e32 v244,v244,v143
	v_ashrrev_i32_e32 v245,31,v244
	v_lshl_add_u64 v[244:245],v[244:245],3,s[74:75]
	global_load_dwordx2 v[188:189], v[244:245], off
	v_mul_f32_e32 v112, 0x3e16c740, v113
	v_cvt_pk_bf16_f32 v114, v112, s0
	v_lshl_add_u64 v[112:113], v[192:193], 1, s[4:5]
	global_store_short v[112:113], v114, off
	v_cmp_lt_i32_e64 s[0:1], s30, v133
	v_add_u32_e32 v192, 0x3300, v132
	s_nop 0
	v_cndmask_b32_e64 v112, 8, v221, s[0:1]
	v_add_u32_e32 v133, v112, v133
	v_lshlrev_b32_e32 v166, 4, v133
	v_add_u32_e32 v112, 0xfffeff00, v166
	v_cmp_lt_i32_e64 s[0:1], s31, v133
	s_nop 1
	v_cndmask_b32_e64 v112, v166, v112, s[0:1]
	v_or_b32_e32 v112, v112, v143
	v_ashrrev_i32_e32 v113, 31, v112
	v_lshl_add_u64 v[112:113], v[112:113], 3, s[74:75]
	ds_read_b128 v[112:115], v155
	v_mad_u64_u32 v[118:119], s[0:1], v154, s26, v[128:129]
	v_cmp_lt_i32_e64 s[0:1], s27, v133
	v_mov_b32_e32 v119, v193
	s_waitcnt lgkmcnt(0)
	v_mul_f32_e32 v112, v120, v112
	ds_bpermute_b32 v120, v131, v112
	v_cndmask_b32_e64 v164, 16, v218, s[0:1]
	v_add_u32_e32 v164, v164, v166
	v_or_b32_e32 v164, v164, v143
	v_lshl_add_u64 v[118:119], v[118:119], 1, s[4:5]
	v_ashrrev_i32_e32 v165, 31, v164
	v_lshl_add_u64 v[164:165], v[164:165], 3, s[74:75]
	v_mul_f32_e32 v114, v122, v114
	s_waitcnt lgkmcnt(0)
	s_waitcnt vmcnt(27)
	v_mul_f32_e32 v117, v191, v120
	v_cndmask_b32_e64 v117, v117, -v117, vcc
	v_fmac_f32_e32 v117, v112, v190
	v_cmp_lt_i32_e64 s[100:101],s33,v162
	s_nop 1
	v_cndmask_b32_e64 v236,32,v222,s[100:101]
	v_add_u32_e32 v236,v236,v162
	v_cmp_lt_i32_e64 s[100:101],s30,v236
	s_nop 1
	v_cndmask_b32_e64 v240,8,v221,s[100:101]
	v_add_u32_e32 v237,v240,v236
	v_cmp_lt_i32_e64 s[100:101],s30,v237
	s_nop 1
	v_cndmask_b32_e64 v240,8,v221,s[100:101]
	v_add_u32_e32 v237,v240,v237
	v_cmp_lt_i32_e64 s[100:101],s30,v237
	s_nop 1
	v_cndmask_b32_e64 v240,8,v221,s[100:101]
	v_add_u32_e32 v242,v240,v237
	v_lshlrev_b32_e32 v243,4,v242
	v_add_u32_e32 v240,0xfffeff00,v243
	v_cmp_lt_i32_e64 s[100:101],s31,v242
	s_nop 1
	v_cndmask_b32_e64 v240,v243,v240,s[100:101]
	v_or_b32_e32 v240,v240,v143
	v_ashrrev_i32_e32 v241,31,v240
	v_lshl_add_u64 v[240:241],v[240:241],3,s[74:75]
	global_load_dwordx2 v[190:191], v[240:241], off
	v_mul_f32_e32 v112, 0x3e16c740, v117
	v_cvt_pk_bf16_f32 v112, v112, s0
	global_store_short v[118:119], v112, off
	v_mul_f32_e32 v120, v121, v113
	ds_bpermute_b32 v121, v131, v120
	v_cmp_lt_i32_e64 s[0:1], s28, v133
	v_lshl_add_u64 v[118:119], v[192:193], 1, s[4:5]
	v_add_u32_e32 v192, 0x3600, v132
	v_cndmask_b32_e64 v112, 32, v219, s[0:1]
	v_add_u32_e32 v112, v112, v166
	v_or_b32_e32 v112, v112, v143
	v_ashrrev_i32_e32 v113, 31, v112
	v_lshl_add_u64 v[112:113], v[112:113], 3, s[74:75]
	s_waitcnt lgkmcnt(0)
	s_waitcnt vmcnt(28)
	v_mul_f32_e32 v117, v195, v121
	v_cndmask_b32_e64 v117, v117, -v117, vcc
	v_fmac_f32_e32 v117, v120, v194
	v_cmp_lt_i32_e64 s[100:101],s33,v162
	s_nop 1
	v_cndmask_b32_e64 v236,32,v222,s[100:101]
	v_add_u32_e32 v236,v236,v162
	v_cmp_lt_i32_e64 s[100:101],s30,v236
	s_nop 1
	v_cndmask_b32_e64 v240,8,v221,s[100:101]
	v_add_u32_e32 v237,v240,v236
	v_cmp_lt_i32_e64 s[100:101],s30,v237
	s_nop 1
	v_cndmask_b32_e64 v240,8,v221,s[100:101]
	v_add_u32_e32 v237,v240,v237
	v_cmp_lt_i32_e64 s[100:101],s30,v237
	s_nop 1
	v_cndmask_b32_e64 v240,8,v221,s[100:101]
	v_add_u32_e32 v242,v240,v237
	v_lshlrev_b32_e32 v243,4,v242
	v_cmp_lt_i32_e64 s[100:101],s27,v242
	s_nop 1
	v_cndmask_b32_e64 v244,16,v218,s[100:101]
	v_add_u32_e32 v244,v244,v243
	v_or_b32_e32 v244,v244,v143
	v_ashrrev_i32_e32 v245,31,v244
	v_lshl_add_u64 v[244:245],v[244:245],3,s[74:75]
	global_load_dwordx2 v[194:195], v[244:245], off
	v_mul_f32_e32 v116, 0x3e16c740, v117
	v_cvt_pk_bf16_f32 v116, v116, s0
	global_store_short v[118:119], v116, off
	ds_bpermute_b32 v120, v131, v114
	v_cmp_lt_i32_e64 s[0:1], s29, v133
	v_lshl_add_u64 v[116:117], v[192:193], 1, s[4:5]
	v_add_u32_e32 v192, 0x3900, v132
	v_cndmask_b32_e64 v118, 48, v220, s[0:1]
	v_add_u32_e32 v118, v118, v166
	v_or_b32_e32 v118, v118, v143
	v_ashrrev_i32_e32 v119, 31, v118
	v_lshl_add_u64 v[118:119], v[118:119], 3, s[74:75]
	s_waitcnt lgkmcnt(0)
	s_waitcnt vmcnt(29)
	v_mul_f32_e32 v113, v197, v120
	v_cndmask_b32_e64 v113, v113, -v113, vcc
	v_fmac_f32_e32 v113, v114, v196
	v_cmp_lt_i32_e64 s[100:101],s33,v162
	s_nop 1
	v_cndmask_b32_e64 v236,32,v222,s[100:101]
	v_add_u32_e32 v236,v236,v162
	v_cmp_lt_i32_e64 s[100:101],s30,v236
	s_nop 1
	v_cndmask_b32_e64 v240,8,v221,s[100:101]
	v_add_u32_e32 v237,v240,v236
	v_cmp_lt_i32_e64 s[100:101],s30,v237
	s_nop 1
	v_cndmask_b32_e64 v240,8,v221,s[100:101]
	v_add_u32_e32 v237,v240,v237
	v_cmp_lt_i32_e64 s[100:101],s30,v237
	s_nop 1
	v_cndmask_b32_e64 v240,8,v221,s[100:101]
	v_add_u32_e32 v242,v240,v237
	v_lshlrev_b32_e32 v243,4,v242
	v_cmp_lt_i32_e64 s[100:101],s28,v242
	s_nop 1
	v_cndmask_b32_e64 v240,32,v219,s[100:101]
	v_add_u32_e32 v240,v240,v243
	v_or_b32_e32 v240,v240,v143
	v_ashrrev_i32_e32 v241,31,v240
	v_lshl_add_u64 v[240:241],v[240:241],3,s[74:75]
	global_load_dwordx2 v[196:197], v[240:241], off
	v_mul_f32_e32 v112, 0x3e16c740, v113
	v_cvt_pk_bf16_f32 v112, v112, s0
	global_store_short v[116:117], v112, off
	v_mul_f32_e32 v114, v123, v115
	ds_bpermute_b32 v115, v131, v114
	s_waitcnt lgkmcnt(0)
	s_waitcnt vmcnt(30)
	v_mul_f32_e32 v113, v199, v115
	v_cndmask_b32_e64 v113, v113, -v113, vcc
	v_fmac_f32_e32 v113, v114, v198
	v_mov_b32_e32 v241, v97
	v_cmp_lt_i32_e64 s[100:101],s33,v162
	s_nop 1
	v_cndmask_b32_e64 v236,32,v222,s[100:101]
	v_add_u32_e32 v236,v236,v162
	v_cmp_lt_i32_e64 s[100:101],s30,v236
	s_nop 1
	v_cndmask_b32_e64 v240,8,v221,s[100:101]
	v_add_u32_e32 v237,v240,v236
	v_cmp_lt_i32_e64 s[100:101],s30,v237
	s_nop 1
	v_cndmask_b32_e64 v240,8,v221,s[100:101]
	v_add_u32_e32 v237,v240,v237
	v_cmp_lt_i32_e64 s[100:101],s30,v237
	s_nop 1
	v_cndmask_b32_e64 v240,8,v221,s[100:101]
	v_add_u32_e32 v242,v240,v237
	v_lshlrev_b32_e32 v243,4,v242
	v_cmp_lt_i32_e64 s[100:101],s29,v242
	s_nop 1
	v_cndmask_b32_e64 v244,48,v220,s[100:101]
	v_add_u32_e32 v244,v244,v243
	v_or_b32_e32 v244,v244,v143
	v_ashrrev_i32_e32 v245,31,v244
	v_lshl_add_u64 v[244:245],v[244:245],3,s[74:75]
	global_load_dwordx2 v[198:199], v[244:245], off
	v_mul_f32_e32 v112, 0x3e16c740, v113
	v_cvt_pk_bf16_f32 v114, v112, s0
	v_lshl_add_u64 v[112:113], v[192:193], 1, s[4:5]
	global_store_short v[112:113], v114, off
	v_cmp_lt_i32_e64 s[0:1], s30, v133
	v_add_u32_e32 v192, 0x4b00, v132
	s_nop 0
	v_cndmask_b32_e64 v112, 8, v221, s[0:1]
	v_add_u32_e32 v122, v112, v133
	v_lshlrev_b32_e32 v123, 4, v122
	v_add_u32_e32 v112, 0xfffeff00, v123
	v_cmp_lt_i32_e64 s[0:1], s31, v122
	s_nop 1
	v_cndmask_b32_e64 v112, v123, v112, s[0:1]
	v_or_b32_e32 v112, v112, v143
	v_ashrrev_i32_e32 v113, 31, v112
	v_lshl_add_u64 v[112:113], v[112:113], 3, s[74:75]
	ds_read_b128 v[112:115], v153
	v_mad_u64_u32 v[118:119], s[0:1], v152, s26, v[128:129]
	v_cmp_lt_i32_e64 s[0:1], s27, v122
	v_mov_b32_e32 v119, v193
	s_waitcnt lgkmcnt(0)
	v_mul_f32_e32 v112, v124, v112
	ds_bpermute_b32 v124, v131, v112
	v_cndmask_b32_e64 v120, 16, v218, s[0:1]
	v_add_u32_e32 v120, v120, v123
	v_or_b32_e32 v120, v120, v143
	v_lshl_add_u64 v[118:119], v[118:119], 1, s[4:5]
	v_ashrrev_i32_e32 v121, 31, v120
	v_lshl_add_u64 v[120:121], v[120:121], 3, s[74:75]
	v_mul_f32_e32 v114, v126, v114
	s_waitcnt lgkmcnt(0)
	s_waitcnt vmcnt(31)
	v_mul_f32_e32 v117, v205, v124
	v_cndmask_b32_e64 v117, v117, -v117, vcc
	v_fmac_f32_e32 v117, v112, v204
	v_cmp_lt_i32_e64 s[100:101],s33,v162
	s_nop 1
	v_cndmask_b32_e64 v236,32,v222,s[100:101]
	v_add_u32_e32 v236,v236,v162
	v_cmp_lt_i32_e64 s[100:101],s33,v236
	s_nop 1
	v_cndmask_b32_e64 v240,32,v222,s[100:101]
	v_add_u32_e32 v240,v240,v236
	v_lshlrev_b32_e32 v241,4,v240
	v_add_u32_e32 v242,0xfffeff00,v241
	v_cmp_lt_i32_e64 s[100:101],s31,v240
	s_nop 1
	v_cndmask_b32_e64 v242,v241,v242,s[100:101]
	v_or_b32_e32 v242,v242,v143
	v_ashrrev_i32_e32 v243,31,v242
	v_lshl_add_u64 v[242:243],v[242:243],3,s[74:75]
	global_load_dwordx2 v[204:205], v[242:243], off
	v_mul_f32_e32 v112, 0x3e16c740, v117
	v_cvt_pk_bf16_f32 v112, v112, s0
	global_store_short v[118:119], v112, off
	v_mul_f32_e32 v120, v125, v113
	ds_bpermute_b32 v121, v131, v120
	v_cmp_lt_i32_e64 s[0:1], s28, v122
	v_lshl_add_u64 v[118:119], v[192:193], 1, s[4:5]
	v_add_u32_e32 v192, 0x4e00, v132
	v_cndmask_b32_e64 v112, 32, v219, s[0:1]
	v_add_u32_e32 v112, v112, v123
	v_or_b32_e32 v112, v112, v143
	v_ashrrev_i32_e32 v113, 31, v112
	v_lshl_add_u64 v[112:113], v[112:113], 3, s[74:75]
	s_waitcnt lgkmcnt(0)
	s_waitcnt vmcnt(32)
	v_mul_f32_e32 v117, v207, v121
	v_cndmask_b32_e64 v117, v117, -v117, vcc
	v_fmac_f32_e32 v117, v120, v206
	v_cmp_lt_i32_e64 s[100:101],s33,v162
	s_nop 1
	v_cndmask_b32_e64 v236,32,v222,s[100:101]
	v_add_u32_e32 v236,v236,v162
	v_cmp_lt_i32_e64 s[100:101],s33,v236
	s_nop 1
	v_cndmask_b32_e64 v240,32,v222,s[100:101]
	v_add_u32_e32 v240,v240,v236
	v_lshlrev_b32_e32 v241,4,v240
	v_cmp_lt_i32_e64 s[100:101],s27,v240
	s_nop 1
	v_cndmask_b32_e64 v242,16,v218,s[100:101]
	v_add_u32_e32 v242,v242,v241
	v_or_b32_e32 v242,v242,v143
	v_ashrrev_i32_e32 v243,31,v242
	v_lshl_add_u64 v[242:243],v[242:243],3,s[74:75]
	global_load_dwordx2 v[206:207], v[242:243], off
	v_mul_f32_e32 v116, 0x3e16c740, v117
	v_cvt_pk_bf16_f32 v116, v116, s0
	global_store_short v[118:119], v116, off
	ds_bpermute_b32 v120, v131, v114
	v_cmp_lt_i32_e64 s[0:1], s29, v122
	v_lshl_add_u64 v[116:117], v[192:193], 1, s[4:5]
	v_add_u32_e32 v192, 0x5100, v132
	v_cndmask_b32_e64 v118, 48, v220, s[0:1]
	v_add_u32_e32 v118, v118, v123
	v_or_b32_e32 v118, v118, v143
	v_ashrrev_i32_e32 v119, 31, v118
	v_lshl_add_u64 v[118:119], v[118:119], 3, s[74:75]
	s_waitcnt lgkmcnt(0)
	s_waitcnt vmcnt(33)
	v_mul_f32_e32 v113, v225, v120
	v_cndmask_b32_e64 v113, v113, -v113, vcc
	v_fmac_f32_e32 v113, v114, v224
	v_cmp_lt_i32_e64 s[100:101],s33,v162
	s_nop 1
	v_cndmask_b32_e64 v236,32,v222,s[100:101]
	v_add_u32_e32 v236,v236,v162
	v_cmp_lt_i32_e64 s[100:101],s33,v236
	s_nop 1
	v_cndmask_b32_e64 v240,32,v222,s[100:101]
	v_add_u32_e32 v240,v240,v236
	v_lshlrev_b32_e32 v241,4,v240
	v_cmp_lt_i32_e64 s[100:101],s28,v240
	s_nop 1
	v_cndmask_b32_e64 v242,32,v219,s[100:101]
	v_add_u32_e32 v242,v242,v241
	v_or_b32_e32 v242,v242,v143
	v_ashrrev_i32_e32 v243,31,v242
	v_lshl_add_u64 v[242:243],v[242:243],3,s[74:75]
	global_load_dwordx2 v[224:225], v[242:243], off
	v_mul_f32_e32 v112, 0x3e16c740, v113
	v_cvt_pk_bf16_f32 v112, v112, s0
	global_store_short v[116:117], v112, off
	v_mul_f32_e32 v114, v127, v115
	ds_bpermute_b32 v115, v131, v114
	s_waitcnt lgkmcnt(0)
	s_waitcnt vmcnt(34)
	v_mul_f32_e32 v113, v227, v115
	v_cndmask_b32_e64 v113, v113, -v113, vcc
	v_fmac_f32_e32 v113, v114, v226
	v_cmp_lt_i32_e64 s[100:101],s33,v162
	s_nop 1
	v_cndmask_b32_e64 v236,32,v222,s[100:101]
	v_add_u32_e32 v236,v236,v162
	v_cmp_lt_i32_e64 s[100:101],s33,v236
	s_nop 1
	v_cndmask_b32_e64 v240,32,v222,s[100:101]
	v_add_u32_e32 v240,v240,v236
	v_lshlrev_b32_e32 v241,4,v240
	v_cmp_lt_i32_e64 s[100:101],s29,v240
	s_nop 1
	v_cndmask_b32_e64 v242,48,v220,s[100:101]
	v_add_u32_e32 v241,v242,v241
	v_or_b32_e32 v242,v241,v143
	v_ashrrev_i32_e32 v243,31,v242
	v_lshl_add_u64 v[242:243],v[242:243],3,s[74:75]
	global_load_dwordx2 v[226:227], v[242:243], off
	v_mul_f32_e32 v112, 0x3e16c740, v113
	v_cvt_pk_bf16_f32 v114, v112, s0
	v_lshl_add_u64 v[112:113], v[192:193], 1, s[4:5]
	global_store_short v[112:113], v114, off
	v_cmp_lt_i32_e64 s[0:1], s33, v162
	v_add_u32_e32 v192, 0x6300, v132
	s_nop 0
	v_cndmask_b32_e64 v112, 32, v222, s[0:1]
	v_add_u32_e32 v112, v112, v162
	v_lshlrev_b32_e32 v113, 4, v112
	v_add_u32_e32 v114, 0xfffeff00, v113
	v_cmp_lt_i32_e64 s[0:1], s31, v112
	s_nop 1
	v_cndmask_b32_e64 v114, v113, v114, s[0:1]
	v_or_b32_e32 v114, v114, v143
	v_ashrrev_i32_e32 v115, 31, v114
	v_lshl_add_u64 v[114:115], v[114:115], 3, s[74:75]
	ds_read_b128 v[114:117], v151
	v_mad_u64_u32 v[120:121], s[0:1], v150, s26, v[128:129]
	v_cmp_lt_i32_e64 s[0:1], s27, v112
	v_mov_b32_e32 v121, v193
	s_waitcnt lgkmcnt(0)
	v_mul_f32_e32 v96, v96, v114
	ds_bpermute_b32 v114, v131, v96
	v_cndmask_b32_e64 v122, 16, v218, s[0:1]
	v_add_u32_e32 v122, v122, v113
	v_or_b32_e32 v122, v122, v143
	v_lshl_add_u64 v[120:121], v[120:121], 1, s[4:5]
	v_ashrrev_i32_e32 v123, 31, v122
	v_lshl_add_u64 v[122:123], v[122:123], 3, s[74:75]
	v_mul_f32_e32 v98, v98, v116
	ds_bpermute_b32 v116, v131, v98
	s_waitcnt lgkmcnt(1)
	s_waitcnt vmcnt(35)
	v_mul_f32_e32 v114, v229, v114
	v_cndmask_b32_e64 v114, v114, -v114, vcc
	v_fmac_f32_e32 v114, v96, v228
	v_cmp_lt_i32_e64 s[100:101],s33,v112
	s_nop 1
	v_cndmask_b32_e64 v236,32,v222,s[100:101]
	v_add_u32_e32 v236,v236,v112
	v_cmp_lt_i32_e64 s[100:101],s30,v236
	s_nop 1
	v_cndmask_b32_e64 v240,8,v221,s[100:101]
	v_add_u32_e32 v237,v240,v236
	v_lshlrev_b32_e32 v242,4,v237
	v_add_u32_e32 v240,0xfffeff00,v242
	v_cmp_lt_i32_e64 s[100:101],s31,v237
	s_nop 1
	v_cndmask_b32_e64 v240,v242,v240,s[100:101]
	v_or_b32_e32 v240,v240,v143
	v_ashrrev_i32_e32 v241,31,v240
	v_lshl_add_u64 v[240:241],v[240:241],3,s[74:75]
	global_load_dwordx2 v[228:229], v[240:241], off
	v_mul_f32_e32 v96, 0x3e16c740, v114
	v_cvt_pk_bf16_f32 v96, v96, s0
	global_store_short v[120:121], v96, off
	v_mul_f32_e32 v114, v97, v115
	ds_bpermute_b32 v115, v131, v114
	v_cmp_lt_i32_e64 s[0:1], s28, v112
	v_lshl_add_u64 v[120:121], v[192:193], 1, s[4:5]
	v_add_u32_e32 v192, 0x6600, v132
	v_cndmask_b32_e64 v96, 32, v219, s[0:1]
	v_add_u32_e32 v96, v96, v113
	v_or_b32_e32 v96, v96, v143
	v_ashrrev_i32_e32 v97, 31, v96
	v_lshl_add_u64 v[96:97], v[96:97], 3, s[74:75]
	s_waitcnt lgkmcnt(0)
	s_waitcnt vmcnt(36)
	v_mul_f32_e32 v115, v231, v115
	v_cndmask_b32_e64 v115, v115, -v115, vcc
	v_fmac_f32_e32 v115, v114, v230
	v_cmp_lt_i32_e64 s[100:101],s33,v112
	s_nop 1
	v_cndmask_b32_e64 v236,32,v222,s[100:101]
	v_add_u32_e32 v236,v236,v112
	v_cmp_lt_i32_e64 s[100:101],s30,v236
	s_nop 1
	v_cndmask_b32_e64 v240,8,v221,s[100:101]
	v_add_u32_e32 v237,v240,v236
	v_lshlrev_b32_e32 v242,4,v237
	v_cmp_lt_i32_e64 s[100:101],s27,v237
	s_nop 1
	v_cndmask_b32_e64 v244,16,v218,s[100:101]
	v_add_u32_e32 v244,v244,v242
	v_or_b32_e32 v244,v244,v143
	v_ashrrev_i32_e32 v245,31,v244
	v_lshl_add_u64 v[244:245],v[244:245],3,s[74:75]
	global_load_dwordx2 v[230:231], v[244:245], off
	v_mul_f32_e32 v114, 0x3e16c740, v115
	v_cvt_pk_bf16_f32 v114, v114, s0
	global_store_short v[120:121], v114, off
	v_cmp_lt_i32_e64 s[0:1], s29, v112
	v_lshl_add_u64 v[114:115], v[192:193], 1, s[4:5]
	v_add_u32_e32 v192, 0x6900, v132
	v_cndmask_b32_e64 v118, 48, v220, s[0:1]
	v_add_u32_e32 v113, v118, v113
	v_or_b32_e32 v118, v113, v143
	v_ashrrev_i32_e32 v119, 31, v118
	v_lshl_add_u64 v[118:119], v[118:119], 3, s[74:75]
	s_waitcnt vmcnt(37)
	v_mul_f32_e32 v97, v233, v116
	v_cndmask_b32_e64 v97, v97, -v97, vcc
	v_fmac_f32_e32 v97, v98, v232
	v_cmp_lt_i32_e64 s[100:101],s33,v112
	s_nop 1
	v_cndmask_b32_e64 v236,32,v222,s[100:101]
	v_add_u32_e32 v236,v236,v112
	v_cmp_lt_i32_e64 s[100:101],s30,v236
	s_nop 1
	v_cndmask_b32_e64 v240,8,v221,s[100:101]
	v_add_u32_e32 v237,v240,v236
	v_lshlrev_b32_e32 v242,4,v237
	v_cmp_lt_i32_e64 s[100:101],s28,v237
	s_nop 1
	v_cndmask_b32_e64 v240,32,v219,s[100:101]
	v_add_u32_e32 v240,v240,v242
	v_or_b32_e32 v240,v240,v143
	v_ashrrev_i32_e32 v241,31,v240
	v_lshl_add_u64 v[240:241],v[240:241],3,s[74:75]
	global_load_dwordx2 v[232:233], v[240:241], off
	v_mul_f32_e32 v96, 0x3e16c740, v97
	v_cvt_pk_bf16_f32 v96, v96, s0
	global_store_short v[114:115], v96, off
	v_mul_f32_e32 v98, v99, v117
	ds_bpermute_b32 v99, v131, v98
	s_waitcnt lgkmcnt(0)
	s_waitcnt vmcnt(38)
	v_mul_f32_e32 v97, v235, v99
	v_cndmask_b32_e64 v97, v97, -v97, vcc
	v_fmac_f32_e32 v97, v98, v234
	v_mov_b32_e32 v241, v81
	v_cmp_lt_i32_e64 s[100:101],s33,v112
	s_nop 1
	v_cndmask_b32_e64 v236,32,v222,s[100:101]
	v_add_u32_e32 v236,v236,v112
	v_cmp_lt_i32_e64 s[100:101],s30,v236
	s_nop 1
	v_cndmask_b32_e64 v240,8,v221,s[100:101]
	v_add_u32_e32 v237,v240,v236
	v_lshlrev_b32_e32 v242,4,v237
	v_cmp_lt_i32_e64 s[100:101],s29,v237
	s_nop 1
	v_cndmask_b32_e64 v244,48,v220,s[100:101]
	v_add_u32_e32 v244,v244,v242
	v_or_b32_e32 v244,v244,v143
	v_ashrrev_i32_e32 v245,31,v244
	v_lshl_add_u64 v[244:245],v[244:245],3,s[74:75]
	global_load_dwordx2 v[234:235], v[244:245], off
	v_mul_f32_e32 v96, 0x3e16c740, v97
	v_cvt_pk_bf16_f32 v98, v96, s0
	v_lshl_add_u64 v[96:97], v[192:193], 1, s[4:5]
	global_store_short v[96:97], v98, off
	v_cmp_lt_i32_e64 s[0:1], s30, v112
	v_add_u32_e32 v192, 0x7b00, v132
	s_nop 0
	v_cndmask_b32_e64 v96, 8, v221, s[0:1]
	v_add_u32_e32 v113, v96, v112
	v_lshlrev_b32_e32 v120, 4, v113
	v_add_u32_e32 v96, 0xfffeff00, v120
	v_cmp_lt_i32_e64 s[0:1], s31, v113
	s_nop 1
	v_cndmask_b32_e64 v96, v120, v96, s[0:1]
	v_or_b32_e32 v96, v96, v143
	v_ashrrev_i32_e32 v97, 31, v96
	v_lshl_add_u64 v[96:97], v[96:97], 3, s[74:75]
	ds_read_b128 v[96:99], v149
	v_mad_u64_u32 v[116:117], s[0:1], v148, s26, v[128:129]
	v_cmp_lt_i32_e64 s[0:1], s27, v113
	v_mov_b32_e32 v117, v193
	s_waitcnt lgkmcnt(0)
	v_mul_f32_e32 v96, v100, v96
	ds_bpermute_b32 v100, v131, v96
	v_cndmask_b32_e64 v118, 16, v218, s[0:1]
	v_add_u32_e32 v118, v118, v120
	v_or_b32_e32 v118, v118, v143
	v_lshl_add_u64 v[116:117], v[116:117], 1, s[4:5]
	v_ashrrev_i32_e32 v119, 31, v118
	v_lshl_add_u64 v[118:119], v[118:119], 3, s[74:75]
	v_mul_f32_e32 v98, v102, v98
	ds_bpermute_b32 v102, v131, v98
	s_waitcnt lgkmcnt(1)
	s_waitcnt vmcnt(39)
	v_mul_f32_e32 v100, v175, v100
	v_cndmask_b32_e64 v100, v100, -v100, vcc
	v_fmac_f32_e32 v100, v96, v174
	v_cmp_lt_i32_e64 s[100:101],s33,v112
	s_nop 1
	v_cndmask_b32_e64 v236,32,v222,s[100:101]
	v_add_u32_e32 v236,v236,v112
	v_cmp_lt_i32_e64 s[100:101],s30,v236
	s_nop 1
	v_cndmask_b32_e64 v240,8,v221,s[100:101]
	v_add_u32_e32 v237,v240,v236
	v_cmp_lt_i32_e64 s[100:101],s30,v237
	s_nop 1
	v_cndmask_b32_e64 v240,8,v221,s[100:101]
	v_add_u32_e32 v237,v240,v237
	v_lshlrev_b32_e32 v242,4,v237
	v_add_u32_e32 v240,0xfffeff00,v242
	v_cmp_lt_i32_e64 s[100:101],s31,v237
	s_nop 1
	v_cndmask_b32_e64 v240,v242,v240,s[100:101]
	v_or_b32_e32 v240,v240,v143
	v_ashrrev_i32_e32 v241,31,v240
	v_lshl_add_u64 v[240:241],v[240:241],3,s[74:75]
	global_load_dwordx2 v[174:175], v[240:241], off
	v_mul_f32_e32 v96, 0x3e16c740, v100
	v_cvt_pk_bf16_f32 v96, v96, s0
	global_store_short v[116:117], v96, off
	v_mul_f32_e32 v100, v101, v97
	ds_bpermute_b32 v101, v131, v100
	v_cmp_lt_i32_e64 s[0:1], s28, v113
	v_lshl_add_u64 v[116:117], v[192:193], 1, s[4:5]
	v_add_u32_e32 v192, 0x7e00, v132
	v_cndmask_b32_e64 v96, 32, v219, s[0:1]
	v_add_u32_e32 v96, v96, v120
	v_or_b32_e32 v96, v96, v143
	v_ashrrev_i32_e32 v97, 31, v96
	v_lshl_add_u64 v[96:97], v[96:97], 3, s[74:75]
	s_waitcnt lgkmcnt(0)
	s_waitcnt vmcnt(39)
	v_mul_f32_e32 v101, v177, v101
	v_cndmask_b32_e64 v101, v101, -v101, vcc
	v_fmac_f32_e32 v101, v100, v176
	v_cmp_lt_i32_e64 s[100:101],s33,v112
	s_nop 1
	v_cndmask_b32_e64 v236,32,v222,s[100:101]
	v_add_u32_e32 v236,v236,v112
	v_cmp_lt_i32_e64 s[100:101],s30,v236
	s_nop 1
	v_cndmask_b32_e64 v240,8,v221,s[100:101]
	v_add_u32_e32 v237,v240,v236
	v_cmp_lt_i32_e64 s[100:101],s30,v237
	s_nop 1
	v_cndmask_b32_e64 v240,8,v221,s[100:101]
	v_add_u32_e32 v237,v240,v237
	v_lshlrev_b32_e32 v242,4,v237
	v_cmp_lt_i32_e64 s[100:101],s27,v237
	s_nop 1
	v_cndmask_b32_e64 v244,16,v218,s[100:101]
	v_add_u32_e32 v244,v244,v242
	v_or_b32_e32 v244,v244,v143
	v_ashrrev_i32_e32 v245,31,v244
	v_lshl_add_u64 v[244:245],v[244:245],3,s[74:75]
	global_load_dwordx2 v[176:177], v[244:245], off
	v_mul_f32_e32 v100, 0x3e16c740, v101
	v_cvt_pk_bf16_f32 v100, v100, s0
	global_store_short v[116:117], v100, off
	v_cmp_lt_i32_e64 s[0:1], s29, v113
	v_lshl_add_u64 v[100:101], v[192:193], 1, s[4:5]
	v_add_u32_e32 v192, 0x8100, v132
	v_cndmask_b32_e64 v114, 48, v220, s[0:1]
	v_add_u32_e32 v114, v114, v120
	v_or_b32_e32 v114, v114, v143
	v_ashrrev_i32_e32 v115, 31, v114
	v_lshl_add_u64 v[114:115], v[114:115], 3, s[74:75]
	s_waitcnt vmcnt(39)
	v_mul_f32_e32 v97, v179, v102
	v_cndmask_b32_e64 v97, v97, -v97, vcc
	v_fmac_f32_e32 v97, v98, v178
	v_cmp_lt_i32_e64 s[100:101],s33,v112
	s_nop 1
	v_cndmask_b32_e64 v236,32,v222,s[100:101]
	v_add_u32_e32 v236,v236,v112
	v_cmp_lt_i32_e64 s[100:101],s30,v236
	s_nop 1
	v_cndmask_b32_e64 v240,8,v221,s[100:101]
	v_add_u32_e32 v237,v240,v236
	v_cmp_lt_i32_e64 s[100:101],s30,v237
	s_nop 1
	v_cndmask_b32_e64 v240,8,v221,s[100:101]
	v_add_u32_e32 v237,v240,v237
	v_lshlrev_b32_e32 v242,4,v237
	v_cmp_lt_i32_e64 s[100:101],s28,v237
	s_nop 1
	v_cndmask_b32_e64 v240,32,v219,s[100:101]
	v_add_u32_e32 v240,v240,v242
	v_or_b32_e32 v240,v240,v143
	v_ashrrev_i32_e32 v241,31,v240
	v_lshl_add_u64 v[240:241],v[240:241],3,s[74:75]
	global_load_dwordx2 v[178:179], v[240:241], off
	v_mul_f32_e32 v96, 0x3e16c740, v97
	v_cvt_pk_bf16_f32 v96, v96, s0
	global_store_short v[100:101], v96, off
	v_mul_f32_e32 v98, v103, v99
	ds_bpermute_b32 v99, v131, v98
	s_waitcnt lgkmcnt(0)
	s_waitcnt vmcnt(39)
	v_mul_f32_e32 v97, v181, v99
	v_cndmask_b32_e64 v97, v97, -v97, vcc
	v_fmac_f32_e32 v97, v98, v180
	v_mov_b32_e32 v241, v81
	v_cmp_lt_i32_e64 s[100:101],s33,v112
	s_nop 1
	v_cndmask_b32_e64 v236,32,v222,s[100:101]
	v_add_u32_e32 v236,v236,v112
	v_cmp_lt_i32_e64 s[100:101],s30,v236
	s_nop 1
	v_cndmask_b32_e64 v240,8,v221,s[100:101]
	v_add_u32_e32 v237,v240,v236
	v_cmp_lt_i32_e64 s[100:101],s30,v237
	s_nop 1
	v_cndmask_b32_e64 v240,8,v221,s[100:101]
	v_add_u32_e32 v237,v240,v237
	v_lshlrev_b32_e32 v242,4,v237
	v_cmp_lt_i32_e64 s[100:101],s29,v237
	s_nop 1
	v_cndmask_b32_e64 v244,48,v220,s[100:101]
	v_add_u32_e32 v244,v244,v242
	v_or_b32_e32 v244,v244,v143
	v_ashrrev_i32_e32 v245,31,v244
	v_lshl_add_u64 v[244:245],v[244:245],3,s[74:75]
	global_load_dwordx2 v[180:181], v[244:245], off
	v_mul_f32_e32 v96, 0x3e16c740, v97
	v_cvt_pk_bf16_f32 v98, v96, s0
	v_lshl_add_u64 v[96:97], v[192:193], 1, s[4:5]
	global_store_short v[96:97], v98, off
	v_cmp_lt_i32_e64 s[0:1], s30, v113
	v_add_u32_e32 v192, 0x9300, v132
	s_nop 0
	v_cndmask_b32_e64 v96, 8, v221, s[0:1]
	v_add_u32_e32 v113, v96, v113
	v_lshlrev_b32_e32 v116, 4, v113
	v_add_u32_e32 v96, 0xfffeff00, v116
	v_cmp_lt_i32_e64 s[0:1], s31, v113
	s_nop 1
	v_cndmask_b32_e64 v96, v116, v96, s[0:1]
	v_or_b32_e32 v96, v96, v143
	v_ashrrev_i32_e32 v97, 31, v96
	v_lshl_add_u64 v[96:97], v[96:97], 3, s[74:75]
	ds_read_b128 v[96:99], v147
	v_mad_u64_u32 v[102:103], s[0:1], v146, s26, v[128:129]
	v_cmp_lt_i32_e64 s[0:1], s27, v113
	v_mov_b32_e32 v103, v193
	s_waitcnt lgkmcnt(0)
	v_mul_f32_e32 v96, v104, v96
	ds_bpermute_b32 v104, v131, v96
	v_cndmask_b32_e64 v114, 16, v218, s[0:1]
	v_add_u32_e32 v114, v114, v116
	v_or_b32_e32 v114, v114, v143
	v_lshl_add_u64 v[102:103], v[102:103], 1, s[4:5]
	v_ashrrev_i32_e32 v115, 31, v114
	v_lshl_add_u64 v[114:115], v[114:115], 3, s[74:75]
	v_mul_f32_e32 v98, v106, v98
	s_waitcnt lgkmcnt(0)
	s_waitcnt vmcnt(39)
	v_mul_f32_e32 v101, v183, v104
	v_cndmask_b32_e64 v101, v101, -v101, vcc
	v_fmac_f32_e32 v101, v96, v182
	v_cmp_lt_i32_e64 s[100:101],s33,v112
	s_nop 1
	v_cndmask_b32_e64 v236,32,v222,s[100:101]
	v_add_u32_e32 v236,v236,v112
	v_cmp_lt_i32_e64 s[100:101],s30,v236
	s_nop 1
	v_cndmask_b32_e64 v240,8,v221,s[100:101]
	v_add_u32_e32 v237,v240,v236
	v_cmp_lt_i32_e64 s[100:101],s30,v237
	s_nop 1
	v_cndmask_b32_e64 v240,8,v221,s[100:101]
	v_add_u32_e32 v237,v240,v237
	v_cmp_lt_i32_e64 s[100:101],s30,v237
	s_nop 1
	v_cndmask_b32_e64 v240,8,v221,s[100:101]
	v_add_u32_e32 v242,v240,v237
	v_lshlrev_b32_e32 v243,4,v242
	v_add_u32_e32 v240,0xfffeff00,v243
	v_cmp_lt_i32_e64 s[100:101],s31,v242
	s_nop 1
	v_cndmask_b32_e64 v240,v243,v240,s[100:101]
	v_or_b32_e32 v240,v240,v143
	v_ashrrev_i32_e32 v241,31,v240
	v_lshl_add_u64 v[240:241],v[240:241],3,s[74:75]
	global_load_dwordx2 v[182:183], v[240:241], off
	v_mul_f32_e32 v96, 0x3e16c740, v101
	v_cvt_pk_bf16_f32 v96, v96, s0
	global_store_short v[102:103], v96, off
	v_mul_f32_e32 v104, v105, v97
	ds_bpermute_b32 v105, v131, v104
	v_cmp_lt_i32_e64 s[0:1], s28, v113
	v_lshl_add_u64 v[102:103], v[192:193], 1, s[4:5]
	v_add_u32_e32 v192, 0x9600, v132
	v_cndmask_b32_e64 v96, 32, v219, s[0:1]
	v_add_u32_e32 v96, v96, v116
	v_or_b32_e32 v96, v96, v143
	v_ashrrev_i32_e32 v97, 31, v96
	v_lshl_add_u64 v[96:97], v[96:97], 3, s[74:75]
	s_waitcnt lgkmcnt(0)
	s_waitcnt vmcnt(39)
	v_mul_f32_e32 v101, v185, v105
	v_cndmask_b32_e64 v101, v101, -v101, vcc
	v_fmac_f32_e32 v101, v104, v184
	v_cmp_lt_i32_e64 s[100:101],s33,v112
	s_nop 1
	v_cndmask_b32_e64 v236,32,v222,s[100:101]
	v_add_u32_e32 v236,v236,v112
	v_cmp_lt_i32_e64 s[100:101],s30,v236
	s_nop 1
	v_cndmask_b32_e64 v240,8,v221,s[100:101]
	v_add_u32_e32 v237,v240,v236
	v_cmp_lt_i32_e64 s[100:101],s30,v237
	s_nop 1
	v_cndmask_b32_e64 v240,8,v221,s[100:101]
	v_add_u32_e32 v237,v240,v237
	v_cmp_lt_i32_e64 s[100:101],s30,v237
	s_nop 1
	v_cndmask_b32_e64 v240,8,v221,s[100:101]
	v_add_u32_e32 v242,v240,v237
	v_lshlrev_b32_e32 v243,4,v242
	v_cmp_lt_i32_e64 s[100:101],s27,v242
	s_nop 1
	v_cndmask_b32_e64 v244,16,v218,s[100:101]
	v_add_u32_e32 v244,v244,v243
	v_or_b32_e32 v244,v244,v143
	v_ashrrev_i32_e32 v245,31,v244
	v_lshl_add_u64 v[244:245],v[244:245],3,s[74:75]
	global_load_dwordx2 v[184:185], v[244:245], off
	v_mul_f32_e32 v100, 0x3e16c740, v101
	v_cvt_pk_bf16_f32 v100, v100, s0
	global_store_short v[102:103], v100, off
	ds_bpermute_b32 v104, v131, v98
	v_cmp_lt_i32_e64 s[0:1], s29, v113
	v_lshl_add_u64 v[100:101], v[192:193], 1, s[4:5]
	v_add_u32_e32 v192, 0x9900, v132
	v_cndmask_b32_e64 v102, 48, v220, s[0:1]
	v_add_u32_e32 v102, v102, v116
	v_or_b32_e32 v102, v102, v143
	v_ashrrev_i32_e32 v103, 31, v102
	v_lshl_add_u64 v[102:103], v[102:103], 3, s[74:75]
	s_waitcnt lgkmcnt(0)
	s_waitcnt vmcnt(39)
	v_mul_f32_e32 v97, v187, v104
	v_cndmask_b32_e64 v97, v97, -v97, vcc
	v_fmac_f32_e32 v97, v98, v186
	v_cmp_lt_i32_e64 s[100:101],s33,v112
	s_nop 1
	v_cndmask_b32_e64 v236,32,v222,s[100:101]
	v_add_u32_e32 v236,v236,v112
	v_cmp_lt_i32_e64 s[100:101],s30,v236
	s_nop 1
	v_cndmask_b32_e64 v240,8,v221,s[100:101]
	v_add_u32_e32 v237,v240,v236
	v_cmp_lt_i32_e64 s[100:101],s30,v237
	s_nop 1
	v_cndmask_b32_e64 v240,8,v221,s[100:101]
	v_add_u32_e32 v237,v240,v237
	v_cmp_lt_i32_e64 s[100:101],s30,v237
	s_nop 1
	v_cndmask_b32_e64 v240,8,v221,s[100:101]
	v_add_u32_e32 v242,v240,v237
	v_lshlrev_b32_e32 v243,4,v242
	v_cmp_lt_i32_e64 s[100:101],s28,v242
	s_nop 1
	v_cndmask_b32_e64 v240,32,v219,s[100:101]
	v_add_u32_e32 v240,v240,v243
	v_or_b32_e32 v240,v240,v143
	v_ashrrev_i32_e32 v241,31,v240
	v_lshl_add_u64 v[240:241],v[240:241],3,s[74:75]
	global_load_dwordx2 v[186:187], v[240:241], off
	v_mul_f32_e32 v96, 0x3e16c740, v97
	v_cvt_pk_bf16_f32 v96, v96, s0
	global_store_short v[100:101], v96, off
	v_mul_f32_e32 v98, v107, v99
	ds_bpermute_b32 v99, v131, v98
	s_waitcnt lgkmcnt(0)
	s_waitcnt vmcnt(39)
	v_mul_f32_e32 v97, v189, v99
	v_cndmask_b32_e64 v97, v97, -v97, vcc
	v_fmac_f32_e32 v97, v98, v188
	v_mov_b32_e32 v241, v81
	v_cmp_lt_i32_e64 s[100:101],s33,v112
	s_nop 1
	v_cndmask_b32_e64 v236,32,v222,s[100:101]
	v_add_u32_e32 v236,v236,v112
	v_cmp_lt_i32_e64 s[100:101],s30,v236
	s_nop 1
	v_cndmask_b32_e64 v240,8,v221,s[100:101]
	v_add_u32_e32 v237,v240,v236
	v_cmp_lt_i32_e64 s[100:101],s30,v237
	s_nop 1
	v_cndmask_b32_e64 v240,8,v221,s[100:101]
	v_add_u32_e32 v237,v240,v237
	v_cmp_lt_i32_e64 s[100:101],s30,v237
	s_nop 1
	v_cndmask_b32_e64 v240,8,v221,s[100:101]
	v_add_u32_e32 v242,v240,v237
	v_lshlrev_b32_e32 v243,4,v242
	v_cmp_lt_i32_e64 s[100:101],s29,v242
	s_nop 1
	v_cndmask_b32_e64 v244,48,v220,s[100:101]
	v_add_u32_e32 v244,v244,v243
	v_or_b32_e32 v244,v244,v143
	v_ashrrev_i32_e32 v245,31,v244
	v_lshl_add_u64 v[244:245],v[244:245],3,s[74:75]
	global_load_dwordx2 v[188:189], v[244:245], off
	v_mul_f32_e32 v96, 0x3e16c740, v97
	v_cvt_pk_bf16_f32 v98, v96, s0
	v_lshl_add_u64 v[96:97], v[192:193], 1, s[4:5]
	global_store_short v[96:97], v98, off
	v_cmp_lt_i32_e64 s[0:1], s30, v113
	v_add_u32_e32 v192, 0xab00, v132
	s_nop 0
	v_cndmask_b32_e64 v96, 8, v221, s[0:1]
	v_add_u32_e32 v106, v96, v113
	v_lshlrev_b32_e32 v107, 4, v106
	v_add_u32_e32 v96, 0xfffeff00, v107
	v_cmp_lt_i32_e64 s[0:1], s31, v106
	s_nop 1
	v_cndmask_b32_e64 v96, v107, v96, s[0:1]
	v_or_b32_e32 v96, v96, v143
	v_ashrrev_i32_e32 v97, 31, v96
	v_lshl_add_u64 v[96:97], v[96:97], 3, s[74:75]
	ds_read_b128 v[96:99], v145
	v_mad_u64_u32 v[102:103], s[0:1], v144, s26, v[128:129]
	v_cmp_lt_i32_e64 s[0:1], s27, v106
	v_mov_b32_e32 v103, v193
	s_waitcnt lgkmcnt(0)
	v_mul_f32_e32 v96, v108, v96
	ds_bpermute_b32 v108, v131, v96
	v_cndmask_b32_e64 v104, 16, v218, s[0:1]
	v_add_u32_e32 v104, v104, v107
	v_or_b32_e32 v104, v104, v143
	v_lshl_add_u64 v[102:103], v[102:103], 1, s[4:5]
	v_ashrrev_i32_e32 v105, 31, v104
	v_lshl_add_u64 v[104:105], v[104:105], 3, s[74:75]
	v_mul_f32_e32 v98, v110, v98
	s_waitcnt lgkmcnt(0)
	s_waitcnt vmcnt(39)
	v_mul_f32_e32 v101, v191, v108
	v_cndmask_b32_e64 v101, v101, -v101, vcc
	v_fmac_f32_e32 v101, v96, v190
	v_cmp_lt_i32_e64 s[100:101],s33,v112
	s_nop 1
	v_cndmask_b32_e64 v236,32,v222,s[100:101]
	v_add_u32_e32 v236,v236,v112
	v_cmp_lt_i32_e64 s[100:101],s33,v236
	s_nop 1
	v_cndmask_b32_e64 v240,32,v222,s[100:101]
	v_add_u32_e32 v242,v240,v236
	v_lshlrev_b32_e32 v243,4,v242
	v_add_u32_e32 v240,0xfffeff00,v243
	v_cmp_lt_i32_e64 s[100:101],s31,v242
	s_nop 1
	v_cndmask_b32_e64 v240,v243,v240,s[100:101]
	v_or_b32_e32 v240,v240,v143
	v_ashrrev_i32_e32 v241,31,v240
	v_lshl_add_u64 v[240:241],v[240:241],3,s[74:75]
	global_load_dwordx2 v[190:191], v[240:241], off
	v_mul_f32_e32 v96, 0x3e16c740, v101
	v_cvt_pk_bf16_f32 v96, v96, s0
	global_store_short v[102:103], v96, off
	v_mul_f32_e32 v104, v109, v97
	ds_bpermute_b32 v105, v131, v104
	v_cmp_lt_i32_e64 s[0:1], s28, v106
	v_lshl_add_u64 v[102:103], v[192:193], 1, s[4:5]
	v_add_u32_e32 v192, 0xae00, v132
	v_cndmask_b32_e64 v96, 32, v219, s[0:1]
	v_add_u32_e32 v96, v96, v107
	v_or_b32_e32 v96, v96, v143
	v_ashrrev_i32_e32 v97, 31, v96
	v_lshl_add_u64 v[96:97], v[96:97], 3, s[74:75]
	s_waitcnt lgkmcnt(0)
	s_waitcnt vmcnt(39)
	v_mul_f32_e32 v101, v195, v105
	v_cndmask_b32_e64 v101, v101, -v101, vcc
	v_fmac_f32_e32 v101, v104, v194
	v_cmp_lt_i32_e64 s[100:101],s33,v112
	s_nop 1
	v_cndmask_b32_e64 v236,32,v222,s[100:101]
	v_add_u32_e32 v236,v236,v112
	v_cmp_lt_i32_e64 s[100:101],s33,v236
	s_nop 1
	v_cndmask_b32_e64 v240,32,v222,s[100:101]
	v_add_u32_e32 v242,v240,v236
	v_lshlrev_b32_e32 v243,4,v242
	v_cmp_lt_i32_e64 s[100:101],s27,v242
	s_nop 1
	v_cndmask_b32_e64 v244,16,v218,s[100:101]
	v_add_u32_e32 v244,v244,v243
	v_or_b32_e32 v244,v244,v143
	v_ashrrev_i32_e32 v245,31,v244
	v_lshl_add_u64 v[244:245],v[244:245],3,s[74:75]
	global_load_dwordx2 v[194:195], v[244:245], off
	v_mul_f32_e32 v100, 0x3e16c740, v101
	v_cvt_pk_bf16_f32 v100, v100, s0
	global_store_short v[102:103], v100, off
	ds_bpermute_b32 v104, v131, v98
	v_cmp_lt_i32_e64 s[0:1], s29, v106
	v_lshl_add_u64 v[100:101], v[192:193], 1, s[4:5]
	v_add_u32_e32 v192, 0xb100, v132
	v_cndmask_b32_e64 v102, 48, v220, s[0:1]
	v_add_u32_e32 v102, v102, v107
	v_or_b32_e32 v102, v102, v143
	v_ashrrev_i32_e32 v103, 31, v102
	v_lshl_add_u64 v[102:103], v[102:103], 3, s[74:75]
	s_waitcnt lgkmcnt(0)
	s_waitcnt vmcnt(39)
	v_mul_f32_e32 v97, v197, v104
	v_cndmask_b32_e64 v97, v97, -v97, vcc
	v_fmac_f32_e32 v97, v98, v196
	v_cmp_lt_i32_e64 s[100:101],s33,v112
	s_nop 1
	v_cndmask_b32_e64 v236,32,v222,s[100:101]
	v_add_u32_e32 v236,v236,v112
	v_cmp_lt_i32_e64 s[100:101],s33,v236
	s_nop 1
	v_cndmask_b32_e64 v240,32,v222,s[100:101]
	v_add_u32_e32 v242,v240,v236
	v_lshlrev_b32_e32 v243,4,v242
	v_cmp_lt_i32_e64 s[100:101],s28,v242
	s_nop 1
	v_cndmask_b32_e64 v244,32,v219,s[100:101]
	v_add_u32_e32 v244,v244,v243
	v_or_b32_e32 v244,v244,v143
	v_ashrrev_i32_e32 v245,31,v244
	v_lshl_add_u64 v[244:245],v[244:245],3,s[74:75]
	global_load_dwordx2 v[196:197], v[244:245], off
	v_mul_f32_e32 v96, 0x3e16c740, v97
	v_cvt_pk_bf16_f32 v96, v96, s0
	global_store_short v[100:101], v96, off
	v_mul_f32_e32 v98, v111, v99
	ds_bpermute_b32 v99, v131, v98
	s_waitcnt lgkmcnt(0)
	s_waitcnt vmcnt(39)
	v_mul_f32_e32 v97, v199, v99
	v_cndmask_b32_e64 v97, v97, -v97, vcc
	v_fmac_f32_e32 v97, v98, v198
	v_cmp_lt_i32_e64 s[100:101],s33,v112
	s_nop 1
	v_cndmask_b32_e64 v236,32,v222,s[100:101]
	v_add_u32_e32 v236,v236,v112
	v_cmp_lt_i32_e64 s[100:101],s33,v236
	s_nop 1
	v_cndmask_b32_e64 v240,32,v222,s[100:101]
	v_add_u32_e32 v242,v240,v236
	v_lshlrev_b32_e32 v243,4,v242
	v_cmp_lt_i32_e64 s[100:101],s29,v242
	s_nop 1
	v_cndmask_b32_e64 v244,48,v220,s[100:101]
	v_add_u32_e32 v244,v244,v243
	v_or_b32_e32 v244,v244,v143
	v_ashrrev_i32_e32 v245,31,v244
	v_lshl_add_u64 v[244:245],v[244:245],3,s[74:75]
	global_load_dwordx2 v[198:199], v[244:245], off
	v_mul_f32_e32 v96, 0x3e16c740, v97
	v_cvt_pk_bf16_f32 v98, v96, s0
	v_lshl_add_u64 v[96:97], v[192:193], 1, s[4:5]
	global_store_short v[96:97], v98, off
	v_cmp_lt_i32_e64 s[0:1], s33, v112
	v_add_u32_e32 v192, 0xc300, v132
	s_nop 0
	v_cndmask_b32_e64 v96, 32, v222, s[0:1]
	v_add_u32_e32 v96, v96, v112
	v_lshlrev_b32_e32 v97, 4, v96
	v_add_u32_e32 v98, 0xfffeff00, v97
	v_cmp_lt_i32_e64 s[0:1], s31, v96
	s_nop 1
	v_cndmask_b32_e64 v98, v97, v98, s[0:1]
	v_or_b32_e32 v98, v98, v143
	v_ashrrev_i32_e32 v99, 31, v98
	v_lshl_add_u64 v[98:99], v[98:99], 3, s[74:75]
	ds_read_b128 v[98:101], v142
	v_mad_u64_u32 v[104:105], s[0:1], v141, s26, v[128:129]
	v_cmp_lt_i32_e64 s[0:1], s27, v96
	v_mov_b32_e32 v105, v193
	s_waitcnt lgkmcnt(0)
	v_mul_f32_e32 v80, v80, v98
	ds_bpermute_b32 v98, v131, v80
	v_cndmask_b32_e64 v106, 16, v218, s[0:1]
	v_add_u32_e32 v106, v106, v97
	v_or_b32_e32 v106, v106, v143
	v_lshl_add_u64 v[104:105], v[104:105], 1, s[4:5]
	v_ashrrev_i32_e32 v107, 31, v106
	v_lshl_add_u64 v[106:107], v[106:107], 3, s[74:75]
	v_mul_f32_e32 v82, v82, v100
	ds_bpermute_b32 v100, v131, v82
	s_waitcnt lgkmcnt(1)
	s_waitcnt vmcnt(39)
	v_mul_f32_e32 v98, v205, v98
	v_cndmask_b32_e64 v98, v98, -v98, vcc
	v_fmac_f32_e32 v98, v80, v204
	v_mov_b32_e32 v237, v81
	v_cmp_lt_i32_e64 s[100:101],s33,v96
	s_nop 1
	v_cndmask_b32_e64 v236,32,v222,s[100:101]
	v_add_u32_e32 v240,v236,v96
	v_cmp_lt_i32_e64 s[100:101],s30,v240
	s_nop 1
	v_cndmask_b32_e64 v242,8,v221,s[100:101]
	v_add_u32_e32 v244,v242,v240
	v_lshlrev_b32_e32 v245,4,v244
	v_add_u32_e32 v242,0xfffeff00,v245
	v_cmp_lt_i32_e64 s[100:101],s31,v244
	s_nop 1
	v_cndmask_b32_e64 v242,v245,v242,s[100:101]
	v_or_b32_e32 v242,v242,v143
	v_ashrrev_i32_e32 v243,31,v242
	v_lshl_add_u64 v[242:243],v[242:243],3,s[74:75]
	global_load_dwordx2 v[204:205], v[242:243], off
	v_mul_f32_e32 v80, 0x3e16c740, v98
	v_cvt_pk_bf16_f32 v80, v80, s0
	global_store_short v[104:105], v80, off
	v_mul_f32_e32 v98, v81, v99
	ds_bpermute_b32 v99, v131, v98
	v_cmp_lt_i32_e64 s[0:1], s28, v96
	v_lshl_add_u64 v[104:105], v[192:193], 1, s[4:5]
	v_add_u32_e32 v192, 0xc600, v132
	v_cndmask_b32_e64 v80, 32, v219, s[0:1]
	v_add_u32_e32 v80, v80, v97
	v_or_b32_e32 v80, v80, v143
	v_ashrrev_i32_e32 v81, 31, v80
	v_lshl_add_u64 v[80:81], v[80:81], 3, s[74:75]
	s_waitcnt lgkmcnt(0)
	s_waitcnt vmcnt(39)
	v_mul_f32_e32 v99, v207, v99
	v_cndmask_b32_e64 v99, v99, -v99, vcc
	v_fmac_f32_e32 v99, v98, v206
	v_mov_b32_e32 v237, v81
	v_cmp_lt_i32_e64 s[100:101],s33,v96
	s_nop 1
	v_cndmask_b32_e64 v236,32,v222,s[100:101]
	v_add_u32_e32 v240,v236,v96
	v_cmp_lt_i32_e64 s[100:101],s30,v240
	s_nop 1
	v_cndmask_b32_e64 v242,8,v221,s[100:101]
	v_add_u32_e32 v244,v242,v240
	v_lshlrev_b32_e32 v245,4,v244
	v_cmp_lt_i32_e64 s[100:101],s27,v244
	s_nop 1
	v_cndmask_b32_e64 v246,16,v218,s[100:101]
	v_add_u32_e32 v246,v246,v245
	v_or_b32_e32 v246,v246,v143
	v_ashrrev_i32_e32 v247,31,v246
	v_lshl_add_u64 v[246:247],v[246:247],3,s[74:75]
	global_load_dwordx2 v[206:207], v[246:247], off
	v_mul_f32_e32 v98, 0x3e16c740, v99
	v_cvt_pk_bf16_f32 v98, v98, s0
	global_store_short v[104:105], v98, off
	v_cmp_lt_i32_e64 s[0:1], s29, v96
	v_lshl_add_u64 v[98:99], v[192:193], 1, s[4:5]
	v_add_u32_e32 v192, 0xc900, v132
	v_cndmask_b32_e64 v102, 48, v220, s[0:1]
	v_add_u32_e32 v97, v102, v97
	v_or_b32_e32 v102, v97, v143
	v_ashrrev_i32_e32 v103, 31, v102
	v_lshl_add_u64 v[102:103], v[102:103], 3, s[74:75]
	s_waitcnt vmcnt(39)
	v_mul_f32_e32 v81, v225, v100
	v_cndmask_b32_e64 v81, v81, -v81, vcc
	v_fmac_f32_e32 v81, v82, v224
	v_cmp_lt_i32_e64 s[100:101],s33,v96
	s_nop 1
	v_cndmask_b32_e64 v236,32,v222,s[100:101]
	v_add_u32_e32 v240,v236,v96
	v_cmp_lt_i32_e64 s[100:101],s30,v240
	s_nop 1
	v_cndmask_b32_e64 v242,8,v221,s[100:101]
	v_add_u32_e32 v244,v242,v240
	v_lshlrev_b32_e32 v245,4,v244
	v_cmp_lt_i32_e64 s[100:101],s28,v244
	s_nop 1
	v_cndmask_b32_e64 v242,32,v219,s[100:101]
	v_add_u32_e32 v242,v242,v245
	v_or_b32_e32 v242,v242,v143
	v_ashrrev_i32_e32 v243,31,v242
	v_lshl_add_u64 v[242:243],v[242:243],3,s[74:75]
	global_load_dwordx2 v[224:225], v[242:243], off
	v_mul_f32_e32 v80, 0x3e16c740, v81
	v_cvt_pk_bf16_f32 v80, v80, s0
	global_store_short v[98:99], v80, off
	v_mul_f32_e32 v82, v83, v101
	ds_bpermute_b32 v83, v131, v82
	s_waitcnt lgkmcnt(0)
	s_waitcnt vmcnt(39)
	v_mul_f32_e32 v81, v227, v83
	v_cndmask_b32_e64 v81, v81, -v81, vcc
	v_fmac_f32_e32 v81, v82, v226
	v_mov_b32_e32 v243, v65
	v_cmp_lt_i32_e64 s[100:101],s33,v96
	s_nop 1
	v_cndmask_b32_e64 v236,32,v222,s[100:101]
	v_add_u32_e32 v240,v236,v96
	v_cmp_lt_i32_e64 s[100:101],s30,v240
	s_nop 1
	v_cndmask_b32_e64 v242,8,v221,s[100:101]
	v_add_u32_e32 v244,v242,v240
	v_lshlrev_b32_e32 v245,4,v244
	v_cmp_lt_i32_e64 s[100:101],s29,v244
	s_nop 1
	v_cndmask_b32_e64 v236,48,v220,s[100:101]
	v_add_u32_e32 v236,v236,v245
	v_or_b32_e32 v236,v236,v143
	v_ashrrev_i32_e32 v237,31,v236
	v_lshl_add_u64 v[236:237],v[236:237],3,s[74:75]
	global_load_dwordx2 v[226:227], v[236:237], off
	v_mul_f32_e32 v80, 0x3e16c740, v81
	v_cvt_pk_bf16_f32 v82, v80, s0
	v_lshl_add_u64 v[80:81], v[192:193], 1, s[4:5]
	global_store_short v[80:81], v82, off
	v_cmp_lt_i32_e64 s[0:1], s30, v96
	v_add_u32_e32 v192, 0xdb00, v132
	s_nop 0
	v_cndmask_b32_e64 v80, 8, v221, s[0:1]
	v_add_u32_e32 v97, v80, v96
	v_lshlrev_b32_e32 v104, 4, v97
	v_add_u32_e32 v80, 0xfffeff00, v104
	v_cmp_lt_i32_e64 s[0:1], s31, v97
	s_nop 1
	v_cndmask_b32_e64 v80, v104, v80, s[0:1]
	v_or_b32_e32 v80, v80, v143
	v_ashrrev_i32_e32 v81, 31, v80
	v_lshl_add_u64 v[80:81], v[80:81], 3, s[74:75]
	ds_read_b128 v[80:83], v140
	v_mad_u64_u32 v[100:101], s[0:1], v139, s26, v[128:129]
	v_cmp_lt_i32_e64 s[0:1], s27, v97
	v_mov_b32_e32 v101, v193
	s_waitcnt lgkmcnt(0)
	v_mul_f32_e32 v80, v84, v80
	ds_bpermute_b32 v84, v131, v80
	v_cndmask_b32_e64 v102, 16, v218, s[0:1]
	v_add_u32_e32 v102, v102, v104
	v_or_b32_e32 v102, v102, v143
	v_lshl_add_u64 v[100:101], v[100:101], 1, s[4:5]
	v_ashrrev_i32_e32 v103, 31, v102
	v_lshl_add_u64 v[102:103], v[102:103], 3, s[74:75]
	v_mul_f32_e32 v82, v86, v82
	ds_bpermute_b32 v86, v131, v82
	s_waitcnt lgkmcnt(1)
	s_waitcnt vmcnt(39)
	v_mul_f32_e32 v84, v229, v84
	v_cndmask_b32_e64 v84, v84, -v84, vcc
	v_fmac_f32_e32 v84, v80, v228
	v_cmp_lt_i32_e64 s[100:101],s33,v96
	s_nop 1
	v_cndmask_b32_e64 v236,32,v222,s[100:101]
	v_add_u32_e32 v240,v236,v96
	v_cmp_lt_i32_e64 s[100:101],s30,v240
	s_nop 1
	v_cndmask_b32_e64 v242,8,v221,s[100:101]
	v_add_u32_e32 v244,v242,v240
	v_cmp_lt_i32_e64 s[100:101],s30,v244
	s_nop 1
	v_cndmask_b32_e64 v242,8,v221,s[100:101]
	v_add_u32_e32 v246,v242,v244
	v_lshlrev_b32_e32 v247,4,v246
	v_add_u32_e32 v242,0xfffeff00,v247
	v_cmp_lt_i32_e64 s[100:101],s31,v246
	s_nop 1
	v_cndmask_b32_e64 v242,v247,v242,s[100:101]
	v_or_b32_e32 v242,v242,v143
	v_ashrrev_i32_e32 v243,31,v242
	v_lshl_add_u64 v[242:243],v[242:243],3,s[74:75]
	global_load_dwordx2 v[228:229], v[242:243], off
	v_mul_f32_e32 v80, 0x3e16c740, v84
	v_cvt_pk_bf16_f32 v80, v80, s0
	global_store_short v[100:101], v80, off
	v_mul_f32_e32 v84, v85, v81
	ds_bpermute_b32 v85, v131, v84
	v_cmp_lt_i32_e64 s[0:1], s28, v97
	v_lshl_add_u64 v[100:101], v[192:193], 1, s[4:5]
	v_add_u32_e32 v192, 0xde00, v132
	v_cndmask_b32_e64 v80, 32, v219, s[0:1]
	v_add_u32_e32 v80, v80, v104
	v_or_b32_e32 v80, v80, v143
	v_ashrrev_i32_e32 v81, 31, v80
	v_lshl_add_u64 v[80:81], v[80:81], 3, s[74:75]
	s_waitcnt lgkmcnt(0)
	s_waitcnt vmcnt(39)
	v_mul_f32_e32 v85, v231, v85
	v_cndmask_b32_e64 v85, v85, -v85, vcc
	v_fmac_f32_e32 v85, v84, v230
	v_cmp_lt_i32_e64 s[100:101],s33,v96
	s_nop 1
	v_cndmask_b32_e64 v236,32,v222,s[100:101]
	v_add_u32_e32 v240,v236,v96
	v_cmp_lt_i32_e64 s[100:101],s30,v240
	s_nop 1
	v_cndmask_b32_e64 v242,8,v221,s[100:101]
	v_add_u32_e32 v244,v242,v240
	v_cmp_lt_i32_e64 s[100:101],s30,v244
	s_nop 1
	v_cndmask_b32_e64 v242,8,v221,s[100:101]
	v_add_u32_e32 v246,v242,v244
	v_lshlrev_b32_e32 v247,4,v246
	v_cmp_lt_i32_e64 s[100:101],s27,v246
	s_nop 1
	v_cndmask_b32_e64 v236,16,v218,s[100:101]
	v_add_u32_e32 v236,v236,v247
	v_or_b32_e32 v236,v236,v143
	v_ashrrev_i32_e32 v237,31,v236
	v_lshl_add_u64 v[236:237],v[236:237],3,s[74:75]
	global_load_dwordx2 v[230:231], v[236:237], off
	v_mul_f32_e32 v84, 0x3e16c740, v85
	v_cvt_pk_bf16_f32 v84, v84, s0
	global_store_short v[100:101], v84, off
	v_cmp_lt_i32_e64 s[0:1], s29, v97
	v_lshl_add_u64 v[84:85], v[192:193], 1, s[4:5]
	v_add_u32_e32 v192, 0xe100, v132
	v_cndmask_b32_e64 v98, 48, v220, s[0:1]
	v_add_u32_e32 v98, v98, v104
	v_or_b32_e32 v98, v98, v143
	v_ashrrev_i32_e32 v99, 31, v98
	v_lshl_add_u64 v[98:99], v[98:99], 3, s[74:75]
	s_waitcnt vmcnt(39)
	v_mul_f32_e32 v81, v233, v86
	v_cndmask_b32_e64 v81, v81, -v81, vcc
	v_fmac_f32_e32 v81, v82, v232
	v_cmp_lt_i32_e64 s[100:101],s33,v96
	s_nop 1
	v_cndmask_b32_e64 v236,32,v222,s[100:101]
	v_add_u32_e32 v240,v236,v96
	v_cmp_lt_i32_e64 s[100:101],s30,v240
	s_nop 1
	v_cndmask_b32_e64 v242,8,v221,s[100:101]
	v_add_u32_e32 v244,v242,v240
	v_cmp_lt_i32_e64 s[100:101],s30,v244
	s_nop 1
	v_cndmask_b32_e64 v242,8,v221,s[100:101]
	v_add_u32_e32 v246,v242,v244
	v_lshlrev_b32_e32 v247,4,v246
	v_cmp_lt_i32_e64 s[100:101],s28,v246
	s_nop 1
	v_cndmask_b32_e64 v242,32,v219,s[100:101]
	v_add_u32_e32 v242,v242,v247
	v_or_b32_e32 v242,v242,v143
	v_ashrrev_i32_e32 v243,31,v242
	v_lshl_add_u64 v[242:243],v[242:243],3,s[74:75]
	global_load_dwordx2 v[232:233], v[242:243], off
	v_mul_f32_e32 v80, 0x3e16c740, v81
	v_cvt_pk_bf16_f32 v80, v80, s0
	global_store_short v[84:85], v80, off
	v_mul_f32_e32 v82, v87, v83
	ds_bpermute_b32 v83, v131, v82
	s_waitcnt lgkmcnt(0)
	s_waitcnt vmcnt(39)
	v_mul_f32_e32 v81, v235, v83
	v_cndmask_b32_e64 v81, v81, -v81, vcc
	v_fmac_f32_e32 v81, v82, v234
	v_mov_b32_e32 v243, v65
	v_cmp_lt_i32_e64 s[100:101],s33,v96
	s_nop 1
	v_cndmask_b32_e64 v236,32,v222,s[100:101]
	v_add_u32_e32 v240,v236,v96
	v_cmp_lt_i32_e64 s[100:101],s30,v240
	s_nop 1
	v_cndmask_b32_e64 v242,8,v221,s[100:101]
	v_add_u32_e32 v244,v242,v240
	v_cmp_lt_i32_e64 s[100:101],s30,v244
	s_nop 1
	v_cndmask_b32_e64 v242,8,v221,s[100:101]
	v_add_u32_e32 v246,v242,v244
	v_lshlrev_b32_e32 v247,4,v246
	v_cmp_lt_i32_e64 s[100:101],s29,v246
	s_nop 1
	v_cndmask_b32_e64 v248,48,v220,s[100:101]
	v_add_u32_e32 v248,v248,v247
	v_or_b32_e32 v248,v248,v143
	v_ashrrev_i32_e32 v249,31,v248
	v_lshl_add_u64 v[248:249],v[248:249],3,s[74:75]
	global_load_dwordx2 v[234:235], v[248:249], off
	v_mul_f32_e32 v80, 0x3e16c740, v81
	v_cvt_pk_bf16_f32 v82, v80, s0
	v_lshl_add_u64 v[80:81], v[192:193], 1, s[4:5]
	global_store_short v[80:81], v82, off
	v_cmp_lt_i32_e64 s[0:1], s30, v97
	v_add_u32_e32 v86, s8, v138
	v_add_u32_e32 v192, 0xf300, v132
	v_cndmask_b32_e64 v80, 8, v221, s[0:1]
	v_add_u32_e32 v97, v80, v97
	v_lshlrev_b32_e32 v100, 4, v97
	v_add_u32_e32 v80, 0xfffeff00, v100
	v_cmp_lt_i32_e64 s[0:1], s31, v97
	s_nop 1
	v_cndmask_b32_e64 v80, v100, v80, s[0:1]
	v_or_b32_e32 v80, v80, v143
	v_ashrrev_i32_e32 v81, 31, v80
	v_lshl_add_u64 v[80:81], v[80:81], 3, s[74:75]
	v_lshl_add_u32 v80, v138, 2, v214
	ds_read_b128 v[80:83], v80
	v_mad_u64_u32 v[86:87], s[0:1], v86, s26, v[128:129]
	v_cmp_lt_i32_e64 s[0:1], s27, v97
	v_mov_b32_e32 v87, v193
	s_waitcnt lgkmcnt(0)
	v_mul_f32_e32 v80, v88, v80
	ds_bpermute_b32 v88, v131, v80
	v_cndmask_b32_e64 v98, 16, v218, s[0:1]
	v_add_u32_e32 v98, v98, v100
	v_or_b32_e32 v98, v98, v143
	v_lshl_add_u64 v[86:87], v[86:87], 1, s[4:5]
	v_ashrrev_i32_e32 v99, 31, v98
	v_lshl_add_u64 v[98:99], v[98:99], 3, s[74:75]
	v_mul_f32_e32 v82, v90, v82
	s_waitcnt lgkmcnt(0)
	s_waitcnt vmcnt(39)
	v_mul_f32_e32 v85, v175, v88
	v_cndmask_b32_e64 v85, v85, -v85, vcc
	v_fmac_f32_e32 v85, v80, v174
	v_cmp_lt_i32_e64 s[100:101],s33,v96
	s_nop 1
	v_cndmask_b32_e64 v236,32,v222,s[100:101]
	v_add_u32_e32 v240,v236,v96
	v_cmp_lt_i32_e64 s[100:101],s30,v240
	s_nop 1
	v_cndmask_b32_e64 v242,8,v221,s[100:101]
	v_add_u32_e32 v244,v242,v240
	v_cmp_lt_i32_e64 s[100:101],s30,v244
	s_nop 1
	v_cndmask_b32_e64 v242,8,v221,s[100:101]
	v_add_u32_e32 v246,v242,v244
	v_cmp_lt_i32_e64 s[100:101],s30,v246
	s_nop 1
	v_cndmask_b32_e64 v242,8,v221,s[100:101]
	v_add_u32_e32 v248,v242,v246
	v_lshlrev_b32_e32 v249,4,v248
	v_add_u32_e32 v242,0xfffeff00,v249
	v_cmp_lt_i32_e64 s[100:101],s31,v248
	s_nop 1
	v_cndmask_b32_e64 v242,v249,v242,s[100:101]
	v_or_b32_e32 v242,v242,v143
	v_ashrrev_i32_e32 v243,31,v242
	v_lshl_add_u64 v[242:243],v[242:243],3,s[74:75]
	global_load_dwordx2 v[174:175], v[242:243], off
	v_mul_f32_e32 v80, 0x3e16c740, v85
	v_cvt_pk_bf16_f32 v80, v80, s0
	global_store_short v[86:87], v80, off
	v_mul_f32_e32 v88, v89, v81
	ds_bpermute_b32 v89, v131, v88
	v_cmp_lt_i32_e64 s[0:1], s28, v97
	v_lshl_add_u64 v[86:87], v[192:193], 1, s[4:5]
	v_add_u32_e32 v192, 0xf600, v132
	v_cndmask_b32_e64 v80, 32, v219, s[0:1]
	v_add_u32_e32 v80, v80, v100
	v_or_b32_e32 v80, v80, v143
	v_ashrrev_i32_e32 v81, 31, v80
	v_lshl_add_u64 v[80:81], v[80:81], 3, s[74:75]
	s_waitcnt lgkmcnt(0)
	s_waitcnt vmcnt(39)
	v_mul_f32_e32 v85, v177, v89
	v_cndmask_b32_e64 v85, v85, -v85, vcc
	v_fmac_f32_e32 v85, v88, v176
	v_cmp_lt_i32_e64 s[100:101],s33,v96
	s_nop 1
	v_cndmask_b32_e64 v236,32,v222,s[100:101]
	v_add_u32_e32 v240,v236,v96
	v_cmp_lt_i32_e64 s[100:101],s30,v240
	s_nop 1
	v_cndmask_b32_e64 v242,8,v221,s[100:101]
	v_add_u32_e32 v244,v242,v240
	v_cmp_lt_i32_e64 s[100:101],s30,v244
	s_nop 1
	v_cndmask_b32_e64 v242,8,v221,s[100:101]
	v_add_u32_e32 v246,v242,v244
	v_cmp_lt_i32_e64 s[100:101],s30,v246
	s_nop 1
	v_cndmask_b32_e64 v242,8,v221,s[100:101]
	v_add_u32_e32 v248,v242,v246
	v_lshlrev_b32_e32 v249,4,v248
	v_cmp_lt_i32_e64 s[100:101],s27,v248
	s_nop 1
	v_cndmask_b32_e64 v250,16,v218,s[100:101]
	v_add_u32_e32 v250,v250,v249
	v_or_b32_e32 v250,v250,v143
	v_ashrrev_i32_e32 v251,31,v250
	v_lshl_add_u64 v[250:251],v[250:251],3,s[74:75]
	global_load_dwordx2 v[176:177], v[250:251], off
	v_mul_f32_e32 v84, 0x3e16c740, v85
	v_cvt_pk_bf16_f32 v84, v84, s0
	global_store_short v[86:87], v84, off
	ds_bpermute_b32 v88, v131, v82
	v_cmp_lt_i32_e64 s[0:1], s29, v97
	v_lshl_add_u64 v[84:85], v[192:193], 1, s[4:5]
	v_add_u32_e32 v192, 0xf900, v132
	v_cndmask_b32_e64 v86, 48, v220, s[0:1]
	v_add_u32_e32 v86, v86, v100
	v_or_b32_e32 v86, v86, v143
	v_ashrrev_i32_e32 v87, 31, v86
	v_lshl_add_u64 v[86:87], v[86:87], 3, s[74:75]
	s_waitcnt lgkmcnt(0)
	s_waitcnt vmcnt(39)
	v_mul_f32_e32 v81, v179, v88
	v_cndmask_b32_e64 v81, v81, -v81, vcc
	v_fmac_f32_e32 v81, v82, v178
	v_cmp_lt_i32_e64 s[100:101],s33,v96
	s_nop 1
	v_cndmask_b32_e64 v236,32,v222,s[100:101]
	v_add_u32_e32 v240,v236,v96
	v_cmp_lt_i32_e64 s[100:101],s30,v240
	s_nop 1
	v_cndmask_b32_e64 v242,8,v221,s[100:101]
	v_add_u32_e32 v244,v242,v240
	v_cmp_lt_i32_e64 s[100:101],s30,v244
	s_nop 1
	v_cndmask_b32_e64 v242,8,v221,s[100:101]
	v_add_u32_e32 v246,v242,v244
	v_cmp_lt_i32_e64 s[100:101],s30,v246
	s_nop 1
	v_cndmask_b32_e64 v242,8,v221,s[100:101]
	v_add_u32_e32 v248,v242,v246
	v_lshlrev_b32_e32 v249,4,v248
	v_cmp_lt_i32_e64 s[100:101],s28,v248
	s_nop 1
	v_cndmask_b32_e64 v242,32,v219,s[100:101]
	v_add_u32_e32 v242,v242,v249
	v_or_b32_e32 v242,v242,v143
	v_ashrrev_i32_e32 v243,31,v242
	v_lshl_add_u64 v[242:243],v[242:243],3,s[74:75]
	global_load_dwordx2 v[178:179], v[242:243], off
	v_mul_f32_e32 v80, 0x3e16c740, v81
	v_cvt_pk_bf16_f32 v80, v80, s0
	global_store_short v[84:85], v80, off
	v_mul_f32_e32 v82, v91, v83
	ds_bpermute_b32 v83, v131, v82
	s_waitcnt lgkmcnt(0)
	s_waitcnt vmcnt(39)
	v_mul_f32_e32 v81, v181, v83
	v_cndmask_b32_e64 v81, v81, -v81, vcc
	v_fmac_f32_e32 v81, v82, v180
	v_mov_b32_e32 v243, v65
	v_cmp_lt_i32_e64 s[100:101],s33,v96
	s_nop 1
	v_cndmask_b32_e64 v236,32,v222,s[100:101]
	v_add_u32_e32 v240,v236,v96
	v_cmp_lt_i32_e64 s[100:101],s30,v240
	s_nop 1
	v_cndmask_b32_e64 v242,8,v221,s[100:101]
	v_add_u32_e32 v244,v242,v240
	v_cmp_lt_i32_e64 s[100:101],s30,v244
	s_nop 1
	v_cndmask_b32_e64 v242,8,v221,s[100:101]
	v_add_u32_e32 v246,v242,v244
	v_cmp_lt_i32_e64 s[100:101],s30,v246
	s_nop 1
	v_cndmask_b32_e64 v242,8,v221,s[100:101]
	v_add_u32_e32 v248,v242,v246
	v_lshlrev_b32_e32 v249,4,v248
	v_cmp_lt_i32_e64 s[100:101],s29,v248
	s_nop 1
	v_cndmask_b32_e64 v250,48,v220,s[100:101]
	v_add_u32_e32 v250,v250,v249
	v_or_b32_e32 v250,v250,v143
	v_ashrrev_i32_e32 v251,31,v250
	v_lshl_add_u64 v[250:251],v[250:251],3,s[74:75]
	global_load_dwordx2 v[180:181], v[250:251], off
	v_mul_f32_e32 v80, 0x3e16c740, v81
	v_cvt_pk_bf16_f32 v82, v80, s0
	v_lshl_add_u64 v[80:81], v[192:193], 1, s[4:5]
	global_store_short v[80:81], v82, off
	v_cmp_lt_i32_e64 s[0:1], s30, v97
	v_add_u32_e32 v86, s8, v137
	v_add_u32_e32 v192, 0x10b00, v132
	v_cndmask_b32_e64 v80, 8, v221, s[0:1]
	v_add_u32_e32 v90, v80, v97
	v_lshlrev_b32_e32 v91, 4, v90
	v_add_u32_e32 v80, 0xfffeff00, v91
	v_cmp_lt_i32_e64 s[0:1], s31, v90
	s_nop 1
	v_cndmask_b32_e64 v80, v91, v80, s[0:1]
	v_or_b32_e32 v80, v80, v143
	v_ashrrev_i32_e32 v81, 31, v80
	v_lshl_add_u64 v[80:81], v[80:81], 3, s[74:75]
	v_lshl_add_u32 v80, v137, 2, v214
	ds_read_b128 v[80:83], v80
	v_mad_u64_u32 v[86:87], s[0:1], v86, s26, v[128:129]
	v_cmp_lt_i32_e64 s[0:1], s27, v90
	v_mov_b32_e32 v87, v193
	s_waitcnt lgkmcnt(0)
	v_mul_f32_e32 v80, v92, v80
	ds_bpermute_b32 v92, v131, v80
	v_cndmask_b32_e64 v88, 16, v218, s[0:1]
	v_add_u32_e32 v88, v88, v91
	v_or_b32_e32 v88, v88, v143
	v_lshl_add_u64 v[86:87], v[86:87], 1, s[4:5]
	v_ashrrev_i32_e32 v89, 31, v88
	v_lshl_add_u64 v[88:89], v[88:89], 3, s[74:75]
	v_mul_f32_e32 v82, v94, v82
	s_waitcnt lgkmcnt(0)
	s_waitcnt vmcnt(39)
	v_mul_f32_e32 v85, v183, v92
	v_cndmask_b32_e64 v85, v85, -v85, vcc
	v_fmac_f32_e32 v85, v80, v182
	v_mul_f32_e32 v80, 0x3e16c740, v85
	v_cvt_pk_bf16_f32 v80, v80, s0
	global_store_short v[86:87], v80, off
	v_mul_f32_e32 v88, v93, v81
	ds_bpermute_b32 v89, v131, v88
	v_cmp_lt_i32_e64 s[0:1], s28, v90
	v_lshl_add_u64 v[86:87], v[192:193], 1, s[4:5]
	v_add_u32_e32 v192, 0x10e00, v132
	v_cndmask_b32_e64 v80, 32, v219, s[0:1]
	v_add_u32_e32 v80, v80, v91
	v_or_b32_e32 v80, v80, v143
	v_ashrrev_i32_e32 v81, 31, v80
	v_lshl_add_u64 v[80:81], v[80:81], 3, s[74:75]
	s_waitcnt lgkmcnt(0)
	s_waitcnt vmcnt(38)
	v_mul_f32_e32 v85, v185, v89
	v_cndmask_b32_e64 v85, v85, -v85, vcc
	v_fmac_f32_e32 v85, v88, v184
	v_mul_f32_e32 v84, 0x3e16c740, v85
	v_cvt_pk_bf16_f32 v84, v84, s0
	global_store_short v[86:87], v84, off
	ds_bpermute_b32 v88, v131, v82
	v_cmp_lt_i32_e64 s[0:1], s29, v90
	v_lshl_add_u64 v[84:85], v[192:193], 1, s[4:5]
	v_add_u32_e32 v192, 0x11100, v132
	v_cndmask_b32_e64 v86, 48, v220, s[0:1]
	v_add_u32_e32 v86, v86, v91
	v_or_b32_e32 v86, v86, v143
	v_ashrrev_i32_e32 v87, 31, v86
	v_lshl_add_u64 v[86:87], v[86:87], 3, s[74:75]
	s_waitcnt lgkmcnt(0)
	s_waitcnt vmcnt(37)
	v_mul_f32_e32 v81, v187, v88
	v_cndmask_b32_e64 v81, v81, -v81, vcc
	v_fmac_f32_e32 v81, v82, v186
	v_mul_f32_e32 v80, 0x3e16c740, v81
	v_cvt_pk_bf16_f32 v80, v80, s0
	global_store_short v[84:85], v80, off
	v_mul_f32_e32 v82, v95, v83
	ds_bpermute_b32 v83, v131, v82
	s_waitcnt lgkmcnt(0)
	s_waitcnt vmcnt(36)
	v_mul_f32_e32 v81, v189, v83
	v_cndmask_b32_e64 v81, v81, -v81, vcc
	v_fmac_f32_e32 v81, v82, v188
	v_mul_f32_e32 v80, 0x3e16c740, v81
	v_cvt_pk_bf16_f32 v82, v80, s0
	v_lshl_add_u64 v[80:81], v[192:193], 1, s[4:5]
	global_store_short v[80:81], v82, off
	v_cmp_lt_i32_e64 s[0:1], s33, v96
	v_add_u32_e32 v86, s8, v136
	v_add_u32_e32 v192, 0x12300, v132
	v_cndmask_b32_e64 v80, 32, v222, s[0:1]
	v_add_u32_e32 v90, v80, v96
	v_lshlrev_b32_e32 v91, 4, v90
	v_add_u32_e32 v80, 0xfffeff00, v91
	v_cmp_lt_i32_e64 s[0:1], s31, v90
	s_nop 1
	v_cndmask_b32_e64 v80, v91, v80, s[0:1]
	v_or_b32_e32 v80, v80, v143
	v_ashrrev_i32_e32 v81, 31, v80
	v_lshl_add_u64 v[80:81], v[80:81], 3, s[74:75]
	v_lshl_add_u32 v80, v136, 2, v214
	ds_read_b128 v[80:83], v80
	v_mad_u64_u32 v[86:87], s[0:1], v86, s26, v[128:129]
	v_cmp_lt_i32_e64 s[0:1], s27, v90
	v_mov_b32_e32 v87, v193
	s_waitcnt lgkmcnt(0)
	v_mul_f32_e32 v64, v64, v80
	ds_bpermute_b32 v80, v131, v64
	v_cndmask_b32_e64 v88, 16, v218, s[0:1]
	v_add_u32_e32 v88, v88, v91
	v_or_b32_e32 v88, v88, v143
	v_lshl_add_u64 v[86:87], v[86:87], 1, s[4:5]
	v_ashrrev_i32_e32 v89, 31, v88
	v_lshl_add_u64 v[88:89], v[88:89], 3, s[74:75]
	v_mul_f32_e32 v66, v66, v82
	ds_bpermute_b32 v82, v131, v66
	s_waitcnt lgkmcnt(1)
	s_waitcnt vmcnt(35)
	v_mul_f32_e32 v80, v191, v80
	v_cndmask_b32_e64 v80, v80, -v80, vcc
	v_fmac_f32_e32 v80, v64, v190
	v_mul_f32_e32 v64, 0x3e16c740, v80
	v_cvt_pk_bf16_f32 v64, v64, s0
	global_store_short v[86:87], v64, off
	v_mul_f32_e32 v80, v65, v81
	ds_bpermute_b32 v81, v131, v80
	v_cmp_lt_i32_e64 s[0:1], s28, v90
	v_lshl_add_u64 v[86:87], v[192:193], 1, s[4:5]
	v_add_u32_e32 v192, 0x12600, v132
	v_cndmask_b32_e64 v64, 32, v219, s[0:1]
	v_add_u32_e32 v64, v64, v91
	v_or_b32_e32 v64, v64, v143
	v_ashrrev_i32_e32 v65, 31, v64
	v_lshl_add_u64 v[64:65], v[64:65], 3, s[74:75]
	s_waitcnt lgkmcnt(0)
	s_waitcnt vmcnt(34)
	v_mul_f32_e32 v81, v195, v81
	v_cndmask_b32_e64 v81, v81, -v81, vcc
	v_fmac_f32_e32 v81, v80, v194
	v_mul_f32_e32 v80, 0x3e16c740, v81
	v_cvt_pk_bf16_f32 v80, v80, s0
	global_store_short v[86:87], v80, off
	v_cmp_lt_i32_e64 s[0:1], s29, v90
	v_lshl_add_u64 v[80:81], v[192:193], 1, s[4:5]
	v_add_u32_e32 v192, 0x12900, v132
	v_cndmask_b32_e64 v84, 48, v220, s[0:1]
	v_add_u32_e32 v84, v84, v91
	v_or_b32_e32 v84, v84, v143
	v_ashrrev_i32_e32 v85, 31, v84
	v_lshl_add_u64 v[84:85], v[84:85], 3, s[74:75]
	s_waitcnt vmcnt(33)
	v_mul_f32_e32 v65, v197, v82
	v_cndmask_b32_e64 v65, v65, -v65, vcc
	v_fmac_f32_e32 v65, v66, v196
	v_mul_f32_e32 v64, 0x3e16c740, v65
	v_cvt_pk_bf16_f32 v64, v64, s0
	global_store_short v[80:81], v64, off
	v_mul_f32_e32 v66, v67, v83
	ds_bpermute_b32 v67, v131, v66
	s_waitcnt lgkmcnt(0)
	s_waitcnt vmcnt(32)
	v_mul_f32_e32 v65, v199, v67
	v_cndmask_b32_e64 v65, v65, -v65, vcc
	v_fmac_f32_e32 v65, v66, v198
	v_mul_f32_e32 v64, 0x3e16c740, v65
	v_cvt_pk_bf16_f32 v66, v64, s0
	v_lshl_add_u64 v[64:65], v[192:193], 1, s[4:5]
	global_store_short v[64:65], v66, off
	v_cmp_lt_i32_e64 s[0:1], s30, v90
	v_add_u32_e32 v82, s8, v135
	v_add_u32_e32 v192, 0x13b00, v132
	v_cndmask_b32_e64 v64, 8, v221, s[0:1]
	v_add_u32_e32 v86, v64, v90
	v_lshlrev_b32_e32 v87, 4, v86
	v_add_u32_e32 v64, 0xfffeff00, v87
	v_cmp_lt_i32_e64 s[0:1], s31, v86
	s_nop 1
	v_cndmask_b32_e64 v64, v87, v64, s[0:1]
	v_or_b32_e32 v64, v64, v143
	v_ashrrev_i32_e32 v65, 31, v64
	v_lshl_add_u64 v[64:65], v[64:65], 3, s[74:75]
	v_lshl_add_u32 v64, v135, 2, v214
	ds_read_b128 v[64:67], v64
	v_mad_u64_u32 v[82:83], s[0:1], v82, s26, v[128:129]
	v_cmp_lt_i32_e64 s[0:1], s27, v86
	v_mov_b32_e32 v83, v193
	s_waitcnt lgkmcnt(0)
	v_mul_f32_e32 v64, v68, v64
	ds_bpermute_b32 v68, v131, v64
	v_cndmask_b32_e64 v84, 16, v218, s[0:1]
	v_add_u32_e32 v84, v84, v87
	v_or_b32_e32 v84, v84, v143
	v_lshl_add_u64 v[82:83], v[82:83], 1, s[4:5]
	v_ashrrev_i32_e32 v85, 31, v84
	v_lshl_add_u64 v[84:85], v[84:85], 3, s[74:75]
	v_mul_f32_e32 v66, v70, v66
	ds_bpermute_b32 v70, v131, v66
	s_waitcnt lgkmcnt(1)
	s_waitcnt vmcnt(31)
	v_mul_f32_e32 v68, v205, v68
	v_cndmask_b32_e64 v68, v68, -v68, vcc
	v_fmac_f32_e32 v68, v64, v204
	v_mul_f32_e32 v64, 0x3e16c740, v68
	v_cvt_pk_bf16_f32 v64, v64, s0
	global_store_short v[82:83], v64, off
	v_mul_f32_e32 v68, v69, v65
	ds_bpermute_b32 v69, v131, v68
	v_cmp_lt_i32_e64 s[0:1], s28, v86
	v_lshl_add_u64 v[82:83], v[192:193], 1, s[4:5]
	v_add_u32_e32 v192, 0x13e00, v132
	v_cndmask_b32_e64 v64, 32, v219, s[0:1]
	v_add_u32_e32 v64, v64, v87
	v_or_b32_e32 v64, v64, v143
	v_ashrrev_i32_e32 v65, 31, v64
	v_lshl_add_u64 v[64:65], v[64:65], 3, s[74:75]
	s_waitcnt lgkmcnt(0)
	s_waitcnt vmcnt(30)
	v_mul_f32_e32 v69, v207, v69
	v_cndmask_b32_e64 v69, v69, -v69, vcc
	v_fmac_f32_e32 v69, v68, v206
	v_mul_f32_e32 v68, 0x3e16c740, v69
	v_cvt_pk_bf16_f32 v68, v68, s0
	global_store_short v[82:83], v68, off
	v_cmp_lt_i32_e64 s[0:1], s29, v86
	v_lshl_add_u64 v[68:69], v[192:193], 1, s[4:5]
	v_add_u32_e32 v192, 0x14100, v132
	v_cndmask_b32_e64 v80, 48, v220, s[0:1]
	v_add_u32_e32 v80, v80, v87
	v_or_b32_e32 v80, v80, v143
	v_ashrrev_i32_e32 v81, 31, v80
	v_lshl_add_u64 v[80:81], v[80:81], 3, s[74:75]
	s_waitcnt vmcnt(29)
	v_mul_f32_e32 v65, v225, v70
	v_cndmask_b32_e64 v65, v65, -v65, vcc
	v_fmac_f32_e32 v65, v66, v224
	v_mul_f32_e32 v64, 0x3e16c740, v65
	v_cvt_pk_bf16_f32 v64, v64, s0
	global_store_short v[68:69], v64, off
	v_mul_f32_e32 v66, v71, v67
	ds_bpermute_b32 v67, v131, v66
	s_waitcnt lgkmcnt(0)
	s_waitcnt vmcnt(28)
	v_mul_f32_e32 v65, v227, v67
	v_cndmask_b32_e64 v65, v65, -v65, vcc
	v_fmac_f32_e32 v65, v66, v226
	v_mul_f32_e32 v64, 0x3e16c740, v65
	v_cvt_pk_bf16_f32 v66, v64, s0
	v_lshl_add_u64 v[64:65], v[192:193], 1, s[4:5]
	global_store_short v[64:65], v66, off
	v_cmp_lt_i32_e64 s[0:1], s30, v86
	v_add_u32_e32 v70, s8, v134
	v_add_u32_e32 v192, 0x15300, v132
	v_cndmask_b32_e64 v64, 8, v221, s[0:1]
	v_add_u32_e32 v82, v64, v86
	v_lshlrev_b32_e32 v83, 4, v82
	v_add_u32_e32 v64, 0xfffeff00, v83
	v_cmp_lt_i32_e64 s[0:1], s31, v82
	s_nop 1
	v_cndmask_b32_e64 v64, v83, v64, s[0:1]
	v_or_b32_e32 v64, v64, v143
	v_ashrrev_i32_e32 v65, 31, v64
	v_lshl_add_u64 v[64:65], v[64:65], 3, s[74:75]
	v_lshl_add_u32 v64, v134, 2, v214
	ds_read_b128 v[64:67], v64
	v_mad_u64_u32 v[70:71], s[0:1], v70, s26, v[128:129]
	v_cmp_lt_i32_e64 s[0:1], s27, v82
	v_mov_b32_e32 v71, v193
	s_waitcnt lgkmcnt(0)
	v_mul_f32_e32 v64, v72, v64
	ds_bpermute_b32 v72, v131, v64
	v_cndmask_b32_e64 v80, 16, v218, s[0:1]
	v_add_u32_e32 v80, v80, v83
	v_or_b32_e32 v80, v80, v143
	v_lshl_add_u64 v[70:71], v[70:71], 1, s[4:5]
	v_ashrrev_i32_e32 v81, 31, v80
	v_lshl_add_u64 v[80:81], v[80:81], 3, s[74:75]
	v_mul_f32_e32 v66, v74, v66
	s_waitcnt lgkmcnt(0)
	s_waitcnt vmcnt(27)
	v_mul_f32_e32 v69, v229, v72
	v_cndmask_b32_e64 v69, v69, -v69, vcc
	v_fmac_f32_e32 v69, v64, v228
	v_mul_f32_e32 v64, 0x3e16c740, v69
	v_cvt_pk_bf16_f32 v64, v64, s0
	global_store_short v[70:71], v64, off
	v_mul_f32_e32 v72, v73, v65
	ds_bpermute_b32 v73, v131, v72
	v_cmp_lt_i32_e64 s[0:1], s28, v82
	v_lshl_add_u64 v[70:71], v[192:193], 1, s[4:5]
	v_add_u32_e32 v192, 0x15600, v132
	v_cndmask_b32_e64 v64, 32, v219, s[0:1]
	v_add_u32_e32 v64, v64, v83
	v_or_b32_e32 v64, v64, v143
	v_ashrrev_i32_e32 v65, 31, v64
	v_lshl_add_u64 v[64:65], v[64:65], 3, s[74:75]
	s_waitcnt lgkmcnt(0)
	s_waitcnt vmcnt(26)
	v_mul_f32_e32 v69, v231, v73
	v_cndmask_b32_e64 v69, v69, -v69, vcc
	v_fmac_f32_e32 v69, v72, v230
	v_mul_f32_e32 v68, 0x3e16c740, v69
	v_cvt_pk_bf16_f32 v68, v68, s0
	global_store_short v[70:71], v68, off
	ds_bpermute_b32 v72, v131, v66
	v_cmp_lt_i32_e64 s[0:1], s29, v82
	v_lshl_add_u64 v[68:69], v[192:193], 1, s[4:5]
	v_add_u32_e32 v192, 0x15900, v132
	v_cndmask_b32_e64 v70, 48, v220, s[0:1]
	v_add_u32_e32 v70, v70, v83
	v_or_b32_e32 v70, v70, v143
	v_ashrrev_i32_e32 v71, 31, v70
	v_lshl_add_u64 v[70:71], v[70:71], 3, s[74:75]
	s_waitcnt lgkmcnt(0)
	s_waitcnt vmcnt(25)
	v_mul_f32_e32 v65, v233, v72
	v_cndmask_b32_e64 v65, v65, -v65, vcc
	v_fmac_f32_e32 v65, v66, v232
	v_mul_f32_e32 v64, 0x3e16c740, v65
	v_cvt_pk_bf16_f32 v64, v64, s0
	global_store_short v[68:69], v64, off
	v_mul_f32_e32 v66, v75, v67
	ds_bpermute_b32 v67, v131, v66
	s_waitcnt lgkmcnt(0)
	s_waitcnt vmcnt(24)
	v_mul_f32_e32 v65, v235, v67
	v_cndmask_b32_e64 v65, v65, -v65, vcc
	v_fmac_f32_e32 v65, v66, v234
	v_mul_f32_e32 v64, 0x3e16c740, v65
	v_cvt_pk_bf16_f32 v66, v64, s0
	v_lshl_add_u64 v[64:65], v[192:193], 1, s[4:5]
	global_store_short v[64:65], v66, off
	v_cmp_lt_i32_e64 s[0:1], s30, v82
	v_add_u32_e32 v192, 0x16b00, v132
	s_nop 0
	v_cndmask_b32_e64 v64, 8, v221, s[0:1]
	v_add_u32_e32 v74, v64, v82
	v_lshlrev_b32_e32 v75, 4, v74
	v_add_u32_e32 v64, 0xfffeff00, v75
	v_cmp_lt_i32_e64 s[0:1], s31, v74
	s_nop 1
	v_cndmask_b32_e64 v64, v75, v64, s[0:1]
	v_or_b32_e32 v64, v64, v143
	v_ashrrev_i32_e32 v65, 31, v64
	v_lshl_add_u64 v[64:65], v[64:65], 3, s[74:75]
	v_or_b32_e32 v64, 0x78, v129
	v_add_u32_e32 v70, s8, v64
	v_lshl_add_u32 v64, v64, 2, v214
	ds_read_b128 v[64:67], v64
	v_mad_u64_u32 v[70:71], s[0:1], v70, s26, v[128:129]
	v_cmp_lt_i32_e64 s[0:1], s27, v74
	v_mov_b32_e32 v71, v193
	s_waitcnt lgkmcnt(0)
	v_mul_f32_e32 v64, v76, v64
	ds_bpermute_b32 v76, v131, v64
	v_cndmask_b32_e64 v72, 16, v218, s[0:1]
	v_add_u32_e32 v72, v72, v75
	v_or_b32_e32 v72, v72, v143
	v_lshl_add_u64 v[70:71], v[70:71], 1, s[4:5]
	v_ashrrev_i32_e32 v73, 31, v72
	v_lshl_add_u64 v[72:73], v[72:73], 3, s[74:75]
	v_mul_f32_e32 v66, v78, v66
	s_waitcnt lgkmcnt(0)
	s_waitcnt vmcnt(23)
	v_mul_f32_e32 v69, v175, v76
	v_cndmask_b32_e64 v69, v69, -v69, vcc
	v_fmac_f32_e32 v69, v64, v174
	v_mul_f32_e32 v64, 0x3e16c740, v69
	v_cvt_pk_bf16_f32 v64, v64, s0
	global_store_short v[70:71], v64, off
	v_mul_f32_e32 v72, v77, v65
	ds_bpermute_b32 v73, v131, v72
	v_cmp_lt_i32_e64 s[0:1], s28, v74
	v_lshl_add_u64 v[70:71], v[192:193], 1, s[4:5]
	v_add_u32_e32 v192, 0x16e00, v132
	v_cndmask_b32_e64 v64, 32, v219, s[0:1]
	v_add_u32_e32 v64, v64, v75
	v_or_b32_e32 v64, v64, v143
	v_ashrrev_i32_e32 v65, 31, v64
	v_lshl_add_u64 v[64:65], v[64:65], 3, s[74:75]
	s_waitcnt lgkmcnt(0)
	s_waitcnt vmcnt(22)
	v_mul_f32_e32 v69, v177, v73
	v_cndmask_b32_e64 v69, v69, -v69, vcc
	v_fmac_f32_e32 v69, v72, v176
	v_mul_f32_e32 v68, 0x3e16c740, v69
	v_cvt_pk_bf16_f32 v68, v68, s0
	global_store_short v[70:71], v68, off
	ds_bpermute_b32 v72, v131, v66
	v_cmp_lt_i32_e64 s[0:1], s29, v74
	v_lshl_add_u64 v[68:69], v[192:193], 1, s[4:5]
	v_add_u32_e32 v192, 0x17100, v132
	v_cndmask_b32_e64 v70, 48, v220, s[0:1]
	v_add_u32_e32 v70, v70, v75
	v_or_b32_e32 v70, v70, v143
	v_ashrrev_i32_e32 v71, 31, v70
	v_lshl_add_u64 v[70:71], v[70:71], 3, s[74:75]
	s_waitcnt lgkmcnt(0)
	s_waitcnt vmcnt(21)
	v_mul_f32_e32 v65, v179, v72
	v_cndmask_b32_e64 v65, v65, -v65, vcc
	v_fmac_f32_e32 v65, v66, v178
	v_mul_f32_e32 v64, 0x3e16c740, v65
	v_cvt_pk_bf16_f32 v64, v64, s0
	global_store_short v[68:69], v64, off
	v_mul_f32_e32 v66, v79, v67
	ds_bpermute_b32 v67, v131, v66
	s_waitcnt lgkmcnt(0)
	s_waitcnt vmcnt(20)
	v_mul_f32_e32 v65, v181, v67
	v_cndmask_b32_e64 v65, v65, -v65, vcc
	v_fmac_f32_e32 v65, v66, v180
	v_mul_f32_e32 v64, 0x3e16c740, v65
	v_cvt_pk_bf16_f32 v66, v64, s0
	v_lshl_add_u64 v[64:65], v[192:193], 1, s[4:5]
	global_store_short v[64:65], v66, off

.LBB0_3052:
	s_waitcnt vmcnt(0)
	v_ashrrev_i32_e32 v131, 31, v130
	v_lshl_add_u64 v[66:67], v[130:131], 3, s[74:75]
	global_load_dwordx2 v[174:175], v[66:67], off
	v_cmp_lt_i32_e64 s[100:101],s27,v162
	s_nop 1
	v_cndmask_b32_e64 v237,16,v218,s[100:101]
	v_add_u32_e32 v240,v237,v163
	v_or_b32_e32 v240,v240,v143
	v_ashrrev_i32_e32 v241,31,v240
	v_lshl_add_u64 v[240:241],v[240:241],3,s[74:75]
	global_load_dwordx2 v[176:177], v[240:241], off
	v_mov_b32_e32 v237, v49
	v_cmp_lt_i32_e64 s[100:101],s28,v162
	s_nop 1
	v_cndmask_b32_e64 v236,32,v219,s[100:101]
	v_add_u32_e32 v241,v236,v163
	v_or_b32_e32 v242,v241,v143
	v_ashrrev_i32_e32 v243,31,v242
	v_lshl_add_u64 v[242:243],v[242:243],3,s[74:75]
	global_load_dwordx2 v[178:179], v[242:243], off
	v_cmp_lt_i32_e64 s[100:101],s29,v162
	s_nop 1
	v_cndmask_b32_e64 v237,48,v220,s[100:101]
	v_add_u32_e32 v237,v237,v163
	v_or_b32_e32 v240,v237,v143
	v_ashrrev_i32_e32 v241,31,v240
	v_lshl_add_u64 v[240:241],v[240:241],3,s[74:75]
	global_load_dwordx2 v[180:181], v[240:241], off
	v_cmp_lt_i32_e64 s[100:101],s30,v162
	s_nop 1
	v_cndmask_b32_e64 v236,8,v221,s[100:101]
	v_add_u32_e32 v241,v236,v162
	v_lshlrev_b32_e32 v242,4,v241
	v_add_u32_e32 v236,0xfffeff00,v242
	v_cmp_lt_i32_e64 s[100:101],s31,v241
	s_nop 1
	v_cndmask_b32_e64 v236,v242,v236,s[100:101]
	v_or_b32_e32 v236,v236,v143
	v_ashrrev_i32_e32 v237,31,v236
	v_lshl_add_u64 v[236:237],v[236:237],3,s[74:75]
	global_load_dwordx2 v[182:183], v[236:237], off
	v_cmp_lt_i32_e64 s[100:101],s30,v162
	s_nop 1
	v_cndmask_b32_e64 v236,8,v221,s[100:101]
	v_add_u32_e32 v241,v236,v162
	v_lshlrev_b32_e32 v242,4,v241
	v_cmp_lt_i32_e64 s[100:101],s27,v241
	s_nop 1
	v_cndmask_b32_e64 v244,16,v218,s[100:101]
	v_add_u32_e32 v244,v244,v242
	v_or_b32_e32 v244,v244,v143
	v_ashrrev_i32_e32 v245,31,v244
	v_lshl_add_u64 v[244:245],v[244:245],3,s[74:75]
	global_load_dwordx2 v[184:185], v[244:245], off
	v_cmp_lt_i32_e64 s[100:101],s30,v162
	s_nop 1
	v_cndmask_b32_e64 v236,8,v221,s[100:101]
	v_add_u32_e32 v241,v236,v162
	v_lshlrev_b32_e32 v242,4,v241
	v_cmp_lt_i32_e64 s[100:101],s28,v241
	s_nop 1
	v_cndmask_b32_e64 v236,32,v219,s[100:101]
	v_add_u32_e32 v236,v236,v242
	v_or_b32_e32 v236,v236,v143
	v_ashrrev_i32_e32 v237,31,v236
	v_lshl_add_u64 v[236:237],v[236:237],3,s[74:75]
	global_load_dwordx2 v[186:187], v[236:237], off
	v_mov_b32_e32 v237, v49
	v_cmp_lt_i32_e64 s[100:101],s30,v162
	s_nop 1
	v_cndmask_b32_e64 v236,8,v221,s[100:101]
	v_add_u32_e32 v241,v236,v162
	v_lshlrev_b32_e32 v242,4,v241
	v_cmp_lt_i32_e64 s[100:101],s29,v241
	s_nop 1
	v_cndmask_b32_e64 v244,48,v220,s[100:101]
	v_add_u32_e32 v244,v244,v242
	v_or_b32_e32 v244,v244,v143
	v_ashrrev_i32_e32 v245,31,v244
	v_lshl_add_u64 v[244:245],v[244:245],3,s[74:75]
	global_load_dwordx2 v[188:189], v[244:245], off
	v_cmp_lt_i32_e64 s[100:101],s30,v162
	s_nop 1
	v_cndmask_b32_e64 v236,8,v221,s[100:101]
	v_add_u32_e32 v241,v236,v162
	v_cmp_lt_i32_e64 s[100:101],s30,v241
	s_nop 1
	v_cndmask_b32_e64 v236,8,v221,s[100:101]
	v_add_u32_e32 v241,v236,v241
	v_lshlrev_b32_e32 v242,4,v241
	v_add_u32_e32 v236,0xfffeff00,v242
	v_cmp_lt_i32_e64 s[100:101],s31,v241
	s_nop 1
	v_cndmask_b32_e64 v236,v242,v236,s[100:101]
	v_or_b32_e32 v236,v236,v143
	v_ashrrev_i32_e32 v237,31,v236
	v_lshl_add_u64 v[236:237],v[236:237],3,s[74:75]
	global_load_dwordx2 v[190:191], v[236:237], off
	v_cmp_lt_i32_e64 s[100:101],s30,v162
	s_nop 1
	v_cndmask_b32_e64 v236,8,v221,s[100:101]
	v_add_u32_e32 v241,v236,v162
	v_cmp_lt_i32_e64 s[100:101],s30,v241
	s_nop 1
	v_cndmask_b32_e64 v236,8,v221,s[100:101]
	v_add_u32_e32 v241,v236,v241
	v_lshlrev_b32_e32 v242,4,v241
	v_cmp_lt_i32_e64 s[100:101],s27,v241
	s_nop 1
	v_cndmask_b32_e64 v244,16,v218,s[100:101]
	v_add_u32_e32 v244,v244,v242
	v_or_b32_e32 v244,v244,v143
	v_ashrrev_i32_e32 v245,31,v244
	v_lshl_add_u64 v[244:245],v[244:245],3,s[74:75]
	global_load_dwordx2 v[194:195], v[244:245], off
	v_cmp_lt_i32_e64 s[100:101],s30,v162
	s_nop 1
	v_cndmask_b32_e64 v236,8,v221,s[100:101]
	v_add_u32_e32 v241,v236,v162
	v_cmp_lt_i32_e64 s[100:101],s30,v241
	s_nop 1
	v_cndmask_b32_e64 v236,8,v221,s[100:101]
	v_add_u32_e32 v241,v236,v241
	v_lshlrev_b32_e32 v242,4,v241
	v_cmp_lt_i32_e64 s[100:101],s28,v241
	s_nop 1
	v_cndmask_b32_e64 v236,32,v219,s[100:101]
	v_add_u32_e32 v236,v236,v242
	v_or_b32_e32 v236,v236,v143
	v_ashrrev_i32_e32 v237,31,v236
	v_lshl_add_u64 v[236:237],v[236:237],3,s[74:75]
	global_load_dwordx2 v[196:197], v[236:237], off
	v_mov_b32_e32 v237, v49
	v_cmp_lt_i32_e64 s[100:101],s30,v162
	s_nop 1
	v_cndmask_b32_e64 v236,8,v221,s[100:101]
	v_add_u32_e32 v241,v236,v162
	v_cmp_lt_i32_e64 s[100:101],s30,v241
	s_nop 1
	v_cndmask_b32_e64 v236,8,v221,s[100:101]
	v_add_u32_e32 v241,v236,v241
	v_lshlrev_b32_e32 v242,4,v241
	v_cmp_lt_i32_e64 s[100:101],s29,v241
	s_nop 1
	v_cndmask_b32_e64 v244,48,v220,s[100:101]
	v_add_u32_e32 v244,v244,v242
	v_or_b32_e32 v244,v244,v143
	v_ashrrev_i32_e32 v245,31,v244
	v_lshl_add_u64 v[244:245],v[244:245],3,s[74:75]
	global_load_dwordx2 v[198:199], v[244:245], off
	v_cmp_lt_i32_e64 s[100:101],s30,v162
	s_nop 1
	v_cndmask_b32_e64 v236,8,v221,s[100:101]
	v_add_u32_e32 v241,v236,v162
	v_cmp_lt_i32_e64 s[100:101],s30,v241
	s_nop 1
	v_cndmask_b32_e64 v236,8,v221,s[100:101]
	v_add_u32_e32 v241,v236,v241
	v_cmp_lt_i32_e64 s[100:101],s30,v241
	s_nop 1
	v_cndmask_b32_e64 v236,8,v221,s[100:101]
	v_add_u32_e32 v242,v236,v241
	v_lshlrev_b32_e32 v243,4,v242
	v_add_u32_e32 v236,0xfffeff00,v243
	v_cmp_lt_i32_e64 s[100:101],s31,v242
	s_nop 1
	v_cndmask_b32_e64 v236,v243,v236,s[100:101]
	v_or_b32_e32 v236,v236,v143
	v_ashrrev_i32_e32 v237,31,v236
	v_lshl_add_u64 v[236:237],v[236:237],3,s[74:75]
	global_load_dwordx2 v[204:205], v[236:237], off
	v_cmp_lt_i32_e64 s[100:101],s30,v162
	s_nop 1
	v_cndmask_b32_e64 v236,8,v221,s[100:101]
	v_add_u32_e32 v241,v236,v162
	v_cmp_lt_i32_e64 s[100:101],s30,v241
	s_nop 1
	v_cndmask_b32_e64 v236,8,v221,s[100:101]
	v_add_u32_e32 v241,v236,v241
	v_cmp_lt_i32_e64 s[100:101],s30,v241
	s_nop 1
	v_cndmask_b32_e64 v236,8,v221,s[100:101]
	v_add_u32_e32 v242,v236,v241
	v_lshlrev_b32_e32 v243,4,v242
	v_cmp_lt_i32_e64 s[100:101],s27,v242
	s_nop 1
	v_cndmask_b32_e64 v244,16,v218,s[100:101]
	v_add_u32_e32 v244,v244,v243
	v_or_b32_e32 v244,v244,v143
	v_ashrrev_i32_e32 v245,31,v244
	v_lshl_add_u64 v[244:245],v[244:245],3,s[74:75]
	global_load_dwordx2 v[206:207], v[244:245], off
	v_cmp_lt_i32_e64 s[100:101],s30,v162
	s_nop 1
	v_cndmask_b32_e64 v236,8,v221,s[100:101]
	v_add_u32_e32 v241,v236,v162
	v_cmp_lt_i32_e64 s[100:101],s30,v241
	s_nop 1
	v_cndmask_b32_e64 v236,8,v221,s[100:101]
	v_add_u32_e32 v241,v236,v241
	v_cmp_lt_i32_e64 s[100:101],s30,v241
	s_nop 1
	v_cndmask_b32_e64 v236,8,v221,s[100:101]
	v_add_u32_e32 v242,v236,v241
	v_lshlrev_b32_e32 v243,4,v242
	v_cmp_lt_i32_e64 s[100:101],s28,v242
	s_nop 1
	v_cndmask_b32_e64 v236,32,v219,s[100:101]
	v_add_u32_e32 v236,v236,v243
	v_or_b32_e32 v236,v236,v143
	v_ashrrev_i32_e32 v237,31,v236
	v_lshl_add_u64 v[236:237],v[236:237],3,s[74:75]
	global_load_dwordx2 v[224:225], v[236:237], off
	v_mov_b32_e32 v237, v49
	v_cmp_lt_i32_e64 s[100:101],s30,v162
	s_nop 1
	v_cndmask_b32_e64 v236,8,v221,s[100:101]
	v_add_u32_e32 v241,v236,v162
	v_cmp_lt_i32_e64 s[100:101],s30,v241
	s_nop 1
	v_cndmask_b32_e64 v236,8,v221,s[100:101]
	v_add_u32_e32 v241,v236,v241
	v_cmp_lt_i32_e64 s[100:101],s30,v241
	s_nop 1
	v_cndmask_b32_e64 v236,8,v221,s[100:101]
	v_add_u32_e32 v242,v236,v241
	v_lshlrev_b32_e32 v243,4,v242
	v_cmp_lt_i32_e64 s[100:101],s29,v242
	s_nop 1
	v_cndmask_b32_e64 v244,48,v220,s[100:101]
	v_add_u32_e32 v244,v244,v243
	v_or_b32_e32 v244,v244,v143
	v_ashrrev_i32_e32 v245,31,v244
	v_lshl_add_u64 v[244:245],v[244:245],3,s[74:75]
	global_load_dwordx2 v[226:227], v[244:245], off
	v_cmp_lt_i32_e64 s[100:101],s33,v162
	s_nop 1
	v_cndmask_b32_e64 v236,32,v222,s[100:101]
	v_add_u32_e32 v236,v236,v162
	v_lshlrev_b32_e32 v237,4,v236
	v_add_u32_e32 v240,0xfffeff00,v237
	v_cmp_lt_i32_e64 s[100:101],s31,v236
	s_nop 1
	v_cndmask_b32_e64 v240,v237,v240,s[100:101]
	v_or_b32_e32 v240,v240,v143
	v_ashrrev_i32_e32 v241,31,v240
	v_lshl_add_u64 v[240:241],v[240:241],3,s[74:75]
	global_load_dwordx2 v[228:229], v[240:241], off
	v_cmp_lt_i32_e64 s[100:101],s33,v162
	s_nop 1
	v_cndmask_b32_e64 v236,32,v222,s[100:101]
	v_add_u32_e32 v236,v236,v162
	v_lshlrev_b32_e32 v237,4,v236
	v_cmp_lt_i32_e64 s[100:101],s27,v236
	s_nop 1
	v_cndmask_b32_e64 v240,16,v218,s[100:101]
	v_add_u32_e32 v240,v240,v237
	v_or_b32_e32 v240,v240,v143
	v_ashrrev_i32_e32 v241,31,v240
	v_lshl_add_u64 v[240:241],v[240:241],3,s[74:75]
	global_load_dwordx2 v[230:231], v[240:241], off
	v_cmp_lt_i32_e64 s[100:101],s33,v162
	s_nop 1
	v_cndmask_b32_e64 v236,32,v222,s[100:101]
	v_add_u32_e32 v236,v236,v162
	v_lshlrev_b32_e32 v237,4,v236
	v_cmp_lt_i32_e64 s[100:101],s28,v236
	s_nop 1
	v_cndmask_b32_e64 v240,32,v219,s[100:101]
	v_add_u32_e32 v240,v240,v237
	v_or_b32_e32 v240,v240,v143
	v_ashrrev_i32_e32 v241,31,v240
	v_lshl_add_u64 v[240:241],v[240:241],3,s[74:75]
	global_load_dwordx2 v[232:233], v[240:241], off
	v_cmp_lt_i32_e64 s[100:101],s33,v162
	s_nop 1
	v_cndmask_b32_e64 v236,32,v222,s[100:101]
	v_add_u32_e32 v236,v236,v162
	v_lshlrev_b32_e32 v237,4,v236
	v_cmp_lt_i32_e64 s[100:101],s29,v236
	s_nop 1
	v_cndmask_b32_e64 v240,48,v220,s[100:101]
	v_add_u32_e32 v237,v240,v237
	v_or_b32_e32 v240,v237,v143
	v_ashrrev_i32_e32 v241,31,v240
	v_lshl_add_u64 v[240:241],v[240:241],3,s[74:75]
	global_load_dwordx2 v[234:235], v[240:241], off
	v_xor_b32_e32 v65, 16, v217
	ds_read_b128 v[68:71], v159
	v_and_b32_e32 v74, 64, v217
	v_mad_u64_u32 v[66:67], s[0:1], v158, s26, v[64:65]
	v_cmp_lt_i32_e64 s[0:1], s27, v162
	v_add_u32_e32 v74, 64, v74
	s_waitcnt lgkmcnt(0)
	v_mul_f32_e32 v48, v48, v68
	v_cndmask_b32_e64 v75, 16, v218, s[0:1]
	v_cmp_lt_i32_e64 s[0:1], v65, v74
	v_mov_b32_e32 v67, v193
	v_add_u32_e32 v76, v75, v163
	v_cndmask_b32_e64 v65, v217, v65, s[0:1]
	v_lshlrev_b32_e32 v65, 2, v65
	ds_bpermute_b32 v68, v65, v48
	v_lshl_add_u64 v[74:75], v[66:67], 1, s[4:5]
	v_or_b32_e32 v76, v76, v143
	v_ashrrev_i32_e32 v77, 31, v76
	v_lshl_add_u64 v[76:77], v[76:77], 3, s[74:75]
	v_add_u32_e32 v192, 0x300, v66
	v_mul_f32_e32 v50, v50, v70
	ds_bpermute_b32 v70, v65, v50
	s_waitcnt lgkmcnt(1)
	s_waitcnt vmcnt(19)
	v_mul_f32_e32 v67, v175, v68
	v_cndmask_b32_e64 v67, v67, -v67, vcc
	v_fmac_f32_e32 v67, v48, v174
	v_cmp_lt_i32_e64 s[100:101],s33,v162
	s_nop 1
	v_cndmask_b32_e64 v236,32,v222,s[100:101]
	v_add_u32_e32 v236,v236,v162
	v_cmp_lt_i32_e64 s[100:101],s30,v236
	s_nop 1
	v_cndmask_b32_e64 v240,8,v221,s[100:101]
	v_add_u32_e32 v237,v240,v236
	v_lshlrev_b32_e32 v242,4,v237
	v_add_u32_e32 v240,0xfffeff00,v242
	v_cmp_lt_i32_e64 s[100:101],s31,v237
	s_nop 1
	v_cndmask_b32_e64 v240,v242,v240,s[100:101]
	v_or_b32_e32 v240,v240,v143
	v_ashrrev_i32_e32 v241,31,v240
	v_lshl_add_u64 v[240:241],v[240:241],3,s[74:75]
	global_load_dwordx2 v[174:175], v[240:241], off
	v_mul_f32_e32 v48, 0x3e16c740, v67
	v_cvt_pk_bf16_f32 v48, v48, s0
	global_store_short v[74:75], v48, off
	v_mul_f32_e32 v74, v49, v69
	ds_bpermute_b32 v75, v65, v74
	v_cmp_lt_i32_e64 s[0:1], s28, v162
	s_nop 1
	v_cndmask_b32_e64 v48, 32, v219, s[0:1]
	v_add_u32_e32 v67, v48, v163
	v_or_b32_e32 v68, v67, v143
	v_lshl_add_u64 v[48:49], v[192:193], 1, s[4:5]
	v_ashrrev_i32_e32 v69, 31, v68
	v_lshl_add_u64 v[68:69], v[68:69], 3, s[74:75]
	v_add_u32_e32 v192, 0x600, v66
	s_waitcnt lgkmcnt(0)
	s_waitcnt vmcnt(20)
	v_mul_f32_e32 v67, v177, v75
	v_cndmask_b32_e64 v67, v67, -v67, vcc
	v_fmac_f32_e32 v67, v74, v176
	v_cmp_lt_i32_e64 s[100:101],s33,v162
	s_nop 1
	v_cndmask_b32_e64 v236,32,v222,s[100:101]
	v_add_u32_e32 v236,v236,v162
	v_cmp_lt_i32_e64 s[100:101],s30,v236
	s_nop 1
	v_cndmask_b32_e64 v240,8,v221,s[100:101]
	v_add_u32_e32 v237,v240,v236
	v_lshlrev_b32_e32 v242,4,v237
	v_cmp_lt_i32_e64 s[100:101],s27,v237
	s_nop 1
	v_cndmask_b32_e64 v244,16,v218,s[100:101]
	v_add_u32_e32 v244,v244,v242
	v_or_b32_e32 v244,v244,v143
	v_ashrrev_i32_e32 v245,31,v244
	v_lshl_add_u64 v[244:245],v[244:245],3,s[74:75]
	global_load_dwordx2 v[176:177], v[244:245], off
	v_mul_f32_e32 v67, 0x3e16c740, v67
	v_cvt_pk_bf16_f32 v67, v67, s0
	global_store_short v[48:49], v67, off
	v_cmp_lt_i32_e64 s[0:1], s29, v162
	v_lshl_add_u64 v[72:73], v[192:193], 1, s[4:5]
	v_add_u32_e32 v192, 0x900, v66
	v_cndmask_b32_e64 v67, 48, v220, s[0:1]
	v_add_u32_e32 v67, v67, v163
	v_or_b32_e32 v68, v67, v143
	v_ashrrev_i32_e32 v69, 31, v68
	v_lshl_add_u64 v[68:69], v[68:69], 3, s[74:75]
	s_waitcnt vmcnt(21)
	v_mul_f32_e32 v49, v179, v70
	v_cndmask_b32_e64 v49, v49, -v49, vcc
	v_fmac_f32_e32 v49, v50, v178
	v_cmp_lt_i32_e64 s[100:101],s33,v162
	s_nop 1
	v_cndmask_b32_e64 v236,32,v222,s[100:101]
	v_add_u32_e32 v236,v236,v162
	v_cmp_lt_i32_e64 s[100:101],s30,v236
	s_nop 1
	v_cndmask_b32_e64 v240,8,v221,s[100:101]
	v_add_u32_e32 v237,v240,v236
	v_lshlrev_b32_e32 v242,4,v237
	v_cmp_lt_i32_e64 s[100:101],s28,v237
	s_nop 1
	v_cndmask_b32_e64 v240,32,v219,s[100:101]
	v_add_u32_e32 v240,v240,v242
	v_or_b32_e32 v240,v240,v143
	v_ashrrev_i32_e32 v241,31,v240
	v_lshl_add_u64 v[240:241],v[240:241],3,s[74:75]
	global_load_dwordx2 v[178:179], v[240:241], off
	v_mul_f32_e32 v48, 0x3e16c740, v49
	v_cvt_pk_bf16_f32 v48, v48, s0
	global_store_short v[72:73], v48, off
	v_mul_f32_e32 v50, v51, v71
	ds_bpermute_b32 v51, v65, v50
	s_waitcnt lgkmcnt(0)
	s_waitcnt vmcnt(22)
	v_mul_f32_e32 v49, v181, v51
	v_cndmask_b32_e64 v49, v49, -v49, vcc
	v_fmac_f32_e32 v49, v50, v180
	v_mov_b32_e32 v241, v33
	v_cmp_lt_i32_e64 s[100:101],s33,v162
	s_nop 1
	v_cndmask_b32_e64 v236,32,v222,s[100:101]
	v_add_u32_e32 v236,v236,v162
	v_cmp_lt_i32_e64 s[100:101],s30,v236
	s_nop 1
	v_cndmask_b32_e64 v240,8,v221,s[100:101]
	v_add_u32_e32 v237,v240,v236
	v_lshlrev_b32_e32 v242,4,v237
	v_cmp_lt_i32_e64 s[100:101],s29,v237
	s_nop 1
	v_cndmask_b32_e64 v244,48,v220,s[100:101]
	v_add_u32_e32 v244,v244,v242
	v_or_b32_e32 v244,v244,v143
	v_ashrrev_i32_e32 v245,31,v244
	v_lshl_add_u64 v[244:245],v[244:245],3,s[74:75]
	global_load_dwordx2 v[180:181], v[244:245], off
	v_mul_f32_e32 v48, 0x3e16c740, v49
	v_cvt_pk_bf16_f32 v50, v48, s0
	v_lshl_add_u64 v[48:49], v[192:193], 1, s[4:5]
	global_store_short v[48:49], v50, off
	v_cmp_lt_i32_e64 s[0:1], s30, v162
	v_add_u32_e32 v192, 0x1b00, v66
	s_nop 0
	v_cndmask_b32_e64 v48, 8, v221, s[0:1]
	v_add_u32_e32 v67, v48, v162
	v_lshlrev_b32_e32 v74, 4, v67
	v_add_u32_e32 v48, 0xfffeff00, v74
	v_cmp_lt_i32_e64 s[0:1], s31, v67
	s_nop 1
	v_cndmask_b32_e64 v48, v74, v48, s[0:1]
	v_or_b32_e32 v48, v48, v143
	v_ashrrev_i32_e32 v49, 31, v48
	v_lshl_add_u64 v[48:49], v[48:49], 3, s[74:75]
	ds_read_b128 v[48:51], v157
	v_mad_u64_u32 v[70:71], s[0:1], v156, s26, v[64:65]
	v_cmp_lt_i32_e64 s[0:1], s27, v67
	v_mov_b32_e32 v71, v193
	s_waitcnt lgkmcnt(0)
	v_mul_f32_e32 v48, v52, v48
	ds_bpermute_b32 v52, v65, v48
	v_cndmask_b32_e64 v72, 16, v218, s[0:1]
	v_add_u32_e32 v72, v72, v74
	v_or_b32_e32 v72, v72, v143
	v_lshl_add_u64 v[70:71], v[70:71], 1, s[4:5]
	v_ashrrev_i32_e32 v73, 31, v72
	v_lshl_add_u64 v[72:73], v[72:73], 3, s[74:75]
	v_mul_f32_e32 v50, v54, v50
	ds_bpermute_b32 v54, v65, v50
	s_waitcnt lgkmcnt(1)
	s_waitcnt vmcnt(23)
	v_mul_f32_e32 v52, v183, v52
	v_cndmask_b32_e64 v52, v52, -v52, vcc
	v_fmac_f32_e32 v52, v48, v182
	v_cmp_lt_i32_e64 s[100:101],s33,v162
	s_nop 1
	v_cndmask_b32_e64 v236,32,v222,s[100:101]
	v_add_u32_e32 v236,v236,v162
	v_cmp_lt_i32_e64 s[100:101],s30,v236
	s_nop 1
	v_cndmask_b32_e64 v240,8,v221,s[100:101]
	v_add_u32_e32 v237,v240,v236
	v_cmp_lt_i32_e64 s[100:101],s30,v237
	s_nop 1
	v_cndmask_b32_e64 v240,8,v221,s[100:101]
	v_add_u32_e32 v237,v240,v237
	v_lshlrev_b32_e32 v242,4,v237
	v_add_u32_e32 v240,0xfffeff00,v242
	v_cmp_lt_i32_e64 s[100:101],s31,v237
	s_nop 1
	v_cndmask_b32_e64 v240,v242,v240,s[100:101]
	v_or_b32_e32 v240,v240,v143
	v_ashrrev_i32_e32 v241,31,v240
	v_lshl_add_u64 v[240:241],v[240:241],3,s[74:75]
	global_load_dwordx2 v[182:183], v[240:241], off
	v_mul_f32_e32 v48, 0x3e16c740, v52
	v_cvt_pk_bf16_f32 v48, v48, s0
	global_store_short v[70:71], v48, off
	v_mul_f32_e32 v52, v53, v49
	ds_bpermute_b32 v53, v65, v52
	v_cmp_lt_i32_e64 s[0:1], s28, v67
	v_lshl_add_u64 v[70:71], v[192:193], 1, s[4:5]
	v_add_u32_e32 v192, 0x1e00, v66
	v_cndmask_b32_e64 v48, 32, v219, s[0:1]
	v_add_u32_e32 v48, v48, v74
	v_or_b32_e32 v48, v48, v143
	v_ashrrev_i32_e32 v49, 31, v48
	v_lshl_add_u64 v[48:49], v[48:49], 3, s[74:75]
	s_waitcnt lgkmcnt(0)
	s_waitcnt vmcnt(24)
	v_mul_f32_e32 v53, v185, v53
	v_cndmask_b32_e64 v53, v53, -v53, vcc
	v_fmac_f32_e32 v53, v52, v184
	v_cmp_lt_i32_e64 s[100:101],s33,v162
	s_nop 1
	v_cndmask_b32_e64 v236,32,v222,s[100:101]
	v_add_u32_e32 v236,v236,v162
	v_cmp_lt_i32_e64 s[100:101],s30,v236
	s_nop 1
	v_cndmask_b32_e64 v240,8,v221,s[100:101]
	v_add_u32_e32 v237,v240,v236
	v_cmp_lt_i32_e64 s[100:101],s30,v237
	s_nop 1
	v_cndmask_b32_e64 v240,8,v221,s[100:101]
	v_add_u32_e32 v237,v240,v237
	v_lshlrev_b32_e32 v242,4,v237
	v_cmp_lt_i32_e64 s[100:101],s27,v237
	s_nop 1
	v_cndmask_b32_e64 v244,16,v218,s[100:101]
	v_add_u32_e32 v244,v244,v242
	v_or_b32_e32 v244,v244,v143
	v_ashrrev_i32_e32 v245,31,v244
	v_lshl_add_u64 v[244:245],v[244:245],3,s[74:75]
	global_load_dwordx2 v[184:185], v[244:245], off
	v_mul_f32_e32 v52, 0x3e16c740, v53
	v_cvt_pk_bf16_f32 v52, v52, s0
	global_store_short v[70:71], v52, off
	v_cmp_lt_i32_e64 s[0:1], s29, v67
	v_lshl_add_u64 v[52:53], v[192:193], 1, s[4:5]
	v_add_u32_e32 v192, 0x2100, v66
	v_cndmask_b32_e64 v68, 48, v220, s[0:1]
	v_add_u32_e32 v68, v68, v74
	v_or_b32_e32 v68, v68, v143
	v_ashrrev_i32_e32 v69, 31, v68
	v_lshl_add_u64 v[68:69], v[68:69], 3, s[74:75]
	s_waitcnt vmcnt(25)
	v_mul_f32_e32 v49, v187, v54
	v_cndmask_b32_e64 v49, v49, -v49, vcc
	v_fmac_f32_e32 v49, v50, v186
	v_cmp_lt_i32_e64 s[100:101],s33,v162
	s_nop 1
	v_cndmask_b32_e64 v236,32,v222,s[100:101]
	v_add_u32_e32 v236,v236,v162
	v_cmp_lt_i32_e64 s[100:101],s30,v236
	s_nop 1
	v_cndmask_b32_e64 v240,8,v221,s[100:101]
	v_add_u32_e32 v237,v240,v236
	v_cmp_lt_i32_e64 s[100:101],s30,v237
	s_nop 1
	v_cndmask_b32_e64 v240,8,v221,s[100:101]
	v_add_u32_e32 v237,v240,v237
	v_lshlrev_b32_e32 v242,4,v237
	v_cmp_lt_i32_e64 s[100:101],s28,v237
	s_nop 1
	v_cndmask_b32_e64 v240,32,v219,s[100:101]
	v_add_u32_e32 v240,v240,v242
	v_or_b32_e32 v240,v240,v143
	v_ashrrev_i32_e32 v241,31,v240
	v_lshl_add_u64 v[240:241],v[240:241],3,s[74:75]
	global_load_dwordx2 v[186:187], v[240:241], off
	v_mul_f32_e32 v48, 0x3e16c740, v49
	v_cvt_pk_bf16_f32 v48, v48, s0
	global_store_short v[52:53], v48, off
	v_mul_f32_e32 v50, v55, v51
	ds_bpermute_b32 v51, v65, v50
	s_waitcnt lgkmcnt(0)
	s_waitcnt vmcnt(26)
	v_mul_f32_e32 v49, v189, v51
	v_cndmask_b32_e64 v49, v49, -v49, vcc
	v_fmac_f32_e32 v49, v50, v188
	v_mov_b32_e32 v241, v33
	v_cmp_lt_i32_e64 s[100:101],s33,v162
	s_nop 1
	v_cndmask_b32_e64 v236,32,v222,s[100:101]
	v_add_u32_e32 v236,v236,v162
	v_cmp_lt_i32_e64 s[100:101],s30,v236
	s_nop 1
	v_cndmask_b32_e64 v240,8,v221,s[100:101]
	v_add_u32_e32 v237,v240,v236
	v_cmp_lt_i32_e64 s[100:101],s30,v237
	s_nop 1
	v_cndmask_b32_e64 v240,8,v221,s[100:101]
	v_add_u32_e32 v237,v240,v237
	v_lshlrev_b32_e32 v242,4,v237
	v_cmp_lt_i32_e64 s[100:101],s29,v237
	s_nop 1
	v_cndmask_b32_e64 v244,48,v220,s[100:101]
	v_add_u32_e32 v244,v244,v242
	v_or_b32_e32 v244,v244,v143
	v_ashrrev_i32_e32 v245,31,v244
	v_lshl_add_u64 v[244:245],v[244:245],3,s[74:75]
	global_load_dwordx2 v[188:189], v[244:245], off
	v_mul_f32_e32 v48, 0x3e16c740, v49
	v_cvt_pk_bf16_f32 v50, v48, s0
	v_lshl_add_u64 v[48:49], v[192:193], 1, s[4:5]
	global_store_short v[48:49], v50, off
	v_cmp_lt_i32_e64 s[0:1], s30, v67
	v_add_u32_e32 v192, 0x3300, v66
	s_nop 0
	v_cndmask_b32_e64 v48, 8, v221, s[0:1]
	v_add_u32_e32 v67, v48, v67
	v_lshlrev_b32_e32 v70, 4, v67
	v_add_u32_e32 v48, 0xfffeff00, v70
	v_cmp_lt_i32_e64 s[0:1], s31, v67
	s_nop 1
	v_cndmask_b32_e64 v48, v70, v48, s[0:1]
	v_or_b32_e32 v48, v48, v143
	v_ashrrev_i32_e32 v49, 31, v48
	v_lshl_add_u64 v[48:49], v[48:49], 3, s[74:75]
	ds_read_b128 v[48:51], v155
	v_mad_u64_u32 v[54:55], s[0:1], v154, s26, v[64:65]
	v_cmp_lt_i32_e64 s[0:1], s27, v67
	v_mov_b32_e32 v55, v193
	s_waitcnt lgkmcnt(0)
	v_mul_f32_e32 v48, v56, v48
	ds_bpermute_b32 v56, v65, v48
	v_cndmask_b32_e64 v68, 16, v218, s[0:1]
	v_add_u32_e32 v68, v68, v70
	v_or_b32_e32 v68, v68, v143
	v_lshl_add_u64 v[54:55], v[54:55], 1, s[4:5]
	v_ashrrev_i32_e32 v69, 31, v68
	v_lshl_add_u64 v[68:69], v[68:69], 3, s[74:75]
	v_mul_f32_e32 v50, v58, v50
	s_waitcnt lgkmcnt(0)
	s_waitcnt vmcnt(27)
	v_mul_f32_e32 v53, v191, v56
	v_cndmask_b32_e64 v53, v53, -v53, vcc
	v_fmac_f32_e32 v53, v48, v190
	v_cmp_lt_i32_e64 s[100:101],s33,v162
	s_nop 1
	v_cndmask_b32_e64 v236,32,v222,s[100:101]
	v_add_u32_e32 v236,v236,v162
	v_cmp_lt_i32_e64 s[100:101],s30,v236
	s_nop 1
	v_cndmask_b32_e64 v240,8,v221,s[100:101]
	v_add_u32_e32 v237,v240,v236
	v_cmp_lt_i32_e64 s[100:101],s30,v237
	s_nop 1
	v_cndmask_b32_e64 v240,8,v221,s[100:101]
	v_add_u32_e32 v237,v240,v237
	v_cmp_lt_i32_e64 s[100:101],s30,v237
	s_nop 1
	v_cndmask_b32_e64 v240,8,v221,s[100:101]
	v_add_u32_e32 v242,v240,v237
	v_lshlrev_b32_e32 v243,4,v242
	v_add_u32_e32 v240,0xfffeff00,v243
	v_cmp_lt_i32_e64 s[100:101],s31,v242
	s_nop 1
	v_cndmask_b32_e64 v240,v243,v240,s[100:101]
	v_or_b32_e32 v240,v240,v143
	v_ashrrev_i32_e32 v241,31,v240
	v_lshl_add_u64 v[240:241],v[240:241],3,s[74:75]
	global_load_dwordx2 v[190:191], v[240:241], off
	v_mul_f32_e32 v48, 0x3e16c740, v53
	v_cvt_pk_bf16_f32 v48, v48, s0
	global_store_short v[54:55], v48, off
	v_mul_f32_e32 v56, v57, v49
	ds_bpermute_b32 v57, v65, v56
	v_cmp_lt_i32_e64 s[0:1], s28, v67
	v_lshl_add_u64 v[54:55], v[192:193], 1, s[4:5]
	v_add_u32_e32 v192, 0x3600, v66
	v_cndmask_b32_e64 v48, 32, v219, s[0:1]
	v_add_u32_e32 v48, v48, v70
	v_or_b32_e32 v48, v48, v143
	v_ashrrev_i32_e32 v49, 31, v48
	v_lshl_add_u64 v[48:49], v[48:49], 3, s[74:75]
	s_waitcnt lgkmcnt(0)
	s_waitcnt vmcnt(28)
	v_mul_f32_e32 v53, v195, v57
	v_cndmask_b32_e64 v53, v53, -v53, vcc
	v_fmac_f32_e32 v53, v56, v194
	v_cmp_lt_i32_e64 s[100:101],s33,v162
	s_nop 1
	v_cndmask_b32_e64 v236,32,v222,s[100:101]
	v_add_u32_e32 v236,v236,v162
	v_cmp_lt_i32_e64 s[100:101],s30,v236
	s_nop 1
	v_cndmask_b32_e64 v240,8,v221,s[100:101]
	v_add_u32_e32 v237,v240,v236
	v_cmp_lt_i32_e64 s[100:101],s30,v237
	s_nop 1
	v_cndmask_b32_e64 v240,8,v221,s[100:101]
	v_add_u32_e32 v237,v240,v237
	v_cmp_lt_i32_e64 s[100:101],s30,v237
	s_nop 1
	v_cndmask_b32_e64 v240,8,v221,s[100:101]
	v_add_u32_e32 v242,v240,v237
	v_lshlrev_b32_e32 v243,4,v242
	v_cmp_lt_i32_e64 s[100:101],s27,v242
	s_nop 1
	v_cndmask_b32_e64 v244,16,v218,s[100:101]
	v_add_u32_e32 v244,v244,v243
	v_or_b32_e32 v244,v244,v143
	v_ashrrev_i32_e32 v245,31,v244
	v_lshl_add_u64 v[244:245],v[244:245],3,s[74:75]
	global_load_dwordx2 v[194:195], v[244:245], off
	v_mul_f32_e32 v52, 0x3e16c740, v53
	v_cvt_pk_bf16_f32 v52, v52, s0
	global_store_short v[54:55], v52, off
	ds_bpermute_b32 v56, v65, v50
	v_cmp_lt_i32_e64 s[0:1], s29, v67
	v_lshl_add_u64 v[52:53], v[192:193], 1, s[4:5]
	v_add_u32_e32 v192, 0x3900, v66
	v_cndmask_b32_e64 v54, 48, v220, s[0:1]
	v_add_u32_e32 v54, v54, v70
	v_or_b32_e32 v54, v54, v143
	v_ashrrev_i32_e32 v55, 31, v54
	v_lshl_add_u64 v[54:55], v[54:55], 3, s[74:75]
	s_waitcnt lgkmcnt(0)
	s_waitcnt vmcnt(29)
	v_mul_f32_e32 v49, v197, v56
	v_cndmask_b32_e64 v49, v49, -v49, vcc
	v_fmac_f32_e32 v49, v50, v196
	v_cmp_lt_i32_e64 s[100:101],s33,v162
	s_nop 1
	v_cndmask_b32_e64 v236,32,v222,s[100:101]
	v_add_u32_e32 v236,v236,v162
	v_cmp_lt_i32_e64 s[100:101],s30,v236
	s_nop 1
	v_cndmask_b32_e64 v240,8,v221,s[100:101]
	v_add_u32_e32 v237,v240,v236
	v_cmp_lt_i32_e64 s[100:101],s30,v237
	s_nop 1
	v_cndmask_b32_e64 v240,8,v221,s[100:101]
	v_add_u32_e32 v237,v240,v237
	v_cmp_lt_i32_e64 s[100:101],s30,v237
	s_nop 1
	v_cndmask_b32_e64 v240,8,v221,s[100:101]
	v_add_u32_e32 v242,v240,v237
	v_lshlrev_b32_e32 v243,4,v242
	v_cmp_lt_i32_e64 s[100:101],s28,v242
	s_nop 1
	v_cndmask_b32_e64 v240,32,v219,s[100:101]
	v_add_u32_e32 v240,v240,v243
	v_or_b32_e32 v240,v240,v143
	v_ashrrev_i32_e32 v241,31,v240
	v_lshl_add_u64 v[240:241],v[240:241],3,s[74:75]
	global_load_dwordx2 v[196:197], v[240:241], off
	v_mul_f32_e32 v48, 0x3e16c740, v49
	v_cvt_pk_bf16_f32 v48, v48, s0
	global_store_short v[52:53], v48, off
	v_mul_f32_e32 v50, v59, v51
	ds_bpermute_b32 v51, v65, v50
	s_waitcnt lgkmcnt(0)
	s_waitcnt vmcnt(30)
	v_mul_f32_e32 v49, v199, v51
	v_cndmask_b32_e64 v49, v49, -v49, vcc
	v_fmac_f32_e32 v49, v50, v198
	v_mov_b32_e32 v241, v33
	v_cmp_lt_i32_e64 s[100:101],s33,v162
	s_nop 1
	v_cndmask_b32_e64 v236,32,v222,s[100:101]
	v_add_u32_e32 v236,v236,v162
	v_cmp_lt_i32_e64 s[100:101],s30,v236
	s_nop 1
	v_cndmask_b32_e64 v240,8,v221,s[100:101]
	v_add_u32_e32 v237,v240,v236
	v_cmp_lt_i32_e64 s[100:101],s30,v237
	s_nop 1
	v_cndmask_b32_e64 v240,8,v221,s[100:101]
	v_add_u32_e32 v237,v240,v237
	v_cmp_lt_i32_e64 s[100:101],s30,v237
	s_nop 1
	v_cndmask_b32_e64 v240,8,v221,s[100:101]
	v_add_u32_e32 v242,v240,v237
	v_lshlrev_b32_e32 v243,4,v242
	v_cmp_lt_i32_e64 s[100:101],s29,v242
	s_nop 1
	v_cndmask_b32_e64 v244,48,v220,s[100:101]
	v_add_u32_e32 v244,v244,v243
	v_or_b32_e32 v244,v244,v143
	v_ashrrev_i32_e32 v245,31,v244
	v_lshl_add_u64 v[244:245],v[244:245],3,s[74:75]
	global_load_dwordx2 v[198:199], v[244:245], off
	v_mul_f32_e32 v48, 0x3e16c740, v49
	v_cvt_pk_bf16_f32 v50, v48, s0
	v_lshl_add_u64 v[48:49], v[192:193], 1, s[4:5]
	global_store_short v[48:49], v50, off
	v_cmp_lt_i32_e64 s[0:1], s30, v67
	v_add_u32_e32 v192, 0x4b00, v66
	s_nop 0
	v_cndmask_b32_e64 v48, 8, v221, s[0:1]
	v_add_u32_e32 v58, v48, v67
	v_lshlrev_b32_e32 v59, 4, v58
	v_add_u32_e32 v48, 0xfffeff00, v59
	v_cmp_lt_i32_e64 s[0:1], s31, v58
	s_nop 1
	v_cndmask_b32_e64 v48, v59, v48, s[0:1]
	v_or_b32_e32 v48, v48, v143
	v_ashrrev_i32_e32 v49, 31, v48
	v_lshl_add_u64 v[48:49], v[48:49], 3, s[74:75]
	ds_read_b128 v[48:51], v153
	v_mad_u64_u32 v[54:55], s[0:1], v152, s26, v[64:65]
	v_cmp_lt_i32_e64 s[0:1], s27, v58
	v_mov_b32_e32 v55, v193
	s_waitcnt lgkmcnt(0)
	v_mul_f32_e32 v48, v60, v48
	ds_bpermute_b32 v60, v65, v48
	v_cndmask_b32_e64 v56, 16, v218, s[0:1]
	v_add_u32_e32 v56, v56, v59
	v_or_b32_e32 v56, v56, v143
	v_lshl_add_u64 v[54:55], v[54:55], 1, s[4:5]
	v_ashrrev_i32_e32 v57, 31, v56
	v_lshl_add_u64 v[56:57], v[56:57], 3, s[74:75]
	v_mul_f32_e32 v50, v62, v50
	s_waitcnt lgkmcnt(0)
	s_waitcnt vmcnt(31)
	v_mul_f32_e32 v53, v205, v60
	v_cndmask_b32_e64 v53, v53, -v53, vcc
	v_fmac_f32_e32 v53, v48, v204
	v_cmp_lt_i32_e64 s[100:101],s33,v162
	s_nop 1
	v_cndmask_b32_e64 v236,32,v222,s[100:101]
	v_add_u32_e32 v236,v236,v162
	v_cmp_lt_i32_e64 s[100:101],s33,v236
	s_nop 1
	v_cndmask_b32_e64 v240,32,v222,s[100:101]
	v_add_u32_e32 v240,v240,v236
	v_lshlrev_b32_e32 v241,4,v240
	v_add_u32_e32 v242,0xfffeff00,v241
	v_cmp_lt_i32_e64 s[100:101],s31,v240
	s_nop 1
	v_cndmask_b32_e64 v242,v241,v242,s[100:101]
	v_or_b32_e32 v242,v242,v143
	v_ashrrev_i32_e32 v243,31,v242
	v_lshl_add_u64 v[242:243],v[242:243],3,s[74:75]
	global_load_dwordx2 v[204:205], v[242:243], off
	v_mul_f32_e32 v48, 0x3e16c740, v53
	v_cvt_pk_bf16_f32 v48, v48, s0
	global_store_short v[54:55], v48, off
	v_mul_f32_e32 v56, v61, v49
	ds_bpermute_b32 v57, v65, v56
	v_cmp_lt_i32_e64 s[0:1], s28, v58
	v_lshl_add_u64 v[54:55], v[192:193], 1, s[4:5]
	v_add_u32_e32 v192, 0x4e00, v66
	v_cndmask_b32_e64 v48, 32, v219, s[0:1]
	v_add_u32_e32 v48, v48, v59
	v_or_b32_e32 v48, v48, v143
	v_ashrrev_i32_e32 v49, 31, v48
	v_lshl_add_u64 v[48:49], v[48:49], 3, s[74:75]
	s_waitcnt lgkmcnt(0)
	s_waitcnt vmcnt(32)
	v_mul_f32_e32 v53, v207, v57
	v_cndmask_b32_e64 v53, v53, -v53, vcc
	v_fmac_f32_e32 v53, v56, v206
	v_cmp_lt_i32_e64 s[100:101],s33,v162
	s_nop 1
	v_cndmask_b32_e64 v236,32,v222,s[100:101]
	v_add_u32_e32 v236,v236,v162
	v_cmp_lt_i32_e64 s[100:101],s33,v236
	s_nop 1
	v_cndmask_b32_e64 v240,32,v222,s[100:101]
	v_add_u32_e32 v240,v240,v236
	v_lshlrev_b32_e32 v241,4,v240
	v_cmp_lt_i32_e64 s[100:101],s27,v240
	s_nop 1
	v_cndmask_b32_e64 v242,16,v218,s[100:101]
	v_add_u32_e32 v242,v242,v241
	v_or_b32_e32 v242,v242,v143
	v_ashrrev_i32_e32 v243,31,v242
	v_lshl_add_u64 v[242:243],v[242:243],3,s[74:75]
	global_load_dwordx2 v[206:207], v[242:243], off
	v_mul_f32_e32 v52, 0x3e16c740, v53
	v_cvt_pk_bf16_f32 v52, v52, s0
	global_store_short v[54:55], v52, off
	ds_bpermute_b32 v56, v65, v50
	v_cmp_lt_i32_e64 s[0:1], s29, v58
	v_lshl_add_u64 v[52:53], v[192:193], 1, s[4:5]
	v_add_u32_e32 v192, 0x5100, v66
	v_cndmask_b32_e64 v54, 48, v220, s[0:1]
	v_add_u32_e32 v54, v54, v59
	v_or_b32_e32 v54, v54, v143
	v_ashrrev_i32_e32 v55, 31, v54
	v_lshl_add_u64 v[54:55], v[54:55], 3, s[74:75]
	s_waitcnt lgkmcnt(0)
	s_waitcnt vmcnt(33)
	v_mul_f32_e32 v49, v225, v56
	v_cndmask_b32_e64 v49, v49, -v49, vcc
	v_fmac_f32_e32 v49, v50, v224
	v_cmp_lt_i32_e64 s[100:101],s33,v162
	s_nop 1
	v_cndmask_b32_e64 v236,32,v222,s[100:101]
	v_add_u32_e32 v236,v236,v162
	v_cmp_lt_i32_e64 s[100:101],s33,v236
	s_nop 1
	v_cndmask_b32_e64 v240,32,v222,s[100:101]
	v_add_u32_e32 v240,v240,v236
	v_lshlrev_b32_e32 v241,4,v240
	v_cmp_lt_i32_e64 s[100:101],s28,v240
	s_nop 1
	v_cndmask_b32_e64 v242,32,v219,s[100:101]
	v_add_u32_e32 v242,v242,v241
	v_or_b32_e32 v242,v242,v143
	v_ashrrev_i32_e32 v243,31,v242
	v_lshl_add_u64 v[242:243],v[242:243],3,s[74:75]
	global_load_dwordx2 v[224:225], v[242:243], off
	v_mul_f32_e32 v48, 0x3e16c740, v49
	v_cvt_pk_bf16_f32 v48, v48, s0
	global_store_short v[52:53], v48, off
	v_mul_f32_e32 v50, v63, v51
	ds_bpermute_b32 v51, v65, v50
	s_waitcnt lgkmcnt(0)
	s_waitcnt vmcnt(34)
	v_mul_f32_e32 v49, v227, v51
	v_cndmask_b32_e64 v49, v49, -v49, vcc
	v_fmac_f32_e32 v49, v50, v226
	v_cmp_lt_i32_e64 s[100:101],s33,v162
	s_nop 1
	v_cndmask_b32_e64 v236,32,v222,s[100:101]
	v_add_u32_e32 v236,v236,v162
	v_cmp_lt_i32_e64 s[100:101],s33,v236
	s_nop 1
	v_cndmask_b32_e64 v240,32,v222,s[100:101]
	v_add_u32_e32 v240,v240,v236
	v_lshlrev_b32_e32 v241,4,v240
	v_cmp_lt_i32_e64 s[100:101],s29,v240
	s_nop 1
	v_cndmask_b32_e64 v242,48,v220,s[100:101]
	v_add_u32_e32 v241,v242,v241
	v_or_b32_e32 v242,v241,v143
	v_ashrrev_i32_e32 v243,31,v242
	v_lshl_add_u64 v[242:243],v[242:243],3,s[74:75]
	global_load_dwordx2 v[226:227], v[242:243], off
	v_mul_f32_e32 v48, 0x3e16c740, v49
	v_cvt_pk_bf16_f32 v50, v48, s0
	v_lshl_add_u64 v[48:49], v[192:193], 1, s[4:5]
	global_store_short v[48:49], v50, off
	v_cmp_lt_i32_e64 s[0:1], s33, v162
	v_add_u32_e32 v192, 0x6300, v66
	s_nop 0
	v_cndmask_b32_e64 v48, 32, v222, s[0:1]
	v_add_u32_e32 v48, v48, v162
	v_lshlrev_b32_e32 v49, 4, v48
	v_add_u32_e32 v50, 0xfffeff00, v49
	v_cmp_lt_i32_e64 s[0:1], s31, v48
	s_nop 1
	v_cndmask_b32_e64 v50, v49, v50, s[0:1]
	v_or_b32_e32 v50, v50, v143
	v_ashrrev_i32_e32 v51, 31, v50
	v_lshl_add_u64 v[50:51], v[50:51], 3, s[74:75]
	ds_read_b128 v[50:53], v151
	v_mad_u64_u32 v[56:57], s[0:1], v150, s26, v[64:65]
	v_cmp_lt_i32_e64 s[0:1], s27, v48
	v_mov_b32_e32 v57, v193
	s_waitcnt lgkmcnt(0)
	v_mul_f32_e32 v32, v32, v50
	ds_bpermute_b32 v50, v65, v32
	v_cndmask_b32_e64 v58, 16, v218, s[0:1]
	v_add_u32_e32 v58, v58, v49
	v_or_b32_e32 v58, v58, v143
	v_lshl_add_u64 v[56:57], v[56:57], 1, s[4:5]
	v_ashrrev_i32_e32 v59, 31, v58
	v_lshl_add_u64 v[58:59], v[58:59], 3, s[74:75]
	v_mul_f32_e32 v34, v34, v52
	ds_bpermute_b32 v52, v65, v34
	s_waitcnt lgkmcnt(1)
	s_waitcnt vmcnt(35)
	v_mul_f32_e32 v50, v229, v50
	v_cndmask_b32_e64 v50, v50, -v50, vcc
	v_fmac_f32_e32 v50, v32, v228
	v_cmp_lt_i32_e64 s[100:101],s33,v48
	s_nop 1
	v_cndmask_b32_e64 v236,32,v222,s[100:101]
	v_add_u32_e32 v236,v236,v48
	v_cmp_lt_i32_e64 s[100:101],s30,v236
	s_nop 1
	v_cndmask_b32_e64 v240,8,v221,s[100:101]
	v_add_u32_e32 v237,v240,v236
	v_lshlrev_b32_e32 v242,4,v237
	v_add_u32_e32 v240,0xfffeff00,v242
	v_cmp_lt_i32_e64 s[100:101],s31,v237
	s_nop 1
	v_cndmask_b32_e64 v240,v242,v240,s[100:101]
	v_or_b32_e32 v240,v240,v143
	v_ashrrev_i32_e32 v241,31,v240
	v_lshl_add_u64 v[240:241],v[240:241],3,s[74:75]
	global_load_dwordx2 v[228:229], v[240:241], off
	v_mul_f32_e32 v32, 0x3e16c740, v50
	v_cvt_pk_bf16_f32 v32, v32, s0
	global_store_short v[56:57], v32, off
	v_mul_f32_e32 v50, v33, v51
	ds_bpermute_b32 v51, v65, v50
	v_cmp_lt_i32_e64 s[0:1], s28, v48
	v_lshl_add_u64 v[56:57], v[192:193], 1, s[4:5]
	v_add_u32_e32 v192, 0x6600, v66
	v_cndmask_b32_e64 v32, 32, v219, s[0:1]
	v_add_u32_e32 v32, v32, v49
	v_or_b32_e32 v32, v32, v143
	v_ashrrev_i32_e32 v33, 31, v32
	v_lshl_add_u64 v[32:33], v[32:33], 3, s[74:75]
	s_waitcnt lgkmcnt(0)
	s_waitcnt vmcnt(36)
	v_mul_f32_e32 v51, v231, v51
	v_cndmask_b32_e64 v51, v51, -v51, vcc
	v_fmac_f32_e32 v51, v50, v230
	v_cmp_lt_i32_e64 s[100:101],s33,v48
	s_nop 1
	v_cndmask_b32_e64 v236,32,v222,s[100:101]
	v_add_u32_e32 v236,v236,v48
	v_cmp_lt_i32_e64 s[100:101],s30,v236
	s_nop 1
	v_cndmask_b32_e64 v240,8,v221,s[100:101]
	v_add_u32_e32 v237,v240,v236
	v_lshlrev_b32_e32 v242,4,v237
	v_cmp_lt_i32_e64 s[100:101],s27,v237
	s_nop 1
	v_cndmask_b32_e64 v244,16,v218,s[100:101]
	v_add_u32_e32 v244,v244,v242
	v_or_b32_e32 v244,v244,v143
	v_ashrrev_i32_e32 v245,31,v244
	v_lshl_add_u64 v[244:245],v[244:245],3,s[74:75]
	global_load_dwordx2 v[230:231], v[244:245], off
	v_mul_f32_e32 v50, 0x3e16c740, v51
	v_cvt_pk_bf16_f32 v50, v50, s0
	global_store_short v[56:57], v50, off
	v_cmp_lt_i32_e64 s[0:1], s29, v48
	v_lshl_add_u64 v[50:51], v[192:193], 1, s[4:5]
	v_add_u32_e32 v192, 0x6900, v66
	v_cndmask_b32_e64 v54, 48, v220, s[0:1]
	v_add_u32_e32 v49, v54, v49
	v_or_b32_e32 v54, v49, v143
	v_ashrrev_i32_e32 v55, 31, v54
	v_lshl_add_u64 v[54:55], v[54:55], 3, s[74:75]
	s_waitcnt vmcnt(37)
	v_mul_f32_e32 v33, v233, v52
	v_cndmask_b32_e64 v33, v33, -v33, vcc
	v_fmac_f32_e32 v33, v34, v232
	v_cmp_lt_i32_e64 s[100:101],s33,v48
	s_nop 1
	v_cndmask_b32_e64 v236,32,v222,s[100:101]
	v_add_u32_e32 v236,v236,v48
	v_cmp_lt_i32_e64 s[100:101],s30,v236
	s_nop 1
	v_cndmask_b32_e64 v240,8,v221,s[100:101]
	v_add_u32_e32 v237,v240,v236
	v_lshlrev_b32_e32 v242,4,v237
	v_cmp_lt_i32_e64 s[100:101],s28,v237
	s_nop 1
	v_cndmask_b32_e64 v240,32,v219,s[100:101]
	v_add_u32_e32 v240,v240,v242
	v_or_b32_e32 v240,v240,v143
	v_ashrrev_i32_e32 v241,31,v240
	v_lshl_add_u64 v[240:241],v[240:241],3,s[74:75]
	global_load_dwordx2 v[232:233], v[240:241], off
	v_mul_f32_e32 v32, 0x3e16c740, v33
	v_cvt_pk_bf16_f32 v32, v32, s0
	global_store_short v[50:51], v32, off
	v_mul_f32_e32 v34, v35, v53
	ds_bpermute_b32 v35, v65, v34
	s_waitcnt lgkmcnt(0)
	s_waitcnt vmcnt(38)
	v_mul_f32_e32 v33, v235, v35
	v_cndmask_b32_e64 v33, v33, -v33, vcc
	v_fmac_f32_e32 v33, v34, v234
	v_mov_b32_e32 v241, v17
	v_cmp_lt_i32_e64 s[100:101],s33,v48
	s_nop 1
	v_cndmask_b32_e64 v236,32,v222,s[100:101]
	v_add_u32_e32 v236,v236,v48
	v_cmp_lt_i32_e64 s[100:101],s30,v236
	s_nop 1
	v_cndmask_b32_e64 v240,8,v221,s[100:101]
	v_add_u32_e32 v237,v240,v236
	v_lshlrev_b32_e32 v242,4,v237
	v_cmp_lt_i32_e64 s[100:101],s29,v237
	s_nop 1
	v_cndmask_b32_e64 v244,48,v220,s[100:101]
	v_add_u32_e32 v244,v244,v242
	v_or_b32_e32 v244,v244,v143
	v_ashrrev_i32_e32 v245,31,v244
	v_lshl_add_u64 v[244:245],v[244:245],3,s[74:75]
	global_load_dwordx2 v[234:235], v[244:245], off
	v_mul_f32_e32 v32, 0x3e16c740, v33
	v_cvt_pk_bf16_f32 v34, v32, s0
	v_lshl_add_u64 v[32:33], v[192:193], 1, s[4:5]
	global_store_short v[32:33], v34, off
	v_cmp_lt_i32_e64 s[0:1], s30, v48
	v_add_u32_e32 v192, 0x7b00, v66
	s_nop 0
	v_cndmask_b32_e64 v32, 8, v221, s[0:1]
	v_add_u32_e32 v49, v32, v48
	v_lshlrev_b32_e32 v56, 4, v49
	v_add_u32_e32 v32, 0xfffeff00, v56
	v_cmp_lt_i32_e64 s[0:1], s31, v49
	s_nop 1
	v_cndmask_b32_e64 v32, v56, v32, s[0:1]
	v_or_b32_e32 v32, v32, v143
	v_ashrrev_i32_e32 v33, 31, v32
	v_lshl_add_u64 v[32:33], v[32:33], 3, s[74:75]
	ds_read_b128 v[32:35], v149
	v_mad_u64_u32 v[52:53], s[0:1], v148, s26, v[64:65]
	v_cmp_lt_i32_e64 s[0:1], s27, v49
	v_mov_b32_e32 v53, v193
	s_waitcnt lgkmcnt(0)
	v_mul_f32_e32 v32, v36, v32
	ds_bpermute_b32 v36, v65, v32
	v_cndmask_b32_e64 v54, 16, v218, s[0:1]
	v_add_u32_e32 v54, v54, v56
	v_or_b32_e32 v54, v54, v143
	v_lshl_add_u64 v[52:53], v[52:53], 1, s[4:5]
	v_ashrrev_i32_e32 v55, 31, v54
	v_lshl_add_u64 v[54:55], v[54:55], 3, s[74:75]
	v_mul_f32_e32 v34, v38, v34
	ds_bpermute_b32 v38, v65, v34
	s_waitcnt lgkmcnt(1)
	s_waitcnt vmcnt(39)
	v_mul_f32_e32 v36, v175, v36
	v_cndmask_b32_e64 v36, v36, -v36, vcc
	v_fmac_f32_e32 v36, v32, v174
	v_cmp_lt_i32_e64 s[100:101],s33,v48
	s_nop 1
	v_cndmask_b32_e64 v236,32,v222,s[100:101]
	v_add_u32_e32 v236,v236,v48
	v_cmp_lt_i32_e64 s[100:101],s30,v236
	s_nop 1
	v_cndmask_b32_e64 v240,8,v221,s[100:101]
	v_add_u32_e32 v237,v240,v236
	v_cmp_lt_i32_e64 s[100:101],s30,v237
	s_nop 1
	v_cndmask_b32_e64 v240,8,v221,s[100:101]
	v_add_u32_e32 v237,v240,v237
	v_lshlrev_b32_e32 v242,4,v237
	v_add_u32_e32 v240,0xfffeff00,v242
	v_cmp_lt_i32_e64 s[100:101],s31,v237
	s_nop 1
	v_cndmask_b32_e64 v240,v242,v240,s[100:101]
	v_or_b32_e32 v240,v240,v143
	v_ashrrev_i32_e32 v241,31,v240
	v_lshl_add_u64 v[240:241],v[240:241],3,s[74:75]
	global_load_dwordx2 v[174:175], v[240:241], off
	v_mul_f32_e32 v32, 0x3e16c740, v36
	v_cvt_pk_bf16_f32 v32, v32, s0
	global_store_short v[52:53], v32, off
	v_mul_f32_e32 v36, v37, v33
	ds_bpermute_b32 v37, v65, v36
	v_cmp_lt_i32_e64 s[0:1], s28, v49
	v_lshl_add_u64 v[52:53], v[192:193], 1, s[4:5]
	v_add_u32_e32 v192, 0x7e00, v66
	v_cndmask_b32_e64 v32, 32, v219, s[0:1]
	v_add_u32_e32 v32, v32, v56
	v_or_b32_e32 v32, v32, v143
	v_ashrrev_i32_e32 v33, 31, v32
	v_lshl_add_u64 v[32:33], v[32:33], 3, s[74:75]
	s_waitcnt lgkmcnt(0)
	s_waitcnt vmcnt(39)
	v_mul_f32_e32 v37, v177, v37
	v_cndmask_b32_e64 v37, v37, -v37, vcc
	v_fmac_f32_e32 v37, v36, v176
	v_cmp_lt_i32_e64 s[100:101],s33,v48
	s_nop 1
	v_cndmask_b32_e64 v236,32,v222,s[100:101]
	v_add_u32_e32 v236,v236,v48
	v_cmp_lt_i32_e64 s[100:101],s30,v236
	s_nop 1
	v_cndmask_b32_e64 v240,8,v221,s[100:101]
	v_add_u32_e32 v237,v240,v236
	v_cmp_lt_i32_e64 s[100:101],s30,v237
	s_nop 1
	v_cndmask_b32_e64 v240,8,v221,s[100:101]
	v_add_u32_e32 v237,v240,v237
	v_lshlrev_b32_e32 v242,4,v237
	v_cmp_lt_i32_e64 s[100:101],s27,v237
	s_nop 1
	v_cndmask_b32_e64 v244,16,v218,s[100:101]
	v_add_u32_e32 v244,v244,v242
	v_or_b32_e32 v244,v244,v143
	v_ashrrev_i32_e32 v245,31,v244
	v_lshl_add_u64 v[244:245],v[244:245],3,s[74:75]
	global_load_dwordx2 v[176:177], v[244:245], off
	v_mul_f32_e32 v36, 0x3e16c740, v37
	v_cvt_pk_bf16_f32 v36, v36, s0
	global_store_short v[52:53], v36, off
	v_cmp_lt_i32_e64 s[0:1], s29, v49
	v_lshl_add_u64 v[36:37], v[192:193], 1, s[4:5]
	v_add_u32_e32 v192, 0x8100, v66
	v_cndmask_b32_e64 v50, 48, v220, s[0:1]
	v_add_u32_e32 v50, v50, v56
	v_or_b32_e32 v50, v50, v143
	v_ashrrev_i32_e32 v51, 31, v50
	v_lshl_add_u64 v[50:51], v[50:51], 3, s[74:75]
	s_waitcnt vmcnt(39)
	v_mul_f32_e32 v33, v179, v38
	v_cndmask_b32_e64 v33, v33, -v33, vcc
	v_fmac_f32_e32 v33, v34, v178
	v_cmp_lt_i32_e64 s[100:101],s33,v48
	s_nop 1
	v_cndmask_b32_e64 v236,32,v222,s[100:101]
	v_add_u32_e32 v236,v236,v48
	v_cmp_lt_i32_e64 s[100:101],s30,v236
	s_nop 1
	v_cndmask_b32_e64 v240,8,v221,s[100:101]
	v_add_u32_e32 v237,v240,v236
	v_cmp_lt_i32_e64 s[100:101],s30,v237
	s_nop 1
	v_cndmask_b32_e64 v240,8,v221,s[100:101]
	v_add_u32_e32 v237,v240,v237
	v_lshlrev_b32_e32 v242,4,v237
	v_cmp_lt_i32_e64 s[100:101],s28,v237
	s_nop 1
	v_cndmask_b32_e64 v240,32,v219,s[100:101]
	v_add_u32_e32 v240,v240,v242
	v_or_b32_e32 v240,v240,v143
	v_ashrrev_i32_e32 v241,31,v240
	v_lshl_add_u64 v[240:241],v[240:241],3,s[74:75]
	global_load_dwordx2 v[178:179], v[240:241], off
	v_mul_f32_e32 v32, 0x3e16c740, v33
	v_cvt_pk_bf16_f32 v32, v32, s0
	global_store_short v[36:37], v32, off
	v_mul_f32_e32 v34, v39, v35
	ds_bpermute_b32 v35, v65, v34
	s_waitcnt lgkmcnt(0)
	s_waitcnt vmcnt(39)
	v_mul_f32_e32 v33, v181, v35
	v_cndmask_b32_e64 v33, v33, -v33, vcc
	v_fmac_f32_e32 v33, v34, v180
	v_mov_b32_e32 v241, v17
	v_cmp_lt_i32_e64 s[100:101],s33,v48
	s_nop 1
	v_cndmask_b32_e64 v236,32,v222,s[100:101]
	v_add_u32_e32 v236,v236,v48
	v_cmp_lt_i32_e64 s[100:101],s30,v236
	s_nop 1
	v_cndmask_b32_e64 v240,8,v221,s[100:101]
	v_add_u32_e32 v237,v240,v236
	v_cmp_lt_i32_e64 s[100:101],s30,v237
	s_nop 1
	v_cndmask_b32_e64 v240,8,v221,s[100:101]
	v_add_u32_e32 v237,v240,v237
	v_lshlrev_b32_e32 v242,4,v237
	v_cmp_lt_i32_e64 s[100:101],s29,v237
	s_nop 1
	v_cndmask_b32_e64 v244,48,v220,s[100:101]
	v_add_u32_e32 v244,v244,v242
	v_or_b32_e32 v244,v244,v143
	v_ashrrev_i32_e32 v245,31,v244
	v_lshl_add_u64 v[244:245],v[244:245],3,s[74:75]
	global_load_dwordx2 v[180:181], v[244:245], off
	v_mul_f32_e32 v32, 0x3e16c740, v33
	v_cvt_pk_bf16_f32 v34, v32, s0
	v_lshl_add_u64 v[32:33], v[192:193], 1, s[4:5]
	global_store_short v[32:33], v34, off
	v_cmp_lt_i32_e64 s[0:1], s30, v49
	v_add_u32_e32 v192, 0x9300, v66
	s_nop 0
	v_cndmask_b32_e64 v32, 8, v221, s[0:1]
	v_add_u32_e32 v49, v32, v49
	v_lshlrev_b32_e32 v52, 4, v49
	v_add_u32_e32 v32, 0xfffeff00, v52
	v_cmp_lt_i32_e64 s[0:1], s31, v49
	s_nop 1
	v_cndmask_b32_e64 v32, v52, v32, s[0:1]
	v_or_b32_e32 v32, v32, v143
	v_ashrrev_i32_e32 v33, 31, v32
	v_lshl_add_u64 v[32:33], v[32:33], 3, s[74:75]
	ds_read_b128 v[32:35], v147
	v_mad_u64_u32 v[38:39], s[0:1], v146, s26, v[64:65]
	v_cmp_lt_i32_e64 s[0:1], s27, v49
	v_mov_b32_e32 v39, v193
	s_waitcnt lgkmcnt(0)
	v_mul_f32_e32 v32, v40, v32
	ds_bpermute_b32 v40, v65, v32
	v_cndmask_b32_e64 v50, 16, v218, s[0:1]
	v_add_u32_e32 v50, v50, v52
	v_or_b32_e32 v50, v50, v143
	v_lshl_add_u64 v[38:39], v[38:39], 1, s[4:5]
	v_ashrrev_i32_e32 v51, 31, v50
	v_lshl_add_u64 v[50:51], v[50:51], 3, s[74:75]
	v_mul_f32_e32 v34, v42, v34
	s_waitcnt lgkmcnt(0)
	s_waitcnt vmcnt(39)
	v_mul_f32_e32 v37, v183, v40
	v_cndmask_b32_e64 v37, v37, -v37, vcc
	v_fmac_f32_e32 v37, v32, v182
	v_cmp_lt_i32_e64 s[100:101],s33,v48
	s_nop 1
	v_cndmask_b32_e64 v236,32,v222,s[100:101]
	v_add_u32_e32 v236,v236,v48
	v_cmp_lt_i32_e64 s[100:101],s30,v236
	s_nop 1
	v_cndmask_b32_e64 v240,8,v221,s[100:101]
	v_add_u32_e32 v237,v240,v236
	v_cmp_lt_i32_e64 s[100:101],s30,v237
	s_nop 1
	v_cndmask_b32_e64 v240,8,v221,s[100:101]
	v_add_u32_e32 v237,v240,v237
	v_cmp_lt_i32_e64 s[100:101],s30,v237
	s_nop 1
	v_cndmask_b32_e64 v240,8,v221,s[100:101]
	v_add_u32_e32 v242,v240,v237
	v_lshlrev_b32_e32 v243,4,v242
	v_add_u32_e32 v240,0xfffeff00,v243
	v_cmp_lt_i32_e64 s[100:101],s31,v242
	s_nop 1
	v_cndmask_b32_e64 v240,v243,v240,s[100:101]
	v_or_b32_e32 v240,v240,v143
	v_ashrrev_i32_e32 v241,31,v240
	v_lshl_add_u64 v[240:241],v[240:241],3,s[74:75]
	global_load_dwordx2 v[182:183], v[240:241], off
	v_mul_f32_e32 v32, 0x3e16c740, v37
	v_cvt_pk_bf16_f32 v32, v32, s0
	global_store_short v[38:39], v32, off
	v_mul_f32_e32 v40, v41, v33
	ds_bpermute_b32 v41, v65, v40
	v_cmp_lt_i32_e64 s[0:1], s28, v49
	v_lshl_add_u64 v[38:39], v[192:193], 1, s[4:5]
	v_add_u32_e32 v192, 0x9600, v66
	v_cndmask_b32_e64 v32, 32, v219, s[0:1]
	v_add_u32_e32 v32, v32, v52
	v_or_b32_e32 v32, v32, v143
	v_ashrrev_i32_e32 v33, 31, v32
	v_lshl_add_u64 v[32:33], v[32:33], 3, s[74:75]
	s_waitcnt lgkmcnt(0)
	s_waitcnt vmcnt(39)
	v_mul_f32_e32 v37, v185, v41
	v_cndmask_b32_e64 v37, v37, -v37, vcc
	v_fmac_f32_e32 v37, v40, v184
	v_cmp_lt_i32_e64 s[100:101],s33,v48
	s_nop 1
	v_cndmask_b32_e64 v236,32,v222,s[100:101]
	v_add_u32_e32 v236,v236,v48
	v_cmp_lt_i32_e64 s[100:101],s30,v236
	s_nop 1
	v_cndmask_b32_e64 v240,8,v221,s[100:101]
	v_add_u32_e32 v237,v240,v236
	v_cmp_lt_i32_e64 s[100:101],s30,v237
	s_nop 1
	v_cndmask_b32_e64 v240,8,v221,s[100:101]
	v_add_u32_e32 v237,v240,v237
	v_cmp_lt_i32_e64 s[100:101],s30,v237
	s_nop 1
	v_cndmask_b32_e64 v240,8,v221,s[100:101]
	v_add_u32_e32 v242,v240,v237
	v_lshlrev_b32_e32 v243,4,v242
	v_cmp_lt_i32_e64 s[100:101],s27,v242
	s_nop 1
	v_cndmask_b32_e64 v244,16,v218,s[100:101]
	v_add_u32_e32 v244,v244,v243
	v_or_b32_e32 v244,v244,v143
	v_ashrrev_i32_e32 v245,31,v244
	v_lshl_add_u64 v[244:245],v[244:245],3,s[74:75]
	global_load_dwordx2 v[184:185], v[244:245], off
	v_mul_f32_e32 v36, 0x3e16c740, v37
	v_cvt_pk_bf16_f32 v36, v36, s0
	global_store_short v[38:39], v36, off
	ds_bpermute_b32 v40, v65, v34
	v_cmp_lt_i32_e64 s[0:1], s29, v49
	v_lshl_add_u64 v[36:37], v[192:193], 1, s[4:5]
	v_add_u32_e32 v192, 0x9900, v66
	v_cndmask_b32_e64 v38, 48, v220, s[0:1]
	v_add_u32_e32 v38, v38, v52
	v_or_b32_e32 v38, v38, v143
	v_ashrrev_i32_e32 v39, 31, v38
	v_lshl_add_u64 v[38:39], v[38:39], 3, s[74:75]
	s_waitcnt lgkmcnt(0)
	s_waitcnt vmcnt(39)
	v_mul_f32_e32 v33, v187, v40
	v_cndmask_b32_e64 v33, v33, -v33, vcc
	v_fmac_f32_e32 v33, v34, v186
	v_cmp_lt_i32_e64 s[100:101],s33,v48
	s_nop 1
	v_cndmask_b32_e64 v236,32,v222,s[100:101]
	v_add_u32_e32 v236,v236,v48
	v_cmp_lt_i32_e64 s[100:101],s30,v236
	s_nop 1
	v_cndmask_b32_e64 v240,8,v221,s[100:101]
	v_add_u32_e32 v237,v240,v236
	v_cmp_lt_i32_e64 s[100:101],s30,v237
	s_nop 1
	v_cndmask_b32_e64 v240,8,v221,s[100:101]
	v_add_u32_e32 v237,v240,v237
	v_cmp_lt_i32_e64 s[100:101],s30,v237
	s_nop 1
	v_cndmask_b32_e64 v240,8,v221,s[100:101]
	v_add_u32_e32 v242,v240,v237
	v_lshlrev_b32_e32 v243,4,v242
	v_cmp_lt_i32_e64 s[100:101],s28,v242
	s_nop 1
	v_cndmask_b32_e64 v240,32,v219,s[100:101]
	v_add_u32_e32 v240,v240,v243
	v_or_b32_e32 v240,v240,v143
	v_ashrrev_i32_e32 v241,31,v240
	v_lshl_add_u64 v[240:241],v[240:241],3,s[74:75]
	global_load_dwordx2 v[186:187], v[240:241], off
	v_mul_f32_e32 v32, 0x3e16c740, v33
	v_cvt_pk_bf16_f32 v32, v32, s0
	global_store_short v[36:37], v32, off
	v_mul_f32_e32 v34, v43, v35
	ds_bpermute_b32 v35, v65, v34
	s_waitcnt lgkmcnt(0)
	s_waitcnt vmcnt(39)
	v_mul_f32_e32 v33, v189, v35
	v_cndmask_b32_e64 v33, v33, -v33, vcc
	v_fmac_f32_e32 v33, v34, v188
	v_mov_b32_e32 v241, v17
	v_cmp_lt_i32_e64 s[100:101],s33,v48
	s_nop 1
	v_cndmask_b32_e64 v236,32,v222,s[100:101]
	v_add_u32_e32 v236,v236,v48
	v_cmp_lt_i32_e64 s[100:101],s30,v236
	s_nop 1
	v_cndmask_b32_e64 v240,8,v221,s[100:101]
	v_add_u32_e32 v237,v240,v236
	v_cmp_lt_i32_e64 s[100:101],s30,v237
	s_nop 1
	v_cndmask_b32_e64 v240,8,v221,s[100:101]
	v_add_u32_e32 v237,v240,v237
	v_cmp_lt_i32_e64 s[100:101],s30,v237
	s_nop 1
	v_cndmask_b32_e64 v240,8,v221,s[100:101]
	v_add_u32_e32 v242,v240,v237
	v_lshlrev_b32_e32 v243,4,v242
	v_cmp_lt_i32_e64 s[100:101],s29,v242
	s_nop 1
	v_cndmask_b32_e64 v244,48,v220,s[100:101]
	v_add_u32_e32 v244,v244,v243
	v_or_b32_e32 v244,v244,v143
	v_ashrrev_i32_e32 v245,31,v244
	v_lshl_add_u64 v[244:245],v[244:245],3,s[74:75]
	global_load_dwordx2 v[188:189], v[244:245], off
	v_mul_f32_e32 v32, 0x3e16c740, v33
	v_cvt_pk_bf16_f32 v34, v32, s0
	v_lshl_add_u64 v[32:33], v[192:193], 1, s[4:5]
	global_store_short v[32:33], v34, off
	v_cmp_lt_i32_e64 s[0:1], s30, v49
	v_add_u32_e32 v192, 0xab00, v66
	s_nop 0
	v_cndmask_b32_e64 v32, 8, v221, s[0:1]
	v_add_u32_e32 v42, v32, v49
	v_lshlrev_b32_e32 v43, 4, v42
	v_add_u32_e32 v32, 0xfffeff00, v43
	v_cmp_lt_i32_e64 s[0:1], s31, v42
	s_nop 1
	v_cndmask_b32_e64 v32, v43, v32, s[0:1]
	v_or_b32_e32 v32, v32, v143
	v_ashrrev_i32_e32 v33, 31, v32
	v_lshl_add_u64 v[32:33], v[32:33], 3, s[74:75]
	ds_read_b128 v[32:35], v145
	v_mad_u64_u32 v[38:39], s[0:1], v144, s26, v[64:65]
	v_cmp_lt_i32_e64 s[0:1], s27, v42
	v_mov_b32_e32 v39, v193
	s_waitcnt lgkmcnt(0)
	v_mul_f32_e32 v32, v44, v32
	ds_bpermute_b32 v44, v65, v32
	v_cndmask_b32_e64 v40, 16, v218, s[0:1]
	v_add_u32_e32 v40, v40, v43
	v_or_b32_e32 v40, v40, v143
	v_lshl_add_u64 v[38:39], v[38:39], 1, s[4:5]
	v_ashrrev_i32_e32 v41, 31, v40
	v_lshl_add_u64 v[40:41], v[40:41], 3, s[74:75]
	v_mul_f32_e32 v34, v46, v34
	s_waitcnt lgkmcnt(0)
	s_waitcnt vmcnt(39)
	v_mul_f32_e32 v37, v191, v44
	v_cndmask_b32_e64 v37, v37, -v37, vcc
	v_fmac_f32_e32 v37, v32, v190
	v_cmp_lt_i32_e64 s[100:101],s33,v48
	s_nop 1
	v_cndmask_b32_e64 v236,32,v222,s[100:101]
	v_add_u32_e32 v236,v236,v48
	v_cmp_lt_i32_e64 s[100:101],s33,v236
	s_nop 1
	v_cndmask_b32_e64 v240,32,v222,s[100:101]
	v_add_u32_e32 v242,v240,v236
	v_lshlrev_b32_e32 v243,4,v242
	v_add_u32_e32 v240,0xfffeff00,v243
	v_cmp_lt_i32_e64 s[100:101],s31,v242
	s_nop 1
	v_cndmask_b32_e64 v240,v243,v240,s[100:101]
	v_or_b32_e32 v240,v240,v143
	v_ashrrev_i32_e32 v241,31,v240
	v_lshl_add_u64 v[240:241],v[240:241],3,s[74:75]
	global_load_dwordx2 v[190:191], v[240:241], off
	v_mul_f32_e32 v32, 0x3e16c740, v37
	v_cvt_pk_bf16_f32 v32, v32, s0
	global_store_short v[38:39], v32, off
	v_mul_f32_e32 v40, v45, v33
	ds_bpermute_b32 v41, v65, v40
	v_cmp_lt_i32_e64 s[0:1], s28, v42
	v_lshl_add_u64 v[38:39], v[192:193], 1, s[4:5]
	v_add_u32_e32 v192, 0xae00, v66
	v_cndmask_b32_e64 v32, 32, v219, s[0:1]
	v_add_u32_e32 v32, v32, v43
	v_or_b32_e32 v32, v32, v143
	v_ashrrev_i32_e32 v33, 31, v32
	v_lshl_add_u64 v[32:33], v[32:33], 3, s[74:75]
	s_waitcnt lgkmcnt(0)
	s_waitcnt vmcnt(39)
	v_mul_f32_e32 v37, v195, v41
	v_cndmask_b32_e64 v37, v37, -v37, vcc
	v_fmac_f32_e32 v37, v40, v194
	v_cmp_lt_i32_e64 s[100:101],s33,v48
	s_nop 1
	v_cndmask_b32_e64 v236,32,v222,s[100:101]
	v_add_u32_e32 v236,v236,v48
	v_cmp_lt_i32_e64 s[100:101],s33,v236
	s_nop 1
	v_cndmask_b32_e64 v240,32,v222,s[100:101]
	v_add_u32_e32 v242,v240,v236
	v_lshlrev_b32_e32 v243,4,v242
	v_cmp_lt_i32_e64 s[100:101],s27,v242
	s_nop 1
	v_cndmask_b32_e64 v244,16,v218,s[100:101]
	v_add_u32_e32 v244,v244,v243
	v_or_b32_e32 v244,v244,v143
	v_ashrrev_i32_e32 v245,31,v244
	v_lshl_add_u64 v[244:245],v[244:245],3,s[74:75]
	global_load_dwordx2 v[194:195], v[244:245], off
	v_mul_f32_e32 v36, 0x3e16c740, v37
	v_cvt_pk_bf16_f32 v36, v36, s0
	global_store_short v[38:39], v36, off
	ds_bpermute_b32 v40, v65, v34
	v_cmp_lt_i32_e64 s[0:1], s29, v42
	v_lshl_add_u64 v[36:37], v[192:193], 1, s[4:5]
	v_add_u32_e32 v192, 0xb100, v66
	v_cndmask_b32_e64 v38, 48, v220, s[0:1]
	v_add_u32_e32 v38, v38, v43
	v_or_b32_e32 v38, v38, v143
	v_ashrrev_i32_e32 v39, 31, v38
	v_lshl_add_u64 v[38:39], v[38:39], 3, s[74:75]
	s_waitcnt lgkmcnt(0)
	s_waitcnt vmcnt(39)
	v_mul_f32_e32 v33, v197, v40
	v_cndmask_b32_e64 v33, v33, -v33, vcc
	v_fmac_f32_e32 v33, v34, v196
	v_cmp_lt_i32_e64 s[100:101],s33,v48
	s_nop 1
	v_cndmask_b32_e64 v236,32,v222,s[100:101]
	v_add_u32_e32 v236,v236,v48
	v_cmp_lt_i32_e64 s[100:101],s33,v236
	s_nop 1
	v_cndmask_b32_e64 v240,32,v222,s[100:101]
	v_add_u32_e32 v242,v240,v236
	v_lshlrev_b32_e32 v243,4,v242
	v_cmp_lt_i32_e64 s[100:101],s28,v242
	s_nop 1
	v_cndmask_b32_e64 v244,32,v219,s[100:101]
	v_add_u32_e32 v244,v244,v243
	v_or_b32_e32 v244,v244,v143
	v_ashrrev_i32_e32 v245,31,v244
	v_lshl_add_u64 v[244:245],v[244:245],3,s[74:75]
	global_load_dwordx2 v[196:197], v[244:245], off
	v_mul_f32_e32 v32, 0x3e16c740, v33
	v_cvt_pk_bf16_f32 v32, v32, s0
	global_store_short v[36:37], v32, off
	v_mul_f32_e32 v34, v47, v35
	ds_bpermute_b32 v35, v65, v34
	s_waitcnt lgkmcnt(0)
	s_waitcnt vmcnt(39)
	v_mul_f32_e32 v33, v199, v35
	v_cndmask_b32_e64 v33, v33, -v33, vcc
	v_fmac_f32_e32 v33, v34, v198
	v_cmp_lt_i32_e64 s[100:101],s33,v48
	s_nop 1
	v_cndmask_b32_e64 v236,32,v222,s[100:101]
	v_add_u32_e32 v236,v236,v48
	v_cmp_lt_i32_e64 s[100:101],s33,v236
	s_nop 1
	v_cndmask_b32_e64 v240,32,v222,s[100:101]
	v_add_u32_e32 v242,v240,v236
	v_lshlrev_b32_e32 v243,4,v242
	v_cmp_lt_i32_e64 s[100:101],s29,v242
	s_nop 1
	v_cndmask_b32_e64 v244,48,v220,s[100:101]
	v_add_u32_e32 v244,v244,v243
	v_or_b32_e32 v244,v244,v143
	v_ashrrev_i32_e32 v245,31,v244
	v_lshl_add_u64 v[244:245],v[244:245],3,s[74:75]
	global_load_dwordx2 v[198:199], v[244:245], off
	v_mul_f32_e32 v32, 0x3e16c740, v33
	v_cvt_pk_bf16_f32 v34, v32, s0
	v_lshl_add_u64 v[32:33], v[192:193], 1, s[4:5]
	global_store_short v[32:33], v34, off
	v_cmp_lt_i32_e64 s[0:1], s33, v48
	v_add_u32_e32 v192, 0xc300, v66
	s_nop 0
	v_cndmask_b32_e64 v32, 32, v222, s[0:1]
	v_add_u32_e32 v32, v32, v48
	v_lshlrev_b32_e32 v33, 4, v32
	v_add_u32_e32 v34, 0xfffeff00, v33
	v_cmp_lt_i32_e64 s[0:1], s31, v32
	s_nop 1
	v_cndmask_b32_e64 v34, v33, v34, s[0:1]
	v_or_b32_e32 v34, v34, v143
	v_ashrrev_i32_e32 v35, 31, v34
	v_lshl_add_u64 v[34:35], v[34:35], 3, s[74:75]
	ds_read_b128 v[34:37], v142
	v_mad_u64_u32 v[40:41], s[0:1], v141, s26, v[64:65]
	v_cmp_lt_i32_e64 s[0:1], s27, v32
	v_mov_b32_e32 v41, v193
	s_waitcnt lgkmcnt(0)
	v_mul_f32_e32 v16, v16, v34
	ds_bpermute_b32 v34, v65, v16
	v_cndmask_b32_e64 v42, 16, v218, s[0:1]
	v_add_u32_e32 v42, v42, v33
	v_or_b32_e32 v42, v42, v143
	v_lshl_add_u64 v[40:41], v[40:41], 1, s[4:5]
	v_ashrrev_i32_e32 v43, 31, v42
	v_lshl_add_u64 v[42:43], v[42:43], 3, s[74:75]
	v_mul_f32_e32 v18, v18, v36
	ds_bpermute_b32 v36, v65, v18
	s_waitcnt lgkmcnt(1)
	s_waitcnt vmcnt(39)
	v_mul_f32_e32 v34, v205, v34
	v_cndmask_b32_e64 v34, v34, -v34, vcc
	v_fmac_f32_e32 v34, v16, v204
	v_mov_b32_e32 v237, v17
	v_cmp_lt_i32_e64 s[100:101],s33,v32
	s_nop 1
	v_cndmask_b32_e64 v236,32,v222,s[100:101]
	v_add_u32_e32 v240,v236,v32
	v_cmp_lt_i32_e64 s[100:101],s30,v240
	s_nop 1
	v_cndmask_b32_e64 v242,8,v221,s[100:101]
	v_add_u32_e32 v244,v242,v240
	v_lshlrev_b32_e32 v245,4,v244
	v_add_u32_e32 v242,0xfffeff00,v245
	v_cmp_lt_i32_e64 s[100:101],s31,v244
	s_nop 1
	v_cndmask_b32_e64 v242,v245,v242,s[100:101]
	v_or_b32_e32 v242,v242,v143
	v_ashrrev_i32_e32 v243,31,v242
	v_lshl_add_u64 v[242:243],v[242:243],3,s[74:75]
	global_load_dwordx2 v[204:205], v[242:243], off
	v_mul_f32_e32 v16, 0x3e16c740, v34
	v_cvt_pk_bf16_f32 v16, v16, s0
	global_store_short v[40:41], v16, off
	v_mul_f32_e32 v34, v17, v35
	ds_bpermute_b32 v35, v65, v34
	v_cmp_lt_i32_e64 s[0:1], s28, v32
	v_lshl_add_u64 v[40:41], v[192:193], 1, s[4:5]
	v_add_u32_e32 v192, 0xc600, v66
	v_cndmask_b32_e64 v16, 32, v219, s[0:1]
	v_add_u32_e32 v16, v16, v33
	v_or_b32_e32 v16, v16, v143
	v_ashrrev_i32_e32 v17, 31, v16
	v_lshl_add_u64 v[16:17], v[16:17], 3, s[74:75]
	s_waitcnt lgkmcnt(0)
	s_waitcnt vmcnt(39)
	v_mul_f32_e32 v35, v207, v35
	v_cndmask_b32_e64 v35, v35, -v35, vcc
	v_fmac_f32_e32 v35, v34, v206
	v_mov_b32_e32 v237, v17
	v_cmp_lt_i32_e64 s[100:101],s33,v32
	s_nop 1
	v_cndmask_b32_e64 v236,32,v222,s[100:101]
	v_add_u32_e32 v240,v236,v32
	v_cmp_lt_i32_e64 s[100:101],s30,v240
	s_nop 1
	v_cndmask_b32_e64 v242,8,v221,s[100:101]
	v_add_u32_e32 v244,v242,v240
	v_lshlrev_b32_e32 v245,4,v244
	v_cmp_lt_i32_e64 s[100:101],s27,v244
	s_nop 1
	v_cndmask_b32_e64 v246,16,v218,s[100:101]
	v_add_u32_e32 v246,v246,v245
	v_or_b32_e32 v246,v246,v143
	v_ashrrev_i32_e32 v247,31,v246
	v_lshl_add_u64 v[246:247],v[246:247],3,s[74:75]
	global_load_dwordx2 v[206:207], v[246:247], off
	v_mul_f32_e32 v34, 0x3e16c740, v35
	v_cvt_pk_bf16_f32 v34, v34, s0
	global_store_short v[40:41], v34, off
	v_cmp_lt_i32_e64 s[0:1], s29, v32
	v_lshl_add_u64 v[34:35], v[192:193], 1, s[4:5]
	v_add_u32_e32 v192, 0xc900, v66
	v_cndmask_b32_e64 v38, 48, v220, s[0:1]
	v_add_u32_e32 v33, v38, v33
	v_or_b32_e32 v38, v33, v143
	v_ashrrev_i32_e32 v39, 31, v38
	v_lshl_add_u64 v[38:39], v[38:39], 3, s[74:75]
	s_waitcnt vmcnt(39)
	v_mul_f32_e32 v17, v225, v36
	v_cndmask_b32_e64 v17, v17, -v17, vcc
	v_fmac_f32_e32 v17, v18, v224
	v_cmp_lt_i32_e64 s[100:101],s33,v32
	s_nop 1
	v_cndmask_b32_e64 v236,32,v222,s[100:101]
	v_add_u32_e32 v240,v236,v32
	v_cmp_lt_i32_e64 s[100:101],s30,v240
	s_nop 1
	v_cndmask_b32_e64 v242,8,v221,s[100:101]
	v_add_u32_e32 v244,v242,v240
	v_lshlrev_b32_e32 v245,4,v244
	v_cmp_lt_i32_e64 s[100:101],s28,v244
	s_nop 1
	v_cndmask_b32_e64 v242,32,v219,s[100:101]
	v_add_u32_e32 v242,v242,v245
	v_or_b32_e32 v242,v242,v143
	v_ashrrev_i32_e32 v243,31,v242
	v_lshl_add_u64 v[242:243],v[242:243],3,s[74:75]
	global_load_dwordx2 v[224:225], v[242:243], off
	v_mul_f32_e32 v16, 0x3e16c740, v17
	v_cvt_pk_bf16_f32 v16, v16, s0
	global_store_short v[34:35], v16, off
	v_mul_f32_e32 v18, v19, v37
	ds_bpermute_b32 v19, v65, v18
	s_waitcnt lgkmcnt(0)
	s_waitcnt vmcnt(39)
	v_mul_f32_e32 v17, v227, v19
	v_cndmask_b32_e64 v17, v17, -v17, vcc
	v_fmac_f32_e32 v17, v18, v226
	v_mov_b32_e32 v243, v1
	v_cmp_lt_i32_e64 s[100:101],s33,v32
	s_nop 1
	v_cndmask_b32_e64 v236,32,v222,s[100:101]
	v_add_u32_e32 v240,v236,v32
	v_cmp_lt_i32_e64 s[100:101],s30,v240
	s_nop 1
	v_cndmask_b32_e64 v242,8,v221,s[100:101]
	v_add_u32_e32 v244,v242,v240
	v_lshlrev_b32_e32 v245,4,v244
	v_cmp_lt_i32_e64 s[100:101],s29,v244
	s_nop 1
	v_cndmask_b32_e64 v236,48,v220,s[100:101]
	v_add_u32_e32 v236,v236,v245
	v_or_b32_e32 v236,v236,v143
	v_ashrrev_i32_e32 v237,31,v236
	v_lshl_add_u64 v[236:237],v[236:237],3,s[74:75]
	global_load_dwordx2 v[226:227], v[236:237], off
	v_mul_f32_e32 v16, 0x3e16c740, v17
	v_cvt_pk_bf16_f32 v18, v16, s0
	v_lshl_add_u64 v[16:17], v[192:193], 1, s[4:5]
	global_store_short v[16:17], v18, off
	v_cmp_lt_i32_e64 s[0:1], s30, v32
	v_add_u32_e32 v192, 0xdb00, v66
	s_nop 0
	v_cndmask_b32_e64 v16, 8, v221, s[0:1]
	v_add_u32_e32 v33, v16, v32
	v_lshlrev_b32_e32 v40, 4, v33
	v_add_u32_e32 v16, 0xfffeff00, v40
	v_cmp_lt_i32_e64 s[0:1], s31, v33
	s_nop 1
	v_cndmask_b32_e64 v16, v40, v16, s[0:1]
	v_or_b32_e32 v16, v16, v143
	v_ashrrev_i32_e32 v17, 31, v16
	v_lshl_add_u64 v[16:17], v[16:17], 3, s[74:75]
	ds_read_b128 v[16:19], v140
	v_mad_u64_u32 v[36:37], s[0:1], v139, s26, v[64:65]
	v_cmp_lt_i32_e64 s[0:1], s27, v33
	v_mov_b32_e32 v37, v193
	s_waitcnt lgkmcnt(0)
	v_mul_f32_e32 v16, v20, v16
	ds_bpermute_b32 v20, v65, v16
	v_cndmask_b32_e64 v38, 16, v218, s[0:1]
	v_add_u32_e32 v38, v38, v40
	v_or_b32_e32 v38, v38, v143
	v_lshl_add_u64 v[36:37], v[36:37], 1, s[4:5]
	v_ashrrev_i32_e32 v39, 31, v38
	v_lshl_add_u64 v[38:39], v[38:39], 3, s[74:75]
	v_mul_f32_e32 v18, v22, v18
	ds_bpermute_b32 v22, v65, v18
	s_waitcnt lgkmcnt(1)
	s_waitcnt vmcnt(39)
	v_mul_f32_e32 v20, v229, v20
	v_cndmask_b32_e64 v20, v20, -v20, vcc
	v_fmac_f32_e32 v20, v16, v228
	v_cmp_lt_i32_e64 s[100:101],s33,v32
	s_nop 1
	v_cndmask_b32_e64 v236,32,v222,s[100:101]
	v_add_u32_e32 v240,v236,v32
	v_cmp_lt_i32_e64 s[100:101],s30,v240
	s_nop 1
	v_cndmask_b32_e64 v242,8,v221,s[100:101]
	v_add_u32_e32 v244,v242,v240
	v_cmp_lt_i32_e64 s[100:101],s30,v244
	s_nop 1
	v_cndmask_b32_e64 v242,8,v221,s[100:101]
	v_add_u32_e32 v246,v242,v244
	v_lshlrev_b32_e32 v247,4,v246
	v_add_u32_e32 v242,0xfffeff00,v247
	v_cmp_lt_i32_e64 s[100:101],s31,v246
	s_nop 1
	v_cndmask_b32_e64 v242,v247,v242,s[100:101]
	v_or_b32_e32 v242,v242,v143
	v_ashrrev_i32_e32 v243,31,v242
	v_lshl_add_u64 v[242:243],v[242:243],3,s[74:75]
	global_load_dwordx2 v[228:229], v[242:243], off
	v_mul_f32_e32 v16, 0x3e16c740, v20
	v_cvt_pk_bf16_f32 v16, v16, s0
	global_store_short v[36:37], v16, off
	v_mul_f32_e32 v20, v21, v17
	ds_bpermute_b32 v21, v65, v20
	v_cmp_lt_i32_e64 s[0:1], s28, v33
	v_lshl_add_u64 v[36:37], v[192:193], 1, s[4:5]
	v_add_u32_e32 v192, 0xde00, v66
	v_cndmask_b32_e64 v16, 32, v219, s[0:1]
	v_add_u32_e32 v16, v16, v40
	v_or_b32_e32 v16, v16, v143
	v_ashrrev_i32_e32 v17, 31, v16
	v_lshl_add_u64 v[16:17], v[16:17], 3, s[74:75]
	s_waitcnt lgkmcnt(0)
	s_waitcnt vmcnt(39)
	v_mul_f32_e32 v21, v231, v21
	v_cndmask_b32_e64 v21, v21, -v21, vcc
	v_fmac_f32_e32 v21, v20, v230
	v_cmp_lt_i32_e64 s[100:101],s33,v32
	s_nop 1
	v_cndmask_b32_e64 v236,32,v222,s[100:101]
	v_add_u32_e32 v240,v236,v32
	v_cmp_lt_i32_e64 s[100:101],s30,v240
	s_nop 1
	v_cndmask_b32_e64 v242,8,v221,s[100:101]
	v_add_u32_e32 v244,v242,v240
	v_cmp_lt_i32_e64 s[100:101],s30,v244
	s_nop 1
	v_cndmask_b32_e64 v242,8,v221,s[100:101]
	v_add_u32_e32 v246,v242,v244
	v_lshlrev_b32_e32 v247,4,v246
	v_cmp_lt_i32_e64 s[100:101],s27,v246
	s_nop 1
	v_cndmask_b32_e64 v236,16,v218,s[100:101]
	v_add_u32_e32 v236,v236,v247
	v_or_b32_e32 v236,v236,v143
	v_ashrrev_i32_e32 v237,31,v236
	v_lshl_add_u64 v[236:237],v[236:237],3,s[74:75]
	global_load_dwordx2 v[230:231], v[236:237], off
	v_mul_f32_e32 v20, 0x3e16c740, v21
	v_cvt_pk_bf16_f32 v20, v20, s0
	global_store_short v[36:37], v20, off
	v_cmp_lt_i32_e64 s[0:1], s29, v33
	v_lshl_add_u64 v[20:21], v[192:193], 1, s[4:5]
	v_add_u32_e32 v192, 0xe100, v66
	v_cndmask_b32_e64 v34, 48, v220, s[0:1]
	v_add_u32_e32 v34, v34, v40
	v_or_b32_e32 v34, v34, v143
	v_ashrrev_i32_e32 v35, 31, v34
	v_lshl_add_u64 v[34:35], v[34:35], 3, s[74:75]
	s_waitcnt vmcnt(39)
	v_mul_f32_e32 v17, v233, v22
	v_cndmask_b32_e64 v17, v17, -v17, vcc
	v_fmac_f32_e32 v17, v18, v232
	v_cmp_lt_i32_e64 s[100:101],s33,v32
	s_nop 1
	v_cndmask_b32_e64 v236,32,v222,s[100:101]
	v_add_u32_e32 v240,v236,v32
	v_cmp_lt_i32_e64 s[100:101],s30,v240
	s_nop 1
	v_cndmask_b32_e64 v242,8,v221,s[100:101]
	v_add_u32_e32 v244,v242,v240
	v_cmp_lt_i32_e64 s[100:101],s30,v244
	s_nop 1
	v_cndmask_b32_e64 v242,8,v221,s[100:101]
	v_add_u32_e32 v246,v242,v244
	v_lshlrev_b32_e32 v247,4,v246
	v_cmp_lt_i32_e64 s[100:101],s28,v246
	s_nop 1
	v_cndmask_b32_e64 v242,32,v219,s[100:101]
	v_add_u32_e32 v242,v242,v247
	v_or_b32_e32 v242,v242,v143
	v_ashrrev_i32_e32 v243,31,v242
	v_lshl_add_u64 v[242:243],v[242:243],3,s[74:75]
	global_load_dwordx2 v[232:233], v[242:243], off
	v_mul_f32_e32 v16, 0x3e16c740, v17
	v_cvt_pk_bf16_f32 v16, v16, s0
	global_store_short v[20:21], v16, off
	v_mul_f32_e32 v18, v23, v19
	ds_bpermute_b32 v19, v65, v18
	s_waitcnt lgkmcnt(0)
	s_waitcnt vmcnt(39)
	v_mul_f32_e32 v17, v235, v19
	v_cndmask_b32_e64 v17, v17, -v17, vcc
	v_fmac_f32_e32 v17, v18, v234
	v_mov_b32_e32 v243, v1
	v_cmp_lt_i32_e64 s[100:101],s33,v32
	s_nop 1
	v_cndmask_b32_e64 v236,32,v222,s[100:101]
	v_add_u32_e32 v240,v236,v32
	v_cmp_lt_i32_e64 s[100:101],s30,v240
	s_nop 1
	v_cndmask_b32_e64 v242,8,v221,s[100:101]
	v_add_u32_e32 v244,v242,v240
	v_cmp_lt_i32_e64 s[100:101],s30,v244
	s_nop 1
	v_cndmask_b32_e64 v242,8,v221,s[100:101]
	v_add_u32_e32 v246,v242,v244
	v_lshlrev_b32_e32 v247,4,v246
	v_cmp_lt_i32_e64 s[100:101],s29,v246
	s_nop 1
	v_cndmask_b32_e64 v248,48,v220,s[100:101]
	v_add_u32_e32 v248,v248,v247
	v_or_b32_e32 v248,v248,v143
	v_ashrrev_i32_e32 v249,31,v248
	v_lshl_add_u64 v[248:249],v[248:249],3,s[74:75]
	global_load_dwordx2 v[234:235], v[248:249], off
	v_mul_f32_e32 v16, 0x3e16c740, v17
	v_cvt_pk_bf16_f32 v18, v16, s0
	v_lshl_add_u64 v[16:17], v[192:193], 1, s[4:5]
	global_store_short v[16:17], v18, off
	v_cmp_lt_i32_e64 s[0:1], s30, v33
	v_add_u32_e32 v22, s8, v138
	v_add_u32_e32 v192, 0xf300, v66
	v_cndmask_b32_e64 v16, 8, v221, s[0:1]
	v_add_u32_e32 v33, v16, v33
	v_lshlrev_b32_e32 v36, 4, v33
	v_add_u32_e32 v16, 0xfffeff00, v36
	v_cmp_lt_i32_e64 s[0:1], s31, v33
	s_nop 1
	v_cndmask_b32_e64 v16, v36, v16, s[0:1]
	v_or_b32_e32 v16, v16, v143
	v_ashrrev_i32_e32 v17, 31, v16
	v_lshl_add_u64 v[16:17], v[16:17], 3, s[74:75]
	v_lshl_add_u32 v16, v138, 2, v214
	ds_read_b128 v[16:19], v16
	v_mad_u64_u32 v[22:23], s[0:1], v22, s26, v[64:65]
	v_cmp_lt_i32_e64 s[0:1], s27, v33
	v_mov_b32_e32 v23, v193
	s_waitcnt lgkmcnt(0)
	v_mul_f32_e32 v16, v24, v16
	ds_bpermute_b32 v24, v65, v16
	v_cndmask_b32_e64 v34, 16, v218, s[0:1]
	v_add_u32_e32 v34, v34, v36
	v_or_b32_e32 v34, v34, v143
	v_lshl_add_u64 v[22:23], v[22:23], 1, s[4:5]
	v_ashrrev_i32_e32 v35, 31, v34
	v_lshl_add_u64 v[34:35], v[34:35], 3, s[74:75]
	v_mul_f32_e32 v18, v26, v18
	s_waitcnt lgkmcnt(0)
	s_waitcnt vmcnt(39)
	v_mul_f32_e32 v21, v175, v24
	v_cndmask_b32_e64 v21, v21, -v21, vcc
	v_fmac_f32_e32 v21, v16, v174
	v_cmp_lt_i32_e64 s[100:101],s33,v32
	s_nop 1
	v_cndmask_b32_e64 v236,32,v222,s[100:101]
	v_add_u32_e32 v240,v236,v32
	v_cmp_lt_i32_e64 s[100:101],s30,v240
	s_nop 1
	v_cndmask_b32_e64 v242,8,v221,s[100:101]
	v_add_u32_e32 v244,v242,v240
	v_cmp_lt_i32_e64 s[100:101],s30,v244
	s_nop 1
	v_cndmask_b32_e64 v242,8,v221,s[100:101]
	v_add_u32_e32 v246,v242,v244
	v_cmp_lt_i32_e64 s[100:101],s30,v246
	s_nop 1
	v_cndmask_b32_e64 v242,8,v221,s[100:101]
	v_add_u32_e32 v248,v242,v246
	v_lshlrev_b32_e32 v249,4,v248
	v_add_u32_e32 v242,0xfffeff00,v249
	v_cmp_lt_i32_e64 s[100:101],s31,v248
	s_nop 1
	v_cndmask_b32_e64 v242,v249,v242,s[100:101]
	v_or_b32_e32 v242,v242,v143
	v_ashrrev_i32_e32 v243,31,v242
	v_lshl_add_u64 v[242:243],v[242:243],3,s[74:75]
	global_load_dwordx2 v[174:175], v[242:243], off
	v_mul_f32_e32 v16, 0x3e16c740, v21
	v_cvt_pk_bf16_f32 v16, v16, s0
	global_store_short v[22:23], v16, off
	v_mul_f32_e32 v24, v25, v17
	ds_bpermute_b32 v25, v65, v24
	v_cmp_lt_i32_e64 s[0:1], s28, v33
	v_lshl_add_u64 v[22:23], v[192:193], 1, s[4:5]
	v_add_u32_e32 v192, 0xf600, v66
	v_cndmask_b32_e64 v16, 32, v219, s[0:1]
	v_add_u32_e32 v16, v16, v36
	v_or_b32_e32 v16, v16, v143
	v_ashrrev_i32_e32 v17, 31, v16
	v_lshl_add_u64 v[16:17], v[16:17], 3, s[74:75]
	s_waitcnt lgkmcnt(0)
	s_waitcnt vmcnt(39)
	v_mul_f32_e32 v21, v177, v25
	v_cndmask_b32_e64 v21, v21, -v21, vcc
	v_fmac_f32_e32 v21, v24, v176
	v_cmp_lt_i32_e64 s[100:101],s33,v32
	s_nop 1
	v_cndmask_b32_e64 v236,32,v222,s[100:101]
	v_add_u32_e32 v240,v236,v32
	v_cmp_lt_i32_e64 s[100:101],s30,v240
	s_nop 1
	v_cndmask_b32_e64 v242,8,v221,s[100:101]
	v_add_u32_e32 v244,v242,v240
	v_cmp_lt_i32_e64 s[100:101],s30,v244
	s_nop 1
	v_cndmask_b32_e64 v242,8,v221,s[100:101]
	v_add_u32_e32 v246,v242,v244
	v_cmp_lt_i32_e64 s[100:101],s30,v246
	s_nop 1
	v_cndmask_b32_e64 v242,8,v221,s[100:101]
	v_add_u32_e32 v248,v242,v246
	v_lshlrev_b32_e32 v249,4,v248
	v_cmp_lt_i32_e64 s[100:101],s27,v248
	s_nop 1
	v_cndmask_b32_e64 v250,16,v218,s[100:101]
	v_add_u32_e32 v250,v250,v249
	v_or_b32_e32 v250,v250,v143
	v_ashrrev_i32_e32 v251,31,v250
	v_lshl_add_u64 v[250:251],v[250:251],3,s[74:75]
	global_load_dwordx2 v[176:177], v[250:251], off
	v_mul_f32_e32 v20, 0x3e16c740, v21
	v_cvt_pk_bf16_f32 v20, v20, s0
	global_store_short v[22:23], v20, off
	ds_bpermute_b32 v24, v65, v18
	v_cmp_lt_i32_e64 s[0:1], s29, v33
	v_lshl_add_u64 v[20:21], v[192:193], 1, s[4:5]
	v_add_u32_e32 v192, 0xf900, v66
	v_cndmask_b32_e64 v22, 48, v220, s[0:1]
	v_add_u32_e32 v22, v22, v36
	v_or_b32_e32 v22, v22, v143
	v_ashrrev_i32_e32 v23, 31, v22
	v_lshl_add_u64 v[22:23], v[22:23], 3, s[74:75]
	s_waitcnt lgkmcnt(0)
	s_waitcnt vmcnt(39)
	v_mul_f32_e32 v17, v179, v24
	v_cndmask_b32_e64 v17, v17, -v17, vcc
	v_fmac_f32_e32 v17, v18, v178
	v_cmp_lt_i32_e64 s[100:101],s33,v32
	s_nop 1
	v_cndmask_b32_e64 v236,32,v222,s[100:101]
	v_add_u32_e32 v240,v236,v32
	v_cmp_lt_i32_e64 s[100:101],s30,v240
	s_nop 1
	v_cndmask_b32_e64 v242,8,v221,s[100:101]
	v_add_u32_e32 v244,v242,v240
	v_cmp_lt_i32_e64 s[100:101],s30,v244
	s_nop 1
	v_cndmask_b32_e64 v242,8,v221,s[100:101]
	v_add_u32_e32 v246,v242,v244
	v_cmp_lt_i32_e64 s[100:101],s30,v246
	s_nop 1
	v_cndmask_b32_e64 v242,8,v221,s[100:101]
	v_add_u32_e32 v248,v242,v246
	v_lshlrev_b32_e32 v249,4,v248
	v_cmp_lt_i32_e64 s[100:101],s28,v248
	s_nop 1
	v_cndmask_b32_e64 v242,32,v219,s[100:101]
	v_add_u32_e32 v242,v242,v249
	v_or_b32_e32 v242,v242,v143
	v_ashrrev_i32_e32 v243,31,v242
	v_lshl_add_u64 v[242:243],v[242:243],3,s[74:75]
	global_load_dwordx2 v[178:179], v[242:243], off
	v_mul_f32_e32 v16, 0x3e16c740, v17
	v_cvt_pk_bf16_f32 v16, v16, s0
	global_store_short v[20:21], v16, off
	v_mul_f32_e32 v18, v27, v19
	ds_bpermute_b32 v19, v65, v18
	s_waitcnt lgkmcnt(0)
	s_waitcnt vmcnt(39)
	v_mul_f32_e32 v17, v181, v19
	v_cndmask_b32_e64 v17, v17, -v17, vcc
	v_fmac_f32_e32 v17, v18, v180
	v_mov_b32_e32 v243, v1
	v_cmp_lt_i32_e64 s[100:101],s33,v32
	s_nop 1
	v_cndmask_b32_e64 v236,32,v222,s[100:101]
	v_add_u32_e32 v240,v236,v32
	v_cmp_lt_i32_e64 s[100:101],s30,v240
	s_nop 1
	v_cndmask_b32_e64 v242,8,v221,s[100:101]
	v_add_u32_e32 v244,v242,v240
	v_cmp_lt_i32_e64 s[100:101],s30,v244
	s_nop 1
	v_cndmask_b32_e64 v242,8,v221,s[100:101]
	v_add_u32_e32 v246,v242,v244
	v_cmp_lt_i32_e64 s[100:101],s30,v246
	s_nop 1
	v_cndmask_b32_e64 v242,8,v221,s[100:101]
	v_add_u32_e32 v248,v242,v246
	v_lshlrev_b32_e32 v249,4,v248
	v_cmp_lt_i32_e64 s[100:101],s29,v248
	s_nop 1
	v_cndmask_b32_e64 v250,48,v220,s[100:101]
	v_add_u32_e32 v250,v250,v249
	v_or_b32_e32 v250,v250,v143
	v_ashrrev_i32_e32 v251,31,v250
	v_lshl_add_u64 v[250:251],v[250:251],3,s[74:75]
	global_load_dwordx2 v[180:181], v[250:251], off
	v_mul_f32_e32 v16, 0x3e16c740, v17
	v_cvt_pk_bf16_f32 v18, v16, s0
	v_lshl_add_u64 v[16:17], v[192:193], 1, s[4:5]
	global_store_short v[16:17], v18, off
	v_cmp_lt_i32_e64 s[0:1], s30, v33
	v_add_u32_e32 v22, s8, v137
	v_add_u32_e32 v192, 0x10b00, v66
	v_cndmask_b32_e64 v16, 8, v221, s[0:1]
	v_add_u32_e32 v26, v16, v33
	v_lshlrev_b32_e32 v27, 4, v26
	v_add_u32_e32 v16, 0xfffeff00, v27
	v_cmp_lt_i32_e64 s[0:1], s31, v26
	s_nop 1
	v_cndmask_b32_e64 v16, v27, v16, s[0:1]
	v_or_b32_e32 v16, v16, v143
	v_ashrrev_i32_e32 v17, 31, v16
	v_lshl_add_u64 v[16:17], v[16:17], 3, s[74:75]
	v_lshl_add_u32 v16, v137, 2, v214
	ds_read_b128 v[16:19], v16
	v_mad_u64_u32 v[22:23], s[0:1], v22, s26, v[64:65]
	v_cmp_lt_i32_e64 s[0:1], s27, v26
	v_mov_b32_e32 v23, v193
	s_waitcnt lgkmcnt(0)
	v_mul_f32_e32 v16, v28, v16
	ds_bpermute_b32 v28, v65, v16
	v_cndmask_b32_e64 v24, 16, v218, s[0:1]
	v_add_u32_e32 v24, v24, v27
	v_or_b32_e32 v24, v24, v143
	v_lshl_add_u64 v[22:23], v[22:23], 1, s[4:5]
	v_ashrrev_i32_e32 v25, 31, v24
	v_lshl_add_u64 v[24:25], v[24:25], 3, s[74:75]
	v_mul_f32_e32 v18, v30, v18
	s_waitcnt lgkmcnt(0)
	s_waitcnt vmcnt(39)
	v_mul_f32_e32 v21, v183, v28
	v_cndmask_b32_e64 v21, v21, -v21, vcc
	v_fmac_f32_e32 v21, v16, v182
	v_mul_f32_e32 v16, 0x3e16c740, v21
	v_cvt_pk_bf16_f32 v16, v16, s0
	global_store_short v[22:23], v16, off
	v_mul_f32_e32 v24, v29, v17
	ds_bpermute_b32 v25, v65, v24
	v_cmp_lt_i32_e64 s[0:1], s28, v26
	v_lshl_add_u64 v[22:23], v[192:193], 1, s[4:5]
	v_add_u32_e32 v192, 0x10e00, v66
	v_cndmask_b32_e64 v16, 32, v219, s[0:1]
	v_add_u32_e32 v16, v16, v27
	v_or_b32_e32 v16, v16, v143
	v_ashrrev_i32_e32 v17, 31, v16
	v_lshl_add_u64 v[16:17], v[16:17], 3, s[74:75]
	s_waitcnt lgkmcnt(0)
	s_waitcnt vmcnt(38)
	v_mul_f32_e32 v21, v185, v25
	v_cndmask_b32_e64 v21, v21, -v21, vcc
	v_fmac_f32_e32 v21, v24, v184
	v_mul_f32_e32 v20, 0x3e16c740, v21
	v_cvt_pk_bf16_f32 v20, v20, s0
	global_store_short v[22:23], v20, off
	ds_bpermute_b32 v24, v65, v18
	v_cmp_lt_i32_e64 s[0:1], s29, v26
	v_lshl_add_u64 v[20:21], v[192:193], 1, s[4:5]
	v_add_u32_e32 v192, 0x11100, v66
	v_cndmask_b32_e64 v22, 48, v220, s[0:1]
	v_add_u32_e32 v22, v22, v27
	v_or_b32_e32 v22, v22, v143
	v_ashrrev_i32_e32 v23, 31, v22
	v_lshl_add_u64 v[22:23], v[22:23], 3, s[74:75]
	s_waitcnt lgkmcnt(0)
	s_waitcnt vmcnt(37)
	v_mul_f32_e32 v17, v187, v24
	v_cndmask_b32_e64 v17, v17, -v17, vcc
	v_fmac_f32_e32 v17, v18, v186
	v_mul_f32_e32 v16, 0x3e16c740, v17
	v_cvt_pk_bf16_f32 v16, v16, s0
	global_store_short v[20:21], v16, off
	v_mul_f32_e32 v18, v31, v19
	ds_bpermute_b32 v19, v65, v18
	s_waitcnt lgkmcnt(0)
	s_waitcnt vmcnt(36)
	v_mul_f32_e32 v17, v189, v19
	v_cndmask_b32_e64 v17, v17, -v17, vcc
	v_fmac_f32_e32 v17, v18, v188
	v_mul_f32_e32 v16, 0x3e16c740, v17
	v_cvt_pk_bf16_f32 v18, v16, s0
	v_lshl_add_u64 v[16:17], v[192:193], 1, s[4:5]
	global_store_short v[16:17], v18, off
	v_cmp_lt_i32_e64 s[0:1], s33, v32
	v_add_u32_e32 v22, s8, v136
	v_add_u32_e32 v192, 0x12300, v66
	v_cndmask_b32_e64 v16, 32, v222, s[0:1]
	v_add_u32_e32 v26, v16, v32
	v_lshlrev_b32_e32 v27, 4, v26
	v_add_u32_e32 v16, 0xfffeff00, v27
	v_cmp_lt_i32_e64 s[0:1], s31, v26
	s_nop 1
	v_cndmask_b32_e64 v16, v27, v16, s[0:1]
	v_or_b32_e32 v16, v16, v143
	v_ashrrev_i32_e32 v17, 31, v16
	v_lshl_add_u64 v[16:17], v[16:17], 3, s[74:75]
	v_lshl_add_u32 v16, v136, 2, v214
	ds_read_b128 v[16:19], v16
	v_mad_u64_u32 v[22:23], s[0:1], v22, s26, v[64:65]
	v_cmp_lt_i32_e64 s[0:1], s27, v26
	v_mov_b32_e32 v23, v193
	s_waitcnt lgkmcnt(0)
	v_mul_f32_e32 v0, v0, v16
	ds_bpermute_b32 v16, v65, v0
	v_cndmask_b32_e64 v24, 16, v218, s[0:1]
	v_add_u32_e32 v24, v24, v27
	v_or_b32_e32 v24, v24, v143
	v_lshl_add_u64 v[22:23], v[22:23], 1, s[4:5]
	v_ashrrev_i32_e32 v25, 31, v24
	v_lshl_add_u64 v[24:25], v[24:25], 3, s[74:75]
	v_mul_f32_e32 v2, v2, v18
	ds_bpermute_b32 v18, v65, v2
	s_waitcnt lgkmcnt(1)
	s_waitcnt vmcnt(35)
	v_mul_f32_e32 v16, v191, v16
	v_cndmask_b32_e64 v16, v16, -v16, vcc
	v_fmac_f32_e32 v16, v0, v190
	v_mul_f32_e32 v0, 0x3e16c740, v16
	v_cvt_pk_bf16_f32 v0, v0, s0
	global_store_short v[22:23], v0, off
	v_mul_f32_e32 v16, v1, v17
	ds_bpermute_b32 v17, v65, v16
	v_cmp_lt_i32_e64 s[0:1], s28, v26
	v_lshl_add_u64 v[22:23], v[192:193], 1, s[4:5]
	v_add_u32_e32 v192, 0x12600, v66
	v_cndmask_b32_e64 v0, 32, v219, s[0:1]
	v_add_u32_e32 v0, v0, v27
	v_or_b32_e32 v0, v0, v143
	v_ashrrev_i32_e32 v1, 31, v0
	v_lshl_add_u64 v[0:1], v[0:1], 3, s[74:75]
	s_waitcnt lgkmcnt(0)
	s_waitcnt vmcnt(34)
	v_mul_f32_e32 v17, v195, v17
	v_cndmask_b32_e64 v17, v17, -v17, vcc
	v_fmac_f32_e32 v17, v16, v194
	v_mul_f32_e32 v16, 0x3e16c740, v17
	v_cvt_pk_bf16_f32 v16, v16, s0
	global_store_short v[22:23], v16, off
	v_cmp_lt_i32_e64 s[0:1], s29, v26
	v_lshl_add_u64 v[16:17], v[192:193], 1, s[4:5]
	v_add_u32_e32 v192, 0x12900, v66
	v_cndmask_b32_e64 v20, 48, v220, s[0:1]
	v_add_u32_e32 v20, v20, v27
	v_or_b32_e32 v20, v20, v143
	v_ashrrev_i32_e32 v21, 31, v20
	v_lshl_add_u64 v[20:21], v[20:21], 3, s[74:75]
	s_waitcnt vmcnt(33)
	v_mul_f32_e32 v1, v197, v18
	v_cndmask_b32_e64 v1, v1, -v1, vcc
	v_fmac_f32_e32 v1, v2, v196
	v_mul_f32_e32 v0, 0x3e16c740, v1
	v_cvt_pk_bf16_f32 v0, v0, s0
	global_store_short v[16:17], v0, off
	v_mul_f32_e32 v2, v3, v19
	ds_bpermute_b32 v3, v65, v2
	s_waitcnt lgkmcnt(0)
	s_waitcnt vmcnt(32)
	v_mul_f32_e32 v1, v199, v3
	v_cndmask_b32_e64 v1, v1, -v1, vcc
	v_fmac_f32_e32 v1, v2, v198
	v_mul_f32_e32 v0, 0x3e16c740, v1
	v_cvt_pk_bf16_f32 v2, v0, s0
	v_lshl_add_u64 v[0:1], v[192:193], 1, s[4:5]
	global_store_short v[0:1], v2, off
	v_cmp_lt_i32_e64 s[0:1], s30, v26
	v_add_u32_e32 v18, s8, v135
	v_add_u32_e32 v192, 0x13b00, v66
	v_cndmask_b32_e64 v0, 8, v221, s[0:1]
	v_add_u32_e32 v22, v0, v26
	v_lshlrev_b32_e32 v23, 4, v22
	v_add_u32_e32 v0, 0xfffeff00, v23
	v_cmp_lt_i32_e64 s[0:1], s31, v22
	s_nop 1
	v_cndmask_b32_e64 v0, v23, v0, s[0:1]
	v_or_b32_e32 v0, v0, v143
	v_ashrrev_i32_e32 v1, 31, v0
	v_lshl_add_u64 v[0:1], v[0:1], 3, s[74:75]
	v_lshl_add_u32 v0, v135, 2, v214
	ds_read_b128 v[0:3], v0
	v_mad_u64_u32 v[18:19], s[0:1], v18, s26, v[64:65]
	v_cmp_lt_i32_e64 s[0:1], s27, v22
	v_mov_b32_e32 v19, v193
	s_waitcnt lgkmcnt(0)
	v_mul_f32_e32 v0, v4, v0
	ds_bpermute_b32 v4, v65, v0
	v_cndmask_b32_e64 v20, 16, v218, s[0:1]
	v_add_u32_e32 v20, v20, v23
	v_or_b32_e32 v20, v20, v143
	v_lshl_add_u64 v[18:19], v[18:19], 1, s[4:5]
	v_ashrrev_i32_e32 v21, 31, v20
	v_lshl_add_u64 v[20:21], v[20:21], 3, s[74:75]
	v_mul_f32_e32 v2, v6, v2
	ds_bpermute_b32 v6, v65, v2
	s_waitcnt lgkmcnt(1)
	s_waitcnt vmcnt(31)
	v_mul_f32_e32 v4, v205, v4
	v_cndmask_b32_e64 v4, v4, -v4, vcc
	v_fmac_f32_e32 v4, v0, v204
	v_mul_f32_e32 v0, 0x3e16c740, v4
	v_cvt_pk_bf16_f32 v0, v0, s0
	global_store_short v[18:19], v0, off
	v_mul_f32_e32 v4, v5, v1
	ds_bpermute_b32 v5, v65, v4
	v_cmp_lt_i32_e64 s[0:1], s28, v22
	v_lshl_add_u64 v[18:19], v[192:193], 1, s[4:5]
	v_add_u32_e32 v192, 0x13e00, v66
	v_cndmask_b32_e64 v0, 32, v219, s[0:1]
	v_add_u32_e32 v0, v0, v23
	v_or_b32_e32 v0, v0, v143
	v_ashrrev_i32_e32 v1, 31, v0
	v_lshl_add_u64 v[0:1], v[0:1], 3, s[74:75]
	s_waitcnt lgkmcnt(0)
	s_waitcnt vmcnt(30)
	v_mul_f32_e32 v5, v207, v5
	v_cndmask_b32_e64 v5, v5, -v5, vcc
	v_fmac_f32_e32 v5, v4, v206
	v_mul_f32_e32 v4, 0x3e16c740, v5
	v_cvt_pk_bf16_f32 v4, v4, s0
	global_store_short v[18:19], v4, off
	v_cmp_lt_i32_e64 s[0:1], s29, v22
	v_lshl_add_u64 v[4:5], v[192:193], 1, s[4:5]
	v_add_u32_e32 v192, 0x14100, v66
	v_cndmask_b32_e64 v16, 48, v220, s[0:1]
	v_add_u32_e32 v16, v16, v23
	v_or_b32_e32 v16, v16, v143
	v_ashrrev_i32_e32 v17, 31, v16
	v_lshl_add_u64 v[16:17], v[16:17], 3, s[74:75]
	s_waitcnt vmcnt(29)
	v_mul_f32_e32 v1, v225, v6
	v_cndmask_b32_e64 v1, v1, -v1, vcc
	v_fmac_f32_e32 v1, v2, v224
	v_mul_f32_e32 v0, 0x3e16c740, v1
	v_cvt_pk_bf16_f32 v0, v0, s0
	global_store_short v[4:5], v0, off
	v_mul_f32_e32 v2, v7, v3
	ds_bpermute_b32 v3, v65, v2
	s_waitcnt lgkmcnt(0)
	s_waitcnt vmcnt(28)
	v_mul_f32_e32 v1, v227, v3
	v_cndmask_b32_e64 v1, v1, -v1, vcc
	v_fmac_f32_e32 v1, v2, v226
	v_mul_f32_e32 v0, 0x3e16c740, v1
	v_cvt_pk_bf16_f32 v2, v0, s0
	v_lshl_add_u64 v[0:1], v[192:193], 1, s[4:5]
	global_store_short v[0:1], v2, off
	v_cmp_lt_i32_e64 s[0:1], s30, v22
	v_add_u32_e32 v6, s8, v134
	v_add_u32_e32 v192, 0x15300, v66
	v_cndmask_b32_e64 v0, 8, v221, s[0:1]
	v_add_u32_e32 v18, v0, v22
	v_lshlrev_b32_e32 v19, 4, v18
	v_add_u32_e32 v0, 0xfffeff00, v19
	v_cmp_lt_i32_e64 s[0:1], s31, v18
	s_nop 1
	v_cndmask_b32_e64 v0, v19, v0, s[0:1]
	v_or_b32_e32 v0, v0, v143
	v_ashrrev_i32_e32 v1, 31, v0
	v_lshl_add_u64 v[0:1], v[0:1], 3, s[74:75]
	v_lshl_add_u32 v0, v134, 2, v214
	ds_read_b128 v[0:3], v0
	v_mad_u64_u32 v[6:7], s[0:1], v6, s26, v[64:65]
	v_cmp_lt_i32_e64 s[0:1], s27, v18
	v_mov_b32_e32 v7, v193
	s_waitcnt lgkmcnt(0)
	v_mul_f32_e32 v0, v8, v0
	ds_bpermute_b32 v8, v65, v0
	v_cndmask_b32_e64 v16, 16, v218, s[0:1]
	v_add_u32_e32 v16, v16, v19
	v_or_b32_e32 v16, v16, v143
	v_lshl_add_u64 v[6:7], v[6:7], 1, s[4:5]
	v_ashrrev_i32_e32 v17, 31, v16
	v_lshl_add_u64 v[16:17], v[16:17], 3, s[74:75]
	v_mul_f32_e32 v2, v10, v2
	s_waitcnt lgkmcnt(0)
	s_waitcnt vmcnt(27)
	v_mul_f32_e32 v5, v229, v8
	v_cndmask_b32_e64 v5, v5, -v5, vcc
	v_fmac_f32_e32 v5, v0, v228
	v_mul_f32_e32 v0, 0x3e16c740, v5
	v_cvt_pk_bf16_f32 v0, v0, s0
	global_store_short v[6:7], v0, off
	v_mul_f32_e32 v8, v9, v1
	ds_bpermute_b32 v9, v65, v8
	v_cmp_lt_i32_e64 s[0:1], s28, v18
	v_lshl_add_u64 v[6:7], v[192:193], 1, s[4:5]
	v_add_u32_e32 v192, 0x15600, v66
	v_cndmask_b32_e64 v0, 32, v219, s[0:1]
	v_add_u32_e32 v0, v0, v19
	v_or_b32_e32 v0, v0, v143
	v_ashrrev_i32_e32 v1, 31, v0
	v_lshl_add_u64 v[0:1], v[0:1], 3, s[74:75]
	s_waitcnt lgkmcnt(0)
	s_waitcnt vmcnt(26)
	v_mul_f32_e32 v5, v231, v9
	v_cndmask_b32_e64 v5, v5, -v5, vcc
	v_fmac_f32_e32 v5, v8, v230
	v_mul_f32_e32 v4, 0x3e16c740, v5
	v_cvt_pk_bf16_f32 v4, v4, s0
	global_store_short v[6:7], v4, off
	ds_bpermute_b32 v8, v65, v2
	v_cmp_lt_i32_e64 s[0:1], s29, v18
	v_lshl_add_u64 v[4:5], v[192:193], 1, s[4:5]
	v_add_u32_e32 v192, 0x15900, v66
	v_cndmask_b32_e64 v6, 48, v220, s[0:1]
	v_add_u32_e32 v6, v6, v19
	v_or_b32_e32 v6, v6, v143
	v_ashrrev_i32_e32 v7, 31, v6
	v_lshl_add_u64 v[6:7], v[6:7], 3, s[74:75]
	s_waitcnt lgkmcnt(0)
	s_waitcnt vmcnt(25)
	v_mul_f32_e32 v1, v233, v8
	v_cndmask_b32_e64 v1, v1, -v1, vcc
	v_fmac_f32_e32 v1, v2, v232
	v_mul_f32_e32 v0, 0x3e16c740, v1
	v_cvt_pk_bf16_f32 v0, v0, s0
	global_store_short v[4:5], v0, off
	v_mul_f32_e32 v2, v11, v3
	ds_bpermute_b32 v3, v65, v2
	s_waitcnt lgkmcnt(0)
	s_waitcnt vmcnt(24)
	v_mul_f32_e32 v1, v235, v3
	v_cndmask_b32_e64 v1, v1, -v1, vcc
	v_fmac_f32_e32 v1, v2, v234
	v_mul_f32_e32 v0, 0x3e16c740, v1
	v_cvt_pk_bf16_f32 v2, v0, s0
	v_lshl_add_u64 v[0:1], v[192:193], 1, s[4:5]
	global_store_short v[0:1], v2, off
	v_cmp_lt_i32_e64 s[0:1], s30, v18
	v_add_u32_e32 v192, 0x16b00, v66
	s_nop 0
	v_cndmask_b32_e64 v0, 8, v221, s[0:1]
	v_add_u32_e32 v10, v0, v18
	v_lshlrev_b32_e32 v11, 4, v10
	v_add_u32_e32 v0, 0xfffeff00, v11
	v_cmp_lt_i32_e64 s[0:1], s31, v10
	s_nop 1
	v_cndmask_b32_e64 v0, v11, v0, s[0:1]
	v_or_b32_e32 v0, v0, v143
	v_ashrrev_i32_e32 v1, 31, v0
	v_lshl_add_u64 v[0:1], v[0:1], 3, s[74:75]
	v_or_b32_e32 v0, 0x78, v129
	v_add_u32_e32 v6, s8, v0
	v_lshl_add_u32 v0, v0, 2, v214
	ds_read_b128 v[0:3], v0
	v_mad_u64_u32 v[6:7], s[0:1], v6, s26, v[64:65]
	v_cmp_lt_i32_e64 s[0:1], s27, v10
	v_mov_b32_e32 v7, v193
	s_waitcnt lgkmcnt(0)
	v_mul_f32_e32 v0, v12, v0
	ds_bpermute_b32 v12, v65, v0
	v_cndmask_b32_e64 v8, 16, v218, s[0:1]
	v_add_u32_e32 v8, v8, v11
	v_or_b32_e32 v8, v8, v143
	v_lshl_add_u64 v[6:7], v[6:7], 1, s[4:5]
	v_ashrrev_i32_e32 v9, 31, v8
	v_lshl_add_u64 v[8:9], v[8:9], 3, s[74:75]
	v_mul_f32_e32 v2, v14, v2
	s_waitcnt lgkmcnt(0)
	s_waitcnt vmcnt(23)
	v_mul_f32_e32 v5, v175, v12
	v_cndmask_b32_e64 v5, v5, -v5, vcc
	v_fmac_f32_e32 v5, v0, v174
	v_mul_f32_e32 v0, 0x3e16c740, v5
	v_cvt_pk_bf16_f32 v0, v0, s0
	global_store_short v[6:7], v0, off
	v_mul_f32_e32 v8, v13, v1
	ds_bpermute_b32 v9, v65, v8
	v_cmp_lt_i32_e64 s[0:1], s28, v10
	v_lshl_add_u64 v[6:7], v[192:193], 1, s[4:5]
	v_add_u32_e32 v192, 0x16e00, v66
	v_cndmask_b32_e64 v0, 32, v219, s[0:1]
	v_add_u32_e32 v0, v0, v11
	v_or_b32_e32 v0, v0, v143
	v_ashrrev_i32_e32 v1, 31, v0
	v_lshl_add_u64 v[0:1], v[0:1], 3, s[74:75]
	s_waitcnt lgkmcnt(0)
	s_waitcnt vmcnt(22)
	v_mul_f32_e32 v5, v177, v9
	v_cndmask_b32_e64 v5, v5, -v5, vcc
	v_fmac_f32_e32 v5, v8, v176
	v_mul_f32_e32 v4, 0x3e16c740, v5
	v_cvt_pk_bf16_f32 v4, v4, s0
	global_store_short v[6:7], v4, off
	ds_bpermute_b32 v8, v65, v2
	v_cmp_lt_i32_e64 s[0:1], s29, v10
	v_lshl_add_u64 v[4:5], v[192:193], 1, s[4:5]
	v_add_u32_e32 v192, 0x17100, v66
	v_cndmask_b32_e64 v6, 48, v220, s[0:1]
	v_add_u32_e32 v6, v6, v11
	v_or_b32_e32 v6, v6, v143
	v_ashrrev_i32_e32 v7, 31, v6
	v_lshl_add_u64 v[6:7], v[6:7], 3, s[74:75]
	s_waitcnt lgkmcnt(0)
	s_waitcnt vmcnt(21)
	v_mul_f32_e32 v1, v179, v8
	v_cndmask_b32_e64 v1, v1, -v1, vcc
	v_fmac_f32_e32 v1, v2, v178
	v_mul_f32_e32 v0, 0x3e16c740, v1
	v_cvt_pk_bf16_f32 v0, v0, s0
	global_store_short v[4:5], v0, off
	v_mul_f32_e32 v2, v15, v3
	ds_bpermute_b32 v3, v65, v2
	s_waitcnt lgkmcnt(0)
	s_waitcnt vmcnt(20)
	v_mul_f32_e32 v1, v181, v3
	v_cndmask_b32_e64 v1, v1, -v1, vcc
	v_fmac_f32_e32 v1, v2, v180
	v_mul_f32_e32 v0, 0x3e16c740, v1
	v_cvt_pk_bf16_f32 v2, v0, s0
	v_lshl_add_u64 v[0:1], v[192:193], 1, s[4:5]
	global_store_short v[0:1], v2, off
	s_branch .LBB0_3025

.LBB0_3640:
	s_and_b64 vcc, exec, s[10:11]
	s_cbranch_vccz .LBB0_3578
	v_mov_b32_e32 v172, v208
	s_nop 0
	v_ashrrev_i32_e32 v0, 1, v172
	v_and_b32_e32 v0, 0xffffff80, v0
	s_waitcnt vmcnt(7)
	v_lshrrev_b32_e32 v130, 3, v172
	v_and_b32_e32 v173, 4, v130
	v_add_u32_e32 v174, s6, v0
	s_waitcnt vmcnt(6)
	v_or_b32_e32 v136, v174, v173
	v_min_i32_e32 v130, 0x403f, v136
	v_mul_hi_i32 v0, v130, s83
	v_lshrrev_b32_e32 v131, 31, v0
	v_ashrrev_i32_e32 v0, 11, v0
	v_add_u32_e32 v0, v0, v131
	v_mad_i32_i24 v130, v0, s84, v130
	v_cmp_lt_i32_e32 vcc, 15, v130
	s_and_saveexec_b64 s[2:3], vcc
	s_xor_b64 s[2:3], exec, s[2:3]
	v_lshlrev_b32_e32 v0, 12, v0
	v_add3_u32 v130, v0, v130, -16
	v_ashrrev_i32_e32 v131, 31, v130
	v_lshlrev_b64 v[130:131], 12, v[130:131]
	v_lshl_add_u64 v[132:133], s[88:89], 0, v[130:131]
	s_andn2_saveexec_b64 s[2:3], s[2:3]
	v_lshlrev_b32_e32 v0, 14, v0
	v_lshl_add_u32 v130, v130, 10, v0
	v_ashrrev_i32_e32 v131, 31, v130
	v_lshl_add_u64 v[132:133], v[130:131], 2, s[16:17]
	s_or_b64 exec, exec, s[2:3]
	v_bfe_u32 v0, v172, 6, 2
	v_and_b32_e32 v175, 31, v172
	v_lshlrev_b32_e32 v130, 6, v0
	v_or3_b32 v130, v130, s0, v175
	v_ashrrev_i32_e32 v131, 31, v130
	v_lshl_add_u64 v[132:133], v[130:131], 2, v[132:133]
	global_load_dword v134, v[132:133], off
	global_load_dword v167, v[132:133], off offset:128
	v_or_b32_e32 v166, 1, v136
	v_min_i32_e32 v132, 0x403f, v166
	v_mul_hi_i32 v133, v132, s83
	v_lshrrev_b32_e32 v135, 31, v133
	v_ashrrev_i32_e32 v133, 11, v133
	v_add_u32_e32 v135, v133, v135
	v_mad_i32_i24 v137, v135, s84, v132
	v_cmp_lt_i32_e32 vcc, 15, v137
	s_and_saveexec_b64 s[0:1], vcc
	s_xor_b64 s[0:1], exec, s[0:1]
	v_lshlrev_b32_e32 v132, 12, v135
	v_add3_u32 v132, v132, v137, -16
	v_ashrrev_i32_e32 v133, 31, v132
	v_lshlrev_b64 v[132:133], 12, v[132:133]
	v_lshl_add_u64 v[132:133], s[88:89], 0, v[132:133]
	s_andn2_saveexec_b64 s[0:1], s[0:1]
	v_lshlrev_b32_e32 v132, 14, v135
	v_lshl_add_u32 v132, v137, 10, v132
	v_ashrrev_i32_e32 v133, 31, v132
	v_lshl_add_u64 v[132:133], v[132:133], 2, s[16:17]
	s_or_b64 exec, exec, s[0:1]
	v_lshl_add_u64 v[132:133], v[130:131], 2, v[132:133]
	global_load_dword v194, v[132:133], off
	global_load_dword v165, v[132:133], off offset:128
	v_or_b32_e32 v164, 2, v136
	v_min_i32_e32 v132, 0x403f, v164
	v_mul_hi_i32 v133, v132, s83
	v_lshrrev_b32_e32 v135, 31, v133
	v_ashrrev_i32_e32 v133, 11, v133
	v_add_u32_e32 v135, v133, v135
	v_mad_i32_i24 v137, v135, s84, v132
	v_cmp_lt_i32_e32 vcc, 15, v137
	s_and_saveexec_b64 s[0:1], vcc
	s_xor_b64 s[0:1], exec, s[0:1]
	v_lshlrev_b32_e32 v132, 12, v135
	v_add3_u32 v132, v132, v137, -16
	v_ashrrev_i32_e32 v133, 31, v132
	v_lshlrev_b64 v[132:133], 12, v[132:133]
	v_lshl_add_u64 v[132:133], s[88:89], 0, v[132:133]
	s_andn2_saveexec_b64 s[0:1], s[0:1]
	v_lshlrev_b32_e32 v132, 14, v135
	v_lshl_add_u32 v132, v137, 10, v132
	v_ashrrev_i32_e32 v133, 31, v132
	v_lshl_add_u64 v[132:133], v[132:133], 2, s[16:17]
	s_or_b64 exec, exec, s[0:1]
	v_lshl_add_u64 v[132:133], v[130:131], 2, v[132:133]
	global_load_dword v193, v[132:133], off
	global_load_dword v163, v[132:133], off offset:128
	v_or_b32_e32 v162, 3, v136
	v_min_i32_e32 v132, 0x403f, v162
	v_mul_hi_i32 v133, v132, s83
	v_lshrrev_b32_e32 v135, 31, v133
	v_ashrrev_i32_e32 v133, 11, v133
	v_add_u32_e32 v135, v133, v135
	v_mad_i32_i24 v137, v135, s84, v132
	v_cmp_lt_i32_e32 vcc, 15, v137
	s_and_saveexec_b64 s[0:1], vcc
	s_xor_b64 s[0:1], exec, s[0:1]
	v_lshlrev_b32_e32 v132, 12, v135
	v_add3_u32 v132, v132, v137, -16
	v_ashrrev_i32_e32 v133, 31, v132
	v_lshlrev_b64 v[132:133], 12, v[132:133]
	v_lshl_add_u64 v[132:133], s[88:89], 0, v[132:133]
	s_andn2_saveexec_b64 s[0:1], s[0:1]
	v_lshlrev_b32_e32 v132, 14, v135
	v_lshl_add_u32 v132, v137, 10, v132
	v_ashrrev_i32_e32 v133, 31, v132
	v_lshl_add_u64 v[132:133], v[132:133], 2, s[16:17]
	s_or_b64 exec, exec, s[0:1]
	v_lshl_add_u64 v[132:133], v[130:131], 2, v[132:133]
	global_load_dword v192, v[132:133], off
	global_load_dword v161, v[132:133], off offset:128
	s_waitcnt vmcnt(13)
	v_or_b32_e32 v160, 8, v136
	v_min_i32_e32 v132, 0x403f, v160
	v_mul_hi_i32 v133, v132, s83
	v_lshrrev_b32_e32 v135, 31, v133
	v_ashrrev_i32_e32 v133, 11, v133
	v_add_u32_e32 v135, v133, v135
	v_mad_i32_i24 v137, v135, s84, v132
	v_cmp_lt_i32_e32 vcc, 15, v137
	s_and_saveexec_b64 s[0:1], vcc
	s_xor_b64 s[0:1], exec, s[0:1]
	v_lshlrev_b32_e32 v132, 12, v135
	v_add3_u32 v132, v132, v137, -16
	v_ashrrev_i32_e32 v133, 31, v132
	v_lshlrev_b64 v[132:133], 12, v[132:133]
	v_lshl_add_u64 v[132:133], s[88:89], 0, v[132:133]
	s_andn2_saveexec_b64 s[0:1], s[0:1]
	v_lshlrev_b32_e32 v132, 14, v135
	v_lshl_add_u32 v132, v137, 10, v132
	v_ashrrev_i32_e32 v133, 31, v132
	v_lshl_add_u64 v[132:133], v[132:133], 2, s[16:17]
	s_or_b64 exec, exec, s[0:1]
	v_lshl_add_u64 v[132:133], v[130:131], 2, v[132:133]
	global_load_dword v191, v[132:133], off
	global_load_dword v159, v[132:133], off offset:128
	v_or_b32_e32 v158, 9, v136
	v_min_i32_e32 v132, 0x403f, v158
	v_mul_hi_i32 v133, v132, s83
	v_lshrrev_b32_e32 v135, 31, v133
	v_ashrrev_i32_e32 v133, 11, v133
	v_add_u32_e32 v135, v133, v135
	v_mad_i32_i24 v137, v135, s84, v132
	v_cmp_lt_i32_e32 vcc, 15, v137
	s_and_saveexec_b64 s[0:1], vcc
	s_xor_b64 s[0:1], exec, s[0:1]
	v_lshlrev_b32_e32 v132, 12, v135
	v_add3_u32 v132, v132, v137, -16
	v_ashrrev_i32_e32 v133, 31, v132
	v_lshlrev_b64 v[132:133], 12, v[132:133]
	v_lshl_add_u64 v[132:133], s[88:89], 0, v[132:133]
	s_andn2_saveexec_b64 s[0:1], s[0:1]
	v_lshlrev_b32_e32 v132, 14, v135
	v_lshl_add_u32 v132, v137, 10, v132
	v_ashrrev_i32_e32 v133, 31, v132
	v_lshl_add_u64 v[132:133], v[132:133], 2, s[16:17]
	s_or_b64 exec, exec, s[0:1]
	v_lshl_add_u64 v[132:133], v[130:131], 2, v[132:133]
	global_load_dword v190, v[132:133], off
	global_load_dword v157, v[132:133], off offset:128
	s_waitcnt vmcnt(12)
	v_or_b32_e32 v156, 10, v136
	v_min_i32_e32 v132, 0x403f, v156
	v_mul_hi_i32 v133, v132, s83
	v_lshrrev_b32_e32 v135, 31, v133
	v_ashrrev_i32_e32 v133, 11, v133
	v_add_u32_e32 v135, v133, v135
	v_mad_i32_i24 v137, v135, s84, v132
	v_cmp_lt_i32_e32 vcc, 15, v137
	s_and_saveexec_b64 s[0:1], vcc
	s_xor_b64 s[0:1], exec, s[0:1]
	v_lshlrev_b32_e32 v132, 12, v135
	v_add3_u32 v132, v132, v137, -16
	v_ashrrev_i32_e32 v133, 31, v132
	v_lshlrev_b64 v[132:133], 12, v[132:133]
	v_lshl_add_u64 v[132:133], s[88:89], 0, v[132:133]
	s_andn2_saveexec_b64 s[0:1], s[0:1]
	v_lshlrev_b32_e32 v132, 14, v135
	v_lshl_add_u32 v132, v137, 10, v132
	v_ashrrev_i32_e32 v133, 31, v132
	v_lshl_add_u64 v[132:133], v[132:133], 2, s[16:17]
	s_or_b64 exec, exec, s[0:1]
	v_lshl_add_u64 v[132:133], v[130:131], 2, v[132:133]
	global_load_dword v189, v[132:133], off
	global_load_dword v155, v[132:133], off offset:128
	v_or_b32_e32 v154, 11, v136
	v_min_i32_e32 v132, 0x403f, v154
	v_mul_hi_i32 v133, v132, s83
	v_lshrrev_b32_e32 v135, 31, v133
	v_ashrrev_i32_e32 v133, 11, v133
	v_add_u32_e32 v135, v133, v135
	v_mad_i32_i24 v137, v135, s84, v132
	v_cmp_lt_i32_e32 vcc, 15, v137
	s_and_saveexec_b64 s[0:1], vcc
	s_xor_b64 s[0:1], exec, s[0:1]
	v_lshlrev_b32_e32 v132, 12, v135
	v_add3_u32 v132, v132, v137, -16
	v_ashrrev_i32_e32 v133, 31, v132
	v_lshlrev_b64 v[132:133], 12, v[132:133]
	v_lshl_add_u64 v[132:133], s[88:89], 0, v[132:133]
	s_andn2_saveexec_b64 s[0:1], s[0:1]
	v_lshlrev_b32_e32 v132, 14, v135
	v_lshl_add_u32 v132, v137, 10, v132
	v_ashrrev_i32_e32 v133, 31, v132
	v_lshl_add_u64 v[132:133], v[132:133], 2, s[16:17]
	s_or_b64 exec, exec, s[0:1]
	v_lshl_add_u64 v[132:133], v[130:131], 2, v[132:133]
	global_load_dword v188, v[132:133], off
	global_load_dword v153, v[132:133], off offset:128
	v_or_b32_e32 v152, 16, v136
	v_min_i32_e32 v132, 0x403f, v152
	v_mul_hi_i32 v133, v132, s83
	v_lshrrev_b32_e32 v135, 31, v133
	v_ashrrev_i32_e32 v133, 11, v133
	v_add_u32_e32 v135, v133, v135
	v_mad_i32_i24 v137, v135, s84, v132
	v_cmp_lt_i32_e32 vcc, 15, v137
	s_and_saveexec_b64 s[0:1], vcc
	s_xor_b64 s[0:1], exec, s[0:1]
	v_lshlrev_b32_e32 v132, 12, v135
	v_add3_u32 v132, v132, v137, -16
	v_ashrrev_i32_e32 v133, 31, v132
	v_lshlrev_b64 v[132:133], 12, v[132:133]
	v_lshl_add_u64 v[132:133], s[88:89], 0, v[132:133]
	s_andn2_saveexec_b64 s[0:1], s[0:1]
	v_lshlrev_b32_e32 v132, 14, v135
	v_lshl_add_u32 v132, v137, 10, v132
	v_ashrrev_i32_e32 v133, 31, v132
	v_lshl_add_u64 v[132:133], v[132:133], 2, s[16:17]
	s_or_b64 exec, exec, s[0:1]
	v_lshl_add_u64 v[132:133], v[130:131], 2, v[132:133]
	global_load_dword v187, v[132:133], off
	global_load_dword v151, v[132:133], off offset:128
	v_or_b32_e32 v150, 17, v136
	v_min_i32_e32 v132, 0x403f, v150
	v_mul_hi_i32 v133, v132, s83
	v_lshrrev_b32_e32 v135, 31, v133
	v_ashrrev_i32_e32 v133, 11, v133
	v_add_u32_e32 v135, v133, v135
	v_mad_i32_i24 v137, v135, s84, v132
	v_cmp_lt_i32_e32 vcc, 15, v137
	s_and_saveexec_b64 s[0:1], vcc
	s_xor_b64 s[0:1], exec, s[0:1]
	v_lshlrev_b32_e32 v132, 12, v135
	v_add3_u32 v132, v132, v137, -16
	v_ashrrev_i32_e32 v133, 31, v132
	v_lshlrev_b64 v[132:133], 12, v[132:133]
	v_lshl_add_u64 v[132:133], s[88:89], 0, v[132:133]
	s_andn2_saveexec_b64 s[0:1], s[0:1]
	v_lshlrev_b32_e32 v132, 14, v135
	v_lshl_add_u32 v132, v137, 10, v132
	v_ashrrev_i32_e32 v133, 31, v132
	v_lshl_add_u64 v[132:133], v[132:133], 2, s[16:17]
	s_or_b64 exec, exec, s[0:1]
	v_lshl_add_u64 v[132:133], v[130:131], 2, v[132:133]
	global_load_dword v186, v[132:133], off
	global_load_dword v149, v[132:133], off offset:128
	v_or_b32_e32 v148, 18, v136
	v_min_i32_e32 v132, 0x403f, v148
	v_mul_hi_i32 v133, v132, s83
	v_lshrrev_b32_e32 v135, 31, v133
	v_ashrrev_i32_e32 v133, 11, v133
	v_add_u32_e32 v135, v133, v135
	v_mad_i32_i24 v137, v135, s84, v132
	v_cmp_lt_i32_e32 vcc, 15, v137
	s_and_saveexec_b64 s[0:1], vcc
	s_xor_b64 s[0:1], exec, s[0:1]
	v_lshlrev_b32_e32 v132, 12, v135
	v_add3_u32 v132, v132, v137, -16
	v_ashrrev_i32_e32 v133, 31, v132
	v_lshlrev_b64 v[132:133], 12, v[132:133]
	v_lshl_add_u64 v[132:133], s[88:89], 0, v[132:133]
	s_andn2_saveexec_b64 s[0:1], s[0:1]
	v_lshlrev_b32_e32 v132, 14, v135
	v_lshl_add_u32 v132, v137, 10, v132
	v_ashrrev_i32_e32 v133, 31, v132
	v_lshl_add_u64 v[132:133], v[132:133], 2, s[16:17]
	s_or_b64 exec, exec, s[0:1]
	v_lshl_add_u64 v[132:133], v[130:131], 2, v[132:133]
	global_load_dword v185, v[132:133], off
	global_load_dword v147, v[132:133], off offset:128
	v_or_b32_e32 v146, 19, v136
	v_min_i32_e32 v132, 0x403f, v146
	v_mul_hi_i32 v133, v132, s83
	v_lshrrev_b32_e32 v135, 31, v133
	v_ashrrev_i32_e32 v133, 11, v133
	v_add_u32_e32 v135, v133, v135
	v_mad_i32_i24 v137, v135, s84, v132
	v_cmp_lt_i32_e32 vcc, 15, v137
	s_and_saveexec_b64 s[0:1], vcc
	s_xor_b64 s[0:1], exec, s[0:1]
	v_lshlrev_b32_e32 v132, 12, v135
	v_add3_u32 v132, v132, v137, -16
	v_ashrrev_i32_e32 v133, 31, v132
	v_lshlrev_b64 v[132:133], 12, v[132:133]
	v_lshl_add_u64 v[132:133], s[88:89], 0, v[132:133]
	s_andn2_saveexec_b64 s[0:1], s[0:1]
	v_lshlrev_b32_e32 v132, 14, v135
	v_lshl_add_u32 v132, v137, 10, v132
	v_ashrrev_i32_e32 v133, 31, v132
	v_lshl_add_u64 v[132:133], v[132:133], 2, s[16:17]
	s_or_b64 exec, exec, s[0:1]
	v_lshl_add_u64 v[132:133], v[130:131], 2, v[132:133]
	global_load_dword v184, v[132:133], off
	global_load_dword v145, v[132:133], off offset:128
	v_or_b32_e32 v144, 24, v136
	v_min_i32_e32 v132, 0x403f, v144
	v_mul_hi_i32 v133, v132, s83
	v_lshrrev_b32_e32 v135, 31, v133
	v_ashrrev_i32_e32 v133, 11, v133
	v_add_u32_e32 v135, v133, v135
	v_mad_i32_i24 v137, v135, s84, v132
	v_cmp_lt_i32_e32 vcc, 15, v137
	s_and_saveexec_b64 s[0:1], vcc
	s_xor_b64 s[0:1], exec, s[0:1]
	v_lshlrev_b32_e32 v132, 12, v135
	v_add3_u32 v132, v132, v137, -16
	v_ashrrev_i32_e32 v133, 31, v132
	v_lshlrev_b64 v[132:133], 12, v[132:133]
	v_lshl_add_u64 v[132:133], s[88:89], 0, v[132:133]
	s_andn2_saveexec_b64 s[0:1], s[0:1]
	v_lshlrev_b32_e32 v132, 14, v135
	v_lshl_add_u32 v132, v137, 10, v132
	v_ashrrev_i32_e32 v133, 31, v132
	v_lshl_add_u64 v[132:133], v[132:133], 2, s[16:17]
	s_or_b64 exec, exec, s[0:1]
	v_lshl_add_u64 v[132:133], v[130:131], 2, v[132:133]
	global_load_dword v183, v[132:133], off
	global_load_dword v143, v[132:133], off offset:128
	v_or_b32_e32 v142, 25, v136
	v_min_i32_e32 v132, 0x403f, v142
	v_mul_hi_i32 v133, v132, s83
	v_lshrrev_b32_e32 v135, 31, v133
	v_ashrrev_i32_e32 v133, 11, v133
	v_add_u32_e32 v135, v133, v135
	v_mad_i32_i24 v137, v135, s84, v132
	v_cmp_lt_i32_e32 vcc, 15, v137
	s_and_saveexec_b64 s[0:1], vcc
	s_xor_b64 s[0:1], exec, s[0:1]
	v_lshlrev_b32_e32 v132, 12, v135
	v_add3_u32 v132, v132, v137, -16
	v_ashrrev_i32_e32 v133, 31, v132
	v_lshlrev_b64 v[132:133], 12, v[132:133]
	v_lshl_add_u64 v[132:133], s[88:89], 0, v[132:133]
	s_andn2_saveexec_b64 s[0:1], s[0:1]
	v_lshlrev_b32_e32 v132, 14, v135
	v_lshl_add_u32 v132, v137, 10, v132
	v_ashrrev_i32_e32 v133, 31, v132
	v_lshl_add_u64 v[132:133], v[132:133], 2, s[16:17]
	s_or_b64 exec, exec, s[0:1]
	v_lshl_add_u64 v[132:133], v[130:131], 2, v[132:133]
	global_load_dword v182, v[132:133], off
	global_load_dword v141, v[132:133], off offset:128
	v_or_b32_e32 v140, 26, v136
	v_min_i32_e32 v132, 0x403f, v140
	v_mul_hi_i32 v133, v132, s83
	v_lshrrev_b32_e32 v135, 31, v133
	v_ashrrev_i32_e32 v133, 11, v133
	v_add_u32_e32 v135, v133, v135
	v_mad_i32_i24 v137, v135, s84, v132
	v_cmp_lt_i32_e32 vcc, 15, v137
	s_and_saveexec_b64 s[0:1], vcc
	s_xor_b64 s[0:1], exec, s[0:1]
	v_lshlrev_b32_e32 v132, 12, v135
	v_add3_u32 v132, v132, v137, -16
	v_ashrrev_i32_e32 v133, 31, v132
	v_lshlrev_b64 v[132:133], 12, v[132:133]
	v_lshl_add_u64 v[132:133], s[88:89], 0, v[132:133]
	s_andn2_saveexec_b64 s[0:1], s[0:1]
	v_lshlrev_b32_e32 v132, 14, v135
	v_lshl_add_u32 v132, v137, 10, v132
	v_ashrrev_i32_e32 v133, 31, v132
	v_lshl_add_u64 v[132:133], v[132:133], 2, s[16:17]
	s_or_b64 exec, exec, s[0:1]
	v_lshl_add_u64 v[132:133], v[130:131], 2, v[132:133]
	global_load_dword v179, v[132:133], off
	global_load_dword v139, v[132:133], off offset:128
	v_or_b32_e32 v138, 27, v136
	v_min_i32_e32 v132, 0x403f, v138
	v_mul_hi_i32 v133, v132, s83
	v_lshrrev_b32_e32 v135, 31, v133
	v_ashrrev_i32_e32 v133, 11, v133
	v_add_u32_e32 v135, v133, v135
	v_mad_i32_i24 v137, v135, s84, v132
	v_cmp_lt_i32_e32 vcc, 15, v137
	s_and_saveexec_b64 s[0:1], vcc
	s_xor_b64 s[0:1], exec, s[0:1]
	v_lshlrev_b32_e32 v132, 12, v135
	v_add3_u32 v132, v132, v137, -16
	v_ashrrev_i32_e32 v133, 31, v132
	v_lshlrev_b64 v[132:133], 12, v[132:133]
	v_lshl_add_u64 v[132:133], s[88:89], 0, v[132:133]
	s_andn2_saveexec_b64 s[0:1], s[0:1]
	v_lshlrev_b32_e32 v132, 14, v135
	v_lshl_add_u32 v132, v137, 10, v132
	v_ashrrev_i32_e32 v133, 31, v132
	v_lshl_add_u64 v[132:133], v[132:133], 2, s[16:17]
	s_or_b64 exec, exec, s[0:1]
	v_lshl_add_u64 v[132:133], v[130:131], 2, v[132:133]
	global_load_dword v178, v[132:133], off
	global_load_dword v177, v[132:133], off offset:128
	v_cmp_gt_i32_e32 vcc, s85, v136
	s_nop 1
	v_cndmask_b32_e32 v132, v181, v136, vcc
	v_mul_hi_i32 v133, v132, s83
	v_lshrrev_b32_e32 v135, 31, v133
	v_ashrrev_i32_e32 v133, 11, v133
	v_add_u32_e32 v135, v133, v135
	v_mad_i32_i24 v137, v135, s84, v132
	v_cmp_lt_i32_e64 s[0:1], 15, v137
	s_and_saveexec_b64 s[2:3], s[0:1]
	s_xor_b64 s[0:1], exec, s[2:3]
	v_lshlrev_b32_e32 v132, 12, v135
	v_add3_u32 v132, v132, v137, -16
	v_ashrrev_i32_e32 v133, 31, v132
	v_lshlrev_b64 v[132:133], 12, v[132:133]
	v_lshl_add_u64 v[132:133], s[88:89], 0, v[132:133]
	s_andn2_saveexec_b64 s[0:1], s[0:1]
	v_lshlrev_b32_e32 v132, 14, v135
	v_lshl_add_u32 v132, v137, 10, v132
	v_ashrrev_i32_e32 v133, 31, v132
	v_lshl_add_u64 v[132:133], v[132:133], 2, s[16:17]
	s_or_b64 exec, exec, s[0:1]
	v_ashrrev_i32_e32 v137, 31, v136
	v_lshlrev_b64 v[168:169], 11, v[136:137]
	v_readlane_b32 s44, v239, 4
	v_lshl_add_u64 v[168:169], s[62:63], 0, v[168:169]
	s_waitcnt vmcnt(31)
	v_add_f32_e32 v137, v114, v134
	v_lshlrev_b64 v[134:135], 2, v[130:131]
	v_readlane_b32 s50, v239, 10
	v_readlane_b32 s51, v239, 11
	v_lshl_add_u64 v[168:169], v[130:131], 1, v[168:169]
	v_lshl_add_u64 v[170:171], v[132:133], 0, v[134:135]
	v_lshl_add_u64 v[132:133], s[50:51], 0, v[134:135]
	global_load_dword v242, v[132:133], off
	global_load_dword v243, v[132:133], off offset:128
	s_waitcnt vmcnt(0)
	v_readlane_b32 s45, v239, 5
	v_readlane_b32 s46, v239, 6
	v_readlane_b32 s47, v239, 7
	v_readlane_b32 s48, v239, 8
	v_readlane_b32 s49, v239, 9
	v_readlane_b32 s52, v239, 12
	v_readlane_b32 s53, v239, 13
	v_readlane_b32 s54, v239, 14
	v_readlane_b32 s55, v239, 15
	v_readlane_b32 s56, v239, 16
	v_readlane_b32 s57, v239, 17
	v_readlane_b32 s58, v239, 18
	v_readlane_b32 s59, v239, 19
	s_and_saveexec_b64 s[0:1], vcc
	s_cbranch_execz .LBB0_3711
	global_store_dword v[170:171], v137, off
	v_mul_f32_e32 v114, v137, v242
	v_cvt_pk_bf16_f32 v114, v114, s0
	global_store_short v[168:169], v114, off
.LBB0_3711:
	s_or_b64 exec, exec, s[0:1]
	s_waitcnt vmcnt(30)
	v_add_f32_e32 v176, v98, v167
	s_and_saveexec_b64 s[0:1], vcc
	s_cbranch_execz .LBB0_3713
	global_store_dword v[170:171], v176, off offset:128
	v_mul_f32_e32 v98, v176, v243
	v_cvt_pk_bf16_f32 v98, v98, s0
	global_store_short v[168:169], v98, off offset:64
.LBB0_3713:
	s_or_b64 exec, exec, s[0:1]
	v_cmp_gt_i32_e32 vcc, s85, v166
	s_nop 1
	v_cndmask_b32_e32 v114, v181, v166, vcc
	v_mul_hi_i32 v98, v114, s83
	v_lshrrev_b32_e32 v167, 31, v98
	v_ashrrev_i32_e32 v98, 11, v98
	v_add_u32_e32 v98, v98, v167
	v_mad_i32_i24 v114, v98, s84, v114
	v_cmp_lt_i32_e64 s[0:1], 15, v114
	s_and_saveexec_b64 s[2:3], s[0:1]
	s_xor_b64 s[0:1], exec, s[2:3]
	v_lshlrev_b32_e32 v98, 12, v98
	v_add3_u32 v168, v98, v114, -16
	v_ashrrev_i32_e32 v169, 31, v168
	v_lshlrev_b64 v[168:169], 12, v[168:169]
	v_lshl_add_u64 v[168:169], s[88:89], 0, v[168:169]
	s_andn2_saveexec_b64 s[0:1], s[0:1]
	v_lshlrev_b32_e32 v98, 14, v98
	v_lshl_add_u32 v168, v114, 10, v98
	v_ashrrev_i32_e32 v169, 31, v168
	v_lshl_add_u64 v[168:169], v[168:169], 2, s[16:17]
	s_or_b64 exec, exec, s[0:1]
	v_ashrrev_i32_e32 v167, 31, v166
	v_lshlrev_b64 v[166:167], 11, v[166:167]
	v_lshl_add_u64 v[166:167], s[62:63], 0, v[166:167]
	s_waitcnt vmcnt(29)
	v_add_f32_e32 v170, v115, v194
	v_lshl_add_u64 v[114:115], v[130:131], 1, v[166:167]
	v_lshl_add_u64 v[166:167], v[168:169], 0, v[134:135]
	s_and_saveexec_b64 s[0:1], vcc
	s_cbranch_execz .LBB0_3719
	global_store_dword v[166:167], v170, off
	v_mul_f32_e32 v98, v170, v242
	v_cvt_pk_bf16_f32 v98, v98, s0
	global_store_short v[114:115], v98, off
.LBB0_3719:
	s_or_b64 exec, exec, s[0:1]
	s_waitcnt vmcnt(28)
	v_add_f32_e32 v168, v99, v165
	s_and_saveexec_b64 s[0:1], vcc
	s_cbranch_execz .LBB0_3721
	global_store_dword v[166:167], v168, off offset:128
	v_mul_f32_e32 v98, v168, v243
	v_cvt_pk_bf16_f32 v98, v98, s0
	global_store_short v[114:115], v98, off offset:64
.LBB0_3721:
	s_or_b64 exec, exec, s[0:1]
	v_cmp_gt_i32_e32 vcc, s85, v164
	s_nop 1
	v_cndmask_b32_e32 v98, v181, v164, vcc
	v_mul_hi_i32 v99, v98, s83
	v_lshrrev_b32_e32 v114, 31, v99
	v_ashrrev_i32_e32 v99, 11, v99
	v_add_u32_e32 v114, v99, v114
	v_mad_i32_i24 v115, v114, s84, v98
	v_cmp_lt_i32_e64 s[0:1], 15, v115
	s_and_saveexec_b64 s[2:3], s[0:1]
	s_xor_b64 s[0:1], exec, s[2:3]
	v_lshlrev_b32_e32 v98, 12, v114
	v_add3_u32 v98, v98, v115, -16
	v_ashrrev_i32_e32 v99, 31, v98
	v_lshlrev_b64 v[98:99], 12, v[98:99]
	v_lshl_add_u64 v[98:99], s[88:89], 0, v[98:99]
	s_andn2_saveexec_b64 s[0:1], s[0:1]
	v_lshlrev_b32_e32 v98, 14, v114
	v_lshl_add_u32 v98, v115, 10, v98
	v_ashrrev_i32_e32 v99, 31, v98
	v_lshl_add_u64 v[98:99], v[98:99], 2, s[16:17]
	s_or_b64 exec, exec, s[0:1]
	v_ashrrev_i32_e32 v165, 31, v164
	v_lshlrev_b64 v[114:115], 11, v[164:165]
	v_lshl_add_u64 v[114:115], s[62:63], 0, v[114:115]
	s_waitcnt vmcnt(27)
	v_add_f32_e32 v164, v116, v193
	v_lshl_add_u64 v[114:115], v[130:131], 1, v[114:115]
	v_lshl_add_u64 v[98:99], v[98:99], 0, v[134:135]
	s_and_saveexec_b64 s[0:1], vcc
	s_cbranch_execz .LBB0_3727
	global_store_dword v[98:99], v164, off
	v_mul_f32_e32 v116, v164, v242
	v_cvt_pk_bf16_f32 v116, v116, s0
	global_store_short v[114:115], v116, off
.LBB0_3727:
	s_or_b64 exec, exec, s[0:1]
	s_waitcnt vmcnt(26)
	v_add_f32_e32 v165, v100, v163
	s_and_saveexec_b64 s[0:1], vcc
	s_cbranch_execz .LBB0_3729
	global_store_dword v[98:99], v165, off offset:128
	v_mul_f32_e32 v98, v165, v243
	v_cvt_pk_bf16_f32 v98, v98, s0
	global_store_short v[114:115], v98, off offset:64
.LBB0_3729:
	s_or_b64 exec, exec, s[0:1]
	v_cmp_gt_i32_e32 vcc, s85, v162
	s_nop 1
	v_cndmask_b32_e32 v98, v181, v162, vcc
	v_mul_hi_i32 v99, v98, s83
	v_lshrrev_b32_e32 v100, 31, v99
	v_ashrrev_i32_e32 v99, 11, v99
	v_add_u32_e32 v100, v99, v100
	v_mad_i32_i24 v114, v100, s84, v98
	v_cmp_lt_i32_e64 s[0:1], 15, v114
	s_and_saveexec_b64 s[2:3], s[0:1]
	s_xor_b64 s[0:1], exec, s[2:3]
	v_lshlrev_b32_e32 v98, 12, v100
	v_add3_u32 v98, v98, v114, -16
	v_ashrrev_i32_e32 v99, 31, v98
	v_lshlrev_b64 v[98:99], 12, v[98:99]
	v_lshl_add_u64 v[98:99], s[88:89], 0, v[98:99]
	s_andn2_saveexec_b64 s[0:1], s[0:1]
	v_lshlrev_b32_e32 v98, 14, v100
	v_lshl_add_u32 v98, v114, 10, v98
	v_ashrrev_i32_e32 v99, 31, v98
	v_lshl_add_u64 v[98:99], v[98:99], 2, s[16:17]
	s_or_b64 exec, exec, s[0:1]
	v_ashrrev_i32_e32 v163, 31, v162
	v_lshlrev_b64 v[114:115], 11, v[162:163]
	v_lshl_add_u64 v[114:115], s[62:63], 0, v[114:115]
	s_waitcnt vmcnt(25)
	v_add_f32_e32 v162, v117, v192
	v_lshl_add_u64 v[114:115], v[130:131], 1, v[114:115]
	v_lshl_add_u64 v[98:99], v[98:99], 0, v[134:135]
	s_and_saveexec_b64 s[0:1], vcc
	s_cbranch_execz .LBB0_3735
	global_store_dword v[98:99], v162, off
	v_mul_f32_e32 v100, v162, v242
	v_cvt_pk_bf16_f32 v100, v100, s0
	global_store_short v[114:115], v100, off
.LBB0_3735:
	s_or_b64 exec, exec, s[0:1]
	s_waitcnt vmcnt(24)
	v_add_f32_e32 v163, v101, v161
	s_and_saveexec_b64 s[0:1], vcc
	s_cbranch_execz .LBB0_3737
	global_store_dword v[98:99], v163, off offset:128
	v_mul_f32_e32 v98, v163, v243
	v_cvt_pk_bf16_f32 v98, v98, s0
	global_store_short v[114:115], v98, off offset:64
.LBB0_3737:
	s_or_b64 exec, exec, s[0:1]
	v_cmp_gt_i32_e32 vcc, s85, v160
	s_nop 1
	v_cndmask_b32_e32 v98, v181, v160, vcc
	v_mul_hi_i32 v99, v98, s83
	v_lshrrev_b32_e32 v100, 31, v99
	v_ashrrev_i32_e32 v99, 11, v99
	v_add_u32_e32 v100, v99, v100
	v_mad_i32_i24 v101, v100, s84, v98
	v_cmp_lt_i32_e64 s[0:1], 15, v101
	s_and_saveexec_b64 s[2:3], s[0:1]
	s_xor_b64 s[0:1], exec, s[2:3]
	v_lshlrev_b32_e32 v98, 12, v100
	v_add3_u32 v98, v98, v101, -16
	v_ashrrev_i32_e32 v99, 31, v98
	v_lshlrev_b64 v[98:99], 12, v[98:99]
	v_lshl_add_u64 v[98:99], s[88:89], 0, v[98:99]
	s_andn2_saveexec_b64 s[0:1], s[0:1]
	v_lshlrev_b32_e32 v98, 14, v100
	v_lshl_add_u32 v98, v101, 10, v98
	v_ashrrev_i32_e32 v99, 31, v98
	v_lshl_add_u64 v[98:99], v[98:99], 2, s[16:17]
	s_or_b64 exec, exec, s[0:1]
	v_ashrrev_i32_e32 v161, 31, v160
	v_lshlrev_b64 v[100:101], 11, v[160:161]
	v_lshl_add_u64 v[100:101], s[62:63], 0, v[100:101]
	s_waitcnt vmcnt(23)
	v_add_f32_e32 v160, v118, v191
	v_lshl_add_u64 v[100:101], v[130:131], 1, v[100:101]
	v_lshl_add_u64 v[98:99], v[98:99], 0, v[134:135]
	s_and_saveexec_b64 s[0:1], vcc
	s_cbranch_execz .LBB0_3743
	global_store_dword v[98:99], v160, off
	v_mul_f32_e32 v114, v160, v242
	v_cvt_pk_bf16_f32 v114, v114, s0
	global_store_short v[100:101], v114, off
.LBB0_3743:
	s_or_b64 exec, exec, s[0:1]
	s_waitcnt vmcnt(22)
	v_add_f32_e32 v161, v102, v159
	s_and_saveexec_b64 s[0:1], vcc
	s_cbranch_execz .LBB0_3745
	global_store_dword v[98:99], v161, off offset:128
	v_mul_f32_e32 v98, v161, v243
	v_cvt_pk_bf16_f32 v98, v98, s0
	global_store_short v[100:101], v98, off offset:64
.LBB0_3745:
	s_or_b64 exec, exec, s[0:1]
	v_cmp_gt_i32_e32 vcc, s85, v158
	s_nop 1
	v_cndmask_b32_e32 v98, v181, v158, vcc
	v_mul_hi_i32 v99, v98, s83
	v_lshrrev_b32_e32 v100, 31, v99
	v_ashrrev_i32_e32 v99, 11, v99
	v_add_u32_e32 v100, v99, v100
	v_mad_i32_i24 v101, v100, s84, v98
	v_cmp_lt_i32_e64 s[0:1], 15, v101
	s_and_saveexec_b64 s[2:3], s[0:1]
	s_xor_b64 s[0:1], exec, s[2:3]
	v_lshlrev_b32_e32 v98, 12, v100
	v_add3_u32 v98, v98, v101, -16
	v_ashrrev_i32_e32 v99, 31, v98
	v_lshlrev_b64 v[98:99], 12, v[98:99]
	v_lshl_add_u64 v[98:99], s[88:89], 0, v[98:99]
	s_andn2_saveexec_b64 s[0:1], s[0:1]
	v_lshlrev_b32_e32 v98, 14, v100
	v_lshl_add_u32 v98, v101, 10, v98
	v_ashrrev_i32_e32 v99, 31, v98
	v_lshl_add_u64 v[98:99], v[98:99], 2, s[16:17]
	s_or_b64 exec, exec, s[0:1]
	v_ashrrev_i32_e32 v159, 31, v158
	v_lshlrev_b64 v[100:101], 11, v[158:159]
	v_lshl_add_u64 v[100:101], s[62:63], 0, v[100:101]
	s_waitcnt vmcnt(21)
	v_add_f32_e32 v158, v119, v190
	v_lshl_add_u64 v[100:101], v[130:131], 1, v[100:101]
	v_lshl_add_u64 v[98:99], v[98:99], 0, v[134:135]
	s_and_saveexec_b64 s[0:1], vcc
	s_cbranch_execz .LBB0_3751
	global_store_dword v[98:99], v158, off
	v_mul_f32_e32 v102, v158, v242
	v_cvt_pk_bf16_f32 v102, v102, s0
	global_store_short v[100:101], v102, off
.LBB0_3751:
	s_or_b64 exec, exec, s[0:1]
	s_waitcnt vmcnt(20)
	v_add_f32_e32 v159, v103, v157
	s_and_saveexec_b64 s[0:1], vcc
	s_cbranch_execz .LBB0_3753
	global_store_dword v[98:99], v159, off offset:128
	v_mul_f32_e32 v98, v159, v243
	v_cvt_pk_bf16_f32 v98, v98, s0
	global_store_short v[100:101], v98, off offset:64
.LBB0_3753:
	s_or_b64 exec, exec, s[0:1]
	v_cmp_gt_i32_e32 vcc, s85, v156
	s_nop 1
	v_cndmask_b32_e32 v98, v181, v156, vcc
	v_mul_hi_i32 v99, v98, s83
	v_lshrrev_b32_e32 v100, 31, v99
	v_ashrrev_i32_e32 v99, 11, v99
	v_add_u32_e32 v100, v99, v100
	v_mad_i32_i24 v101, v100, s84, v98
	v_cmp_lt_i32_e64 s[0:1], 15, v101
	s_and_saveexec_b64 s[2:3], s[0:1]
	s_xor_b64 s[0:1], exec, s[2:3]
	v_lshlrev_b32_e32 v98, 12, v100
	v_add3_u32 v98, v98, v101, -16
	v_ashrrev_i32_e32 v99, 31, v98
	v_lshlrev_b64 v[98:99], 12, v[98:99]
	v_lshl_add_u64 v[98:99], s[88:89], 0, v[98:99]
	s_andn2_saveexec_b64 s[0:1], s[0:1]
	v_lshlrev_b32_e32 v98, 14, v100
	v_lshl_add_u32 v98, v101, 10, v98
	v_ashrrev_i32_e32 v99, 31, v98
	v_lshl_add_u64 v[98:99], v[98:99], 2, s[16:17]
	s_or_b64 exec, exec, s[0:1]
	v_ashrrev_i32_e32 v157, 31, v156
	v_lshlrev_b64 v[100:101], 11, v[156:157]
	v_lshl_add_u64 v[100:101], s[62:63], 0, v[100:101]
	s_waitcnt vmcnt(19)
	v_add_f32_e32 v156, v120, v189
	v_lshl_add_u64 v[100:101], v[130:131], 1, v[100:101]
	v_lshl_add_u64 v[98:99], v[98:99], 0, v[134:135]
	s_and_saveexec_b64 s[0:1], vcc
	s_cbranch_execz .LBB0_3759
	global_store_dword v[98:99], v156, off
	v_mul_f32_e32 v102, v156, v242
	v_cvt_pk_bf16_f32 v102, v102, s0
	global_store_short v[100:101], v102, off
.LBB0_3759:
	s_or_b64 exec, exec, s[0:1]
	s_waitcnt vmcnt(18)
	v_add_f32_e32 v157, v104, v155
	s_and_saveexec_b64 s[0:1], vcc
	s_cbranch_execz .LBB0_3761
	global_store_dword v[98:99], v157, off offset:128
	v_mul_f32_e32 v98, v157, v243
	v_cvt_pk_bf16_f32 v98, v98, s0
	global_store_short v[100:101], v98, off offset:64
.LBB0_3761:
	s_or_b64 exec, exec, s[0:1]
	v_cmp_gt_i32_e32 vcc, s85, v154
	s_nop 1
	v_cndmask_b32_e32 v98, v181, v154, vcc
	v_mul_hi_i32 v99, v98, s83
	v_lshrrev_b32_e32 v100, 31, v99
	v_ashrrev_i32_e32 v99, 11, v99
	v_add_u32_e32 v100, v99, v100
	v_mad_i32_i24 v101, v100, s84, v98
	v_cmp_lt_i32_e64 s[0:1], 15, v101
	s_and_saveexec_b64 s[2:3], s[0:1]
	s_xor_b64 s[0:1], exec, s[2:3]
	v_lshlrev_b32_e32 v98, 12, v100
	v_add3_u32 v98, v98, v101, -16
	v_ashrrev_i32_e32 v99, 31, v98
	v_lshlrev_b64 v[98:99], 12, v[98:99]
	v_lshl_add_u64 v[98:99], s[88:89], 0, v[98:99]
	s_andn2_saveexec_b64 s[0:1], s[0:1]
	v_lshlrev_b32_e32 v98, 14, v100
	v_lshl_add_u32 v98, v101, 10, v98
	v_ashrrev_i32_e32 v99, 31, v98
	v_lshl_add_u64 v[98:99], v[98:99], 2, s[16:17]
	s_or_b64 exec, exec, s[0:1]
	v_ashrrev_i32_e32 v155, 31, v154
	v_lshlrev_b64 v[100:101], 11, v[154:155]
	v_lshl_add_u64 v[100:101], s[62:63], 0, v[100:101]
	s_waitcnt vmcnt(17)
	v_add_f32_e32 v154, v121, v188
	v_lshl_add_u64 v[100:101], v[130:131], 1, v[100:101]
	v_lshl_add_u64 v[98:99], v[98:99], 0, v[134:135]
	s_and_saveexec_b64 s[0:1], vcc
	s_cbranch_execz .LBB0_3767
	global_store_dword v[98:99], v154, off
	v_mul_f32_e32 v102, v154, v242
	v_cvt_pk_bf16_f32 v102, v102, s0
	global_store_short v[100:101], v102, off
.LBB0_3767:
	s_or_b64 exec, exec, s[0:1]
	s_waitcnt vmcnt(16)
	v_add_f32_e32 v155, v105, v153
	s_and_saveexec_b64 s[0:1], vcc
	s_cbranch_execz .LBB0_3769
	global_store_dword v[98:99], v155, off offset:128
	v_mul_f32_e32 v98, v155, v243
	v_cvt_pk_bf16_f32 v98, v98, s0
	global_store_short v[100:101], v98, off offset:64
.LBB0_3769:
	s_or_b64 exec, exec, s[0:1]
	v_cmp_gt_i32_e32 vcc, s85, v152
	s_nop 1
	v_cndmask_b32_e32 v98, v181, v152, vcc
	v_mul_hi_i32 v99, v98, s83
	v_lshrrev_b32_e32 v100, 31, v99
	v_ashrrev_i32_e32 v99, 11, v99
	v_add_u32_e32 v100, v99, v100
	v_mad_i32_i24 v101, v100, s84, v98
	v_cmp_lt_i32_e64 s[0:1], 15, v101
	s_and_saveexec_b64 s[2:3], s[0:1]
	s_xor_b64 s[0:1], exec, s[2:3]
	v_lshlrev_b32_e32 v98, 12, v100
	v_add3_u32 v98, v98, v101, -16
	v_ashrrev_i32_e32 v99, 31, v98
	v_lshlrev_b64 v[98:99], 12, v[98:99]
	v_lshl_add_u64 v[98:99], s[88:89], 0, v[98:99]
	s_andn2_saveexec_b64 s[0:1], s[0:1]
	v_lshlrev_b32_e32 v98, 14, v100
	v_lshl_add_u32 v98, v101, 10, v98
	v_ashrrev_i32_e32 v99, 31, v98
	v_lshl_add_u64 v[98:99], v[98:99], 2, s[16:17]
	s_or_b64 exec, exec, s[0:1]
	v_ashrrev_i32_e32 v153, 31, v152
	v_lshlrev_b64 v[100:101], 11, v[152:153]
	v_lshl_add_u64 v[100:101], s[62:63], 0, v[100:101]
	s_waitcnt vmcnt(15)
	v_add_f32_e32 v152, v122, v187
	v_lshl_add_u64 v[100:101], v[130:131], 1, v[100:101]
	v_lshl_add_u64 v[98:99], v[98:99], 0, v[134:135]
	s_and_saveexec_b64 s[0:1], vcc
	s_cbranch_execz .LBB0_3775
	global_store_dword v[98:99], v152, off
	v_mul_f32_e32 v102, v152, v242
	v_cvt_pk_bf16_f32 v102, v102, s0
	global_store_short v[100:101], v102, off
.LBB0_3775:
	s_or_b64 exec, exec, s[0:1]
	s_waitcnt vmcnt(14)
	v_add_f32_e32 v153, v106, v151
	s_and_saveexec_b64 s[0:1], vcc
	s_cbranch_execz .LBB0_3777
	global_store_dword v[98:99], v153, off offset:128
	v_mul_f32_e32 v98, v153, v243
	v_cvt_pk_bf16_f32 v98, v98, s0
	global_store_short v[100:101], v98, off offset:64
.LBB0_3777:
	s_or_b64 exec, exec, s[0:1]
	v_cmp_gt_i32_e32 vcc, s85, v150
	s_nop 1
	v_cndmask_b32_e32 v98, v181, v150, vcc
	v_mul_hi_i32 v99, v98, s83
	v_lshrrev_b32_e32 v100, 31, v99
	v_ashrrev_i32_e32 v99, 11, v99
	v_add_u32_e32 v100, v99, v100
	v_mad_i32_i24 v101, v100, s84, v98
	v_cmp_lt_i32_e64 s[0:1], 15, v101
	s_and_saveexec_b64 s[2:3], s[0:1]
	s_xor_b64 s[0:1], exec, s[2:3]
	v_lshlrev_b32_e32 v98, 12, v100
	v_add3_u32 v98, v98, v101, -16
	v_ashrrev_i32_e32 v99, 31, v98
	v_lshlrev_b64 v[98:99], 12, v[98:99]
	v_lshl_add_u64 v[98:99], s[88:89], 0, v[98:99]
	s_andn2_saveexec_b64 s[0:1], s[0:1]
	v_lshlrev_b32_e32 v98, 14, v100
	v_lshl_add_u32 v98, v101, 10, v98
	v_ashrrev_i32_e32 v99, 31, v98
	v_lshl_add_u64 v[98:99], v[98:99], 2, s[16:17]
	s_or_b64 exec, exec, s[0:1]
	v_ashrrev_i32_e32 v151, 31, v150
	v_lshlrev_b64 v[100:101], 11, v[150:151]
	v_lshl_add_u64 v[100:101], s[62:63], 0, v[100:101]
	s_waitcnt vmcnt(13)
	v_add_f32_e32 v150, v123, v186
	v_lshl_add_u64 v[100:101], v[130:131], 1, v[100:101]
	v_lshl_add_u64 v[98:99], v[98:99], 0, v[134:135]
	s_and_saveexec_b64 s[0:1], vcc
	s_cbranch_execz .LBB0_3783
	global_store_dword v[98:99], v150, off
	v_mul_f32_e32 v102, v150, v242
	v_cvt_pk_bf16_f32 v102, v102, s0
	global_store_short v[100:101], v102, off
.LBB0_3783:
	s_or_b64 exec, exec, s[0:1]
	s_waitcnt vmcnt(12)
	v_add_f32_e32 v151, v107, v149
	s_and_saveexec_b64 s[0:1], vcc
	s_cbranch_execz .LBB0_3785
	global_store_dword v[98:99], v151, off offset:128
	v_mul_f32_e32 v98, v151, v243
	v_cvt_pk_bf16_f32 v98, v98, s0
	global_store_short v[100:101], v98, off offset:64
.LBB0_3785:
	s_or_b64 exec, exec, s[0:1]
	v_cmp_gt_i32_e32 vcc, s85, v148
	s_nop 1
	v_cndmask_b32_e32 v98, v181, v148, vcc
	v_mul_hi_i32 v99, v98, s83
	v_lshrrev_b32_e32 v100, 31, v99
	v_ashrrev_i32_e32 v99, 11, v99
	v_add_u32_e32 v100, v99, v100
	v_mad_i32_i24 v101, v100, s84, v98
	v_cmp_lt_i32_e64 s[0:1], 15, v101
	s_and_saveexec_b64 s[2:3], s[0:1]
	s_xor_b64 s[0:1], exec, s[2:3]
	v_lshlrev_b32_e32 v98, 12, v100
	v_add3_u32 v98, v98, v101, -16
	v_ashrrev_i32_e32 v99, 31, v98
	v_lshlrev_b64 v[98:99], 12, v[98:99]
	v_lshl_add_u64 v[98:99], s[88:89], 0, v[98:99]
	s_andn2_saveexec_b64 s[0:1], s[0:1]
	v_lshlrev_b32_e32 v98, 14, v100
	v_lshl_add_u32 v98, v101, 10, v98
	v_ashrrev_i32_e32 v99, 31, v98
	v_lshl_add_u64 v[98:99], v[98:99], 2, s[16:17]
	s_or_b64 exec, exec, s[0:1]
	v_ashrrev_i32_e32 v149, 31, v148
	v_lshlrev_b64 v[100:101], 11, v[148:149]
	v_lshl_add_u64 v[100:101], s[62:63], 0, v[100:101]
	s_waitcnt vmcnt(11)
	v_add_f32_e32 v148, v124, v185
	v_lshl_add_u64 v[100:101], v[130:131], 1, v[100:101]
	v_lshl_add_u64 v[98:99], v[98:99], 0, v[134:135]
	s_and_saveexec_b64 s[0:1], vcc
	s_cbranch_execz .LBB0_3791
	global_store_dword v[98:99], v148, off
	v_mul_f32_e32 v102, v148, v242
	v_cvt_pk_bf16_f32 v102, v102, s0
	global_store_short v[100:101], v102, off
.LBB0_3791:
	s_or_b64 exec, exec, s[0:1]
	s_waitcnt vmcnt(10)
	v_add_f32_e32 v149, v108, v147
	s_and_saveexec_b64 s[0:1], vcc
	s_cbranch_execz .LBB0_3793
	global_store_dword v[98:99], v149, off offset:128
	v_mul_f32_e32 v98, v149, v243
	v_cvt_pk_bf16_f32 v98, v98, s0
	global_store_short v[100:101], v98, off offset:64
.LBB0_3793:
	s_or_b64 exec, exec, s[0:1]
	v_cmp_gt_i32_e32 vcc, s85, v146
	s_nop 1
	v_cndmask_b32_e32 v98, v181, v146, vcc
	v_mul_hi_i32 v99, v98, s83
	v_lshrrev_b32_e32 v100, 31, v99
	v_ashrrev_i32_e32 v99, 11, v99
	v_add_u32_e32 v100, v99, v100
	v_mad_i32_i24 v101, v100, s84, v98
	v_cmp_lt_i32_e64 s[0:1], 15, v101
	s_and_saveexec_b64 s[2:3], s[0:1]
	s_xor_b64 s[0:1], exec, s[2:3]
	v_lshlrev_b32_e32 v98, 12, v100
	v_add3_u32 v98, v98, v101, -16
	v_ashrrev_i32_e32 v99, 31, v98
	v_lshlrev_b64 v[98:99], 12, v[98:99]
	v_lshl_add_u64 v[98:99], s[88:89], 0, v[98:99]
	s_andn2_saveexec_b64 s[0:1], s[0:1]
	v_lshlrev_b32_e32 v98, 14, v100
	v_lshl_add_u32 v98, v101, 10, v98
	v_ashrrev_i32_e32 v99, 31, v98
	v_lshl_add_u64 v[98:99], v[98:99], 2, s[16:17]
	s_or_b64 exec, exec, s[0:1]
	v_ashrrev_i32_e32 v147, 31, v146
	v_lshlrev_b64 v[100:101], 11, v[146:147]
	v_lshl_add_u64 v[100:101], s[62:63], 0, v[100:101]
	s_waitcnt vmcnt(9)
	v_add_f32_e32 v146, v125, v184
	v_lshl_add_u64 v[100:101], v[130:131], 1, v[100:101]
	v_lshl_add_u64 v[98:99], v[98:99], 0, v[134:135]
	s_and_saveexec_b64 s[0:1], vcc
	s_cbranch_execz .LBB0_3799
	global_store_dword v[98:99], v146, off
	v_mul_f32_e32 v102, v146, v242
	v_cvt_pk_bf16_f32 v102, v102, s0
	global_store_short v[100:101], v102, off
.LBB0_3799:
	s_or_b64 exec, exec, s[0:1]
	s_waitcnt vmcnt(8)
	v_add_f32_e32 v147, v109, v145
	s_and_saveexec_b64 s[0:1], vcc
	s_cbranch_execz .LBB0_3801
	global_store_dword v[98:99], v147, off offset:128
	v_mul_f32_e32 v98, v147, v243
	v_cvt_pk_bf16_f32 v98, v98, s0
	global_store_short v[100:101], v98, off offset:64
.LBB0_3801:
	s_or_b64 exec, exec, s[0:1]
	v_cmp_gt_i32_e32 vcc, s85, v144
	s_nop 1
	v_cndmask_b32_e32 v98, v181, v144, vcc
	v_mul_hi_i32 v99, v98, s83
	v_lshrrev_b32_e32 v100, 31, v99
	v_ashrrev_i32_e32 v99, 11, v99
	v_add_u32_e32 v100, v99, v100
	v_mad_i32_i24 v101, v100, s84, v98
	v_cmp_lt_i32_e64 s[0:1], 15, v101
	s_and_saveexec_b64 s[2:3], s[0:1]
	s_xor_b64 s[0:1], exec, s[2:3]
	v_lshlrev_b32_e32 v98, 12, v100
	v_add3_u32 v98, v98, v101, -16
	v_ashrrev_i32_e32 v99, 31, v98
	v_lshlrev_b64 v[98:99], 12, v[98:99]
	v_lshl_add_u64 v[98:99], s[88:89], 0, v[98:99]
	s_andn2_saveexec_b64 s[0:1], s[0:1]
	v_lshlrev_b32_e32 v98, 14, v100
	v_lshl_add_u32 v98, v101, 10, v98
	v_ashrrev_i32_e32 v99, 31, v98
	v_lshl_add_u64 v[98:99], v[98:99], 2, s[16:17]
	s_or_b64 exec, exec, s[0:1]
	v_ashrrev_i32_e32 v145, 31, v144
	v_lshlrev_b64 v[100:101], 11, v[144:145]
	v_lshl_add_u64 v[100:101], s[62:63], 0, v[100:101]
	s_waitcnt vmcnt(7)
	v_add_f32_e32 v144, v126, v183
	v_lshl_add_u64 v[100:101], v[130:131], 1, v[100:101]
	v_lshl_add_u64 v[98:99], v[98:99], 0, v[134:135]
	s_and_saveexec_b64 s[0:1], vcc
	s_cbranch_execz .LBB0_3807
	global_store_dword v[98:99], v144, off
	v_mul_f32_e32 v102, v144, v242
	v_cvt_pk_bf16_f32 v102, v102, s0
	global_store_short v[100:101], v102, off
.LBB0_3807:
	s_or_b64 exec, exec, s[0:1]
	s_waitcnt vmcnt(6)
	v_add_f32_e32 v145, v110, v143
	s_and_saveexec_b64 s[0:1], vcc
	s_cbranch_execz .LBB0_3809
	global_store_dword v[98:99], v145, off offset:128
	v_mul_f32_e32 v98, v145, v243
	v_cvt_pk_bf16_f32 v98, v98, s0
	global_store_short v[100:101], v98, off offset:64
.LBB0_3809:
	s_or_b64 exec, exec, s[0:1]
	v_cmp_gt_i32_e32 vcc, s85, v142
	s_nop 1
	v_cndmask_b32_e32 v98, v181, v142, vcc
	v_mul_hi_i32 v99, v98, s83
	v_lshrrev_b32_e32 v100, 31, v99
	v_ashrrev_i32_e32 v99, 11, v99
	v_add_u32_e32 v100, v99, v100
	v_mad_i32_i24 v101, v100, s84, v98
	v_cmp_lt_i32_e64 s[0:1], 15, v101
	s_and_saveexec_b64 s[2:3], s[0:1]
	s_xor_b64 s[0:1], exec, s[2:3]
	v_lshlrev_b32_e32 v98, 12, v100
	v_add3_u32 v98, v98, v101, -16
	v_ashrrev_i32_e32 v99, 31, v98
	v_lshlrev_b64 v[98:99], 12, v[98:99]
	v_lshl_add_u64 v[98:99], s[88:89], 0, v[98:99]
	s_andn2_saveexec_b64 s[0:1], s[0:1]
	v_lshlrev_b32_e32 v98, 14, v100
	v_lshl_add_u32 v98, v101, 10, v98
	v_ashrrev_i32_e32 v99, 31, v98
	v_lshl_add_u64 v[98:99], v[98:99], 2, s[16:17]
	s_or_b64 exec, exec, s[0:1]
	v_ashrrev_i32_e32 v143, 31, v142
	v_lshlrev_b64 v[100:101], 11, v[142:143]
	v_lshl_add_u64 v[100:101], s[62:63], 0, v[100:101]
	s_waitcnt vmcnt(5)
	v_add_f32_e32 v142, v127, v182
	v_lshl_add_u64 v[100:101], v[130:131], 1, v[100:101]
	v_lshl_add_u64 v[98:99], v[98:99], 0, v[134:135]
	s_and_saveexec_b64 s[0:1], vcc
	s_cbranch_execz .LBB0_3815
	global_store_dword v[98:99], v142, off
	v_mul_f32_e32 v102, v142, v242
	v_cvt_pk_bf16_f32 v102, v102, s0
	global_store_short v[100:101], v102, off
.LBB0_3815:
	s_or_b64 exec, exec, s[0:1]
	s_waitcnt vmcnt(4)
	v_add_f32_e32 v143, v111, v141
	s_and_saveexec_b64 s[0:1], vcc
	s_cbranch_execz .LBB0_3817
	global_store_dword v[98:99], v143, off offset:128
	v_mul_f32_e32 v98, v143, v243
	v_cvt_pk_bf16_f32 v98, v98, s0
	global_store_short v[100:101], v98, off offset:64
.LBB0_3817:
	s_or_b64 exec, exec, s[0:1]
	v_cmp_gt_i32_e32 vcc, s85, v140
	s_nop 1
	v_cndmask_b32_e32 v98, v181, v140, vcc
	v_mul_hi_i32 v99, v98, s83
	v_lshrrev_b32_e32 v100, 31, v99
	v_ashrrev_i32_e32 v99, 11, v99
	v_add_u32_e32 v100, v99, v100
	v_mad_i32_i24 v101, v100, s84, v98
	v_cmp_lt_i32_e64 s[0:1], 15, v101
	s_and_saveexec_b64 s[2:3], s[0:1]
	s_xor_b64 s[0:1], exec, s[2:3]
	v_lshlrev_b32_e32 v98, 12, v100
	v_add3_u32 v98, v98, v101, -16
	v_ashrrev_i32_e32 v99, 31, v98
	v_lshlrev_b64 v[98:99], 12, v[98:99]
	v_lshl_add_u64 v[98:99], s[88:89], 0, v[98:99]
	s_andn2_saveexec_b64 s[0:1], s[0:1]
	v_lshlrev_b32_e32 v98, 14, v100
	v_lshl_add_u32 v98, v101, 10, v98
	v_ashrrev_i32_e32 v99, 31, v98
	v_lshl_add_u64 v[98:99], v[98:99], 2, s[16:17]
	s_or_b64 exec, exec, s[0:1]
	v_ashrrev_i32_e32 v141, 31, v140
	v_lshlrev_b64 v[100:101], 11, v[140:141]
	v_lshl_add_u64 v[100:101], s[62:63], 0, v[100:101]
	s_waitcnt vmcnt(3)
	v_add_f32_e32 v140, v128, v179
	v_lshl_add_u64 v[100:101], v[130:131], 1, v[100:101]
	v_lshl_add_u64 v[98:99], v[98:99], 0, v[134:135]
	s_and_saveexec_b64 s[0:1], vcc
	s_cbranch_execz .LBB0_3823
	global_store_dword v[98:99], v140, off
	v_mul_f32_e32 v102, v140, v242
	v_cvt_pk_bf16_f32 v102, v102, s0
	global_store_short v[100:101], v102, off
.LBB0_3823:
	s_or_b64 exec, exec, s[0:1]
	s_waitcnt vmcnt(2)
	v_add_f32_e32 v141, v112, v139
	s_and_saveexec_b64 s[0:1], vcc
	s_cbranch_execz .LBB0_3825
	global_store_dword v[98:99], v141, off offset:128
	v_mul_f32_e32 v98, v141, v243
	v_cvt_pk_bf16_f32 v98, v98, s0
	global_store_short v[100:101], v98, off offset:64
.LBB0_3825:
	s_or_b64 exec, exec, s[0:1]
	v_cmp_gt_i32_e32 vcc, s85, v138
	s_nop 1
	v_cndmask_b32_e32 v98, v181, v138, vcc
	v_mul_hi_i32 v99, v98, s83
	v_lshrrev_b32_e32 v100, 31, v99
	v_ashrrev_i32_e32 v99, 11, v99
	v_add_u32_e32 v100, v99, v100
	v_mad_i32_i24 v101, v100, s84, v98
	v_cmp_lt_i32_e64 s[0:1], 15, v101
	s_and_saveexec_b64 s[2:3], s[0:1]
	s_xor_b64 s[0:1], exec, s[2:3]
	v_lshlrev_b32_e32 v98, 12, v100
	v_add3_u32 v98, v98, v101, -16
	v_ashrrev_i32_e32 v99, 31, v98
	v_lshlrev_b64 v[98:99], 12, v[98:99]
	v_lshl_add_u64 v[98:99], s[88:89], 0, v[98:99]
	s_andn2_saveexec_b64 s[0:1], s[0:1]
	v_lshlrev_b32_e32 v98, 14, v100
	v_lshl_add_u32 v98, v101, 10, v98
	v_ashrrev_i32_e32 v99, 31, v98
	v_lshl_add_u64 v[98:99], v[98:99], 2, s[16:17]
	s_or_b64 exec, exec, s[0:1]
	v_ashrrev_i32_e32 v139, 31, v138
	v_lshlrev_b64 v[100:101], 11, v[138:139]
	v_lshl_add_u64 v[100:101], s[62:63], 0, v[100:101]
	s_waitcnt vmcnt(1)
	v_add_f32_e32 v166, v129, v178
	v_lshl_add_u64 v[100:101], v[130:131], 1, v[100:101]
	v_lshl_add_u64 v[98:99], v[98:99], 0, v[134:135]
	s_and_saveexec_b64 s[0:1], vcc
	s_cbranch_execz .LBB0_3831
	global_store_dword v[98:99], v166, off
	v_mul_f32_e32 v102, v166, v242
	v_cvt_pk_bf16_f32 v102, v102, s0
	global_store_short v[100:101], v102, off
.LBB0_3831:
	s_or_b64 exec, exec, s[0:1]
	s_waitcnt vmcnt(0)
	v_add_f32_e32 v167, v113, v177
	s_and_saveexec_b64 s[0:1], vcc
	s_cbranch_execz .LBB0_3833
	global_store_dword v[98:99], v167, off offset:128
	v_mul_f32_e32 v98, v167, v243
	v_cvt_pk_bf16_f32 v98, v98, s0
	global_store_short v[100:101], v98, off offset:64
.LBB0_3833:
	s_or_b64 exec, exec, s[0:1]
	v_or_b32_e32 v128, 32, v136
	v_min_i32_e32 v98, 0x403f, v128
	v_mul_hi_i32 v99, v98, s83
	v_lshrrev_b32_e32 v100, 31, v99
	v_ashrrev_i32_e32 v99, 11, v99
	v_add_u32_e32 v100, v99, v100
	v_mad_i32_i24 v101, v100, s84, v98
	v_cmp_lt_i32_e32 vcc, 15, v101
	s_and_saveexec_b64 s[0:1], vcc
	s_xor_b64 s[0:1], exec, s[0:1]
	v_lshlrev_b32_e32 v98, 12, v100
	v_add3_u32 v98, v98, v101, -16
	v_ashrrev_i32_e32 v99, 31, v98
	v_lshlrev_b64 v[98:99], 12, v[98:99]
	v_lshl_add_u64 v[98:99], s[88:89], 0, v[98:99]
	s_andn2_saveexec_b64 s[0:1], s[0:1]
	v_lshlrev_b32_e32 v98, 14, v100
	v_lshl_add_u32 v98, v101, 10, v98
	v_ashrrev_i32_e32 v99, 31, v98
	v_lshl_add_u64 v[98:99], v[98:99], 2, s[16:17]
	s_or_b64 exec, exec, s[0:1]
	v_lshl_add_u64 v[98:99], v[130:131], 2, v[98:99]
	global_load_dword v169, v[98:99], off
	global_load_dword v127, v[98:99], off offset:128
	v_or_b32_e32 v126, 33, v136
	v_min_i32_e32 v98, 0x403f, v126
	v_mul_hi_i32 v99, v98, s83
	v_lshrrev_b32_e32 v100, 31, v99
	v_ashrrev_i32_e32 v99, 11, v99
	v_add_u32_e32 v100, v99, v100
	v_mad_i32_i24 v101, v100, s84, v98
	v_cmp_lt_i32_e32 vcc, 15, v101
	s_and_saveexec_b64 s[0:1], vcc
	s_xor_b64 s[0:1], exec, s[0:1]
	v_lshlrev_b32_e32 v98, 12, v100
	v_add3_u32 v98, v98, v101, -16
	v_ashrrev_i32_e32 v99, 31, v98
	v_lshlrev_b64 v[98:99], 12, v[98:99]
	v_lshl_add_u64 v[98:99], s[88:89], 0, v[98:99]
	s_andn2_saveexec_b64 s[0:1], s[0:1]
	v_lshlrev_b32_e32 v98, 14, v100
	v_lshl_add_u32 v98, v101, 10, v98
	v_ashrrev_i32_e32 v99, 31, v98
	v_lshl_add_u64 v[98:99], v[98:99], 2, s[16:17]
	s_or_b64 exec, exec, s[0:1]
	v_lshl_add_u64 v[98:99], v[130:131], 2, v[98:99]
	global_load_dword v194, v[98:99], off
	global_load_dword v125, v[98:99], off offset:128
	v_or_b32_e32 v124, 34, v136
	v_min_i32_e32 v98, 0x403f, v124
	v_mul_hi_i32 v99, v98, s83
	v_lshrrev_b32_e32 v100, 31, v99
	v_ashrrev_i32_e32 v99, 11, v99
	v_add_u32_e32 v100, v99, v100
	v_mad_i32_i24 v101, v100, s84, v98
	v_cmp_lt_i32_e32 vcc, 15, v101
	s_and_saveexec_b64 s[0:1], vcc
	s_xor_b64 s[0:1], exec, s[0:1]
	v_lshlrev_b32_e32 v98, 12, v100
	v_add3_u32 v98, v98, v101, -16
	v_ashrrev_i32_e32 v99, 31, v98
	v_lshlrev_b64 v[98:99], 12, v[98:99]
	v_lshl_add_u64 v[98:99], s[88:89], 0, v[98:99]
	s_andn2_saveexec_b64 s[0:1], s[0:1]
	v_lshlrev_b32_e32 v98, 14, v100
	v_lshl_add_u32 v98, v101, 10, v98
	v_ashrrev_i32_e32 v99, 31, v98
	v_lshl_add_u64 v[98:99], v[98:99], 2, s[16:17]
	s_or_b64 exec, exec, s[0:1]
	v_lshl_add_u64 v[98:99], v[130:131], 2, v[98:99]
	global_load_dword v193, v[98:99], off
	global_load_dword v123, v[98:99], off offset:128
	v_or_b32_e32 v122, 35, v136
	v_min_i32_e32 v98, 0x403f, v122
	v_mul_hi_i32 v99, v98, s83
	v_lshrrev_b32_e32 v100, 31, v99
	v_ashrrev_i32_e32 v99, 11, v99
	v_add_u32_e32 v100, v99, v100
	v_mad_i32_i24 v101, v100, s84, v98
	v_cmp_lt_i32_e32 vcc, 15, v101
	s_and_saveexec_b64 s[0:1], vcc
	s_xor_b64 s[0:1], exec, s[0:1]
	v_lshlrev_b32_e32 v98, 12, v100
	v_add3_u32 v98, v98, v101, -16
	v_ashrrev_i32_e32 v99, 31, v98
	v_lshlrev_b64 v[98:99], 12, v[98:99]
	v_lshl_add_u64 v[98:99], s[88:89], 0, v[98:99]
	s_andn2_saveexec_b64 s[0:1], s[0:1]
	v_lshlrev_b32_e32 v98, 14, v100
	v_lshl_add_u32 v98, v101, 10, v98
	v_ashrrev_i32_e32 v99, 31, v98
	v_lshl_add_u64 v[98:99], v[98:99], 2, s[16:17]
	s_or_b64 exec, exec, s[0:1]
	v_lshl_add_u64 v[98:99], v[130:131], 2, v[98:99]
	global_load_dword v192, v[98:99], off
	global_load_dword v121, v[98:99], off offset:128
	v_or_b32_e32 v120, 40, v136
	v_min_i32_e32 v98, 0x403f, v120
	v_mul_hi_i32 v99, v98, s83
	v_lshrrev_b32_e32 v100, 31, v99
	v_ashrrev_i32_e32 v99, 11, v99
	v_add_u32_e32 v100, v99, v100
	v_mad_i32_i24 v101, v100, s84, v98
	v_cmp_lt_i32_e32 vcc, 15, v101
	s_and_saveexec_b64 s[0:1], vcc
	s_xor_b64 s[0:1], exec, s[0:1]
	v_lshlrev_b32_e32 v98, 12, v100
	v_add3_u32 v98, v98, v101, -16
	v_ashrrev_i32_e32 v99, 31, v98
	v_lshlrev_b64 v[98:99], 12, v[98:99]
	v_lshl_add_u64 v[98:99], s[88:89], 0, v[98:99]
	s_andn2_saveexec_b64 s[0:1], s[0:1]
	v_lshlrev_b32_e32 v98, 14, v100
	v_lshl_add_u32 v98, v101, 10, v98
	v_ashrrev_i32_e32 v99, 31, v98
	v_lshl_add_u64 v[98:99], v[98:99], 2, s[16:17]
	s_or_b64 exec, exec, s[0:1]
	v_lshl_add_u64 v[98:99], v[130:131], 2, v[98:99]
	global_load_dword v191, v[98:99], off
	global_load_dword v119, v[98:99], off offset:128
	v_or_b32_e32 v118, 41, v136
	v_min_i32_e32 v98, 0x403f, v118
	v_mul_hi_i32 v99, v98, s83
	v_lshrrev_b32_e32 v100, 31, v99
	v_ashrrev_i32_e32 v99, 11, v99
	v_add_u32_e32 v100, v99, v100
	v_mad_i32_i24 v101, v100, s84, v98
	v_cmp_lt_i32_e32 vcc, 15, v101
	s_and_saveexec_b64 s[0:1], vcc
	s_xor_b64 s[0:1], exec, s[0:1]
	v_lshlrev_b32_e32 v98, 12, v100
	v_add3_u32 v98, v98, v101, -16
	v_ashrrev_i32_e32 v99, 31, v98
	v_lshlrev_b64 v[98:99], 12, v[98:99]
	v_lshl_add_u64 v[98:99], s[88:89], 0, v[98:99]
	s_andn2_saveexec_b64 s[0:1], s[0:1]
	v_lshlrev_b32_e32 v98, 14, v100
	v_lshl_add_u32 v98, v101, 10, v98
	v_ashrrev_i32_e32 v99, 31, v98
	v_lshl_add_u64 v[98:99], v[98:99], 2, s[16:17]
	s_or_b64 exec, exec, s[0:1]
	v_lshl_add_u64 v[98:99], v[130:131], 2, v[98:99]
	global_load_dword v190, v[98:99], off
	global_load_dword v117, v[98:99], off offset:128
	v_or_b32_e32 v116, 42, v136
	v_min_i32_e32 v98, 0x403f, v116
	v_mul_hi_i32 v99, v98, s83
	v_lshrrev_b32_e32 v100, 31, v99
	v_ashrrev_i32_e32 v99, 11, v99
	v_add_u32_e32 v100, v99, v100
	v_mad_i32_i24 v101, v100, s84, v98
	v_cmp_lt_i32_e32 vcc, 15, v101
	s_and_saveexec_b64 s[0:1], vcc
	s_xor_b64 s[0:1], exec, s[0:1]
	v_lshlrev_b32_e32 v98, 12, v100
	v_add3_u32 v98, v98, v101, -16
	v_ashrrev_i32_e32 v99, 31, v98
	v_lshlrev_b64 v[98:99], 12, v[98:99]
	v_lshl_add_u64 v[98:99], s[88:89], 0, v[98:99]
	s_andn2_saveexec_b64 s[0:1], s[0:1]
	v_lshlrev_b32_e32 v98, 14, v100
	v_lshl_add_u32 v98, v101, 10, v98
	v_ashrrev_i32_e32 v99, 31, v98
	v_lshl_add_u64 v[98:99], v[98:99], 2, s[16:17]
	s_or_b64 exec, exec, s[0:1]
	v_lshl_add_u64 v[98:99], v[130:131], 2, v[98:99]
	global_load_dword v189, v[98:99], off
	global_load_dword v115, v[98:99], off offset:128
	v_or_b32_e32 v114, 43, v136
	v_min_i32_e32 v98, 0x403f, v114
	v_mul_hi_i32 v99, v98, s83
	v_lshrrev_b32_e32 v100, 31, v99
	v_ashrrev_i32_e32 v99, 11, v99
	v_add_u32_e32 v100, v99, v100
	v_mad_i32_i24 v101, v100, s84, v98
	v_cmp_lt_i32_e32 vcc, 15, v101
	s_and_saveexec_b64 s[0:1], vcc
	s_xor_b64 s[0:1], exec, s[0:1]
	v_lshlrev_b32_e32 v98, 12, v100
	v_add3_u32 v98, v98, v101, -16
	v_ashrrev_i32_e32 v99, 31, v98
	v_lshlrev_b64 v[98:99], 12, v[98:99]
	v_lshl_add_u64 v[98:99], s[88:89], 0, v[98:99]
	s_andn2_saveexec_b64 s[0:1], s[0:1]
	v_lshlrev_b32_e32 v98, 14, v100
	v_lshl_add_u32 v98, v101, 10, v98
	v_ashrrev_i32_e32 v99, 31, v98
	v_lshl_add_u64 v[98:99], v[98:99], 2, s[16:17]
	s_or_b64 exec, exec, s[0:1]
	v_lshl_add_u64 v[98:99], v[130:131], 2, v[98:99]
	global_load_dword v188, v[98:99], off
	global_load_dword v113, v[98:99], off offset:128
	v_or_b32_e32 v112, 48, v136
	v_min_i32_e32 v98, 0x403f, v112
	v_mul_hi_i32 v99, v98, s83
	v_lshrrev_b32_e32 v100, 31, v99
	v_ashrrev_i32_e32 v99, 11, v99
	v_add_u32_e32 v100, v99, v100
	v_mad_i32_i24 v101, v100, s84, v98
	v_cmp_lt_i32_e32 vcc, 15, v101
	s_and_saveexec_b64 s[0:1], vcc
	s_xor_b64 s[0:1], exec, s[0:1]
	v_lshlrev_b32_e32 v98, 12, v100
	v_add3_u32 v98, v98, v101, -16
	v_ashrrev_i32_e32 v99, 31, v98
	v_lshlrev_b64 v[98:99], 12, v[98:99]
	v_lshl_add_u64 v[98:99], s[88:89], 0, v[98:99]
	s_andn2_saveexec_b64 s[0:1], s[0:1]
	v_lshlrev_b32_e32 v98, 14, v100
	v_lshl_add_u32 v98, v101, 10, v98
	v_ashrrev_i32_e32 v99, 31, v98
	v_lshl_add_u64 v[98:99], v[98:99], 2, s[16:17]
	s_or_b64 exec, exec, s[0:1]
	v_lshl_add_u64 v[98:99], v[130:131], 2, v[98:99]
	global_load_dword v187, v[98:99], off
	global_load_dword v111, v[98:99], off offset:128
	v_or_b32_e32 v110, 49, v136
	v_min_i32_e32 v98, 0x403f, v110
	v_mul_hi_i32 v99, v98, s83
	v_lshrrev_b32_e32 v100, 31, v99
	v_ashrrev_i32_e32 v99, 11, v99
	v_add_u32_e32 v100, v99, v100
	v_mad_i32_i24 v101, v100, s84, v98
	v_cmp_lt_i32_e32 vcc, 15, v101
	s_and_saveexec_b64 s[0:1], vcc
	s_xor_b64 s[0:1], exec, s[0:1]
	v_lshlrev_b32_e32 v98, 12, v100
	v_add3_u32 v98, v98, v101, -16
	v_ashrrev_i32_e32 v99, 31, v98
	v_lshlrev_b64 v[98:99], 12, v[98:99]
	v_lshl_add_u64 v[98:99], s[88:89], 0, v[98:99]
	s_andn2_saveexec_b64 s[0:1], s[0:1]
	v_lshlrev_b32_e32 v98, 14, v100
	v_lshl_add_u32 v98, v101, 10, v98
	v_ashrrev_i32_e32 v99, 31, v98
	v_lshl_add_u64 v[98:99], v[98:99], 2, s[16:17]
	s_or_b64 exec, exec, s[0:1]
	v_lshl_add_u64 v[98:99], v[130:131], 2, v[98:99]
	global_load_dword v186, v[98:99], off
	global_load_dword v109, v[98:99], off offset:128
	v_or_b32_e32 v108, 50, v136
	v_min_i32_e32 v98, 0x403f, v108
	v_mul_hi_i32 v99, v98, s83
	v_lshrrev_b32_e32 v100, 31, v99
	v_ashrrev_i32_e32 v99, 11, v99
	v_add_u32_e32 v100, v99, v100
	v_mad_i32_i24 v101, v100, s84, v98
	v_cmp_lt_i32_e32 vcc, 15, v101
	s_and_saveexec_b64 s[0:1], vcc
	s_xor_b64 s[0:1], exec, s[0:1]
	v_lshlrev_b32_e32 v98, 12, v100
	v_add3_u32 v98, v98, v101, -16
	v_ashrrev_i32_e32 v99, 31, v98
	v_lshlrev_b64 v[98:99], 12, v[98:99]
	v_lshl_add_u64 v[98:99], s[88:89], 0, v[98:99]
	s_andn2_saveexec_b64 s[0:1], s[0:1]
	v_lshlrev_b32_e32 v98, 14, v100
	v_lshl_add_u32 v98, v101, 10, v98
	v_ashrrev_i32_e32 v99, 31, v98
	v_lshl_add_u64 v[98:99], v[98:99], 2, s[16:17]
	s_or_b64 exec, exec, s[0:1]
	v_lshl_add_u64 v[98:99], v[130:131], 2, v[98:99]
	global_load_dword v185, v[98:99], off
	global_load_dword v107, v[98:99], off offset:128
	v_or_b32_e32 v106, 51, v136
	v_min_i32_e32 v98, 0x403f, v106
	v_mul_hi_i32 v99, v98, s83
	v_lshrrev_b32_e32 v100, 31, v99
	v_ashrrev_i32_e32 v99, 11, v99
	v_add_u32_e32 v100, v99, v100
	v_mad_i32_i24 v101, v100, s84, v98
	v_cmp_lt_i32_e32 vcc, 15, v101
	s_and_saveexec_b64 s[0:1], vcc
	s_xor_b64 s[0:1], exec, s[0:1]
	v_lshlrev_b32_e32 v98, 12, v100
	v_add3_u32 v98, v98, v101, -16
	v_ashrrev_i32_e32 v99, 31, v98
	v_lshlrev_b64 v[98:99], 12, v[98:99]
	v_lshl_add_u64 v[98:99], s[88:89], 0, v[98:99]
	s_andn2_saveexec_b64 s[0:1], s[0:1]
	v_lshlrev_b32_e32 v98, 14, v100
	v_lshl_add_u32 v98, v101, 10, v98
	v_ashrrev_i32_e32 v99, 31, v98
	v_lshl_add_u64 v[98:99], v[98:99], 2, s[16:17]
	s_or_b64 exec, exec, s[0:1]
	v_lshl_add_u64 v[98:99], v[130:131], 2, v[98:99]
	global_load_dword v184, v[98:99], off
	global_load_dword v105, v[98:99], off offset:128
	v_or_b32_e32 v104, 56, v136
	v_min_i32_e32 v98, 0x403f, v104
	v_mul_hi_i32 v99, v98, s83
	v_lshrrev_b32_e32 v100, 31, v99
	v_ashrrev_i32_e32 v99, 11, v99
	v_add_u32_e32 v100, v99, v100
	v_mad_i32_i24 v101, v100, s84, v98
	v_cmp_lt_i32_e32 vcc, 15, v101
	s_and_saveexec_b64 s[0:1], vcc
	s_xor_b64 s[0:1], exec, s[0:1]
	v_lshlrev_b32_e32 v98, 12, v100
	v_add3_u32 v98, v98, v101, -16
	v_ashrrev_i32_e32 v99, 31, v98
	v_lshlrev_b64 v[98:99], 12, v[98:99]
	v_lshl_add_u64 v[98:99], s[88:89], 0, v[98:99]
	s_andn2_saveexec_b64 s[0:1], s[0:1]
	v_lshlrev_b32_e32 v98, 14, v100
	v_lshl_add_u32 v98, v101, 10, v98
	v_ashrrev_i32_e32 v99, 31, v98
	v_lshl_add_u64 v[98:99], v[98:99], 2, s[16:17]
	s_or_b64 exec, exec, s[0:1]
	v_lshl_add_u64 v[98:99], v[130:131], 2, v[98:99]
	global_load_dword v183, v[98:99], off
	global_load_dword v103, v[98:99], off offset:128
	v_or_b32_e32 v102, 57, v136
	v_min_i32_e32 v98, 0x403f, v102
	v_mul_hi_i32 v99, v98, s83
	v_lshrrev_b32_e32 v100, 31, v99
	v_ashrrev_i32_e32 v99, 11, v99
	v_add_u32_e32 v100, v99, v100
	v_mad_i32_i24 v101, v100, s84, v98
	v_cmp_lt_i32_e32 vcc, 15, v101
	s_and_saveexec_b64 s[0:1], vcc
	s_xor_b64 s[0:1], exec, s[0:1]
	v_lshlrev_b32_e32 v98, 12, v100
	v_add3_u32 v98, v98, v101, -16
	v_ashrrev_i32_e32 v99, 31, v98
	v_lshlrev_b64 v[98:99], 12, v[98:99]
	v_lshl_add_u64 v[98:99], s[88:89], 0, v[98:99]
	s_andn2_saveexec_b64 s[0:1], s[0:1]
	v_lshlrev_b32_e32 v98, 14, v100
	v_lshl_add_u32 v98, v101, 10, v98
	v_ashrrev_i32_e32 v99, 31, v98
	v_lshl_add_u64 v[98:99], v[98:99], 2, s[16:17]
	s_or_b64 exec, exec, s[0:1]
	v_lshl_add_u64 v[98:99], v[130:131], 2, v[98:99]
	global_load_dword v182, v[98:99], off
	global_load_dword v101, v[98:99], off offset:128
	v_or_b32_e32 v100, 58, v136
	v_min_i32_e32 v98, 0x403f, v100
	v_mul_hi_i32 v99, v98, s83
	v_lshrrev_b32_e32 v129, 31, v99
	v_ashrrev_i32_e32 v99, 11, v99
	v_add_u32_e32 v129, v99, v129
	v_mad_i32_i24 v138, v129, s84, v98
	v_cmp_lt_i32_e32 vcc, 15, v138
	s_and_saveexec_b64 s[0:1], vcc
	s_xor_b64 s[0:1], exec, s[0:1]
	v_lshlrev_b32_e32 v98, 12, v129
	v_add3_u32 v98, v98, v138, -16
	v_ashrrev_i32_e32 v99, 31, v98
	v_lshlrev_b64 v[98:99], 12, v[98:99]
	v_lshl_add_u64 v[98:99], s[88:89], 0, v[98:99]
	s_andn2_saveexec_b64 s[0:1], s[0:1]
	v_lshlrev_b32_e32 v98, 14, v129
	v_lshl_add_u32 v98, v138, 10, v98
	v_ashrrev_i32_e32 v99, 31, v98
	v_lshl_add_u64 v[98:99], v[98:99], 2, s[16:17]
	s_or_b64 exec, exec, s[0:1]
	v_lshl_add_u64 v[98:99], v[130:131], 2, v[98:99]
	global_load_dword v179, v[98:99], off
	s_nop 0
	global_load_dword v99, v[98:99], off offset:128
	v_or_b32_e32 v98, 59, v136
	v_min_i32_e32 v138, 0x403f, v98
	v_mul_hi_i32 v129, v138, s83
	v_lshrrev_b32_e32 v139, 31, v129
	v_ashrrev_i32_e32 v129, 11, v129
	v_add_u32_e32 v129, v129, v139
	v_mad_i32_i24 v171, v129, s84, v138
	v_cmp_lt_i32_e32 vcc, 15, v171
	s_and_saveexec_b64 s[0:1], vcc
	s_xor_b64 s[0:1], exec, s[0:1]
	v_lshlrev_b32_e32 v129, 12, v129
	v_add3_u32 v138, v129, v171, -16
	v_ashrrev_i32_e32 v139, 31, v138
	v_lshlrev_b64 v[138:139], 12, v[138:139]
	v_lshl_add_u64 v[138:139], s[88:89], 0, v[138:139]
	s_andn2_saveexec_b64 s[0:1], s[0:1]
	v_lshlrev_b32_e32 v129, 14, v129
	v_lshl_add_u32 v138, v171, 10, v129
	v_ashrrev_i32_e32 v139, 31, v138
	v_lshl_add_u64 v[138:139], v[138:139], 2, s[16:17]
	s_or_b64 exec, exec, s[0:1]
	v_lshl_add_u64 v[138:139], v[130:131], 2, v[138:139]
	global_load_dword v177, v[138:139], off
	global_load_dword v171, v[138:139], off offset:128
	v_cmp_gt_i32_e32 vcc, s85, v128
	s_nop 1
	v_cndmask_b32_e32 v138, v181, v128, vcc
	v_mul_hi_i32 v129, v138, s83
	v_lshrrev_b32_e32 v139, 31, v129
	v_ashrrev_i32_e32 v129, 11, v129
	v_add_u32_e32 v129, v129, v139
	v_mad_i32_i24 v178, v129, s84, v138
	v_cmp_lt_i32_e64 s[0:1], 15, v178
	s_and_saveexec_b64 s[2:3], s[0:1]
	s_xor_b64 s[0:1], exec, s[2:3]
	v_lshlrev_b32_e32 v129, 12, v129
	v_add3_u32 v138, v129, v178, -16
	v_ashrrev_i32_e32 v139, 31, v138
	v_lshlrev_b64 v[138:139], 12, v[138:139]
	v_lshl_add_u64 v[138:139], s[88:89], 0, v[138:139]
	s_andn2_saveexec_b64 s[0:1], s[0:1]
	v_lshlrev_b32_e32 v129, 14, v129
	v_lshl_add_u32 v138, v178, 10, v129
	v_ashrrev_i32_e32 v139, 31, v138
	v_lshl_add_u64 v[138:139], v[138:139], 2, s[16:17]
	s_or_b64 exec, exec, s[0:1]
	v_ashrrev_i32_e32 v129, 31, v128
	v_lshlrev_b64 v[128:129], 11, v[128:129]
	v_lshl_add_u64 v[128:129], s[62:63], 0, v[128:129]
	s_waitcnt vmcnt(31)
	v_add_f32_e32 v169, v82, v169
	v_lshl_add_u64 v[128:129], v[130:131], 1, v[128:129]
	v_lshl_add_u64 v[138:139], v[138:139], 0, v[134:135]
	s_and_saveexec_b64 s[0:1], vcc
	s_cbranch_execz .LBB0_3903
	global_store_dword v[138:139], v169, off
	v_mul_f32_e32 v82, v169, v242
	v_cvt_pk_bf16_f32 v82, v82, s0
	global_store_short v[128:129], v82, off
.LBB0_3903:
	s_or_b64 exec, exec, s[0:1]
	s_waitcnt vmcnt(30)
	v_add_f32_e32 v178, v66, v127
	s_and_saveexec_b64 s[0:1], vcc
	s_cbranch_execz .LBB0_3905
	global_store_dword v[138:139], v178, off offset:128
	v_mul_f32_e32 v66, v178, v243
	v_cvt_pk_bf16_f32 v66, v66, s0
	global_store_short v[128:129], v66, off offset:64
.LBB0_3905:
	s_or_b64 exec, exec, s[0:1]
	v_cmp_gt_i32_e32 vcc, s85, v126
	s_nop 1
	v_cndmask_b32_e32 v82, v181, v126, vcc
	v_mul_hi_i32 v66, v82, s83
	v_lshrrev_b32_e32 v127, 31, v66
	v_ashrrev_i32_e32 v66, 11, v66
	v_add_u32_e32 v66, v66, v127
	v_mad_i32_i24 v82, v66, s84, v82
	v_cmp_lt_i32_e64 s[0:1], 15, v82
	s_and_saveexec_b64 s[2:3], s[0:1]
	s_xor_b64 s[0:1], exec, s[2:3]
	v_lshlrev_b32_e32 v66, 12, v66
	v_add3_u32 v128, v66, v82, -16
	v_ashrrev_i32_e32 v129, 31, v128
	v_lshlrev_b64 v[128:129], 12, v[128:129]
	v_lshl_add_u64 v[128:129], s[88:89], 0, v[128:129]
	s_andn2_saveexec_b64 s[0:1], s[0:1]
	v_lshlrev_b32_e32 v66, 14, v66
	v_lshl_add_u32 v128, v82, 10, v66
	v_ashrrev_i32_e32 v129, 31, v128
	v_lshl_add_u64 v[128:129], v[128:129], 2, s[16:17]
	s_or_b64 exec, exec, s[0:1]
	v_ashrrev_i32_e32 v127, 31, v126
	v_lshlrev_b64 v[126:127], 11, v[126:127]
	v_lshl_add_u64 v[126:127], s[62:63], 0, v[126:127]
	s_waitcnt vmcnt(29)
	v_add_f32_e32 v138, v83, v194
	v_lshl_add_u64 v[82:83], v[130:131], 1, v[126:127]
	v_lshl_add_u64 v[126:127], v[128:129], 0, v[134:135]
	s_and_saveexec_b64 s[0:1], vcc
	s_cbranch_execz .LBB0_3911
	global_store_dword v[126:127], v138, off
	v_mul_f32_e32 v66, v138, v242
	v_cvt_pk_bf16_f32 v66, v66, s0
	global_store_short v[82:83], v66, off
.LBB0_3911:
	s_or_b64 exec, exec, s[0:1]
	s_waitcnt vmcnt(28)
	v_add_f32_e32 v128, v67, v125
	s_and_saveexec_b64 s[0:1], vcc
	s_cbranch_execz .LBB0_3913
	global_store_dword v[126:127], v128, off offset:128
	v_mul_f32_e32 v66, v128, v243
	v_cvt_pk_bf16_f32 v66, v66, s0
	global_store_short v[82:83], v66, off offset:64
.LBB0_3913:
	s_or_b64 exec, exec, s[0:1]
	v_cmp_gt_i32_e32 vcc, s85, v124
	s_nop 1
	v_cndmask_b32_e32 v66, v181, v124, vcc
	v_mul_hi_i32 v67, v66, s83
	v_lshrrev_b32_e32 v82, 31, v67
	v_ashrrev_i32_e32 v67, 11, v67
	v_add_u32_e32 v82, v67, v82
	v_mad_i32_i24 v83, v82, s84, v66
	v_cmp_lt_i32_e64 s[0:1], 15, v83
	s_and_saveexec_b64 s[2:3], s[0:1]
	s_xor_b64 s[0:1], exec, s[2:3]
	v_lshlrev_b32_e32 v66, 12, v82
	v_add3_u32 v66, v66, v83, -16
	v_ashrrev_i32_e32 v67, 31, v66
	v_lshlrev_b64 v[66:67], 12, v[66:67]
	v_lshl_add_u64 v[66:67], s[88:89], 0, v[66:67]
	s_andn2_saveexec_b64 s[0:1], s[0:1]
	v_lshlrev_b32_e32 v66, 14, v82
	v_lshl_add_u32 v66, v83, 10, v66
	v_ashrrev_i32_e32 v67, 31, v66
	v_lshl_add_u64 v[66:67], v[66:67], 2, s[16:17]
	s_or_b64 exec, exec, s[0:1]
	v_ashrrev_i32_e32 v125, 31, v124
	v_lshlrev_b64 v[82:83], 11, v[124:125]
	v_lshl_add_u64 v[82:83], s[62:63], 0, v[82:83]
	s_waitcnt vmcnt(27)
	v_add_f32_e32 v84, v84, v193
	v_lshl_add_u64 v[82:83], v[130:131], 1, v[82:83]
	v_lshl_add_u64 v[66:67], v[66:67], 0, v[134:135]
	s_and_saveexec_b64 s[0:1], vcc
	s_cbranch_execz .LBB0_3919
	global_store_dword v[66:67], v84, off
	v_mul_f32_e32 v124, v84, v242
	v_cvt_pk_bf16_f32 v124, v124, s0
	global_store_short v[82:83], v124, off
.LBB0_3919:
	s_or_b64 exec, exec, s[0:1]
	s_waitcnt vmcnt(26)
	v_add_f32_e32 v124, v68, v123
	s_and_saveexec_b64 s[0:1], vcc
	s_cbranch_execz .LBB0_3921
	global_store_dword v[66:67], v124, off offset:128
	v_mul_f32_e32 v66, v124, v243
	v_cvt_pk_bf16_f32 v66, v66, s0
	global_store_short v[82:83], v66, off offset:64
.LBB0_3921:
	s_or_b64 exec, exec, s[0:1]
	v_cmp_gt_i32_e32 vcc, s85, v122
	s_nop 1
	v_cndmask_b32_e32 v66, v181, v122, vcc
	v_mul_hi_i32 v67, v66, s83
	v_lshrrev_b32_e32 v68, 31, v67
	v_ashrrev_i32_e32 v67, 11, v67
	v_add_u32_e32 v68, v67, v68
	v_mad_i32_i24 v82, v68, s84, v66
	v_cmp_lt_i32_e64 s[0:1], 15, v82
	s_and_saveexec_b64 s[2:3], s[0:1]
	s_xor_b64 s[0:1], exec, s[2:3]
	v_lshlrev_b32_e32 v66, 12, v68
	v_add3_u32 v66, v66, v82, -16
	v_ashrrev_i32_e32 v67, 31, v66
	v_lshlrev_b64 v[66:67], 12, v[66:67]
	v_lshl_add_u64 v[66:67], s[88:89], 0, v[66:67]
	s_andn2_saveexec_b64 s[0:1], s[0:1]
	v_lshlrev_b32_e32 v66, 14, v68
	v_lshl_add_u32 v66, v82, 10, v66
	v_ashrrev_i32_e32 v67, 31, v66
	v_lshl_add_u64 v[66:67], v[66:67], 2, s[16:17]
	s_or_b64 exec, exec, s[0:1]
	v_ashrrev_i32_e32 v123, 31, v122
	v_lshlrev_b64 v[82:83], 11, v[122:123]
	v_lshl_add_u64 v[82:83], s[62:63], 0, v[82:83]
	s_waitcnt vmcnt(25)
	v_add_f32_e32 v85, v85, v192
	v_lshl_add_u64 v[82:83], v[130:131], 1, v[82:83]
	v_lshl_add_u64 v[66:67], v[66:67], 0, v[134:135]
	s_and_saveexec_b64 s[0:1], vcc
	s_cbranch_execz .LBB0_3927
	global_store_dword v[66:67], v85, off
	v_mul_f32_e32 v68, v85, v242
	v_cvt_pk_bf16_f32 v68, v68, s0
	global_store_short v[82:83], v68, off
.LBB0_3927:
	s_or_b64 exec, exec, s[0:1]
	s_waitcnt vmcnt(24)
	v_add_f32_e32 v122, v69, v121
	s_and_saveexec_b64 s[0:1], vcc
	s_cbranch_execz .LBB0_3929
	global_store_dword v[66:67], v122, off offset:128
	v_mul_f32_e32 v66, v122, v243
	v_cvt_pk_bf16_f32 v66, v66, s0
	global_store_short v[82:83], v66, off offset:64
.LBB0_3929:
	s_or_b64 exec, exec, s[0:1]
	v_cmp_gt_i32_e32 vcc, s85, v120
	s_nop 1
	v_cndmask_b32_e32 v66, v181, v120, vcc
	v_mul_hi_i32 v67, v66, s83
	v_lshrrev_b32_e32 v68, 31, v67
	v_ashrrev_i32_e32 v67, 11, v67
	v_add_u32_e32 v68, v67, v68
	v_mad_i32_i24 v69, v68, s84, v66
	v_cmp_lt_i32_e64 s[0:1], 15, v69
	s_and_saveexec_b64 s[2:3], s[0:1]
	s_xor_b64 s[0:1], exec, s[2:3]
	v_lshlrev_b32_e32 v66, 12, v68
	v_add3_u32 v66, v66, v69, -16
	v_ashrrev_i32_e32 v67, 31, v66
	v_lshlrev_b64 v[66:67], 12, v[66:67]
	v_lshl_add_u64 v[66:67], s[88:89], 0, v[66:67]
	s_andn2_saveexec_b64 s[0:1], s[0:1]
	v_lshlrev_b32_e32 v66, 14, v68
	v_lshl_add_u32 v66, v69, 10, v66
	v_ashrrev_i32_e32 v67, 31, v66
	v_lshl_add_u64 v[66:67], v[66:67], 2, s[16:17]
	s_or_b64 exec, exec, s[0:1]
	v_ashrrev_i32_e32 v121, 31, v120
	v_lshlrev_b64 v[68:69], 11, v[120:121]
	v_lshl_add_u64 v[68:69], s[62:63], 0, v[68:69]
	s_waitcnt vmcnt(23)
	v_add_f32_e32 v82, v86, v191
	v_lshl_add_u64 v[68:69], v[130:131], 1, v[68:69]
	v_lshl_add_u64 v[66:67], v[66:67], 0, v[134:135]
	s_and_saveexec_b64 s[0:1], vcc
	s_cbranch_execz .LBB0_3935
	global_store_dword v[66:67], v82, off
	v_mul_f32_e32 v83, v82, v242
	v_cvt_pk_bf16_f32 v83, v83, s0
	global_store_short v[68:69], v83, off
.LBB0_3935:
	s_or_b64 exec, exec, s[0:1]
	s_waitcnt vmcnt(22)
	v_add_f32_e32 v70, v70, v119
	s_and_saveexec_b64 s[0:1], vcc
	s_cbranch_execz .LBB0_3937
	global_store_dword v[66:67], v70, off offset:128
	v_mul_f32_e32 v66, v70, v243
	v_cvt_pk_bf16_f32 v66, v66, s0
	global_store_short v[68:69], v66, off offset:64
.LBB0_3937:
	s_or_b64 exec, exec, s[0:1]
	v_cmp_gt_i32_e32 vcc, s85, v118
	s_nop 1
	v_cndmask_b32_e32 v66, v181, v118, vcc
	v_mul_hi_i32 v67, v66, s83
	v_lshrrev_b32_e32 v68, 31, v67
	v_ashrrev_i32_e32 v67, 11, v67
	v_add_u32_e32 v68, v67, v68
	v_mad_i32_i24 v69, v68, s84, v66
	v_cmp_lt_i32_e64 s[0:1], 15, v69
	s_and_saveexec_b64 s[2:3], s[0:1]
	s_xor_b64 s[0:1], exec, s[2:3]
	v_lshlrev_b32_e32 v66, 12, v68
	v_add3_u32 v66, v66, v69, -16
	v_ashrrev_i32_e32 v67, 31, v66
	v_lshlrev_b64 v[66:67], 12, v[66:67]
	v_lshl_add_u64 v[66:67], s[88:89], 0, v[66:67]
	s_andn2_saveexec_b64 s[0:1], s[0:1]
	v_lshlrev_b32_e32 v66, 14, v68
	v_lshl_add_u32 v66, v69, 10, v66
	v_ashrrev_i32_e32 v67, 31, v66
	v_lshl_add_u64 v[66:67], v[66:67], 2, s[16:17]
	s_or_b64 exec, exec, s[0:1]
	v_ashrrev_i32_e32 v119, 31, v118
	v_lshlrev_b64 v[68:69], 11, v[118:119]
	v_lshl_add_u64 v[68:69], s[62:63], 0, v[68:69]
	s_waitcnt vmcnt(21)
	v_add_f32_e32 v83, v87, v190
	v_lshl_add_u64 v[68:69], v[130:131], 1, v[68:69]
	v_lshl_add_u64 v[66:67], v[66:67], 0, v[134:135]
	s_and_saveexec_b64 s[0:1], vcc
	s_cbranch_execz .LBB0_3943
	global_store_dword v[66:67], v83, off
	v_mul_f32_e32 v86, v83, v242
	v_cvt_pk_bf16_f32 v86, v86, s0
	global_store_short v[68:69], v86, off
.LBB0_3943:
	s_or_b64 exec, exec, s[0:1]
	s_waitcnt vmcnt(20)
	v_add_f32_e32 v71, v71, v117
	s_and_saveexec_b64 s[0:1], vcc
	s_cbranch_execz .LBB0_3945
	global_store_dword v[66:67], v71, off offset:128
	v_mul_f32_e32 v66, v71, v243
	v_cvt_pk_bf16_f32 v66, v66, s0
	global_store_short v[68:69], v66, off offset:64
.LBB0_3945:
	s_or_b64 exec, exec, s[0:1]
	v_cmp_gt_i32_e32 vcc, s85, v116
	s_nop 1
	v_cndmask_b32_e32 v66, v181, v116, vcc
	v_mul_hi_i32 v67, v66, s83
	v_lshrrev_b32_e32 v68, 31, v67
	v_ashrrev_i32_e32 v67, 11, v67
	v_add_u32_e32 v68, v67, v68
	v_mad_i32_i24 v69, v68, s84, v66
	v_cmp_lt_i32_e64 s[0:1], 15, v69
	s_and_saveexec_b64 s[2:3], s[0:1]
	s_xor_b64 s[0:1], exec, s[2:3]
	v_lshlrev_b32_e32 v66, 12, v68
	v_add3_u32 v66, v66, v69, -16
	v_ashrrev_i32_e32 v67, 31, v66
	v_lshlrev_b64 v[66:67], 12, v[66:67]
	v_lshl_add_u64 v[66:67], s[88:89], 0, v[66:67]
	s_andn2_saveexec_b64 s[0:1], s[0:1]
	v_lshlrev_b32_e32 v66, 14, v68
	v_lshl_add_u32 v66, v69, 10, v66
	v_ashrrev_i32_e32 v67, 31, v66
	v_lshl_add_u64 v[66:67], v[66:67], 2, s[16:17]
	s_or_b64 exec, exec, s[0:1]
	v_ashrrev_i32_e32 v117, 31, v116
	v_lshlrev_b64 v[68:69], 11, v[116:117]
	v_lshl_add_u64 v[68:69], s[62:63], 0, v[68:69]
	s_waitcnt vmcnt(19)
	v_add_f32_e32 v86, v88, v189
	v_lshl_add_u64 v[68:69], v[130:131], 1, v[68:69]
	v_lshl_add_u64 v[66:67], v[66:67], 0, v[134:135]
	s_and_saveexec_b64 s[0:1], vcc
	s_cbranch_execz .LBB0_3951
	global_store_dword v[66:67], v86, off
	v_mul_f32_e32 v87, v86, v242
	v_cvt_pk_bf16_f32 v87, v87, s0
	global_store_short v[68:69], v87, off
.LBB0_3951:
	s_or_b64 exec, exec, s[0:1]
	s_waitcnt vmcnt(18)
	v_add_f32_e32 v72, v72, v115
	s_and_saveexec_b64 s[0:1], vcc
	s_cbranch_execz .LBB0_3953
	global_store_dword v[66:67], v72, off offset:128
	v_mul_f32_e32 v66, v72, v243
	v_cvt_pk_bf16_f32 v66, v66, s0
	global_store_short v[68:69], v66, off offset:64
.LBB0_3953:
	s_or_b64 exec, exec, s[0:1]
	v_cmp_gt_i32_e32 vcc, s85, v114
	s_nop 1
	v_cndmask_b32_e32 v66, v181, v114, vcc
	v_mul_hi_i32 v67, v66, s83
	v_lshrrev_b32_e32 v68, 31, v67
	v_ashrrev_i32_e32 v67, 11, v67
	v_add_u32_e32 v68, v67, v68
	v_mad_i32_i24 v69, v68, s84, v66
	v_cmp_lt_i32_e64 s[0:1], 15, v69
	s_and_saveexec_b64 s[2:3], s[0:1]
	s_xor_b64 s[0:1], exec, s[2:3]
	v_lshlrev_b32_e32 v66, 12, v68
	v_add3_u32 v66, v66, v69, -16
	v_ashrrev_i32_e32 v67, 31, v66
	v_lshlrev_b64 v[66:67], 12, v[66:67]
	v_lshl_add_u64 v[66:67], s[88:89], 0, v[66:67]
	s_andn2_saveexec_b64 s[0:1], s[0:1]
	v_lshlrev_b32_e32 v66, 14, v68
	v_lshl_add_u32 v66, v69, 10, v66
	v_ashrrev_i32_e32 v67, 31, v66
	v_lshl_add_u64 v[66:67], v[66:67], 2, s[16:17]
	s_or_b64 exec, exec, s[0:1]
	v_ashrrev_i32_e32 v115, 31, v114
	v_lshlrev_b64 v[68:69], 11, v[114:115]
	v_lshl_add_u64 v[68:69], s[62:63], 0, v[68:69]
	s_waitcnt vmcnt(17)
	v_add_f32_e32 v87, v89, v188
	v_lshl_add_u64 v[68:69], v[130:131], 1, v[68:69]
	v_lshl_add_u64 v[66:67], v[66:67], 0, v[134:135]
	s_and_saveexec_b64 s[0:1], vcc
	s_cbranch_execz .LBB0_3959
	global_store_dword v[66:67], v87, off
	v_mul_f32_e32 v88, v87, v242
	v_cvt_pk_bf16_f32 v88, v88, s0
	global_store_short v[68:69], v88, off
.LBB0_3959:
	s_or_b64 exec, exec, s[0:1]
	s_waitcnt vmcnt(16)
	v_add_f32_e32 v73, v73, v113
	s_and_saveexec_b64 s[0:1], vcc
	s_cbranch_execz .LBB0_3961
	global_store_dword v[66:67], v73, off offset:128
	v_mul_f32_e32 v66, v73, v243
	v_cvt_pk_bf16_f32 v66, v66, s0
	global_store_short v[68:69], v66, off offset:64
.LBB0_3961:
	s_or_b64 exec, exec, s[0:1]
	v_cmp_gt_i32_e32 vcc, s85, v112
	s_nop 1
	v_cndmask_b32_e32 v66, v181, v112, vcc
	v_mul_hi_i32 v67, v66, s83
	v_lshrrev_b32_e32 v68, 31, v67
	v_ashrrev_i32_e32 v67, 11, v67
	v_add_u32_e32 v68, v67, v68
	v_mad_i32_i24 v69, v68, s84, v66
	v_cmp_lt_i32_e64 s[0:1], 15, v69
	s_and_saveexec_b64 s[2:3], s[0:1]
	s_xor_b64 s[0:1], exec, s[2:3]
	v_lshlrev_b32_e32 v66, 12, v68
	v_add3_u32 v66, v66, v69, -16
	v_ashrrev_i32_e32 v67, 31, v66
	v_lshlrev_b64 v[66:67], 12, v[66:67]
	v_lshl_add_u64 v[66:67], s[88:89], 0, v[66:67]
	s_andn2_saveexec_b64 s[0:1], s[0:1]
	v_lshlrev_b32_e32 v66, 14, v68
	v_lshl_add_u32 v66, v69, 10, v66
	v_ashrrev_i32_e32 v67, 31, v66
	v_lshl_add_u64 v[66:67], v[66:67], 2, s[16:17]
	s_or_b64 exec, exec, s[0:1]
	v_ashrrev_i32_e32 v113, 31, v112
	v_lshlrev_b64 v[68:69], 11, v[112:113]
	v_lshl_add_u64 v[68:69], s[62:63], 0, v[68:69]
	s_waitcnt vmcnt(15)
	v_add_f32_e32 v88, v90, v187
	v_lshl_add_u64 v[68:69], v[130:131], 1, v[68:69]
	v_lshl_add_u64 v[66:67], v[66:67], 0, v[134:135]
	s_and_saveexec_b64 s[0:1], vcc
	s_cbranch_execz .LBB0_3967
	global_store_dword v[66:67], v88, off
	v_mul_f32_e32 v89, v88, v242
	v_cvt_pk_bf16_f32 v89, v89, s0
	global_store_short v[68:69], v89, off
.LBB0_3967:
	s_or_b64 exec, exec, s[0:1]
	s_waitcnt vmcnt(14)
	v_add_f32_e32 v74, v74, v111
	s_and_saveexec_b64 s[0:1], vcc
	s_cbranch_execz .LBB0_3969
	global_store_dword v[66:67], v74, off offset:128
	v_mul_f32_e32 v66, v74, v243
	v_cvt_pk_bf16_f32 v66, v66, s0
	global_store_short v[68:69], v66, off offset:64
.LBB0_3969:
	s_or_b64 exec, exec, s[0:1]
	v_cmp_gt_i32_e32 vcc, s85, v110
	s_nop 1
	v_cndmask_b32_e32 v66, v181, v110, vcc
	v_mul_hi_i32 v67, v66, s83
	v_lshrrev_b32_e32 v68, 31, v67
	v_ashrrev_i32_e32 v67, 11, v67
	v_add_u32_e32 v68, v67, v68
	v_mad_i32_i24 v69, v68, s84, v66
	v_cmp_lt_i32_e64 s[0:1], 15, v69
	s_and_saveexec_b64 s[2:3], s[0:1]
	s_xor_b64 s[0:1], exec, s[2:3]
	v_lshlrev_b32_e32 v66, 12, v68
	v_add3_u32 v66, v66, v69, -16
	v_ashrrev_i32_e32 v67, 31, v66
	v_lshlrev_b64 v[66:67], 12, v[66:67]
	v_lshl_add_u64 v[66:67], s[88:89], 0, v[66:67]
	s_andn2_saveexec_b64 s[0:1], s[0:1]
	v_lshlrev_b32_e32 v66, 14, v68
	v_lshl_add_u32 v66, v69, 10, v66
	v_ashrrev_i32_e32 v67, 31, v66
	v_lshl_add_u64 v[66:67], v[66:67], 2, s[16:17]
	s_or_b64 exec, exec, s[0:1]
	v_ashrrev_i32_e32 v111, 31, v110
	v_lshlrev_b64 v[68:69], 11, v[110:111]
	v_lshl_add_u64 v[68:69], s[62:63], 0, v[68:69]
	s_waitcnt vmcnt(13)
	v_add_f32_e32 v89, v91, v186
	v_lshl_add_u64 v[68:69], v[130:131], 1, v[68:69]
	v_lshl_add_u64 v[66:67], v[66:67], 0, v[134:135]
	s_and_saveexec_b64 s[0:1], vcc
	s_cbranch_execz .LBB0_3975
	global_store_dword v[66:67], v89, off
	v_mul_f32_e32 v90, v89, v242
	v_cvt_pk_bf16_f32 v90, v90, s0
	global_store_short v[68:69], v90, off
.LBB0_3975:
	s_or_b64 exec, exec, s[0:1]
	s_waitcnt vmcnt(12)
	v_add_f32_e32 v75, v75, v109
	s_and_saveexec_b64 s[0:1], vcc
	s_cbranch_execz .LBB0_3977
	global_store_dword v[66:67], v75, off offset:128
	v_mul_f32_e32 v66, v75, v243
	v_cvt_pk_bf16_f32 v66, v66, s0
	global_store_short v[68:69], v66, off offset:64
.LBB0_3977:
	s_or_b64 exec, exec, s[0:1]
	v_cmp_gt_i32_e32 vcc, s85, v108
	s_nop 1
	v_cndmask_b32_e32 v66, v181, v108, vcc
	v_mul_hi_i32 v67, v66, s83
	v_lshrrev_b32_e32 v68, 31, v67
	v_ashrrev_i32_e32 v67, 11, v67
	v_add_u32_e32 v68, v67, v68
	v_mad_i32_i24 v69, v68, s84, v66
	v_cmp_lt_i32_e64 s[0:1], 15, v69
	s_and_saveexec_b64 s[2:3], s[0:1]
	s_xor_b64 s[0:1], exec, s[2:3]
	v_lshlrev_b32_e32 v66, 12, v68
	v_add3_u32 v66, v66, v69, -16
	v_ashrrev_i32_e32 v67, 31, v66
	v_lshlrev_b64 v[66:67], 12, v[66:67]
	v_lshl_add_u64 v[66:67], s[88:89], 0, v[66:67]
	s_andn2_saveexec_b64 s[0:1], s[0:1]
	v_lshlrev_b32_e32 v66, 14, v68
	v_lshl_add_u32 v66, v69, 10, v66
	v_ashrrev_i32_e32 v67, 31, v66
	v_lshl_add_u64 v[66:67], v[66:67], 2, s[16:17]
	s_or_b64 exec, exec, s[0:1]
	v_ashrrev_i32_e32 v109, 31, v108
	v_lshlrev_b64 v[68:69], 11, v[108:109]
	v_lshl_add_u64 v[68:69], s[62:63], 0, v[68:69]
	s_waitcnt vmcnt(11)
	v_add_f32_e32 v90, v92, v185
	v_lshl_add_u64 v[68:69], v[130:131], 1, v[68:69]
	v_lshl_add_u64 v[66:67], v[66:67], 0, v[134:135]
	s_and_saveexec_b64 s[0:1], vcc
	s_cbranch_execz .LBB0_3983
	global_store_dword v[66:67], v90, off
	v_mul_f32_e32 v91, v90, v242
	v_cvt_pk_bf16_f32 v91, v91, s0
	global_store_short v[68:69], v91, off
.LBB0_3983:
	s_or_b64 exec, exec, s[0:1]
	s_waitcnt vmcnt(10)
	v_add_f32_e32 v76, v76, v107
	s_and_saveexec_b64 s[0:1], vcc
	s_cbranch_execz .LBB0_3985
	global_store_dword v[66:67], v76, off offset:128
	v_mul_f32_e32 v66, v76, v243
	v_cvt_pk_bf16_f32 v66, v66, s0
	global_store_short v[68:69], v66, off offset:64
.LBB0_3985:
	s_or_b64 exec, exec, s[0:1]
	v_cmp_gt_i32_e32 vcc, s85, v106
	s_nop 1
	v_cndmask_b32_e32 v66, v181, v106, vcc
	v_mul_hi_i32 v67, v66, s83
	v_lshrrev_b32_e32 v68, 31, v67
	v_ashrrev_i32_e32 v67, 11, v67
	v_add_u32_e32 v68, v67, v68
	v_mad_i32_i24 v69, v68, s84, v66
	v_cmp_lt_i32_e64 s[0:1], 15, v69
	s_and_saveexec_b64 s[2:3], s[0:1]
	s_xor_b64 s[0:1], exec, s[2:3]
	v_lshlrev_b32_e32 v66, 12, v68
	v_add3_u32 v66, v66, v69, -16
	v_ashrrev_i32_e32 v67, 31, v66
	v_lshlrev_b64 v[66:67], 12, v[66:67]
	v_lshl_add_u64 v[66:67], s[88:89], 0, v[66:67]
	s_andn2_saveexec_b64 s[0:1], s[0:1]
	v_lshlrev_b32_e32 v66, 14, v68
	v_lshl_add_u32 v66, v69, 10, v66
	v_ashrrev_i32_e32 v67, 31, v66
	v_lshl_add_u64 v[66:67], v[66:67], 2, s[16:17]
	s_or_b64 exec, exec, s[0:1]
	v_ashrrev_i32_e32 v107, 31, v106
	v_lshlrev_b64 v[68:69], 11, v[106:107]
	v_lshl_add_u64 v[68:69], s[62:63], 0, v[68:69]
	s_waitcnt vmcnt(9)
	v_add_f32_e32 v91, v93, v184
	v_lshl_add_u64 v[68:69], v[130:131], 1, v[68:69]
	v_lshl_add_u64 v[66:67], v[66:67], 0, v[134:135]
	s_and_saveexec_b64 s[0:1], vcc
	s_cbranch_execz .LBB0_3991
	global_store_dword v[66:67], v91, off
	v_mul_f32_e32 v92, v91, v242
	v_cvt_pk_bf16_f32 v92, v92, s0
	global_store_short v[68:69], v92, off
.LBB0_3991:
	s_or_b64 exec, exec, s[0:1]
	s_waitcnt vmcnt(8)
	v_add_f32_e32 v77, v77, v105
	s_and_saveexec_b64 s[0:1], vcc
	s_cbranch_execz .LBB0_3993
	global_store_dword v[66:67], v77, off offset:128
	v_mul_f32_e32 v66, v77, v243
	v_cvt_pk_bf16_f32 v66, v66, s0
	global_store_short v[68:69], v66, off offset:64
.LBB0_3993:
	s_or_b64 exec, exec, s[0:1]
	v_cmp_gt_i32_e32 vcc, s85, v104
	s_nop 1
	v_cndmask_b32_e32 v66, v181, v104, vcc
	v_mul_hi_i32 v67, v66, s83
	v_lshrrev_b32_e32 v68, 31, v67
	v_ashrrev_i32_e32 v67, 11, v67
	v_add_u32_e32 v68, v67, v68
	v_mad_i32_i24 v69, v68, s84, v66
	v_cmp_lt_i32_e64 s[0:1], 15, v69
	s_and_saveexec_b64 s[2:3], s[0:1]
	s_xor_b64 s[0:1], exec, s[2:3]
	v_lshlrev_b32_e32 v66, 12, v68
	v_add3_u32 v66, v66, v69, -16
	v_ashrrev_i32_e32 v67, 31, v66
	v_lshlrev_b64 v[66:67], 12, v[66:67]
	v_lshl_add_u64 v[66:67], s[88:89], 0, v[66:67]
	s_andn2_saveexec_b64 s[0:1], s[0:1]
	v_lshlrev_b32_e32 v66, 14, v68
	v_lshl_add_u32 v66, v69, 10, v66
	v_ashrrev_i32_e32 v67, 31, v66
	v_lshl_add_u64 v[66:67], v[66:67], 2, s[16:17]
	s_or_b64 exec, exec, s[0:1]
	v_ashrrev_i32_e32 v105, 31, v104
	v_lshlrev_b64 v[68:69], 11, v[104:105]
	v_lshl_add_u64 v[68:69], s[62:63], 0, v[68:69]
	s_waitcnt vmcnt(7)
	v_add_f32_e32 v92, v94, v183
	v_lshl_add_u64 v[68:69], v[130:131], 1, v[68:69]
	v_lshl_add_u64 v[66:67], v[66:67], 0, v[134:135]
	s_and_saveexec_b64 s[0:1], vcc
	s_cbranch_execz .LBB0_3999
	global_store_dword v[66:67], v92, off
	v_mul_f32_e32 v93, v92, v242
	v_cvt_pk_bf16_f32 v93, v93, s0
	global_store_short v[68:69], v93, off
.LBB0_3999:
	s_or_b64 exec, exec, s[0:1]
	s_waitcnt vmcnt(6)
	v_add_f32_e32 v78, v78, v103
	s_and_saveexec_b64 s[0:1], vcc
	s_cbranch_execz .LBB0_4001
	global_store_dword v[66:67], v78, off offset:128
	v_mul_f32_e32 v66, v78, v243
	v_cvt_pk_bf16_f32 v66, v66, s0
	global_store_short v[68:69], v66, off offset:64
.LBB0_4001:
	s_or_b64 exec, exec, s[0:1]
	v_cmp_gt_i32_e32 vcc, s85, v102
	s_nop 1
	v_cndmask_b32_e32 v66, v181, v102, vcc
	v_mul_hi_i32 v67, v66, s83
	v_lshrrev_b32_e32 v68, 31, v67
	v_ashrrev_i32_e32 v67, 11, v67
	v_add_u32_e32 v68, v67, v68
	v_mad_i32_i24 v69, v68, s84, v66
	v_cmp_lt_i32_e64 s[0:1], 15, v69
	s_and_saveexec_b64 s[2:3], s[0:1]
	s_xor_b64 s[0:1], exec, s[2:3]
	v_lshlrev_b32_e32 v66, 12, v68
	v_add3_u32 v66, v66, v69, -16
	v_ashrrev_i32_e32 v67, 31, v66
	v_lshlrev_b64 v[66:67], 12, v[66:67]
	v_lshl_add_u64 v[66:67], s[88:89], 0, v[66:67]
	s_andn2_saveexec_b64 s[0:1], s[0:1]
	v_lshlrev_b32_e32 v66, 14, v68
	v_lshl_add_u32 v66, v69, 10, v66
	v_ashrrev_i32_e32 v67, 31, v66
	v_lshl_add_u64 v[66:67], v[66:67], 2, s[16:17]
	s_or_b64 exec, exec, s[0:1]
	v_ashrrev_i32_e32 v103, 31, v102
	v_lshlrev_b64 v[68:69], 11, v[102:103]
	v_lshl_add_u64 v[68:69], s[62:63], 0, v[68:69]
	s_waitcnt vmcnt(5)
	v_add_f32_e32 v93, v95, v182
	v_lshl_add_u64 v[68:69], v[130:131], 1, v[68:69]
	v_lshl_add_u64 v[66:67], v[66:67], 0, v[134:135]
	s_and_saveexec_b64 s[0:1], vcc
	s_cbranch_execz .LBB0_4007
	global_store_dword v[66:67], v93, off
	v_mul_f32_e32 v94, v93, v242
	v_cvt_pk_bf16_f32 v94, v94, s0
	global_store_short v[68:69], v94, off
.LBB0_4007:
	s_or_b64 exec, exec, s[0:1]
	s_waitcnt vmcnt(4)
	v_add_f32_e32 v79, v79, v101
	s_and_saveexec_b64 s[0:1], vcc
	s_cbranch_execz .LBB0_4009
	global_store_dword v[66:67], v79, off offset:128
	v_mul_f32_e32 v66, v79, v243
	v_cvt_pk_bf16_f32 v66, v66, s0
	global_store_short v[68:69], v66, off offset:64
.LBB0_4009:
	s_or_b64 exec, exec, s[0:1]
	v_cmp_gt_i32_e32 vcc, s85, v100
	s_nop 1
	v_cndmask_b32_e32 v66, v181, v100, vcc
	v_mul_hi_i32 v67, v66, s83
	v_lshrrev_b32_e32 v68, 31, v67
	v_ashrrev_i32_e32 v67, 11, v67
	v_add_u32_e32 v68, v67, v68
	v_mad_i32_i24 v69, v68, s84, v66
	v_cmp_lt_i32_e64 s[0:1], 15, v69
	s_and_saveexec_b64 s[2:3], s[0:1]
	s_xor_b64 s[0:1], exec, s[2:3]
	v_lshlrev_b32_e32 v66, 12, v68
	v_add3_u32 v66, v66, v69, -16
	v_ashrrev_i32_e32 v67, 31, v66
	v_lshlrev_b64 v[66:67], 12, v[66:67]
	v_lshl_add_u64 v[66:67], s[88:89], 0, v[66:67]
	s_andn2_saveexec_b64 s[0:1], s[0:1]
	v_lshlrev_b32_e32 v66, 14, v68
	v_lshl_add_u32 v66, v69, 10, v66
	v_ashrrev_i32_e32 v67, 31, v66
	v_lshl_add_u64 v[66:67], v[66:67], 2, s[16:17]
	s_or_b64 exec, exec, s[0:1]
	v_ashrrev_i32_e32 v101, 31, v100
	v_lshlrev_b64 v[68:69], 11, v[100:101]
	v_lshl_add_u64 v[68:69], s[62:63], 0, v[68:69]
	s_waitcnt vmcnt(3)
	v_add_f32_e32 v94, v96, v179
	v_lshl_add_u64 v[68:69], v[130:131], 1, v[68:69]
	v_lshl_add_u64 v[66:67], v[66:67], 0, v[134:135]
	s_and_saveexec_b64 s[0:1], vcc
	s_cbranch_execz .LBB0_4015
	global_store_dword v[66:67], v94, off
	v_mul_f32_e32 v95, v94, v242
	v_cvt_pk_bf16_f32 v95, v95, s0
	global_store_short v[68:69], v95, off
.LBB0_4015:
	s_or_b64 exec, exec, s[0:1]
	s_waitcnt vmcnt(2)
	v_add_f32_e32 v95, v80, v99
	s_and_saveexec_b64 s[0:1], vcc
	s_cbranch_execz .LBB0_4017
	global_store_dword v[66:67], v95, off offset:128
	v_mul_f32_e32 v66, v95, v243
	v_cvt_pk_bf16_f32 v66, v66, s0
	global_store_short v[68:69], v66, off offset:64
.LBB0_4017:
	s_or_b64 exec, exec, s[0:1]
	v_cmp_gt_i32_e32 vcc, s85, v98
	s_nop 1
	v_cndmask_b32_e32 v66, v181, v98, vcc
	v_mul_hi_i32 v67, v66, s83
	v_lshrrev_b32_e32 v68, 31, v67
	v_ashrrev_i32_e32 v67, 11, v67
	v_add_u32_e32 v68, v67, v68
	v_mad_i32_i24 v69, v68, s84, v66
	v_cmp_lt_i32_e64 s[0:1], 15, v69
	s_and_saveexec_b64 s[2:3], s[0:1]
	s_xor_b64 s[0:1], exec, s[2:3]
	v_lshlrev_b32_e32 v66, 12, v68
	v_add3_u32 v66, v66, v69, -16
	v_ashrrev_i32_e32 v67, 31, v66
	v_lshlrev_b64 v[66:67], 12, v[66:67]
	v_lshl_add_u64 v[66:67], s[88:89], 0, v[66:67]
	s_andn2_saveexec_b64 s[0:1], s[0:1]
	v_lshlrev_b32_e32 v66, 14, v68
	v_lshl_add_u32 v66, v69, 10, v66
	v_ashrrev_i32_e32 v67, 31, v66
	v_lshl_add_u64 v[66:67], v[66:67], 2, s[16:17]
	s_or_b64 exec, exec, s[0:1]
	v_ashrrev_i32_e32 v99, 31, v98
	v_lshlrev_b64 v[68:69], 11, v[98:99]
	v_lshl_add_u64 v[68:69], s[62:63], 0, v[68:69]
	s_waitcnt vmcnt(1)
	v_add_f32_e32 v80, v97, v177
	v_lshl_add_u64 v[68:69], v[130:131], 1, v[68:69]
	v_lshl_add_u64 v[66:67], v[66:67], 0, v[134:135]
	s_and_saveexec_b64 s[0:1], vcc
	s_cbranch_execz .LBB0_4023
	global_store_dword v[66:67], v80, off
	v_mul_f32_e32 v96, v80, v242
	v_cvt_pk_bf16_f32 v96, v96, s0
	global_store_short v[68:69], v96, off
.LBB0_4023:
	s_or_b64 exec, exec, s[0:1]
	s_waitcnt vmcnt(0)
	v_add_f32_e32 v81, v81, v171
	s_and_saveexec_b64 s[0:1], vcc
	s_cbranch_execz .LBB0_4025
	global_store_dword v[66:67], v81, off offset:128
	v_mul_f32_e32 v66, v81, v243
	v_cvt_pk_bf16_f32 v66, v66, s0
	global_store_short v[68:69], v66, off offset:64
.LBB0_4025:
	s_or_b64 exec, exec, s[0:1]
	v_lshlrev_b32_e32 v66, 1, v175
	v_lshlrev_b32_e32 v104, 1, v172
	v_and_b32_e32 v66, 32, v66
	v_and_b32_e32 v104, 24, v104
	v_and_b32_e32 v105, 3, v172
	v_or3_b32 v66, v105, v104, v66
	v_and_b32_e32 v105, 64, v200
	v_mul_f32_e32 v71, v71, v71
	v_mul_f32_e32 v70, v70, v70
	v_xor_b32_e32 v104, 16, v200
	v_add_u32_e32 v109, 64, v105
	v_fmac_f32_e32 v71, v83, v83
	v_fmac_f32_e32 v70, v82, v82
	v_mul_f32_e32 v82, v128, v128
	v_mul_f32_e32 v83, v178, v178
	v_mul_f32_e32 v98, v168, v168
	v_mul_f32_e32 v99, v176, v176
	v_and_b32_e32 v100, 16, v172
	v_cmp_lt_i32_e32 vcc, v104, v109
	v_fmac_f32_e32 v82, v138, v138
	v_fmac_f32_e32 v83, v169, v169
	v_fmac_f32_e32 v98, v170, v170
	v_fmac_f32_e32 v99, v137, v137
	v_cndmask_b32_e32 v104, v200, v104, vcc
	v_cmp_eq_u32_e32 vcc, 0, v100
	v_mul_f32_e32 v81, v81, v81
	v_lshlrev_b32_e32 v104, 2, v104
	v_cndmask_b32_e32 v100, v99, v83, vcc
	v_fmac_f32_e32 v81, v80, v80
	v_cndmask_b32_e32 v80, v83, v99, vcc
	v_cndmask_b32_e32 v83, v98, v82, vcc
	ds_bpermute_b32 v83, v104, v83
	v_mul_f32_e32 v67, v95, v95
	v_mul_f32_e32 v95, v161, v161
	v_fmac_f32_e32 v95, v160, v160
	v_cndmask_b32_e32 v82, v82, v98, vcc
	s_waitcnt lgkmcnt(0)
	v_add_f32_e32 v82, v82, v83
	v_cndmask_b32_e32 v83, v95, v70, vcc
	ds_bpermute_b32 v83, v104, v83
	v_mul_f32_e32 v69, v78, v78
	v_fmac_f32_e32 v69, v92, v92
	v_mul_f32_e32 v73, v73, v73
	v_mul_f32_e32 v92, v155, v155
	v_fmac_f32_e32 v73, v87, v87
	v_fmac_f32_e32 v92, v154, v154
	v_cndmask_b32_e32 v70, v70, v95, vcc
	s_waitcnt lgkmcnt(0)
	v_add_f32_e32 v70, v70, v83
	v_cndmask_b32_e32 v83, v92, v73, vcc
	ds_bpermute_b32 v83, v104, v83
	v_mul_f32_e32 v75, v75, v75
	v_mul_f32_e32 v76, v76, v76
	v_fmac_f32_e32 v75, v89, v89
	v_mul_f32_e32 v89, v149, v149
	v_fmac_f32_e32 v76, v90, v90
	v_fmac_f32_e32 v89, v148, v148
	v_cndmask_b32_e32 v73, v73, v92, vcc
	s_waitcnt lgkmcnt(0)
	v_add_f32_e32 v73, v73, v83
	v_cndmask_b32_e32 v83, v89, v76, vcc
	ds_bpermute_b32 v83, v104, v83
	v_mul_f32_e32 v72, v72, v72
	v_mul_f32_e32 v68, v79, v79
	v_fmac_f32_e32 v72, v86, v86
	v_mul_f32_e32 v86, v143, v143
	v_fmac_f32_e32 v68, v93, v93
	v_mul_f32_e32 v77, v77, v77
	v_fmac_f32_e32 v86, v142, v142
	v_cndmask_b32_e32 v76, v76, v89, vcc
	v_fmac_f32_e32 v77, v91, v91
	v_mul_f32_e32 v74, v74, v74
	v_mul_f32_e32 v91, v153, v153
	s_waitcnt lgkmcnt(0)
	v_add_f32_e32 v76, v76, v83
	v_cndmask_b32_e32 v83, v86, v68, vcc
	v_fmac_f32_e32 v74, v88, v88
	v_mul_f32_e32 v78, v122, v122
	v_mul_f32_e32 v79, v124, v124
	v_mul_f32_e32 v88, v147, v147
	v_fmac_f32_e32 v91, v152, v152
	v_mul_f32_e32 v96, v163, v163
	v_mul_f32_e32 v97, v165, v165
	ds_bpermute_b32 v83, v104, v83
	v_fmac_f32_e32 v78, v85, v85
	v_fmac_f32_e32 v79, v84, v84
	v_mul_f32_e32 v87, v145, v145
	v_fmac_f32_e32 v88, v146, v146
	v_mul_f32_e32 v90, v151, v151
	v_mul_f32_e32 v93, v157, v157
	v_fmac_f32_e32 v96, v162, v162
	v_fmac_f32_e32 v97, v164, v164
	v_cndmask_b32_e32 v92, v91, v74, vcc
	v_fmac_f32_e32 v87, v144, v144
	v_fmac_f32_e32 v90, v150, v150
	v_fmac_f32_e32 v93, v156, v156
	ds_bpermute_b32 v100, v104, v100
	v_cndmask_b32_e32 v98, v97, v79, vcc
	v_cndmask_b32_e32 v99, v96, v78, vcc
	ds_bpermute_b32 v92, v104, v92
	v_cndmask_b32_e32 v89, v88, v77, vcc
	ds_bpermute_b32 v98, v104, v98
	ds_bpermute_b32 v99, v104, v99
	v_cndmask_b32_e32 v78, v78, v96, vcc
	v_cndmask_b32_e32 v96, v93, v72, vcc
	v_cndmask_b32_e32 v72, v72, v93, vcc
	v_cndmask_b32_e32 v93, v90, v75, vcc
	v_cndmask_b32_e32 v75, v75, v90, vcc
	ds_bpermute_b32 v89, v104, v89
	v_cndmask_b32_e32 v90, v87, v69, vcc
	s_lshl_b32 s0, s4, 2
	ds_bpermute_b32 v90, v104, v90
	v_cndmask_b32_e32 v68, v68, v86, vcc
	v_fmac_f32_e32 v67, v94, v94
	v_mul_f32_e32 v85, v141, v141
	v_mul_f32_e32 v94, v159, v159
	s_ashr_i32 s1, s0, 31
	s_waitcnt lgkmcnt(6)
	v_add_f32_e32 v68, v68, v83
	v_xor_b32_e32 v83, 8, v200
	v_mul_f32_e32 v84, v167, v167
	v_fmac_f32_e32 v85, v140, v140
	v_fmac_f32_e32 v94, v158, v158
	v_and_b32_e32 v101, 8, v172
	s_lshl_b64 s[8:9], s[0:1], 2
	v_cndmask_b32_e32 v74, v74, v91, vcc
	v_cmp_lt_i32_e64 s[0:1], v83, v109
	v_fmac_f32_e32 v84, v166, v166
	s_waitcnt lgkmcnt(5)
	v_add_f32_e32 v80, v80, v100
	v_cndmask_b32_e32 v79, v79, v97, vcc
	v_cndmask_b32_e32 v95, v94, v71, vcc
	s_waitcnt lgkmcnt(4)
	v_add_f32_e32 v74, v74, v92
	v_cndmask_b32_e32 v77, v77, v88, vcc
	v_cndmask_b32_e32 v86, v85, v67, vcc
	v_cndmask_b32_e64 v83, v200, v83, s[0:1]
	v_cmp_eq_u32_e64 s[2:3], 0, v101
	s_waitcnt lgkmcnt(3)
	v_add_f32_e32 v79, v79, v98
	s_waitcnt lgkmcnt(2)
	v_add_f32_e32 v78, v78, v99
	ds_bpermute_b32 v95, v104, v95
	ds_bpermute_b32 v96, v104, v96
	ds_bpermute_b32 v93, v104, v93
	s_waitcnt lgkmcnt(4)
	v_add_f32_e32 v77, v77, v89
	v_cndmask_b32_e32 v69, v69, v87, vcc
	ds_bpermute_b32 v86, v104, v86
	v_cndmask_b32_e32 v87, v84, v81, vcc
	v_lshlrev_b32_e32 v105, 2, v83
	v_cndmask_b32_e64 v83, v80, v74, s[2:3]
	s_waitcnt lgkmcnt(4)
	v_add_f32_e32 v69, v69, v90
	ds_bpermute_b32 v87, v104, v87
	v_cndmask_b32_e32 v81, v81, v84, vcc
	v_cndmask_b32_e64 v74, v74, v80, s[2:3]
	ds_bpermute_b32 v80, v105, v83
	v_cndmask_b32_e64 v84, v79, v76, s[2:3]
	v_cndmask_b32_e64 v76, v76, v79, s[2:3]
	v_cndmask_b32_e64 v79, v78, v77, s[2:3]
	v_cndmask_b32_e64 v77, v77, v78, s[2:3]
	ds_bpermute_b32 v78, v105, v79
	v_cndmask_b32_e64 v79, v70, v69, s[2:3]
	ds_bpermute_b32 v79, v105, v79
	v_cndmask_b32_e32 v71, v71, v94, vcc
	v_cndmask_b32_e32 v67, v67, v85, vcc
	s_waitcnt lgkmcnt(7)
	v_add_f32_e32 v71, v71, v95
	s_waitcnt lgkmcnt(6)
	v_add_f32_e32 v72, v72, v96
	s_waitcnt lgkmcnt(5)
	v_add_f32_e32 v75, v75, v93
	s_waitcnt lgkmcnt(4)
	v_add_f32_e32 v67, v67, v86
	s_waitcnt lgkmcnt(3)
	v_add_f32_e32 v81, v81, v87
	v_cndmask_b32_e64 v83, v82, v75, s[2:3]
	s_waitcnt lgkmcnt(2)
	v_add_f32_e32 v74, v74, v80
	v_cndmask_b32_e64 v80, v71, v68, s[2:3]
	v_cndmask_b32_e64 v69, v69, v70, s[2:3]
	v_cndmask_b32_e64 v70, v72, v67, s[2:3]
	v_cndmask_b32_e64 v67, v67, v72, s[2:3]
	v_xor_b32_e32 v72, 4, v200
	v_and_b32_e32 v102, 4, v172
	ds_bpermute_b32 v83, v105, v83
	ds_bpermute_b32 v80, v105, v80
	v_cndmask_b32_e64 v68, v68, v71, s[2:3]
	ds_bpermute_b32 v70, v105, v70
	v_cndmask_b32_e64 v71, v73, v81, s[2:3]
	v_cmp_lt_i32_e64 s[0:1], v72, v109
	s_waitcnt lgkmcnt(3)
	v_add_f32_e32 v69, v69, v79
	ds_bpermute_b32 v71, v105, v71
	v_cndmask_b32_e64 v72, v200, v72, s[0:1]
	v_cmp_eq_u32_e64 s[4:5], 0, v102
	ds_bpermute_b32 v84, v105, v84
	v_lshlrev_b32_e32 v106, 2, v72
	v_cndmask_b32_e64 v72, v74, v69, s[4:5]
	ds_bpermute_b32 v72, v106, v72
	v_cndmask_b32_e64 v75, v75, v82, s[2:3]
	s_waitcnt lgkmcnt(5)
	v_add_f32_e32 v75, v75, v83
	s_waitcnt lgkmcnt(4)
	v_add_f32_e32 v68, v68, v80
	s_waitcnt lgkmcnt(3)
	v_add_f32_e32 v67, v67, v70
	v_cndmask_b32_e64 v70, v81, v73, s[2:3]
	s_waitcnt lgkmcnt(2)
	v_add_f32_e32 v70, v70, v71
	v_cndmask_b32_e64 v71, v75, v68, s[4:5]
	s_waitcnt lgkmcnt(1)
	v_add_f32_e32 v76, v76, v84
	v_add_f32_e32 v77, v77, v78
	v_cndmask_b32_e64 v69, v69, v74, s[4:5]
	ds_bpermute_b32 v71, v106, v71
	s_waitcnt lgkmcnt(1)
	v_add_f32_e32 v69, v69, v72
	v_cndmask_b32_e64 v72, v76, v67, s[4:5]
	v_cndmask_b32_e64 v73, v77, v70, s[4:5]
	ds_bpermute_b32 v72, v106, v72
	ds_bpermute_b32 v73, v106, v73
	v_cndmask_b32_e64 v68, v68, v75, s[4:5]
	s_waitcnt lgkmcnt(2)
	v_add_f32_e32 v68, v68, v71
	v_xor_b32_e32 v71, 2, v200
	v_and_b32_e32 v103, 2, v172
	v_cndmask_b32_e64 v67, v67, v76, s[4:5]
	v_cndmask_b32_e64 v70, v70, v77, s[4:5]
	v_cmp_lt_i32_e64 s[0:1], v71, v109
	s_waitcnt lgkmcnt(1)
	v_add_f32_e32 v67, v67, v72
	s_waitcnt lgkmcnt(0)
	v_add_f32_e32 v70, v70, v73
	v_cndmask_b32_e64 v71, v200, v71, s[0:1]
	v_cmp_eq_u32_e64 s[6:7], 0, v103
	v_lshlrev_b32_e32 v107, 2, v71
	v_and_b32_e32 v108, 1, v172
	v_cndmask_b32_e64 v71, v69, v67, s[6:7]
	v_cndmask_b32_e64 v72, v68, v70, s[6:7]
	ds_bpermute_b32 v71, v107, v71
	ds_bpermute_b32 v72, v107, v72
	v_cndmask_b32_e64 v67, v67, v69, s[6:7]
	v_xor_b32_e32 v69, 1, v200
	s_add_u32 s10, s12, s8
	v_cndmask_b32_e64 v68, v70, v68, s[6:7]
	v_cmp_lt_i32_e64 s[0:1], v69, v109
	s_addc_u32 s11, s13, s9
	s_waitcnt lgkmcnt(1)
	v_add_f32_e32 v67, v67, v71
	s_waitcnt lgkmcnt(0)
	v_add_f32_e32 v70, v68, v72
	v_cmp_eq_u32_e64 s[8:9], 0, v108
	v_cndmask_b32_e64 v69, v200, v69, s[0:1]
	v_lshlrev_b32_e32 v108, 2, v69
	v_cndmask_b32_e64 v68, v67, v70, s[8:9]
	ds_bpermute_b32 v71, v108, v68
	v_or3_b32 v66, v66, v173, v174
	v_lshlrev_b32_e32 v0, 2, v0
	v_lshl_add_u64 v[68:69], s[10:11], 0, v[0:1]
	v_cndmask_b32_e64 v0, v70, v67, s[8:9]
	v_ashrrev_i32_e32 v67, 31, v66
	s_waitcnt lgkmcnt(0)
	v_add_f32_e32 v0, v0, v71
	v_lshlrev_b64 v[70:71], 6, v[66:67]
	v_or_b32_e32 v100, 64, v136
	v_lshl_add_u64 v[70:71], v[68:69], 0, v[70:71]
	v_min_i32_e32 v67, 0x403f, v100
	global_store_dword v[70:71], v0, off
	v_mul_hi_i32 v0, v67, s83
	v_lshrrev_b32_e32 v70, 31, v0
	v_ashrrev_i32_e32 v0, 11, v0
	v_add_u32_e32 v0, v0, v70
	v_mad_i32_i24 v67, v0, s84, v67
	v_cmp_lt_i32_e64 s[0:1], 15, v67
	s_and_saveexec_b64 s[10:11], s[0:1]
	s_xor_b64 s[0:1], exec, s[10:11]
	v_lshlrev_b32_e32 v0, 12, v0
	v_add3_u32 v70, v0, v67, -16
	v_ashrrev_i32_e32 v71, 31, v70
	v_lshlrev_b64 v[70:71], 12, v[70:71]
	v_lshl_add_u64 v[70:71], s[88:89], 0, v[70:71]
	s_andn2_saveexec_b64 s[0:1], s[0:1]
	v_lshlrev_b32_e32 v0, 14, v0
	v_lshl_add_u32 v70, v67, 10, v0
	v_ashrrev_i32_e32 v71, 31, v70
	v_lshl_add_u64 v[70:71], v[70:71], 2, s[16:17]
	s_or_b64 exec, exec, s[0:1]
	v_lshl_add_u64 v[70:71], v[130:131], 2, v[70:71]
	global_load_dword v0, v[70:71], off
	global_load_dword v67, v[70:71], off offset:128
	v_or_b32_e32 v98, 0x41, v136
	v_min_i32_e32 v70, 0x403f, v98
	v_mul_hi_i32 v71, v70, s83
	v_lshrrev_b32_e32 v72, 31, v71
	v_ashrrev_i32_e32 v71, 11, v71
	v_add_u32_e32 v72, v71, v72
	v_mad_i32_i24 v73, v72, s84, v70
	v_cmp_lt_i32_e64 s[0:1], 15, v73
	s_and_saveexec_b64 s[10:11], s[0:1]
	s_xor_b64 s[0:1], exec, s[10:11]
	v_lshlrev_b32_e32 v70, 12, v72
	v_add3_u32 v70, v70, v73, -16
	v_ashrrev_i32_e32 v71, 31, v70
	v_lshlrev_b64 v[70:71], 12, v[70:71]
	v_lshl_add_u64 v[70:71], s[88:89], 0, v[70:71]
	s_andn2_saveexec_b64 s[0:1], s[0:1]
	v_lshlrev_b32_e32 v70, 14, v72
	v_lshl_add_u32 v70, v73, 10, v70
	v_ashrrev_i32_e32 v71, 31, v70
	v_lshl_add_u64 v[70:71], v[70:71], 2, s[16:17]
	s_or_b64 exec, exec, s[0:1]
	v_lshl_add_u64 v[70:71], v[130:131], 2, v[70:71]
	global_load_dword v124, v[70:71], off
	global_load_dword v97, v[70:71], off offset:128
	v_or_b32_e32 v96, 0x42, v136
	v_min_i32_e32 v70, 0x403f, v96
	v_mul_hi_i32 v71, v70, s83
	v_lshrrev_b32_e32 v72, 31, v71
	v_ashrrev_i32_e32 v71, 11, v71
	v_add_u32_e32 v72, v71, v72
	v_mad_i32_i24 v73, v72, s84, v70
	v_cmp_lt_i32_e64 s[0:1], 15, v73
	s_and_saveexec_b64 s[10:11], s[0:1]
	s_xor_b64 s[0:1], exec, s[10:11]
	v_lshlrev_b32_e32 v70, 12, v72
	v_add3_u32 v70, v70, v73, -16
	v_ashrrev_i32_e32 v71, 31, v70
	v_lshlrev_b64 v[70:71], 12, v[70:71]
	v_lshl_add_u64 v[70:71], s[88:89], 0, v[70:71]
	s_andn2_saveexec_b64 s[0:1], s[0:1]
	v_lshlrev_b32_e32 v70, 14, v72
	v_lshl_add_u32 v70, v73, 10, v70
	v_ashrrev_i32_e32 v71, 31, v70
	v_lshl_add_u64 v[70:71], v[70:71], 2, s[16:17]
	s_or_b64 exec, exec, s[0:1]
	v_lshl_add_u64 v[70:71], v[130:131], 2, v[70:71]
	global_load_dword v123, v[70:71], off
	global_load_dword v95, v[70:71], off offset:128
	v_or_b32_e32 v94, 0x43, v136
	v_min_i32_e32 v70, 0x403f, v94
	v_mul_hi_i32 v71, v70, s83
	v_lshrrev_b32_e32 v72, 31, v71
	v_ashrrev_i32_e32 v71, 11, v71
	v_add_u32_e32 v72, v71, v72
	v_mad_i32_i24 v73, v72, s84, v70
	v_cmp_lt_i32_e64 s[0:1], 15, v73
	s_and_saveexec_b64 s[10:11], s[0:1]
	s_xor_b64 s[0:1], exec, s[10:11]
	v_lshlrev_b32_e32 v70, 12, v72
	v_add3_u32 v70, v70, v73, -16
	v_ashrrev_i32_e32 v71, 31, v70
	v_lshlrev_b64 v[70:71], 12, v[70:71]
	v_lshl_add_u64 v[70:71], s[88:89], 0, v[70:71]
	s_andn2_saveexec_b64 s[0:1], s[0:1]
	v_lshlrev_b32_e32 v70, 14, v72
	v_lshl_add_u32 v70, v73, 10, v70
	v_ashrrev_i32_e32 v71, 31, v70
	v_lshl_add_u64 v[70:71], v[70:71], 2, s[16:17]
	s_or_b64 exec, exec, s[0:1]
	v_lshl_add_u64 v[70:71], v[130:131], 2, v[70:71]
	global_load_dword v122, v[70:71], off
	global_load_dword v93, v[70:71], off offset:128
	v_or_b32_e32 v92, 0x48, v136
	v_min_i32_e32 v70, 0x403f, v92
	v_mul_hi_i32 v71, v70, s83
	v_lshrrev_b32_e32 v72, 31, v71
	v_ashrrev_i32_e32 v71, 11, v71
	v_add_u32_e32 v72, v71, v72
	v_mad_i32_i24 v73, v72, s84, v70
	v_cmp_lt_i32_e64 s[0:1], 15, v73
	s_and_saveexec_b64 s[10:11], s[0:1]
	s_xor_b64 s[0:1], exec, s[10:11]
	v_lshlrev_b32_e32 v70, 12, v72
	v_add3_u32 v70, v70, v73, -16
	v_ashrrev_i32_e32 v71, 31, v70
	v_lshlrev_b64 v[70:71], 12, v[70:71]
	v_lshl_add_u64 v[70:71], s[88:89], 0, v[70:71]
	s_andn2_saveexec_b64 s[0:1], s[0:1]
	v_lshlrev_b32_e32 v70, 14, v72
	v_lshl_add_u32 v70, v73, 10, v70
	v_ashrrev_i32_e32 v71, 31, v70
	v_lshl_add_u64 v[70:71], v[70:71], 2, s[16:17]
	s_or_b64 exec, exec, s[0:1]
	v_lshl_add_u64 v[70:71], v[130:131], 2, v[70:71]
	global_load_dword v121, v[70:71], off
	global_load_dword v91, v[70:71], off offset:128
	v_or_b32_e32 v90, 0x49, v136
	v_min_i32_e32 v70, 0x403f, v90
	v_mul_hi_i32 v71, v70, s83
	v_lshrrev_b32_e32 v72, 31, v71
	v_ashrrev_i32_e32 v71, 11, v71
	v_add_u32_e32 v72, v71, v72
	v_mad_i32_i24 v73, v72, s84, v70
	v_cmp_lt_i32_e64 s[0:1], 15, v73
	s_and_saveexec_b64 s[10:11], s[0:1]
	s_xor_b64 s[0:1], exec, s[10:11]
	v_lshlrev_b32_e32 v70, 12, v72
	v_add3_u32 v70, v70, v73, -16
	v_ashrrev_i32_e32 v71, 31, v70
	v_lshlrev_b64 v[70:71], 12, v[70:71]
	v_lshl_add_u64 v[70:71], s[88:89], 0, v[70:71]
	s_andn2_saveexec_b64 s[0:1], s[0:1]
	v_lshlrev_b32_e32 v70, 14, v72
	v_lshl_add_u32 v70, v73, 10, v70
	v_ashrrev_i32_e32 v71, 31, v70
	v_lshl_add_u64 v[70:71], v[70:71], 2, s[16:17]
	s_or_b64 exec, exec, s[0:1]
	v_lshl_add_u64 v[70:71], v[130:131], 2, v[70:71]
	global_load_dword v120, v[70:71], off
	global_load_dword v89, v[70:71], off offset:128
	v_or_b32_e32 v88, 0x4a, v136
	v_min_i32_e32 v70, 0x403f, v88
	v_mul_hi_i32 v71, v70, s83
	v_lshrrev_b32_e32 v72, 31, v71
	v_ashrrev_i32_e32 v71, 11, v71
	v_add_u32_e32 v72, v71, v72
	v_mad_i32_i24 v73, v72, s84, v70
	v_cmp_lt_i32_e64 s[0:1], 15, v73
	s_and_saveexec_b64 s[10:11], s[0:1]
	s_xor_b64 s[0:1], exec, s[10:11]
	v_lshlrev_b32_e32 v70, 12, v72
	v_add3_u32 v70, v70, v73, -16
	v_ashrrev_i32_e32 v71, 31, v70
	v_lshlrev_b64 v[70:71], 12, v[70:71]
	v_lshl_add_u64 v[70:71], s[88:89], 0, v[70:71]
	s_andn2_saveexec_b64 s[0:1], s[0:1]
	v_lshlrev_b32_e32 v70, 14, v72
	v_lshl_add_u32 v70, v73, 10, v70
	v_ashrrev_i32_e32 v71, 31, v70
	v_lshl_add_u64 v[70:71], v[70:71], 2, s[16:17]
	s_or_b64 exec, exec, s[0:1]
	v_lshl_add_u64 v[70:71], v[130:131], 2, v[70:71]
	global_load_dword v119, v[70:71], off
	global_load_dword v87, v[70:71], off offset:128
	v_or_b32_e32 v86, 0x4b, v136
	v_min_i32_e32 v70, 0x403f, v86
	v_mul_hi_i32 v71, v70, s83
	v_lshrrev_b32_e32 v72, 31, v71
	v_ashrrev_i32_e32 v71, 11, v71
	v_add_u32_e32 v72, v71, v72
	v_mad_i32_i24 v73, v72, s84, v70
	v_cmp_lt_i32_e64 s[0:1], 15, v73
	s_and_saveexec_b64 s[10:11], s[0:1]
	s_xor_b64 s[0:1], exec, s[10:11]
	v_lshlrev_b32_e32 v70, 12, v72
	v_add3_u32 v70, v70, v73, -16
	v_ashrrev_i32_e32 v71, 31, v70
	v_lshlrev_b64 v[70:71], 12, v[70:71]
	v_lshl_add_u64 v[70:71], s[88:89], 0, v[70:71]
	s_andn2_saveexec_b64 s[0:1], s[0:1]
	v_lshlrev_b32_e32 v70, 14, v72
	v_lshl_add_u32 v70, v73, 10, v70
	v_ashrrev_i32_e32 v71, 31, v70
	v_lshl_add_u64 v[70:71], v[70:71], 2, s[16:17]
	s_or_b64 exec, exec, s[0:1]
	v_lshl_add_u64 v[70:71], v[130:131], 2, v[70:71]
	global_load_dword v118, v[70:71], off
	global_load_dword v85, v[70:71], off offset:128
	v_or_b32_e32 v84, 0x50, v136
	v_min_i32_e32 v70, 0x403f, v84
	v_mul_hi_i32 v71, v70, s83
	v_lshrrev_b32_e32 v72, 31, v71
	v_ashrrev_i32_e32 v71, 11, v71
	v_add_u32_e32 v72, v71, v72
	v_mad_i32_i24 v73, v72, s84, v70
	v_cmp_lt_i32_e64 s[0:1], 15, v73
	s_and_saveexec_b64 s[10:11], s[0:1]
	s_xor_b64 s[0:1], exec, s[10:11]
	v_lshlrev_b32_e32 v70, 12, v72
	v_add3_u32 v70, v70, v73, -16
	v_ashrrev_i32_e32 v71, 31, v70
	v_lshlrev_b64 v[70:71], 12, v[70:71]
	v_lshl_add_u64 v[70:71], s[88:89], 0, v[70:71]
	s_andn2_saveexec_b64 s[0:1], s[0:1]
	v_lshlrev_b32_e32 v70, 14, v72
	v_lshl_add_u32 v70, v73, 10, v70
	v_ashrrev_i32_e32 v71, 31, v70
	v_lshl_add_u64 v[70:71], v[70:71], 2, s[16:17]
	s_or_b64 exec, exec, s[0:1]
	v_lshl_add_u64 v[70:71], v[130:131], 2, v[70:71]
	global_load_dword v117, v[70:71], off
	global_load_dword v83, v[70:71], off offset:128
	v_or_b32_e32 v82, 0x51, v136
	v_min_i32_e32 v70, 0x403f, v82
	v_mul_hi_i32 v71, v70, s83
	v_lshrrev_b32_e32 v72, 31, v71
	v_ashrrev_i32_e32 v71, 11, v71
	v_add_u32_e32 v72, v71, v72
	v_mad_i32_i24 v73, v72, s84, v70
	v_cmp_lt_i32_e64 s[0:1], 15, v73
	s_and_saveexec_b64 s[10:11], s[0:1]
	s_xor_b64 s[0:1], exec, s[10:11]
	v_lshlrev_b32_e32 v70, 12, v72
	v_add3_u32 v70, v70, v73, -16
	v_ashrrev_i32_e32 v71, 31, v70
	v_lshlrev_b64 v[70:71], 12, v[70:71]
	v_lshl_add_u64 v[70:71], s[88:89], 0, v[70:71]
	s_andn2_saveexec_b64 s[0:1], s[0:1]
	v_lshlrev_b32_e32 v70, 14, v72
	v_lshl_add_u32 v70, v73, 10, v70
	v_ashrrev_i32_e32 v71, 31, v70
	v_lshl_add_u64 v[70:71], v[70:71], 2, s[16:17]
	s_or_b64 exec, exec, s[0:1]
	v_lshl_add_u64 v[70:71], v[130:131], 2, v[70:71]
	global_load_dword v116, v[70:71], off
	global_load_dword v81, v[70:71], off offset:128
	v_or_b32_e32 v80, 0x52, v136
	v_min_i32_e32 v70, 0x403f, v80
	v_mul_hi_i32 v71, v70, s83
	v_lshrrev_b32_e32 v72, 31, v71
	v_ashrrev_i32_e32 v71, 11, v71
	v_add_u32_e32 v72, v71, v72
	v_mad_i32_i24 v73, v72, s84, v70
	v_cmp_lt_i32_e64 s[0:1], 15, v73
	s_and_saveexec_b64 s[10:11], s[0:1]
	s_xor_b64 s[0:1], exec, s[10:11]
	v_lshlrev_b32_e32 v70, 12, v72
	v_add3_u32 v70, v70, v73, -16
	v_ashrrev_i32_e32 v71, 31, v70
	v_lshlrev_b64 v[70:71], 12, v[70:71]
	v_lshl_add_u64 v[70:71], s[88:89], 0, v[70:71]
	s_andn2_saveexec_b64 s[0:1], s[0:1]
	v_lshlrev_b32_e32 v70, 14, v72
	v_lshl_add_u32 v70, v73, 10, v70
	v_ashrrev_i32_e32 v71, 31, v70
	v_lshl_add_u64 v[70:71], v[70:71], 2, s[16:17]
	s_or_b64 exec, exec, s[0:1]
	v_lshl_add_u64 v[70:71], v[130:131], 2, v[70:71]
	global_load_dword v115, v[70:71], off
	global_load_dword v79, v[70:71], off offset:128
	v_or_b32_e32 v78, 0x53, v136
	v_min_i32_e32 v70, 0x403f, v78
	v_mul_hi_i32 v71, v70, s83
	v_lshrrev_b32_e32 v72, 31, v71
	v_ashrrev_i32_e32 v71, 11, v71
	v_add_u32_e32 v72, v71, v72
	v_mad_i32_i24 v73, v72, s84, v70
	v_cmp_lt_i32_e64 s[0:1], 15, v73
	s_and_saveexec_b64 s[10:11], s[0:1]
	s_xor_b64 s[0:1], exec, s[10:11]
	v_lshlrev_b32_e32 v70, 12, v72
	v_add3_u32 v70, v70, v73, -16
	v_ashrrev_i32_e32 v71, 31, v70
	v_lshlrev_b64 v[70:71], 12, v[70:71]
	v_lshl_add_u64 v[70:71], s[88:89], 0, v[70:71]
	s_andn2_saveexec_b64 s[0:1], s[0:1]
	v_lshlrev_b32_e32 v70, 14, v72
	v_lshl_add_u32 v70, v73, 10, v70
	v_ashrrev_i32_e32 v71, 31, v70
	v_lshl_add_u64 v[70:71], v[70:71], 2, s[16:17]
	s_or_b64 exec, exec, s[0:1]
	v_lshl_add_u64 v[70:71], v[130:131], 2, v[70:71]
	global_load_dword v114, v[70:71], off
	global_load_dword v77, v[70:71], off offset:128
	v_or_b32_e32 v76, 0x58, v136
	v_min_i32_e32 v70, 0x403f, v76
	v_mul_hi_i32 v71, v70, s83
	v_lshrrev_b32_e32 v72, 31, v71
	v_ashrrev_i32_e32 v71, 11, v71
	v_add_u32_e32 v72, v71, v72
	v_mad_i32_i24 v73, v72, s84, v70
	v_cmp_lt_i32_e64 s[0:1], 15, v73
	s_and_saveexec_b64 s[10:11], s[0:1]
	s_xor_b64 s[0:1], exec, s[10:11]
	v_lshlrev_b32_e32 v70, 12, v72
	v_add3_u32 v70, v70, v73, -16
	v_ashrrev_i32_e32 v71, 31, v70
	v_lshlrev_b64 v[70:71], 12, v[70:71]
	v_lshl_add_u64 v[70:71], s[88:89], 0, v[70:71]
	s_andn2_saveexec_b64 s[0:1], s[0:1]
	v_lshlrev_b32_e32 v70, 14, v72
	v_lshl_add_u32 v70, v73, 10, v70
	v_ashrrev_i32_e32 v71, 31, v70
	v_lshl_add_u64 v[70:71], v[70:71], 2, s[16:17]
	s_or_b64 exec, exec, s[0:1]
	v_lshl_add_u64 v[70:71], v[130:131], 2, v[70:71]
	global_load_dword v113, v[70:71], off
	global_load_dword v75, v[70:71], off offset:128
	v_or_b32_e32 v74, 0x59, v136
	v_min_i32_e32 v70, 0x403f, v74
	v_mul_hi_i32 v71, v70, s83
	v_lshrrev_b32_e32 v72, 31, v71
	v_ashrrev_i32_e32 v71, 11, v71
	v_add_u32_e32 v72, v71, v72
	v_mad_i32_i24 v73, v72, s84, v70
	v_cmp_lt_i32_e64 s[0:1], 15, v73
	s_and_saveexec_b64 s[10:11], s[0:1]
	s_xor_b64 s[0:1], exec, s[10:11]
	v_lshlrev_b32_e32 v70, 12, v72
	v_add3_u32 v70, v70, v73, -16
	v_ashrrev_i32_e32 v71, 31, v70
	v_lshlrev_b64 v[70:71], 12, v[70:71]
	v_lshl_add_u64 v[70:71], s[88:89], 0, v[70:71]
	s_andn2_saveexec_b64 s[0:1], s[0:1]
	v_lshlrev_b32_e32 v70, 14, v72
	v_lshl_add_u32 v70, v73, 10, v70
	v_ashrrev_i32_e32 v71, 31, v70
	v_lshl_add_u64 v[70:71], v[70:71], 2, s[16:17]
	s_or_b64 exec, exec, s[0:1]
	v_lshl_add_u64 v[70:71], v[130:131], 2, v[70:71]
	global_load_dword v112, v[70:71], off
	global_load_dword v73, v[70:71], off offset:128
	v_or_b32_e32 v72, 0x5a, v136
	v_min_i32_e32 v70, 0x403f, v72
	v_mul_hi_i32 v71, v70, s83
	v_lshrrev_b32_e32 v99, 31, v71
	v_ashrrev_i32_e32 v71, 11, v71
	v_add_u32_e32 v99, v71, v99
	v_mad_i32_i24 v101, v99, s84, v70
	v_cmp_lt_i32_e64 s[0:1], 15, v101
	s_and_saveexec_b64 s[10:11], s[0:1]
	s_xor_b64 s[0:1], exec, s[10:11]
	v_lshlrev_b32_e32 v70, 12, v99
	v_add3_u32 v70, v70, v101, -16
	v_ashrrev_i32_e32 v71, 31, v70
	v_lshlrev_b64 v[70:71], 12, v[70:71]
	v_lshl_add_u64 v[70:71], s[88:89], 0, v[70:71]
	s_andn2_saveexec_b64 s[0:1], s[0:1]
	v_lshlrev_b32_e32 v70, 14, v99
	v_lshl_add_u32 v70, v101, 10, v70
	v_ashrrev_i32_e32 v71, 31, v70
	v_lshl_add_u64 v[70:71], v[70:71], 2, s[16:17]
	s_or_b64 exec, exec, s[0:1]
	v_lshl_add_u64 v[70:71], v[130:131], 2, v[70:71]
	global_load_dword v111, v[70:71], off
	s_nop 0
	global_load_dword v71, v[70:71], off offset:128
	v_or_b32_e32 v70, 0x5b, v136
	v_min_i32_e32 v101, 0x403f, v70
	v_mul_hi_i32 v99, v101, s83
	v_lshrrev_b32_e32 v102, 31, v99
	v_ashrrev_i32_e32 v99, 11, v99
	v_add_u32_e32 v99, v99, v102
	v_mad_i32_i24 v101, v99, s84, v101
	v_cmp_lt_i32_e64 s[0:1], 15, v101
	s_and_saveexec_b64 s[10:11], s[0:1]
	s_xor_b64 s[0:1], exec, s[10:11]
	v_lshlrev_b32_e32 v99, 12, v99
	v_add3_u32 v102, v99, v101, -16
	v_ashrrev_i32_e32 v103, 31, v102
	v_lshlrev_b64 v[102:103], 12, v[102:103]
	v_lshl_add_u64 v[102:103], s[88:89], 0, v[102:103]
	s_andn2_saveexec_b64 s[0:1], s[0:1]
	v_lshlrev_b32_e32 v99, 14, v99
	v_lshl_add_u32 v102, v101, 10, v99
	v_ashrrev_i32_e32 v103, 31, v102
	v_lshl_add_u64 v[102:103], v[102:103], 2, s[16:17]
	s_or_b64 exec, exec, s[0:1]
	v_lshl_add_u64 v[102:103], v[130:131], 2, v[102:103]
	global_load_dword v110, v[102:103], off
	global_load_dword v109, v[102:103], off offset:128
	v_cmp_gt_i32_e64 s[10:11], s85, v100
	s_nop 1
	v_cndmask_b32_e64 v101, v181, v100, s[10:11]
	v_mul_hi_i32 v99, v101, s83
	v_lshrrev_b32_e32 v102, 31, v99
	v_ashrrev_i32_e32 v99, 11, v99
	v_add_u32_e32 v99, v99, v102
	v_mad_i32_i24 v101, v99, s84, v101
	v_cmp_lt_i32_e64 s[0:1], 15, v101
	s_and_saveexec_b64 s[22:23], s[0:1]
	s_xor_b64 s[0:1], exec, s[22:23]
	v_lshlrev_b32_e32 v99, 12, v99
	v_add3_u32 v102, v99, v101, -16
	v_ashrrev_i32_e32 v103, 31, v102
	v_lshlrev_b64 v[102:103], 12, v[102:103]
	v_lshl_add_u64 v[102:103], s[88:89], 0, v[102:103]
	s_andn2_saveexec_b64 s[0:1], s[0:1]
	v_lshlrev_b32_e32 v99, 14, v99
	v_lshl_add_u32 v102, v101, 10, v99
	v_ashrrev_i32_e32 v103, 31, v102
	v_lshl_add_u64 v[102:103], v[102:103], 2, s[16:17]
	s_or_b64 exec, exec, s[0:1]
	v_ashrrev_i32_e32 v101, 31, v100
	v_lshlrev_b64 v[100:101], 11, v[100:101]
	v_lshl_add_u64 v[100:101], s[62:63], 0, v[100:101]
	s_waitcnt vmcnt(31)
	v_add_f32_e32 v0, v50, v0
	v_lshl_add_u64 v[100:101], v[130:131], 1, v[100:101]
	v_lshl_add_u64 v[102:103], v[102:103], 0, v[134:135]
	s_and_saveexec_b64 s[0:1], s[10:11]
	s_cbranch_execz .LBB0_4095
	global_store_dword v[102:103], v0, off
	v_mul_f32_e32 v50, v0, v242
	v_cvt_pk_bf16_f32 v50, v50, s0
	global_store_short v[100:101], v50, off
.LBB0_4095:
	s_or_b64 exec, exec, s[0:1]
	s_waitcnt vmcnt(30)
	v_add_f32_e32 v67, v34, v67
	s_and_saveexec_b64 s[0:1], s[10:11]
	s_cbranch_execz .LBB0_4097
	global_store_dword v[102:103], v67, off offset:128
	v_mul_f32_e32 v34, v67, v243
	v_cvt_pk_bf16_f32 v34, v34, s0
	global_store_short v[100:101], v34, off offset:64
.LBB0_4097:
	s_or_b64 exec, exec, s[0:1]
	v_cmp_gt_i32_e64 s[10:11], s85, v98
	s_nop 1
	v_cndmask_b32_e64 v50, v181, v98, s[10:11]
	v_mul_hi_i32 v34, v50, s83
	v_lshrrev_b32_e32 v99, 31, v34
	v_ashrrev_i32_e32 v34, 11, v34
	v_add_u32_e32 v34, v34, v99
	v_mad_i32_i24 v50, v34, s84, v50
	v_cmp_lt_i32_e64 s[0:1], 15, v50
	s_and_saveexec_b64 s[22:23], s[0:1]
	s_xor_b64 s[0:1], exec, s[22:23]
	v_lshlrev_b32_e32 v34, 12, v34
	v_add3_u32 v100, v34, v50, -16
	v_ashrrev_i32_e32 v101, 31, v100
	v_lshlrev_b64 v[100:101], 12, v[100:101]
	v_lshl_add_u64 v[100:101], s[88:89], 0, v[100:101]
	s_andn2_saveexec_b64 s[0:1], s[0:1]
	v_lshlrev_b32_e32 v34, 14, v34
	v_lshl_add_u32 v100, v50, 10, v34
	v_ashrrev_i32_e32 v101, 31, v100
	v_lshl_add_u64 v[100:101], v[100:101], 2, s[16:17]
	s_or_b64 exec, exec, s[0:1]
	v_ashrrev_i32_e32 v99, 31, v98
	v_lshlrev_b64 v[98:99], 11, v[98:99]
	v_lshl_add_u64 v[98:99], s[62:63], 0, v[98:99]
	s_waitcnt vmcnt(29)
	v_add_f32_e32 v102, v51, v124
	v_lshl_add_u64 v[50:51], v[130:131], 1, v[98:99]
	v_lshl_add_u64 v[98:99], v[100:101], 0, v[134:135]
	s_and_saveexec_b64 s[0:1], s[10:11]
	s_cbranch_execz .LBB0_4103
	global_store_dword v[98:99], v102, off
	v_mul_f32_e32 v34, v102, v242
	v_cvt_pk_bf16_f32 v34, v34, s0
	global_store_short v[50:51], v34, off
.LBB0_4103:
	s_or_b64 exec, exec, s[0:1]
	s_waitcnt vmcnt(28)
	v_add_f32_e32 v100, v35, v97
	s_and_saveexec_b64 s[0:1], s[10:11]
	s_cbranch_execz .LBB0_4105
	global_store_dword v[98:99], v100, off offset:128
	v_mul_f32_e32 v34, v100, v243
	v_cvt_pk_bf16_f32 v34, v34, s0
	global_store_short v[50:51], v34, off offset:64
.LBB0_4105:
	s_or_b64 exec, exec, s[0:1]
	v_cmp_gt_i32_e64 s[10:11], s85, v96
	s_nop 1
	v_cndmask_b32_e64 v34, v181, v96, s[10:11]
	v_mul_hi_i32 v35, v34, s83
	v_lshrrev_b32_e32 v50, 31, v35
	v_ashrrev_i32_e32 v35, 11, v35
	v_add_u32_e32 v50, v35, v50
	v_mad_i32_i24 v51, v50, s84, v34
	v_cmp_lt_i32_e64 s[0:1], 15, v51
	s_and_saveexec_b64 s[22:23], s[0:1]
	s_xor_b64 s[0:1], exec, s[22:23]
	v_lshlrev_b32_e32 v34, 12, v50
	v_add3_u32 v34, v34, v51, -16
	v_ashrrev_i32_e32 v35, 31, v34
	v_lshlrev_b64 v[34:35], 12, v[34:35]
	v_lshl_add_u64 v[34:35], s[88:89], 0, v[34:35]
	s_andn2_saveexec_b64 s[0:1], s[0:1]
	v_lshlrev_b32_e32 v34, 14, v50
	v_lshl_add_u32 v34, v51, 10, v34
	v_ashrrev_i32_e32 v35, 31, v34
	v_lshl_add_u64 v[34:35], v[34:35], 2, s[16:17]
	s_or_b64 exec, exec, s[0:1]
	v_ashrrev_i32_e32 v97, 31, v96
	v_lshlrev_b64 v[50:51], 11, v[96:97]
	v_lshl_add_u64 v[50:51], s[62:63], 0, v[50:51]
	s_waitcnt vmcnt(27)
	v_add_f32_e32 v96, v52, v123
	v_lshl_add_u64 v[50:51], v[130:131], 1, v[50:51]
	v_lshl_add_u64 v[34:35], v[34:35], 0, v[134:135]
	s_and_saveexec_b64 s[0:1], s[10:11]
	s_cbranch_execz .LBB0_4111
	global_store_dword v[34:35], v96, off
	v_mul_f32_e32 v52, v96, v242
	v_cvt_pk_bf16_f32 v52, v52, s0
	global_store_short v[50:51], v52, off
.LBB0_4111:
	s_or_b64 exec, exec, s[0:1]
	s_waitcnt vmcnt(26)
	v_add_f32_e32 v97, v36, v95
	s_and_saveexec_b64 s[0:1], s[10:11]
	s_cbranch_execz .LBB0_4113
	global_store_dword v[34:35], v97, off offset:128
	v_mul_f32_e32 v34, v97, v243
	v_cvt_pk_bf16_f32 v34, v34, s0
	global_store_short v[50:51], v34, off offset:64
.LBB0_4113:
	s_or_b64 exec, exec, s[0:1]
	v_cmp_gt_i32_e64 s[10:11], s85, v94
	s_nop 1
	v_cndmask_b32_e64 v34, v181, v94, s[10:11]
	v_mul_hi_i32 v35, v34, s83
	v_lshrrev_b32_e32 v36, 31, v35
	v_ashrrev_i32_e32 v35, 11, v35
	v_add_u32_e32 v36, v35, v36
	v_mad_i32_i24 v50, v36, s84, v34
	v_cmp_lt_i32_e64 s[0:1], 15, v50
	s_and_saveexec_b64 s[22:23], s[0:1]
	s_xor_b64 s[0:1], exec, s[22:23]
	v_lshlrev_b32_e32 v34, 12, v36
	v_add3_u32 v34, v34, v50, -16
	v_ashrrev_i32_e32 v35, 31, v34
	v_lshlrev_b64 v[34:35], 12, v[34:35]
	v_lshl_add_u64 v[34:35], s[88:89], 0, v[34:35]
	s_andn2_saveexec_b64 s[0:1], s[0:1]
	v_lshlrev_b32_e32 v34, 14, v36
	v_lshl_add_u32 v34, v50, 10, v34
	v_ashrrev_i32_e32 v35, 31, v34
	v_lshl_add_u64 v[34:35], v[34:35], 2, s[16:17]
	s_or_b64 exec, exec, s[0:1]
	v_ashrrev_i32_e32 v95, 31, v94
	v_lshlrev_b64 v[50:51], 11, v[94:95]
	v_lshl_add_u64 v[50:51], s[62:63], 0, v[50:51]
	s_waitcnt vmcnt(25)
	v_add_f32_e32 v94, v53, v122
	v_lshl_add_u64 v[50:51], v[130:131], 1, v[50:51]
	v_lshl_add_u64 v[34:35], v[34:35], 0, v[134:135]
	s_and_saveexec_b64 s[0:1], s[10:11]
	s_cbranch_execz .LBB0_4119
	global_store_dword v[34:35], v94, off
	v_mul_f32_e32 v36, v94, v242
	v_cvt_pk_bf16_f32 v36, v36, s0
	global_store_short v[50:51], v36, off
.LBB0_4119:
	s_or_b64 exec, exec, s[0:1]
	s_waitcnt vmcnt(24)
	v_add_f32_e32 v95, v37, v93
	s_and_saveexec_b64 s[0:1], s[10:11]
	s_cbranch_execz .LBB0_4121
	global_store_dword v[34:35], v95, off offset:128
	v_mul_f32_e32 v34, v95, v243
	v_cvt_pk_bf16_f32 v34, v34, s0
	global_store_short v[50:51], v34, off offset:64
.LBB0_4121:
	s_or_b64 exec, exec, s[0:1]
	v_cmp_gt_i32_e64 s[10:11], s85, v92
	s_nop 1
	v_cndmask_b32_e64 v34, v181, v92, s[10:11]
	v_mul_hi_i32 v35, v34, s83
	v_lshrrev_b32_e32 v36, 31, v35
	v_ashrrev_i32_e32 v35, 11, v35
	v_add_u32_e32 v36, v35, v36
	v_mad_i32_i24 v37, v36, s84, v34
	v_cmp_lt_i32_e64 s[0:1], 15, v37
	s_and_saveexec_b64 s[22:23], s[0:1]
	s_xor_b64 s[0:1], exec, s[22:23]
	v_lshlrev_b32_e32 v34, 12, v36
	v_add3_u32 v34, v34, v37, -16
	v_ashrrev_i32_e32 v35, 31, v34
	v_lshlrev_b64 v[34:35], 12, v[34:35]
	v_lshl_add_u64 v[34:35], s[88:89], 0, v[34:35]
	s_andn2_saveexec_b64 s[0:1], s[0:1]
	v_lshlrev_b32_e32 v34, 14, v36
	v_lshl_add_u32 v34, v37, 10, v34
	v_ashrrev_i32_e32 v35, 31, v34
	v_lshl_add_u64 v[34:35], v[34:35], 2, s[16:17]
	s_or_b64 exec, exec, s[0:1]
	v_ashrrev_i32_e32 v93, 31, v92
	v_lshlrev_b64 v[36:37], 11, v[92:93]
	v_lshl_add_u64 v[36:37], s[62:63], 0, v[36:37]
	s_waitcnt vmcnt(23)
	v_add_f32_e32 v92, v54, v121
	v_lshl_add_u64 v[36:37], v[130:131], 1, v[36:37]
	v_lshl_add_u64 v[34:35], v[34:35], 0, v[134:135]
	s_and_saveexec_b64 s[0:1], s[10:11]
	s_cbranch_execz .LBB0_4127
	global_store_dword v[34:35], v92, off
	v_mul_f32_e32 v50, v92, v242
	v_cvt_pk_bf16_f32 v50, v50, s0
	global_store_short v[36:37], v50, off
.LBB0_4127:
	s_or_b64 exec, exec, s[0:1]
	s_waitcnt vmcnt(22)
	v_add_f32_e32 v93, v38, v91
	s_and_saveexec_b64 s[0:1], s[10:11]
	s_cbranch_execz .LBB0_4129
	global_store_dword v[34:35], v93, off offset:128
	v_mul_f32_e32 v34, v93, v243
	v_cvt_pk_bf16_f32 v34, v34, s0
	global_store_short v[36:37], v34, off offset:64
.LBB0_4129:
	s_or_b64 exec, exec, s[0:1]
	v_cmp_gt_i32_e64 s[10:11], s85, v90
	s_nop 1
	v_cndmask_b32_e64 v34, v181, v90, s[10:11]
	v_mul_hi_i32 v35, v34, s83
	v_lshrrev_b32_e32 v36, 31, v35
	v_ashrrev_i32_e32 v35, 11, v35
	v_add_u32_e32 v36, v35, v36
	v_mad_i32_i24 v37, v36, s84, v34
	v_cmp_lt_i32_e64 s[0:1], 15, v37
	s_and_saveexec_b64 s[22:23], s[0:1]
	s_xor_b64 s[0:1], exec, s[22:23]
	v_lshlrev_b32_e32 v34, 12, v36
	v_add3_u32 v34, v34, v37, -16
	v_ashrrev_i32_e32 v35, 31, v34
	v_lshlrev_b64 v[34:35], 12, v[34:35]
	v_lshl_add_u64 v[34:35], s[88:89], 0, v[34:35]
	s_andn2_saveexec_b64 s[0:1], s[0:1]
	v_lshlrev_b32_e32 v34, 14, v36
	v_lshl_add_u32 v34, v37, 10, v34
	v_ashrrev_i32_e32 v35, 31, v34
	v_lshl_add_u64 v[34:35], v[34:35], 2, s[16:17]
	s_or_b64 exec, exec, s[0:1]
	v_ashrrev_i32_e32 v91, 31, v90
	v_lshlrev_b64 v[36:37], 11, v[90:91]
	v_lshl_add_u64 v[36:37], s[62:63], 0, v[36:37]
	s_waitcnt vmcnt(21)
	v_add_f32_e32 v90, v55, v120
	v_lshl_add_u64 v[36:37], v[130:131], 1, v[36:37]
	v_lshl_add_u64 v[34:35], v[34:35], 0, v[134:135]
	s_and_saveexec_b64 s[0:1], s[10:11]
	s_cbranch_execz .LBB0_4135
	global_store_dword v[34:35], v90, off
	v_mul_f32_e32 v38, v90, v242
	v_cvt_pk_bf16_f32 v38, v38, s0
	global_store_short v[36:37], v38, off
.LBB0_4135:
	s_or_b64 exec, exec, s[0:1]
	s_waitcnt vmcnt(20)
	v_add_f32_e32 v91, v39, v89
	s_and_saveexec_b64 s[0:1], s[10:11]
	s_cbranch_execz .LBB0_4137
	global_store_dword v[34:35], v91, off offset:128
	v_mul_f32_e32 v34, v91, v243
	v_cvt_pk_bf16_f32 v34, v34, s0
	global_store_short v[36:37], v34, off offset:64
.LBB0_4137:
	s_or_b64 exec, exec, s[0:1]
	v_cmp_gt_i32_e64 s[10:11], s85, v88
	s_nop 1
	v_cndmask_b32_e64 v34, v181, v88, s[10:11]
	v_mul_hi_i32 v35, v34, s83
	v_lshrrev_b32_e32 v36, 31, v35
	v_ashrrev_i32_e32 v35, 11, v35
	v_add_u32_e32 v36, v35, v36
	v_mad_i32_i24 v37, v36, s84, v34
	v_cmp_lt_i32_e64 s[0:1], 15, v37
	s_and_saveexec_b64 s[22:23], s[0:1]
	s_xor_b64 s[0:1], exec, s[22:23]
	v_lshlrev_b32_e32 v34, 12, v36
	v_add3_u32 v34, v34, v37, -16
	v_ashrrev_i32_e32 v35, 31, v34
	v_lshlrev_b64 v[34:35], 12, v[34:35]
	v_lshl_add_u64 v[34:35], s[88:89], 0, v[34:35]
	s_andn2_saveexec_b64 s[0:1], s[0:1]
	v_lshlrev_b32_e32 v34, 14, v36
	v_lshl_add_u32 v34, v37, 10, v34
	v_ashrrev_i32_e32 v35, 31, v34
	v_lshl_add_u64 v[34:35], v[34:35], 2, s[16:17]
	s_or_b64 exec, exec, s[0:1]
	v_ashrrev_i32_e32 v89, 31, v88
	v_lshlrev_b64 v[36:37], 11, v[88:89]
	v_lshl_add_u64 v[36:37], s[62:63], 0, v[36:37]
	s_waitcnt vmcnt(19)
	v_add_f32_e32 v88, v56, v119
	v_lshl_add_u64 v[36:37], v[130:131], 1, v[36:37]
	v_lshl_add_u64 v[34:35], v[34:35], 0, v[134:135]
	s_and_saveexec_b64 s[0:1], s[10:11]
	s_cbranch_execz .LBB0_4143
	global_store_dword v[34:35], v88, off
	v_mul_f32_e32 v38, v88, v242
	v_cvt_pk_bf16_f32 v38, v38, s0
	global_store_short v[36:37], v38, off
.LBB0_4143:
	s_or_b64 exec, exec, s[0:1]
	s_waitcnt vmcnt(18)
	v_add_f32_e32 v89, v40, v87
	s_and_saveexec_b64 s[0:1], s[10:11]
	s_cbranch_execz .LBB0_4145
	global_store_dword v[34:35], v89, off offset:128
	v_mul_f32_e32 v34, v89, v243
	v_cvt_pk_bf16_f32 v34, v34, s0
	global_store_short v[36:37], v34, off offset:64
.LBB0_4145:
	s_or_b64 exec, exec, s[0:1]
	v_cmp_gt_i32_e64 s[10:11], s85, v86
	s_nop 1
	v_cndmask_b32_e64 v34, v181, v86, s[10:11]
	v_mul_hi_i32 v35, v34, s83
	v_lshrrev_b32_e32 v36, 31, v35
	v_ashrrev_i32_e32 v35, 11, v35
	v_add_u32_e32 v36, v35, v36
	v_mad_i32_i24 v37, v36, s84, v34
	v_cmp_lt_i32_e64 s[0:1], 15, v37
	s_and_saveexec_b64 s[22:23], s[0:1]
	s_xor_b64 s[0:1], exec, s[22:23]
	v_lshlrev_b32_e32 v34, 12, v36
	v_add3_u32 v34, v34, v37, -16
	v_ashrrev_i32_e32 v35, 31, v34
	v_lshlrev_b64 v[34:35], 12, v[34:35]
	v_lshl_add_u64 v[34:35], s[88:89], 0, v[34:35]
	s_andn2_saveexec_b64 s[0:1], s[0:1]
	v_lshlrev_b32_e32 v34, 14, v36
	v_lshl_add_u32 v34, v37, 10, v34
	v_ashrrev_i32_e32 v35, 31, v34
	v_lshl_add_u64 v[34:35], v[34:35], 2, s[16:17]
	s_or_b64 exec, exec, s[0:1]
	v_ashrrev_i32_e32 v87, 31, v86
	v_lshlrev_b64 v[36:37], 11, v[86:87]
	v_lshl_add_u64 v[36:37], s[62:63], 0, v[36:37]
	s_waitcnt vmcnt(17)
	v_add_f32_e32 v86, v57, v118
	v_lshl_add_u64 v[36:37], v[130:131], 1, v[36:37]
	v_lshl_add_u64 v[34:35], v[34:35], 0, v[134:135]
	s_and_saveexec_b64 s[0:1], s[10:11]
	s_cbranch_execz .LBB0_4151
	global_store_dword v[34:35], v86, off
	v_mul_f32_e32 v38, v86, v242
	v_cvt_pk_bf16_f32 v38, v38, s0
	global_store_short v[36:37], v38, off
.LBB0_4151:
	s_or_b64 exec, exec, s[0:1]
	s_waitcnt vmcnt(16)
	v_add_f32_e32 v87, v41, v85
	s_and_saveexec_b64 s[0:1], s[10:11]
	s_cbranch_execz .LBB0_4153
	global_store_dword v[34:35], v87, off offset:128
	v_mul_f32_e32 v34, v87, v243
	v_cvt_pk_bf16_f32 v34, v34, s0
	global_store_short v[36:37], v34, off offset:64
.LBB0_4153:
	s_or_b64 exec, exec, s[0:1]
	v_cmp_gt_i32_e64 s[10:11], s85, v84
	s_nop 1
	v_cndmask_b32_e64 v34, v181, v84, s[10:11]
	v_mul_hi_i32 v35, v34, s83
	v_lshrrev_b32_e32 v36, 31, v35
	v_ashrrev_i32_e32 v35, 11, v35
	v_add_u32_e32 v36, v35, v36
	v_mad_i32_i24 v37, v36, s84, v34
	v_cmp_lt_i32_e64 s[0:1], 15, v37
	s_and_saveexec_b64 s[22:23], s[0:1]
	s_xor_b64 s[0:1], exec, s[22:23]
	v_lshlrev_b32_e32 v34, 12, v36
	v_add3_u32 v34, v34, v37, -16
	v_ashrrev_i32_e32 v35, 31, v34
	v_lshlrev_b64 v[34:35], 12, v[34:35]
	v_lshl_add_u64 v[34:35], s[88:89], 0, v[34:35]
	s_andn2_saveexec_b64 s[0:1], s[0:1]
	v_lshlrev_b32_e32 v34, 14, v36
	v_lshl_add_u32 v34, v37, 10, v34
	v_ashrrev_i32_e32 v35, 31, v34
	v_lshl_add_u64 v[34:35], v[34:35], 2, s[16:17]
	s_or_b64 exec, exec, s[0:1]
	v_ashrrev_i32_e32 v85, 31, v84
	v_lshlrev_b64 v[36:37], 11, v[84:85]
	v_lshl_add_u64 v[36:37], s[62:63], 0, v[36:37]
	s_waitcnt vmcnt(15)
	v_add_f32_e32 v84, v58, v117
	v_lshl_add_u64 v[36:37], v[130:131], 1, v[36:37]
	v_lshl_add_u64 v[34:35], v[34:35], 0, v[134:135]
	s_and_saveexec_b64 s[0:1], s[10:11]
	s_cbranch_execz .LBB0_4159
	global_store_dword v[34:35], v84, off
	v_mul_f32_e32 v38, v84, v242
	v_cvt_pk_bf16_f32 v38, v38, s0
	global_store_short v[36:37], v38, off
.LBB0_4159:
	s_or_b64 exec, exec, s[0:1]
	s_waitcnt vmcnt(14)
	v_add_f32_e32 v85, v42, v83
	s_and_saveexec_b64 s[0:1], s[10:11]
	s_cbranch_execz .LBB0_4161
	global_store_dword v[34:35], v85, off offset:128
	v_mul_f32_e32 v34, v85, v243
	v_cvt_pk_bf16_f32 v34, v34, s0
	global_store_short v[36:37], v34, off offset:64
.LBB0_4161:
	s_or_b64 exec, exec, s[0:1]
	v_cmp_gt_i32_e64 s[10:11], s85, v82
	s_nop 1
	v_cndmask_b32_e64 v34, v181, v82, s[10:11]
	v_mul_hi_i32 v35, v34, s83
	v_lshrrev_b32_e32 v36, 31, v35
	v_ashrrev_i32_e32 v35, 11, v35
	v_add_u32_e32 v36, v35, v36
	v_mad_i32_i24 v37, v36, s84, v34
	v_cmp_lt_i32_e64 s[0:1], 15, v37
	s_and_saveexec_b64 s[22:23], s[0:1]
	s_xor_b64 s[0:1], exec, s[22:23]
	v_lshlrev_b32_e32 v34, 12, v36
	v_add3_u32 v34, v34, v37, -16
	v_ashrrev_i32_e32 v35, 31, v34
	v_lshlrev_b64 v[34:35], 12, v[34:35]
	v_lshl_add_u64 v[34:35], s[88:89], 0, v[34:35]
	s_andn2_saveexec_b64 s[0:1], s[0:1]
	v_lshlrev_b32_e32 v34, 14, v36
	v_lshl_add_u32 v34, v37, 10, v34
	v_ashrrev_i32_e32 v35, 31, v34
	v_lshl_add_u64 v[34:35], v[34:35], 2, s[16:17]
	s_or_b64 exec, exec, s[0:1]
	v_ashrrev_i32_e32 v83, 31, v82
	v_lshlrev_b64 v[36:37], 11, v[82:83]
	v_lshl_add_u64 v[36:37], s[62:63], 0, v[36:37]
	s_waitcnt vmcnt(13)
	v_add_f32_e32 v82, v59, v116
	v_lshl_add_u64 v[36:37], v[130:131], 1, v[36:37]
	v_lshl_add_u64 v[34:35], v[34:35], 0, v[134:135]
	s_and_saveexec_b64 s[0:1], s[10:11]
	s_cbranch_execz .LBB0_4167
	global_store_dword v[34:35], v82, off
	v_mul_f32_e32 v38, v82, v242
	v_cvt_pk_bf16_f32 v38, v38, s0
	global_store_short v[36:37], v38, off
.LBB0_4167:
	s_or_b64 exec, exec, s[0:1]
	s_waitcnt vmcnt(12)
	v_add_f32_e32 v83, v43, v81
	s_and_saveexec_b64 s[0:1], s[10:11]
	s_cbranch_execz .LBB0_4169
	global_store_dword v[34:35], v83, off offset:128
	v_mul_f32_e32 v34, v83, v243
	v_cvt_pk_bf16_f32 v34, v34, s0
	global_store_short v[36:37], v34, off offset:64
.LBB0_4169:
	s_or_b64 exec, exec, s[0:1]
	v_cmp_gt_i32_e64 s[10:11], s85, v80
	s_nop 1
	v_cndmask_b32_e64 v34, v181, v80, s[10:11]
	v_mul_hi_i32 v35, v34, s83
	v_lshrrev_b32_e32 v36, 31, v35
	v_ashrrev_i32_e32 v35, 11, v35
	v_add_u32_e32 v36, v35, v36
	v_mad_i32_i24 v37, v36, s84, v34
	v_cmp_lt_i32_e64 s[0:1], 15, v37
	s_and_saveexec_b64 s[22:23], s[0:1]
	s_xor_b64 s[0:1], exec, s[22:23]
	v_lshlrev_b32_e32 v34, 12, v36
	v_add3_u32 v34, v34, v37, -16
	v_ashrrev_i32_e32 v35, 31, v34
	v_lshlrev_b64 v[34:35], 12, v[34:35]
	v_lshl_add_u64 v[34:35], s[88:89], 0, v[34:35]
	s_andn2_saveexec_b64 s[0:1], s[0:1]
	v_lshlrev_b32_e32 v34, 14, v36
	v_lshl_add_u32 v34, v37, 10, v34
	v_ashrrev_i32_e32 v35, 31, v34
	v_lshl_add_u64 v[34:35], v[34:35], 2, s[16:17]
	s_or_b64 exec, exec, s[0:1]
	v_ashrrev_i32_e32 v81, 31, v80
	v_lshlrev_b64 v[36:37], 11, v[80:81]
	v_lshl_add_u64 v[36:37], s[62:63], 0, v[36:37]
	s_waitcnt vmcnt(11)
	v_add_f32_e32 v80, v60, v115
	v_lshl_add_u64 v[36:37], v[130:131], 1, v[36:37]
	v_lshl_add_u64 v[34:35], v[34:35], 0, v[134:135]
	s_and_saveexec_b64 s[0:1], s[10:11]
	s_cbranch_execz .LBB0_4175
	global_store_dword v[34:35], v80, off
	v_mul_f32_e32 v38, v80, v242
	v_cvt_pk_bf16_f32 v38, v38, s0
	global_store_short v[36:37], v38, off
.LBB0_4175:
	s_or_b64 exec, exec, s[0:1]
	s_waitcnt vmcnt(10)
	v_add_f32_e32 v81, v44, v79
	s_and_saveexec_b64 s[0:1], s[10:11]
	s_cbranch_execz .LBB0_4177
	global_store_dword v[34:35], v81, off offset:128
	v_mul_f32_e32 v34, v81, v243
	v_cvt_pk_bf16_f32 v34, v34, s0
	global_store_short v[36:37], v34, off offset:64
.LBB0_4177:
	s_or_b64 exec, exec, s[0:1]
	v_cmp_gt_i32_e64 s[10:11], s85, v78
	s_nop 1
	v_cndmask_b32_e64 v34, v181, v78, s[10:11]
	v_mul_hi_i32 v35, v34, s83
	v_lshrrev_b32_e32 v36, 31, v35
	v_ashrrev_i32_e32 v35, 11, v35
	v_add_u32_e32 v36, v35, v36
	v_mad_i32_i24 v37, v36, s84, v34
	v_cmp_lt_i32_e64 s[0:1], 15, v37
	s_and_saveexec_b64 s[22:23], s[0:1]
	s_xor_b64 s[0:1], exec, s[22:23]
	v_lshlrev_b32_e32 v34, 12, v36
	v_add3_u32 v34, v34, v37, -16
	v_ashrrev_i32_e32 v35, 31, v34
	v_lshlrev_b64 v[34:35], 12, v[34:35]
	v_lshl_add_u64 v[34:35], s[88:89], 0, v[34:35]
	s_andn2_saveexec_b64 s[0:1], s[0:1]
	v_lshlrev_b32_e32 v34, 14, v36
	v_lshl_add_u32 v34, v37, 10, v34
	v_ashrrev_i32_e32 v35, 31, v34
	v_lshl_add_u64 v[34:35], v[34:35], 2, s[16:17]
	s_or_b64 exec, exec, s[0:1]
	v_ashrrev_i32_e32 v79, 31, v78
	v_lshlrev_b64 v[36:37], 11, v[78:79]
	v_lshl_add_u64 v[36:37], s[62:63], 0, v[36:37]
	s_waitcnt vmcnt(9)
	v_add_f32_e32 v78, v61, v114
	v_lshl_add_u64 v[36:37], v[130:131], 1, v[36:37]
	v_lshl_add_u64 v[34:35], v[34:35], 0, v[134:135]
	s_and_saveexec_b64 s[0:1], s[10:11]
	s_cbranch_execz .LBB0_4183
	global_store_dword v[34:35], v78, off
	v_mul_f32_e32 v38, v78, v242
	v_cvt_pk_bf16_f32 v38, v38, s0
	global_store_short v[36:37], v38, off
.LBB0_4183:
	s_or_b64 exec, exec, s[0:1]
	s_waitcnt vmcnt(8)
	v_add_f32_e32 v79, v45, v77
	s_and_saveexec_b64 s[0:1], s[10:11]
	s_cbranch_execz .LBB0_4185
	global_store_dword v[34:35], v79, off offset:128
	v_mul_f32_e32 v34, v79, v243
	v_cvt_pk_bf16_f32 v34, v34, s0
	global_store_short v[36:37], v34, off offset:64
.LBB0_4185:
	s_or_b64 exec, exec, s[0:1]
	v_cmp_gt_i32_e64 s[10:11], s85, v76
	s_nop 1
	v_cndmask_b32_e64 v34, v181, v76, s[10:11]
	v_mul_hi_i32 v35, v34, s83
	v_lshrrev_b32_e32 v36, 31, v35
	v_ashrrev_i32_e32 v35, 11, v35
	v_add_u32_e32 v36, v35, v36
	v_mad_i32_i24 v37, v36, s84, v34
	v_cmp_lt_i32_e64 s[0:1], 15, v37
	s_and_saveexec_b64 s[22:23], s[0:1]
	s_xor_b64 s[0:1], exec, s[22:23]
	v_lshlrev_b32_e32 v34, 12, v36
	v_add3_u32 v34, v34, v37, -16
	v_ashrrev_i32_e32 v35, 31, v34
	v_lshlrev_b64 v[34:35], 12, v[34:35]
	v_lshl_add_u64 v[34:35], s[88:89], 0, v[34:35]
	s_andn2_saveexec_b64 s[0:1], s[0:1]
	v_lshlrev_b32_e32 v34, 14, v36
	v_lshl_add_u32 v34, v37, 10, v34
	v_ashrrev_i32_e32 v35, 31, v34
	v_lshl_add_u64 v[34:35], v[34:35], 2, s[16:17]
	s_or_b64 exec, exec, s[0:1]
	v_ashrrev_i32_e32 v77, 31, v76
	v_lshlrev_b64 v[36:37], 11, v[76:77]
	v_lshl_add_u64 v[36:37], s[62:63], 0, v[36:37]
	s_waitcnt vmcnt(7)
	v_add_f32_e32 v76, v62, v113
	v_lshl_add_u64 v[36:37], v[130:131], 1, v[36:37]
	v_lshl_add_u64 v[34:35], v[34:35], 0, v[134:135]
	s_and_saveexec_b64 s[0:1], s[10:11]
	s_cbranch_execz .LBB0_4191
	global_store_dword v[34:35], v76, off
	v_mul_f32_e32 v38, v76, v242
	v_cvt_pk_bf16_f32 v38, v38, s0
	global_store_short v[36:37], v38, off
.LBB0_4191:
	s_or_b64 exec, exec, s[0:1]
	s_waitcnt vmcnt(6)
	v_add_f32_e32 v77, v46, v75
	s_and_saveexec_b64 s[0:1], s[10:11]
	s_cbranch_execz .LBB0_4193
	global_store_dword v[34:35], v77, off offset:128
	v_mul_f32_e32 v34, v77, v243
	v_cvt_pk_bf16_f32 v34, v34, s0
	global_store_short v[36:37], v34, off offset:64
.LBB0_4193:
	s_or_b64 exec, exec, s[0:1]
	v_cmp_gt_i32_e64 s[10:11], s85, v74
	s_nop 1
	v_cndmask_b32_e64 v34, v181, v74, s[10:11]
	v_mul_hi_i32 v35, v34, s83
	v_lshrrev_b32_e32 v36, 31, v35
	v_ashrrev_i32_e32 v35, 11, v35
	v_add_u32_e32 v36, v35, v36
	v_mad_i32_i24 v37, v36, s84, v34
	v_cmp_lt_i32_e64 s[0:1], 15, v37
	s_and_saveexec_b64 s[22:23], s[0:1]
	s_xor_b64 s[0:1], exec, s[22:23]
	v_lshlrev_b32_e32 v34, 12, v36
	v_add3_u32 v34, v34, v37, -16
	v_ashrrev_i32_e32 v35, 31, v34
	v_lshlrev_b64 v[34:35], 12, v[34:35]
	v_lshl_add_u64 v[34:35], s[88:89], 0, v[34:35]
	s_andn2_saveexec_b64 s[0:1], s[0:1]
	v_lshlrev_b32_e32 v34, 14, v36
	v_lshl_add_u32 v34, v37, 10, v34
	v_ashrrev_i32_e32 v35, 31, v34
	v_lshl_add_u64 v[34:35], v[34:35], 2, s[16:17]
	s_or_b64 exec, exec, s[0:1]
	v_ashrrev_i32_e32 v75, 31, v74
	v_lshlrev_b64 v[36:37], 11, v[74:75]
	v_lshl_add_u64 v[36:37], s[62:63], 0, v[36:37]
	s_waitcnt vmcnt(5)
	v_add_f32_e32 v74, v63, v112
	v_lshl_add_u64 v[36:37], v[130:131], 1, v[36:37]
	v_lshl_add_u64 v[34:35], v[34:35], 0, v[134:135]
	s_and_saveexec_b64 s[0:1], s[10:11]
	s_cbranch_execz .LBB0_4199
	global_store_dword v[34:35], v74, off
	v_mul_f32_e32 v38, v74, v242
	v_cvt_pk_bf16_f32 v38, v38, s0
	global_store_short v[36:37], v38, off
.LBB0_4199:
	s_or_b64 exec, exec, s[0:1]
	s_waitcnt vmcnt(4)
	v_add_f32_e32 v75, v47, v73
	s_and_saveexec_b64 s[0:1], s[10:11]
	s_cbranch_execz .LBB0_4201
	global_store_dword v[34:35], v75, off offset:128
	v_mul_f32_e32 v34, v75, v243
	v_cvt_pk_bf16_f32 v34, v34, s0
	global_store_short v[36:37], v34, off offset:64
.LBB0_4201:
	s_or_b64 exec, exec, s[0:1]
	v_cmp_gt_i32_e64 s[10:11], s85, v72
	s_nop 1
	v_cndmask_b32_e64 v34, v181, v72, s[10:11]
	v_mul_hi_i32 v35, v34, s83
	v_lshrrev_b32_e32 v36, 31, v35
	v_ashrrev_i32_e32 v35, 11, v35
	v_add_u32_e32 v36, v35, v36
	v_mad_i32_i24 v37, v36, s84, v34
	v_cmp_lt_i32_e64 s[0:1], 15, v37
	s_and_saveexec_b64 s[22:23], s[0:1]
	s_xor_b64 s[0:1], exec, s[22:23]
	v_lshlrev_b32_e32 v34, 12, v36
	v_add3_u32 v34, v34, v37, -16
	v_ashrrev_i32_e32 v35, 31, v34
	v_lshlrev_b64 v[34:35], 12, v[34:35]
	v_lshl_add_u64 v[34:35], s[88:89], 0, v[34:35]
	s_andn2_saveexec_b64 s[0:1], s[0:1]
	v_lshlrev_b32_e32 v34, 14, v36
	v_lshl_add_u32 v34, v37, 10, v34
	v_ashrrev_i32_e32 v35, 31, v34
	v_lshl_add_u64 v[34:35], v[34:35], 2, s[16:17]
	s_or_b64 exec, exec, s[0:1]
	v_ashrrev_i32_e32 v73, 31, v72
	v_lshlrev_b64 v[36:37], 11, v[72:73]
	v_lshl_add_u64 v[36:37], s[62:63], 0, v[36:37]
	s_waitcnt vmcnt(3)
	v_add_f32_e32 v72, v64, v111
	v_lshl_add_u64 v[36:37], v[130:131], 1, v[36:37]
	v_lshl_add_u64 v[34:35], v[34:35], 0, v[134:135]
	s_and_saveexec_b64 s[0:1], s[10:11]
	s_cbranch_execz .LBB0_4207
	global_store_dword v[34:35], v72, off
	v_mul_f32_e32 v38, v72, v242
	v_cvt_pk_bf16_f32 v38, v38, s0
	global_store_short v[36:37], v38, off
.LBB0_4207:
	s_or_b64 exec, exec, s[0:1]
	s_waitcnt vmcnt(2)
	v_add_f32_e32 v73, v48, v71
	s_and_saveexec_b64 s[0:1], s[10:11]
	s_cbranch_execz .LBB0_4209
	global_store_dword v[34:35], v73, off offset:128
	v_mul_f32_e32 v34, v73, v243
	v_cvt_pk_bf16_f32 v34, v34, s0
	global_store_short v[36:37], v34, off offset:64
.LBB0_4209:
	s_or_b64 exec, exec, s[0:1]
	v_cmp_gt_i32_e64 s[10:11], s85, v70
	s_nop 1
	v_cndmask_b32_e64 v34, v181, v70, s[10:11]
	v_mul_hi_i32 v35, v34, s83
	v_lshrrev_b32_e32 v36, 31, v35
	v_ashrrev_i32_e32 v35, 11, v35
	v_add_u32_e32 v36, v35, v36
	v_mad_i32_i24 v37, v36, s84, v34
	v_cmp_lt_i32_e64 s[0:1], 15, v37
	s_and_saveexec_b64 s[22:23], s[0:1]
	s_xor_b64 s[0:1], exec, s[22:23]
	v_lshlrev_b32_e32 v34, 12, v36
	v_add3_u32 v34, v34, v37, -16
	v_ashrrev_i32_e32 v35, 31, v34
	v_lshlrev_b64 v[34:35], 12, v[34:35]
	v_lshl_add_u64 v[34:35], s[88:89], 0, v[34:35]
	s_andn2_saveexec_b64 s[0:1], s[0:1]
	v_lshlrev_b32_e32 v34, 14, v36
	v_lshl_add_u32 v34, v37, 10, v34
	v_ashrrev_i32_e32 v35, 31, v34
	v_lshl_add_u64 v[34:35], v[34:35], 2, s[16:17]
	s_or_b64 exec, exec, s[0:1]
	v_ashrrev_i32_e32 v71, 31, v70
	v_lshlrev_b64 v[36:37], 11, v[70:71]
	v_lshl_add_u64 v[36:37], s[62:63], 0, v[36:37]
	s_waitcnt vmcnt(1)
	v_add_f32_e32 v98, v65, v110
	v_lshl_add_u64 v[36:37], v[130:131], 1, v[36:37]
	v_lshl_add_u64 v[34:35], v[34:35], 0, v[134:135]
	s_and_saveexec_b64 s[0:1], s[10:11]
	s_cbranch_execz .LBB0_4215
	global_store_dword v[34:35], v98, off
	v_mul_f32_e32 v38, v98, v242
	v_cvt_pk_bf16_f32 v38, v38, s0
	global_store_short v[36:37], v38, off
.LBB0_4215:
	s_or_b64 exec, exec, s[0:1]
	s_waitcnt vmcnt(0)
	v_add_f32_e32 v99, v49, v109
	s_and_saveexec_b64 s[0:1], s[10:11]
	s_cbranch_execz .LBB0_4217
	global_store_dword v[34:35], v99, off offset:128
	v_mul_f32_e32 v34, v99, v243
	v_cvt_pk_bf16_f32 v34, v34, s0
	global_store_short v[36:37], v34, off offset:64
.LBB0_4217:
	s_or_b64 exec, exec, s[0:1]
	v_or_b32_e32 v64, 0x60, v136
	v_min_i32_e32 v34, 0x403f, v64
	v_mul_hi_i32 v35, v34, s83
	v_lshrrev_b32_e32 v36, 31, v35
	v_ashrrev_i32_e32 v35, 11, v35
	v_add_u32_e32 v36, v35, v36
	v_mad_i32_i24 v37, v36, s84, v34
	v_cmp_lt_i32_e64 s[0:1], 15, v37
	s_and_saveexec_b64 s[10:11], s[0:1]
	s_xor_b64 s[0:1], exec, s[10:11]
	v_lshlrev_b32_e32 v34, 12, v36
	v_add3_u32 v34, v34, v37, -16
	v_ashrrev_i32_e32 v35, 31, v34
	v_lshlrev_b64 v[34:35], 12, v[34:35]
	v_lshl_add_u64 v[34:35], s[88:89], 0, v[34:35]
	s_andn2_saveexec_b64 s[0:1], s[0:1]
	v_lshlrev_b32_e32 v34, 14, v36
	v_lshl_add_u32 v34, v37, 10, v34
	v_ashrrev_i32_e32 v35, 31, v34
	v_lshl_add_u64 v[34:35], v[34:35], 2, s[16:17]
	s_or_b64 exec, exec, s[0:1]
	v_lshl_add_u64 v[34:35], v[130:131], 2, v[34:35]
	global_load_dword v101, v[34:35], off
	global_load_dword v63, v[34:35], off offset:128
	v_or_b32_e32 v62, 0x61, v136
	v_min_i32_e32 v34, 0x403f, v62
	v_mul_hi_i32 v35, v34, s83
	v_lshrrev_b32_e32 v36, 31, v35
	v_ashrrev_i32_e32 v35, 11, v35
	v_add_u32_e32 v36, v35, v36
	v_mad_i32_i24 v37, v36, s84, v34
	v_cmp_lt_i32_e64 s[0:1], 15, v37
	s_and_saveexec_b64 s[10:11], s[0:1]
	s_xor_b64 s[0:1], exec, s[10:11]
	v_lshlrev_b32_e32 v34, 12, v36
	v_add3_u32 v34, v34, v37, -16
	v_ashrrev_i32_e32 v35, 31, v34
	v_lshlrev_b64 v[34:35], 12, v[34:35]
	v_lshl_add_u64 v[34:35], s[88:89], 0, v[34:35]
	s_andn2_saveexec_b64 s[0:1], s[0:1]
	v_lshlrev_b32_e32 v34, 14, v36
	v_lshl_add_u32 v34, v37, 10, v34
	v_ashrrev_i32_e32 v35, 31, v34
	v_lshl_add_u64 v[34:35], v[34:35], 2, s[16:17]
	s_or_b64 exec, exec, s[0:1]
	v_lshl_add_u64 v[34:35], v[130:131], 2, v[34:35]
	global_load_dword v124, v[34:35], off
	global_load_dword v61, v[34:35], off offset:128
	v_or_b32_e32 v60, 0x62, v136
	v_min_i32_e32 v34, 0x403f, v60
	v_mul_hi_i32 v35, v34, s83
	v_lshrrev_b32_e32 v36, 31, v35
	v_ashrrev_i32_e32 v35, 11, v35
	v_add_u32_e32 v36, v35, v36
	v_mad_i32_i24 v37, v36, s84, v34
	v_cmp_lt_i32_e64 s[0:1], 15, v37
	s_and_saveexec_b64 s[10:11], s[0:1]
	s_xor_b64 s[0:1], exec, s[10:11]
	v_lshlrev_b32_e32 v34, 12, v36
	v_add3_u32 v34, v34, v37, -16
	v_ashrrev_i32_e32 v35, 31, v34
	v_lshlrev_b64 v[34:35], 12, v[34:35]
	v_lshl_add_u64 v[34:35], s[88:89], 0, v[34:35]
	s_andn2_saveexec_b64 s[0:1], s[0:1]
	v_lshlrev_b32_e32 v34, 14, v36
	v_lshl_add_u32 v34, v37, 10, v34
	v_ashrrev_i32_e32 v35, 31, v34
	v_lshl_add_u64 v[34:35], v[34:35], 2, s[16:17]
	s_or_b64 exec, exec, s[0:1]
	v_lshl_add_u64 v[34:35], v[130:131], 2, v[34:35]
	global_load_dword v123, v[34:35], off
	global_load_dword v59, v[34:35], off offset:128
	v_or_b32_e32 v58, 0x63, v136
	v_min_i32_e32 v34, 0x403f, v58
	v_mul_hi_i32 v35, v34, s83
	v_lshrrev_b32_e32 v36, 31, v35
	v_ashrrev_i32_e32 v35, 11, v35
	v_add_u32_e32 v36, v35, v36
	v_mad_i32_i24 v37, v36, s84, v34
	v_cmp_lt_i32_e64 s[0:1], 15, v37
	s_and_saveexec_b64 s[10:11], s[0:1]
	s_xor_b64 s[0:1], exec, s[10:11]
	v_lshlrev_b32_e32 v34, 12, v36
	v_add3_u32 v34, v34, v37, -16
	v_ashrrev_i32_e32 v35, 31, v34
	v_lshlrev_b64 v[34:35], 12, v[34:35]
	v_lshl_add_u64 v[34:35], s[88:89], 0, v[34:35]
	s_andn2_saveexec_b64 s[0:1], s[0:1]
	v_lshlrev_b32_e32 v34, 14, v36
	v_lshl_add_u32 v34, v37, 10, v34
	v_ashrrev_i32_e32 v35, 31, v34
	v_lshl_add_u64 v[34:35], v[34:35], 2, s[16:17]
	s_or_b64 exec, exec, s[0:1]
	v_lshl_add_u64 v[34:35], v[130:131], 2, v[34:35]
	global_load_dword v122, v[34:35], off
	global_load_dword v57, v[34:35], off offset:128
	v_or_b32_e32 v56, 0x68, v136
	v_min_i32_e32 v34, 0x403f, v56
	v_mul_hi_i32 v35, v34, s83
	v_lshrrev_b32_e32 v36, 31, v35
	v_ashrrev_i32_e32 v35, 11, v35
	v_add_u32_e32 v36, v35, v36
	v_mad_i32_i24 v37, v36, s84, v34
	v_cmp_lt_i32_e64 s[0:1], 15, v37
	s_and_saveexec_b64 s[10:11], s[0:1]
	s_xor_b64 s[0:1], exec, s[10:11]
	v_lshlrev_b32_e32 v34, 12, v36
	v_add3_u32 v34, v34, v37, -16
	v_ashrrev_i32_e32 v35, 31, v34
	v_lshlrev_b64 v[34:35], 12, v[34:35]
	v_lshl_add_u64 v[34:35], s[88:89], 0, v[34:35]
	s_andn2_saveexec_b64 s[0:1], s[0:1]
	v_lshlrev_b32_e32 v34, 14, v36
	v_lshl_add_u32 v34, v37, 10, v34
	v_ashrrev_i32_e32 v35, 31, v34
	v_lshl_add_u64 v[34:35], v[34:35], 2, s[16:17]
	s_or_b64 exec, exec, s[0:1]
	v_lshl_add_u64 v[34:35], v[130:131], 2, v[34:35]
	global_load_dword v121, v[34:35], off
	global_load_dword v55, v[34:35], off offset:128
	v_or_b32_e32 v54, 0x69, v136
	v_min_i32_e32 v34, 0x403f, v54
	v_mul_hi_i32 v35, v34, s83
	v_lshrrev_b32_e32 v36, 31, v35
	v_ashrrev_i32_e32 v35, 11, v35
	v_add_u32_e32 v36, v35, v36
	v_mad_i32_i24 v37, v36, s84, v34
	v_cmp_lt_i32_e64 s[0:1], 15, v37
	s_and_saveexec_b64 s[10:11], s[0:1]
	s_xor_b64 s[0:1], exec, s[10:11]
	v_lshlrev_b32_e32 v34, 12, v36
	v_add3_u32 v34, v34, v37, -16
	v_ashrrev_i32_e32 v35, 31, v34
	v_lshlrev_b64 v[34:35], 12, v[34:35]
	v_lshl_add_u64 v[34:35], s[88:89], 0, v[34:35]
	s_andn2_saveexec_b64 s[0:1], s[0:1]
	v_lshlrev_b32_e32 v34, 14, v36
	v_lshl_add_u32 v34, v37, 10, v34
	v_ashrrev_i32_e32 v35, 31, v34
	v_lshl_add_u64 v[34:35], v[34:35], 2, s[16:17]
	s_or_b64 exec, exec, s[0:1]
	v_lshl_add_u64 v[34:35], v[130:131], 2, v[34:35]
	global_load_dword v120, v[34:35], off
	global_load_dword v53, v[34:35], off offset:128
	v_or_b32_e32 v52, 0x6a, v136
	v_min_i32_e32 v34, 0x403f, v52
	v_mul_hi_i32 v35, v34, s83
	v_lshrrev_b32_e32 v36, 31, v35
	v_ashrrev_i32_e32 v35, 11, v35
	v_add_u32_e32 v36, v35, v36
	v_mad_i32_i24 v37, v36, s84, v34
	v_cmp_lt_i32_e64 s[0:1], 15, v37
	s_and_saveexec_b64 s[10:11], s[0:1]
	s_xor_b64 s[0:1], exec, s[10:11]
	v_lshlrev_b32_e32 v34, 12, v36
	v_add3_u32 v34, v34, v37, -16
	v_ashrrev_i32_e32 v35, 31, v34
	v_lshlrev_b64 v[34:35], 12, v[34:35]
	v_lshl_add_u64 v[34:35], s[88:89], 0, v[34:35]
	s_andn2_saveexec_b64 s[0:1], s[0:1]
	v_lshlrev_b32_e32 v34, 14, v36
	v_lshl_add_u32 v34, v37, 10, v34
	v_ashrrev_i32_e32 v35, 31, v34
	v_lshl_add_u64 v[34:35], v[34:35], 2, s[16:17]
	s_or_b64 exec, exec, s[0:1]
	v_lshl_add_u64 v[34:35], v[130:131], 2, v[34:35]
	global_load_dword v119, v[34:35], off
	global_load_dword v51, v[34:35], off offset:128
	v_or_b32_e32 v50, 0x6b, v136
	v_min_i32_e32 v34, 0x403f, v50
	v_mul_hi_i32 v35, v34, s83
	v_lshrrev_b32_e32 v36, 31, v35
	v_ashrrev_i32_e32 v35, 11, v35
	v_add_u32_e32 v36, v35, v36
	v_mad_i32_i24 v37, v36, s84, v34
	v_cmp_lt_i32_e64 s[0:1], 15, v37
	s_and_saveexec_b64 s[10:11], s[0:1]
	s_xor_b64 s[0:1], exec, s[10:11]
	v_lshlrev_b32_e32 v34, 12, v36
	v_add3_u32 v34, v34, v37, -16
	v_ashrrev_i32_e32 v35, 31, v34
	v_lshlrev_b64 v[34:35], 12, v[34:35]
	v_lshl_add_u64 v[34:35], s[88:89], 0, v[34:35]
	s_andn2_saveexec_b64 s[0:1], s[0:1]
	v_lshlrev_b32_e32 v34, 14, v36
	v_lshl_add_u32 v34, v37, 10, v34
	v_ashrrev_i32_e32 v35, 31, v34
	v_lshl_add_u64 v[34:35], v[34:35], 2, s[16:17]
	s_or_b64 exec, exec, s[0:1]
	v_lshl_add_u64 v[34:35], v[130:131], 2, v[34:35]
	global_load_dword v118, v[34:35], off
	global_load_dword v49, v[34:35], off offset:128
	v_or_b32_e32 v48, 0x70, v136
	v_min_i32_e32 v34, 0x403f, v48
	v_mul_hi_i32 v35, v34, s83
	v_lshrrev_b32_e32 v36, 31, v35
	v_ashrrev_i32_e32 v35, 11, v35
	v_add_u32_e32 v36, v35, v36
	v_mad_i32_i24 v37, v36, s84, v34
	v_cmp_lt_i32_e64 s[0:1], 15, v37
	s_and_saveexec_b64 s[10:11], s[0:1]
	s_xor_b64 s[0:1], exec, s[10:11]
	v_lshlrev_b32_e32 v34, 12, v36
	v_add3_u32 v34, v34, v37, -16
	v_ashrrev_i32_e32 v35, 31, v34
	v_lshlrev_b64 v[34:35], 12, v[34:35]
	v_lshl_add_u64 v[34:35], s[88:89], 0, v[34:35]
	s_andn2_saveexec_b64 s[0:1], s[0:1]
	v_lshlrev_b32_e32 v34, 14, v36
	v_lshl_add_u32 v34, v37, 10, v34
	v_ashrrev_i32_e32 v35, 31, v34
	v_lshl_add_u64 v[34:35], v[34:35], 2, s[16:17]
	s_or_b64 exec, exec, s[0:1]
	v_lshl_add_u64 v[34:35], v[130:131], 2, v[34:35]
	global_load_dword v117, v[34:35], off
	global_load_dword v47, v[34:35], off offset:128
	v_or_b32_e32 v46, 0x71, v136
	v_min_i32_e32 v34, 0x403f, v46
	v_mul_hi_i32 v35, v34, s83
	v_lshrrev_b32_e32 v36, 31, v35
	v_ashrrev_i32_e32 v35, 11, v35
	v_add_u32_e32 v36, v35, v36
	v_mad_i32_i24 v37, v36, s84, v34
	v_cmp_lt_i32_e64 s[0:1], 15, v37
	s_and_saveexec_b64 s[10:11], s[0:1]
	s_xor_b64 s[0:1], exec, s[10:11]
	v_lshlrev_b32_e32 v34, 12, v36
	v_add3_u32 v34, v34, v37, -16
	v_ashrrev_i32_e32 v35, 31, v34
	v_lshlrev_b64 v[34:35], 12, v[34:35]
	v_lshl_add_u64 v[34:35], s[88:89], 0, v[34:35]
	s_andn2_saveexec_b64 s[0:1], s[0:1]
	v_lshlrev_b32_e32 v34, 14, v36
	v_lshl_add_u32 v34, v37, 10, v34
	v_ashrrev_i32_e32 v35, 31, v34
	v_lshl_add_u64 v[34:35], v[34:35], 2, s[16:17]
	s_or_b64 exec, exec, s[0:1]
	v_lshl_add_u64 v[34:35], v[130:131], 2, v[34:35]
	global_load_dword v116, v[34:35], off
	global_load_dword v45, v[34:35], off offset:128
	v_or_b32_e32 v44, 0x72, v136
	v_min_i32_e32 v34, 0x403f, v44
	v_mul_hi_i32 v35, v34, s83
	v_lshrrev_b32_e32 v36, 31, v35
	v_ashrrev_i32_e32 v35, 11, v35
	v_add_u32_e32 v36, v35, v36
	v_mad_i32_i24 v37, v36, s84, v34
	v_cmp_lt_i32_e64 s[0:1], 15, v37
	s_and_saveexec_b64 s[10:11], s[0:1]
	s_xor_b64 s[0:1], exec, s[10:11]
	v_lshlrev_b32_e32 v34, 12, v36
	v_add3_u32 v34, v34, v37, -16
	v_ashrrev_i32_e32 v35, 31, v34
	v_lshlrev_b64 v[34:35], 12, v[34:35]
	v_lshl_add_u64 v[34:35], s[88:89], 0, v[34:35]
	s_andn2_saveexec_b64 s[0:1], s[0:1]
	v_lshlrev_b32_e32 v34, 14, v36
	v_lshl_add_u32 v34, v37, 10, v34
	v_ashrrev_i32_e32 v35, 31, v34
	v_lshl_add_u64 v[34:35], v[34:35], 2, s[16:17]
	s_or_b64 exec, exec, s[0:1]
	v_lshl_add_u64 v[34:35], v[130:131], 2, v[34:35]
	global_load_dword v115, v[34:35], off
	global_load_dword v43, v[34:35], off offset:128
	v_or_b32_e32 v42, 0x73, v136
	v_min_i32_e32 v34, 0x403f, v42
	v_mul_hi_i32 v35, v34, s83
	v_lshrrev_b32_e32 v36, 31, v35
	v_ashrrev_i32_e32 v35, 11, v35
	v_add_u32_e32 v36, v35, v36
	v_mad_i32_i24 v37, v36, s84, v34
	v_cmp_lt_i32_e64 s[0:1], 15, v37
	s_and_saveexec_b64 s[10:11], s[0:1]
	s_xor_b64 s[0:1], exec, s[10:11]
	v_lshlrev_b32_e32 v34, 12, v36
	v_add3_u32 v34, v34, v37, -16
	v_ashrrev_i32_e32 v35, 31, v34
	v_lshlrev_b64 v[34:35], 12, v[34:35]
	v_lshl_add_u64 v[34:35], s[88:89], 0, v[34:35]
	s_andn2_saveexec_b64 s[0:1], s[0:1]
	v_lshlrev_b32_e32 v34, 14, v36
	v_lshl_add_u32 v34, v37, 10, v34
	v_ashrrev_i32_e32 v35, 31, v34
	v_lshl_add_u64 v[34:35], v[34:35], 2, s[16:17]
	s_or_b64 exec, exec, s[0:1]
	v_lshl_add_u64 v[34:35], v[130:131], 2, v[34:35]
	global_load_dword v114, v[34:35], off
	global_load_dword v41, v[34:35], off offset:128
	v_or_b32_e32 v40, 0x78, v136
	v_min_i32_e32 v34, 0x403f, v40
	v_mul_hi_i32 v35, v34, s83
	v_lshrrev_b32_e32 v36, 31, v35
	v_ashrrev_i32_e32 v35, 11, v35
	v_add_u32_e32 v36, v35, v36
	v_mad_i32_i24 v37, v36, s84, v34
	v_cmp_lt_i32_e64 s[0:1], 15, v37
	s_and_saveexec_b64 s[10:11], s[0:1]
	s_xor_b64 s[0:1], exec, s[10:11]
	v_lshlrev_b32_e32 v34, 12, v36
	v_add3_u32 v34, v34, v37, -16
	v_ashrrev_i32_e32 v35, 31, v34
	v_lshlrev_b64 v[34:35], 12, v[34:35]
	v_lshl_add_u64 v[34:35], s[88:89], 0, v[34:35]
	s_andn2_saveexec_b64 s[0:1], s[0:1]
	v_lshlrev_b32_e32 v34, 14, v36
	v_lshl_add_u32 v34, v37, 10, v34
	v_ashrrev_i32_e32 v35, 31, v34
	v_lshl_add_u64 v[34:35], v[34:35], 2, s[16:17]
	s_or_b64 exec, exec, s[0:1]
	v_lshl_add_u64 v[34:35], v[130:131], 2, v[34:35]
	global_load_dword v113, v[34:35], off
	global_load_dword v39, v[34:35], off offset:128
	v_or_b32_e32 v38, 0x79, v136
	v_min_i32_e32 v34, 0x403f, v38
	v_mul_hi_i32 v35, v34, s83
	v_lshrrev_b32_e32 v36, 31, v35
	v_ashrrev_i32_e32 v35, 11, v35
	v_add_u32_e32 v36, v35, v36
	v_mad_i32_i24 v37, v36, s84, v34
	v_cmp_lt_i32_e64 s[0:1], 15, v37
	s_and_saveexec_b64 s[10:11], s[0:1]
	s_xor_b64 s[0:1], exec, s[10:11]
	v_lshlrev_b32_e32 v34, 12, v36
	v_add3_u32 v34, v34, v37, -16
	v_ashrrev_i32_e32 v35, 31, v34
	v_lshlrev_b64 v[34:35], 12, v[34:35]
	v_lshl_add_u64 v[34:35], s[88:89], 0, v[34:35]
	s_andn2_saveexec_b64 s[0:1], s[0:1]
	v_lshlrev_b32_e32 v34, 14, v36
	v_lshl_add_u32 v34, v37, 10, v34
	v_ashrrev_i32_e32 v35, 31, v34
	v_lshl_add_u64 v[34:35], v[34:35], 2, s[16:17]
	s_or_b64 exec, exec, s[0:1]
	v_lshl_add_u64 v[34:35], v[130:131], 2, v[34:35]
	global_load_dword v112, v[34:35], off
	global_load_dword v37, v[34:35], off offset:128
	v_or_b32_e32 v36, 0x7a, v136
	v_min_i32_e32 v34, 0x403f, v36
	v_mul_hi_i32 v35, v34, s83
	v_lshrrev_b32_e32 v65, 31, v35
	v_ashrrev_i32_e32 v35, 11, v35
	v_add_u32_e32 v65, v35, v65
	v_mad_i32_i24 v70, v65, s84, v34
	v_cmp_lt_i32_e64 s[0:1], 15, v70
	s_and_saveexec_b64 s[10:11], s[0:1]
	s_xor_b64 s[0:1], exec, s[10:11]
	v_lshlrev_b32_e32 v34, 12, v65
	v_add3_u32 v34, v34, v70, -16
	v_ashrrev_i32_e32 v35, 31, v34
	v_lshlrev_b64 v[34:35], 12, v[34:35]
	v_lshl_add_u64 v[34:35], s[88:89], 0, v[34:35]
	s_andn2_saveexec_b64 s[0:1], s[0:1]
	v_lshlrev_b32_e32 v34, 14, v65
	v_lshl_add_u32 v34, v70, 10, v34
	v_ashrrev_i32_e32 v35, 31, v34
	v_lshl_add_u64 v[34:35], v[34:35], 2, s[16:17]
	s_or_b64 exec, exec, s[0:1]
	v_lshl_add_u64 v[34:35], v[130:131], 2, v[34:35]
	global_load_dword v111, v[34:35], off
	s_nop 0
	global_load_dword v35, v[34:35], off offset:128
	v_or_b32_e32 v34, 0x7b, v136
	v_min_i32_e32 v70, 0x403f, v34
	v_mul_hi_i32 v65, v70, s83
	v_lshrrev_b32_e32 v71, 31, v65
	v_ashrrev_i32_e32 v65, 11, v65
	v_add_u32_e32 v65, v65, v71
	v_mad_i32_i24 v103, v65, s84, v70
	v_cmp_lt_i32_e64 s[0:1], 15, v103
	s_and_saveexec_b64 s[10:11], s[0:1]
	s_xor_b64 s[0:1], exec, s[10:11]
	v_lshlrev_b32_e32 v65, 12, v65
	v_add3_u32 v70, v65, v103, -16
	v_ashrrev_i32_e32 v71, 31, v70
	v_lshlrev_b64 v[70:71], 12, v[70:71]
	v_lshl_add_u64 v[70:71], s[88:89], 0, v[70:71]
	s_andn2_saveexec_b64 s[0:1], s[0:1]
	v_lshlrev_b32_e32 v65, 14, v65
	v_lshl_add_u32 v70, v103, 10, v65
	v_ashrrev_i32_e32 v71, 31, v70
	v_lshl_add_u64 v[70:71], v[70:71], 2, s[16:17]
	s_or_b64 exec, exec, s[0:1]
	v_lshl_add_u64 v[70:71], v[130:131], 2, v[70:71]
	global_load_dword v109, v[70:71], off
	global_load_dword v103, v[70:71], off offset:128
	v_cmp_gt_i32_e64 s[10:11], s85, v64
	s_nop 1
	v_cndmask_b32_e64 v70, v181, v64, s[10:11]
	v_mul_hi_i32 v65, v70, s83
	v_lshrrev_b32_e32 v71, 31, v65
	v_ashrrev_i32_e32 v65, 11, v65
	v_add_u32_e32 v65, v65, v71
	v_mad_i32_i24 v110, v65, s84, v70
	v_cmp_lt_i32_e64 s[0:1], 15, v110
	s_and_saveexec_b64 s[22:23], s[0:1]
	s_xor_b64 s[0:1], exec, s[22:23]
	v_lshlrev_b32_e32 v65, 12, v65
	v_add3_u32 v70, v65, v110, -16
	v_ashrrev_i32_e32 v71, 31, v70
	v_lshlrev_b64 v[70:71], 12, v[70:71]
	v_lshl_add_u64 v[70:71], s[88:89], 0, v[70:71]
	s_andn2_saveexec_b64 s[0:1], s[0:1]
	v_lshlrev_b32_e32 v65, 14, v65
	v_lshl_add_u32 v70, v110, 10, v65
	v_ashrrev_i32_e32 v71, 31, v70
	v_lshl_add_u64 v[70:71], v[70:71], 2, s[16:17]
	s_or_b64 exec, exec, s[0:1]
	v_ashrrev_i32_e32 v65, 31, v64
	v_lshlrev_b64 v[64:65], 11, v[64:65]
	v_lshl_add_u64 v[64:65], s[62:63], 0, v[64:65]
	s_waitcnt vmcnt(31)
	v_add_f32_e32 v101, v18, v101
	v_lshl_add_u64 v[64:65], v[130:131], 1, v[64:65]
	v_lshl_add_u64 v[70:71], v[70:71], 0, v[134:135]
	s_and_saveexec_b64 s[0:1], s[10:11]
	s_cbranch_execz .LBB0_4287
	global_store_dword v[70:71], v101, off
	v_mul_f32_e32 v18, v101, v242
	v_cvt_pk_bf16_f32 v18, v18, s0
	global_store_short v[64:65], v18, off
.LBB0_4287:
	s_or_b64 exec, exec, s[0:1]
	s_waitcnt vmcnt(30)
	v_add_f32_e32 v110, v2, v63
	s_and_saveexec_b64 s[0:1], s[10:11]
	s_cbranch_execz .LBB0_4289
	global_store_dword v[70:71], v110, off offset:128
	v_mul_f32_e32 v2, v110, v243
	v_cvt_pk_bf16_f32 v2, v2, s0
	global_store_short v[64:65], v2, off offset:64
.LBB0_4289:
	s_or_b64 exec, exec, s[0:1]
	v_cmp_gt_i32_e64 s[10:11], s85, v62
	s_nop 1
	v_cndmask_b32_e64 v18, v181, v62, s[10:11]
	v_mul_hi_i32 v2, v18, s83
	v_lshrrev_b32_e32 v63, 31, v2
	v_ashrrev_i32_e32 v2, 11, v2
	v_add_u32_e32 v2, v2, v63
	v_mad_i32_i24 v18, v2, s84, v18
	v_cmp_lt_i32_e64 s[0:1], 15, v18
	s_and_saveexec_b64 s[22:23], s[0:1]
	s_xor_b64 s[0:1], exec, s[22:23]
	v_lshlrev_b32_e32 v2, 12, v2
	v_add3_u32 v64, v2, v18, -16
	v_ashrrev_i32_e32 v65, 31, v64
	v_lshlrev_b64 v[64:65], 12, v[64:65]
	v_lshl_add_u64 v[64:65], s[88:89], 0, v[64:65]
	s_andn2_saveexec_b64 s[0:1], s[0:1]
	v_lshlrev_b32_e32 v2, 14, v2
	v_lshl_add_u32 v64, v18, 10, v2
	v_ashrrev_i32_e32 v65, 31, v64
	v_lshl_add_u64 v[64:65], v[64:65], 2, s[16:17]
	s_or_b64 exec, exec, s[0:1]
	v_ashrrev_i32_e32 v63, 31, v62
	v_lshlrev_b64 v[62:63], 11, v[62:63]
	v_lshl_add_u64 v[62:63], s[62:63], 0, v[62:63]
	s_waitcnt vmcnt(29)
	v_add_f32_e32 v70, v19, v124
	v_lshl_add_u64 v[18:19], v[130:131], 1, v[62:63]
	v_lshl_add_u64 v[62:63], v[64:65], 0, v[134:135]
	s_and_saveexec_b64 s[0:1], s[10:11]
	s_cbranch_execz .LBB0_4295
	global_store_dword v[62:63], v70, off
	v_mul_f32_e32 v2, v70, v242
	v_cvt_pk_bf16_f32 v2, v2, s0
	global_store_short v[18:19], v2, off
.LBB0_4295:
	s_or_b64 exec, exec, s[0:1]
	s_waitcnt vmcnt(28)
	v_add_f32_e32 v64, v3, v61
	s_and_saveexec_b64 s[0:1], s[10:11]
	s_cbranch_execz .LBB0_4297
	global_store_dword v[62:63], v64, off offset:128
	v_mul_f32_e32 v2, v64, v243
	v_cvt_pk_bf16_f32 v2, v2, s0
	global_store_short v[18:19], v2, off offset:64
.LBB0_4297:
	s_or_b64 exec, exec, s[0:1]
	v_cmp_gt_i32_e64 s[10:11], s85, v60
	s_nop 1
	v_cndmask_b32_e64 v2, v181, v60, s[10:11]
	v_mul_hi_i32 v3, v2, s83
	v_lshrrev_b32_e32 v18, 31, v3
	v_ashrrev_i32_e32 v3, 11, v3
	v_add_u32_e32 v18, v3, v18
	v_mad_i32_i24 v19, v18, s84, v2
	v_cmp_lt_i32_e64 s[0:1], 15, v19
	s_and_saveexec_b64 s[22:23], s[0:1]
	s_xor_b64 s[0:1], exec, s[22:23]
	v_lshlrev_b32_e32 v2, 12, v18
	v_add3_u32 v2, v2, v19, -16
	v_ashrrev_i32_e32 v3, 31, v2
	v_lshlrev_b64 v[2:3], 12, v[2:3]
	v_lshl_add_u64 v[2:3], s[88:89], 0, v[2:3]
	s_andn2_saveexec_b64 s[0:1], s[0:1]
	v_lshlrev_b32_e32 v2, 14, v18
	v_lshl_add_u32 v2, v19, 10, v2
	v_ashrrev_i32_e32 v3, 31, v2
	v_lshl_add_u64 v[2:3], v[2:3], 2, s[16:17]
	s_or_b64 exec, exec, s[0:1]
	v_ashrrev_i32_e32 v61, 31, v60
	v_lshlrev_b64 v[18:19], 11, v[60:61]
	v_lshl_add_u64 v[18:19], s[62:63], 0, v[18:19]
	s_waitcnt vmcnt(27)
	v_add_f32_e32 v20, v20, v123
	v_lshl_add_u64 v[18:19], v[130:131], 1, v[18:19]
	v_lshl_add_u64 v[2:3], v[2:3], 0, v[134:135]
	s_and_saveexec_b64 s[0:1], s[10:11]
	s_cbranch_execz .LBB0_4303
	global_store_dword v[2:3], v20, off
	v_mul_f32_e32 v60, v20, v242
	v_cvt_pk_bf16_f32 v60, v60, s0
	global_store_short v[18:19], v60, off
.LBB0_4303:
	s_or_b64 exec, exec, s[0:1]
	s_waitcnt vmcnt(26)
	v_add_f32_e32 v60, v4, v59
	s_and_saveexec_b64 s[0:1], s[10:11]
	s_cbranch_execz .LBB0_4305
	global_store_dword v[2:3], v60, off offset:128
	v_mul_f32_e32 v2, v60, v243
	v_cvt_pk_bf16_f32 v2, v2, s0
	global_store_short v[18:19], v2, off offset:64
.LBB0_4305:
	s_or_b64 exec, exec, s[0:1]
	v_cmp_gt_i32_e64 s[10:11], s85, v58
	s_nop 1
	v_cndmask_b32_e64 v2, v181, v58, s[10:11]
	v_mul_hi_i32 v3, v2, s83
	v_lshrrev_b32_e32 v4, 31, v3
	v_ashrrev_i32_e32 v3, 11, v3
	v_add_u32_e32 v4, v3, v4
	v_mad_i32_i24 v18, v4, s84, v2
	v_cmp_lt_i32_e64 s[0:1], 15, v18
	s_and_saveexec_b64 s[22:23], s[0:1]
	s_xor_b64 s[0:1], exec, s[22:23]
	v_lshlrev_b32_e32 v2, 12, v4
	v_add3_u32 v2, v2, v18, -16
	v_ashrrev_i32_e32 v3, 31, v2
	v_lshlrev_b64 v[2:3], 12, v[2:3]
	v_lshl_add_u64 v[2:3], s[88:89], 0, v[2:3]
	s_andn2_saveexec_b64 s[0:1], s[0:1]
	v_lshlrev_b32_e32 v2, 14, v4
	v_lshl_add_u32 v2, v18, 10, v2
	v_ashrrev_i32_e32 v3, 31, v2
	v_lshl_add_u64 v[2:3], v[2:3], 2, s[16:17]
	s_or_b64 exec, exec, s[0:1]
	v_ashrrev_i32_e32 v59, 31, v58
	v_lshlrev_b64 v[18:19], 11, v[58:59]
	v_lshl_add_u64 v[18:19], s[62:63], 0, v[18:19]
	s_waitcnt vmcnt(25)
	v_add_f32_e32 v21, v21, v122
	v_lshl_add_u64 v[18:19], v[130:131], 1, v[18:19]
	v_lshl_add_u64 v[2:3], v[2:3], 0, v[134:135]
	s_and_saveexec_b64 s[0:1], s[10:11]
	s_cbranch_execz .LBB0_4311
	global_store_dword v[2:3], v21, off
	v_mul_f32_e32 v4, v21, v242
	v_cvt_pk_bf16_f32 v4, v4, s0
	global_store_short v[18:19], v4, off
.LBB0_4311:
	s_or_b64 exec, exec, s[0:1]
	s_waitcnt vmcnt(24)
	v_add_f32_e32 v58, v5, v57
	s_and_saveexec_b64 s[0:1], s[10:11]
	s_cbranch_execz .LBB0_4313
	global_store_dword v[2:3], v58, off offset:128
	v_mul_f32_e32 v2, v58, v243
	v_cvt_pk_bf16_f32 v2, v2, s0
	global_store_short v[18:19], v2, off offset:64
.LBB0_4313:
	s_or_b64 exec, exec, s[0:1]
	v_cmp_gt_i32_e64 s[10:11], s85, v56
	s_nop 1
	v_cndmask_b32_e64 v2, v181, v56, s[10:11]
	v_mul_hi_i32 v3, v2, s83
	v_lshrrev_b32_e32 v4, 31, v3
	v_ashrrev_i32_e32 v3, 11, v3
	v_add_u32_e32 v4, v3, v4
	v_mad_i32_i24 v5, v4, s84, v2
	v_cmp_lt_i32_e64 s[0:1], 15, v5
	s_and_saveexec_b64 s[22:23], s[0:1]
	s_xor_b64 s[0:1], exec, s[22:23]
	v_lshlrev_b32_e32 v2, 12, v4
	v_add3_u32 v2, v2, v5, -16
	v_ashrrev_i32_e32 v3, 31, v2
	v_lshlrev_b64 v[2:3], 12, v[2:3]
	v_lshl_add_u64 v[2:3], s[88:89], 0, v[2:3]
	s_andn2_saveexec_b64 s[0:1], s[0:1]
	v_lshlrev_b32_e32 v2, 14, v4
	v_lshl_add_u32 v2, v5, 10, v2
	v_ashrrev_i32_e32 v3, 31, v2
	v_lshl_add_u64 v[2:3], v[2:3], 2, s[16:17]
	s_or_b64 exec, exec, s[0:1]
	v_ashrrev_i32_e32 v57, 31, v56
	v_lshlrev_b64 v[4:5], 11, v[56:57]
	v_lshl_add_u64 v[4:5], s[62:63], 0, v[4:5]
	s_waitcnt vmcnt(23)
	v_add_f32_e32 v18, v22, v121
	v_lshl_add_u64 v[4:5], v[130:131], 1, v[4:5]
	v_lshl_add_u64 v[2:3], v[2:3], 0, v[134:135]
	s_and_saveexec_b64 s[0:1], s[10:11]
	s_cbranch_execz .LBB0_4319
	global_store_dword v[2:3], v18, off
	v_mul_f32_e32 v19, v18, v242
	v_cvt_pk_bf16_f32 v19, v19, s0
	global_store_short v[4:5], v19, off
.LBB0_4319:
	s_or_b64 exec, exec, s[0:1]
	s_waitcnt vmcnt(22)
	v_add_f32_e32 v6, v6, v55
	s_and_saveexec_b64 s[0:1], s[10:11]
	s_cbranch_execz .LBB0_4321
	global_store_dword v[2:3], v6, off offset:128
	v_mul_f32_e32 v2, v6, v243
	v_cvt_pk_bf16_f32 v2, v2, s0
	global_store_short v[4:5], v2, off offset:64
.LBB0_4321:
	s_or_b64 exec, exec, s[0:1]
	v_cmp_gt_i32_e64 s[10:11], s85, v54
	s_nop 1
	v_cndmask_b32_e64 v2, v181, v54, s[10:11]
	v_mul_hi_i32 v3, v2, s83
	v_lshrrev_b32_e32 v4, 31, v3
	v_ashrrev_i32_e32 v3, 11, v3
	v_add_u32_e32 v4, v3, v4
	v_mad_i32_i24 v5, v4, s84, v2
	v_cmp_lt_i32_e64 s[0:1], 15, v5
	s_and_saveexec_b64 s[22:23], s[0:1]
	s_xor_b64 s[0:1], exec, s[22:23]
	v_lshlrev_b32_e32 v2, 12, v4
	v_add3_u32 v2, v2, v5, -16
	v_ashrrev_i32_e32 v3, 31, v2
	v_lshlrev_b64 v[2:3], 12, v[2:3]
	v_lshl_add_u64 v[2:3], s[88:89], 0, v[2:3]
	s_andn2_saveexec_b64 s[0:1], s[0:1]
	v_lshlrev_b32_e32 v2, 14, v4
	v_lshl_add_u32 v2, v5, 10, v2
	v_ashrrev_i32_e32 v3, 31, v2
	v_lshl_add_u64 v[2:3], v[2:3], 2, s[16:17]
	s_or_b64 exec, exec, s[0:1]
	v_ashrrev_i32_e32 v55, 31, v54
	v_lshlrev_b64 v[4:5], 11, v[54:55]
	v_lshl_add_u64 v[4:5], s[62:63], 0, v[4:5]
	s_waitcnt vmcnt(21)
	v_add_f32_e32 v19, v23, v120
	v_lshl_add_u64 v[4:5], v[130:131], 1, v[4:5]
	v_lshl_add_u64 v[2:3], v[2:3], 0, v[134:135]
	s_and_saveexec_b64 s[0:1], s[10:11]
	s_cbranch_execz .LBB0_4327
	global_store_dword v[2:3], v19, off
	v_mul_f32_e32 v22, v19, v242
	v_cvt_pk_bf16_f32 v22, v22, s0
	global_store_short v[4:5], v22, off
.LBB0_4327:
	s_or_b64 exec, exec, s[0:1]
	s_waitcnt vmcnt(20)
	v_add_f32_e32 v7, v7, v53
	s_and_saveexec_b64 s[0:1], s[10:11]
	s_cbranch_execz .LBB0_4329
	global_store_dword v[2:3], v7, off offset:128
	v_mul_f32_e32 v2, v7, v243
	v_cvt_pk_bf16_f32 v2, v2, s0
	global_store_short v[4:5], v2, off offset:64
.LBB0_4329:
	s_or_b64 exec, exec, s[0:1]
	v_cmp_gt_i32_e64 s[10:11], s85, v52
	s_nop 1
	v_cndmask_b32_e64 v2, v181, v52, s[10:11]
	v_mul_hi_i32 v3, v2, s83
	v_lshrrev_b32_e32 v4, 31, v3
	v_ashrrev_i32_e32 v3, 11, v3
	v_add_u32_e32 v4, v3, v4
	v_mad_i32_i24 v5, v4, s84, v2
	v_cmp_lt_i32_e64 s[0:1], 15, v5
	s_and_saveexec_b64 s[22:23], s[0:1]
	s_xor_b64 s[0:1], exec, s[22:23]
	v_lshlrev_b32_e32 v2, 12, v4
	v_add3_u32 v2, v2, v5, -16
	v_ashrrev_i32_e32 v3, 31, v2
	v_lshlrev_b64 v[2:3], 12, v[2:3]
	v_lshl_add_u64 v[2:3], s[88:89], 0, v[2:3]
	s_andn2_saveexec_b64 s[0:1], s[0:1]
	v_lshlrev_b32_e32 v2, 14, v4
	v_lshl_add_u32 v2, v5, 10, v2
	v_ashrrev_i32_e32 v3, 31, v2
	v_lshl_add_u64 v[2:3], v[2:3], 2, s[16:17]
	s_or_b64 exec, exec, s[0:1]
	v_ashrrev_i32_e32 v53, 31, v52
	v_lshlrev_b64 v[4:5], 11, v[52:53]
	v_lshl_add_u64 v[4:5], s[62:63], 0, v[4:5]
	s_waitcnt vmcnt(19)
	v_add_f32_e32 v22, v24, v119
	v_lshl_add_u64 v[4:5], v[130:131], 1, v[4:5]
	v_lshl_add_u64 v[2:3], v[2:3], 0, v[134:135]
	s_and_saveexec_b64 s[0:1], s[10:11]
	s_cbranch_execz .LBB0_4335
	global_store_dword v[2:3], v22, off
	v_mul_f32_e32 v23, v22, v242
	v_cvt_pk_bf16_f32 v23, v23, s0
	global_store_short v[4:5], v23, off
.LBB0_4335:
	s_or_b64 exec, exec, s[0:1]
	s_waitcnt vmcnt(18)
	v_add_f32_e32 v8, v8, v51
	s_and_saveexec_b64 s[0:1], s[10:11]
	s_cbranch_execz .LBB0_4337
	global_store_dword v[2:3], v8, off offset:128
	v_mul_f32_e32 v2, v8, v243
	v_cvt_pk_bf16_f32 v2, v2, s0
	global_store_short v[4:5], v2, off offset:64
.LBB0_4337:
	s_or_b64 exec, exec, s[0:1]
	v_cmp_gt_i32_e64 s[10:11], s85, v50
	s_nop 1
	v_cndmask_b32_e64 v2, v181, v50, s[10:11]
	v_mul_hi_i32 v3, v2, s83
	v_lshrrev_b32_e32 v4, 31, v3
	v_ashrrev_i32_e32 v3, 11, v3
	v_add_u32_e32 v4, v3, v4
	v_mad_i32_i24 v5, v4, s84, v2
	v_cmp_lt_i32_e64 s[0:1], 15, v5
	s_and_saveexec_b64 s[22:23], s[0:1]
	s_xor_b64 s[0:1], exec, s[22:23]
	v_lshlrev_b32_e32 v2, 12, v4
	v_add3_u32 v2, v2, v5, -16
	v_ashrrev_i32_e32 v3, 31, v2
	v_lshlrev_b64 v[2:3], 12, v[2:3]
	v_lshl_add_u64 v[2:3], s[88:89], 0, v[2:3]
	s_andn2_saveexec_b64 s[0:1], s[0:1]
	v_lshlrev_b32_e32 v2, 14, v4
	v_lshl_add_u32 v2, v5, 10, v2
	v_ashrrev_i32_e32 v3, 31, v2
	v_lshl_add_u64 v[2:3], v[2:3], 2, s[16:17]
	s_or_b64 exec, exec, s[0:1]
	v_ashrrev_i32_e32 v51, 31, v50
	v_lshlrev_b64 v[4:5], 11, v[50:51]
	v_lshl_add_u64 v[4:5], s[62:63], 0, v[4:5]
	s_waitcnt vmcnt(17)
	v_add_f32_e32 v23, v25, v118
	v_lshl_add_u64 v[4:5], v[130:131], 1, v[4:5]
	v_lshl_add_u64 v[2:3], v[2:3], 0, v[134:135]
	s_and_saveexec_b64 s[0:1], s[10:11]
	s_cbranch_execz .LBB0_4343
	global_store_dword v[2:3], v23, off
	v_mul_f32_e32 v24, v23, v242
	v_cvt_pk_bf16_f32 v24, v24, s0
	global_store_short v[4:5], v24, off
.LBB0_4343:
	s_or_b64 exec, exec, s[0:1]
	s_waitcnt vmcnt(16)
	v_add_f32_e32 v9, v9, v49
	s_and_saveexec_b64 s[0:1], s[10:11]
	s_cbranch_execz .LBB0_4345
	global_store_dword v[2:3], v9, off offset:128
	v_mul_f32_e32 v2, v9, v243
	v_cvt_pk_bf16_f32 v2, v2, s0
	global_store_short v[4:5], v2, off offset:64
.LBB0_4345:
	s_or_b64 exec, exec, s[0:1]
	v_cmp_gt_i32_e64 s[10:11], s85, v48
	s_nop 1
	v_cndmask_b32_e64 v2, v181, v48, s[10:11]
	v_mul_hi_i32 v3, v2, s83
	v_lshrrev_b32_e32 v4, 31, v3
	v_ashrrev_i32_e32 v3, 11, v3
	v_add_u32_e32 v4, v3, v4
	v_mad_i32_i24 v5, v4, s84, v2
	v_cmp_lt_i32_e64 s[0:1], 15, v5
	s_and_saveexec_b64 s[22:23], s[0:1]
	s_xor_b64 s[0:1], exec, s[22:23]
	v_lshlrev_b32_e32 v2, 12, v4
	v_add3_u32 v2, v2, v5, -16
	v_ashrrev_i32_e32 v3, 31, v2
	v_lshlrev_b64 v[2:3], 12, v[2:3]
	v_lshl_add_u64 v[2:3], s[88:89], 0, v[2:3]
	s_andn2_saveexec_b64 s[0:1], s[0:1]
	v_lshlrev_b32_e32 v2, 14, v4
	v_lshl_add_u32 v2, v5, 10, v2
	v_ashrrev_i32_e32 v3, 31, v2
	v_lshl_add_u64 v[2:3], v[2:3], 2, s[16:17]
	s_or_b64 exec, exec, s[0:1]
	v_ashrrev_i32_e32 v49, 31, v48
	v_lshlrev_b64 v[4:5], 11, v[48:49]
	v_lshl_add_u64 v[4:5], s[62:63], 0, v[4:5]
	s_waitcnt vmcnt(15)
	v_add_f32_e32 v24, v26, v117
	v_lshl_add_u64 v[4:5], v[130:131], 1, v[4:5]
	v_lshl_add_u64 v[2:3], v[2:3], 0, v[134:135]
	s_and_saveexec_b64 s[0:1], s[10:11]
	s_cbranch_execz .LBB0_4351
	global_store_dword v[2:3], v24, off
	v_mul_f32_e32 v25, v24, v242
	v_cvt_pk_bf16_f32 v25, v25, s0
	global_store_short v[4:5], v25, off
.LBB0_4351:
	s_or_b64 exec, exec, s[0:1]
	s_waitcnt vmcnt(14)
	v_add_f32_e32 v10, v10, v47
	s_and_saveexec_b64 s[0:1], s[10:11]
	s_cbranch_execz .LBB0_4353
	global_store_dword v[2:3], v10, off offset:128
	v_mul_f32_e32 v2, v10, v243
	v_cvt_pk_bf16_f32 v2, v2, s0
	global_store_short v[4:5], v2, off offset:64
.LBB0_4353:
	s_or_b64 exec, exec, s[0:1]
	v_cmp_gt_i32_e64 s[10:11], s85, v46
	s_nop 1
	v_cndmask_b32_e64 v2, v181, v46, s[10:11]
	v_mul_hi_i32 v3, v2, s83
	v_lshrrev_b32_e32 v4, 31, v3
	v_ashrrev_i32_e32 v3, 11, v3
	v_add_u32_e32 v4, v3, v4
	v_mad_i32_i24 v5, v4, s84, v2
	v_cmp_lt_i32_e64 s[0:1], 15, v5
	s_and_saveexec_b64 s[22:23], s[0:1]
	s_xor_b64 s[0:1], exec, s[22:23]
	v_lshlrev_b32_e32 v2, 12, v4
	v_add3_u32 v2, v2, v5, -16
	v_ashrrev_i32_e32 v3, 31, v2
	v_lshlrev_b64 v[2:3], 12, v[2:3]
	v_lshl_add_u64 v[2:3], s[88:89], 0, v[2:3]
	s_andn2_saveexec_b64 s[0:1], s[0:1]
	v_lshlrev_b32_e32 v2, 14, v4
	v_lshl_add_u32 v2, v5, 10, v2
	v_ashrrev_i32_e32 v3, 31, v2
	v_lshl_add_u64 v[2:3], v[2:3], 2, s[16:17]
	s_or_b64 exec, exec, s[0:1]
	v_ashrrev_i32_e32 v47, 31, v46
	v_lshlrev_b64 v[4:5], 11, v[46:47]
	v_lshl_add_u64 v[4:5], s[62:63], 0, v[4:5]
	s_waitcnt vmcnt(13)
	v_add_f32_e32 v25, v27, v116
	v_lshl_add_u64 v[4:5], v[130:131], 1, v[4:5]
	v_lshl_add_u64 v[2:3], v[2:3], 0, v[134:135]
	s_and_saveexec_b64 s[0:1], s[10:11]
	s_cbranch_execz .LBB0_4359
	global_store_dword v[2:3], v25, off
	v_mul_f32_e32 v26, v25, v242
	v_cvt_pk_bf16_f32 v26, v26, s0
	global_store_short v[4:5], v26, off
.LBB0_4359:
	s_or_b64 exec, exec, s[0:1]
	s_waitcnt vmcnt(12)
	v_add_f32_e32 v11, v11, v45
	s_and_saveexec_b64 s[0:1], s[10:11]
	s_cbranch_execz .LBB0_4361
	global_store_dword v[2:3], v11, off offset:128
	v_mul_f32_e32 v2, v11, v243
	v_cvt_pk_bf16_f32 v2, v2, s0
	global_store_short v[4:5], v2, off offset:64
.LBB0_4361:
	s_or_b64 exec, exec, s[0:1]
	v_cmp_gt_i32_e64 s[10:11], s85, v44
	s_nop 1
	v_cndmask_b32_e64 v2, v181, v44, s[10:11]
	v_mul_hi_i32 v3, v2, s83
	v_lshrrev_b32_e32 v4, 31, v3
	v_ashrrev_i32_e32 v3, 11, v3
	v_add_u32_e32 v4, v3, v4
	v_mad_i32_i24 v5, v4, s84, v2
	v_cmp_lt_i32_e64 s[0:1], 15, v5
	s_and_saveexec_b64 s[22:23], s[0:1]
	s_xor_b64 s[0:1], exec, s[22:23]
	v_lshlrev_b32_e32 v2, 12, v4
	v_add3_u32 v2, v2, v5, -16
	v_ashrrev_i32_e32 v3, 31, v2
	v_lshlrev_b64 v[2:3], 12, v[2:3]
	v_lshl_add_u64 v[2:3], s[88:89], 0, v[2:3]
	s_andn2_saveexec_b64 s[0:1], s[0:1]
	v_lshlrev_b32_e32 v2, 14, v4
	v_lshl_add_u32 v2, v5, 10, v2
	v_ashrrev_i32_e32 v3, 31, v2
	v_lshl_add_u64 v[2:3], v[2:3], 2, s[16:17]
	s_or_b64 exec, exec, s[0:1]
	v_ashrrev_i32_e32 v45, 31, v44
	v_lshlrev_b64 v[4:5], 11, v[44:45]
	v_lshl_add_u64 v[4:5], s[62:63], 0, v[4:5]
	s_waitcnt vmcnt(11)
	v_add_f32_e32 v26, v28, v115
	v_lshl_add_u64 v[4:5], v[130:131], 1, v[4:5]
	v_lshl_add_u64 v[2:3], v[2:3], 0, v[134:135]
	s_and_saveexec_b64 s[0:1], s[10:11]
	s_cbranch_execz .LBB0_4367
	global_store_dword v[2:3], v26, off
	v_mul_f32_e32 v27, v26, v242
	v_cvt_pk_bf16_f32 v27, v27, s0
	global_store_short v[4:5], v27, off
.LBB0_4367:
	s_or_b64 exec, exec, s[0:1]
	s_waitcnt vmcnt(10)
	v_add_f32_e32 v12, v12, v43
	s_and_saveexec_b64 s[0:1], s[10:11]
	s_cbranch_execz .LBB0_4369
	global_store_dword v[2:3], v12, off offset:128
	v_mul_f32_e32 v2, v12, v243
	v_cvt_pk_bf16_f32 v2, v2, s0
	global_store_short v[4:5], v2, off offset:64
.LBB0_4369:
	s_or_b64 exec, exec, s[0:1]
	v_cmp_gt_i32_e64 s[10:11], s85, v42
	s_nop 1
	v_cndmask_b32_e64 v2, v181, v42, s[10:11]
	v_mul_hi_i32 v3, v2, s83
	v_lshrrev_b32_e32 v4, 31, v3
	v_ashrrev_i32_e32 v3, 11, v3
	v_add_u32_e32 v4, v3, v4
	v_mad_i32_i24 v5, v4, s84, v2
	v_cmp_lt_i32_e64 s[0:1], 15, v5
	s_and_saveexec_b64 s[22:23], s[0:1]
	s_xor_b64 s[0:1], exec, s[22:23]
	v_lshlrev_b32_e32 v2, 12, v4
	v_add3_u32 v2, v2, v5, -16
	v_ashrrev_i32_e32 v3, 31, v2
	v_lshlrev_b64 v[2:3], 12, v[2:3]
	v_lshl_add_u64 v[2:3], s[88:89], 0, v[2:3]
	s_andn2_saveexec_b64 s[0:1], s[0:1]
	v_lshlrev_b32_e32 v2, 14, v4
	v_lshl_add_u32 v2, v5, 10, v2
	v_ashrrev_i32_e32 v3, 31, v2
	v_lshl_add_u64 v[2:3], v[2:3], 2, s[16:17]
	s_or_b64 exec, exec, s[0:1]
	v_ashrrev_i32_e32 v43, 31, v42
	v_lshlrev_b64 v[4:5], 11, v[42:43]
	v_lshl_add_u64 v[4:5], s[62:63], 0, v[4:5]
	s_waitcnt vmcnt(9)
	v_add_f32_e32 v27, v29, v114
	v_lshl_add_u64 v[4:5], v[130:131], 1, v[4:5]
	v_lshl_add_u64 v[2:3], v[2:3], 0, v[134:135]
	s_and_saveexec_b64 s[0:1], s[10:11]
	s_cbranch_execz .LBB0_4375
	global_store_dword v[2:3], v27, off
	v_mul_f32_e32 v28, v27, v242
	v_cvt_pk_bf16_f32 v28, v28, s0
	global_store_short v[4:5], v28, off
.LBB0_4375:
	s_or_b64 exec, exec, s[0:1]
	s_waitcnt vmcnt(8)
	v_add_f32_e32 v13, v13, v41
	s_and_saveexec_b64 s[0:1], s[10:11]
	s_cbranch_execz .LBB0_4377
	global_store_dword v[2:3], v13, off offset:128
	v_mul_f32_e32 v2, v13, v243
	v_cvt_pk_bf16_f32 v2, v2, s0
	global_store_short v[4:5], v2, off offset:64
.LBB0_4377:
	s_or_b64 exec, exec, s[0:1]
	v_cmp_gt_i32_e64 s[10:11], s85, v40
	s_nop 1
	v_cndmask_b32_e64 v2, v181, v40, s[10:11]
	v_mul_hi_i32 v3, v2, s83
	v_lshrrev_b32_e32 v4, 31, v3
	v_ashrrev_i32_e32 v3, 11, v3
	v_add_u32_e32 v4, v3, v4
	v_mad_i32_i24 v5, v4, s84, v2
	v_cmp_lt_i32_e64 s[0:1], 15, v5
	s_and_saveexec_b64 s[22:23], s[0:1]
	s_xor_b64 s[0:1], exec, s[22:23]
	v_lshlrev_b32_e32 v2, 12, v4
	v_add3_u32 v2, v2, v5, -16
	v_ashrrev_i32_e32 v3, 31, v2
	v_lshlrev_b64 v[2:3], 12, v[2:3]
	v_lshl_add_u64 v[2:3], s[88:89], 0, v[2:3]
	s_andn2_saveexec_b64 s[0:1], s[0:1]
	v_lshlrev_b32_e32 v2, 14, v4
	v_lshl_add_u32 v2, v5, 10, v2
	v_ashrrev_i32_e32 v3, 31, v2
	v_lshl_add_u64 v[2:3], v[2:3], 2, s[16:17]
	s_or_b64 exec, exec, s[0:1]
	v_ashrrev_i32_e32 v41, 31, v40
	v_lshlrev_b64 v[4:5], 11, v[40:41]
	v_lshl_add_u64 v[4:5], s[62:63], 0, v[4:5]
	s_waitcnt vmcnt(7)
	v_add_f32_e32 v28, v30, v113
	v_lshl_add_u64 v[4:5], v[130:131], 1, v[4:5]
	v_lshl_add_u64 v[2:3], v[2:3], 0, v[134:135]
	s_and_saveexec_b64 s[0:1], s[10:11]
	s_cbranch_execz .LBB0_4383
	global_store_dword v[2:3], v28, off
	v_mul_f32_e32 v29, v28, v242
	v_cvt_pk_bf16_f32 v29, v29, s0
	global_store_short v[4:5], v29, off
.LBB0_4383:
	s_or_b64 exec, exec, s[0:1]
	s_waitcnt vmcnt(6)
	v_add_f32_e32 v14, v14, v39
	s_and_saveexec_b64 s[0:1], s[10:11]
	s_cbranch_execz .LBB0_4385
	global_store_dword v[2:3], v14, off offset:128
	v_mul_f32_e32 v2, v14, v243
	v_cvt_pk_bf16_f32 v2, v2, s0
	global_store_short v[4:5], v2, off offset:64
.LBB0_4385:
	s_or_b64 exec, exec, s[0:1]
	v_cmp_gt_i32_e64 s[10:11], s85, v38
	s_nop 1
	v_cndmask_b32_e64 v2, v181, v38, s[10:11]
	v_mul_hi_i32 v3, v2, s83
	v_lshrrev_b32_e32 v4, 31, v3
	v_ashrrev_i32_e32 v3, 11, v3
	v_add_u32_e32 v4, v3, v4
	v_mad_i32_i24 v5, v4, s84, v2
	v_cmp_lt_i32_e64 s[0:1], 15, v5
	s_and_saveexec_b64 s[22:23], s[0:1]
	s_xor_b64 s[0:1], exec, s[22:23]
	v_lshlrev_b32_e32 v2, 12, v4
	v_add3_u32 v2, v2, v5, -16
	v_ashrrev_i32_e32 v3, 31, v2
	v_lshlrev_b64 v[2:3], 12, v[2:3]
	v_lshl_add_u64 v[2:3], s[88:89], 0, v[2:3]
	s_andn2_saveexec_b64 s[0:1], s[0:1]
	v_lshlrev_b32_e32 v2, 14, v4
	v_lshl_add_u32 v2, v5, 10, v2
	v_ashrrev_i32_e32 v3, 31, v2
	v_lshl_add_u64 v[2:3], v[2:3], 2, s[16:17]
	s_or_b64 exec, exec, s[0:1]
	v_ashrrev_i32_e32 v39, 31, v38
	v_lshlrev_b64 v[4:5], 11, v[38:39]
	v_lshl_add_u64 v[4:5], s[62:63], 0, v[4:5]
	s_waitcnt vmcnt(5)
	v_add_f32_e32 v29, v31, v112
	v_lshl_add_u64 v[4:5], v[130:131], 1, v[4:5]
	v_lshl_add_u64 v[2:3], v[2:3], 0, v[134:135]
	s_and_saveexec_b64 s[0:1], s[10:11]
	s_cbranch_execz .LBB0_4391
	global_store_dword v[2:3], v29, off
	v_mul_f32_e32 v30, v29, v242
	v_cvt_pk_bf16_f32 v30, v30, s0
	global_store_short v[4:5], v30, off
.LBB0_4391:
	s_or_b64 exec, exec, s[0:1]
	s_waitcnt vmcnt(4)
	v_add_f32_e32 v15, v15, v37
	s_and_saveexec_b64 s[0:1], s[10:11]
	s_cbranch_execz .LBB0_4393
	global_store_dword v[2:3], v15, off offset:128
	v_mul_f32_e32 v2, v15, v243
	v_cvt_pk_bf16_f32 v2, v2, s0
	global_store_short v[4:5], v2, off offset:64
.LBB0_4393:
	s_or_b64 exec, exec, s[0:1]
	v_cmp_gt_i32_e64 s[10:11], s85, v36
	s_nop 1
	v_cndmask_b32_e64 v2, v181, v36, s[10:11]
	v_mul_hi_i32 v3, v2, s83
	v_lshrrev_b32_e32 v4, 31, v3
	v_ashrrev_i32_e32 v3, 11, v3
	v_add_u32_e32 v4, v3, v4
	v_mad_i32_i24 v5, v4, s84, v2
	v_cmp_lt_i32_e64 s[0:1], 15, v5
	s_and_saveexec_b64 s[22:23], s[0:1]
	s_xor_b64 s[0:1], exec, s[22:23]
	v_lshlrev_b32_e32 v2, 12, v4
	v_add3_u32 v2, v2, v5, -16
	v_ashrrev_i32_e32 v3, 31, v2
	v_lshlrev_b64 v[2:3], 12, v[2:3]
	v_lshl_add_u64 v[2:3], s[88:89], 0, v[2:3]
	s_andn2_saveexec_b64 s[0:1], s[0:1]
	v_lshlrev_b32_e32 v2, 14, v4
	v_lshl_add_u32 v2, v5, 10, v2
	v_ashrrev_i32_e32 v3, 31, v2
	v_lshl_add_u64 v[2:3], v[2:3], 2, s[16:17]
	s_or_b64 exec, exec, s[0:1]
	v_ashrrev_i32_e32 v37, 31, v36
	v_lshlrev_b64 v[4:5], 11, v[36:37]
	v_lshl_add_u64 v[4:5], s[62:63], 0, v[4:5]
	s_waitcnt vmcnt(3)
	v_add_f32_e32 v30, v32, v111
	v_lshl_add_u64 v[4:5], v[130:131], 1, v[4:5]
	v_lshl_add_u64 v[2:3], v[2:3], 0, v[134:135]
	s_and_saveexec_b64 s[0:1], s[10:11]
	s_cbranch_execz .LBB0_4399
	global_store_dword v[2:3], v30, off
	v_mul_f32_e32 v31, v30, v242
	v_cvt_pk_bf16_f32 v31, v31, s0
	global_store_short v[4:5], v31, off
.LBB0_4399:
	s_or_b64 exec, exec, s[0:1]
	s_waitcnt vmcnt(2)
	v_add_f32_e32 v31, v16, v35
	s_and_saveexec_b64 s[0:1], s[10:11]
	s_cbranch_execz .LBB0_4401
	global_store_dword v[2:3], v31, off offset:128
	v_mul_f32_e32 v2, v31, v243
	v_cvt_pk_bf16_f32 v2, v2, s0
	global_store_short v[4:5], v2, off offset:64
.LBB0_4401:
	s_or_b64 exec, exec, s[0:1]
	v_cmp_gt_i32_e64 s[10:11], s85, v34
	s_nop 1
	v_cndmask_b32_e64 v2, v181, v34, s[10:11]
	v_mul_hi_i32 v3, v2, s83
	v_lshrrev_b32_e32 v4, 31, v3
	v_ashrrev_i32_e32 v3, 11, v3
	v_add_u32_e32 v4, v3, v4
	v_mad_i32_i24 v5, v4, s84, v2
	v_cmp_lt_i32_e64 s[0:1], 15, v5
	s_and_saveexec_b64 s[22:23], s[0:1]
	s_xor_b64 s[0:1], exec, s[22:23]
	v_lshlrev_b32_e32 v2, 12, v4
	v_add3_u32 v2, v2, v5, -16
	v_ashrrev_i32_e32 v3, 31, v2
	v_lshlrev_b64 v[2:3], 12, v[2:3]
	v_lshl_add_u64 v[2:3], s[88:89], 0, v[2:3]
	s_andn2_saveexec_b64 s[0:1], s[0:1]
	v_lshlrev_b32_e32 v2, 14, v4
	v_lshl_add_u32 v2, v5, 10, v2
	v_ashrrev_i32_e32 v3, 31, v2
	v_lshl_add_u64 v[2:3], v[2:3], 2, s[16:17]
	s_or_b64 exec, exec, s[0:1]
	v_ashrrev_i32_e32 v35, 31, v34
	v_lshlrev_b64 v[4:5], 11, v[34:35]
	v_lshl_add_u64 v[4:5], s[62:63], 0, v[4:5]
	s_waitcnt vmcnt(1)
	v_add_f32_e32 v16, v33, v109
	v_lshl_add_u64 v[4:5], v[130:131], 1, v[4:5]
	v_lshl_add_u64 v[2:3], v[2:3], 0, v[134:135]
	s_and_saveexec_b64 s[0:1], s[10:11]
	s_cbranch_execz .LBB0_4407
	global_store_dword v[2:3], v16, off
	v_mul_f32_e32 v32, v16, v242
	v_cvt_pk_bf16_f32 v32, v32, s0
	global_store_short v[4:5], v32, off
